# GEMM k-tiles: LDS staging writes and next-tile global loads split into 4 groups interleaved with the MFMAs (counted vmcnt/lgkmcnt re-derived) + attention QK fast path
# speedup vs baseline: 1.0099x; 1.0099x over previous
; #define MFMA(a, b, c) __builtin_amdgcn_mfma_f32_32x32x16_bf16((a), (b), (c), 0, 0, 0)
; template <int TM, int TN>
; DI void gemm_mainloop(const u16* __restrict__ A, long lda, const u16* __restrict__ Bt, long ldb, int K, char* smem,
;                       f32x16 (&acc)[TM][TN]) {
;     ...
;   const int nk = K / 64;
;   const int lrow = tid >> 3, lch = (tid & 7) * 8;
;   const u16* gA = A + (long)lrow * lda + lch;
;   const u16* gB = Bt + (long)lrow * ldb + lch;
;   const int soff = lrow * LD + lch;
;     ...
;   GEMM_GLOAD(0)
;   __syncthreads();
;   GEMM_SSTORE(0)
;   if (nk > 1) GEMM_GLOAD(64)
;   __syncthreads();
;   for (int kt = 0; kt < nk; kt++) {
;     const int buf = kt & 1;
;     const u16* cA = sA + buf * BM * LD + (wm * 32 * TM + r) * LD + h * 8;
;     const u16* cB = sB + buf * BN * LD + (wn * 32 * TN + r) * LD + h * 8;
;     bf16x8 af[TM], bfr[TN];
; #pragma unroll
;     for (int tm = 0; tm < TM; tm++) af[tm] = *(const bf16x8*)(cA + tm * 32 * LD);
; #pragma unroll
;     for (int tn = 0; tn < TN; tn++) bfr[tn] = *(const bf16x8*)(cB + tn * 32 * LD);
;     if (kt + 1 < nk) GEMM_SSTORE(buf ^ 1)
;     __builtin_amdgcn_sched_barrier(0);
;     __builtin_amdgcn_s_setprio(1);
; #pragma unroll
;     for (int tm = 0; tm < TM; tm++)
; #pragma unroll
;       for (int tn = 0; tn < TN; tn++) acc[tm][tn] = MFMA(af[tm], bfr[tn], acc[tm][tn]);
; #pragma unroll
;     for (int tm = 0; tm < TM; tm++) af[tm] = *(const bf16x8*)(cA + tm * 32 * LD + 16);
; #pragma unroll
;     for (int tn = 0; tn < TN; tn++) bfr[tn] = *(const bf16x8*)(cB + tn * 32 * LD + 16);
; #pragma unroll
;     for (int tm = 0; tm < TM; tm++)
; #pragma unroll
;       for (int tn = 0; tn < TN; tn++) acc[tm][tn] = MFMA(af[tm], bfr[tn], acc[tm][tn]);
;     __builtin_amdgcn_sched_group_barrier(0x8, 4, 0);
;     if (kt + 2 < nk) GEMM_GLOAD((kt + 2) * 64)
; template <class Epi>
; DI void phase_gemm128(const Sched& sc, const u16* A, long lda, const u16* Bt, long ldb, int K, int MT, int NT, int SN, char* smem, const Epi& epi) {
;     ...
;     for (int st = xg; st < nfull; st += 8) {
;       int sm = st / sng, sn = st % sng;
;       int mt = sm * SM + xi / SN, nt = sn * SN + xi % SN;
;       gemm_tile<2, 2>(A, lda, Bt, ldb, K, mt * 128, nt * 128, smem, epi);
.LBB0_146:
	s_mul_hi_u32 s4, s36, 0xcccccccd
	s_lshr_b32 s4, s4, 2
	s_mul_i32 s5, s4, 5
	s_sub_i32 s5, s36, s5
	s_lshl_b32 s37, s4, 11
	s_add_i32 s37, s37, s3
	s_lshl_b32 s4, s5, 9
	s_add_i32 s4, s4, s20
	s_mul_i32 s16, s37, 0x880
	s_mul_hi_i32 s5, s37, 0x880
	s_add_u32 s16, s8, s16
	v_mov_b32_e32 v1, v0
	s_addc_u32 s17, s9, s5
	s_mul_i32 s5, s4, 0x880
	v_lshlrev_b32_e32 v2, 3, v1
	v_ashrrev_i32_e32 v68, 3, v1
	v_and_b32_e32 v69, 56, v2
	v_mov_b64_e32 v[2:3], s[16:17]
	v_mad_i64_i32 v[2:3], s[16:17], v68, s21, v[2:3]
	v_lshlrev_b32_e32 v66, 1, v69
	v_lshl_add_u64 v[72:73], v[2:3], 0, v[66:67]
	s_ashr_i32 s19, s5, 31
	v_add_co_u32_e32 v70, vcc, s23, v72
	s_add_u32 s18, s10, s5
	s_nop 0
	v_addc_co_u32_e32 v71, vcc, 0, v73, vcc
	s_addc_u32 s19, s11, s19
	v_add_co_u32_e32 v74, vcc, s24, v72
	v_mov_b64_e32 v[2:3], s[18:19]
	s_nop 0
	v_addc_co_u32_e32 v75, vcc, 0, v73, vcc
	v_mad_i64_i32 v[18:19], s[16:17], v68, s21, v[2:3]
	v_add_co_u32_e32 v76, vcc, s25, v72
	v_lshl_add_u64 v[78:79], v[18:19], 0, v[66:67]
	s_nop 0
	v_addc_co_u32_e32 v77, vcc, 0, v73, vcc
	v_add_co_u32_e32 v80, vcc, s23, v78
	global_load_dwordx4 v[2:5], v[72:73], off
	s_nop 0
	v_addc_co_u32_e32 v81, vcc, 0, v79, vcc
	v_add_co_u32_e32 v82, vcc, s24, v78
	global_load_dwordx4 v[6:9], v[70:71], off
	s_nop 0
	v_addc_co_u32_e32 v83, vcc, 0, v79, vcc
	v_add_co_u32_e32 v84, vcc, s25, v78
	global_load_dwordx4 v[10:13], v[74:75], off
	s_nop 0
	v_addc_co_u32_e32 v85, vcc, 0, v79, vcc
	global_load_dwordx4 v[14:17], v[76:77], off
	global_load_dwordx4 v[18:21], v[78:79], off
	global_load_dwordx4 v[22:25], v[80:81], off
	global_load_dwordx4 v[26:29], v[82:83], off
	global_load_dwordx4 v[30:33], v[84:85], off
	s_barrier
	global_load_dwordx4 v[34:37], v[72:73], off offset:128
	global_load_dwordx4 v[38:41], v[70:71], off offset:128
	global_load_dwordx4 v[42:45], v[74:75], off offset:128
	global_load_dwordx4 v[46:49], v[76:77], off offset:128
	global_load_dwordx4 v[50:53], v[78:79], off offset:128
	global_load_dwordx4 v[54:57], v[80:81], off offset:128
	global_load_dwordx4 v[58:61], v[82:83], off offset:128
	global_load_dwordx4 v[62:65], v[84:85], off offset:128
	v_and_b32_e32 v66, 31, v1
	v_lshrrev_b32_e32 v86, 1, v1
	v_and_b32_e32 v1, 0x5f, v1
	v_mul_lo_u32 v68, v68, s22
	v_and_or_b32 v87, v86, s26, v66
	v_and_b32_e32 v86, 16, v86
	v_add_lshl_u32 v66, v68, v69, 1
	v_mad_u64_u32 v[68:69], s[16:17], v87, s27, v[86:87]
	v_mad_u32_u24 v1, v1, s27, v86
	v_add_u32_e32 v69, 0x9000, v66
	s_waitcnt vmcnt(15)
	ds_write_b128 v66, v[2:5]
	s_waitcnt vmcnt(14)
	ds_write_b128 v66, v[6:9] offset:4608
	s_waitcnt vmcnt(13)
	ds_write_b128 v66, v[10:13] offset:9216
	s_waitcnt vmcnt(12)
	ds_write_b128 v66, v[14:17] offset:13824
	s_waitcnt vmcnt(11)
	ds_write_b128 v66, v[18:21] offset:36864
	s_waitcnt vmcnt(10)
	ds_write_b128 v66, v[22:25] offset:41472
	s_waitcnt vmcnt(9)
	ds_write_b128 v66, v[26:29] offset:46080
	s_waitcnt vmcnt(8)
	ds_write_b128 v66, v[30:33] offset:50688
	s_waitcnt lgkmcnt(0)
	s_barrier
	ds_read_b128 v[2:5], v68
	ds_read_b128 v[18:21], v68 offset:4608
	ds_read_b128 v[6:9], v1 offset:36864
	ds_read_b128 v[22:25], v1 offset:41472
	s_waitcnt vmcnt(7)
	ds_write_b128 v66, v[34:37] offset:18432
	s_waitcnt vmcnt(6)
	ds_write_b128 v66, v[38:41] offset:23040
	s_waitcnt vmcnt(5)
	ds_write_b128 v66, v[42:45] offset:27648
	s_waitcnt vmcnt(4)
	ds_write_b128 v66, v[46:49] offset:32256
	s_waitcnt vmcnt(3)
	ds_write_b128 v66, v[50:53] offset:55296
	s_waitcnt vmcnt(2)
	ds_write_b128 v66, v[54:57] offset:59904
	s_waitcnt vmcnt(1)
	ds_write_b128 v66, v[58:61] offset:64512
	s_waitcnt vmcnt(0)
	ds_write_b128 v69, v[62:65] offset:32256
	s_setprio 1
	ds_read_b128 v[86:89], v68 offset:32
	s_waitcnt lgkmcnt(10)
	v_mfma_f32_32x32x16_bf16 v[34:49], v[2:5], v[6:9], 0
	ds_read_b128 v[90:93], v1 offset:36896
	ds_read_b128 v[94:97], v1 offset:41504
	ds_read_b128 v[98:101], v68 offset:4704
	global_load_dwordx4 v[102:105], v[70:71], off offset:256
	global_load_dwordx4 v[106:109], v[74:75], off offset:256
	global_load_dwordx4 v[110:113], v[76:77], off offset:256
	global_load_dwordx4 v[114:117], v[84:85], off offset:256
	s_waitcnt lgkmcnt(12)
	v_mfma_f32_32x32x16_bf16 v[50:65], v[2:5], v[22:25], 0
	global_load_dwordx4 v[118:121], v[82:83], off offset:256
	global_load_dwordx4 v[122:125], v[80:81], off offset:256
	global_load_dwordx4 v[140:143], v[72:73], off offset:256
	global_load_dwordx4 v[144:147], v[78:79], off offset:256
	s_waitcnt lgkmcnt(2)
	v_mfma_f32_32x32x16_bf16 v[34:49], v[86:89], v[90:93], v[34:49]
	s_waitcnt lgkmcnt(1)
	v_mfma_f32_32x32x16_bf16 v[50:65], v[86:89], v[94:97], v[50:65]
	ds_read_b128 v[86:89], v68 offset:4640
	v_mfma_f32_32x32x16_bf16 v[2:17], v[18:21], v[6:9], 0
	v_mfma_f32_32x32x16_bf16 v[18:33], v[18:21], v[22:25], 0
	s_waitcnt lgkmcnt(0)
	v_mfma_f32_32x32x16_bf16 v[2:17], v[86:89], v[90:93], v[2:17]
	ds_read_b128 v[90:93], v1 offset:36928
	v_mfma_f32_32x32x16_bf16 v[18:33], v[86:89], v[94:97], v[18:33]
	ds_read_b128 v[86:89], v68 offset:64
	ds_read_b128 v[94:97], v1 offset:41536
	s_waitcnt lgkmcnt(1)
	v_mfma_f32_32x32x16_bf16 v[34:49], v[86:89], v[90:93], v[34:49]
	s_waitcnt lgkmcnt(0)
	v_mfma_f32_32x32x16_bf16 v[50:65], v[86:89], v[94:97], v[50:65]
	ds_read_b128 v[86:89], v68 offset:4672
	s_waitcnt lgkmcnt(0)
	v_mfma_f32_32x32x16_bf16 v[2:17], v[86:89], v[90:93], v[2:17]
	ds_read_b128 v[90:93], v1 offset:36960
	v_mfma_f32_32x32x16_bf16 v[18:33], v[86:89], v[94:97], v[18:33]
	ds_read_b128 v[86:89], v68 offset:96
	ds_read_b128 v[94:97], v1 offset:41568
	s_waitcnt lgkmcnt(1)
	v_mfma_f32_32x32x16_bf16 v[34:49], v[86:89], v[90:93], v[34:49]
	s_waitcnt lgkmcnt(0)
	v_mfma_f32_32x32x16_bf16 v[50:65], v[86:89], v[94:97], v[50:65]
	v_mfma_f32_32x32x16_bf16 v[2:17], v[98:101], v[90:93], v[2:17]
	v_mfma_f32_32x32x16_bf16 v[18:33], v[98:101], v[94:97], v[18:33]
	s_setprio 0
	s_barrier
; #define MFMA(a, b, c) __builtin_amdgcn_mfma_f32_32x32x16_bf16((a), (b), (c), 0, 0, 0)
; template <int TM, int TN>
; DI void gemm_mainloop(const u16* __restrict__ A, long lda, const u16* __restrict__ Bt, long ldb, int K, char* smem,
;                       f32x16 (&acc)[TM][TN]) {
;     ...
;   for (int kt = 0; kt < nk; kt++) {
;     const int buf = kt & 1;
;     const u16* cA = sA + buf * BM * LD + (wm * 32 * TM + r) * LD + h * 8;
;     const u16* cB = sB + buf * BN * LD + (wn * 32 * TN + r) * LD + h * 8;
;     bf16x8 af[TM], bfr[TN];
; #pragma unroll
;     for (int tm = 0; tm < TM; tm++) af[tm] = *(const bf16x8*)(cA + tm * 32 * LD);
; #pragma unroll
;     for (int tn = 0; tn < TN; tn++) bfr[tn] = *(const bf16x8*)(cB + tn * 32 * LD);
;     if (kt + 1 < nk) GEMM_SSTORE(buf ^ 1)
;     __builtin_amdgcn_sched_barrier(0);
;     __builtin_amdgcn_s_setprio(1);
; #pragma unroll
;     for (int tm = 0; tm < TM; tm++)
; #pragma unroll
;       for (int tn = 0; tn < TN; tn++) acc[tm][tn] = MFMA(af[tm], bfr[tn], acc[tm][tn]);
; #pragma unroll
;     for (int tm = 0; tm < TM; tm++) af[tm] = *(const bf16x8*)(cA + tm * 32 * LD + 16);
; #pragma unroll
;     for (int tn = 0; tn < TN; tn++) bfr[tn] = *(const bf16x8*)(cB + tn * 32 * LD + 16);
; #pragma unroll
;     for (int tm = 0; tm < TM; tm++)
; #pragma unroll
;       for (int tn = 0; tn < TN; tn++) acc[tm][tn] = MFMA(af[tm], bfr[tn], acc[tm][tn]);
;     __builtin_amdgcn_sched_group_barrier(0x8, 4, 0);
;     if (kt + 2 < nk) GEMM_GLOAD((kt + 2) * 64)
; #pragma unroll
;     for (int ks = 2; ks < 4; ks++) {
; #pragma unroll
;       for (int tm = 0; tm < TM; tm++) af[tm] = *(const bf16x8*)(cA + tm * 32 * LD + ks * 16);
; #pragma unroll
;       for (int tn = 0; tn < TN; tn++) bfr[tn] = *(const bf16x8*)(cB + tn * 32 * LD + ks * 16);
; #pragma unroll
;       for (int tm = 0; tm < TM; tm++)
; #pragma unroll
;         for (int tn = 0; tn < TN; tn++) acc[tm][tn] = MFMA(af[tm], bfr[tn], acc[tm][tn]);
;     }
;     __builtin_amdgcn_s_setprio(0);
;     __syncthreads();
;   }
	ds_read_b128 v[94:97], v68 offset:18432
	ds_read_b128 v[98:101], v68 offset:23040
	ds_read_b128 v[126:129], v1 offset:55296
	ds_read_b128 v[130:133], v1 offset:59904
	s_setprio 1
	ds_read_b128 v[86:89], v68 offset:18464
	s_waitcnt lgkmcnt(2)
	v_mfma_f32_32x32x16_bf16 v[34:49], v[94:97], v[126:129], v[34:49]
	ds_read_b128 v[90:93], v1 offset:55328
	s_waitcnt lgkmcnt(2)
	v_mfma_f32_32x32x16_bf16 v[50:65], v[94:97], v[130:133], v[50:65]
	s_waitcnt vmcnt(1)
	ds_write_b128 v66, v[140:143]
	ds_write_b128 v66, v[102:105] offset:4608
	global_load_dwordx4 v[140:143], v[72:73], off offset:384
	global_load_dwordx4 v[102:105], v[70:71], off offset:384
	ds_read_b128 v[94:97], v1 offset:59936
	s_waitcnt lgkmcnt(3)
	v_mfma_f32_32x32x16_bf16 v[34:49], v[86:89], v[90:93], v[34:49]
	s_waitcnt lgkmcnt(0)
	v_mfma_f32_32x32x16_bf16 v[50:65], v[86:89], v[94:97], v[50:65]
	ds_read_b128 v[86:89], v68 offset:23072
	v_mfma_f32_32x32x16_bf16 v[2:17], v[98:101], v[126:129], v[2:17]
	v_mfma_f32_32x32x16_bf16 v[18:33], v[98:101], v[130:133], v[18:33]
	ds_write_b128 v66, v[106:109] offset:9216
	ds_write_b128 v66, v[110:113] offset:13824
	global_load_dwordx4 v[106:109], v[74:75], off offset:384
	global_load_dwordx4 v[110:113], v[76:77], off offset:384
	ds_read_b128 v[98:101], v68 offset:23136
	s_waitcnt lgkmcnt(3)
	v_mfma_f32_32x32x16_bf16 v[2:17], v[86:89], v[90:93], v[2:17]
	ds_read_b128 v[90:93], v1 offset:55360
	v_mfma_f32_32x32x16_bf16 v[18:33], v[86:89], v[94:97], v[18:33]
	ds_read_b128 v[86:89], v68 offset:18496
	ds_read_b128 v[94:97], v1 offset:59968
	s_waitcnt lgkmcnt(1)
	v_mfma_f32_32x32x16_bf16 v[34:49], v[86:89], v[90:93], v[34:49]
	s_waitcnt lgkmcnt(0)
	v_mfma_f32_32x32x16_bf16 v[50:65], v[86:89], v[94:97], v[50:65]
	s_waitcnt vmcnt(4)
	ds_write_b128 v66, v[144:147] offset:36864
	ds_write_b128 v66, v[122:125] offset:41472
	global_load_dwordx4 v[144:147], v[78:79], off offset:384
	global_load_dwordx4 v[122:125], v[80:81], off offset:384
	ds_read_b128 v[86:89], v68 offset:23104
	s_waitcnt lgkmcnt(0)
	v_mfma_f32_32x32x16_bf16 v[2:17], v[86:89], v[90:93], v[2:17]
	ds_read_b128 v[90:93], v1 offset:55392
	v_mfma_f32_32x32x16_bf16 v[18:33], v[86:89], v[94:97], v[18:33]
	ds_read_b128 v[86:89], v68 offset:18528
	ds_read_b128 v[94:97], v1 offset:60000
	s_waitcnt lgkmcnt(1)
	v_mfma_f32_32x32x16_bf16 v[34:49], v[86:89], v[90:93], v[34:49]
	s_waitcnt lgkmcnt(0)
	v_mfma_f32_32x32x16_bf16 v[50:65], v[86:89], v[94:97], v[50:65]
	ds_write_b128 v66, v[118:121] offset:46080
	ds_write_b128 v66, v[114:117] offset:50688
	global_load_dwordx4 v[118:121], v[82:83], off offset:384
	global_load_dwordx4 v[114:117], v[84:85], off offset:384
	v_mfma_f32_32x32x16_bf16 v[2:17], v[98:101], v[90:93], v[2:17]
	v_mfma_f32_32x32x16_bf16 v[18:33], v[98:101], v[94:97], v[18:33]
	s_setprio 0
	s_waitcnt lgkmcnt(0)
	s_barrier
	ds_read_b128 v[94:97], v68
	ds_read_b128 v[98:101], v68 offset:4608
	ds_read_b128 v[126:129], v1 offset:36864
	ds_read_b128 v[130:133], v1 offset:41472
	s_setprio 1
	ds_read_b128 v[86:89], v68 offset:32
	s_waitcnt lgkmcnt(2)
	v_mfma_f32_32x32x16_bf16 v[34:49], v[94:97], v[126:129], v[34:49]
	ds_read_b128 v[90:93], v1 offset:36896
	s_waitcnt lgkmcnt(2)
	v_mfma_f32_32x32x16_bf16 v[50:65], v[94:97], v[130:133], v[50:65]
	s_waitcnt vmcnt(7)
	ds_write_b128 v66, v[140:143] offset:18432
	s_waitcnt vmcnt(6)
	ds_write_b128 v66, v[102:105] offset:23040
	global_load_dwordx4 v[140:143], v[72:73], off offset:512
	global_load_dwordx4 v[102:105], v[70:71], off offset:512
	ds_read_b128 v[94:97], v1 offset:41504
	s_waitcnt lgkmcnt(3)
	v_mfma_f32_32x32x16_bf16 v[34:49], v[86:89], v[90:93], v[34:49]
	s_waitcnt lgkmcnt(0)
	v_mfma_f32_32x32x16_bf16 v[50:65], v[86:89], v[94:97], v[50:65]
	ds_read_b128 v[86:89], v68 offset:4640
	v_mfma_f32_32x32x16_bf16 v[2:17], v[98:101], v[126:129], v[2:17]
	v_mfma_f32_32x32x16_bf16 v[18:33], v[98:101], v[130:133], v[18:33]
	s_waitcnt vmcnt(7)
	ds_write_b128 v66, v[106:109] offset:27648
	s_waitcnt vmcnt(6)
	ds_write_b128 v66, v[110:113] offset:32256
	global_load_dwordx4 v[106:109], v[74:75], off offset:512
	global_load_dwordx4 v[110:113], v[76:77], off offset:512
	ds_read_b128 v[98:101], v68 offset:4704
	s_waitcnt lgkmcnt(3)
	v_mfma_f32_32x32x16_bf16 v[2:17], v[86:89], v[90:93], v[2:17]
	ds_read_b128 v[90:93], v1 offset:36928
	v_mfma_f32_32x32x16_bf16 v[18:33], v[86:89], v[94:97], v[18:33]
	ds_read_b128 v[86:89], v68 offset:64
	ds_read_b128 v[94:97], v1 offset:41536
	s_waitcnt lgkmcnt(1)
	v_mfma_f32_32x32x16_bf16 v[34:49], v[86:89], v[90:93], v[34:49]
	s_waitcnt lgkmcnt(0)
	v_mfma_f32_32x32x16_bf16 v[50:65], v[86:89], v[94:97], v[50:65]
	s_waitcnt vmcnt(7)
	ds_write_b128 v66, v[144:147] offset:55296
	s_waitcnt vmcnt(6)
	ds_write_b128 v66, v[122:125] offset:59904
	global_load_dwordx4 v[144:147], v[78:79], off offset:512
	global_load_dwordx4 v[122:125], v[80:81], off offset:512
	ds_read_b128 v[86:89], v68 offset:4672
	s_waitcnt lgkmcnt(0)
	v_mfma_f32_32x32x16_bf16 v[2:17], v[86:89], v[90:93], v[2:17]
	ds_read_b128 v[90:93], v1 offset:36960
	v_mfma_f32_32x32x16_bf16 v[18:33], v[86:89], v[94:97], v[18:33]
	ds_read_b128 v[86:89], v68 offset:96
	ds_read_b128 v[94:97], v1 offset:41568
	s_waitcnt lgkmcnt(1)
	v_mfma_f32_32x32x16_bf16 v[34:49], v[86:89], v[90:93], v[34:49]
	s_waitcnt lgkmcnt(0)
	v_mfma_f32_32x32x16_bf16 v[50:65], v[86:89], v[94:97], v[50:65]
	s_waitcnt vmcnt(7)
	ds_write_b128 v66, v[118:121] offset:64512
	s_waitcnt vmcnt(6)
	ds_write_b128 v69, v[114:117] offset:32256
	global_load_dwordx4 v[118:121], v[82:83], off offset:512
	global_load_dwordx4 v[114:117], v[84:85], off offset:512
	v_mfma_f32_32x32x16_bf16 v[2:17], v[98:101], v[90:93], v[2:17]
	v_mfma_f32_32x32x16_bf16 v[18:33], v[98:101], v[94:97], v[18:33]
	s_setprio 0
	s_waitcnt lgkmcnt(0)
	s_barrier
; #define MFMA(a, b, c) __builtin_amdgcn_mfma_f32_32x32x16_bf16((a), (b), (c), 0, 0, 0)
; template <int TM, int TN>
; DI void gemm_mainloop(const u16* __restrict__ A, long lda, const u16* __restrict__ Bt, long ldb, int K, char* smem,
;                       f32x16 (&acc)[TM][TN]) {
;     ...
;   for (int kt = 0; kt < nk; kt++) {
;     const int buf = kt & 1;
;     const u16* cA = sA + buf * BM * LD + (wm * 32 * TM + r) * LD + h * 8;
;     const u16* cB = sB + buf * BN * LD + (wn * 32 * TN + r) * LD + h * 8;
;     bf16x8 af[TM], bfr[TN];
; #pragma unroll
;     for (int tm = 0; tm < TM; tm++) af[tm] = *(const bf16x8*)(cA + tm * 32 * LD);
; #pragma unroll
;     for (int tn = 0; tn < TN; tn++) bfr[tn] = *(const bf16x8*)(cB + tn * 32 * LD);
;     if (kt + 1 < nk) GEMM_SSTORE(buf ^ 1)
;     __builtin_amdgcn_sched_barrier(0);
;     __builtin_amdgcn_s_setprio(1);
; #pragma unroll
;     for (int tm = 0; tm < TM; tm++)
; #pragma unroll
;       for (int tn = 0; tn < TN; tn++) acc[tm][tn] = MFMA(af[tm], bfr[tn], acc[tm][tn]);
; #pragma unroll
;     for (int tm = 0; tm < TM; tm++) af[tm] = *(const bf16x8*)(cA + tm * 32 * LD + 16);
; #pragma unroll
;     for (int tn = 0; tn < TN; tn++) bfr[tn] = *(const bf16x8*)(cB + tn * 32 * LD + 16);
; #pragma unroll
;     for (int tm = 0; tm < TM; tm++)
; #pragma unroll
;       for (int tn = 0; tn < TN; tn++) acc[tm][tn] = MFMA(af[tm], bfr[tn], acc[tm][tn]);
;     __builtin_amdgcn_sched_group_barrier(0x8, 4, 0);
;     if (kt + 2 < nk) GEMM_GLOAD((kt + 2) * 64)
; #pragma unroll
;     for (int ks = 2; ks < 4; ks++) {
; #pragma unroll
;       for (int tm = 0; tm < TM; tm++) af[tm] = *(const bf16x8*)(cA + tm * 32 * LD + ks * 16);
; #pragma unroll
;       for (int tn = 0; tn < TN; tn++) bfr[tn] = *(const bf16x8*)(cB + tn * 32 * LD + ks * 16);
; #pragma unroll
;       for (int tm = 0; tm < TM; tm++)
; #pragma unroll
;         for (int tn = 0; tn < TN; tn++) acc[tm][tn] = MFMA(af[tm], bfr[tn], acc[tm][tn]);
;     }
;     __builtin_amdgcn_s_setprio(0);
;     __syncthreads();
;   }
	ds_read_b128 v[94:97], v68 offset:18432
	ds_read_b128 v[98:101], v68 offset:23040
	ds_read_b128 v[126:129], v1 offset:55296
	ds_read_b128 v[130:133], v1 offset:59904
	s_setprio 1
	ds_read_b128 v[86:89], v68 offset:18464
	s_waitcnt lgkmcnt(2)
	v_mfma_f32_32x32x16_bf16 v[34:49], v[94:97], v[126:129], v[34:49]
	ds_read_b128 v[90:93], v1 offset:55328
	s_waitcnt lgkmcnt(2)
	v_mfma_f32_32x32x16_bf16 v[50:65], v[94:97], v[130:133], v[50:65]
	s_waitcnt vmcnt(7)
	ds_write_b128 v66, v[140:143]
	s_waitcnt vmcnt(6)
	ds_write_b128 v66, v[102:105] offset:4608
	global_load_dwordx4 v[140:143], v[72:73], off offset:640
	global_load_dwordx4 v[102:105], v[70:71], off offset:640
	ds_read_b128 v[94:97], v1 offset:59936
	s_waitcnt lgkmcnt(3)
	v_mfma_f32_32x32x16_bf16 v[34:49], v[86:89], v[90:93], v[34:49]
	s_waitcnt lgkmcnt(0)
	v_mfma_f32_32x32x16_bf16 v[50:65], v[86:89], v[94:97], v[50:65]
	ds_read_b128 v[86:89], v68 offset:23072
	v_mfma_f32_32x32x16_bf16 v[2:17], v[98:101], v[126:129], v[2:17]
	v_mfma_f32_32x32x16_bf16 v[18:33], v[98:101], v[130:133], v[18:33]
	s_waitcnt vmcnt(7)
	ds_write_b128 v66, v[106:109] offset:9216
	s_waitcnt vmcnt(6)
	ds_write_b128 v66, v[110:113] offset:13824
	global_load_dwordx4 v[106:109], v[74:75], off offset:640
	global_load_dwordx4 v[110:113], v[76:77], off offset:640
	ds_read_b128 v[98:101], v68 offset:23136
	s_waitcnt lgkmcnt(3)
	v_mfma_f32_32x32x16_bf16 v[2:17], v[86:89], v[90:93], v[2:17]
	ds_read_b128 v[90:93], v1 offset:55360
	v_mfma_f32_32x32x16_bf16 v[18:33], v[86:89], v[94:97], v[18:33]
	ds_read_b128 v[86:89], v68 offset:18496
	ds_read_b128 v[94:97], v1 offset:59968
	s_waitcnt lgkmcnt(1)
	v_mfma_f32_32x32x16_bf16 v[34:49], v[86:89], v[90:93], v[34:49]
	s_waitcnt lgkmcnt(0)
	v_mfma_f32_32x32x16_bf16 v[50:65], v[86:89], v[94:97], v[50:65]
	s_waitcnt vmcnt(7)
	ds_write_b128 v66, v[144:147] offset:36864
	s_waitcnt vmcnt(6)
	ds_write_b128 v66, v[122:125] offset:41472
	global_load_dwordx4 v[144:147], v[78:79], off offset:640
	global_load_dwordx4 v[122:125], v[80:81], off offset:640
	ds_read_b128 v[86:89], v68 offset:23104
	s_waitcnt lgkmcnt(0)
	v_mfma_f32_32x32x16_bf16 v[2:17], v[86:89], v[90:93], v[2:17]
	ds_read_b128 v[90:93], v1 offset:55392
	v_mfma_f32_32x32x16_bf16 v[18:33], v[86:89], v[94:97], v[18:33]
	ds_read_b128 v[86:89], v68 offset:18528
	ds_read_b128 v[94:97], v1 offset:60000
	s_waitcnt lgkmcnt(1)
	v_mfma_f32_32x32x16_bf16 v[34:49], v[86:89], v[90:93], v[34:49]
	s_waitcnt lgkmcnt(0)
	v_mfma_f32_32x32x16_bf16 v[50:65], v[86:89], v[94:97], v[50:65]
	s_waitcnt vmcnt(7)
	ds_write_b128 v66, v[118:121] offset:46080
	s_waitcnt vmcnt(6)
	ds_write_b128 v66, v[114:117] offset:50688
	global_load_dwordx4 v[118:121], v[82:83], off offset:640
	global_load_dwordx4 v[114:117], v[84:85], off offset:640
	v_mfma_f32_32x32x16_bf16 v[2:17], v[98:101], v[90:93], v[2:17]
	v_mfma_f32_32x32x16_bf16 v[18:33], v[98:101], v[94:97], v[18:33]
	s_setprio 0
	s_waitcnt lgkmcnt(0)
	s_barrier
	ds_read_b128 v[94:97], v68
	ds_read_b128 v[98:101], v68 offset:4608
	ds_read_b128 v[126:129], v1 offset:36864
	ds_read_b128 v[130:133], v1 offset:41472
	s_setprio 1
	ds_read_b128 v[86:89], v68 offset:32
	s_waitcnt lgkmcnt(2)
	v_mfma_f32_32x32x16_bf16 v[34:49], v[94:97], v[126:129], v[34:49]
	ds_read_b128 v[90:93], v1 offset:36896
	s_waitcnt lgkmcnt(2)
	v_mfma_f32_32x32x16_bf16 v[50:65], v[94:97], v[130:133], v[50:65]
	s_waitcnt vmcnt(7)
	ds_write_b128 v66, v[140:143] offset:18432
	s_waitcnt vmcnt(6)
	ds_write_b128 v66, v[102:105] offset:23040
	global_load_dwordx4 v[140:143], v[72:73], off offset:768
	global_load_dwordx4 v[102:105], v[70:71], off offset:768
	ds_read_b128 v[94:97], v1 offset:41504
	s_waitcnt lgkmcnt(3)
	v_mfma_f32_32x32x16_bf16 v[34:49], v[86:89], v[90:93], v[34:49]
	s_waitcnt lgkmcnt(0)
	v_mfma_f32_32x32x16_bf16 v[50:65], v[86:89], v[94:97], v[50:65]
	ds_read_b128 v[86:89], v68 offset:4640
	v_mfma_f32_32x32x16_bf16 v[2:17], v[98:101], v[126:129], v[2:17]
	v_mfma_f32_32x32x16_bf16 v[18:33], v[98:101], v[130:133], v[18:33]
	s_waitcnt vmcnt(7)
	ds_write_b128 v66, v[106:109] offset:27648
	s_waitcnt vmcnt(6)
	ds_write_b128 v66, v[110:113] offset:32256
	global_load_dwordx4 v[106:109], v[74:75], off offset:768
	global_load_dwordx4 v[110:113], v[76:77], off offset:768
	ds_read_b128 v[98:101], v68 offset:4704
	s_waitcnt lgkmcnt(3)
	v_mfma_f32_32x32x16_bf16 v[2:17], v[86:89], v[90:93], v[2:17]
	ds_read_b128 v[90:93], v1 offset:36928
	v_mfma_f32_32x32x16_bf16 v[18:33], v[86:89], v[94:97], v[18:33]
	ds_read_b128 v[86:89], v68 offset:64
	ds_read_b128 v[94:97], v1 offset:41536
	s_waitcnt lgkmcnt(1)
	v_mfma_f32_32x32x16_bf16 v[34:49], v[86:89], v[90:93], v[34:49]
	s_waitcnt lgkmcnt(0)
	v_mfma_f32_32x32x16_bf16 v[50:65], v[86:89], v[94:97], v[50:65]
	s_waitcnt vmcnt(7)
	ds_write_b128 v66, v[144:147] offset:55296
	s_waitcnt vmcnt(6)
	ds_write_b128 v66, v[122:125] offset:59904
	global_load_dwordx4 v[144:147], v[78:79], off offset:768
	global_load_dwordx4 v[122:125], v[80:81], off offset:768
	ds_read_b128 v[86:89], v68 offset:4672
	s_waitcnt lgkmcnt(0)
	v_mfma_f32_32x32x16_bf16 v[2:17], v[86:89], v[90:93], v[2:17]
	ds_read_b128 v[90:93], v1 offset:36960
	v_mfma_f32_32x32x16_bf16 v[18:33], v[86:89], v[94:97], v[18:33]
	ds_read_b128 v[86:89], v68 offset:96
	ds_read_b128 v[94:97], v1 offset:41568
	s_waitcnt lgkmcnt(1)
	v_mfma_f32_32x32x16_bf16 v[34:49], v[86:89], v[90:93], v[34:49]
	s_waitcnt lgkmcnt(0)
	v_mfma_f32_32x32x16_bf16 v[50:65], v[86:89], v[94:97], v[50:65]
	s_waitcnt vmcnt(7)
	ds_write_b128 v66, v[118:121] offset:64512
	s_waitcnt vmcnt(6)
	ds_write_b128 v69, v[114:117] offset:32256
	global_load_dwordx4 v[118:121], v[82:83], off offset:768
	global_load_dwordx4 v[114:117], v[84:85], off offset:768
	v_mfma_f32_32x32x16_bf16 v[2:17], v[98:101], v[90:93], v[2:17]
	v_mfma_f32_32x32x16_bf16 v[18:33], v[98:101], v[94:97], v[18:33]
	s_setprio 0
	s_waitcnt lgkmcnt(0)
	s_barrier
; #define MFMA(a, b, c) __builtin_amdgcn_mfma_f32_32x32x16_bf16((a), (b), (c), 0, 0, 0)
; template <int TM, int TN>
; DI void gemm_mainloop(const u16* __restrict__ A, long lda, const u16* __restrict__ Bt, long ldb, int K, char* smem,
;                       f32x16 (&acc)[TM][TN]) {
;     ...
;   for (int kt = 0; kt < nk; kt++) {
;     const int buf = kt & 1;
;     const u16* cA = sA + buf * BM * LD + (wm * 32 * TM + r) * LD + h * 8;
;     const u16* cB = sB + buf * BN * LD + (wn * 32 * TN + r) * LD + h * 8;
;     bf16x8 af[TM], bfr[TN];
; #pragma unroll
;     for (int tm = 0; tm < TM; tm++) af[tm] = *(const bf16x8*)(cA + tm * 32 * LD);
; #pragma unroll
;     for (int tn = 0; tn < TN; tn++) bfr[tn] = *(const bf16x8*)(cB + tn * 32 * LD);
;     if (kt + 1 < nk) GEMM_SSTORE(buf ^ 1)
;     __builtin_amdgcn_sched_barrier(0);
;     __builtin_amdgcn_s_setprio(1);
; #pragma unroll
;     for (int tm = 0; tm < TM; tm++)
; #pragma unroll
;       for (int tn = 0; tn < TN; tn++) acc[tm][tn] = MFMA(af[tm], bfr[tn], acc[tm][tn]);
; #pragma unroll
;     for (int tm = 0; tm < TM; tm++) af[tm] = *(const bf16x8*)(cA + tm * 32 * LD + 16);
; #pragma unroll
;     for (int tn = 0; tn < TN; tn++) bfr[tn] = *(const bf16x8*)(cB + tn * 32 * LD + 16);
; #pragma unroll
;     for (int tm = 0; tm < TM; tm++)
; #pragma unroll
;       for (int tn = 0; tn < TN; tn++) acc[tm][tn] = MFMA(af[tm], bfr[tn], acc[tm][tn]);
;     __builtin_amdgcn_sched_group_barrier(0x8, 4, 0);
;     if (kt + 2 < nk) GEMM_GLOAD((kt + 2) * 64)
; #pragma unroll
;     for (int ks = 2; ks < 4; ks++) {
; #pragma unroll
;       for (int tm = 0; tm < TM; tm++) af[tm] = *(const bf16x8*)(cA + tm * 32 * LD + ks * 16);
; #pragma unroll
;       for (int tn = 0; tn < TN; tn++) bfr[tn] = *(const bf16x8*)(cB + tn * 32 * LD + ks * 16);
; #pragma unroll
;       for (int tm = 0; tm < TM; tm++)
; #pragma unroll
;         for (int tn = 0; tn < TN; tn++) acc[tm][tn] = MFMA(af[tm], bfr[tn], acc[tm][tn]);
;     }
;     __builtin_amdgcn_s_setprio(0);
;     __syncthreads();
;   }
	ds_read_b128 v[94:97], v68 offset:18432
	ds_read_b128 v[98:101], v68 offset:23040
	ds_read_b128 v[126:129], v1 offset:55296
	ds_read_b128 v[130:133], v1 offset:59904
	s_setprio 1
	ds_read_b128 v[86:89], v68 offset:18464
	s_waitcnt lgkmcnt(2)
	v_mfma_f32_32x32x16_bf16 v[34:49], v[94:97], v[126:129], v[34:49]
	ds_read_b128 v[90:93], v1 offset:55328
	s_waitcnt lgkmcnt(2)
	v_mfma_f32_32x32x16_bf16 v[50:65], v[94:97], v[130:133], v[50:65]
	s_waitcnt vmcnt(7)
	ds_write_b128 v66, v[140:143]
	s_waitcnt vmcnt(6)
	ds_write_b128 v66, v[102:105] offset:4608
	global_load_dwordx4 v[140:143], v[72:73], off offset:896
	global_load_dwordx4 v[102:105], v[70:71], off offset:896
	ds_read_b128 v[94:97], v1 offset:59936
	s_waitcnt lgkmcnt(3)
	v_mfma_f32_32x32x16_bf16 v[34:49], v[86:89], v[90:93], v[34:49]
	s_waitcnt lgkmcnt(0)
	v_mfma_f32_32x32x16_bf16 v[50:65], v[86:89], v[94:97], v[50:65]
	ds_read_b128 v[86:89], v68 offset:23072
	v_mfma_f32_32x32x16_bf16 v[2:17], v[98:101], v[126:129], v[2:17]
	v_mfma_f32_32x32x16_bf16 v[18:33], v[98:101], v[130:133], v[18:33]
	s_waitcnt vmcnt(7)
	ds_write_b128 v66, v[106:109] offset:9216
	s_waitcnt vmcnt(6)
	ds_write_b128 v66, v[110:113] offset:13824
	global_load_dwordx4 v[106:109], v[74:75], off offset:896
	global_load_dwordx4 v[110:113], v[76:77], off offset:896
	ds_read_b128 v[98:101], v68 offset:23136
	s_waitcnt lgkmcnt(3)
	v_mfma_f32_32x32x16_bf16 v[2:17], v[86:89], v[90:93], v[2:17]
	ds_read_b128 v[90:93], v1 offset:55360
	v_mfma_f32_32x32x16_bf16 v[18:33], v[86:89], v[94:97], v[18:33]
	ds_read_b128 v[86:89], v68 offset:18496
	ds_read_b128 v[94:97], v1 offset:59968
	s_waitcnt lgkmcnt(1)
	v_mfma_f32_32x32x16_bf16 v[34:49], v[86:89], v[90:93], v[34:49]
	s_waitcnt lgkmcnt(0)
	v_mfma_f32_32x32x16_bf16 v[50:65], v[86:89], v[94:97], v[50:65]
	s_waitcnt vmcnt(7)
	ds_write_b128 v66, v[144:147] offset:36864
	s_waitcnt vmcnt(6)
	ds_write_b128 v66, v[122:125] offset:41472
	global_load_dwordx4 v[144:147], v[78:79], off offset:896
	global_load_dwordx4 v[122:125], v[80:81], off offset:896
	ds_read_b128 v[86:89], v68 offset:23104
	s_waitcnt lgkmcnt(0)
	v_mfma_f32_32x32x16_bf16 v[2:17], v[86:89], v[90:93], v[2:17]
	ds_read_b128 v[90:93], v1 offset:55392
	v_mfma_f32_32x32x16_bf16 v[18:33], v[86:89], v[94:97], v[18:33]
	ds_read_b128 v[86:89], v68 offset:18528
	ds_read_b128 v[94:97], v1 offset:60000
	s_waitcnt lgkmcnt(1)
	v_mfma_f32_32x32x16_bf16 v[34:49], v[86:89], v[90:93], v[34:49]
	s_waitcnt lgkmcnt(0)
	v_mfma_f32_32x32x16_bf16 v[50:65], v[86:89], v[94:97], v[50:65]
	s_waitcnt vmcnt(7)
	ds_write_b128 v66, v[118:121] offset:46080
	s_waitcnt vmcnt(6)
	ds_write_b128 v66, v[114:117] offset:50688
	global_load_dwordx4 v[118:121], v[82:83], off offset:896
	global_load_dwordx4 v[114:117], v[84:85], off offset:896
	v_mfma_f32_32x32x16_bf16 v[2:17], v[98:101], v[90:93], v[2:17]
	v_mfma_f32_32x32x16_bf16 v[18:33], v[98:101], v[94:97], v[18:33]
	s_setprio 0
	s_waitcnt lgkmcnt(0)
	s_barrier
	ds_read_b128 v[94:97], v68
	ds_read_b128 v[98:101], v68 offset:4608
	ds_read_b128 v[126:129], v1 offset:36864
	ds_read_b128 v[130:133], v1 offset:41472
	s_setprio 1
	ds_read_b128 v[86:89], v68 offset:32
	s_waitcnt lgkmcnt(2)
	v_mfma_f32_32x32x16_bf16 v[34:49], v[94:97], v[126:129], v[34:49]
	ds_read_b128 v[90:93], v1 offset:36896
	s_waitcnt lgkmcnt(2)
	v_mfma_f32_32x32x16_bf16 v[50:65], v[94:97], v[130:133], v[50:65]
	s_waitcnt vmcnt(7)
	ds_write_b128 v66, v[140:143] offset:18432
	s_waitcnt vmcnt(6)
	ds_write_b128 v66, v[102:105] offset:23040
	global_load_dwordx4 v[140:143], v[72:73], off offset:1024
	global_load_dwordx4 v[102:105], v[70:71], off offset:1024
	ds_read_b128 v[94:97], v1 offset:41504
	s_waitcnt lgkmcnt(3)
	v_mfma_f32_32x32x16_bf16 v[34:49], v[86:89], v[90:93], v[34:49]
	s_waitcnt lgkmcnt(0)
	v_mfma_f32_32x32x16_bf16 v[50:65], v[86:89], v[94:97], v[50:65]
	ds_read_b128 v[86:89], v68 offset:4640
	v_mfma_f32_32x32x16_bf16 v[2:17], v[98:101], v[126:129], v[2:17]
	v_mfma_f32_32x32x16_bf16 v[18:33], v[98:101], v[130:133], v[18:33]
	s_waitcnt vmcnt(7)
	ds_write_b128 v66, v[106:109] offset:27648
	s_waitcnt vmcnt(6)
	ds_write_b128 v66, v[110:113] offset:32256
	global_load_dwordx4 v[106:109], v[74:75], off offset:1024
	global_load_dwordx4 v[110:113], v[76:77], off offset:1024
	ds_read_b128 v[98:101], v68 offset:4704
	s_waitcnt lgkmcnt(3)
	v_mfma_f32_32x32x16_bf16 v[2:17], v[86:89], v[90:93], v[2:17]
	ds_read_b128 v[90:93], v1 offset:36928
	v_mfma_f32_32x32x16_bf16 v[18:33], v[86:89], v[94:97], v[18:33]
	ds_read_b128 v[86:89], v68 offset:64
	ds_read_b128 v[94:97], v1 offset:41536
	s_waitcnt lgkmcnt(1)
	v_mfma_f32_32x32x16_bf16 v[34:49], v[86:89], v[90:93], v[34:49]
	s_waitcnt lgkmcnt(0)
	v_mfma_f32_32x32x16_bf16 v[50:65], v[86:89], v[94:97], v[50:65]
	s_waitcnt vmcnt(7)
	ds_write_b128 v66, v[144:147] offset:55296
	s_waitcnt vmcnt(6)
	ds_write_b128 v66, v[122:125] offset:59904
	global_load_dwordx4 v[144:147], v[78:79], off offset:1024
	global_load_dwordx4 v[122:125], v[80:81], off offset:1024
	ds_read_b128 v[86:89], v68 offset:4672
	s_waitcnt lgkmcnt(0)
	v_mfma_f32_32x32x16_bf16 v[2:17], v[86:89], v[90:93], v[2:17]
	ds_read_b128 v[90:93], v1 offset:36960
	v_mfma_f32_32x32x16_bf16 v[18:33], v[86:89], v[94:97], v[18:33]
	ds_read_b128 v[86:89], v68 offset:96
	ds_read_b128 v[94:97], v1 offset:41568
	s_waitcnt lgkmcnt(1)
	v_mfma_f32_32x32x16_bf16 v[34:49], v[86:89], v[90:93], v[34:49]
	s_waitcnt lgkmcnt(0)
	v_mfma_f32_32x32x16_bf16 v[50:65], v[86:89], v[94:97], v[50:65]
	s_waitcnt vmcnt(7)
	ds_write_b128 v66, v[118:121] offset:64512
	s_waitcnt vmcnt(6)
	ds_write_b128 v69, v[114:117] offset:32256
	global_load_dwordx4 v[118:121], v[82:83], off offset:1024
	global_load_dwordx4 v[114:117], v[84:85], off offset:1024
	v_mfma_f32_32x32x16_bf16 v[2:17], v[98:101], v[90:93], v[2:17]
	v_mfma_f32_32x32x16_bf16 v[18:33], v[98:101], v[94:97], v[18:33]
	s_setprio 0
	s_waitcnt lgkmcnt(0)
	s_barrier
; #define MFMA(a, b, c) __builtin_amdgcn_mfma_f32_32x32x16_bf16((a), (b), (c), 0, 0, 0)
; template <int TM, int TN>
; DI void gemm_mainloop(const u16* __restrict__ A, long lda, const u16* __restrict__ Bt, long ldb, int K, char* smem,
;                       f32x16 (&acc)[TM][TN]) {
;     ...
;   for (int kt = 0; kt < nk; kt++) {
;     const int buf = kt & 1;
;     const u16* cA = sA + buf * BM * LD + (wm * 32 * TM + r) * LD + h * 8;
;     const u16* cB = sB + buf * BN * LD + (wn * 32 * TN + r) * LD + h * 8;
;     bf16x8 af[TM], bfr[TN];
; #pragma unroll
;     for (int tm = 0; tm < TM; tm++) af[tm] = *(const bf16x8*)(cA + tm * 32 * LD);
; #pragma unroll
;     for (int tn = 0; tn < TN; tn++) bfr[tn] = *(const bf16x8*)(cB + tn * 32 * LD);
;     if (kt + 1 < nk) GEMM_SSTORE(buf ^ 1)
;     __builtin_amdgcn_sched_barrier(0);
;     __builtin_amdgcn_s_setprio(1);
; #pragma unroll
;     for (int tm = 0; tm < TM; tm++)
; #pragma unroll
;       for (int tn = 0; tn < TN; tn++) acc[tm][tn] = MFMA(af[tm], bfr[tn], acc[tm][tn]);
; #pragma unroll
;     for (int tm = 0; tm < TM; tm++) af[tm] = *(const bf16x8*)(cA + tm * 32 * LD + 16);
; #pragma unroll
;     for (int tn = 0; tn < TN; tn++) bfr[tn] = *(const bf16x8*)(cB + tn * 32 * LD + 16);
; #pragma unroll
;     for (int tm = 0; tm < TM; tm++)
; #pragma unroll
;       for (int tn = 0; tn < TN; tn++) acc[tm][tn] = MFMA(af[tm], bfr[tn], acc[tm][tn]);
;     __builtin_amdgcn_sched_group_barrier(0x8, 4, 0);
;     if (kt + 2 < nk) GEMM_GLOAD((kt + 2) * 64)
; #pragma unroll
;     for (int ks = 2; ks < 4; ks++) {
; #pragma unroll
;       for (int tm = 0; tm < TM; tm++) af[tm] = *(const bf16x8*)(cA + tm * 32 * LD + ks * 16);
; #pragma unroll
;       for (int tn = 0; tn < TN; tn++) bfr[tn] = *(const bf16x8*)(cB + tn * 32 * LD + ks * 16);
; #pragma unroll
;       for (int tm = 0; tm < TM; tm++)
; #pragma unroll
;         for (int tn = 0; tn < TN; tn++) acc[tm][tn] = MFMA(af[tm], bfr[tn], acc[tm][tn]);
;     }
;     __builtin_amdgcn_s_setprio(0);
;     __syncthreads();
;   }
	ds_read_b128 v[94:97], v68 offset:18432
	ds_read_b128 v[98:101], v68 offset:23040
	ds_read_b128 v[126:129], v1 offset:55296
	ds_read_b128 v[130:133], v1 offset:59904
	s_setprio 1
	ds_read_b128 v[86:89], v68 offset:18464
	s_waitcnt lgkmcnt(2)
	v_mfma_f32_32x32x16_bf16 v[34:49], v[94:97], v[126:129], v[34:49]
	ds_read_b128 v[90:93], v1 offset:55328
	s_waitcnt lgkmcnt(2)
	v_mfma_f32_32x32x16_bf16 v[50:65], v[94:97], v[130:133], v[50:65]
	s_waitcnt vmcnt(7)
	ds_write_b128 v66, v[140:143]
	s_waitcnt vmcnt(6)
	ds_write_b128 v66, v[102:105] offset:4608
	global_load_dwordx4 v[140:143], v[72:73], off offset:1152
	global_load_dwordx4 v[102:105], v[70:71], off offset:1152
	ds_read_b128 v[94:97], v1 offset:59936
	s_waitcnt lgkmcnt(3)
	v_mfma_f32_32x32x16_bf16 v[34:49], v[86:89], v[90:93], v[34:49]
	s_waitcnt lgkmcnt(0)
	v_mfma_f32_32x32x16_bf16 v[50:65], v[86:89], v[94:97], v[50:65]
	ds_read_b128 v[86:89], v68 offset:23072
	v_mfma_f32_32x32x16_bf16 v[2:17], v[98:101], v[126:129], v[2:17]
	v_mfma_f32_32x32x16_bf16 v[18:33], v[98:101], v[130:133], v[18:33]
	s_waitcnt vmcnt(7)
	ds_write_b128 v66, v[106:109] offset:9216
	s_waitcnt vmcnt(6)
	ds_write_b128 v66, v[110:113] offset:13824
	global_load_dwordx4 v[106:109], v[74:75], off offset:1152
	global_load_dwordx4 v[110:113], v[76:77], off offset:1152
	ds_read_b128 v[98:101], v68 offset:23136
	s_waitcnt lgkmcnt(3)
	v_mfma_f32_32x32x16_bf16 v[2:17], v[86:89], v[90:93], v[2:17]
	ds_read_b128 v[90:93], v1 offset:55360
	v_mfma_f32_32x32x16_bf16 v[18:33], v[86:89], v[94:97], v[18:33]
	ds_read_b128 v[86:89], v68 offset:18496
	ds_read_b128 v[94:97], v1 offset:59968
	s_waitcnt lgkmcnt(1)
	v_mfma_f32_32x32x16_bf16 v[34:49], v[86:89], v[90:93], v[34:49]
	s_waitcnt lgkmcnt(0)
	v_mfma_f32_32x32x16_bf16 v[50:65], v[86:89], v[94:97], v[50:65]
	s_waitcnt vmcnt(7)
	ds_write_b128 v66, v[144:147] offset:36864
	s_waitcnt vmcnt(6)
	ds_write_b128 v66, v[122:125] offset:41472
	global_load_dwordx4 v[144:147], v[78:79], off offset:1152
	global_load_dwordx4 v[122:125], v[80:81], off offset:1152
	ds_read_b128 v[86:89], v68 offset:23104
	s_waitcnt lgkmcnt(0)
	v_mfma_f32_32x32x16_bf16 v[2:17], v[86:89], v[90:93], v[2:17]
	ds_read_b128 v[90:93], v1 offset:55392
	v_mfma_f32_32x32x16_bf16 v[18:33], v[86:89], v[94:97], v[18:33]
	ds_read_b128 v[86:89], v68 offset:18528
	ds_read_b128 v[94:97], v1 offset:60000
	s_waitcnt lgkmcnt(1)
	v_mfma_f32_32x32x16_bf16 v[34:49], v[86:89], v[90:93], v[34:49]
	s_waitcnt lgkmcnt(0)
	v_mfma_f32_32x32x16_bf16 v[50:65], v[86:89], v[94:97], v[50:65]
	s_waitcnt vmcnt(7)
	ds_write_b128 v66, v[118:121] offset:46080
	s_waitcnt vmcnt(6)
	ds_write_b128 v66, v[114:117] offset:50688
	global_load_dwordx4 v[118:121], v[82:83], off offset:1152
	global_load_dwordx4 v[114:117], v[84:85], off offset:1152
	v_mfma_f32_32x32x16_bf16 v[2:17], v[98:101], v[90:93], v[2:17]
	v_mfma_f32_32x32x16_bf16 v[18:33], v[98:101], v[94:97], v[18:33]
	s_setprio 0
	s_waitcnt lgkmcnt(0)
	s_barrier
	ds_read_b128 v[94:97], v68
	ds_read_b128 v[98:101], v68 offset:4608
	ds_read_b128 v[126:129], v1 offset:36864
	ds_read_b128 v[130:133], v1 offset:41472
	s_setprio 1
	ds_read_b128 v[86:89], v68 offset:32
	s_waitcnt lgkmcnt(2)
	v_mfma_f32_32x32x16_bf16 v[34:49], v[94:97], v[126:129], v[34:49]
	ds_read_b128 v[90:93], v1 offset:36896
	s_waitcnt lgkmcnt(2)
	v_mfma_f32_32x32x16_bf16 v[50:65], v[94:97], v[130:133], v[50:65]
	s_waitcnt vmcnt(7)
	ds_write_b128 v66, v[140:143] offset:18432
	s_waitcnt vmcnt(6)
	ds_write_b128 v66, v[102:105] offset:23040
	global_load_dwordx4 v[140:143], v[72:73], off offset:1280
	global_load_dwordx4 v[102:105], v[70:71], off offset:1280
	ds_read_b128 v[94:97], v1 offset:41504
	s_waitcnt lgkmcnt(3)
	v_mfma_f32_32x32x16_bf16 v[34:49], v[86:89], v[90:93], v[34:49]
	s_waitcnt lgkmcnt(0)
	v_mfma_f32_32x32x16_bf16 v[50:65], v[86:89], v[94:97], v[50:65]
	ds_read_b128 v[86:89], v68 offset:4640
	v_mfma_f32_32x32x16_bf16 v[2:17], v[98:101], v[126:129], v[2:17]
	v_mfma_f32_32x32x16_bf16 v[18:33], v[98:101], v[130:133], v[18:33]
	s_waitcnt vmcnt(7)
	ds_write_b128 v66, v[106:109] offset:27648
	s_waitcnt vmcnt(6)
	ds_write_b128 v66, v[110:113] offset:32256
	global_load_dwordx4 v[106:109], v[74:75], off offset:1280
	global_load_dwordx4 v[110:113], v[76:77], off offset:1280
	ds_read_b128 v[98:101], v68 offset:4704
	s_waitcnt lgkmcnt(3)
	v_mfma_f32_32x32x16_bf16 v[2:17], v[86:89], v[90:93], v[2:17]
	ds_read_b128 v[90:93], v1 offset:36928
	v_mfma_f32_32x32x16_bf16 v[18:33], v[86:89], v[94:97], v[18:33]
	ds_read_b128 v[86:89], v68 offset:64
	ds_read_b128 v[94:97], v1 offset:41536
	s_waitcnt lgkmcnt(1)
	v_mfma_f32_32x32x16_bf16 v[34:49], v[86:89], v[90:93], v[34:49]
	s_waitcnt lgkmcnt(0)
	v_mfma_f32_32x32x16_bf16 v[50:65], v[86:89], v[94:97], v[50:65]
	s_waitcnt vmcnt(7)
	ds_write_b128 v66, v[144:147] offset:55296
	s_waitcnt vmcnt(6)
	ds_write_b128 v66, v[122:125] offset:59904
	global_load_dwordx4 v[144:147], v[78:79], off offset:1280
	global_load_dwordx4 v[122:125], v[80:81], off offset:1280
	ds_read_b128 v[86:89], v68 offset:4672
	s_waitcnt lgkmcnt(0)
	v_mfma_f32_32x32x16_bf16 v[2:17], v[86:89], v[90:93], v[2:17]
	ds_read_b128 v[90:93], v1 offset:36960
	v_mfma_f32_32x32x16_bf16 v[18:33], v[86:89], v[94:97], v[18:33]
	ds_read_b128 v[86:89], v68 offset:96
	ds_read_b128 v[94:97], v1 offset:41568
	s_waitcnt lgkmcnt(1)
	v_mfma_f32_32x32x16_bf16 v[34:49], v[86:89], v[90:93], v[34:49]
	s_waitcnt lgkmcnt(0)
	v_mfma_f32_32x32x16_bf16 v[50:65], v[86:89], v[94:97], v[50:65]
	s_waitcnt vmcnt(7)
	ds_write_b128 v66, v[118:121] offset:64512
	s_waitcnt vmcnt(6)
	ds_write_b128 v69, v[114:117] offset:32256
	global_load_dwordx4 v[118:121], v[82:83], off offset:1280
	global_load_dwordx4 v[114:117], v[84:85], off offset:1280
	v_mfma_f32_32x32x16_bf16 v[2:17], v[98:101], v[90:93], v[2:17]
	v_mfma_f32_32x32x16_bf16 v[18:33], v[98:101], v[94:97], v[18:33]
	s_setprio 0
	s_waitcnt lgkmcnt(0)
	s_barrier
; #define MFMA(a, b, c) __builtin_amdgcn_mfma_f32_32x32x16_bf16((a), (b), (c), 0, 0, 0)
; template <int TM, int TN>
; DI void gemm_mainloop(const u16* __restrict__ A, long lda, const u16* __restrict__ Bt, long ldb, int K, char* smem,
;                       f32x16 (&acc)[TM][TN]) {
;     ...
;   for (int kt = 0; kt < nk; kt++) {
;     const int buf = kt & 1;
;     const u16* cA = sA + buf * BM * LD + (wm * 32 * TM + r) * LD + h * 8;
;     const u16* cB = sB + buf * BN * LD + (wn * 32 * TN + r) * LD + h * 8;
;     bf16x8 af[TM], bfr[TN];
; #pragma unroll
;     for (int tm = 0; tm < TM; tm++) af[tm] = *(const bf16x8*)(cA + tm * 32 * LD);
; #pragma unroll
;     for (int tn = 0; tn < TN; tn++) bfr[tn] = *(const bf16x8*)(cB + tn * 32 * LD);
;     if (kt + 1 < nk) GEMM_SSTORE(buf ^ 1)
;     __builtin_amdgcn_sched_barrier(0);
;     __builtin_amdgcn_s_setprio(1);
; #pragma unroll
;     for (int tm = 0; tm < TM; tm++)
; #pragma unroll
;       for (int tn = 0; tn < TN; tn++) acc[tm][tn] = MFMA(af[tm], bfr[tn], acc[tm][tn]);
; #pragma unroll
;     for (int tm = 0; tm < TM; tm++) af[tm] = *(const bf16x8*)(cA + tm * 32 * LD + 16);
; #pragma unroll
;     for (int tn = 0; tn < TN; tn++) bfr[tn] = *(const bf16x8*)(cB + tn * 32 * LD + 16);
; #pragma unroll
;     for (int tm = 0; tm < TM; tm++)
; #pragma unroll
;       for (int tn = 0; tn < TN; tn++) acc[tm][tn] = MFMA(af[tm], bfr[tn], acc[tm][tn]);
;     __builtin_amdgcn_sched_group_barrier(0x8, 4, 0);
;     if (kt + 2 < nk) GEMM_GLOAD((kt + 2) * 64)
; #pragma unroll
;     for (int ks = 2; ks < 4; ks++) {
; #pragma unroll
;       for (int tm = 0; tm < TM; tm++) af[tm] = *(const bf16x8*)(cA + tm * 32 * LD + ks * 16);
; #pragma unroll
;       for (int tn = 0; tn < TN; tn++) bfr[tn] = *(const bf16x8*)(cB + tn * 32 * LD + ks * 16);
; #pragma unroll
;       for (int tm = 0; tm < TM; tm++)
; #pragma unroll
;         for (int tn = 0; tn < TN; tn++) acc[tm][tn] = MFMA(af[tm], bfr[tn], acc[tm][tn]);
;     }
;     __builtin_amdgcn_s_setprio(0);
;     __syncthreads();
;   }
	ds_read_b128 v[94:97], v68 offset:18432
	ds_read_b128 v[98:101], v68 offset:23040
	ds_read_b128 v[126:129], v1 offset:55296
	ds_read_b128 v[130:133], v1 offset:59904
	s_setprio 1
	ds_read_b128 v[86:89], v68 offset:18464
	s_waitcnt lgkmcnt(2)
	v_mfma_f32_32x32x16_bf16 v[34:49], v[94:97], v[126:129], v[34:49]
	ds_read_b128 v[90:93], v1 offset:55328
	s_waitcnt lgkmcnt(2)
	v_mfma_f32_32x32x16_bf16 v[50:65], v[94:97], v[130:133], v[50:65]
	s_waitcnt vmcnt(7)
	ds_write_b128 v66, v[140:143]
	s_waitcnt vmcnt(6)
	ds_write_b128 v66, v[102:105] offset:4608
	global_load_dwordx4 v[140:143], v[72:73], off offset:1408
	global_load_dwordx4 v[102:105], v[70:71], off offset:1408
	ds_read_b128 v[94:97], v1 offset:59936
	s_waitcnt lgkmcnt(3)
	v_mfma_f32_32x32x16_bf16 v[34:49], v[86:89], v[90:93], v[34:49]
	s_waitcnt lgkmcnt(0)
	v_mfma_f32_32x32x16_bf16 v[50:65], v[86:89], v[94:97], v[50:65]
	ds_read_b128 v[86:89], v68 offset:23072
	v_mfma_f32_32x32x16_bf16 v[2:17], v[98:101], v[126:129], v[2:17]
	v_mfma_f32_32x32x16_bf16 v[18:33], v[98:101], v[130:133], v[18:33]
	s_waitcnt vmcnt(7)
	ds_write_b128 v66, v[106:109] offset:9216
	s_waitcnt vmcnt(6)
	ds_write_b128 v66, v[110:113] offset:13824
	global_load_dwordx4 v[106:109], v[74:75], off offset:1408
	global_load_dwordx4 v[110:113], v[76:77], off offset:1408
	ds_read_b128 v[98:101], v68 offset:23136
	s_waitcnt lgkmcnt(3)
	v_mfma_f32_32x32x16_bf16 v[2:17], v[86:89], v[90:93], v[2:17]
	ds_read_b128 v[90:93], v1 offset:55360
	v_mfma_f32_32x32x16_bf16 v[18:33], v[86:89], v[94:97], v[18:33]
	ds_read_b128 v[86:89], v68 offset:18496
	ds_read_b128 v[94:97], v1 offset:59968
	s_waitcnt lgkmcnt(1)
	v_mfma_f32_32x32x16_bf16 v[34:49], v[86:89], v[90:93], v[34:49]
	s_waitcnt lgkmcnt(0)
	v_mfma_f32_32x32x16_bf16 v[50:65], v[86:89], v[94:97], v[50:65]
	s_waitcnt vmcnt(7)
	ds_write_b128 v66, v[144:147] offset:36864
	s_waitcnt vmcnt(6)
	ds_write_b128 v66, v[122:125] offset:41472
	global_load_dwordx4 v[144:147], v[78:79], off offset:1408
	global_load_dwordx4 v[122:125], v[80:81], off offset:1408
	ds_read_b128 v[86:89], v68 offset:23104
	s_waitcnt lgkmcnt(0)
	v_mfma_f32_32x32x16_bf16 v[2:17], v[86:89], v[90:93], v[2:17]
	ds_read_b128 v[90:93], v1 offset:55392
	v_mfma_f32_32x32x16_bf16 v[18:33], v[86:89], v[94:97], v[18:33]
	ds_read_b128 v[86:89], v68 offset:18528
	ds_read_b128 v[94:97], v1 offset:60000
	s_waitcnt lgkmcnt(1)
	v_mfma_f32_32x32x16_bf16 v[34:49], v[86:89], v[90:93], v[34:49]
	s_waitcnt lgkmcnt(0)
	v_mfma_f32_32x32x16_bf16 v[50:65], v[86:89], v[94:97], v[50:65]
	s_waitcnt vmcnt(7)
	ds_write_b128 v66, v[118:121] offset:46080
	s_waitcnt vmcnt(6)
	ds_write_b128 v66, v[114:117] offset:50688
	global_load_dwordx4 v[118:121], v[82:83], off offset:1408
	global_load_dwordx4 v[114:117], v[84:85], off offset:1408
	v_mfma_f32_32x32x16_bf16 v[2:17], v[98:101], v[90:93], v[2:17]
	v_mfma_f32_32x32x16_bf16 v[18:33], v[98:101], v[94:97], v[18:33]
	s_setprio 0
	s_waitcnt lgkmcnt(0)
	s_barrier
	ds_read_b128 v[94:97], v68
	ds_read_b128 v[98:101], v68 offset:4608
	ds_read_b128 v[126:129], v1 offset:36864
	ds_read_b128 v[130:133], v1 offset:41472
	s_setprio 1
	ds_read_b128 v[86:89], v68 offset:32
	s_waitcnt lgkmcnt(2)
	v_mfma_f32_32x32x16_bf16 v[34:49], v[94:97], v[126:129], v[34:49]
	ds_read_b128 v[90:93], v1 offset:36896
	s_waitcnt lgkmcnt(2)
	v_mfma_f32_32x32x16_bf16 v[50:65], v[94:97], v[130:133], v[50:65]
	s_waitcnt vmcnt(7)
	ds_write_b128 v66, v[140:143] offset:18432
	s_waitcnt vmcnt(6)
	ds_write_b128 v66, v[102:105] offset:23040
	global_load_dwordx4 v[140:143], v[72:73], off offset:1536
	global_load_dwordx4 v[102:105], v[70:71], off offset:1536
	ds_read_b128 v[94:97], v1 offset:41504
	s_waitcnt lgkmcnt(3)
	v_mfma_f32_32x32x16_bf16 v[34:49], v[86:89], v[90:93], v[34:49]
	s_waitcnt lgkmcnt(0)
	v_mfma_f32_32x32x16_bf16 v[50:65], v[86:89], v[94:97], v[50:65]
	ds_read_b128 v[86:89], v68 offset:4640
	v_mfma_f32_32x32x16_bf16 v[2:17], v[98:101], v[126:129], v[2:17]
	v_mfma_f32_32x32x16_bf16 v[18:33], v[98:101], v[130:133], v[18:33]
	s_waitcnt vmcnt(7)
	ds_write_b128 v66, v[106:109] offset:27648
	s_waitcnt vmcnt(6)
	ds_write_b128 v66, v[110:113] offset:32256
	global_load_dwordx4 v[106:109], v[74:75], off offset:1536
	global_load_dwordx4 v[110:113], v[76:77], off offset:1536
	ds_read_b128 v[98:101], v68 offset:4704
	s_waitcnt lgkmcnt(3)
	v_mfma_f32_32x32x16_bf16 v[2:17], v[86:89], v[90:93], v[2:17]
	ds_read_b128 v[90:93], v1 offset:36928
	v_mfma_f32_32x32x16_bf16 v[18:33], v[86:89], v[94:97], v[18:33]
	ds_read_b128 v[86:89], v68 offset:64
	ds_read_b128 v[94:97], v1 offset:41536
	s_waitcnt lgkmcnt(1)
	v_mfma_f32_32x32x16_bf16 v[34:49], v[86:89], v[90:93], v[34:49]
	s_waitcnt lgkmcnt(0)
	v_mfma_f32_32x32x16_bf16 v[50:65], v[86:89], v[94:97], v[50:65]
	s_waitcnt vmcnt(7)
	ds_write_b128 v66, v[144:147] offset:55296
	s_waitcnt vmcnt(6)
	ds_write_b128 v66, v[122:125] offset:59904
	global_load_dwordx4 v[144:147], v[78:79], off offset:1536
	global_load_dwordx4 v[122:125], v[80:81], off offset:1536
	ds_read_b128 v[86:89], v68 offset:4672
	s_waitcnt lgkmcnt(0)
	v_mfma_f32_32x32x16_bf16 v[2:17], v[86:89], v[90:93], v[2:17]
	ds_read_b128 v[90:93], v1 offset:36960
	v_mfma_f32_32x32x16_bf16 v[18:33], v[86:89], v[94:97], v[18:33]
	ds_read_b128 v[86:89], v68 offset:96
	ds_read_b128 v[94:97], v1 offset:41568
	s_waitcnt lgkmcnt(1)
	v_mfma_f32_32x32x16_bf16 v[34:49], v[86:89], v[90:93], v[34:49]
	s_waitcnt lgkmcnt(0)
	v_mfma_f32_32x32x16_bf16 v[50:65], v[86:89], v[94:97], v[50:65]
	s_waitcnt vmcnt(7)
	ds_write_b128 v66, v[118:121] offset:64512
	s_waitcnt vmcnt(6)
	ds_write_b128 v69, v[114:117] offset:32256
	global_load_dwordx4 v[118:121], v[82:83], off offset:1536
	global_load_dwordx4 v[114:117], v[84:85], off offset:1536
	v_mfma_f32_32x32x16_bf16 v[2:17], v[98:101], v[90:93], v[2:17]
	v_mfma_f32_32x32x16_bf16 v[18:33], v[98:101], v[94:97], v[18:33]
	s_setprio 0
	s_waitcnt lgkmcnt(0)
	s_barrier
; #define MFMA(a, b, c) __builtin_amdgcn_mfma_f32_32x32x16_bf16((a), (b), (c), 0, 0, 0)
; template <int TM, int TN>
; DI void gemm_mainloop(const u16* __restrict__ A, long lda, const u16* __restrict__ Bt, long ldb, int K, char* smem,
;                       f32x16 (&acc)[TM][TN]) {
;     ...
;   for (int kt = 0; kt < nk; kt++) {
;     const int buf = kt & 1;
;     const u16* cA = sA + buf * BM * LD + (wm * 32 * TM + r) * LD + h * 8;
;     const u16* cB = sB + buf * BN * LD + (wn * 32 * TN + r) * LD + h * 8;
;     bf16x8 af[TM], bfr[TN];
; #pragma unroll
;     for (int tm = 0; tm < TM; tm++) af[tm] = *(const bf16x8*)(cA + tm * 32 * LD);
; #pragma unroll
;     for (int tn = 0; tn < TN; tn++) bfr[tn] = *(const bf16x8*)(cB + tn * 32 * LD);
;     if (kt + 1 < nk) GEMM_SSTORE(buf ^ 1)
;     __builtin_amdgcn_sched_barrier(0);
;     __builtin_amdgcn_s_setprio(1);
; #pragma unroll
;     for (int tm = 0; tm < TM; tm++)
; #pragma unroll
;       for (int tn = 0; tn < TN; tn++) acc[tm][tn] = MFMA(af[tm], bfr[tn], acc[tm][tn]);
; #pragma unroll
;     for (int tm = 0; tm < TM; tm++) af[tm] = *(const bf16x8*)(cA + tm * 32 * LD + 16);
; #pragma unroll
;     for (int tn = 0; tn < TN; tn++) bfr[tn] = *(const bf16x8*)(cB + tn * 32 * LD + 16);
; #pragma unroll
;     for (int tm = 0; tm < TM; tm++)
; #pragma unroll
;       for (int tn = 0; tn < TN; tn++) acc[tm][tn] = MFMA(af[tm], bfr[tn], acc[tm][tn]);
;     __builtin_amdgcn_sched_group_barrier(0x8, 4, 0);
;     if (kt + 2 < nk) GEMM_GLOAD((kt + 2) * 64)
; #pragma unroll
;     for (int ks = 2; ks < 4; ks++) {
; #pragma unroll
;       for (int tm = 0; tm < TM; tm++) af[tm] = *(const bf16x8*)(cA + tm * 32 * LD + ks * 16);
; #pragma unroll
;       for (int tn = 0; tn < TN; tn++) bfr[tn] = *(const bf16x8*)(cB + tn * 32 * LD + ks * 16);
; #pragma unroll
;       for (int tm = 0; tm < TM; tm++)
; #pragma unroll
;         for (int tn = 0; tn < TN; tn++) acc[tm][tn] = MFMA(af[tm], bfr[tn], acc[tm][tn]);
;     }
;     __builtin_amdgcn_s_setprio(0);
;     __syncthreads();
;   }
	ds_read_b128 v[94:97], v68 offset:18432
	ds_read_b128 v[98:101], v68 offset:23040
	ds_read_b128 v[126:129], v1 offset:55296
	ds_read_b128 v[130:133], v1 offset:59904
	s_setprio 1
	ds_read_b128 v[86:89], v68 offset:18464
	s_waitcnt lgkmcnt(2)
	v_mfma_f32_32x32x16_bf16 v[34:49], v[94:97], v[126:129], v[34:49]
	ds_read_b128 v[90:93], v1 offset:55328
	s_waitcnt lgkmcnt(2)
	v_mfma_f32_32x32x16_bf16 v[50:65], v[94:97], v[130:133], v[50:65]
	s_waitcnt vmcnt(7)
	ds_write_b128 v66, v[140:143]
	s_waitcnt vmcnt(6)
	ds_write_b128 v66, v[102:105] offset:4608
	global_load_dwordx4 v[140:143], v[72:73], off offset:1664
	global_load_dwordx4 v[102:105], v[70:71], off offset:1664
	ds_read_b128 v[94:97], v1 offset:59936
	s_waitcnt lgkmcnt(3)
	v_mfma_f32_32x32x16_bf16 v[34:49], v[86:89], v[90:93], v[34:49]
	s_waitcnt lgkmcnt(0)
	v_mfma_f32_32x32x16_bf16 v[50:65], v[86:89], v[94:97], v[50:65]
	ds_read_b128 v[86:89], v68 offset:23072
	v_mfma_f32_32x32x16_bf16 v[2:17], v[98:101], v[126:129], v[2:17]
	v_mfma_f32_32x32x16_bf16 v[18:33], v[98:101], v[130:133], v[18:33]
	s_waitcnt vmcnt(7)
	ds_write_b128 v66, v[106:109] offset:9216
	s_waitcnt vmcnt(6)
	ds_write_b128 v66, v[110:113] offset:13824
	global_load_dwordx4 v[106:109], v[74:75], off offset:1664
	global_load_dwordx4 v[110:113], v[76:77], off offset:1664
	ds_read_b128 v[98:101], v68 offset:23136
	s_waitcnt lgkmcnt(3)
	v_mfma_f32_32x32x16_bf16 v[2:17], v[86:89], v[90:93], v[2:17]
	ds_read_b128 v[90:93], v1 offset:55360
	v_mfma_f32_32x32x16_bf16 v[18:33], v[86:89], v[94:97], v[18:33]
	ds_read_b128 v[86:89], v68 offset:18496
	ds_read_b128 v[94:97], v1 offset:59968
	s_waitcnt lgkmcnt(1)
	v_mfma_f32_32x32x16_bf16 v[34:49], v[86:89], v[90:93], v[34:49]
	s_waitcnt lgkmcnt(0)
	v_mfma_f32_32x32x16_bf16 v[50:65], v[86:89], v[94:97], v[50:65]
	s_waitcnt vmcnt(7)
	ds_write_b128 v66, v[144:147] offset:36864
	s_waitcnt vmcnt(6)
	ds_write_b128 v66, v[122:125] offset:41472
	global_load_dwordx4 v[144:147], v[78:79], off offset:1664
	global_load_dwordx4 v[122:125], v[80:81], off offset:1664
	ds_read_b128 v[86:89], v68 offset:23104
	s_waitcnt lgkmcnt(0)
	v_mfma_f32_32x32x16_bf16 v[2:17], v[86:89], v[90:93], v[2:17]
	ds_read_b128 v[90:93], v1 offset:55392
	v_mfma_f32_32x32x16_bf16 v[18:33], v[86:89], v[94:97], v[18:33]
	ds_read_b128 v[86:89], v68 offset:18528
	ds_read_b128 v[94:97], v1 offset:60000
	s_waitcnt lgkmcnt(1)
	v_mfma_f32_32x32x16_bf16 v[34:49], v[86:89], v[90:93], v[34:49]
	s_waitcnt lgkmcnt(0)
	v_mfma_f32_32x32x16_bf16 v[50:65], v[86:89], v[94:97], v[50:65]
	s_waitcnt vmcnt(7)
	ds_write_b128 v66, v[118:121] offset:46080
	s_waitcnt vmcnt(6)
	ds_write_b128 v66, v[114:117] offset:50688
	global_load_dwordx4 v[118:121], v[82:83], off offset:1664
	global_load_dwordx4 v[114:117], v[84:85], off offset:1664
	v_mfma_f32_32x32x16_bf16 v[2:17], v[98:101], v[90:93], v[2:17]
	v_mfma_f32_32x32x16_bf16 v[18:33], v[98:101], v[94:97], v[18:33]
	s_setprio 0
	s_waitcnt lgkmcnt(0)
	s_barrier
	ds_read_b128 v[94:97], v68
	ds_read_b128 v[98:101], v68 offset:4608
	ds_read_b128 v[126:129], v1 offset:36864
	ds_read_b128 v[130:133], v1 offset:41472
	s_setprio 1
	ds_read_b128 v[86:89], v68 offset:32
	s_waitcnt lgkmcnt(2)
	v_mfma_f32_32x32x16_bf16 v[34:49], v[94:97], v[126:129], v[34:49]
	ds_read_b128 v[90:93], v1 offset:36896
	s_waitcnt lgkmcnt(2)
	v_mfma_f32_32x32x16_bf16 v[50:65], v[94:97], v[130:133], v[50:65]
	s_waitcnt vmcnt(7)
	ds_write_b128 v66, v[140:143] offset:18432
	s_waitcnt vmcnt(6)
	ds_write_b128 v66, v[102:105] offset:23040
	global_load_dwordx4 v[140:143], v[72:73], off offset:1792
	global_load_dwordx4 v[102:105], v[70:71], off offset:1792
	ds_read_b128 v[94:97], v1 offset:41504
	s_waitcnt lgkmcnt(3)
	v_mfma_f32_32x32x16_bf16 v[34:49], v[86:89], v[90:93], v[34:49]
	s_waitcnt lgkmcnt(0)
	v_mfma_f32_32x32x16_bf16 v[50:65], v[86:89], v[94:97], v[50:65]
	ds_read_b128 v[86:89], v68 offset:4640
	v_mfma_f32_32x32x16_bf16 v[2:17], v[98:101], v[126:129], v[2:17]
	v_mfma_f32_32x32x16_bf16 v[18:33], v[98:101], v[130:133], v[18:33]
	s_waitcnt vmcnt(7)
	ds_write_b128 v66, v[106:109] offset:27648
	s_waitcnt vmcnt(6)
	ds_write_b128 v66, v[110:113] offset:32256
	global_load_dwordx4 v[106:109], v[74:75], off offset:1792
	global_load_dwordx4 v[110:113], v[76:77], off offset:1792
	ds_read_b128 v[98:101], v68 offset:4704
	s_waitcnt lgkmcnt(3)
	v_mfma_f32_32x32x16_bf16 v[2:17], v[86:89], v[90:93], v[2:17]
	ds_read_b128 v[90:93], v1 offset:36928
	v_mfma_f32_32x32x16_bf16 v[18:33], v[86:89], v[94:97], v[18:33]
	ds_read_b128 v[86:89], v68 offset:64
	ds_read_b128 v[94:97], v1 offset:41536
	s_waitcnt lgkmcnt(1)
	v_mfma_f32_32x32x16_bf16 v[34:49], v[86:89], v[90:93], v[34:49]
	s_waitcnt lgkmcnt(0)
	v_mfma_f32_32x32x16_bf16 v[50:65], v[86:89], v[94:97], v[50:65]
	s_waitcnt vmcnt(7)
	ds_write_b128 v66, v[144:147] offset:55296
	s_waitcnt vmcnt(6)
	ds_write_b128 v66, v[122:125] offset:59904
	global_load_dwordx4 v[144:147], v[78:79], off offset:1792
	global_load_dwordx4 v[122:125], v[80:81], off offset:1792
	ds_read_b128 v[86:89], v68 offset:4672
	s_waitcnt lgkmcnt(0)
	v_mfma_f32_32x32x16_bf16 v[2:17], v[86:89], v[90:93], v[2:17]
	ds_read_b128 v[90:93], v1 offset:36960
	v_mfma_f32_32x32x16_bf16 v[18:33], v[86:89], v[94:97], v[18:33]
	ds_read_b128 v[86:89], v68 offset:96
	ds_read_b128 v[94:97], v1 offset:41568
	s_waitcnt lgkmcnt(1)
	v_mfma_f32_32x32x16_bf16 v[34:49], v[86:89], v[90:93], v[34:49]
	s_waitcnt lgkmcnt(0)
	v_mfma_f32_32x32x16_bf16 v[50:65], v[86:89], v[94:97], v[50:65]
	s_waitcnt vmcnt(7)
	ds_write_b128 v66, v[118:121] offset:64512
	s_waitcnt vmcnt(6)
	ds_write_b128 v69, v[114:117] offset:32256
	global_load_dwordx4 v[118:121], v[82:83], off offset:1792
	global_load_dwordx4 v[114:117], v[84:85], off offset:1792
	v_mfma_f32_32x32x16_bf16 v[2:17], v[98:101], v[90:93], v[2:17]
	v_mfma_f32_32x32x16_bf16 v[18:33], v[98:101], v[94:97], v[18:33]
	s_setprio 0
	s_waitcnt lgkmcnt(0)
	s_barrier
; #define MFMA(a, b, c) __builtin_amdgcn_mfma_f32_32x32x16_bf16((a), (b), (c), 0, 0, 0)
; template <int TM, int TN>
; DI void gemm_mainloop(const u16* __restrict__ A, long lda, const u16* __restrict__ Bt, long ldb, int K, char* smem,
;                       f32x16 (&acc)[TM][TN]) {
;     ...
;   for (int kt = 0; kt < nk; kt++) {
;     const int buf = kt & 1;
;     const u16* cA = sA + buf * BM * LD + (wm * 32 * TM + r) * LD + h * 8;
;     const u16* cB = sB + buf * BN * LD + (wn * 32 * TN + r) * LD + h * 8;
;     bf16x8 af[TM], bfr[TN];
; #pragma unroll
;     for (int tm = 0; tm < TM; tm++) af[tm] = *(const bf16x8*)(cA + tm * 32 * LD);
; #pragma unroll
;     for (int tn = 0; tn < TN; tn++) bfr[tn] = *(const bf16x8*)(cB + tn * 32 * LD);
;     if (kt + 1 < nk) GEMM_SSTORE(buf ^ 1)
;     __builtin_amdgcn_sched_barrier(0);
;     __builtin_amdgcn_s_setprio(1);
; #pragma unroll
;     for (int tm = 0; tm < TM; tm++)
; #pragma unroll
;       for (int tn = 0; tn < TN; tn++) acc[tm][tn] = MFMA(af[tm], bfr[tn], acc[tm][tn]);
; #pragma unroll
;     for (int tm = 0; tm < TM; tm++) af[tm] = *(const bf16x8*)(cA + tm * 32 * LD + 16);
; #pragma unroll
;     for (int tn = 0; tn < TN; tn++) bfr[tn] = *(const bf16x8*)(cB + tn * 32 * LD + 16);
; #pragma unroll
;     for (int tm = 0; tm < TM; tm++)
; #pragma unroll
;       for (int tn = 0; tn < TN; tn++) acc[tm][tn] = MFMA(af[tm], bfr[tn], acc[tm][tn]);
;     __builtin_amdgcn_sched_group_barrier(0x8, 4, 0);
;     if (kt + 2 < nk) GEMM_GLOAD((kt + 2) * 64)
; #pragma unroll
;     for (int ks = 2; ks < 4; ks++) {
; #pragma unroll
;       for (int tm = 0; tm < TM; tm++) af[tm] = *(const bf16x8*)(cA + tm * 32 * LD + ks * 16);
; #pragma unroll
;       for (int tn = 0; tn < TN; tn++) bfr[tn] = *(const bf16x8*)(cB + tn * 32 * LD + ks * 16);
; #pragma unroll
;       for (int tm = 0; tm < TM; tm++)
; #pragma unroll
;         for (int tn = 0; tn < TN; tn++) acc[tm][tn] = MFMA(af[tm], bfr[tn], acc[tm][tn]);
;     }
;     __builtin_amdgcn_s_setprio(0);
;     __syncthreads();
;   }
	ds_read_b128 v[94:97], v68 offset:18432
	ds_read_b128 v[98:101], v68 offset:23040
	ds_read_b128 v[126:129], v1 offset:55296
	ds_read_b128 v[130:133], v1 offset:59904
	s_setprio 1
	ds_read_b128 v[86:89], v68 offset:18464
	s_waitcnt lgkmcnt(2)
	v_mfma_f32_32x32x16_bf16 v[34:49], v[94:97], v[126:129], v[34:49]
	ds_read_b128 v[90:93], v1 offset:55328
	s_waitcnt lgkmcnt(2)
	v_mfma_f32_32x32x16_bf16 v[50:65], v[94:97], v[130:133], v[50:65]
	s_waitcnt vmcnt(7)
	ds_write_b128 v66, v[140:143]
	s_waitcnt vmcnt(6)
	ds_write_b128 v66, v[102:105] offset:4608
	global_load_dwordx4 v[140:143], v[72:73], off offset:1920
	global_load_dwordx4 v[102:105], v[70:71], off offset:1920
	ds_read_b128 v[94:97], v1 offset:59936
	s_waitcnt lgkmcnt(3)
	v_mfma_f32_32x32x16_bf16 v[34:49], v[86:89], v[90:93], v[34:49]
	s_waitcnt lgkmcnt(0)
	v_mfma_f32_32x32x16_bf16 v[50:65], v[86:89], v[94:97], v[50:65]
	ds_read_b128 v[86:89], v68 offset:23072
	v_mfma_f32_32x32x16_bf16 v[2:17], v[98:101], v[126:129], v[2:17]
	v_mfma_f32_32x32x16_bf16 v[18:33], v[98:101], v[130:133], v[18:33]
	s_waitcnt vmcnt(7)
	ds_write_b128 v66, v[106:109] offset:9216
	s_waitcnt vmcnt(6)
	ds_write_b128 v66, v[110:113] offset:13824
	global_load_dwordx4 v[106:109], v[74:75], off offset:1920
	global_load_dwordx4 v[110:113], v[76:77], off offset:1920
	ds_read_b128 v[98:101], v68 offset:23136
	s_waitcnt lgkmcnt(3)
	v_mfma_f32_32x32x16_bf16 v[2:17], v[86:89], v[90:93], v[2:17]
	ds_read_b128 v[90:93], v1 offset:55360
	v_mfma_f32_32x32x16_bf16 v[18:33], v[86:89], v[94:97], v[18:33]
	ds_read_b128 v[86:89], v68 offset:18496
	ds_read_b128 v[94:97], v1 offset:59968
	s_waitcnt lgkmcnt(1)
	v_mfma_f32_32x32x16_bf16 v[34:49], v[86:89], v[90:93], v[34:49]
	s_waitcnt lgkmcnt(0)
	v_mfma_f32_32x32x16_bf16 v[50:65], v[86:89], v[94:97], v[50:65]
	s_waitcnt vmcnt(7)
	ds_write_b128 v66, v[144:147] offset:36864
	s_waitcnt vmcnt(6)
	ds_write_b128 v66, v[122:125] offset:41472
	global_load_dwordx4 v[144:147], v[78:79], off offset:1920
	global_load_dwordx4 v[122:125], v[80:81], off offset:1920
	ds_read_b128 v[86:89], v68 offset:23104
	s_waitcnt lgkmcnt(0)
	v_mfma_f32_32x32x16_bf16 v[2:17], v[86:89], v[90:93], v[2:17]
	ds_read_b128 v[90:93], v1 offset:55392
	v_mfma_f32_32x32x16_bf16 v[18:33], v[86:89], v[94:97], v[18:33]
	ds_read_b128 v[86:89], v68 offset:18528
	ds_read_b128 v[94:97], v1 offset:60000
	s_waitcnt lgkmcnt(1)
	v_mfma_f32_32x32x16_bf16 v[34:49], v[86:89], v[90:93], v[34:49]
	s_waitcnt lgkmcnt(0)
	v_mfma_f32_32x32x16_bf16 v[50:65], v[86:89], v[94:97], v[50:65]
	s_waitcnt vmcnt(7)
	ds_write_b128 v66, v[118:121] offset:46080
	s_waitcnt vmcnt(6)
	ds_write_b128 v66, v[114:117] offset:50688
	global_load_dwordx4 v[118:121], v[82:83], off offset:1920
	global_load_dwordx4 v[114:117], v[84:85], off offset:1920
	s_nop 0
	v_mfma_f32_32x32x16_bf16 v[2:17], v[98:101], v[90:93], v[2:17]
	v_mfma_f32_32x32x16_bf16 v[18:33], v[98:101], v[94:97], v[18:33]
	s_setprio 0
	s_waitcnt lgkmcnt(0)
	s_barrier
	ds_read_b128 v[74:77], v68
	ds_read_b128 v[78:81], v68 offset:4608
	ds_read_b128 v[82:85], v1 offset:36864
	ds_read_b128 v[90:93], v1 offset:41472
	s_setprio 1
	ds_read_b128 v[70:73], v68 offset:32
	s_waitcnt lgkmcnt(2)
	v_mfma_f32_32x32x16_bf16 v[34:49], v[74:77], v[82:85], v[34:49]
	s_waitcnt lgkmcnt(1)
	v_mfma_f32_32x32x16_bf16 v[50:65], v[74:77], v[90:93], v[50:65]
	s_waitcnt vmcnt(7)
	ds_write_b128 v66, v[140:143] offset:18432
	s_waitcnt vmcnt(6)
	ds_write_b128 v66, v[102:105] offset:23040
	ds_read_b128 v[74:77], v1 offset:36896
	v_mfma_f32_32x32x16_bf16 v[2:17], v[78:81], v[82:85], v[2:17]
	v_mfma_f32_32x32x16_bf16 v[18:33], v[78:81], v[90:93], v[18:33]
	ds_read_b128 v[78:81], v1 offset:41504
	s_waitcnt lgkmcnt(1)
	v_mfma_f32_32x32x16_bf16 v[34:49], v[70:73], v[74:77], v[34:49]
	s_waitcnt lgkmcnt(0)
	v_mfma_f32_32x32x16_bf16 v[50:65], v[70:73], v[78:81], v[50:65]
	s_waitcnt vmcnt(5)
	ds_write_b128 v66, v[106:109] offset:27648
	s_waitcnt vmcnt(4)
	ds_write_b128 v66, v[110:113] offset:32256
	ds_read_b128 v[70:73], v68 offset:4640
	s_waitcnt lgkmcnt(0)
	v_mfma_f32_32x32x16_bf16 v[2:17], v[70:73], v[74:77], v[2:17]
	ds_read_b128 v[74:77], v1 offset:36928
	v_mfma_f32_32x32x16_bf16 v[18:33], v[70:73], v[78:81], v[18:33]
	ds_read_b128 v[70:73], v68 offset:64
	ds_read_b128 v[78:81], v1 offset:41536
	s_waitcnt lgkmcnt(1)
	v_mfma_f32_32x32x16_bf16 v[34:49], v[70:73], v[74:77], v[34:49]
	s_waitcnt lgkmcnt(0)
	v_mfma_f32_32x32x16_bf16 v[50:65], v[70:73], v[78:81], v[50:65]
	s_waitcnt vmcnt(3)
	ds_write_b128 v66, v[144:147] offset:55296
	s_waitcnt vmcnt(2)
	ds_write_b128 v66, v[122:125] offset:59904
	ds_read_b128 v[70:73], v68 offset:4672
	s_waitcnt lgkmcnt(0)
	v_mfma_f32_32x32x16_bf16 v[2:17], v[70:73], v[74:77], v[2:17]
	ds_read_b128 v[74:77], v1 offset:36960
	v_mfma_f32_32x32x16_bf16 v[18:33], v[70:73], v[78:81], v[18:33]
	ds_read_b128 v[70:73], v68 offset:96
	ds_read_b128 v[78:81], v1 offset:41568
	s_waitcnt lgkmcnt(1)
	v_mfma_f32_32x32x16_bf16 v[34:49], v[70:73], v[74:77], v[34:49]
	s_waitcnt lgkmcnt(0)
	v_mfma_f32_32x32x16_bf16 v[50:65], v[70:73], v[78:81], v[50:65]
	s_waitcnt vmcnt(1)
	ds_write_b128 v66, v[118:121] offset:64512
	s_waitcnt vmcnt(0)
	ds_write_b128 v69, v[114:117] offset:32256
	ds_read_b128 v[70:73], v68 offset:4704
	s_waitcnt lgkmcnt(0)
	v_mfma_f32_32x32x16_bf16 v[2:17], v[70:73], v[74:77], v[2:17]
	v_mfma_f32_32x32x16_bf16 v[18:33], v[70:73], v[78:81], v[18:33]
	s_setprio 0
	s_barrier
; #define MFMA(a, b, c) __builtin_amdgcn_mfma_f32_32x32x16_bf16((a), (b), (c), 0, 0, 0)
; DI int crow(int i, int h) { return (i & 3) + 8 * (i >> 2) + 4 * h; }
; template <int TM, int TN>
; DI void gemm_mainloop(const u16* __restrict__ A, long lda, const u16* __restrict__ Bt, long ldb, int K, char* smem,
;                       f32x16 (&acc)[TM][TN]) {
;     ...
;     for (int tm = 0; tm < TM; tm++)
; #pragma unroll
;       for (int tn = 0; tn < TN; tn++) acc[tm][tn] = MFMA(af[tm], bfr[tn], acc[tm][tn]);
;     __builtin_amdgcn_sched_group_barrier(0x8, 4, 0);
;     if (kt + 2 < nk) GEMM_GLOAD((kt + 2) * 64)
; #pragma unroll
;     for (int ks = 2; ks < 4; ks++) {
; #pragma unroll
;       for (int tm = 0; tm < TM; tm++) af[tm] = *(const bf16x8*)(cA + tm * 32 * LD + ks * 16);
; #pragma unroll
;       for (int tn = 0; tn < TN; tn++) bfr[tn] = *(const bf16x8*)(cB + tn * 32 * LD + ks * 16);
; #pragma unroll
;       for (int tm = 0; tm < TM; tm++)
; #pragma unroll
;         for (int tn = 0; tn < TN; tn++) acc[tm][tn] = MFMA(af[tm], bfr[tn], acc[tm][tn]);
;     }
;     __builtin_amdgcn_s_setprio(0);
;     __syncthreads();
;   }
; template <int TM, int TN, class Epi>
; DI void gemm_tile(const u16* A, long lda, const u16* Bt, long ldb, int K, int m0, int n0, char* smem, const Epi& epi) {
;     ...
; #pragma unroll
;   for (int tm = 0; tm < TM; tm++)
; #pragma unroll
;     for (int tn = 0; tn < TN; tn++)
; #pragma unroll
;       for (int i = 0; i < 16; i++)
;         Ct[(wm * 32 * TM + tm * 32 + crow(i, h)) * LDC + wn * 32 * TN + tn * 32 + r] = acc[tm][tn][i];
;   __syncthreads();
;   epi(Ct, LDC, m0, n0, tid, BM);
	ds_read_b128 v[70:73], v68 offset:18432
	ds_read_b128 v[74:77], v68 offset:23040
	ds_read_b128 v[78:81], v1 offset:55296
	ds_read_b128 v[82:85], v1 offset:59904
	s_setprio 1
	s_waitcnt lgkmcnt(1)
	v_mfma_f32_32x32x16_bf16 v[34:49], v[70:73], v[78:81], v[34:49]
	s_waitcnt lgkmcnt(0)
	v_mfma_f32_32x32x16_bf16 v[50:65], v[70:73], v[82:85], v[50:65]
	ds_read_b128 v[70:73], v68 offset:18464
	v_mfma_f32_32x32x16_bf16 v[2:17], v[74:77], v[78:81], v[2:17]
	ds_read_b128 v[78:81], v1 offset:59936
	v_mfma_f32_32x32x16_bf16 v[18:33], v[74:77], v[82:85], v[18:33]
	ds_read_b128 v[74:77], v1 offset:55328
	s_waitcnt lgkmcnt(0)
	v_mfma_f32_32x32x16_bf16 v[34:49], v[70:73], v[74:77], v[34:49]
	v_mfma_f32_32x32x16_bf16 v[50:65], v[70:73], v[78:81], v[50:65]
	ds_read_b128 v[70:73], v68 offset:23072
	s_waitcnt lgkmcnt(0)
	v_mfma_f32_32x32x16_bf16 v[2:17], v[70:73], v[74:77], v[2:17]
	ds_read_b128 v[74:77], v1 offset:55360
	v_mfma_f32_32x32x16_bf16 v[18:33], v[70:73], v[78:81], v[18:33]
	ds_read_b128 v[70:73], v68 offset:18496
	ds_read_b128 v[78:81], v1 offset:59968
	s_waitcnt lgkmcnt(1)
	v_mfma_f32_32x32x16_bf16 v[34:49], v[70:73], v[74:77], v[34:49]
	s_waitcnt lgkmcnt(0)
	v_mfma_f32_32x32x16_bf16 v[50:65], v[70:73], v[78:81], v[50:65]
	ds_read_b128 v[70:73], v68 offset:23104
	s_waitcnt lgkmcnt(0)
	v_mfma_f32_32x32x16_bf16 v[2:17], v[70:73], v[74:77], v[2:17]
	ds_read_b128 v[74:77], v1 offset:55392
	v_mfma_f32_32x32x16_bf16 v[18:33], v[70:73], v[78:81], v[18:33]
	ds_read_b128 v[70:73], v68 offset:18528
	ds_read_b128 v[78:81], v1 offset:60000
	s_waitcnt lgkmcnt(1)
	v_mfma_f32_32x32x16_bf16 v[34:49], v[70:73], v[74:77], v[34:49]
	s_waitcnt lgkmcnt(0)
	v_mfma_f32_32x32x16_bf16 v[50:65], v[70:73], v[78:81], v[50:65]
	ds_read_b128 v[68:71], v68 offset:23136
	s_waitcnt lgkmcnt(0)
	v_mfma_f32_32x32x16_bf16 v[2:17], v[68:71], v[74:77], v[2:17]
	v_mfma_f32_32x32x16_bf16 v[18:33], v[68:71], v[78:81], v[18:33]
	s_setprio 0
	v_mov_b32_e32 v1, v0
	s_barrier
	s_mov_b32 s38, 0
	v_lshrrev_b32_e32 v66, 1, v1
	v_and_b32_e32 v66, 0xfffffc0, v66
	v_lshrrev_b32_e32 v68, 3, v1
	v_and_or_b32 v66, v68, 4, v66
	v_and_b32_e32 v68, 0x5f, v1
	v_mul_lo_u32 v66, v66, s28
	v_lshl_add_u32 v66, v68, 2, v66
	ds_write2_b32 v66, v34, v50 offset1:32
	v_add_u32_e32 v34, 0x400, v66
	ds_write2_b32 v34, v36, v52 offset0:8 offset1:40
	ds_write2_b32 v34, v37, v53 offset0:140 offset1:172
	v_add_u32_e32 v34, 0x1000, v66
	ds_write2_b32 v34, v38, v54 offset0:32 offset1:64
	ds_write2_b32 v34, v39, v55 offset0:164 offset1:196
	v_add_u32_e32 v34, 0x1400, v66
	ds_write2_b32 v34, v40, v56 offset0:40 offset1:72
	ds_write2_b32 v34, v41, v57 offset0:172 offset1:204
	v_add_u32_e32 v34, 0x2000, v66
	ds_write2_b32 v34, v42, v58 offset0:64 offset1:96
	ds_write2_b32 v34, v43, v59 offset0:196 offset1:228
	v_add_u32_e32 v34, 0x2400, v66
	ds_write2_b32 v34, v44, v60 offset0:72 offset1:104
	ds_write2_b32 v34, v45, v61 offset0:204 offset1:236
	v_add_u32_e32 v34, 0x3000, v66
	ds_write2_b32 v34, v46, v62 offset0:96 offset1:128
	v_add_u32_e32 v34, 0x3200, v66
	ds_write2_b32 v34, v47, v63 offset0:100 offset1:132
	v_add_u32_e32 v34, 0x3400, v66
	ds_write2_b32 v34, v48, v64 offset0:104 offset1:136
	v_add_u32_e32 v34, 0x3600, v66
	ds_write2_b32 v34, v49, v65 offset0:108 offset1:140
	v_add_u32_e32 v34, 0x4000, v66
	ds_write2_b32 v34, v2, v18 offset0:128 offset1:160
	v_add_u32_e32 v2, 0x4400, v66
	ds_write2_b32 v2, v3, v19 offset0:4 offset1:36
	ds_write2_b32 v2, v4, v20 offset0:136 offset1:168
	v_add_u32_e32 v2, 0x4800, v66
	ds_write2_b32 v2, v5, v21 offset0:12 offset1:44
	v_add_u32_e32 v2, 0x5000, v66
	ds_write2_b32 v2, v6, v22 offset0:160 offset1:192
	v_add_u32_e32 v2, 0x5400, v66
	ds_write2_b32 v2, v7, v23 offset0:36 offset1:68
	ds_write2_b32 v2, v8, v24 offset0:168 offset1:200
	v_add_u32_e32 v2, 0x5800, v66
	ds_write2_b32 v2, v9, v25 offset0:44 offset1:76
	v_add_u32_e32 v2, 0x6000, v66
	ds_write2_b32 v2, v10, v26 offset0:192 offset1:224
	v_add_u32_e32 v2, 0x6400, v66
	ds_write2_b32 v2, v11, v27 offset0:68 offset1:100
	ds_write2_b32 v2, v12, v28 offset0:200 offset1:232
	v_add_u32_e32 v2, 0x6800, v66
	ds_write2_b32 v2, v13, v29 offset0:76 offset1:108
	v_add_u32_e32 v2, 0x7200, v66
	ds_write2_b32 v2, v14, v30 offset0:96 offset1:128
	v_add_u32_e32 v2, 0x7400, v66
	ds_write2_b32 v2, v15, v31 offset0:100 offset1:132
	v_add_u32_e32 v2, 0x7600, v66
	ds_write2_b32 v2, v16, v32 offset0:104 offset1:136
	v_add_u32_e32 v2, 0x7800, v66
	ds_write2_b32 v2, v17, v33 offset0:108 offset1:140
	v_lshlrev_b32_e32 v2, 3, v1
	v_and_b32_e32 v3, 0x78, v2
	v_or_b32_e32 v2, s4, v3
	v_lshlrev_b32_e32 v10, 2, v3
	v_ashrrev_i32_e32 v3, 31, v2
	v_cmp_eq_u32_e32 vcc, s29, v2
	v_cmp_gt_i32_e64 s[4:5], s30, v2
	v_lshl_add_u64 v[12:13], v[2:3], 1, s[6:7]
	ds_write2_b32 v66, v35, v51 offset0:132 offset1:164
	s_waitcnt lgkmcnt(0)
	s_barrier
	s_branch .LBB0_148

; #define MFMA(a, b, c) __builtin_amdgcn_mfma_f32_32x32x16_bf16((a), (b), (c), 0, 0, 0)
; DI u16* wsb(const Params& p, size_t off) { return (u16*)(p.ws + off); }
; template <int TM, int TN>
; DI void gemm_mainloop(const u16* __restrict__ A, long lda, const u16* __restrict__ Bt, long ldb, int K, char* smem,
;                       f32x16 (&acc)[TM][TN]) {
;     ...
;   const int nk = K / 64;
;   const int lrow = tid >> 3, lch = (tid & 7) * 8;
;   const u16* gA = A + (long)lrow * lda + lch;
;   const u16* gB = Bt + (long)lrow * ldb + lch;
;   const int soff = lrow * LD + lch;
;     ...
;   GEMM_GLOAD(0)
;   __syncthreads();
;   GEMM_SSTORE(0)
;   if (nk > 1) GEMM_GLOAD(64)
;   __syncthreads();
;   for (int kt = 0; kt < nk; kt++) {
;     const int buf = kt & 1;
;     const u16* cA = sA + buf * BM * LD + (wm * 32 * TM + r) * LD + h * 8;
;     const u16* cB = sB + buf * BN * LD + (wn * 32 * TN + r) * LD + h * 8;
;     bf16x8 af[TM], bfr[TN];
; #pragma unroll
;     for (int tm = 0; tm < TM; tm++) af[tm] = *(const bf16x8*)(cA + tm * 32 * LD);
; #pragma unroll
;     for (int tn = 0; tn < TN; tn++) bfr[tn] = *(const bf16x8*)(cB + tn * 32 * LD);
;     if (kt + 1 < nk) GEMM_SSTORE(buf ^ 1)
;     __builtin_amdgcn_sched_barrier(0);
;     __builtin_amdgcn_s_setprio(1);
; #pragma unroll
;     for (int tm = 0; tm < TM; tm++)
; #pragma unroll
;       for (int tn = 0; tn < TN; tn++) acc[tm][tn] = MFMA(af[tm], bfr[tn], acc[tm][tn]);
; #pragma unroll
;     for (int tm = 0; tm < TM; tm++) af[tm] = *(const bf16x8*)(cA + tm * 32 * LD + 16);
; #pragma unroll
;     for (int tn = 0; tn < TN; tn++) bfr[tn] = *(const bf16x8*)(cB + tn * 32 * LD + 16);
; #pragma unroll
;     for (int tm = 0; tm < TM; tm++)
; #pragma unroll
;       for (int tn = 0; tn < TN; tn++) acc[tm][tn] = MFMA(af[tm], bfr[tn], acc[tm][tn]);
;     __builtin_amdgcn_sched_group_barrier(0x8, 4, 0);
;     if (kt + 2 < nk) GEMM_GLOAD((kt + 2) * 64)
; DI void phase_inproj(const Params& p, const Sched& sc, int l, char* smem) {
;     ...
;     for (int u = blockIdx.x; u < 128; u += gridDim.x) {
;       int l2 = u >> 6, which = (u >> 5) & 1, mt = (u >> 3) & 3, nt = u & 7;
;       const u16* W2 = wsb(p, WS_W) + (size_t)l2 * W_LAYER + (which ? W_XV : W_XK);
;       EpiF32 epi{p.out + (which ? O_PMEMV : O_PMEMK) + (size_t)l2 * 524288, 1024};
;       gemm_tile<2, 2>(wsb(p, WS_HM), LDA, W2, LDW, 1024, mt * 128, nt * 128, smem, epi);
.LBB0_159:
	s_ashr_i32 s22, s21, 6
	s_ashr_i32 s23, s22, 31
	s_mul_i32 s25, s22, 0x2168000
	s_mul_hi_i32 s24, s22, 0x2168000
	s_add_u32 s25, s10, s25
	s_addc_u32 s24, s11, s24
	s_bitcmp0_b32 s21, 5
	s_cselect_b32 s26, s5, 0xc88000
	s_cselect_b32 s27, s6, 0xb50e040
	s_add_u32 s28, s25, s26
	s_addc_u32 s29, s24, 0
	s_add_u32 s26, s8, s27
	s_addc_u32 s27, s9, 0
	s_lshl_b64 s[24:25], s[22:23], 21
	s_add_u32 s23, s26, s24
	s_addc_u32 s24, s27, s25
	s_lshl_b32 s22, s21, 4
	s_and_b32 s22, s22, 0x180
	s_lshl_b32 s25, s21, 7
	s_and_b32 s25, s25, 0x380
	s_mul_i32 s26, s22, 0x880
	s_add_u32 s26, s3, s26
	v_mov_b32_e32 v1, v0
	s_addc_u32 s27, s4, 0
	s_mul_i32 s30, s25, 0x880
	v_lshlrev_b32_e32 v2, 3, v1
	v_ashrrev_i32_e32 v68, 3, v1
	v_and_b32_e32 v69, 56, v2
	v_mov_b64_e32 v[2:3], s[26:27]
	v_mad_i64_i32 v[2:3], s[26:27], v68, s7, v[2:3]
	v_lshlrev_b32_e32 v66, 1, v69
	v_lshl_add_u64 v[72:73], v[2:3], 0, v[66:67]
	v_add_co_u32_e32 v70, vcc, s15, v72
	s_add_u32 s28, s28, s30
	s_nop 0
	v_addc_co_u32_e32 v71, vcc, 0, v73, vcc
	s_addc_u32 s29, s29, 0
	v_add_co_u32_e32 v74, vcc, s16, v72
	v_mov_b64_e32 v[2:3], s[28:29]
	s_nop 0
	v_addc_co_u32_e32 v75, vcc, 0, v73, vcc
	v_mad_i64_i32 v[18:19], s[26:27], v68, s7, v[2:3]
	v_add_co_u32_e32 v78, vcc, s17, v72
	v_lshl_add_u64 v[76:77], v[18:19], 0, v[66:67]
	s_nop 0
	v_addc_co_u32_e32 v79, vcc, 0, v73, vcc
	v_add_co_u32_e32 v80, vcc, s15, v76
	global_load_dwordx4 v[2:5], v[72:73], off
	s_nop 0
	v_addc_co_u32_e32 v81, vcc, 0, v77, vcc
	v_add_co_u32_e32 v82, vcc, s16, v76
	global_load_dwordx4 v[6:9], v[70:71], off
	s_nop 0
	v_addc_co_u32_e32 v83, vcc, 0, v77, vcc
	v_add_co_u32_e32 v84, vcc, s17, v76
	global_load_dwordx4 v[10:13], v[74:75], off
	s_nop 0
	v_addc_co_u32_e32 v85, vcc, 0, v77, vcc
	global_load_dwordx4 v[14:17], v[78:79], off
	global_load_dwordx4 v[18:21], v[76:77], off
	global_load_dwordx4 v[22:25], v[80:81], off
	global_load_dwordx4 v[26:29], v[82:83], off
	global_load_dwordx4 v[30:33], v[84:85], off
	s_barrier
	global_load_dwordx4 v[34:37], v[72:73], off offset:128
	global_load_dwordx4 v[38:41], v[70:71], off offset:128
	global_load_dwordx4 v[42:45], v[74:75], off offset:128
	global_load_dwordx4 v[46:49], v[78:79], off offset:128
	global_load_dwordx4 v[50:53], v[76:77], off offset:128
	global_load_dwordx4 v[54:57], v[80:81], off offset:128
	global_load_dwordx4 v[58:61], v[82:83], off offset:128
	global_load_dwordx4 v[62:65], v[84:85], off offset:128
	v_and_b32_e32 v66, 31, v1
	v_lshrrev_b32_e32 v86, 1, v1
	v_mul_lo_u32 v68, v68, s14
	v_and_or_b32 v87, v86, s18, v66
	v_and_b32_e32 v86, 16, v86
	v_add_lshl_u32 v66, v68, v69, 1
	v_mad_u64_u32 v[68:69], s[26:27], v87, s19, v[86:87]
	v_and_b32_e32 v1, 0x5f, v1
	v_mad_u32_u24 v1, v1, s19, v86
	v_add_u32_e32 v69, 0x9000, v66
	s_waitcnt vmcnt(15)
	ds_write_b128 v66, v[2:5]
	s_waitcnt vmcnt(14)
	ds_write_b128 v66, v[6:9] offset:4608
	s_waitcnt vmcnt(13)
	ds_write_b128 v66, v[10:13] offset:9216
	s_waitcnt vmcnt(12)
	ds_write_b128 v66, v[14:17] offset:13824
	s_waitcnt vmcnt(11)
	ds_write_b128 v66, v[18:21] offset:36864
	s_waitcnt vmcnt(10)
	ds_write_b128 v66, v[22:25] offset:41472
	s_waitcnt vmcnt(9)
	ds_write_b128 v66, v[26:29] offset:46080
	s_waitcnt vmcnt(8)
	ds_write_b128 v66, v[30:33] offset:50688
	s_waitcnt lgkmcnt(0)
	s_barrier
	ds_read_b128 v[2:5], v68
	ds_read_b128 v[18:21], v68 offset:4608
	ds_read_b128 v[6:9], v1 offset:36864
	ds_read_b128 v[22:25], v1 offset:41472
	s_waitcnt vmcnt(7)
	ds_write_b128 v66, v[34:37] offset:18432
	s_waitcnt vmcnt(6)
	ds_write_b128 v66, v[38:41] offset:23040
	s_waitcnt vmcnt(5)
	ds_write_b128 v66, v[42:45] offset:27648
	s_waitcnt vmcnt(4)
	ds_write_b128 v66, v[46:49] offset:32256
	s_waitcnt vmcnt(3)
	ds_write_b128 v66, v[50:53] offset:55296
	s_waitcnt vmcnt(2)
	ds_write_b128 v66, v[54:57] offset:59904
	s_waitcnt vmcnt(1)
	ds_write_b128 v66, v[58:61] offset:64512
	s_waitcnt vmcnt(0)
	ds_write_b128 v69, v[62:65] offset:32256
	s_setprio 1
	ds_read_b128 v[86:89], v68 offset:32
	s_waitcnt lgkmcnt(10)
	v_mfma_f32_32x32x16_bf16 v[34:49], v[2:5], v[6:9], 0
	ds_read_b128 v[90:93], v1 offset:36896
	ds_read_b128 v[94:97], v1 offset:41504
	ds_read_b128 v[98:101], v68 offset:4704
	global_load_dwordx4 v[102:105], v[70:71], off offset:256
	global_load_dwordx4 v[106:109], v[74:75], off offset:256
	global_load_dwordx4 v[110:113], v[78:79], off offset:256
	global_load_dwordx4 v[114:117], v[84:85], off offset:256
	s_waitcnt lgkmcnt(12)
	v_mfma_f32_32x32x16_bf16 v[50:65], v[2:5], v[22:25], 0
	global_load_dwordx4 v[118:121], v[82:83], off offset:256
	global_load_dwordx4 v[122:125], v[80:81], off offset:256
	global_load_dwordx4 v[140:143], v[72:73], off offset:256
	global_load_dwordx4 v[144:147], v[76:77], off offset:256
	s_waitcnt lgkmcnt(2)
	v_mfma_f32_32x32x16_bf16 v[34:49], v[86:89], v[90:93], v[34:49]
	s_waitcnt lgkmcnt(1)
	v_mfma_f32_32x32x16_bf16 v[50:65], v[86:89], v[94:97], v[50:65]
	ds_read_b128 v[86:89], v68 offset:4640
	v_mfma_f32_32x32x16_bf16 v[2:17], v[18:21], v[6:9], 0
	v_mfma_f32_32x32x16_bf16 v[18:33], v[18:21], v[22:25], 0
	s_waitcnt lgkmcnt(0)
	v_mfma_f32_32x32x16_bf16 v[2:17], v[86:89], v[90:93], v[2:17]
	ds_read_b128 v[90:93], v1 offset:36928
	v_mfma_f32_32x32x16_bf16 v[18:33], v[86:89], v[94:97], v[18:33]
	ds_read_b128 v[86:89], v68 offset:64
	ds_read_b128 v[94:97], v1 offset:41536
	s_waitcnt lgkmcnt(1)
	v_mfma_f32_32x32x16_bf16 v[34:49], v[86:89], v[90:93], v[34:49]
	s_waitcnt lgkmcnt(0)
	v_mfma_f32_32x32x16_bf16 v[50:65], v[86:89], v[94:97], v[50:65]
	ds_read_b128 v[86:89], v68 offset:4672
	s_waitcnt lgkmcnt(0)
	v_mfma_f32_32x32x16_bf16 v[2:17], v[86:89], v[90:93], v[2:17]
	ds_read_b128 v[90:93], v1 offset:36960
	v_mfma_f32_32x32x16_bf16 v[18:33], v[86:89], v[94:97], v[18:33]
	ds_read_b128 v[86:89], v68 offset:96
	ds_read_b128 v[94:97], v1 offset:41568
	s_waitcnt lgkmcnt(1)
	v_mfma_f32_32x32x16_bf16 v[34:49], v[86:89], v[90:93], v[34:49]
	s_waitcnt lgkmcnt(0)
	v_mfma_f32_32x32x16_bf16 v[50:65], v[86:89], v[94:97], v[50:65]
	v_mfma_f32_32x32x16_bf16 v[2:17], v[98:101], v[90:93], v[2:17]
	v_mfma_f32_32x32x16_bf16 v[18:33], v[98:101], v[94:97], v[18:33]
	s_setprio 0
	s_barrier
; #define MFMA(a, b, c) __builtin_amdgcn_mfma_f32_32x32x16_bf16((a), (b), (c), 0, 0, 0)
; template <int TM, int TN>
; DI void gemm_mainloop(const u16* __restrict__ A, long lda, const u16* __restrict__ Bt, long ldb, int K, char* smem,
;                       f32x16 (&acc)[TM][TN]) {
;     ...
;   for (int kt = 0; kt < nk; kt++) {
;     const int buf = kt & 1;
;     const u16* cA = sA + buf * BM * LD + (wm * 32 * TM + r) * LD + h * 8;
;     const u16* cB = sB + buf * BN * LD + (wn * 32 * TN + r) * LD + h * 8;
;     bf16x8 af[TM], bfr[TN];
; #pragma unroll
;     for (int tm = 0; tm < TM; tm++) af[tm] = *(const bf16x8*)(cA + tm * 32 * LD);
; #pragma unroll
;     for (int tn = 0; tn < TN; tn++) bfr[tn] = *(const bf16x8*)(cB + tn * 32 * LD);
;     if (kt + 1 < nk) GEMM_SSTORE(buf ^ 1)
;     __builtin_amdgcn_sched_barrier(0);
;     __builtin_amdgcn_s_setprio(1);
; #pragma unroll
;     for (int tm = 0; tm < TM; tm++)
; #pragma unroll
;       for (int tn = 0; tn < TN; tn++) acc[tm][tn] = MFMA(af[tm], bfr[tn], acc[tm][tn]);
; #pragma unroll
;     for (int tm = 0; tm < TM; tm++) af[tm] = *(const bf16x8*)(cA + tm * 32 * LD + 16);
; #pragma unroll
;     for (int tn = 0; tn < TN; tn++) bfr[tn] = *(const bf16x8*)(cB + tn * 32 * LD + 16);
; #pragma unroll
;     for (int tm = 0; tm < TM; tm++)
; #pragma unroll
;       for (int tn = 0; tn < TN; tn++) acc[tm][tn] = MFMA(af[tm], bfr[tn], acc[tm][tn]);
;     __builtin_amdgcn_sched_group_barrier(0x8, 4, 0);
;     if (kt + 2 < nk) GEMM_GLOAD((kt + 2) * 64)
; #pragma unroll
;     for (int ks = 2; ks < 4; ks++) {
; #pragma unroll
;       for (int tm = 0; tm < TM; tm++) af[tm] = *(const bf16x8*)(cA + tm * 32 * LD + ks * 16);
; #pragma unroll
;       for (int tn = 0; tn < TN; tn++) bfr[tn] = *(const bf16x8*)(cB + tn * 32 * LD + ks * 16);
; #pragma unroll
;       for (int tm = 0; tm < TM; tm++)
; #pragma unroll
;         for (int tn = 0; tn < TN; tn++) acc[tm][tn] = MFMA(af[tm], bfr[tn], acc[tm][tn]);
;     }
;     __builtin_amdgcn_s_setprio(0);
;     __syncthreads();
;   }
	ds_read_b128 v[94:97], v68 offset:18432
	ds_read_b128 v[98:101], v68 offset:23040
	ds_read_b128 v[126:129], v1 offset:55296
	ds_read_b128 v[130:133], v1 offset:59904
	s_setprio 1
	ds_read_b128 v[86:89], v68 offset:18464
	s_waitcnt lgkmcnt(2)
	v_mfma_f32_32x32x16_bf16 v[34:49], v[94:97], v[126:129], v[34:49]
	ds_read_b128 v[90:93], v1 offset:55328
	s_waitcnt lgkmcnt(2)
	v_mfma_f32_32x32x16_bf16 v[50:65], v[94:97], v[130:133], v[50:65]
	s_waitcnt vmcnt(1)
	ds_write_b128 v66, v[140:143]
	ds_write_b128 v66, v[102:105] offset:4608
	global_load_dwordx4 v[140:143], v[72:73], off offset:384
	global_load_dwordx4 v[102:105], v[70:71], off offset:384
	ds_read_b128 v[94:97], v1 offset:59936
	s_waitcnt lgkmcnt(3)
	v_mfma_f32_32x32x16_bf16 v[34:49], v[86:89], v[90:93], v[34:49]
	s_waitcnt lgkmcnt(0)
	v_mfma_f32_32x32x16_bf16 v[50:65], v[86:89], v[94:97], v[50:65]
	ds_read_b128 v[86:89], v68 offset:23072
	v_mfma_f32_32x32x16_bf16 v[2:17], v[98:101], v[126:129], v[2:17]
	v_mfma_f32_32x32x16_bf16 v[18:33], v[98:101], v[130:133], v[18:33]
	ds_write_b128 v66, v[106:109] offset:9216
	ds_write_b128 v66, v[110:113] offset:13824
	global_load_dwordx4 v[106:109], v[74:75], off offset:384
	global_load_dwordx4 v[110:113], v[78:79], off offset:384
	ds_read_b128 v[98:101], v68 offset:23136
	s_waitcnt lgkmcnt(3)
	v_mfma_f32_32x32x16_bf16 v[2:17], v[86:89], v[90:93], v[2:17]
	ds_read_b128 v[90:93], v1 offset:55360
	v_mfma_f32_32x32x16_bf16 v[18:33], v[86:89], v[94:97], v[18:33]
	ds_read_b128 v[86:89], v68 offset:18496
	ds_read_b128 v[94:97], v1 offset:59968
	s_waitcnt lgkmcnt(1)
	v_mfma_f32_32x32x16_bf16 v[34:49], v[86:89], v[90:93], v[34:49]
	s_waitcnt lgkmcnt(0)
	v_mfma_f32_32x32x16_bf16 v[50:65], v[86:89], v[94:97], v[50:65]
	s_waitcnt vmcnt(4)
	ds_write_b128 v66, v[144:147] offset:36864
	ds_write_b128 v66, v[122:125] offset:41472
	global_load_dwordx4 v[144:147], v[76:77], off offset:384
	global_load_dwordx4 v[122:125], v[80:81], off offset:384
	ds_read_b128 v[86:89], v68 offset:23104
	s_waitcnt lgkmcnt(0)
	v_mfma_f32_32x32x16_bf16 v[2:17], v[86:89], v[90:93], v[2:17]
	ds_read_b128 v[90:93], v1 offset:55392
	v_mfma_f32_32x32x16_bf16 v[18:33], v[86:89], v[94:97], v[18:33]
	ds_read_b128 v[86:89], v68 offset:18528
	ds_read_b128 v[94:97], v1 offset:60000
	s_waitcnt lgkmcnt(1)
	v_mfma_f32_32x32x16_bf16 v[34:49], v[86:89], v[90:93], v[34:49]
	s_waitcnt lgkmcnt(0)
	v_mfma_f32_32x32x16_bf16 v[50:65], v[86:89], v[94:97], v[50:65]
	ds_write_b128 v66, v[118:121] offset:46080
	ds_write_b128 v66, v[114:117] offset:50688
	global_load_dwordx4 v[118:121], v[82:83], off offset:384
	global_load_dwordx4 v[114:117], v[84:85], off offset:384
	v_mfma_f32_32x32x16_bf16 v[2:17], v[98:101], v[90:93], v[2:17]
	v_mfma_f32_32x32x16_bf16 v[18:33], v[98:101], v[94:97], v[18:33]
	s_setprio 0
	s_waitcnt lgkmcnt(0)
	s_barrier
	ds_read_b128 v[94:97], v68
	ds_read_b128 v[98:101], v68 offset:4608
	ds_read_b128 v[126:129], v1 offset:36864
	ds_read_b128 v[130:133], v1 offset:41472
	s_setprio 1
	ds_read_b128 v[86:89], v68 offset:32
	s_waitcnt lgkmcnt(2)
	v_mfma_f32_32x32x16_bf16 v[34:49], v[94:97], v[126:129], v[34:49]
	ds_read_b128 v[90:93], v1 offset:36896
	s_waitcnt lgkmcnt(2)
	v_mfma_f32_32x32x16_bf16 v[50:65], v[94:97], v[130:133], v[50:65]
	s_waitcnt vmcnt(7)
	ds_write_b128 v66, v[140:143] offset:18432
	s_waitcnt vmcnt(6)
	ds_write_b128 v66, v[102:105] offset:23040
	global_load_dwordx4 v[140:143], v[72:73], off offset:512
	global_load_dwordx4 v[102:105], v[70:71], off offset:512
	ds_read_b128 v[94:97], v1 offset:41504
	s_waitcnt lgkmcnt(3)
	v_mfma_f32_32x32x16_bf16 v[34:49], v[86:89], v[90:93], v[34:49]
	s_waitcnt lgkmcnt(0)
	v_mfma_f32_32x32x16_bf16 v[50:65], v[86:89], v[94:97], v[50:65]
	ds_read_b128 v[86:89], v68 offset:4640
	v_mfma_f32_32x32x16_bf16 v[2:17], v[98:101], v[126:129], v[2:17]
	v_mfma_f32_32x32x16_bf16 v[18:33], v[98:101], v[130:133], v[18:33]
	s_waitcnt vmcnt(7)
	ds_write_b128 v66, v[106:109] offset:27648
	s_waitcnt vmcnt(6)
	ds_write_b128 v66, v[110:113] offset:32256
	global_load_dwordx4 v[106:109], v[74:75], off offset:512
	global_load_dwordx4 v[110:113], v[78:79], off offset:512
	ds_read_b128 v[98:101], v68 offset:4704
	s_waitcnt lgkmcnt(3)
	v_mfma_f32_32x32x16_bf16 v[2:17], v[86:89], v[90:93], v[2:17]
	ds_read_b128 v[90:93], v1 offset:36928
	v_mfma_f32_32x32x16_bf16 v[18:33], v[86:89], v[94:97], v[18:33]
	ds_read_b128 v[86:89], v68 offset:64
	ds_read_b128 v[94:97], v1 offset:41536
	s_waitcnt lgkmcnt(1)
	v_mfma_f32_32x32x16_bf16 v[34:49], v[86:89], v[90:93], v[34:49]
	s_waitcnt lgkmcnt(0)
	v_mfma_f32_32x32x16_bf16 v[50:65], v[86:89], v[94:97], v[50:65]
	s_waitcnt vmcnt(7)
	ds_write_b128 v66, v[144:147] offset:55296
	s_waitcnt vmcnt(6)
	ds_write_b128 v66, v[122:125] offset:59904
	global_load_dwordx4 v[144:147], v[76:77], off offset:512
	global_load_dwordx4 v[122:125], v[80:81], off offset:512
	ds_read_b128 v[86:89], v68 offset:4672
	s_waitcnt lgkmcnt(0)
	v_mfma_f32_32x32x16_bf16 v[2:17], v[86:89], v[90:93], v[2:17]
	ds_read_b128 v[90:93], v1 offset:36960
	v_mfma_f32_32x32x16_bf16 v[18:33], v[86:89], v[94:97], v[18:33]
	ds_read_b128 v[86:89], v68 offset:96
	ds_read_b128 v[94:97], v1 offset:41568
	s_waitcnt lgkmcnt(1)
	v_mfma_f32_32x32x16_bf16 v[34:49], v[86:89], v[90:93], v[34:49]
	s_waitcnt lgkmcnt(0)
	v_mfma_f32_32x32x16_bf16 v[50:65], v[86:89], v[94:97], v[50:65]
	s_waitcnt vmcnt(7)
	ds_write_b128 v66, v[118:121] offset:64512
	s_waitcnt vmcnt(6)
	ds_write_b128 v69, v[114:117] offset:32256
	global_load_dwordx4 v[118:121], v[82:83], off offset:512
	global_load_dwordx4 v[114:117], v[84:85], off offset:512
	v_mfma_f32_32x32x16_bf16 v[2:17], v[98:101], v[90:93], v[2:17]
	v_mfma_f32_32x32x16_bf16 v[18:33], v[98:101], v[94:97], v[18:33]
	s_setprio 0
	s_waitcnt lgkmcnt(0)
	s_barrier
; #define MFMA(a, b, c) __builtin_amdgcn_mfma_f32_32x32x16_bf16((a), (b), (c), 0, 0, 0)
; template <int TM, int TN>
; DI void gemm_mainloop(const u16* __restrict__ A, long lda, const u16* __restrict__ Bt, long ldb, int K, char* smem,
;                       f32x16 (&acc)[TM][TN]) {
;     ...
;   for (int kt = 0; kt < nk; kt++) {
;     const int buf = kt & 1;
;     const u16* cA = sA + buf * BM * LD + (wm * 32 * TM + r) * LD + h * 8;
;     const u16* cB = sB + buf * BN * LD + (wn * 32 * TN + r) * LD + h * 8;
;     bf16x8 af[TM], bfr[TN];
; #pragma unroll
;     for (int tm = 0; tm < TM; tm++) af[tm] = *(const bf16x8*)(cA + tm * 32 * LD);
; #pragma unroll
;     for (int tn = 0; tn < TN; tn++) bfr[tn] = *(const bf16x8*)(cB + tn * 32 * LD);
;     if (kt + 1 < nk) GEMM_SSTORE(buf ^ 1)
;     __builtin_amdgcn_sched_barrier(0);
;     __builtin_amdgcn_s_setprio(1);
; #pragma unroll
;     for (int tm = 0; tm < TM; tm++)
; #pragma unroll
;       for (int tn = 0; tn < TN; tn++) acc[tm][tn] = MFMA(af[tm], bfr[tn], acc[tm][tn]);
; #pragma unroll
;     for (int tm = 0; tm < TM; tm++) af[tm] = *(const bf16x8*)(cA + tm * 32 * LD + 16);
; #pragma unroll
;     for (int tn = 0; tn < TN; tn++) bfr[tn] = *(const bf16x8*)(cB + tn * 32 * LD + 16);
; #pragma unroll
;     for (int tm = 0; tm < TM; tm++)
; #pragma unroll
;       for (int tn = 0; tn < TN; tn++) acc[tm][tn] = MFMA(af[tm], bfr[tn], acc[tm][tn]);
;     __builtin_amdgcn_sched_group_barrier(0x8, 4, 0);
;     if (kt + 2 < nk) GEMM_GLOAD((kt + 2) * 64)
; #pragma unroll
;     for (int ks = 2; ks < 4; ks++) {
; #pragma unroll
;       for (int tm = 0; tm < TM; tm++) af[tm] = *(const bf16x8*)(cA + tm * 32 * LD + ks * 16);
; #pragma unroll
;       for (int tn = 0; tn < TN; tn++) bfr[tn] = *(const bf16x8*)(cB + tn * 32 * LD + ks * 16);
; #pragma unroll
;       for (int tm = 0; tm < TM; tm++)
; #pragma unroll
;         for (int tn = 0; tn < TN; tn++) acc[tm][tn] = MFMA(af[tm], bfr[tn], acc[tm][tn]);
;     }
;     __builtin_amdgcn_s_setprio(0);
;     __syncthreads();
;   }
	ds_read_b128 v[94:97], v68 offset:18432
	ds_read_b128 v[98:101], v68 offset:23040
	ds_read_b128 v[126:129], v1 offset:55296
	ds_read_b128 v[130:133], v1 offset:59904
	s_setprio 1
	ds_read_b128 v[86:89], v68 offset:18464
	s_waitcnt lgkmcnt(2)
	v_mfma_f32_32x32x16_bf16 v[34:49], v[94:97], v[126:129], v[34:49]
	ds_read_b128 v[90:93], v1 offset:55328
	s_waitcnt lgkmcnt(2)
	v_mfma_f32_32x32x16_bf16 v[50:65], v[94:97], v[130:133], v[50:65]
	s_waitcnt vmcnt(7)
	ds_write_b128 v66, v[140:143]
	s_waitcnt vmcnt(6)
	ds_write_b128 v66, v[102:105] offset:4608
	global_load_dwordx4 v[140:143], v[72:73], off offset:640
	global_load_dwordx4 v[102:105], v[70:71], off offset:640
	ds_read_b128 v[94:97], v1 offset:59936
	s_waitcnt lgkmcnt(3)
	v_mfma_f32_32x32x16_bf16 v[34:49], v[86:89], v[90:93], v[34:49]
	s_waitcnt lgkmcnt(0)
	v_mfma_f32_32x32x16_bf16 v[50:65], v[86:89], v[94:97], v[50:65]
	ds_read_b128 v[86:89], v68 offset:23072
	v_mfma_f32_32x32x16_bf16 v[2:17], v[98:101], v[126:129], v[2:17]
	v_mfma_f32_32x32x16_bf16 v[18:33], v[98:101], v[130:133], v[18:33]
	s_waitcnt vmcnt(7)
	ds_write_b128 v66, v[106:109] offset:9216
	s_waitcnt vmcnt(6)
	ds_write_b128 v66, v[110:113] offset:13824
	global_load_dwordx4 v[106:109], v[74:75], off offset:640
	global_load_dwordx4 v[110:113], v[78:79], off offset:640
	ds_read_b128 v[98:101], v68 offset:23136
	s_waitcnt lgkmcnt(3)
	v_mfma_f32_32x32x16_bf16 v[2:17], v[86:89], v[90:93], v[2:17]
	ds_read_b128 v[90:93], v1 offset:55360
	v_mfma_f32_32x32x16_bf16 v[18:33], v[86:89], v[94:97], v[18:33]
	ds_read_b128 v[86:89], v68 offset:18496
	ds_read_b128 v[94:97], v1 offset:59968
	s_waitcnt lgkmcnt(1)
	v_mfma_f32_32x32x16_bf16 v[34:49], v[86:89], v[90:93], v[34:49]
	s_waitcnt lgkmcnt(0)
	v_mfma_f32_32x32x16_bf16 v[50:65], v[86:89], v[94:97], v[50:65]
	s_waitcnt vmcnt(7)
	ds_write_b128 v66, v[144:147] offset:36864
	s_waitcnt vmcnt(6)
	ds_write_b128 v66, v[122:125] offset:41472
	global_load_dwordx4 v[144:147], v[76:77], off offset:640
	global_load_dwordx4 v[122:125], v[80:81], off offset:640
	ds_read_b128 v[86:89], v68 offset:23104
	s_waitcnt lgkmcnt(0)
	v_mfma_f32_32x32x16_bf16 v[2:17], v[86:89], v[90:93], v[2:17]
	ds_read_b128 v[90:93], v1 offset:55392
	v_mfma_f32_32x32x16_bf16 v[18:33], v[86:89], v[94:97], v[18:33]
	ds_read_b128 v[86:89], v68 offset:18528
	ds_read_b128 v[94:97], v1 offset:60000
	s_waitcnt lgkmcnt(1)
	v_mfma_f32_32x32x16_bf16 v[34:49], v[86:89], v[90:93], v[34:49]
	s_waitcnt lgkmcnt(0)
	v_mfma_f32_32x32x16_bf16 v[50:65], v[86:89], v[94:97], v[50:65]
	s_waitcnt vmcnt(7)
	ds_write_b128 v66, v[118:121] offset:46080
	s_waitcnt vmcnt(6)
	ds_write_b128 v66, v[114:117] offset:50688
	global_load_dwordx4 v[118:121], v[82:83], off offset:640
	global_load_dwordx4 v[114:117], v[84:85], off offset:640
	v_mfma_f32_32x32x16_bf16 v[2:17], v[98:101], v[90:93], v[2:17]
	v_mfma_f32_32x32x16_bf16 v[18:33], v[98:101], v[94:97], v[18:33]
	s_setprio 0
	s_waitcnt lgkmcnt(0)
	s_barrier
	ds_read_b128 v[94:97], v68
	ds_read_b128 v[98:101], v68 offset:4608
	ds_read_b128 v[126:129], v1 offset:36864
	ds_read_b128 v[130:133], v1 offset:41472
	s_setprio 1
	ds_read_b128 v[86:89], v68 offset:32
	s_waitcnt lgkmcnt(2)
	v_mfma_f32_32x32x16_bf16 v[34:49], v[94:97], v[126:129], v[34:49]
	ds_read_b128 v[90:93], v1 offset:36896
	s_waitcnt lgkmcnt(2)
	v_mfma_f32_32x32x16_bf16 v[50:65], v[94:97], v[130:133], v[50:65]
	s_waitcnt vmcnt(7)
	ds_write_b128 v66, v[140:143] offset:18432
	s_waitcnt vmcnt(6)
	ds_write_b128 v66, v[102:105] offset:23040
	global_load_dwordx4 v[140:143], v[72:73], off offset:768
	global_load_dwordx4 v[102:105], v[70:71], off offset:768
	ds_read_b128 v[94:97], v1 offset:41504
	s_waitcnt lgkmcnt(3)
	v_mfma_f32_32x32x16_bf16 v[34:49], v[86:89], v[90:93], v[34:49]
	s_waitcnt lgkmcnt(0)
	v_mfma_f32_32x32x16_bf16 v[50:65], v[86:89], v[94:97], v[50:65]
	ds_read_b128 v[86:89], v68 offset:4640
	v_mfma_f32_32x32x16_bf16 v[2:17], v[98:101], v[126:129], v[2:17]
	v_mfma_f32_32x32x16_bf16 v[18:33], v[98:101], v[130:133], v[18:33]
	s_waitcnt vmcnt(7)
	ds_write_b128 v66, v[106:109] offset:27648
	s_waitcnt vmcnt(6)
	ds_write_b128 v66, v[110:113] offset:32256
	global_load_dwordx4 v[106:109], v[74:75], off offset:768
	global_load_dwordx4 v[110:113], v[78:79], off offset:768
	ds_read_b128 v[98:101], v68 offset:4704
	s_waitcnt lgkmcnt(3)
	v_mfma_f32_32x32x16_bf16 v[2:17], v[86:89], v[90:93], v[2:17]
	ds_read_b128 v[90:93], v1 offset:36928
	v_mfma_f32_32x32x16_bf16 v[18:33], v[86:89], v[94:97], v[18:33]
	ds_read_b128 v[86:89], v68 offset:64
	ds_read_b128 v[94:97], v1 offset:41536
	s_waitcnt lgkmcnt(1)
	v_mfma_f32_32x32x16_bf16 v[34:49], v[86:89], v[90:93], v[34:49]
	s_waitcnt lgkmcnt(0)
	v_mfma_f32_32x32x16_bf16 v[50:65], v[86:89], v[94:97], v[50:65]
	s_waitcnt vmcnt(7)
	ds_write_b128 v66, v[144:147] offset:55296
	s_waitcnt vmcnt(6)
	ds_write_b128 v66, v[122:125] offset:59904
	global_load_dwordx4 v[144:147], v[76:77], off offset:768
	global_load_dwordx4 v[122:125], v[80:81], off offset:768
	ds_read_b128 v[86:89], v68 offset:4672
	s_waitcnt lgkmcnt(0)
	v_mfma_f32_32x32x16_bf16 v[2:17], v[86:89], v[90:93], v[2:17]
	ds_read_b128 v[90:93], v1 offset:36960
	v_mfma_f32_32x32x16_bf16 v[18:33], v[86:89], v[94:97], v[18:33]
	ds_read_b128 v[86:89], v68 offset:96
	ds_read_b128 v[94:97], v1 offset:41568
	s_waitcnt lgkmcnt(1)
	v_mfma_f32_32x32x16_bf16 v[34:49], v[86:89], v[90:93], v[34:49]
	s_waitcnt lgkmcnt(0)
	v_mfma_f32_32x32x16_bf16 v[50:65], v[86:89], v[94:97], v[50:65]
	s_waitcnt vmcnt(7)
	ds_write_b128 v66, v[118:121] offset:64512
	s_waitcnt vmcnt(6)
	ds_write_b128 v69, v[114:117] offset:32256
	global_load_dwordx4 v[118:121], v[82:83], off offset:768
	global_load_dwordx4 v[114:117], v[84:85], off offset:768
	v_mfma_f32_32x32x16_bf16 v[2:17], v[98:101], v[90:93], v[2:17]
	v_mfma_f32_32x32x16_bf16 v[18:33], v[98:101], v[94:97], v[18:33]
	s_setprio 0
	s_waitcnt lgkmcnt(0)
	s_barrier
; #define MFMA(a, b, c) __builtin_amdgcn_mfma_f32_32x32x16_bf16((a), (b), (c), 0, 0, 0)
; template <int TM, int TN>
; DI void gemm_mainloop(const u16* __restrict__ A, long lda, const u16* __restrict__ Bt, long ldb, int K, char* smem,
;                       f32x16 (&acc)[TM][TN]) {
;     ...
;   for (int kt = 0; kt < nk; kt++) {
;     const int buf = kt & 1;
;     const u16* cA = sA + buf * BM * LD + (wm * 32 * TM + r) * LD + h * 8;
;     const u16* cB = sB + buf * BN * LD + (wn * 32 * TN + r) * LD + h * 8;
;     bf16x8 af[TM], bfr[TN];
; #pragma unroll
;     for (int tm = 0; tm < TM; tm++) af[tm] = *(const bf16x8*)(cA + tm * 32 * LD);
; #pragma unroll
;     for (int tn = 0; tn < TN; tn++) bfr[tn] = *(const bf16x8*)(cB + tn * 32 * LD);
;     if (kt + 1 < nk) GEMM_SSTORE(buf ^ 1)
;     __builtin_amdgcn_sched_barrier(0);
;     __builtin_amdgcn_s_setprio(1);
; #pragma unroll
;     for (int tm = 0; tm < TM; tm++)
; #pragma unroll
;       for (int tn = 0; tn < TN; tn++) acc[tm][tn] = MFMA(af[tm], bfr[tn], acc[tm][tn]);
; #pragma unroll
;     for (int tm = 0; tm < TM; tm++) af[tm] = *(const bf16x8*)(cA + tm * 32 * LD + 16);
; #pragma unroll
;     for (int tn = 0; tn < TN; tn++) bfr[tn] = *(const bf16x8*)(cB + tn * 32 * LD + 16);
; #pragma unroll
;     for (int tm = 0; tm < TM; tm++)
; #pragma unroll
;       for (int tn = 0; tn < TN; tn++) acc[tm][tn] = MFMA(af[tm], bfr[tn], acc[tm][tn]);
;     __builtin_amdgcn_sched_group_barrier(0x8, 4, 0);
;     if (kt + 2 < nk) GEMM_GLOAD((kt + 2) * 64)
; #pragma unroll
;     for (int ks = 2; ks < 4; ks++) {
; #pragma unroll
;       for (int tm = 0; tm < TM; tm++) af[tm] = *(const bf16x8*)(cA + tm * 32 * LD + ks * 16);
; #pragma unroll
;       for (int tn = 0; tn < TN; tn++) bfr[tn] = *(const bf16x8*)(cB + tn * 32 * LD + ks * 16);
; #pragma unroll
;       for (int tm = 0; tm < TM; tm++)
; #pragma unroll
;         for (int tn = 0; tn < TN; tn++) acc[tm][tn] = MFMA(af[tm], bfr[tn], acc[tm][tn]);
;     }
;     __builtin_amdgcn_s_setprio(0);
;     __syncthreads();
;   }
	ds_read_b128 v[94:97], v68 offset:18432
	ds_read_b128 v[98:101], v68 offset:23040
	ds_read_b128 v[126:129], v1 offset:55296
	ds_read_b128 v[130:133], v1 offset:59904
	s_setprio 1
	ds_read_b128 v[86:89], v68 offset:18464
	s_waitcnt lgkmcnt(2)
	v_mfma_f32_32x32x16_bf16 v[34:49], v[94:97], v[126:129], v[34:49]
	ds_read_b128 v[90:93], v1 offset:55328
	s_waitcnt lgkmcnt(2)
	v_mfma_f32_32x32x16_bf16 v[50:65], v[94:97], v[130:133], v[50:65]
	s_waitcnt vmcnt(7)
	ds_write_b128 v66, v[140:143]
	s_waitcnt vmcnt(6)
	ds_write_b128 v66, v[102:105] offset:4608
	global_load_dwordx4 v[140:143], v[72:73], off offset:896
	global_load_dwordx4 v[102:105], v[70:71], off offset:896
	ds_read_b128 v[94:97], v1 offset:59936
	s_waitcnt lgkmcnt(3)
	v_mfma_f32_32x32x16_bf16 v[34:49], v[86:89], v[90:93], v[34:49]
	s_waitcnt lgkmcnt(0)
	v_mfma_f32_32x32x16_bf16 v[50:65], v[86:89], v[94:97], v[50:65]
	ds_read_b128 v[86:89], v68 offset:23072
	v_mfma_f32_32x32x16_bf16 v[2:17], v[98:101], v[126:129], v[2:17]
	v_mfma_f32_32x32x16_bf16 v[18:33], v[98:101], v[130:133], v[18:33]
	s_waitcnt vmcnt(7)
	ds_write_b128 v66, v[106:109] offset:9216
	s_waitcnt vmcnt(6)
	ds_write_b128 v66, v[110:113] offset:13824
	global_load_dwordx4 v[106:109], v[74:75], off offset:896
	global_load_dwordx4 v[110:113], v[78:79], off offset:896
	ds_read_b128 v[98:101], v68 offset:23136
	s_waitcnt lgkmcnt(3)
	v_mfma_f32_32x32x16_bf16 v[2:17], v[86:89], v[90:93], v[2:17]
	ds_read_b128 v[90:93], v1 offset:55360
	v_mfma_f32_32x32x16_bf16 v[18:33], v[86:89], v[94:97], v[18:33]
	ds_read_b128 v[86:89], v68 offset:18496
	ds_read_b128 v[94:97], v1 offset:59968
	s_waitcnt lgkmcnt(1)
	v_mfma_f32_32x32x16_bf16 v[34:49], v[86:89], v[90:93], v[34:49]
	s_waitcnt lgkmcnt(0)
	v_mfma_f32_32x32x16_bf16 v[50:65], v[86:89], v[94:97], v[50:65]
	s_waitcnt vmcnt(7)
	ds_write_b128 v66, v[144:147] offset:36864
	s_waitcnt vmcnt(6)
	ds_write_b128 v66, v[122:125] offset:41472
	global_load_dwordx4 v[144:147], v[76:77], off offset:896
	global_load_dwordx4 v[122:125], v[80:81], off offset:896
	ds_read_b128 v[86:89], v68 offset:23104
	s_waitcnt lgkmcnt(0)
	v_mfma_f32_32x32x16_bf16 v[2:17], v[86:89], v[90:93], v[2:17]
	ds_read_b128 v[90:93], v1 offset:55392
	v_mfma_f32_32x32x16_bf16 v[18:33], v[86:89], v[94:97], v[18:33]
	ds_read_b128 v[86:89], v68 offset:18528
	ds_read_b128 v[94:97], v1 offset:60000
	s_waitcnt lgkmcnt(1)
	v_mfma_f32_32x32x16_bf16 v[34:49], v[86:89], v[90:93], v[34:49]
	s_waitcnt lgkmcnt(0)
	v_mfma_f32_32x32x16_bf16 v[50:65], v[86:89], v[94:97], v[50:65]
	s_waitcnt vmcnt(7)
	ds_write_b128 v66, v[118:121] offset:46080
	s_waitcnt vmcnt(6)
	ds_write_b128 v66, v[114:117] offset:50688
	global_load_dwordx4 v[118:121], v[82:83], off offset:896
	global_load_dwordx4 v[114:117], v[84:85], off offset:896
	v_mfma_f32_32x32x16_bf16 v[2:17], v[98:101], v[90:93], v[2:17]
	v_mfma_f32_32x32x16_bf16 v[18:33], v[98:101], v[94:97], v[18:33]
	s_setprio 0
	s_waitcnt lgkmcnt(0)
	s_barrier
	ds_read_b128 v[94:97], v68
	ds_read_b128 v[98:101], v68 offset:4608
	ds_read_b128 v[126:129], v1 offset:36864
	ds_read_b128 v[130:133], v1 offset:41472
	s_setprio 1
	ds_read_b128 v[86:89], v68 offset:32
	s_waitcnt lgkmcnt(2)
	v_mfma_f32_32x32x16_bf16 v[34:49], v[94:97], v[126:129], v[34:49]
	ds_read_b128 v[90:93], v1 offset:36896
	s_waitcnt lgkmcnt(2)
	v_mfma_f32_32x32x16_bf16 v[50:65], v[94:97], v[130:133], v[50:65]
	s_waitcnt vmcnt(7)
	ds_write_b128 v66, v[140:143] offset:18432
	s_waitcnt vmcnt(6)
	ds_write_b128 v66, v[102:105] offset:23040
	global_load_dwordx4 v[140:143], v[72:73], off offset:1024
	global_load_dwordx4 v[102:105], v[70:71], off offset:1024
	ds_read_b128 v[94:97], v1 offset:41504
	s_waitcnt lgkmcnt(3)
	v_mfma_f32_32x32x16_bf16 v[34:49], v[86:89], v[90:93], v[34:49]
	s_waitcnt lgkmcnt(0)
	v_mfma_f32_32x32x16_bf16 v[50:65], v[86:89], v[94:97], v[50:65]
	ds_read_b128 v[86:89], v68 offset:4640
	v_mfma_f32_32x32x16_bf16 v[2:17], v[98:101], v[126:129], v[2:17]
	v_mfma_f32_32x32x16_bf16 v[18:33], v[98:101], v[130:133], v[18:33]
	s_waitcnt vmcnt(7)
	ds_write_b128 v66, v[106:109] offset:27648
	s_waitcnt vmcnt(6)
	ds_write_b128 v66, v[110:113] offset:32256
	global_load_dwordx4 v[106:109], v[74:75], off offset:1024
	global_load_dwordx4 v[110:113], v[78:79], off offset:1024
	ds_read_b128 v[98:101], v68 offset:4704
	s_waitcnt lgkmcnt(3)
	v_mfma_f32_32x32x16_bf16 v[2:17], v[86:89], v[90:93], v[2:17]
	ds_read_b128 v[90:93], v1 offset:36928
	v_mfma_f32_32x32x16_bf16 v[18:33], v[86:89], v[94:97], v[18:33]
	ds_read_b128 v[86:89], v68 offset:64
	ds_read_b128 v[94:97], v1 offset:41536
	s_waitcnt lgkmcnt(1)
	v_mfma_f32_32x32x16_bf16 v[34:49], v[86:89], v[90:93], v[34:49]
	s_waitcnt lgkmcnt(0)
	v_mfma_f32_32x32x16_bf16 v[50:65], v[86:89], v[94:97], v[50:65]
	s_waitcnt vmcnt(7)
	ds_write_b128 v66, v[144:147] offset:55296
	s_waitcnt vmcnt(6)
	ds_write_b128 v66, v[122:125] offset:59904
	global_load_dwordx4 v[144:147], v[76:77], off offset:1024
	global_load_dwordx4 v[122:125], v[80:81], off offset:1024
	ds_read_b128 v[86:89], v68 offset:4672
	s_waitcnt lgkmcnt(0)
	v_mfma_f32_32x32x16_bf16 v[2:17], v[86:89], v[90:93], v[2:17]
	ds_read_b128 v[90:93], v1 offset:36960
	v_mfma_f32_32x32x16_bf16 v[18:33], v[86:89], v[94:97], v[18:33]
	ds_read_b128 v[86:89], v68 offset:96
	ds_read_b128 v[94:97], v1 offset:41568
	s_waitcnt lgkmcnt(1)
	v_mfma_f32_32x32x16_bf16 v[34:49], v[86:89], v[90:93], v[34:49]
	s_waitcnt lgkmcnt(0)
	v_mfma_f32_32x32x16_bf16 v[50:65], v[86:89], v[94:97], v[50:65]
	s_waitcnt vmcnt(7)
	ds_write_b128 v66, v[118:121] offset:64512
	s_waitcnt vmcnt(6)
	ds_write_b128 v69, v[114:117] offset:32256
	global_load_dwordx4 v[118:121], v[82:83], off offset:1024
	global_load_dwordx4 v[114:117], v[84:85], off offset:1024
	v_mfma_f32_32x32x16_bf16 v[2:17], v[98:101], v[90:93], v[2:17]
	v_mfma_f32_32x32x16_bf16 v[18:33], v[98:101], v[94:97], v[18:33]
	s_setprio 0
	s_waitcnt lgkmcnt(0)
	s_barrier
; #define MFMA(a, b, c) __builtin_amdgcn_mfma_f32_32x32x16_bf16((a), (b), (c), 0, 0, 0)
; template <int TM, int TN>
; DI void gemm_mainloop(const u16* __restrict__ A, long lda, const u16* __restrict__ Bt, long ldb, int K, char* smem,
;                       f32x16 (&acc)[TM][TN]) {
;     ...
;   for (int kt = 0; kt < nk; kt++) {
;     const int buf = kt & 1;
;     const u16* cA = sA + buf * BM * LD + (wm * 32 * TM + r) * LD + h * 8;
;     const u16* cB = sB + buf * BN * LD + (wn * 32 * TN + r) * LD + h * 8;
;     bf16x8 af[TM], bfr[TN];
; #pragma unroll
;     for (int tm = 0; tm < TM; tm++) af[tm] = *(const bf16x8*)(cA + tm * 32 * LD);
; #pragma unroll
;     for (int tn = 0; tn < TN; tn++) bfr[tn] = *(const bf16x8*)(cB + tn * 32 * LD);
;     if (kt + 1 < nk) GEMM_SSTORE(buf ^ 1)
;     __builtin_amdgcn_sched_barrier(0);
;     __builtin_amdgcn_s_setprio(1);
; #pragma unroll
;     for (int tm = 0; tm < TM; tm++)
; #pragma unroll
;       for (int tn = 0; tn < TN; tn++) acc[tm][tn] = MFMA(af[tm], bfr[tn], acc[tm][tn]);
; #pragma unroll
;     for (int tm = 0; tm < TM; tm++) af[tm] = *(const bf16x8*)(cA + tm * 32 * LD + 16);
; #pragma unroll
;     for (int tn = 0; tn < TN; tn++) bfr[tn] = *(const bf16x8*)(cB + tn * 32 * LD + 16);
; #pragma unroll
;     for (int tm = 0; tm < TM; tm++)
; #pragma unroll
;       for (int tn = 0; tn < TN; tn++) acc[tm][tn] = MFMA(af[tm], bfr[tn], acc[tm][tn]);
;     __builtin_amdgcn_sched_group_barrier(0x8, 4, 0);
;     if (kt + 2 < nk) GEMM_GLOAD((kt + 2) * 64)
; #pragma unroll
;     for (int ks = 2; ks < 4; ks++) {
; #pragma unroll
;       for (int tm = 0; tm < TM; tm++) af[tm] = *(const bf16x8*)(cA + tm * 32 * LD + ks * 16);
; #pragma unroll
;       for (int tn = 0; tn < TN; tn++) bfr[tn] = *(const bf16x8*)(cB + tn * 32 * LD + ks * 16);
; #pragma unroll
;       for (int tm = 0; tm < TM; tm++)
; #pragma unroll
;         for (int tn = 0; tn < TN; tn++) acc[tm][tn] = MFMA(af[tm], bfr[tn], acc[tm][tn]);
;     }
;     __builtin_amdgcn_s_setprio(0);
;     __syncthreads();
;   }
	ds_read_b128 v[94:97], v68 offset:18432
	ds_read_b128 v[98:101], v68 offset:23040
	ds_read_b128 v[126:129], v1 offset:55296
	ds_read_b128 v[130:133], v1 offset:59904
	s_setprio 1
	ds_read_b128 v[86:89], v68 offset:18464
	s_waitcnt lgkmcnt(2)
	v_mfma_f32_32x32x16_bf16 v[34:49], v[94:97], v[126:129], v[34:49]
	ds_read_b128 v[90:93], v1 offset:55328
	s_waitcnt lgkmcnt(2)
	v_mfma_f32_32x32x16_bf16 v[50:65], v[94:97], v[130:133], v[50:65]
	s_waitcnt vmcnt(7)
	ds_write_b128 v66, v[140:143]
	s_waitcnt vmcnt(6)
	ds_write_b128 v66, v[102:105] offset:4608
	global_load_dwordx4 v[140:143], v[72:73], off offset:1152
	global_load_dwordx4 v[102:105], v[70:71], off offset:1152
	ds_read_b128 v[94:97], v1 offset:59936
	s_waitcnt lgkmcnt(3)
	v_mfma_f32_32x32x16_bf16 v[34:49], v[86:89], v[90:93], v[34:49]
	s_waitcnt lgkmcnt(0)
	v_mfma_f32_32x32x16_bf16 v[50:65], v[86:89], v[94:97], v[50:65]
	ds_read_b128 v[86:89], v68 offset:23072
	v_mfma_f32_32x32x16_bf16 v[2:17], v[98:101], v[126:129], v[2:17]
	v_mfma_f32_32x32x16_bf16 v[18:33], v[98:101], v[130:133], v[18:33]
	s_waitcnt vmcnt(7)
	ds_write_b128 v66, v[106:109] offset:9216
	s_waitcnt vmcnt(6)
	ds_write_b128 v66, v[110:113] offset:13824
	global_load_dwordx4 v[106:109], v[74:75], off offset:1152
	global_load_dwordx4 v[110:113], v[78:79], off offset:1152
	ds_read_b128 v[98:101], v68 offset:23136
	s_waitcnt lgkmcnt(3)
	v_mfma_f32_32x32x16_bf16 v[2:17], v[86:89], v[90:93], v[2:17]
	ds_read_b128 v[90:93], v1 offset:55360
	v_mfma_f32_32x32x16_bf16 v[18:33], v[86:89], v[94:97], v[18:33]
	ds_read_b128 v[86:89], v68 offset:18496
	ds_read_b128 v[94:97], v1 offset:59968
	s_waitcnt lgkmcnt(1)
	v_mfma_f32_32x32x16_bf16 v[34:49], v[86:89], v[90:93], v[34:49]
	s_waitcnt lgkmcnt(0)
	v_mfma_f32_32x32x16_bf16 v[50:65], v[86:89], v[94:97], v[50:65]
	s_waitcnt vmcnt(7)
	ds_write_b128 v66, v[144:147] offset:36864
	s_waitcnt vmcnt(6)
	ds_write_b128 v66, v[122:125] offset:41472
	global_load_dwordx4 v[144:147], v[76:77], off offset:1152
	global_load_dwordx4 v[122:125], v[80:81], off offset:1152
	ds_read_b128 v[86:89], v68 offset:23104
	s_waitcnt lgkmcnt(0)
	v_mfma_f32_32x32x16_bf16 v[2:17], v[86:89], v[90:93], v[2:17]
	ds_read_b128 v[90:93], v1 offset:55392
	v_mfma_f32_32x32x16_bf16 v[18:33], v[86:89], v[94:97], v[18:33]
	ds_read_b128 v[86:89], v68 offset:18528
	ds_read_b128 v[94:97], v1 offset:60000
	s_waitcnt lgkmcnt(1)
	v_mfma_f32_32x32x16_bf16 v[34:49], v[86:89], v[90:93], v[34:49]
	s_waitcnt lgkmcnt(0)
	v_mfma_f32_32x32x16_bf16 v[50:65], v[86:89], v[94:97], v[50:65]
	s_waitcnt vmcnt(7)
	ds_write_b128 v66, v[118:121] offset:46080
	s_waitcnt vmcnt(6)
	ds_write_b128 v66, v[114:117] offset:50688
	global_load_dwordx4 v[118:121], v[82:83], off offset:1152
	global_load_dwordx4 v[114:117], v[84:85], off offset:1152
	v_mfma_f32_32x32x16_bf16 v[2:17], v[98:101], v[90:93], v[2:17]
	v_mfma_f32_32x32x16_bf16 v[18:33], v[98:101], v[94:97], v[18:33]
	s_setprio 0
	s_waitcnt lgkmcnt(0)
	s_barrier
	ds_read_b128 v[94:97], v68
	ds_read_b128 v[98:101], v68 offset:4608
	ds_read_b128 v[126:129], v1 offset:36864
	ds_read_b128 v[130:133], v1 offset:41472
	s_setprio 1
	ds_read_b128 v[86:89], v68 offset:32
	s_waitcnt lgkmcnt(2)
	v_mfma_f32_32x32x16_bf16 v[34:49], v[94:97], v[126:129], v[34:49]
	ds_read_b128 v[90:93], v1 offset:36896
	s_waitcnt lgkmcnt(2)
	v_mfma_f32_32x32x16_bf16 v[50:65], v[94:97], v[130:133], v[50:65]
	s_waitcnt vmcnt(7)
	ds_write_b128 v66, v[140:143] offset:18432
	s_waitcnt vmcnt(6)
	ds_write_b128 v66, v[102:105] offset:23040
	global_load_dwordx4 v[140:143], v[72:73], off offset:1280
	global_load_dwordx4 v[102:105], v[70:71], off offset:1280
	ds_read_b128 v[94:97], v1 offset:41504
	s_waitcnt lgkmcnt(3)
	v_mfma_f32_32x32x16_bf16 v[34:49], v[86:89], v[90:93], v[34:49]
	s_waitcnt lgkmcnt(0)
	v_mfma_f32_32x32x16_bf16 v[50:65], v[86:89], v[94:97], v[50:65]
	ds_read_b128 v[86:89], v68 offset:4640
	v_mfma_f32_32x32x16_bf16 v[2:17], v[98:101], v[126:129], v[2:17]
	v_mfma_f32_32x32x16_bf16 v[18:33], v[98:101], v[130:133], v[18:33]
	s_waitcnt vmcnt(7)
	ds_write_b128 v66, v[106:109] offset:27648
	s_waitcnt vmcnt(6)
	ds_write_b128 v66, v[110:113] offset:32256
	global_load_dwordx4 v[106:109], v[74:75], off offset:1280
	global_load_dwordx4 v[110:113], v[78:79], off offset:1280
	ds_read_b128 v[98:101], v68 offset:4704
	s_waitcnt lgkmcnt(3)
	v_mfma_f32_32x32x16_bf16 v[2:17], v[86:89], v[90:93], v[2:17]
	ds_read_b128 v[90:93], v1 offset:36928
	v_mfma_f32_32x32x16_bf16 v[18:33], v[86:89], v[94:97], v[18:33]
	ds_read_b128 v[86:89], v68 offset:64
	ds_read_b128 v[94:97], v1 offset:41536
	s_waitcnt lgkmcnt(1)
	v_mfma_f32_32x32x16_bf16 v[34:49], v[86:89], v[90:93], v[34:49]
	s_waitcnt lgkmcnt(0)
	v_mfma_f32_32x32x16_bf16 v[50:65], v[86:89], v[94:97], v[50:65]
	s_waitcnt vmcnt(7)
	ds_write_b128 v66, v[144:147] offset:55296
	s_waitcnt vmcnt(6)
	ds_write_b128 v66, v[122:125] offset:59904
	global_load_dwordx4 v[144:147], v[76:77], off offset:1280
	global_load_dwordx4 v[122:125], v[80:81], off offset:1280
	ds_read_b128 v[86:89], v68 offset:4672
	s_waitcnt lgkmcnt(0)
	v_mfma_f32_32x32x16_bf16 v[2:17], v[86:89], v[90:93], v[2:17]
	ds_read_b128 v[90:93], v1 offset:36960
	v_mfma_f32_32x32x16_bf16 v[18:33], v[86:89], v[94:97], v[18:33]
	ds_read_b128 v[86:89], v68 offset:96
	ds_read_b128 v[94:97], v1 offset:41568
	s_waitcnt lgkmcnt(1)
	v_mfma_f32_32x32x16_bf16 v[34:49], v[86:89], v[90:93], v[34:49]
	s_waitcnt lgkmcnt(0)
	v_mfma_f32_32x32x16_bf16 v[50:65], v[86:89], v[94:97], v[50:65]
	s_waitcnt vmcnt(7)
	ds_write_b128 v66, v[118:121] offset:64512
	s_waitcnt vmcnt(6)
	ds_write_b128 v69, v[114:117] offset:32256
	global_load_dwordx4 v[118:121], v[82:83], off offset:1280
	global_load_dwordx4 v[114:117], v[84:85], off offset:1280
	v_mfma_f32_32x32x16_bf16 v[2:17], v[98:101], v[90:93], v[2:17]
	v_mfma_f32_32x32x16_bf16 v[18:33], v[98:101], v[94:97], v[18:33]
	s_setprio 0
	s_waitcnt lgkmcnt(0)
	s_barrier
; #define MFMA(a, b, c) __builtin_amdgcn_mfma_f32_32x32x16_bf16((a), (b), (c), 0, 0, 0)
; template <int TM, int TN>
; DI void gemm_mainloop(const u16* __restrict__ A, long lda, const u16* __restrict__ Bt, long ldb, int K, char* smem,
;                       f32x16 (&acc)[TM][TN]) {
;     ...
;   for (int kt = 0; kt < nk; kt++) {
;     const int buf = kt & 1;
;     const u16* cA = sA + buf * BM * LD + (wm * 32 * TM + r) * LD + h * 8;
;     const u16* cB = sB + buf * BN * LD + (wn * 32 * TN + r) * LD + h * 8;
;     bf16x8 af[TM], bfr[TN];
; #pragma unroll
;     for (int tm = 0; tm < TM; tm++) af[tm] = *(const bf16x8*)(cA + tm * 32 * LD);
; #pragma unroll
;     for (int tn = 0; tn < TN; tn++) bfr[tn] = *(const bf16x8*)(cB + tn * 32 * LD);
;     if (kt + 1 < nk) GEMM_SSTORE(buf ^ 1)
;     __builtin_amdgcn_sched_barrier(0);
;     __builtin_amdgcn_s_setprio(1);
; #pragma unroll
;     for (int tm = 0; tm < TM; tm++)
; #pragma unroll
;       for (int tn = 0; tn < TN; tn++) acc[tm][tn] = MFMA(af[tm], bfr[tn], acc[tm][tn]);
; #pragma unroll
;     for (int tm = 0; tm < TM; tm++) af[tm] = *(const bf16x8*)(cA + tm * 32 * LD + 16);
; #pragma unroll
;     for (int tn = 0; tn < TN; tn++) bfr[tn] = *(const bf16x8*)(cB + tn * 32 * LD + 16);
; #pragma unroll
;     for (int tm = 0; tm < TM; tm++)
; #pragma unroll
;       for (int tn = 0; tn < TN; tn++) acc[tm][tn] = MFMA(af[tm], bfr[tn], acc[tm][tn]);
;     __builtin_amdgcn_sched_group_barrier(0x8, 4, 0);
;     if (kt + 2 < nk) GEMM_GLOAD((kt + 2) * 64)
; #pragma unroll
;     for (int ks = 2; ks < 4; ks++) {
; #pragma unroll
;       for (int tm = 0; tm < TM; tm++) af[tm] = *(const bf16x8*)(cA + tm * 32 * LD + ks * 16);
; #pragma unroll
;       for (int tn = 0; tn < TN; tn++) bfr[tn] = *(const bf16x8*)(cB + tn * 32 * LD + ks * 16);
; #pragma unroll
;       for (int tm = 0; tm < TM; tm++)
; #pragma unroll
;         for (int tn = 0; tn < TN; tn++) acc[tm][tn] = MFMA(af[tm], bfr[tn], acc[tm][tn]);
;     }
;     __builtin_amdgcn_s_setprio(0);
;     __syncthreads();
;   }
	ds_read_b128 v[94:97], v68 offset:18432
	ds_read_b128 v[98:101], v68 offset:23040
	ds_read_b128 v[126:129], v1 offset:55296
	ds_read_b128 v[130:133], v1 offset:59904
	s_setprio 1
	ds_read_b128 v[86:89], v68 offset:18464
	s_waitcnt lgkmcnt(2)
	v_mfma_f32_32x32x16_bf16 v[34:49], v[94:97], v[126:129], v[34:49]
	ds_read_b128 v[90:93], v1 offset:55328
	s_waitcnt lgkmcnt(2)
	v_mfma_f32_32x32x16_bf16 v[50:65], v[94:97], v[130:133], v[50:65]
	s_waitcnt vmcnt(7)
	ds_write_b128 v66, v[140:143]
	s_waitcnt vmcnt(6)
	ds_write_b128 v66, v[102:105] offset:4608
	global_load_dwordx4 v[140:143], v[72:73], off offset:1408
	global_load_dwordx4 v[102:105], v[70:71], off offset:1408
	ds_read_b128 v[94:97], v1 offset:59936
	s_waitcnt lgkmcnt(3)
	v_mfma_f32_32x32x16_bf16 v[34:49], v[86:89], v[90:93], v[34:49]
	s_waitcnt lgkmcnt(0)
	v_mfma_f32_32x32x16_bf16 v[50:65], v[86:89], v[94:97], v[50:65]
	ds_read_b128 v[86:89], v68 offset:23072
	v_mfma_f32_32x32x16_bf16 v[2:17], v[98:101], v[126:129], v[2:17]
	v_mfma_f32_32x32x16_bf16 v[18:33], v[98:101], v[130:133], v[18:33]
	s_waitcnt vmcnt(7)
	ds_write_b128 v66, v[106:109] offset:9216
	s_waitcnt vmcnt(6)
	ds_write_b128 v66, v[110:113] offset:13824
	global_load_dwordx4 v[106:109], v[74:75], off offset:1408
	global_load_dwordx4 v[110:113], v[78:79], off offset:1408
	ds_read_b128 v[98:101], v68 offset:23136
	s_waitcnt lgkmcnt(3)
	v_mfma_f32_32x32x16_bf16 v[2:17], v[86:89], v[90:93], v[2:17]
	ds_read_b128 v[90:93], v1 offset:55360
	v_mfma_f32_32x32x16_bf16 v[18:33], v[86:89], v[94:97], v[18:33]
	ds_read_b128 v[86:89], v68 offset:18496
	ds_read_b128 v[94:97], v1 offset:59968
	s_waitcnt lgkmcnt(1)
	v_mfma_f32_32x32x16_bf16 v[34:49], v[86:89], v[90:93], v[34:49]
	s_waitcnt lgkmcnt(0)
	v_mfma_f32_32x32x16_bf16 v[50:65], v[86:89], v[94:97], v[50:65]
	s_waitcnt vmcnt(7)
	ds_write_b128 v66, v[144:147] offset:36864
	s_waitcnt vmcnt(6)
	ds_write_b128 v66, v[122:125] offset:41472
	global_load_dwordx4 v[144:147], v[76:77], off offset:1408
	global_load_dwordx4 v[122:125], v[80:81], off offset:1408
	ds_read_b128 v[86:89], v68 offset:23104
	s_waitcnt lgkmcnt(0)
	v_mfma_f32_32x32x16_bf16 v[2:17], v[86:89], v[90:93], v[2:17]
	ds_read_b128 v[90:93], v1 offset:55392
	v_mfma_f32_32x32x16_bf16 v[18:33], v[86:89], v[94:97], v[18:33]
	ds_read_b128 v[86:89], v68 offset:18528
	ds_read_b128 v[94:97], v1 offset:60000
	s_waitcnt lgkmcnt(1)
	v_mfma_f32_32x32x16_bf16 v[34:49], v[86:89], v[90:93], v[34:49]
	s_waitcnt lgkmcnt(0)
	v_mfma_f32_32x32x16_bf16 v[50:65], v[86:89], v[94:97], v[50:65]
	s_waitcnt vmcnt(7)
	ds_write_b128 v66, v[118:121] offset:46080
	s_waitcnt vmcnt(6)
	ds_write_b128 v66, v[114:117] offset:50688
	global_load_dwordx4 v[118:121], v[82:83], off offset:1408
	global_load_dwordx4 v[114:117], v[84:85], off offset:1408
	v_mfma_f32_32x32x16_bf16 v[2:17], v[98:101], v[90:93], v[2:17]
	v_mfma_f32_32x32x16_bf16 v[18:33], v[98:101], v[94:97], v[18:33]
	s_setprio 0
	s_waitcnt lgkmcnt(0)
	s_barrier
	ds_read_b128 v[94:97], v68
	ds_read_b128 v[98:101], v68 offset:4608
	ds_read_b128 v[126:129], v1 offset:36864
	ds_read_b128 v[130:133], v1 offset:41472
	s_setprio 1
	ds_read_b128 v[86:89], v68 offset:32
	s_waitcnt lgkmcnt(2)
	v_mfma_f32_32x32x16_bf16 v[34:49], v[94:97], v[126:129], v[34:49]
	ds_read_b128 v[90:93], v1 offset:36896
	s_waitcnt lgkmcnt(2)
	v_mfma_f32_32x32x16_bf16 v[50:65], v[94:97], v[130:133], v[50:65]
	s_waitcnt vmcnt(7)
	ds_write_b128 v66, v[140:143] offset:18432
	s_waitcnt vmcnt(6)
	ds_write_b128 v66, v[102:105] offset:23040
	global_load_dwordx4 v[140:143], v[72:73], off offset:1536
	global_load_dwordx4 v[102:105], v[70:71], off offset:1536
	ds_read_b128 v[94:97], v1 offset:41504
	s_waitcnt lgkmcnt(3)
	v_mfma_f32_32x32x16_bf16 v[34:49], v[86:89], v[90:93], v[34:49]
	s_waitcnt lgkmcnt(0)
	v_mfma_f32_32x32x16_bf16 v[50:65], v[86:89], v[94:97], v[50:65]
	ds_read_b128 v[86:89], v68 offset:4640
	v_mfma_f32_32x32x16_bf16 v[2:17], v[98:101], v[126:129], v[2:17]
	v_mfma_f32_32x32x16_bf16 v[18:33], v[98:101], v[130:133], v[18:33]
	s_waitcnt vmcnt(7)
	ds_write_b128 v66, v[106:109] offset:27648
	s_waitcnt vmcnt(6)
	ds_write_b128 v66, v[110:113] offset:32256
	global_load_dwordx4 v[106:109], v[74:75], off offset:1536
	global_load_dwordx4 v[110:113], v[78:79], off offset:1536
	ds_read_b128 v[98:101], v68 offset:4704
	s_waitcnt lgkmcnt(3)
	v_mfma_f32_32x32x16_bf16 v[2:17], v[86:89], v[90:93], v[2:17]
	ds_read_b128 v[90:93], v1 offset:36928
	v_mfma_f32_32x32x16_bf16 v[18:33], v[86:89], v[94:97], v[18:33]
	ds_read_b128 v[86:89], v68 offset:64
	ds_read_b128 v[94:97], v1 offset:41536
	s_waitcnt lgkmcnt(1)
	v_mfma_f32_32x32x16_bf16 v[34:49], v[86:89], v[90:93], v[34:49]
	s_waitcnt lgkmcnt(0)
	v_mfma_f32_32x32x16_bf16 v[50:65], v[86:89], v[94:97], v[50:65]
	s_waitcnt vmcnt(7)
	ds_write_b128 v66, v[144:147] offset:55296
	s_waitcnt vmcnt(6)
	ds_write_b128 v66, v[122:125] offset:59904
	global_load_dwordx4 v[144:147], v[76:77], off offset:1536
	global_load_dwordx4 v[122:125], v[80:81], off offset:1536
	ds_read_b128 v[86:89], v68 offset:4672
	s_waitcnt lgkmcnt(0)
	v_mfma_f32_32x32x16_bf16 v[2:17], v[86:89], v[90:93], v[2:17]
	ds_read_b128 v[90:93], v1 offset:36960
	v_mfma_f32_32x32x16_bf16 v[18:33], v[86:89], v[94:97], v[18:33]
	ds_read_b128 v[86:89], v68 offset:96
	ds_read_b128 v[94:97], v1 offset:41568
	s_waitcnt lgkmcnt(1)
	v_mfma_f32_32x32x16_bf16 v[34:49], v[86:89], v[90:93], v[34:49]
	s_waitcnt lgkmcnt(0)
	v_mfma_f32_32x32x16_bf16 v[50:65], v[86:89], v[94:97], v[50:65]
	s_waitcnt vmcnt(7)
	ds_write_b128 v66, v[118:121] offset:64512
	s_waitcnt vmcnt(6)
	ds_write_b128 v69, v[114:117] offset:32256
	global_load_dwordx4 v[118:121], v[82:83], off offset:1536
	global_load_dwordx4 v[114:117], v[84:85], off offset:1536
	v_mfma_f32_32x32x16_bf16 v[2:17], v[98:101], v[90:93], v[2:17]
	v_mfma_f32_32x32x16_bf16 v[18:33], v[98:101], v[94:97], v[18:33]
	s_setprio 0
	s_waitcnt lgkmcnt(0)
	s_barrier
; #define MFMA(a, b, c) __builtin_amdgcn_mfma_f32_32x32x16_bf16((a), (b), (c), 0, 0, 0)
; template <int TM, int TN>
; DI void gemm_mainloop(const u16* __restrict__ A, long lda, const u16* __restrict__ Bt, long ldb, int K, char* smem,
;                       f32x16 (&acc)[TM][TN]) {
;     ...
;   for (int kt = 0; kt < nk; kt++) {
;     const int buf = kt & 1;
;     const u16* cA = sA + buf * BM * LD + (wm * 32 * TM + r) * LD + h * 8;
;     const u16* cB = sB + buf * BN * LD + (wn * 32 * TN + r) * LD + h * 8;
;     bf16x8 af[TM], bfr[TN];
; #pragma unroll
;     for (int tm = 0; tm < TM; tm++) af[tm] = *(const bf16x8*)(cA + tm * 32 * LD);
; #pragma unroll
;     for (int tn = 0; tn < TN; tn++) bfr[tn] = *(const bf16x8*)(cB + tn * 32 * LD);
;     if (kt + 1 < nk) GEMM_SSTORE(buf ^ 1)
;     __builtin_amdgcn_sched_barrier(0);
;     __builtin_amdgcn_s_setprio(1);
; #pragma unroll
;     for (int tm = 0; tm < TM; tm++)
; #pragma unroll
;       for (int tn = 0; tn < TN; tn++) acc[tm][tn] = MFMA(af[tm], bfr[tn], acc[tm][tn]);
; #pragma unroll
;     for (int tm = 0; tm < TM; tm++) af[tm] = *(const bf16x8*)(cA + tm * 32 * LD + 16);
; #pragma unroll
;     for (int tn = 0; tn < TN; tn++) bfr[tn] = *(const bf16x8*)(cB + tn * 32 * LD + 16);
; #pragma unroll
;     for (int tm = 0; tm < TM; tm++)
; #pragma unroll
;       for (int tn = 0; tn < TN; tn++) acc[tm][tn] = MFMA(af[tm], bfr[tn], acc[tm][tn]);
;     __builtin_amdgcn_sched_group_barrier(0x8, 4, 0);
;     if (kt + 2 < nk) GEMM_GLOAD((kt + 2) * 64)
; #pragma unroll
;     for (int ks = 2; ks < 4; ks++) {
; #pragma unroll
;       for (int tm = 0; tm < TM; tm++) af[tm] = *(const bf16x8*)(cA + tm * 32 * LD + ks * 16);
; #pragma unroll
;       for (int tn = 0; tn < TN; tn++) bfr[tn] = *(const bf16x8*)(cB + tn * 32 * LD + ks * 16);
; #pragma unroll
;       for (int tm = 0; tm < TM; tm++)
; #pragma unroll
;         for (int tn = 0; tn < TN; tn++) acc[tm][tn] = MFMA(af[tm], bfr[tn], acc[tm][tn]);
;     }
;     __builtin_amdgcn_s_setprio(0);
;     __syncthreads();
;   }
	ds_read_b128 v[94:97], v68 offset:18432
	ds_read_b128 v[98:101], v68 offset:23040
	ds_read_b128 v[126:129], v1 offset:55296
	ds_read_b128 v[130:133], v1 offset:59904
	s_setprio 1
	ds_read_b128 v[86:89], v68 offset:18464
	s_waitcnt lgkmcnt(2)
	v_mfma_f32_32x32x16_bf16 v[34:49], v[94:97], v[126:129], v[34:49]
	ds_read_b128 v[90:93], v1 offset:55328
	s_waitcnt lgkmcnt(2)
	v_mfma_f32_32x32x16_bf16 v[50:65], v[94:97], v[130:133], v[50:65]
	s_waitcnt vmcnt(7)
	ds_write_b128 v66, v[140:143]
	s_waitcnt vmcnt(6)
	ds_write_b128 v66, v[102:105] offset:4608
	global_load_dwordx4 v[140:143], v[72:73], off offset:1664
	global_load_dwordx4 v[102:105], v[70:71], off offset:1664
	ds_read_b128 v[94:97], v1 offset:59936
	s_waitcnt lgkmcnt(3)
	v_mfma_f32_32x32x16_bf16 v[34:49], v[86:89], v[90:93], v[34:49]
	s_waitcnt lgkmcnt(0)
	v_mfma_f32_32x32x16_bf16 v[50:65], v[86:89], v[94:97], v[50:65]
	ds_read_b128 v[86:89], v68 offset:23072
	v_mfma_f32_32x32x16_bf16 v[2:17], v[98:101], v[126:129], v[2:17]
	v_mfma_f32_32x32x16_bf16 v[18:33], v[98:101], v[130:133], v[18:33]
	s_waitcnt vmcnt(7)
	ds_write_b128 v66, v[106:109] offset:9216
	s_waitcnt vmcnt(6)
	ds_write_b128 v66, v[110:113] offset:13824
	global_load_dwordx4 v[106:109], v[74:75], off offset:1664
	global_load_dwordx4 v[110:113], v[78:79], off offset:1664
	ds_read_b128 v[98:101], v68 offset:23136
	s_waitcnt lgkmcnt(3)
	v_mfma_f32_32x32x16_bf16 v[2:17], v[86:89], v[90:93], v[2:17]
	ds_read_b128 v[90:93], v1 offset:55360
	v_mfma_f32_32x32x16_bf16 v[18:33], v[86:89], v[94:97], v[18:33]
	ds_read_b128 v[86:89], v68 offset:18496
	ds_read_b128 v[94:97], v1 offset:59968
	s_waitcnt lgkmcnt(1)
	v_mfma_f32_32x32x16_bf16 v[34:49], v[86:89], v[90:93], v[34:49]
	s_waitcnt lgkmcnt(0)
	v_mfma_f32_32x32x16_bf16 v[50:65], v[86:89], v[94:97], v[50:65]
	s_waitcnt vmcnt(7)
	ds_write_b128 v66, v[144:147] offset:36864
	s_waitcnt vmcnt(6)
	ds_write_b128 v66, v[122:125] offset:41472
	global_load_dwordx4 v[144:147], v[76:77], off offset:1664
	global_load_dwordx4 v[122:125], v[80:81], off offset:1664
	ds_read_b128 v[86:89], v68 offset:23104
	s_waitcnt lgkmcnt(0)
	v_mfma_f32_32x32x16_bf16 v[2:17], v[86:89], v[90:93], v[2:17]
	ds_read_b128 v[90:93], v1 offset:55392
	v_mfma_f32_32x32x16_bf16 v[18:33], v[86:89], v[94:97], v[18:33]
	ds_read_b128 v[86:89], v68 offset:18528
	ds_read_b128 v[94:97], v1 offset:60000
	s_waitcnt lgkmcnt(1)
	v_mfma_f32_32x32x16_bf16 v[34:49], v[86:89], v[90:93], v[34:49]
	s_waitcnt lgkmcnt(0)
	v_mfma_f32_32x32x16_bf16 v[50:65], v[86:89], v[94:97], v[50:65]
	s_waitcnt vmcnt(7)
	ds_write_b128 v66, v[118:121] offset:46080
	s_waitcnt vmcnt(6)
	ds_write_b128 v66, v[114:117] offset:50688
	global_load_dwordx4 v[118:121], v[82:83], off offset:1664
	global_load_dwordx4 v[114:117], v[84:85], off offset:1664
	v_mfma_f32_32x32x16_bf16 v[2:17], v[98:101], v[90:93], v[2:17]
	v_mfma_f32_32x32x16_bf16 v[18:33], v[98:101], v[94:97], v[18:33]
	s_setprio 0
	s_waitcnt lgkmcnt(0)
	s_barrier
	ds_read_b128 v[94:97], v68
	ds_read_b128 v[98:101], v68 offset:4608
	ds_read_b128 v[126:129], v1 offset:36864
	ds_read_b128 v[130:133], v1 offset:41472
	s_setprio 1
	ds_read_b128 v[86:89], v68 offset:32
	s_waitcnt lgkmcnt(2)
	v_mfma_f32_32x32x16_bf16 v[34:49], v[94:97], v[126:129], v[34:49]
	ds_read_b128 v[90:93], v1 offset:36896
	s_waitcnt lgkmcnt(2)
	v_mfma_f32_32x32x16_bf16 v[50:65], v[94:97], v[130:133], v[50:65]
	s_waitcnt vmcnt(7)
	ds_write_b128 v66, v[140:143] offset:18432
	s_waitcnt vmcnt(6)
	ds_write_b128 v66, v[102:105] offset:23040
	global_load_dwordx4 v[140:143], v[72:73], off offset:1792
	global_load_dwordx4 v[102:105], v[70:71], off offset:1792
	ds_read_b128 v[94:97], v1 offset:41504
	s_waitcnt lgkmcnt(3)
	v_mfma_f32_32x32x16_bf16 v[34:49], v[86:89], v[90:93], v[34:49]
	s_waitcnt lgkmcnt(0)
	v_mfma_f32_32x32x16_bf16 v[50:65], v[86:89], v[94:97], v[50:65]
	ds_read_b128 v[86:89], v68 offset:4640
	v_mfma_f32_32x32x16_bf16 v[2:17], v[98:101], v[126:129], v[2:17]
	v_mfma_f32_32x32x16_bf16 v[18:33], v[98:101], v[130:133], v[18:33]
	s_waitcnt vmcnt(7)
	ds_write_b128 v66, v[106:109] offset:27648
	s_waitcnt vmcnt(6)
	ds_write_b128 v66, v[110:113] offset:32256
	global_load_dwordx4 v[106:109], v[74:75], off offset:1792
	global_load_dwordx4 v[110:113], v[78:79], off offset:1792
	ds_read_b128 v[98:101], v68 offset:4704
	s_waitcnt lgkmcnt(3)
	v_mfma_f32_32x32x16_bf16 v[2:17], v[86:89], v[90:93], v[2:17]
	ds_read_b128 v[90:93], v1 offset:36928
	v_mfma_f32_32x32x16_bf16 v[18:33], v[86:89], v[94:97], v[18:33]
	ds_read_b128 v[86:89], v68 offset:64
	ds_read_b128 v[94:97], v1 offset:41536
	s_waitcnt lgkmcnt(1)
	v_mfma_f32_32x32x16_bf16 v[34:49], v[86:89], v[90:93], v[34:49]
	s_waitcnt lgkmcnt(0)
	v_mfma_f32_32x32x16_bf16 v[50:65], v[86:89], v[94:97], v[50:65]
	s_waitcnt vmcnt(7)
	ds_write_b128 v66, v[144:147] offset:55296
	s_waitcnt vmcnt(6)
	ds_write_b128 v66, v[122:125] offset:59904
	global_load_dwordx4 v[144:147], v[76:77], off offset:1792
	global_load_dwordx4 v[122:125], v[80:81], off offset:1792
	ds_read_b128 v[86:89], v68 offset:4672
	s_waitcnt lgkmcnt(0)
	v_mfma_f32_32x32x16_bf16 v[2:17], v[86:89], v[90:93], v[2:17]
	ds_read_b128 v[90:93], v1 offset:36960
	v_mfma_f32_32x32x16_bf16 v[18:33], v[86:89], v[94:97], v[18:33]
	ds_read_b128 v[86:89], v68 offset:96
	ds_read_b128 v[94:97], v1 offset:41568
	s_waitcnt lgkmcnt(1)
	v_mfma_f32_32x32x16_bf16 v[34:49], v[86:89], v[90:93], v[34:49]
	s_waitcnt lgkmcnt(0)
	v_mfma_f32_32x32x16_bf16 v[50:65], v[86:89], v[94:97], v[50:65]
	s_waitcnt vmcnt(7)
	ds_write_b128 v66, v[118:121] offset:64512
	s_waitcnt vmcnt(6)
	ds_write_b128 v69, v[114:117] offset:32256
	global_load_dwordx4 v[118:121], v[82:83], off offset:1792
	global_load_dwordx4 v[114:117], v[84:85], off offset:1792
	v_mfma_f32_32x32x16_bf16 v[2:17], v[98:101], v[90:93], v[2:17]
	v_mfma_f32_32x32x16_bf16 v[18:33], v[98:101], v[94:97], v[18:33]
	s_setprio 0
	s_waitcnt lgkmcnt(0)
	s_barrier
; #define MFMA(a, b, c) __builtin_amdgcn_mfma_f32_32x32x16_bf16((a), (b), (c), 0, 0, 0)
; template <int TM, int TN>
; DI void gemm_mainloop(const u16* __restrict__ A, long lda, const u16* __restrict__ Bt, long ldb, int K, char* smem,
;                       f32x16 (&acc)[TM][TN]) {
;     ...
;   for (int kt = 0; kt < nk; kt++) {
;     const int buf = kt & 1;
;     const u16* cA = sA + buf * BM * LD + (wm * 32 * TM + r) * LD + h * 8;
;     const u16* cB = sB + buf * BN * LD + (wn * 32 * TN + r) * LD + h * 8;
;     bf16x8 af[TM], bfr[TN];
; #pragma unroll
;     for (int tm = 0; tm < TM; tm++) af[tm] = *(const bf16x8*)(cA + tm * 32 * LD);
; #pragma unroll
;     for (int tn = 0; tn < TN; tn++) bfr[tn] = *(const bf16x8*)(cB + tn * 32 * LD);
;     if (kt + 1 < nk) GEMM_SSTORE(buf ^ 1)
;     __builtin_amdgcn_sched_barrier(0);
;     __builtin_amdgcn_s_setprio(1);
; #pragma unroll
;     for (int tm = 0; tm < TM; tm++)
; #pragma unroll
;       for (int tn = 0; tn < TN; tn++) acc[tm][tn] = MFMA(af[tm], bfr[tn], acc[tm][tn]);
; #pragma unroll
;     for (int tm = 0; tm < TM; tm++) af[tm] = *(const bf16x8*)(cA + tm * 32 * LD + 16);
; #pragma unroll
;     for (int tn = 0; tn < TN; tn++) bfr[tn] = *(const bf16x8*)(cB + tn * 32 * LD + 16);
; #pragma unroll
;     for (int tm = 0; tm < TM; tm++)
; #pragma unroll
;       for (int tn = 0; tn < TN; tn++) acc[tm][tn] = MFMA(af[tm], bfr[tn], acc[tm][tn]);
;     __builtin_amdgcn_sched_group_barrier(0x8, 4, 0);
;     if (kt + 2 < nk) GEMM_GLOAD((kt + 2) * 64)
; #pragma unroll
;     for (int ks = 2; ks < 4; ks++) {
; #pragma unroll
;       for (int tm = 0; tm < TM; tm++) af[tm] = *(const bf16x8*)(cA + tm * 32 * LD + ks * 16);
; #pragma unroll
;       for (int tn = 0; tn < TN; tn++) bfr[tn] = *(const bf16x8*)(cB + tn * 32 * LD + ks * 16);
; #pragma unroll
;       for (int tm = 0; tm < TM; tm++)
; #pragma unroll
;         for (int tn = 0; tn < TN; tn++) acc[tm][tn] = MFMA(af[tm], bfr[tn], acc[tm][tn]);
;     }
;     __builtin_amdgcn_s_setprio(0);
;     __syncthreads();
;   }
	ds_read_b128 v[94:97], v68 offset:18432
	ds_read_b128 v[98:101], v68 offset:23040
	ds_read_b128 v[126:129], v1 offset:55296
	ds_read_b128 v[130:133], v1 offset:59904
	s_setprio 1
	ds_read_b128 v[86:89], v68 offset:18464
	s_waitcnt lgkmcnt(2)
	v_mfma_f32_32x32x16_bf16 v[34:49], v[94:97], v[126:129], v[34:49]
	ds_read_b128 v[90:93], v1 offset:55328
	s_waitcnt lgkmcnt(2)
	v_mfma_f32_32x32x16_bf16 v[50:65], v[94:97], v[130:133], v[50:65]
	s_waitcnt vmcnt(7)
	ds_write_b128 v66, v[140:143]
	s_waitcnt vmcnt(6)
	ds_write_b128 v66, v[102:105] offset:4608
	global_load_dwordx4 v[140:143], v[72:73], off offset:1920
	global_load_dwordx4 v[102:105], v[70:71], off offset:1920
	ds_read_b128 v[94:97], v1 offset:59936
	s_waitcnt lgkmcnt(3)
	v_mfma_f32_32x32x16_bf16 v[34:49], v[86:89], v[90:93], v[34:49]
	s_waitcnt lgkmcnt(0)
	v_mfma_f32_32x32x16_bf16 v[50:65], v[86:89], v[94:97], v[50:65]
	ds_read_b128 v[86:89], v68 offset:23072
	v_mfma_f32_32x32x16_bf16 v[2:17], v[98:101], v[126:129], v[2:17]
	v_mfma_f32_32x32x16_bf16 v[18:33], v[98:101], v[130:133], v[18:33]
	s_waitcnt vmcnt(7)
	ds_write_b128 v66, v[106:109] offset:9216
	s_waitcnt vmcnt(6)
	ds_write_b128 v66, v[110:113] offset:13824
	global_load_dwordx4 v[106:109], v[74:75], off offset:1920
	global_load_dwordx4 v[110:113], v[78:79], off offset:1920
	ds_read_b128 v[98:101], v68 offset:23136
	s_waitcnt lgkmcnt(3)
	v_mfma_f32_32x32x16_bf16 v[2:17], v[86:89], v[90:93], v[2:17]
	ds_read_b128 v[90:93], v1 offset:55360
	v_mfma_f32_32x32x16_bf16 v[18:33], v[86:89], v[94:97], v[18:33]
	ds_read_b128 v[86:89], v68 offset:18496
	ds_read_b128 v[94:97], v1 offset:59968
	s_waitcnt lgkmcnt(1)
	v_mfma_f32_32x32x16_bf16 v[34:49], v[86:89], v[90:93], v[34:49]
	s_waitcnt lgkmcnt(0)
	v_mfma_f32_32x32x16_bf16 v[50:65], v[86:89], v[94:97], v[50:65]
	s_waitcnt vmcnt(7)
	ds_write_b128 v66, v[144:147] offset:36864
	s_waitcnt vmcnt(6)
	ds_write_b128 v66, v[122:125] offset:41472
	global_load_dwordx4 v[144:147], v[76:77], off offset:1920
	global_load_dwordx4 v[122:125], v[80:81], off offset:1920
	ds_read_b128 v[86:89], v68 offset:23104
	s_waitcnt lgkmcnt(0)
	v_mfma_f32_32x32x16_bf16 v[2:17], v[86:89], v[90:93], v[2:17]
	ds_read_b128 v[90:93], v1 offset:55392
	v_mfma_f32_32x32x16_bf16 v[18:33], v[86:89], v[94:97], v[18:33]
	ds_read_b128 v[86:89], v68 offset:18528
	ds_read_b128 v[94:97], v1 offset:60000
	s_waitcnt lgkmcnt(1)
	v_mfma_f32_32x32x16_bf16 v[34:49], v[86:89], v[90:93], v[34:49]
	s_waitcnt lgkmcnt(0)
	v_mfma_f32_32x32x16_bf16 v[50:65], v[86:89], v[94:97], v[50:65]
	s_waitcnt vmcnt(7)
	ds_write_b128 v66, v[118:121] offset:46080
	s_waitcnt vmcnt(6)
	ds_write_b128 v66, v[114:117] offset:50688
	global_load_dwordx4 v[118:121], v[82:83], off offset:1920
	global_load_dwordx4 v[114:117], v[84:85], off offset:1920
	s_nop 0
	v_mfma_f32_32x32x16_bf16 v[2:17], v[98:101], v[90:93], v[2:17]
	v_mfma_f32_32x32x16_bf16 v[18:33], v[98:101], v[94:97], v[18:33]
	s_setprio 0
	s_waitcnt lgkmcnt(0)
	s_barrier
	ds_read_b128 v[74:77], v68
	ds_read_b128 v[78:81], v68 offset:4608
	ds_read_b128 v[82:85], v1 offset:36864
	ds_read_b128 v[90:93], v1 offset:41472
	s_setprio 1
	ds_read_b128 v[70:73], v68 offset:32
	s_waitcnt lgkmcnt(2)
	v_mfma_f32_32x32x16_bf16 v[34:49], v[74:77], v[82:85], v[34:49]
	s_waitcnt lgkmcnt(1)
	v_mfma_f32_32x32x16_bf16 v[50:65], v[74:77], v[90:93], v[50:65]
	s_waitcnt vmcnt(7)
	ds_write_b128 v66, v[140:143] offset:18432
	s_waitcnt vmcnt(6)
	ds_write_b128 v66, v[102:105] offset:23040
	ds_read_b128 v[74:77], v1 offset:36896
	v_mfma_f32_32x32x16_bf16 v[2:17], v[78:81], v[82:85], v[2:17]
	v_mfma_f32_32x32x16_bf16 v[18:33], v[78:81], v[90:93], v[18:33]
	ds_read_b128 v[78:81], v1 offset:41504
	s_waitcnt lgkmcnt(1)
	v_mfma_f32_32x32x16_bf16 v[34:49], v[70:73], v[74:77], v[34:49]
	s_waitcnt lgkmcnt(0)
	v_mfma_f32_32x32x16_bf16 v[50:65], v[70:73], v[78:81], v[50:65]
	s_waitcnt vmcnt(5)
	ds_write_b128 v66, v[106:109] offset:27648
	s_waitcnt vmcnt(4)
	ds_write_b128 v66, v[110:113] offset:32256
	ds_read_b128 v[70:73], v68 offset:4640
	s_waitcnt lgkmcnt(0)
	v_mfma_f32_32x32x16_bf16 v[2:17], v[70:73], v[74:77], v[2:17]
	ds_read_b128 v[74:77], v1 offset:36928
	v_mfma_f32_32x32x16_bf16 v[18:33], v[70:73], v[78:81], v[18:33]
	ds_read_b128 v[70:73], v68 offset:64
	ds_read_b128 v[78:81], v1 offset:41536
	s_waitcnt lgkmcnt(1)
	v_mfma_f32_32x32x16_bf16 v[34:49], v[70:73], v[74:77], v[34:49]
	s_waitcnt lgkmcnt(0)
	v_mfma_f32_32x32x16_bf16 v[50:65], v[70:73], v[78:81], v[50:65]
	s_waitcnt vmcnt(3)
	ds_write_b128 v66, v[144:147] offset:55296
	s_waitcnt vmcnt(2)
	ds_write_b128 v66, v[122:125] offset:59904
	ds_read_b128 v[70:73], v68 offset:4672
	s_waitcnt lgkmcnt(0)
	v_mfma_f32_32x32x16_bf16 v[2:17], v[70:73], v[74:77], v[2:17]
	ds_read_b128 v[74:77], v1 offset:36960
	v_mfma_f32_32x32x16_bf16 v[18:33], v[70:73], v[78:81], v[18:33]
	ds_read_b128 v[70:73], v68 offset:96
	ds_read_b128 v[78:81], v1 offset:41568
	s_waitcnt lgkmcnt(1)
	v_mfma_f32_32x32x16_bf16 v[34:49], v[70:73], v[74:77], v[34:49]
	s_waitcnt lgkmcnt(0)
	v_mfma_f32_32x32x16_bf16 v[50:65], v[70:73], v[78:81], v[50:65]
	s_waitcnt vmcnt(1)
	ds_write_b128 v66, v[118:121] offset:64512
	s_waitcnt vmcnt(0)
	ds_write_b128 v69, v[114:117] offset:32256
	ds_read_b128 v[70:73], v68 offset:4704
	s_waitcnt lgkmcnt(0)
	v_mfma_f32_32x32x16_bf16 v[2:17], v[70:73], v[74:77], v[2:17]
	v_mfma_f32_32x32x16_bf16 v[18:33], v[70:73], v[78:81], v[18:33]
	s_setprio 0
	s_barrier
; template <int TM, int TN>
; DI void gemm_mainloop(const u16* __restrict__ A, long lda, const u16* __restrict__ Bt, long ldb, int K, char* smem,
;                       f32x16 (&acc)[TM][TN]) {
;     ...
;   for (int kt = 0; kt < nk; kt++) {
;     const int buf = kt & 1;
;     const u16* cA = sA + buf * BM * LD + (wm * 32 * TM + r) * LD + h * 8;
;     const u16* cB = sB + buf * BN * LD + (wn * 32 * TN + r) * LD + h * 8;
;     bf16x8 af[TM], bfr[TN];
; #pragma unroll
;     for (int tm = 0; tm < TM; tm++) af[tm] = *(const bf16x8*)(cA + tm * 32 * LD);
; #pragma unroll
;     for (int tn = 0; tn < TN; tn++) bfr[tn] = *(const bf16x8*)(cB + tn * 32 * LD);
;     if (kt + 1 < nk) GEMM_SSTORE(buf ^ 1)
;     __builtin_amdgcn_sched_barrier(0);
;     __builtin_amdgcn_s_setprio(1);
; #pragma unroll
;     for (int tm = 0; tm < TM; tm++)
; #pragma unroll
;       for (int tn = 0; tn < TN; tn++) acc[tm][tn] = MFMA(af[tm], bfr[tn], acc[tm][tn]);
; #pragma unroll
;     for (int tm = 0; tm < TM; tm++) af[tm] = *(const bf16x8*)(cA + tm * 32 * LD + 16);
; #pragma unroll
;     for (int tn = 0; tn < TN; tn++) bfr[tn] = *(const bf16x8*)(cB + tn * 32 * LD + 16);
; #pragma unroll
;     for (int tm = 0; tm < TM; tm++)
; #pragma unroll
;       for (int tn = 0; tn < TN; tn++) acc[tm][tn] = MFMA(af[tm], bfr[tn], acc[tm][tn]);
;     __builtin_amdgcn_sched_group_barrier(0x8, 4, 0);
;     if (kt + 2 < nk) GEMM_GLOAD((kt + 2) * 64)
; #pragma unroll
;     for (int ks = 2; ks < 4; ks++) {
; #pragma unroll
;       for (int tm = 0; tm < TM; tm++) af[tm] = *(const bf16x8*)(cA + tm * 32 * LD + ks * 16);
; #pragma unroll
;       for (int tn = 0; tn < TN; tn++) bfr[tn] = *(const bf16x8*)(cB + tn * 32 * LD + ks * 16);
; #pragma unroll
;       for (int tm = 0; tm < TM; tm++)
; #pragma unroll
;         for (int tn = 0; tn < TN; tn++) acc[tm][tn] = MFMA(af[tm], bfr[tn], acc[tm][tn]);
;     }
;     __builtin_amdgcn_s_setprio(0);
;     __syncthreads();
;   }
;     ...
; }
; template <int TM, int TN, class Epi>
; DI void gemm_tile(const u16* A, long lda, const u16* Bt, long ldb, int K, int m0, int n0, char* smem, const Epi& epi) {
;   constexpr int BM = 64 * TM, BN = 64 * TN, LDC = BN + Epi::PAD;
;   f32x16 acc[TM][TN];
;   gemm_mainloop<TM, TN>(A + (long)m0 * lda, lda, Bt + (long)n0 * ldb, ldb, K, smem, acc);
;   const int tid = tidx(), lane = tid & 63, w = tid >> 6, r = lane & 31, h = lane >> 5;
	ds_read_b128 v[70:73], v68 offset:18432
	ds_read_b128 v[74:77], v68 offset:23040
	ds_read_b128 v[78:81], v1 offset:55296
	ds_read_b128 v[82:85], v1 offset:59904
	s_setprio 1
	s_waitcnt lgkmcnt(1)
	v_mfma_f32_32x32x16_bf16 v[34:49], v[70:73], v[78:81], v[34:49]
	s_waitcnt lgkmcnt(0)
	v_mfma_f32_32x32x16_bf16 v[50:65], v[70:73], v[82:85], v[50:65]
	ds_read_b128 v[70:73], v68 offset:18464
	v_mfma_f32_32x32x16_bf16 v[2:17], v[74:77], v[78:81], v[2:17]
	ds_read_b128 v[78:81], v1 offset:59936
	v_mfma_f32_32x32x16_bf16 v[18:33], v[74:77], v[82:85], v[18:33]
	ds_read_b128 v[74:77], v1 offset:55328
	s_waitcnt lgkmcnt(0)
	v_mfma_f32_32x32x16_bf16 v[34:49], v[70:73], v[74:77], v[34:49]
	v_mfma_f32_32x32x16_bf16 v[50:65], v[70:73], v[78:81], v[50:65]
	ds_read_b128 v[70:73], v68 offset:23072
	s_waitcnt lgkmcnt(0)
	v_mfma_f32_32x32x16_bf16 v[2:17], v[70:73], v[74:77], v[2:17]
	ds_read_b128 v[74:77], v1 offset:55360
	v_mfma_f32_32x32x16_bf16 v[18:33], v[70:73], v[78:81], v[18:33]
	ds_read_b128 v[70:73], v68 offset:18496
	ds_read_b128 v[78:81], v1 offset:59968
	s_waitcnt lgkmcnt(1)
	v_mfma_f32_32x32x16_bf16 v[34:49], v[70:73], v[74:77], v[34:49]
	s_waitcnt lgkmcnt(0)
	v_mfma_f32_32x32x16_bf16 v[50:65], v[70:73], v[78:81], v[50:65]
	ds_read_b128 v[70:73], v68 offset:23104
	s_waitcnt lgkmcnt(0)
	v_mfma_f32_32x32x16_bf16 v[2:17], v[70:73], v[74:77], v[2:17]
	ds_read_b128 v[74:77], v1 offset:55392
	v_mfma_f32_32x32x16_bf16 v[18:33], v[70:73], v[78:81], v[18:33]
	ds_read_b128 v[70:73], v68 offset:18528
	ds_read_b128 v[78:81], v1 offset:60000
	s_waitcnt lgkmcnt(1)
	v_mfma_f32_32x32x16_bf16 v[34:49], v[70:73], v[74:77], v[34:49]
	s_waitcnt lgkmcnt(0)
	v_mfma_f32_32x32x16_bf16 v[50:65], v[70:73], v[78:81], v[50:65]
	ds_read_b128 v[68:71], v68 offset:23136
	s_waitcnt lgkmcnt(0)
	v_mfma_f32_32x32x16_bf16 v[2:17], v[68:71], v[74:77], v[2:17]
	v_mfma_f32_32x32x16_bf16 v[18:33], v[68:71], v[78:81], v[18:33]
	s_setprio 0
	v_mov_b32_e32 v1, v0
	s_barrier
	s_lshl_b32 s25, s25, 2
	v_lshrrev_b32_e32 v66, 1, v1
	v_and_b32_e32 v66, 0xfffffc0, v66
	v_lshrrev_b32_e32 v68, 3, v1
	v_and_or_b32 v66, v68, 4, v66
	v_and_b32_e32 v68, 0x5f, v1
	v_mul_lo_u32 v66, v66, s20
	v_lshl_add_u32 v66, v68, 2, v66
	ds_write2_b32 v66, v34, v50 offset1:32
	v_add_u32_e32 v34, 0x400, v66
	ds_write2_b32 v34, v36, v52 offset0:8 offset1:40
	ds_write2_b32 v34, v37, v53 offset0:140 offset1:172
	v_add_u32_e32 v34, 0x1000, v66
	ds_write2_b32 v34, v38, v54 offset0:32 offset1:64
	ds_write2_b32 v34, v39, v55 offset0:164 offset1:196
	v_add_u32_e32 v34, 0x1400, v66
	ds_write2_b32 v34, v40, v56 offset0:40 offset1:72
	ds_write2_b32 v34, v41, v57 offset0:172 offset1:204
	v_add_u32_e32 v34, 0x2000, v66
	ds_write2_b32 v34, v42, v58 offset0:64 offset1:96
	ds_write2_b32 v34, v43, v59 offset0:196 offset1:228
	v_add_u32_e32 v34, 0x2400, v66
	ds_write2_b32 v34, v44, v60 offset0:72 offset1:104
	ds_write2_b32 v34, v45, v61 offset0:204 offset1:236
	v_add_u32_e32 v34, 0x3000, v66
	ds_write2_b32 v34, v46, v62 offset0:96 offset1:128
	v_add_u32_e32 v34, 0x3200, v66
	ds_write2_b32 v34, v47, v63 offset0:100 offset1:132
	v_add_u32_e32 v34, 0x3400, v66
	ds_write2_b32 v34, v48, v64 offset0:104 offset1:136
	v_add_u32_e32 v34, 0x3600, v66
	ds_write2_b32 v34, v49, v65 offset0:108 offset1:140
	v_add_u32_e32 v34, 0x4000, v66
	ds_write2_b32 v34, v2, v18 offset0:128 offset1:160
	v_add_u32_e32 v2, 0x4400, v66
	ds_write2_b32 v2, v3, v19 offset0:4 offset1:36
	ds_write2_b32 v2, v4, v20 offset0:136 offset1:168
	v_add_u32_e32 v2, 0x4800, v66
	ds_write2_b32 v2, v5, v21 offset0:12 offset1:44
	v_add_u32_e32 v2, 0x5000, v66
	ds_write2_b32 v2, v6, v22 offset0:160 offset1:192
	v_add_u32_e32 v2, 0x5400, v66
	ds_write2_b32 v2, v7, v23 offset0:36 offset1:68
	ds_write2_b32 v2, v8, v24 offset0:168 offset1:200
	v_add_u32_e32 v2, 0x5800, v66
	ds_write2_b32 v2, v9, v25 offset0:44 offset1:76
	v_add_u32_e32 v2, 0x6000, v66
	ds_write2_b32 v2, v10, v26 offset0:192 offset1:224
	v_add_u32_e32 v2, 0x6400, v66
	ds_write2_b32 v2, v11, v27 offset0:68 offset1:100
	ds_write2_b32 v2, v12, v28 offset0:200 offset1:232
	v_add_u32_e32 v2, 0x6800, v66
	ds_write2_b32 v2, v13, v29 offset0:76 offset1:108
	v_add_u32_e32 v2, 0x7200, v66
	ds_write2_b32 v2, v14, v30 offset0:96 offset1:128
	v_add_u32_e32 v2, 0x7400, v66
	ds_write2_b32 v2, v15, v31 offset0:100 offset1:132
	v_add_u32_e32 v2, 0x7600, v66
	ds_write2_b32 v2, v16, v32 offset0:104 offset1:136
	v_add_u32_e32 v2, 0x7800, v66
	ds_write2_b32 v2, v17, v33 offset0:108 offset1:140
	v_lshlrev_b32_e32 v2, 5, v1
	s_add_u32 s26, s23, s25
	ds_write2_b32 v66, v35, v51 offset0:132 offset1:164
	v_and_b32_e32 v66, 0x1e0, v2
	s_addc_u32 s27, s24, 0
	v_lshl_add_u64 v[2:3], s[26:27], 0, v[66:67]
	s_mov_b32 s23, 0
	s_waitcnt lgkmcnt(0)
	s_barrier

; #define MFMA(a, b, c) __builtin_amdgcn_mfma_f32_32x32x16_bf16((a), (b), (c), 0, 0, 0)
; template <int TM, int TN>
; DI void gemm_mainloop(const u16* __restrict__ A, long lda, const u16* __restrict__ Bt, long ldb, int K, char* smem,
;                       f32x16 (&acc)[TM][TN]) {
;     ...
;   const int nk = K / 64;
;   const int lrow = tid >> 3, lch = (tid & 7) * 8;
;   const u16* gA = A + (long)lrow * lda + lch;
;   const u16* gB = Bt + (long)lrow * ldb + lch;
;   const int soff = lrow * LD + lch;
;     ...
;   GEMM_GLOAD(0)
;   __syncthreads();
;   GEMM_SSTORE(0)
;   if (nk > 1) GEMM_GLOAD(64)
;   __syncthreads();
;   for (int kt = 0; kt < nk; kt++) {
;     const int buf = kt & 1;
;     const u16* cA = sA + buf * BM * LD + (wm * 32 * TM + r) * LD + h * 8;
;     const u16* cB = sB + buf * BN * LD + (wn * 32 * TN + r) * LD + h * 8;
;     bf16x8 af[TM], bfr[TN];
; #pragma unroll
;     for (int tm = 0; tm < TM; tm++) af[tm] = *(const bf16x8*)(cA + tm * 32 * LD);
; #pragma unroll
;     for (int tn = 0; tn < TN; tn++) bfr[tn] = *(const bf16x8*)(cB + tn * 32 * LD);
;     if (kt + 1 < nk) GEMM_SSTORE(buf ^ 1)
;     __builtin_amdgcn_sched_barrier(0);
;     __builtin_amdgcn_s_setprio(1);
; #pragma unroll
;     for (int tm = 0; tm < TM; tm++)
; #pragma unroll
;       for (int tn = 0; tn < TN; tn++) acc[tm][tn] = MFMA(af[tm], bfr[tn], acc[tm][tn]);
; #pragma unroll
;     for (int tm = 0; tm < TM; tm++) af[tm] = *(const bf16x8*)(cA + tm * 32 * LD + 16);
; #pragma unroll
;     for (int tn = 0; tn < TN; tn++) bfr[tn] = *(const bf16x8*)(cB + tn * 32 * LD + 16);
; #pragma unroll
;     for (int tm = 0; tm < TM; tm++)
; #pragma unroll
;       for (int tn = 0; tn < TN; tn++) acc[tm][tn] = MFMA(af[tm], bfr[tn], acc[tm][tn]);
;     __builtin_amdgcn_sched_group_barrier(0x8, 4, 0);
;     if (kt + 2 < nk) GEMM_GLOAD((kt + 2) * 64)
.LBB0_1072:
	s_lshl_b32 s27, s26, 10
	s_add_i32 s27, s27, s14
	s_mul_i32 s4, s27, 0x880
	s_mul_hi_i32 s5, s27, 0x880
	s_add_u32 s4, s8, s4
	v_mov_b32_e32 v1, v0
	s_addc_u32 s5, s9, s5
	s_nop 0
	v_lshlrev_b32_e32 v2, 3, v1
	v_ashrrev_i32_e32 v70, 3, v1
	v_and_b32_e32 v71, 56, v2
	v_mov_b64_e32 v[2:3], s[4:5]
	v_mad_i64_i32 v[2:3], s[4:5], v70, s17, v[2:3]
	v_lshlrev_b32_e32 v66, 1, v71
	v_lshl_add_u64 v[74:75], v[2:3], 0, v[66:67]
	v_add_co_u32_e32 v72, vcc, s19, v74
	v_mad_i64_i32 v[10:11], s[4:5], v70, s17, v[68:69]
	s_nop 0
	v_addc_co_u32_e32 v73, vcc, 0, v75, vcc
	v_add_co_u32_e32 v76, vcc, s20, v74
	v_lshl_add_u64 v[78:79], v[10:11], 0, v[66:67]
	s_nop 0
	v_addc_co_u32_e32 v77, vcc, 0, v75, vcc
	v_add_co_u32_e32 v80, vcc, s19, v78
	global_load_dwordx4 v[2:5], v[74:75], off
	s_nop 0
	v_addc_co_u32_e32 v81, vcc, 0, v79, vcc
	v_add_co_u32_e32 v82, vcc, s20, v78
	global_load_dwordx4 v[6:9], v[72:73], off
	s_nop 0
	v_addc_co_u32_e32 v83, vcc, 0, v79, vcc
	v_add_co_u32_e32 v84, vcc, s21, v78
	global_load_dwordx4 v[10:13], v[78:79], off
	s_nop 0
	v_addc_co_u32_e32 v85, vcc, 0, v79, vcc
	v_add_co_u32_e32 v86, vcc, s21, v74
	global_load_dwordx4 v[14:17], v[80:81], off
	s_nop 0
	v_addc_co_u32_e32 v87, vcc, 0, v75, vcc
	global_load_dwordx4 v[18:21], v[82:83], off
	global_load_dwordx4 v[22:25], v[84:85], off
	global_load_dwordx4 v[26:29], v[76:77], off
	global_load_dwordx4 v[30:33], v[86:87], off
	s_barrier
	global_load_dwordx4 v[34:37], v[74:75], off offset:128
	global_load_dwordx4 v[38:41], v[72:73], off offset:128
	global_load_dwordx4 v[42:45], v[76:77], off offset:128
	global_load_dwordx4 v[46:49], v[86:87], off offset:128
	global_load_dwordx4 v[50:53], v[78:79], off offset:128
	global_load_dwordx4 v[54:57], v[80:81], off offset:128
	global_load_dwordx4 v[58:61], v[82:83], off offset:128
	global_load_dwordx4 v[62:65], v[84:85], off offset:128
	v_and_b32_e32 v66, 31, v1
	v_lshrrev_b32_e32 v88, 1, v1
	v_mul_lo_u32 v70, v70, s18
	v_and_or_b32 v89, v88, s22, v66
	v_and_b32_e32 v88, 16, v88
	v_and_b32_e32 v1, 0x5f, v1
	v_add_lshl_u32 v66, v70, v71, 1
	v_mad_u64_u32 v[70:71], s[4:5], v89, s23, v[88:89]
	v_mad_u32_u24 v1, v1, s23, v88
	v_add_u32_e32 v71, 0x9000, v66
	s_waitcnt vmcnt(15)
	ds_write_b128 v66, v[2:5]
	s_waitcnt vmcnt(14)
	ds_write_b128 v66, v[6:9] offset:4608
	s_waitcnt vmcnt(13)
	ds_write_b128 v66, v[10:13] offset:36864
	s_waitcnt vmcnt(12)
	ds_write_b128 v66, v[14:17] offset:41472
	s_waitcnt vmcnt(11)
	ds_write_b128 v66, v[18:21] offset:46080
	s_waitcnt vmcnt(10)
	ds_write_b128 v66, v[22:25] offset:50688
	s_waitcnt vmcnt(9)
	ds_write_b128 v66, v[26:29] offset:9216
	s_waitcnt vmcnt(8)
	ds_write_b128 v66, v[30:33] offset:13824
	s_waitcnt lgkmcnt(0)
	s_barrier
	ds_read_b128 v[2:5], v70
	ds_read_b128 v[18:21], v70 offset:4608
	ds_read_b128 v[6:9], v1 offset:36864
	ds_read_b128 v[22:25], v1 offset:41472
	s_waitcnt vmcnt(7)
	ds_write_b128 v66, v[34:37] offset:18432
	s_waitcnt vmcnt(6)
	ds_write_b128 v66, v[38:41] offset:23040
	s_waitcnt vmcnt(5)
	ds_write_b128 v66, v[42:45] offset:27648
	s_waitcnt vmcnt(4)
	ds_write_b128 v66, v[46:49] offset:32256
	s_waitcnt vmcnt(3)
	ds_write_b128 v66, v[50:53] offset:55296
	s_waitcnt vmcnt(2)
	ds_write_b128 v66, v[54:57] offset:59904
	s_waitcnt vmcnt(1)
	ds_write_b128 v66, v[58:61] offset:64512
	s_waitcnt vmcnt(0)
	ds_write_b128 v71, v[62:65] offset:32256
	s_setprio 1
	ds_read_b128 v[88:91], v70 offset:32
	s_waitcnt lgkmcnt(10)
	v_mfma_f32_32x32x16_bf16 v[34:49], v[2:5], v[6:9], 0
	ds_read_b128 v[92:95], v1 offset:36896
	ds_read_b128 v[96:99], v1 offset:41504
	ds_read_b128 v[100:103], v70 offset:4704
	global_load_dwordx4 v[104:107], v[72:73], off offset:256
	global_load_dwordx4 v[108:111], v[76:77], off offset:256
	global_load_dwordx4 v[112:115], v[86:87], off offset:256
	global_load_dwordx4 v[116:119], v[84:85], off offset:256
	s_waitcnt lgkmcnt(12)
	v_mfma_f32_32x32x16_bf16 v[50:65], v[2:5], v[22:25], 0
	global_load_dwordx4 v[120:123], v[82:83], off offset:256
	global_load_dwordx4 v[124:127], v[80:81], off offset:256
	global_load_dwordx4 v[140:143], v[74:75], off offset:256
	global_load_dwordx4 v[144:147], v[78:79], off offset:256
	s_waitcnt lgkmcnt(2)
	v_mfma_f32_32x32x16_bf16 v[34:49], v[88:91], v[92:95], v[34:49]
	s_waitcnt lgkmcnt(1)
	v_mfma_f32_32x32x16_bf16 v[50:65], v[88:91], v[96:99], v[50:65]
	ds_read_b128 v[88:91], v70 offset:4640
	v_mfma_f32_32x32x16_bf16 v[2:17], v[18:21], v[6:9], 0
	v_mfma_f32_32x32x16_bf16 v[18:33], v[18:21], v[22:25], 0
	s_waitcnt lgkmcnt(0)
	v_mfma_f32_32x32x16_bf16 v[2:17], v[88:91], v[92:95], v[2:17]
	ds_read_b128 v[92:95], v1 offset:36928
	v_mfma_f32_32x32x16_bf16 v[18:33], v[88:91], v[96:99], v[18:33]
	ds_read_b128 v[88:91], v70 offset:64
	ds_read_b128 v[96:99], v1 offset:41536
	s_waitcnt lgkmcnt(1)
	v_mfma_f32_32x32x16_bf16 v[34:49], v[88:91], v[92:95], v[34:49]
	s_waitcnt lgkmcnt(0)
	v_mfma_f32_32x32x16_bf16 v[50:65], v[88:91], v[96:99], v[50:65]
	ds_read_b128 v[88:91], v70 offset:4672
	s_waitcnt lgkmcnt(0)
	v_mfma_f32_32x32x16_bf16 v[2:17], v[88:91], v[92:95], v[2:17]
	ds_read_b128 v[92:95], v1 offset:36960
	v_mfma_f32_32x32x16_bf16 v[18:33], v[88:91], v[96:99], v[18:33]
	ds_read_b128 v[88:91], v70 offset:96
	ds_read_b128 v[96:99], v1 offset:41568
	s_waitcnt lgkmcnt(1)
	v_mfma_f32_32x32x16_bf16 v[34:49], v[88:91], v[92:95], v[34:49]
	s_waitcnt lgkmcnt(0)
	v_mfma_f32_32x32x16_bf16 v[50:65], v[88:91], v[96:99], v[50:65]
	v_mfma_f32_32x32x16_bf16 v[2:17], v[100:103], v[92:95], v[2:17]
	v_mfma_f32_32x32x16_bf16 v[18:33], v[100:103], v[96:99], v[18:33]
	s_setprio 0
	s_barrier
; #define MFMA(a, b, c) __builtin_amdgcn_mfma_f32_32x32x16_bf16((a), (b), (c), 0, 0, 0)
; template <int TM, int TN>
; DI void gemm_mainloop(const u16* __restrict__ A, long lda, const u16* __restrict__ Bt, long ldb, int K, char* smem,
;                       f32x16 (&acc)[TM][TN]) {
;     ...
;   for (int kt = 0; kt < nk; kt++) {
;     const int buf = kt & 1;
;     const u16* cA = sA + buf * BM * LD + (wm * 32 * TM + r) * LD + h * 8;
;     const u16* cB = sB + buf * BN * LD + (wn * 32 * TN + r) * LD + h * 8;
;     bf16x8 af[TM], bfr[TN];
; #pragma unroll
;     for (int tm = 0; tm < TM; tm++) af[tm] = *(const bf16x8*)(cA + tm * 32 * LD);
; #pragma unroll
;     for (int tn = 0; tn < TN; tn++) bfr[tn] = *(const bf16x8*)(cB + tn * 32 * LD);
;     if (kt + 1 < nk) GEMM_SSTORE(buf ^ 1)
;     __builtin_amdgcn_sched_barrier(0);
;     __builtin_amdgcn_s_setprio(1);
; #pragma unroll
;     for (int tm = 0; tm < TM; tm++)
; #pragma unroll
;       for (int tn = 0; tn < TN; tn++) acc[tm][tn] = MFMA(af[tm], bfr[tn], acc[tm][tn]);
; #pragma unroll
;     for (int tm = 0; tm < TM; tm++) af[tm] = *(const bf16x8*)(cA + tm * 32 * LD + 16);
; #pragma unroll
;     for (int tn = 0; tn < TN; tn++) bfr[tn] = *(const bf16x8*)(cB + tn * 32 * LD + 16);
; #pragma unroll
;     for (int tm = 0; tm < TM; tm++)
; #pragma unroll
;       for (int tn = 0; tn < TN; tn++) acc[tm][tn] = MFMA(af[tm], bfr[tn], acc[tm][tn]);
;     __builtin_amdgcn_sched_group_barrier(0x8, 4, 0);
;     if (kt + 2 < nk) GEMM_GLOAD((kt + 2) * 64)
; #pragma unroll
;     for (int ks = 2; ks < 4; ks++) {
; #pragma unroll
;       for (int tm = 0; tm < TM; tm++) af[tm] = *(const bf16x8*)(cA + tm * 32 * LD + ks * 16);
; #pragma unroll
;       for (int tn = 0; tn < TN; tn++) bfr[tn] = *(const bf16x8*)(cB + tn * 32 * LD + ks * 16);
; #pragma unroll
;       for (int tm = 0; tm < TM; tm++)
; #pragma unroll
;         for (int tn = 0; tn < TN; tn++) acc[tm][tn] = MFMA(af[tm], bfr[tn], acc[tm][tn]);
;     }
;     __builtin_amdgcn_s_setprio(0);
;     __syncthreads();
;   }
	ds_read_b128 v[96:99], v70 offset:18432
	ds_read_b128 v[100:103], v70 offset:23040
	ds_read_b128 v[128:131], v1 offset:55296
	ds_read_b128 v[132:135], v1 offset:59904
	s_setprio 1
	ds_read_b128 v[88:91], v70 offset:18464
	s_waitcnt lgkmcnt(2)
	v_mfma_f32_32x32x16_bf16 v[34:49], v[96:99], v[128:131], v[34:49]
	ds_read_b128 v[92:95], v1 offset:55328
	s_waitcnt lgkmcnt(2)
	v_mfma_f32_32x32x16_bf16 v[50:65], v[96:99], v[132:135], v[50:65]
	s_waitcnt vmcnt(1)
	ds_write_b128 v66, v[140:143]
	ds_write_b128 v66, v[104:107] offset:4608
	global_load_dwordx4 v[140:143], v[74:75], off offset:384
	global_load_dwordx4 v[104:107], v[72:73], off offset:384
	ds_read_b128 v[96:99], v1 offset:59936
	s_waitcnt lgkmcnt(3)
	v_mfma_f32_32x32x16_bf16 v[34:49], v[88:91], v[92:95], v[34:49]
	s_waitcnt lgkmcnt(0)
	v_mfma_f32_32x32x16_bf16 v[50:65], v[88:91], v[96:99], v[50:65]
	ds_read_b128 v[88:91], v70 offset:23072
	v_mfma_f32_32x32x16_bf16 v[2:17], v[100:103], v[128:131], v[2:17]
	v_mfma_f32_32x32x16_bf16 v[18:33], v[100:103], v[132:135], v[18:33]
	ds_write_b128 v66, v[108:111] offset:9216
	ds_write_b128 v66, v[112:115] offset:13824
	global_load_dwordx4 v[108:111], v[76:77], off offset:384
	global_load_dwordx4 v[112:115], v[86:87], off offset:384
	ds_read_b128 v[100:103], v70 offset:23136
	s_waitcnt lgkmcnt(3)
	v_mfma_f32_32x32x16_bf16 v[2:17], v[88:91], v[92:95], v[2:17]
	ds_read_b128 v[92:95], v1 offset:55360
	v_mfma_f32_32x32x16_bf16 v[18:33], v[88:91], v[96:99], v[18:33]
	ds_read_b128 v[88:91], v70 offset:18496
	ds_read_b128 v[96:99], v1 offset:59968
	s_waitcnt lgkmcnt(1)
	v_mfma_f32_32x32x16_bf16 v[34:49], v[88:91], v[92:95], v[34:49]
	s_waitcnt lgkmcnt(0)
	v_mfma_f32_32x32x16_bf16 v[50:65], v[88:91], v[96:99], v[50:65]
	s_waitcnt vmcnt(4)
	ds_write_b128 v66, v[144:147] offset:36864
	ds_write_b128 v66, v[124:127] offset:41472
	global_load_dwordx4 v[144:147], v[78:79], off offset:384
	global_load_dwordx4 v[124:127], v[80:81], off offset:384
	ds_read_b128 v[88:91], v70 offset:23104
	s_waitcnt lgkmcnt(0)
	v_mfma_f32_32x32x16_bf16 v[2:17], v[88:91], v[92:95], v[2:17]
	ds_read_b128 v[92:95], v1 offset:55392
	v_mfma_f32_32x32x16_bf16 v[18:33], v[88:91], v[96:99], v[18:33]
	ds_read_b128 v[88:91], v70 offset:18528
	ds_read_b128 v[96:99], v1 offset:60000
	s_waitcnt lgkmcnt(1)
	v_mfma_f32_32x32x16_bf16 v[34:49], v[88:91], v[92:95], v[34:49]
	s_waitcnt lgkmcnt(0)
	v_mfma_f32_32x32x16_bf16 v[50:65], v[88:91], v[96:99], v[50:65]
	ds_write_b128 v66, v[120:123] offset:46080
	ds_write_b128 v66, v[116:119] offset:50688
	global_load_dwordx4 v[120:123], v[82:83], off offset:384
	global_load_dwordx4 v[116:119], v[84:85], off offset:384
	v_mfma_f32_32x32x16_bf16 v[2:17], v[100:103], v[92:95], v[2:17]
	v_mfma_f32_32x32x16_bf16 v[18:33], v[100:103], v[96:99], v[18:33]
	s_setprio 0
	s_waitcnt lgkmcnt(0)
	s_barrier
	ds_read_b128 v[96:99], v70
	ds_read_b128 v[100:103], v70 offset:4608
	ds_read_b128 v[128:131], v1 offset:36864
	ds_read_b128 v[132:135], v1 offset:41472
	s_setprio 1
	ds_read_b128 v[88:91], v70 offset:32
	s_waitcnt lgkmcnt(2)
	v_mfma_f32_32x32x16_bf16 v[34:49], v[96:99], v[128:131], v[34:49]
	ds_read_b128 v[92:95], v1 offset:36896
	s_waitcnt lgkmcnt(2)
	v_mfma_f32_32x32x16_bf16 v[50:65], v[96:99], v[132:135], v[50:65]
	s_waitcnt vmcnt(7)
	ds_write_b128 v66, v[140:143] offset:18432
	s_waitcnt vmcnt(6)
	ds_write_b128 v66, v[104:107] offset:23040
	global_load_dwordx4 v[140:143], v[74:75], off offset:512
	global_load_dwordx4 v[104:107], v[72:73], off offset:512
	ds_read_b128 v[96:99], v1 offset:41504
	s_waitcnt lgkmcnt(3)
	v_mfma_f32_32x32x16_bf16 v[34:49], v[88:91], v[92:95], v[34:49]
	s_waitcnt lgkmcnt(0)
	v_mfma_f32_32x32x16_bf16 v[50:65], v[88:91], v[96:99], v[50:65]
	ds_read_b128 v[88:91], v70 offset:4640
	v_mfma_f32_32x32x16_bf16 v[2:17], v[100:103], v[128:131], v[2:17]
	v_mfma_f32_32x32x16_bf16 v[18:33], v[100:103], v[132:135], v[18:33]
	s_waitcnt vmcnt(7)
	ds_write_b128 v66, v[108:111] offset:27648
	s_waitcnt vmcnt(6)
	ds_write_b128 v66, v[112:115] offset:32256
	global_load_dwordx4 v[108:111], v[76:77], off offset:512
	global_load_dwordx4 v[112:115], v[86:87], off offset:512
	ds_read_b128 v[100:103], v70 offset:4704
	s_waitcnt lgkmcnt(3)
	v_mfma_f32_32x32x16_bf16 v[2:17], v[88:91], v[92:95], v[2:17]
	ds_read_b128 v[92:95], v1 offset:36928
	v_mfma_f32_32x32x16_bf16 v[18:33], v[88:91], v[96:99], v[18:33]
	ds_read_b128 v[88:91], v70 offset:64
	ds_read_b128 v[96:99], v1 offset:41536
	s_waitcnt lgkmcnt(1)
	v_mfma_f32_32x32x16_bf16 v[34:49], v[88:91], v[92:95], v[34:49]
	s_waitcnt lgkmcnt(0)
	v_mfma_f32_32x32x16_bf16 v[50:65], v[88:91], v[96:99], v[50:65]
	s_waitcnt vmcnt(7)
	ds_write_b128 v66, v[144:147] offset:55296
	s_waitcnt vmcnt(6)
	ds_write_b128 v66, v[124:127] offset:59904
	global_load_dwordx4 v[144:147], v[78:79], off offset:512
	global_load_dwordx4 v[124:127], v[80:81], off offset:512
	ds_read_b128 v[88:91], v70 offset:4672
	s_waitcnt lgkmcnt(0)
	v_mfma_f32_32x32x16_bf16 v[2:17], v[88:91], v[92:95], v[2:17]
	ds_read_b128 v[92:95], v1 offset:36960
	v_mfma_f32_32x32x16_bf16 v[18:33], v[88:91], v[96:99], v[18:33]
	ds_read_b128 v[88:91], v70 offset:96
	ds_read_b128 v[96:99], v1 offset:41568
	s_waitcnt lgkmcnt(1)
	v_mfma_f32_32x32x16_bf16 v[34:49], v[88:91], v[92:95], v[34:49]
	s_waitcnt lgkmcnt(0)
	v_mfma_f32_32x32x16_bf16 v[50:65], v[88:91], v[96:99], v[50:65]
	s_waitcnt vmcnt(7)
	ds_write_b128 v66, v[120:123] offset:64512
	s_waitcnt vmcnt(6)
	ds_write_b128 v71, v[116:119] offset:32256
	global_load_dwordx4 v[120:123], v[82:83], off offset:512
	global_load_dwordx4 v[116:119], v[84:85], off offset:512
	v_mfma_f32_32x32x16_bf16 v[2:17], v[100:103], v[92:95], v[2:17]
	v_mfma_f32_32x32x16_bf16 v[18:33], v[100:103], v[96:99], v[18:33]
	s_setprio 0
	s_waitcnt lgkmcnt(0)
	s_barrier
; #define MFMA(a, b, c) __builtin_amdgcn_mfma_f32_32x32x16_bf16((a), (b), (c), 0, 0, 0)
; template <int TM, int TN>
; DI void gemm_mainloop(const u16* __restrict__ A, long lda, const u16* __restrict__ Bt, long ldb, int K, char* smem,
;                       f32x16 (&acc)[TM][TN]) {
;     ...
;   for (int kt = 0; kt < nk; kt++) {
;     const int buf = kt & 1;
;     const u16* cA = sA + buf * BM * LD + (wm * 32 * TM + r) * LD + h * 8;
;     const u16* cB = sB + buf * BN * LD + (wn * 32 * TN + r) * LD + h * 8;
;     bf16x8 af[TM], bfr[TN];
; #pragma unroll
;     for (int tm = 0; tm < TM; tm++) af[tm] = *(const bf16x8*)(cA + tm * 32 * LD);
; #pragma unroll
;     for (int tn = 0; tn < TN; tn++) bfr[tn] = *(const bf16x8*)(cB + tn * 32 * LD);
;     if (kt + 1 < nk) GEMM_SSTORE(buf ^ 1)
;     __builtin_amdgcn_sched_barrier(0);
;     __builtin_amdgcn_s_setprio(1);
; #pragma unroll
;     for (int tm = 0; tm < TM; tm++)
; #pragma unroll
;       for (int tn = 0; tn < TN; tn++) acc[tm][tn] = MFMA(af[tm], bfr[tn], acc[tm][tn]);
; #pragma unroll
;     for (int tm = 0; tm < TM; tm++) af[tm] = *(const bf16x8*)(cA + tm * 32 * LD + 16);
; #pragma unroll
;     for (int tn = 0; tn < TN; tn++) bfr[tn] = *(const bf16x8*)(cB + tn * 32 * LD + 16);
; #pragma unroll
;     for (int tm = 0; tm < TM; tm++)
; #pragma unroll
;       for (int tn = 0; tn < TN; tn++) acc[tm][tn] = MFMA(af[tm], bfr[tn], acc[tm][tn]);
;     __builtin_amdgcn_sched_group_barrier(0x8, 4, 0);
;     if (kt + 2 < nk) GEMM_GLOAD((kt + 2) * 64)
; #pragma unroll
;     for (int ks = 2; ks < 4; ks++) {
; #pragma unroll
;       for (int tm = 0; tm < TM; tm++) af[tm] = *(const bf16x8*)(cA + tm * 32 * LD + ks * 16);
; #pragma unroll
;       for (int tn = 0; tn < TN; tn++) bfr[tn] = *(const bf16x8*)(cB + tn * 32 * LD + ks * 16);
; #pragma unroll
;       for (int tm = 0; tm < TM; tm++)
; #pragma unroll
;         for (int tn = 0; tn < TN; tn++) acc[tm][tn] = MFMA(af[tm], bfr[tn], acc[tm][tn]);
;     }
;     __builtin_amdgcn_s_setprio(0);
;     __syncthreads();
;   }
	ds_read_b128 v[96:99], v70 offset:18432
	ds_read_b128 v[100:103], v70 offset:23040
	ds_read_b128 v[128:131], v1 offset:55296
	ds_read_b128 v[132:135], v1 offset:59904
	s_setprio 1
	ds_read_b128 v[88:91], v70 offset:18464
	s_waitcnt lgkmcnt(2)
	v_mfma_f32_32x32x16_bf16 v[34:49], v[96:99], v[128:131], v[34:49]
	ds_read_b128 v[92:95], v1 offset:55328
	s_waitcnt lgkmcnt(2)
	v_mfma_f32_32x32x16_bf16 v[50:65], v[96:99], v[132:135], v[50:65]
	s_waitcnt vmcnt(7)
	ds_write_b128 v66, v[140:143]
	s_waitcnt vmcnt(6)
	ds_write_b128 v66, v[104:107] offset:4608
	global_load_dwordx4 v[140:143], v[74:75], off offset:640
	global_load_dwordx4 v[104:107], v[72:73], off offset:640
	ds_read_b128 v[96:99], v1 offset:59936
	s_waitcnt lgkmcnt(3)
	v_mfma_f32_32x32x16_bf16 v[34:49], v[88:91], v[92:95], v[34:49]
	s_waitcnt lgkmcnt(0)
	v_mfma_f32_32x32x16_bf16 v[50:65], v[88:91], v[96:99], v[50:65]
	ds_read_b128 v[88:91], v70 offset:23072
	v_mfma_f32_32x32x16_bf16 v[2:17], v[100:103], v[128:131], v[2:17]
	v_mfma_f32_32x32x16_bf16 v[18:33], v[100:103], v[132:135], v[18:33]
	s_waitcnt vmcnt(7)
	ds_write_b128 v66, v[108:111] offset:9216
	s_waitcnt vmcnt(6)
	ds_write_b128 v66, v[112:115] offset:13824
	global_load_dwordx4 v[108:111], v[76:77], off offset:640
	global_load_dwordx4 v[112:115], v[86:87], off offset:640
	ds_read_b128 v[100:103], v70 offset:23136
	s_waitcnt lgkmcnt(3)
	v_mfma_f32_32x32x16_bf16 v[2:17], v[88:91], v[92:95], v[2:17]
	ds_read_b128 v[92:95], v1 offset:55360
	v_mfma_f32_32x32x16_bf16 v[18:33], v[88:91], v[96:99], v[18:33]
	ds_read_b128 v[88:91], v70 offset:18496
	ds_read_b128 v[96:99], v1 offset:59968
	s_waitcnt lgkmcnt(1)
	v_mfma_f32_32x32x16_bf16 v[34:49], v[88:91], v[92:95], v[34:49]
	s_waitcnt lgkmcnt(0)
	v_mfma_f32_32x32x16_bf16 v[50:65], v[88:91], v[96:99], v[50:65]
	s_waitcnt vmcnt(7)
	ds_write_b128 v66, v[144:147] offset:36864
	s_waitcnt vmcnt(6)
	ds_write_b128 v66, v[124:127] offset:41472
	global_load_dwordx4 v[144:147], v[78:79], off offset:640
	global_load_dwordx4 v[124:127], v[80:81], off offset:640
	ds_read_b128 v[88:91], v70 offset:23104
	s_waitcnt lgkmcnt(0)
	v_mfma_f32_32x32x16_bf16 v[2:17], v[88:91], v[92:95], v[2:17]
	ds_read_b128 v[92:95], v1 offset:55392
	v_mfma_f32_32x32x16_bf16 v[18:33], v[88:91], v[96:99], v[18:33]
	ds_read_b128 v[88:91], v70 offset:18528
	ds_read_b128 v[96:99], v1 offset:60000
	s_waitcnt lgkmcnt(1)
	v_mfma_f32_32x32x16_bf16 v[34:49], v[88:91], v[92:95], v[34:49]
	s_waitcnt lgkmcnt(0)
	v_mfma_f32_32x32x16_bf16 v[50:65], v[88:91], v[96:99], v[50:65]
	s_waitcnt vmcnt(7)
	ds_write_b128 v66, v[120:123] offset:46080
	s_waitcnt vmcnt(6)
	ds_write_b128 v66, v[116:119] offset:50688
	global_load_dwordx4 v[120:123], v[82:83], off offset:640
	global_load_dwordx4 v[116:119], v[84:85], off offset:640
	v_mfma_f32_32x32x16_bf16 v[2:17], v[100:103], v[92:95], v[2:17]
	v_mfma_f32_32x32x16_bf16 v[18:33], v[100:103], v[96:99], v[18:33]
	s_setprio 0
	s_waitcnt lgkmcnt(0)
	s_barrier
	ds_read_b128 v[96:99], v70
	ds_read_b128 v[100:103], v70 offset:4608
	ds_read_b128 v[128:131], v1 offset:36864
	ds_read_b128 v[132:135], v1 offset:41472
	s_setprio 1
	ds_read_b128 v[88:91], v70 offset:32
	s_waitcnt lgkmcnt(2)
	v_mfma_f32_32x32x16_bf16 v[34:49], v[96:99], v[128:131], v[34:49]
	ds_read_b128 v[92:95], v1 offset:36896
	s_waitcnt lgkmcnt(2)
	v_mfma_f32_32x32x16_bf16 v[50:65], v[96:99], v[132:135], v[50:65]
	s_waitcnt vmcnt(7)
	ds_write_b128 v66, v[140:143] offset:18432
	s_waitcnt vmcnt(6)
	ds_write_b128 v66, v[104:107] offset:23040
	global_load_dwordx4 v[140:143], v[74:75], off offset:768
	global_load_dwordx4 v[104:107], v[72:73], off offset:768
	ds_read_b128 v[96:99], v1 offset:41504
	s_waitcnt lgkmcnt(3)
	v_mfma_f32_32x32x16_bf16 v[34:49], v[88:91], v[92:95], v[34:49]
	s_waitcnt lgkmcnt(0)
	v_mfma_f32_32x32x16_bf16 v[50:65], v[88:91], v[96:99], v[50:65]
	ds_read_b128 v[88:91], v70 offset:4640
	v_mfma_f32_32x32x16_bf16 v[2:17], v[100:103], v[128:131], v[2:17]
	v_mfma_f32_32x32x16_bf16 v[18:33], v[100:103], v[132:135], v[18:33]
	s_waitcnt vmcnt(7)
	ds_write_b128 v66, v[108:111] offset:27648
	s_waitcnt vmcnt(6)
	ds_write_b128 v66, v[112:115] offset:32256
	global_load_dwordx4 v[108:111], v[76:77], off offset:768
	global_load_dwordx4 v[112:115], v[86:87], off offset:768
	ds_read_b128 v[100:103], v70 offset:4704
	s_waitcnt lgkmcnt(3)
	v_mfma_f32_32x32x16_bf16 v[2:17], v[88:91], v[92:95], v[2:17]
	ds_read_b128 v[92:95], v1 offset:36928
	v_mfma_f32_32x32x16_bf16 v[18:33], v[88:91], v[96:99], v[18:33]
	ds_read_b128 v[88:91], v70 offset:64
	ds_read_b128 v[96:99], v1 offset:41536
	s_waitcnt lgkmcnt(1)
	v_mfma_f32_32x32x16_bf16 v[34:49], v[88:91], v[92:95], v[34:49]
	s_waitcnt lgkmcnt(0)
	v_mfma_f32_32x32x16_bf16 v[50:65], v[88:91], v[96:99], v[50:65]
	s_waitcnt vmcnt(7)
	ds_write_b128 v66, v[144:147] offset:55296
	s_waitcnt vmcnt(6)
	ds_write_b128 v66, v[124:127] offset:59904
	global_load_dwordx4 v[144:147], v[78:79], off offset:768
	global_load_dwordx4 v[124:127], v[80:81], off offset:768
	ds_read_b128 v[88:91], v70 offset:4672
	s_waitcnt lgkmcnt(0)
	v_mfma_f32_32x32x16_bf16 v[2:17], v[88:91], v[92:95], v[2:17]
	ds_read_b128 v[92:95], v1 offset:36960
	v_mfma_f32_32x32x16_bf16 v[18:33], v[88:91], v[96:99], v[18:33]
	ds_read_b128 v[88:91], v70 offset:96
	ds_read_b128 v[96:99], v1 offset:41568
	s_waitcnt lgkmcnt(1)
	v_mfma_f32_32x32x16_bf16 v[34:49], v[88:91], v[92:95], v[34:49]
	s_waitcnt lgkmcnt(0)
	v_mfma_f32_32x32x16_bf16 v[50:65], v[88:91], v[96:99], v[50:65]
	s_waitcnt vmcnt(7)
	ds_write_b128 v66, v[120:123] offset:64512
	s_waitcnt vmcnt(6)
	ds_write_b128 v71, v[116:119] offset:32256
	global_load_dwordx4 v[120:123], v[82:83], off offset:768
	global_load_dwordx4 v[116:119], v[84:85], off offset:768
	v_mfma_f32_32x32x16_bf16 v[2:17], v[100:103], v[92:95], v[2:17]
	v_mfma_f32_32x32x16_bf16 v[18:33], v[100:103], v[96:99], v[18:33]
	s_setprio 0
	s_waitcnt lgkmcnt(0)
	s_barrier
; #define MFMA(a, b, c) __builtin_amdgcn_mfma_f32_32x32x16_bf16((a), (b), (c), 0, 0, 0)
; template <int TM, int TN>
; DI void gemm_mainloop(const u16* __restrict__ A, long lda, const u16* __restrict__ Bt, long ldb, int K, char* smem,
;                       f32x16 (&acc)[TM][TN]) {
;     ...
;   for (int kt = 0; kt < nk; kt++) {
;     const int buf = kt & 1;
;     const u16* cA = sA + buf * BM * LD + (wm * 32 * TM + r) * LD + h * 8;
;     const u16* cB = sB + buf * BN * LD + (wn * 32 * TN + r) * LD + h * 8;
;     bf16x8 af[TM], bfr[TN];
; #pragma unroll
;     for (int tm = 0; tm < TM; tm++) af[tm] = *(const bf16x8*)(cA + tm * 32 * LD);
; #pragma unroll
;     for (int tn = 0; tn < TN; tn++) bfr[tn] = *(const bf16x8*)(cB + tn * 32 * LD);
;     if (kt + 1 < nk) GEMM_SSTORE(buf ^ 1)
;     __builtin_amdgcn_sched_barrier(0);
;     __builtin_amdgcn_s_setprio(1);
; #pragma unroll
;     for (int tm = 0; tm < TM; tm++)
; #pragma unroll
;       for (int tn = 0; tn < TN; tn++) acc[tm][tn] = MFMA(af[tm], bfr[tn], acc[tm][tn]);
; #pragma unroll
;     for (int tm = 0; tm < TM; tm++) af[tm] = *(const bf16x8*)(cA + tm * 32 * LD + 16);
; #pragma unroll
;     for (int tn = 0; tn < TN; tn++) bfr[tn] = *(const bf16x8*)(cB + tn * 32 * LD + 16);
; #pragma unroll
;     for (int tm = 0; tm < TM; tm++)
; #pragma unroll
;       for (int tn = 0; tn < TN; tn++) acc[tm][tn] = MFMA(af[tm], bfr[tn], acc[tm][tn]);
;     __builtin_amdgcn_sched_group_barrier(0x8, 4, 0);
;     if (kt + 2 < nk) GEMM_GLOAD((kt + 2) * 64)
; #pragma unroll
;     for (int ks = 2; ks < 4; ks++) {
; #pragma unroll
;       for (int tm = 0; tm < TM; tm++) af[tm] = *(const bf16x8*)(cA + tm * 32 * LD + ks * 16);
; #pragma unroll
;       for (int tn = 0; tn < TN; tn++) bfr[tn] = *(const bf16x8*)(cB + tn * 32 * LD + ks * 16);
; #pragma unroll
;       for (int tm = 0; tm < TM; tm++)
; #pragma unroll
;         for (int tn = 0; tn < TN; tn++) acc[tm][tn] = MFMA(af[tm], bfr[tn], acc[tm][tn]);
;     }
;     __builtin_amdgcn_s_setprio(0);
;     __syncthreads();
;   }
	ds_read_b128 v[96:99], v70 offset:18432
	ds_read_b128 v[100:103], v70 offset:23040
	ds_read_b128 v[128:131], v1 offset:55296
	ds_read_b128 v[132:135], v1 offset:59904
	s_setprio 1
	ds_read_b128 v[88:91], v70 offset:18464
	s_waitcnt lgkmcnt(2)
	v_mfma_f32_32x32x16_bf16 v[34:49], v[96:99], v[128:131], v[34:49]
	ds_read_b128 v[92:95], v1 offset:55328
	s_waitcnt lgkmcnt(2)
	v_mfma_f32_32x32x16_bf16 v[50:65], v[96:99], v[132:135], v[50:65]
	s_waitcnt vmcnt(7)
	ds_write_b128 v66, v[140:143]
	s_waitcnt vmcnt(6)
	ds_write_b128 v66, v[104:107] offset:4608
	global_load_dwordx4 v[140:143], v[74:75], off offset:896
	global_load_dwordx4 v[104:107], v[72:73], off offset:896
	ds_read_b128 v[96:99], v1 offset:59936
	s_waitcnt lgkmcnt(3)
	v_mfma_f32_32x32x16_bf16 v[34:49], v[88:91], v[92:95], v[34:49]
	s_waitcnt lgkmcnt(0)
	v_mfma_f32_32x32x16_bf16 v[50:65], v[88:91], v[96:99], v[50:65]
	ds_read_b128 v[88:91], v70 offset:23072
	v_mfma_f32_32x32x16_bf16 v[2:17], v[100:103], v[128:131], v[2:17]
	v_mfma_f32_32x32x16_bf16 v[18:33], v[100:103], v[132:135], v[18:33]
	s_waitcnt vmcnt(7)
	ds_write_b128 v66, v[108:111] offset:9216
	s_waitcnt vmcnt(6)
	ds_write_b128 v66, v[112:115] offset:13824
	global_load_dwordx4 v[108:111], v[76:77], off offset:896
	global_load_dwordx4 v[112:115], v[86:87], off offset:896
	ds_read_b128 v[100:103], v70 offset:23136
	s_waitcnt lgkmcnt(3)
	v_mfma_f32_32x32x16_bf16 v[2:17], v[88:91], v[92:95], v[2:17]
	ds_read_b128 v[92:95], v1 offset:55360
	v_mfma_f32_32x32x16_bf16 v[18:33], v[88:91], v[96:99], v[18:33]
	ds_read_b128 v[88:91], v70 offset:18496
	ds_read_b128 v[96:99], v1 offset:59968
	s_waitcnt lgkmcnt(1)
	v_mfma_f32_32x32x16_bf16 v[34:49], v[88:91], v[92:95], v[34:49]
	s_waitcnt lgkmcnt(0)
	v_mfma_f32_32x32x16_bf16 v[50:65], v[88:91], v[96:99], v[50:65]
	s_waitcnt vmcnt(7)
	ds_write_b128 v66, v[144:147] offset:36864
	s_waitcnt vmcnt(6)
	ds_write_b128 v66, v[124:127] offset:41472
	global_load_dwordx4 v[144:147], v[78:79], off offset:896
	global_load_dwordx4 v[124:127], v[80:81], off offset:896
	ds_read_b128 v[88:91], v70 offset:23104
	s_waitcnt lgkmcnt(0)
	v_mfma_f32_32x32x16_bf16 v[2:17], v[88:91], v[92:95], v[2:17]
	ds_read_b128 v[92:95], v1 offset:55392
	v_mfma_f32_32x32x16_bf16 v[18:33], v[88:91], v[96:99], v[18:33]
	ds_read_b128 v[88:91], v70 offset:18528
	ds_read_b128 v[96:99], v1 offset:60000
	s_waitcnt lgkmcnt(1)
	v_mfma_f32_32x32x16_bf16 v[34:49], v[88:91], v[92:95], v[34:49]
	s_waitcnt lgkmcnt(0)
	v_mfma_f32_32x32x16_bf16 v[50:65], v[88:91], v[96:99], v[50:65]
	s_waitcnt vmcnt(7)
	ds_write_b128 v66, v[120:123] offset:46080
	s_waitcnt vmcnt(6)
	ds_write_b128 v66, v[116:119] offset:50688
	global_load_dwordx4 v[120:123], v[82:83], off offset:896
	global_load_dwordx4 v[116:119], v[84:85], off offset:896
	v_mfma_f32_32x32x16_bf16 v[2:17], v[100:103], v[92:95], v[2:17]
	v_mfma_f32_32x32x16_bf16 v[18:33], v[100:103], v[96:99], v[18:33]
	s_setprio 0
	s_waitcnt lgkmcnt(0)
	s_barrier
	ds_read_b128 v[96:99], v70
	ds_read_b128 v[100:103], v70 offset:4608
	ds_read_b128 v[128:131], v1 offset:36864
	ds_read_b128 v[132:135], v1 offset:41472
	s_setprio 1
	ds_read_b128 v[88:91], v70 offset:32
	s_waitcnt lgkmcnt(2)
	v_mfma_f32_32x32x16_bf16 v[34:49], v[96:99], v[128:131], v[34:49]
	ds_read_b128 v[92:95], v1 offset:36896
	s_waitcnt lgkmcnt(2)
	v_mfma_f32_32x32x16_bf16 v[50:65], v[96:99], v[132:135], v[50:65]
	s_waitcnt vmcnt(7)
	ds_write_b128 v66, v[140:143] offset:18432
	s_waitcnt vmcnt(6)
	ds_write_b128 v66, v[104:107] offset:23040
	global_load_dwordx4 v[140:143], v[74:75], off offset:1024
	global_load_dwordx4 v[104:107], v[72:73], off offset:1024
	ds_read_b128 v[96:99], v1 offset:41504
	s_waitcnt lgkmcnt(3)
	v_mfma_f32_32x32x16_bf16 v[34:49], v[88:91], v[92:95], v[34:49]
	s_waitcnt lgkmcnt(0)
	v_mfma_f32_32x32x16_bf16 v[50:65], v[88:91], v[96:99], v[50:65]
	ds_read_b128 v[88:91], v70 offset:4640
	v_mfma_f32_32x32x16_bf16 v[2:17], v[100:103], v[128:131], v[2:17]
	v_mfma_f32_32x32x16_bf16 v[18:33], v[100:103], v[132:135], v[18:33]
	s_waitcnt vmcnt(7)
	ds_write_b128 v66, v[108:111] offset:27648
	s_waitcnt vmcnt(6)
	ds_write_b128 v66, v[112:115] offset:32256
	global_load_dwordx4 v[108:111], v[76:77], off offset:1024
	global_load_dwordx4 v[112:115], v[86:87], off offset:1024
	ds_read_b128 v[100:103], v70 offset:4704
	s_waitcnt lgkmcnt(3)
	v_mfma_f32_32x32x16_bf16 v[2:17], v[88:91], v[92:95], v[2:17]
	ds_read_b128 v[92:95], v1 offset:36928
	v_mfma_f32_32x32x16_bf16 v[18:33], v[88:91], v[96:99], v[18:33]
	ds_read_b128 v[88:91], v70 offset:64
	ds_read_b128 v[96:99], v1 offset:41536
	s_waitcnt lgkmcnt(1)
	v_mfma_f32_32x32x16_bf16 v[34:49], v[88:91], v[92:95], v[34:49]
	s_waitcnt lgkmcnt(0)
	v_mfma_f32_32x32x16_bf16 v[50:65], v[88:91], v[96:99], v[50:65]
	s_waitcnt vmcnt(7)
	ds_write_b128 v66, v[144:147] offset:55296
	s_waitcnt vmcnt(6)
	ds_write_b128 v66, v[124:127] offset:59904
	global_load_dwordx4 v[144:147], v[78:79], off offset:1024
	global_load_dwordx4 v[124:127], v[80:81], off offset:1024
	ds_read_b128 v[88:91], v70 offset:4672
	s_waitcnt lgkmcnt(0)
	v_mfma_f32_32x32x16_bf16 v[2:17], v[88:91], v[92:95], v[2:17]
	ds_read_b128 v[92:95], v1 offset:36960
	v_mfma_f32_32x32x16_bf16 v[18:33], v[88:91], v[96:99], v[18:33]
	ds_read_b128 v[88:91], v70 offset:96
	ds_read_b128 v[96:99], v1 offset:41568
	s_waitcnt lgkmcnt(1)
	v_mfma_f32_32x32x16_bf16 v[34:49], v[88:91], v[92:95], v[34:49]
	s_waitcnt lgkmcnt(0)
	v_mfma_f32_32x32x16_bf16 v[50:65], v[88:91], v[96:99], v[50:65]
	s_waitcnt vmcnt(7)
	ds_write_b128 v66, v[120:123] offset:64512
	s_waitcnt vmcnt(6)
	ds_write_b128 v71, v[116:119] offset:32256
	global_load_dwordx4 v[120:123], v[82:83], off offset:1024
	global_load_dwordx4 v[116:119], v[84:85], off offset:1024
	v_mfma_f32_32x32x16_bf16 v[2:17], v[100:103], v[92:95], v[2:17]
	v_mfma_f32_32x32x16_bf16 v[18:33], v[100:103], v[96:99], v[18:33]
	s_setprio 0
	s_waitcnt lgkmcnt(0)
	s_barrier
; #define MFMA(a, b, c) __builtin_amdgcn_mfma_f32_32x32x16_bf16((a), (b), (c), 0, 0, 0)
; template <int TM, int TN>
; DI void gemm_mainloop(const u16* __restrict__ A, long lda, const u16* __restrict__ Bt, long ldb, int K, char* smem,
;                       f32x16 (&acc)[TM][TN]) {
;     ...
;   for (int kt = 0; kt < nk; kt++) {
;     const int buf = kt & 1;
;     const u16* cA = sA + buf * BM * LD + (wm * 32 * TM + r) * LD + h * 8;
;     const u16* cB = sB + buf * BN * LD + (wn * 32 * TN + r) * LD + h * 8;
;     bf16x8 af[TM], bfr[TN];
; #pragma unroll
;     for (int tm = 0; tm < TM; tm++) af[tm] = *(const bf16x8*)(cA + tm * 32 * LD);
; #pragma unroll
;     for (int tn = 0; tn < TN; tn++) bfr[tn] = *(const bf16x8*)(cB + tn * 32 * LD);
;     if (kt + 1 < nk) GEMM_SSTORE(buf ^ 1)
;     __builtin_amdgcn_sched_barrier(0);
;     __builtin_amdgcn_s_setprio(1);
; #pragma unroll
;     for (int tm = 0; tm < TM; tm++)
; #pragma unroll
;       for (int tn = 0; tn < TN; tn++) acc[tm][tn] = MFMA(af[tm], bfr[tn], acc[tm][tn]);
; #pragma unroll
;     for (int tm = 0; tm < TM; tm++) af[tm] = *(const bf16x8*)(cA + tm * 32 * LD + 16);
; #pragma unroll
;     for (int tn = 0; tn < TN; tn++) bfr[tn] = *(const bf16x8*)(cB + tn * 32 * LD + 16);
; #pragma unroll
;     for (int tm = 0; tm < TM; tm++)
; #pragma unroll
;       for (int tn = 0; tn < TN; tn++) acc[tm][tn] = MFMA(af[tm], bfr[tn], acc[tm][tn]);
;     __builtin_amdgcn_sched_group_barrier(0x8, 4, 0);
;     if (kt + 2 < nk) GEMM_GLOAD((kt + 2) * 64)
; #pragma unroll
;     for (int ks = 2; ks < 4; ks++) {
; #pragma unroll
;       for (int tm = 0; tm < TM; tm++) af[tm] = *(const bf16x8*)(cA + tm * 32 * LD + ks * 16);
; #pragma unroll
;       for (int tn = 0; tn < TN; tn++) bfr[tn] = *(const bf16x8*)(cB + tn * 32 * LD + ks * 16);
; #pragma unroll
;       for (int tm = 0; tm < TM; tm++)
; #pragma unroll
;         for (int tn = 0; tn < TN; tn++) acc[tm][tn] = MFMA(af[tm], bfr[tn], acc[tm][tn]);
;     }
;     __builtin_amdgcn_s_setprio(0);
;     __syncthreads();
;   }
	ds_read_b128 v[96:99], v70 offset:18432
	ds_read_b128 v[100:103], v70 offset:23040
	ds_read_b128 v[128:131], v1 offset:55296
	ds_read_b128 v[132:135], v1 offset:59904
	s_setprio 1
	ds_read_b128 v[88:91], v70 offset:18464
	s_waitcnt lgkmcnt(2)
	v_mfma_f32_32x32x16_bf16 v[34:49], v[96:99], v[128:131], v[34:49]
	ds_read_b128 v[92:95], v1 offset:55328
	s_waitcnt lgkmcnt(2)
	v_mfma_f32_32x32x16_bf16 v[50:65], v[96:99], v[132:135], v[50:65]
	s_waitcnt vmcnt(7)
	ds_write_b128 v66, v[140:143]
	s_waitcnt vmcnt(6)
	ds_write_b128 v66, v[104:107] offset:4608
	global_load_dwordx4 v[140:143], v[74:75], off offset:1152
	global_load_dwordx4 v[104:107], v[72:73], off offset:1152
	ds_read_b128 v[96:99], v1 offset:59936
	s_waitcnt lgkmcnt(3)
	v_mfma_f32_32x32x16_bf16 v[34:49], v[88:91], v[92:95], v[34:49]
	s_waitcnt lgkmcnt(0)
	v_mfma_f32_32x32x16_bf16 v[50:65], v[88:91], v[96:99], v[50:65]
	ds_read_b128 v[88:91], v70 offset:23072
	v_mfma_f32_32x32x16_bf16 v[2:17], v[100:103], v[128:131], v[2:17]
	v_mfma_f32_32x32x16_bf16 v[18:33], v[100:103], v[132:135], v[18:33]
	s_waitcnt vmcnt(7)
	ds_write_b128 v66, v[108:111] offset:9216
	s_waitcnt vmcnt(6)
	ds_write_b128 v66, v[112:115] offset:13824
	global_load_dwordx4 v[108:111], v[76:77], off offset:1152
	global_load_dwordx4 v[112:115], v[86:87], off offset:1152
	ds_read_b128 v[100:103], v70 offset:23136
	s_waitcnt lgkmcnt(3)
	v_mfma_f32_32x32x16_bf16 v[2:17], v[88:91], v[92:95], v[2:17]
	ds_read_b128 v[92:95], v1 offset:55360
	v_mfma_f32_32x32x16_bf16 v[18:33], v[88:91], v[96:99], v[18:33]
	ds_read_b128 v[88:91], v70 offset:18496
	ds_read_b128 v[96:99], v1 offset:59968
	s_waitcnt lgkmcnt(1)
	v_mfma_f32_32x32x16_bf16 v[34:49], v[88:91], v[92:95], v[34:49]
	s_waitcnt lgkmcnt(0)
	v_mfma_f32_32x32x16_bf16 v[50:65], v[88:91], v[96:99], v[50:65]
	s_waitcnt vmcnt(7)
	ds_write_b128 v66, v[144:147] offset:36864
	s_waitcnt vmcnt(6)
	ds_write_b128 v66, v[124:127] offset:41472
	global_load_dwordx4 v[144:147], v[78:79], off offset:1152
	global_load_dwordx4 v[124:127], v[80:81], off offset:1152
	ds_read_b128 v[88:91], v70 offset:23104
	s_waitcnt lgkmcnt(0)
	v_mfma_f32_32x32x16_bf16 v[2:17], v[88:91], v[92:95], v[2:17]
	ds_read_b128 v[92:95], v1 offset:55392
	v_mfma_f32_32x32x16_bf16 v[18:33], v[88:91], v[96:99], v[18:33]
	ds_read_b128 v[88:91], v70 offset:18528
	ds_read_b128 v[96:99], v1 offset:60000
	s_waitcnt lgkmcnt(1)
	v_mfma_f32_32x32x16_bf16 v[34:49], v[88:91], v[92:95], v[34:49]
	s_waitcnt lgkmcnt(0)
	v_mfma_f32_32x32x16_bf16 v[50:65], v[88:91], v[96:99], v[50:65]
	s_waitcnt vmcnt(7)
	ds_write_b128 v66, v[120:123] offset:46080
	s_waitcnt vmcnt(6)
	ds_write_b128 v66, v[116:119] offset:50688
	global_load_dwordx4 v[120:123], v[82:83], off offset:1152
	global_load_dwordx4 v[116:119], v[84:85], off offset:1152
	v_mfma_f32_32x32x16_bf16 v[2:17], v[100:103], v[92:95], v[2:17]
	v_mfma_f32_32x32x16_bf16 v[18:33], v[100:103], v[96:99], v[18:33]
	s_setprio 0
	s_waitcnt lgkmcnt(0)
	s_barrier
	ds_read_b128 v[96:99], v70
	ds_read_b128 v[100:103], v70 offset:4608
	ds_read_b128 v[128:131], v1 offset:36864
	ds_read_b128 v[132:135], v1 offset:41472
	s_setprio 1
	ds_read_b128 v[88:91], v70 offset:32
	s_waitcnt lgkmcnt(2)
	v_mfma_f32_32x32x16_bf16 v[34:49], v[96:99], v[128:131], v[34:49]
	ds_read_b128 v[92:95], v1 offset:36896
	s_waitcnt lgkmcnt(2)
	v_mfma_f32_32x32x16_bf16 v[50:65], v[96:99], v[132:135], v[50:65]
	s_waitcnt vmcnt(7)
	ds_write_b128 v66, v[140:143] offset:18432
	s_waitcnt vmcnt(6)
	ds_write_b128 v66, v[104:107] offset:23040
	global_load_dwordx4 v[140:143], v[74:75], off offset:1280
	global_load_dwordx4 v[104:107], v[72:73], off offset:1280
	ds_read_b128 v[96:99], v1 offset:41504
	s_waitcnt lgkmcnt(3)
	v_mfma_f32_32x32x16_bf16 v[34:49], v[88:91], v[92:95], v[34:49]
	s_waitcnt lgkmcnt(0)
	v_mfma_f32_32x32x16_bf16 v[50:65], v[88:91], v[96:99], v[50:65]
	ds_read_b128 v[88:91], v70 offset:4640
	v_mfma_f32_32x32x16_bf16 v[2:17], v[100:103], v[128:131], v[2:17]
	v_mfma_f32_32x32x16_bf16 v[18:33], v[100:103], v[132:135], v[18:33]
	s_waitcnt vmcnt(7)
	ds_write_b128 v66, v[108:111] offset:27648
	s_waitcnt vmcnt(6)
	ds_write_b128 v66, v[112:115] offset:32256
	global_load_dwordx4 v[108:111], v[76:77], off offset:1280
	global_load_dwordx4 v[112:115], v[86:87], off offset:1280
	ds_read_b128 v[100:103], v70 offset:4704
	s_waitcnt lgkmcnt(3)
	v_mfma_f32_32x32x16_bf16 v[2:17], v[88:91], v[92:95], v[2:17]
	ds_read_b128 v[92:95], v1 offset:36928
	v_mfma_f32_32x32x16_bf16 v[18:33], v[88:91], v[96:99], v[18:33]
	ds_read_b128 v[88:91], v70 offset:64
	ds_read_b128 v[96:99], v1 offset:41536
	s_waitcnt lgkmcnt(1)
	v_mfma_f32_32x32x16_bf16 v[34:49], v[88:91], v[92:95], v[34:49]
	s_waitcnt lgkmcnt(0)
	v_mfma_f32_32x32x16_bf16 v[50:65], v[88:91], v[96:99], v[50:65]
	s_waitcnt vmcnt(7)
	ds_write_b128 v66, v[144:147] offset:55296
	s_waitcnt vmcnt(6)
	ds_write_b128 v66, v[124:127] offset:59904
	global_load_dwordx4 v[144:147], v[78:79], off offset:1280
	global_load_dwordx4 v[124:127], v[80:81], off offset:1280
	ds_read_b128 v[88:91], v70 offset:4672
	s_waitcnt lgkmcnt(0)
	v_mfma_f32_32x32x16_bf16 v[2:17], v[88:91], v[92:95], v[2:17]
	ds_read_b128 v[92:95], v1 offset:36960
	v_mfma_f32_32x32x16_bf16 v[18:33], v[88:91], v[96:99], v[18:33]
	ds_read_b128 v[88:91], v70 offset:96
	ds_read_b128 v[96:99], v1 offset:41568
	s_waitcnt lgkmcnt(1)
	v_mfma_f32_32x32x16_bf16 v[34:49], v[88:91], v[92:95], v[34:49]
	s_waitcnt lgkmcnt(0)
	v_mfma_f32_32x32x16_bf16 v[50:65], v[88:91], v[96:99], v[50:65]
	s_waitcnt vmcnt(7)
	ds_write_b128 v66, v[120:123] offset:64512
	s_waitcnt vmcnt(6)
	ds_write_b128 v71, v[116:119] offset:32256
	global_load_dwordx4 v[120:123], v[82:83], off offset:1280
	global_load_dwordx4 v[116:119], v[84:85], off offset:1280
	v_mfma_f32_32x32x16_bf16 v[2:17], v[100:103], v[92:95], v[2:17]
	v_mfma_f32_32x32x16_bf16 v[18:33], v[100:103], v[96:99], v[18:33]
	s_setprio 0
	s_waitcnt lgkmcnt(0)
	s_barrier
; #define MFMA(a, b, c) __builtin_amdgcn_mfma_f32_32x32x16_bf16((a), (b), (c), 0, 0, 0)
; template <int TM, int TN>
; DI void gemm_mainloop(const u16* __restrict__ A, long lda, const u16* __restrict__ Bt, long ldb, int K, char* smem,
;                       f32x16 (&acc)[TM][TN]) {
;     ...
;   for (int kt = 0; kt < nk; kt++) {
;     const int buf = kt & 1;
;     const u16* cA = sA + buf * BM * LD + (wm * 32 * TM + r) * LD + h * 8;
;     const u16* cB = sB + buf * BN * LD + (wn * 32 * TN + r) * LD + h * 8;
;     bf16x8 af[TM], bfr[TN];
; #pragma unroll
;     for (int tm = 0; tm < TM; tm++) af[tm] = *(const bf16x8*)(cA + tm * 32 * LD);
; #pragma unroll
;     for (int tn = 0; tn < TN; tn++) bfr[tn] = *(const bf16x8*)(cB + tn * 32 * LD);
;     if (kt + 1 < nk) GEMM_SSTORE(buf ^ 1)
;     __builtin_amdgcn_sched_barrier(0);
;     __builtin_amdgcn_s_setprio(1);
; #pragma unroll
;     for (int tm = 0; tm < TM; tm++)
; #pragma unroll
;       for (int tn = 0; tn < TN; tn++) acc[tm][tn] = MFMA(af[tm], bfr[tn], acc[tm][tn]);
; #pragma unroll
;     for (int tm = 0; tm < TM; tm++) af[tm] = *(const bf16x8*)(cA + tm * 32 * LD + 16);
; #pragma unroll
;     for (int tn = 0; tn < TN; tn++) bfr[tn] = *(const bf16x8*)(cB + tn * 32 * LD + 16);
; #pragma unroll
;     for (int tm = 0; tm < TM; tm++)
; #pragma unroll
;       for (int tn = 0; tn < TN; tn++) acc[tm][tn] = MFMA(af[tm], bfr[tn], acc[tm][tn]);
;     __builtin_amdgcn_sched_group_barrier(0x8, 4, 0);
;     if (kt + 2 < nk) GEMM_GLOAD((kt + 2) * 64)
; #pragma unroll
;     for (int ks = 2; ks < 4; ks++) {
; #pragma unroll
;       for (int tm = 0; tm < TM; tm++) af[tm] = *(const bf16x8*)(cA + tm * 32 * LD + ks * 16);
; #pragma unroll
;       for (int tn = 0; tn < TN; tn++) bfr[tn] = *(const bf16x8*)(cB + tn * 32 * LD + ks * 16);
; #pragma unroll
;       for (int tm = 0; tm < TM; tm++)
; #pragma unroll
;         for (int tn = 0; tn < TN; tn++) acc[tm][tn] = MFMA(af[tm], bfr[tn], acc[tm][tn]);
;     }
;     __builtin_amdgcn_s_setprio(0);
;     __syncthreads();
;   }
	ds_read_b128 v[96:99], v70 offset:18432
	ds_read_b128 v[100:103], v70 offset:23040
	ds_read_b128 v[128:131], v1 offset:55296
	ds_read_b128 v[132:135], v1 offset:59904
	s_setprio 1
	ds_read_b128 v[88:91], v70 offset:18464
	s_waitcnt lgkmcnt(2)
	v_mfma_f32_32x32x16_bf16 v[34:49], v[96:99], v[128:131], v[34:49]
	ds_read_b128 v[92:95], v1 offset:55328
	s_waitcnt lgkmcnt(2)
	v_mfma_f32_32x32x16_bf16 v[50:65], v[96:99], v[132:135], v[50:65]
	s_waitcnt vmcnt(7)
	ds_write_b128 v66, v[140:143]
	s_waitcnt vmcnt(6)
	ds_write_b128 v66, v[104:107] offset:4608
	global_load_dwordx4 v[140:143], v[74:75], off offset:1408
	global_load_dwordx4 v[104:107], v[72:73], off offset:1408
	ds_read_b128 v[96:99], v1 offset:59936
	s_waitcnt lgkmcnt(3)
	v_mfma_f32_32x32x16_bf16 v[34:49], v[88:91], v[92:95], v[34:49]
	s_waitcnt lgkmcnt(0)
	v_mfma_f32_32x32x16_bf16 v[50:65], v[88:91], v[96:99], v[50:65]
	ds_read_b128 v[88:91], v70 offset:23072
	v_mfma_f32_32x32x16_bf16 v[2:17], v[100:103], v[128:131], v[2:17]
	v_mfma_f32_32x32x16_bf16 v[18:33], v[100:103], v[132:135], v[18:33]
	s_waitcnt vmcnt(7)
	ds_write_b128 v66, v[108:111] offset:9216
	s_waitcnt vmcnt(6)
	ds_write_b128 v66, v[112:115] offset:13824
	global_load_dwordx4 v[108:111], v[76:77], off offset:1408
	global_load_dwordx4 v[112:115], v[86:87], off offset:1408
	ds_read_b128 v[100:103], v70 offset:23136
	s_waitcnt lgkmcnt(3)
	v_mfma_f32_32x32x16_bf16 v[2:17], v[88:91], v[92:95], v[2:17]
	ds_read_b128 v[92:95], v1 offset:55360
	v_mfma_f32_32x32x16_bf16 v[18:33], v[88:91], v[96:99], v[18:33]
	ds_read_b128 v[88:91], v70 offset:18496
	ds_read_b128 v[96:99], v1 offset:59968
	s_waitcnt lgkmcnt(1)
	v_mfma_f32_32x32x16_bf16 v[34:49], v[88:91], v[92:95], v[34:49]
	s_waitcnt lgkmcnt(0)
	v_mfma_f32_32x32x16_bf16 v[50:65], v[88:91], v[96:99], v[50:65]
	s_waitcnt vmcnt(7)
	ds_write_b128 v66, v[144:147] offset:36864
	s_waitcnt vmcnt(6)
	ds_write_b128 v66, v[124:127] offset:41472
	global_load_dwordx4 v[144:147], v[78:79], off offset:1408
	global_load_dwordx4 v[124:127], v[80:81], off offset:1408
	ds_read_b128 v[88:91], v70 offset:23104
	s_waitcnt lgkmcnt(0)
	v_mfma_f32_32x32x16_bf16 v[2:17], v[88:91], v[92:95], v[2:17]
	ds_read_b128 v[92:95], v1 offset:55392
	v_mfma_f32_32x32x16_bf16 v[18:33], v[88:91], v[96:99], v[18:33]
	ds_read_b128 v[88:91], v70 offset:18528
	ds_read_b128 v[96:99], v1 offset:60000
	s_waitcnt lgkmcnt(1)
	v_mfma_f32_32x32x16_bf16 v[34:49], v[88:91], v[92:95], v[34:49]
	s_waitcnt lgkmcnt(0)
	v_mfma_f32_32x32x16_bf16 v[50:65], v[88:91], v[96:99], v[50:65]
	s_waitcnt vmcnt(7)
	ds_write_b128 v66, v[120:123] offset:46080
	s_waitcnt vmcnt(6)
	ds_write_b128 v66, v[116:119] offset:50688
	global_load_dwordx4 v[120:123], v[82:83], off offset:1408
	global_load_dwordx4 v[116:119], v[84:85], off offset:1408
	v_mfma_f32_32x32x16_bf16 v[2:17], v[100:103], v[92:95], v[2:17]
	v_mfma_f32_32x32x16_bf16 v[18:33], v[100:103], v[96:99], v[18:33]
	s_setprio 0
	s_waitcnt lgkmcnt(0)
	s_barrier
	ds_read_b128 v[96:99], v70
	ds_read_b128 v[100:103], v70 offset:4608
	ds_read_b128 v[128:131], v1 offset:36864
	ds_read_b128 v[132:135], v1 offset:41472
	s_setprio 1
	ds_read_b128 v[88:91], v70 offset:32
	s_waitcnt lgkmcnt(2)
	v_mfma_f32_32x32x16_bf16 v[34:49], v[96:99], v[128:131], v[34:49]
	ds_read_b128 v[92:95], v1 offset:36896
	s_waitcnt lgkmcnt(2)
	v_mfma_f32_32x32x16_bf16 v[50:65], v[96:99], v[132:135], v[50:65]
	s_waitcnt vmcnt(7)
	ds_write_b128 v66, v[140:143] offset:18432
	s_waitcnt vmcnt(6)
	ds_write_b128 v66, v[104:107] offset:23040
	global_load_dwordx4 v[140:143], v[74:75], off offset:1536
	global_load_dwordx4 v[104:107], v[72:73], off offset:1536
	ds_read_b128 v[96:99], v1 offset:41504
	s_waitcnt lgkmcnt(3)
	v_mfma_f32_32x32x16_bf16 v[34:49], v[88:91], v[92:95], v[34:49]
	s_waitcnt lgkmcnt(0)
	v_mfma_f32_32x32x16_bf16 v[50:65], v[88:91], v[96:99], v[50:65]
	ds_read_b128 v[88:91], v70 offset:4640
	v_mfma_f32_32x32x16_bf16 v[2:17], v[100:103], v[128:131], v[2:17]
	v_mfma_f32_32x32x16_bf16 v[18:33], v[100:103], v[132:135], v[18:33]
	s_waitcnt vmcnt(7)
	ds_write_b128 v66, v[108:111] offset:27648
	s_waitcnt vmcnt(6)
	ds_write_b128 v66, v[112:115] offset:32256
	global_load_dwordx4 v[108:111], v[76:77], off offset:1536
	global_load_dwordx4 v[112:115], v[86:87], off offset:1536
	ds_read_b128 v[100:103], v70 offset:4704
	s_waitcnt lgkmcnt(3)
	v_mfma_f32_32x32x16_bf16 v[2:17], v[88:91], v[92:95], v[2:17]
	ds_read_b128 v[92:95], v1 offset:36928
	v_mfma_f32_32x32x16_bf16 v[18:33], v[88:91], v[96:99], v[18:33]
	ds_read_b128 v[88:91], v70 offset:64
	ds_read_b128 v[96:99], v1 offset:41536
	s_waitcnt lgkmcnt(1)
	v_mfma_f32_32x32x16_bf16 v[34:49], v[88:91], v[92:95], v[34:49]
	s_waitcnt lgkmcnt(0)
	v_mfma_f32_32x32x16_bf16 v[50:65], v[88:91], v[96:99], v[50:65]
	s_waitcnt vmcnt(7)
	ds_write_b128 v66, v[144:147] offset:55296
	s_waitcnt vmcnt(6)
	ds_write_b128 v66, v[124:127] offset:59904
	global_load_dwordx4 v[144:147], v[78:79], off offset:1536
	global_load_dwordx4 v[124:127], v[80:81], off offset:1536
	ds_read_b128 v[88:91], v70 offset:4672
	s_waitcnt lgkmcnt(0)
	v_mfma_f32_32x32x16_bf16 v[2:17], v[88:91], v[92:95], v[2:17]
	ds_read_b128 v[92:95], v1 offset:36960
	v_mfma_f32_32x32x16_bf16 v[18:33], v[88:91], v[96:99], v[18:33]
	ds_read_b128 v[88:91], v70 offset:96
	ds_read_b128 v[96:99], v1 offset:41568
	s_waitcnt lgkmcnt(1)
	v_mfma_f32_32x32x16_bf16 v[34:49], v[88:91], v[92:95], v[34:49]
	s_waitcnt lgkmcnt(0)
	v_mfma_f32_32x32x16_bf16 v[50:65], v[88:91], v[96:99], v[50:65]
	s_waitcnt vmcnt(7)
	ds_write_b128 v66, v[120:123] offset:64512
	s_waitcnt vmcnt(6)
	ds_write_b128 v71, v[116:119] offset:32256
	global_load_dwordx4 v[120:123], v[82:83], off offset:1536
	global_load_dwordx4 v[116:119], v[84:85], off offset:1536
	v_mfma_f32_32x32x16_bf16 v[2:17], v[100:103], v[92:95], v[2:17]
	v_mfma_f32_32x32x16_bf16 v[18:33], v[100:103], v[96:99], v[18:33]
	s_setprio 0
	s_waitcnt lgkmcnt(0)
	s_barrier
; #define MFMA(a, b, c) __builtin_amdgcn_mfma_f32_32x32x16_bf16((a), (b), (c), 0, 0, 0)
; template <int TM, int TN>
; DI void gemm_mainloop(const u16* __restrict__ A, long lda, const u16* __restrict__ Bt, long ldb, int K, char* smem,
;                       f32x16 (&acc)[TM][TN]) {
;     ...
;   for (int kt = 0; kt < nk; kt++) {
;     const int buf = kt & 1;
;     const u16* cA = sA + buf * BM * LD + (wm * 32 * TM + r) * LD + h * 8;
;     const u16* cB = sB + buf * BN * LD + (wn * 32 * TN + r) * LD + h * 8;
;     bf16x8 af[TM], bfr[TN];
; #pragma unroll
;     for (int tm = 0; tm < TM; tm++) af[tm] = *(const bf16x8*)(cA + tm * 32 * LD);
; #pragma unroll
;     for (int tn = 0; tn < TN; tn++) bfr[tn] = *(const bf16x8*)(cB + tn * 32 * LD);
;     if (kt + 1 < nk) GEMM_SSTORE(buf ^ 1)
;     __builtin_amdgcn_sched_barrier(0);
;     __builtin_amdgcn_s_setprio(1);
; #pragma unroll
;     for (int tm = 0; tm < TM; tm++)
; #pragma unroll
;       for (int tn = 0; tn < TN; tn++) acc[tm][tn] = MFMA(af[tm], bfr[tn], acc[tm][tn]);
; #pragma unroll
;     for (int tm = 0; tm < TM; tm++) af[tm] = *(const bf16x8*)(cA + tm * 32 * LD + 16);
; #pragma unroll
;     for (int tn = 0; tn < TN; tn++) bfr[tn] = *(const bf16x8*)(cB + tn * 32 * LD + 16);
; #pragma unroll
;     for (int tm = 0; tm < TM; tm++)
; #pragma unroll
;       for (int tn = 0; tn < TN; tn++) acc[tm][tn] = MFMA(af[tm], bfr[tn], acc[tm][tn]);
;     __builtin_amdgcn_sched_group_barrier(0x8, 4, 0);
;     if (kt + 2 < nk) GEMM_GLOAD((kt + 2) * 64)
; #pragma unroll
;     for (int ks = 2; ks < 4; ks++) {
; #pragma unroll
;       for (int tm = 0; tm < TM; tm++) af[tm] = *(const bf16x8*)(cA + tm * 32 * LD + ks * 16);
; #pragma unroll
;       for (int tn = 0; tn < TN; tn++) bfr[tn] = *(const bf16x8*)(cB + tn * 32 * LD + ks * 16);
; #pragma unroll
;       for (int tm = 0; tm < TM; tm++)
; #pragma unroll
;         for (int tn = 0; tn < TN; tn++) acc[tm][tn] = MFMA(af[tm], bfr[tn], acc[tm][tn]);
;     }
;     __builtin_amdgcn_s_setprio(0);
;     __syncthreads();
;   }
	ds_read_b128 v[96:99], v70 offset:18432
	ds_read_b128 v[100:103], v70 offset:23040
	ds_read_b128 v[128:131], v1 offset:55296
	ds_read_b128 v[132:135], v1 offset:59904
	s_setprio 1
	ds_read_b128 v[88:91], v70 offset:18464
	s_waitcnt lgkmcnt(2)
	v_mfma_f32_32x32x16_bf16 v[34:49], v[96:99], v[128:131], v[34:49]
	ds_read_b128 v[92:95], v1 offset:55328
	s_waitcnt lgkmcnt(2)
	v_mfma_f32_32x32x16_bf16 v[50:65], v[96:99], v[132:135], v[50:65]
	s_waitcnt vmcnt(7)
	ds_write_b128 v66, v[140:143]
	s_waitcnt vmcnt(6)
	ds_write_b128 v66, v[104:107] offset:4608
	global_load_dwordx4 v[140:143], v[74:75], off offset:1664
	global_load_dwordx4 v[104:107], v[72:73], off offset:1664
	ds_read_b128 v[96:99], v1 offset:59936
	s_waitcnt lgkmcnt(3)
	v_mfma_f32_32x32x16_bf16 v[34:49], v[88:91], v[92:95], v[34:49]
	s_waitcnt lgkmcnt(0)
	v_mfma_f32_32x32x16_bf16 v[50:65], v[88:91], v[96:99], v[50:65]
	ds_read_b128 v[88:91], v70 offset:23072
	v_mfma_f32_32x32x16_bf16 v[2:17], v[100:103], v[128:131], v[2:17]
	v_mfma_f32_32x32x16_bf16 v[18:33], v[100:103], v[132:135], v[18:33]
	s_waitcnt vmcnt(7)
	ds_write_b128 v66, v[108:111] offset:9216
	s_waitcnt vmcnt(6)
	ds_write_b128 v66, v[112:115] offset:13824
	global_load_dwordx4 v[108:111], v[76:77], off offset:1664
	global_load_dwordx4 v[112:115], v[86:87], off offset:1664
	ds_read_b128 v[100:103], v70 offset:23136
	s_waitcnt lgkmcnt(3)
	v_mfma_f32_32x32x16_bf16 v[2:17], v[88:91], v[92:95], v[2:17]
	ds_read_b128 v[92:95], v1 offset:55360
	v_mfma_f32_32x32x16_bf16 v[18:33], v[88:91], v[96:99], v[18:33]
	ds_read_b128 v[88:91], v70 offset:18496
	ds_read_b128 v[96:99], v1 offset:59968
	s_waitcnt lgkmcnt(1)
	v_mfma_f32_32x32x16_bf16 v[34:49], v[88:91], v[92:95], v[34:49]
	s_waitcnt lgkmcnt(0)
	v_mfma_f32_32x32x16_bf16 v[50:65], v[88:91], v[96:99], v[50:65]
	s_waitcnt vmcnt(7)
	ds_write_b128 v66, v[144:147] offset:36864
	s_waitcnt vmcnt(6)
	ds_write_b128 v66, v[124:127] offset:41472
	global_load_dwordx4 v[144:147], v[78:79], off offset:1664
	global_load_dwordx4 v[124:127], v[80:81], off offset:1664
	ds_read_b128 v[88:91], v70 offset:23104
	s_waitcnt lgkmcnt(0)
	v_mfma_f32_32x32x16_bf16 v[2:17], v[88:91], v[92:95], v[2:17]
	ds_read_b128 v[92:95], v1 offset:55392
	v_mfma_f32_32x32x16_bf16 v[18:33], v[88:91], v[96:99], v[18:33]
	ds_read_b128 v[88:91], v70 offset:18528
	ds_read_b128 v[96:99], v1 offset:60000
	s_waitcnt lgkmcnt(1)
	v_mfma_f32_32x32x16_bf16 v[34:49], v[88:91], v[92:95], v[34:49]
	s_waitcnt lgkmcnt(0)
	v_mfma_f32_32x32x16_bf16 v[50:65], v[88:91], v[96:99], v[50:65]
	s_waitcnt vmcnt(7)
	ds_write_b128 v66, v[120:123] offset:46080
	s_waitcnt vmcnt(6)
	ds_write_b128 v66, v[116:119] offset:50688
	global_load_dwordx4 v[120:123], v[82:83], off offset:1664
	global_load_dwordx4 v[116:119], v[84:85], off offset:1664
	v_mfma_f32_32x32x16_bf16 v[2:17], v[100:103], v[92:95], v[2:17]
	v_mfma_f32_32x32x16_bf16 v[18:33], v[100:103], v[96:99], v[18:33]
	s_setprio 0
	s_waitcnt lgkmcnt(0)
	s_barrier
	ds_read_b128 v[96:99], v70
	ds_read_b128 v[100:103], v70 offset:4608
	ds_read_b128 v[128:131], v1 offset:36864
	ds_read_b128 v[132:135], v1 offset:41472
	s_setprio 1
	ds_read_b128 v[88:91], v70 offset:32
	s_waitcnt lgkmcnt(2)
	v_mfma_f32_32x32x16_bf16 v[34:49], v[96:99], v[128:131], v[34:49]
	ds_read_b128 v[92:95], v1 offset:36896
	s_waitcnt lgkmcnt(2)
	v_mfma_f32_32x32x16_bf16 v[50:65], v[96:99], v[132:135], v[50:65]
	s_waitcnt vmcnt(7)
	ds_write_b128 v66, v[140:143] offset:18432
	s_waitcnt vmcnt(6)
	ds_write_b128 v66, v[104:107] offset:23040
	global_load_dwordx4 v[140:143], v[74:75], off offset:1792
	global_load_dwordx4 v[104:107], v[72:73], off offset:1792
	ds_read_b128 v[96:99], v1 offset:41504
	s_waitcnt lgkmcnt(3)
	v_mfma_f32_32x32x16_bf16 v[34:49], v[88:91], v[92:95], v[34:49]
	s_waitcnt lgkmcnt(0)
	v_mfma_f32_32x32x16_bf16 v[50:65], v[88:91], v[96:99], v[50:65]
	ds_read_b128 v[88:91], v70 offset:4640
	v_mfma_f32_32x32x16_bf16 v[2:17], v[100:103], v[128:131], v[2:17]
	v_mfma_f32_32x32x16_bf16 v[18:33], v[100:103], v[132:135], v[18:33]
	s_waitcnt vmcnt(7)
	ds_write_b128 v66, v[108:111] offset:27648
	s_waitcnt vmcnt(6)
	ds_write_b128 v66, v[112:115] offset:32256
	global_load_dwordx4 v[108:111], v[76:77], off offset:1792
	global_load_dwordx4 v[112:115], v[86:87], off offset:1792
	ds_read_b128 v[100:103], v70 offset:4704
	s_waitcnt lgkmcnt(3)
	v_mfma_f32_32x32x16_bf16 v[2:17], v[88:91], v[92:95], v[2:17]
	ds_read_b128 v[92:95], v1 offset:36928
	v_mfma_f32_32x32x16_bf16 v[18:33], v[88:91], v[96:99], v[18:33]
	ds_read_b128 v[88:91], v70 offset:64
	ds_read_b128 v[96:99], v1 offset:41536
	s_waitcnt lgkmcnt(1)
	v_mfma_f32_32x32x16_bf16 v[34:49], v[88:91], v[92:95], v[34:49]
	s_waitcnt lgkmcnt(0)
	v_mfma_f32_32x32x16_bf16 v[50:65], v[88:91], v[96:99], v[50:65]
	s_waitcnt vmcnt(7)
	ds_write_b128 v66, v[144:147] offset:55296
	s_waitcnt vmcnt(6)
	ds_write_b128 v66, v[124:127] offset:59904
	global_load_dwordx4 v[144:147], v[78:79], off offset:1792
	global_load_dwordx4 v[124:127], v[80:81], off offset:1792
	ds_read_b128 v[88:91], v70 offset:4672
	s_waitcnt lgkmcnt(0)
	v_mfma_f32_32x32x16_bf16 v[2:17], v[88:91], v[92:95], v[2:17]
	ds_read_b128 v[92:95], v1 offset:36960
	v_mfma_f32_32x32x16_bf16 v[18:33], v[88:91], v[96:99], v[18:33]
	ds_read_b128 v[88:91], v70 offset:96
	ds_read_b128 v[96:99], v1 offset:41568
	s_waitcnt lgkmcnt(1)
	v_mfma_f32_32x32x16_bf16 v[34:49], v[88:91], v[92:95], v[34:49]
	s_waitcnt lgkmcnt(0)
	v_mfma_f32_32x32x16_bf16 v[50:65], v[88:91], v[96:99], v[50:65]
	s_waitcnt vmcnt(7)
	ds_write_b128 v66, v[120:123] offset:64512
	s_waitcnt vmcnt(6)
	ds_write_b128 v71, v[116:119] offset:32256
	global_load_dwordx4 v[120:123], v[82:83], off offset:1792
	global_load_dwordx4 v[116:119], v[84:85], off offset:1792
	v_mfma_f32_32x32x16_bf16 v[2:17], v[100:103], v[92:95], v[2:17]
	v_mfma_f32_32x32x16_bf16 v[18:33], v[100:103], v[96:99], v[18:33]
	s_setprio 0
	s_waitcnt lgkmcnt(0)
	s_barrier
; #define MFMA(a, b, c) __builtin_amdgcn_mfma_f32_32x32x16_bf16((a), (b), (c), 0, 0, 0)
; template <int TM, int TN>
; DI void gemm_mainloop(const u16* __restrict__ A, long lda, const u16* __restrict__ Bt, long ldb, int K, char* smem,
;                       f32x16 (&acc)[TM][TN]) {
;     ...
;   for (int kt = 0; kt < nk; kt++) {
;     const int buf = kt & 1;
;     const u16* cA = sA + buf * BM * LD + (wm * 32 * TM + r) * LD + h * 8;
;     const u16* cB = sB + buf * BN * LD + (wn * 32 * TN + r) * LD + h * 8;
;     bf16x8 af[TM], bfr[TN];
; #pragma unroll
;     for (int tm = 0; tm < TM; tm++) af[tm] = *(const bf16x8*)(cA + tm * 32 * LD);
; #pragma unroll
;     for (int tn = 0; tn < TN; tn++) bfr[tn] = *(const bf16x8*)(cB + tn * 32 * LD);
;     if (kt + 1 < nk) GEMM_SSTORE(buf ^ 1)
;     __builtin_amdgcn_sched_barrier(0);
;     __builtin_amdgcn_s_setprio(1);
; #pragma unroll
;     for (int tm = 0; tm < TM; tm++)
; #pragma unroll
;       for (int tn = 0; tn < TN; tn++) acc[tm][tn] = MFMA(af[tm], bfr[tn], acc[tm][tn]);
; #pragma unroll
;     for (int tm = 0; tm < TM; tm++) af[tm] = *(const bf16x8*)(cA + tm * 32 * LD + 16);
; #pragma unroll
;     for (int tn = 0; tn < TN; tn++) bfr[tn] = *(const bf16x8*)(cB + tn * 32 * LD + 16);
; #pragma unroll
;     for (int tm = 0; tm < TM; tm++)
; #pragma unroll
;       for (int tn = 0; tn < TN; tn++) acc[tm][tn] = MFMA(af[tm], bfr[tn], acc[tm][tn]);
;     __builtin_amdgcn_sched_group_barrier(0x8, 4, 0);
;     if (kt + 2 < nk) GEMM_GLOAD((kt + 2) * 64)
; #pragma unroll
;     for (int ks = 2; ks < 4; ks++) {
; #pragma unroll
;       for (int tm = 0; tm < TM; tm++) af[tm] = *(const bf16x8*)(cA + tm * 32 * LD + ks * 16);
; #pragma unroll
;       for (int tn = 0; tn < TN; tn++) bfr[tn] = *(const bf16x8*)(cB + tn * 32 * LD + ks * 16);
; #pragma unroll
;       for (int tm = 0; tm < TM; tm++)
; #pragma unroll
;         for (int tn = 0; tn < TN; tn++) acc[tm][tn] = MFMA(af[tm], bfr[tn], acc[tm][tn]);
;     }
;     __builtin_amdgcn_s_setprio(0);
;     __syncthreads();
;   }
	ds_read_b128 v[96:99], v70 offset:18432
	ds_read_b128 v[100:103], v70 offset:23040
	ds_read_b128 v[128:131], v1 offset:55296
	ds_read_b128 v[132:135], v1 offset:59904
	s_setprio 1
	ds_read_b128 v[88:91], v70 offset:18464
	s_waitcnt lgkmcnt(2)
	v_mfma_f32_32x32x16_bf16 v[34:49], v[96:99], v[128:131], v[34:49]
	ds_read_b128 v[92:95], v1 offset:55328
	s_waitcnt lgkmcnt(2)
	v_mfma_f32_32x32x16_bf16 v[50:65], v[96:99], v[132:135], v[50:65]
	s_waitcnt vmcnt(7)
	ds_write_b128 v66, v[140:143]
	s_waitcnt vmcnt(6)
	ds_write_b128 v66, v[104:107] offset:4608
	global_load_dwordx4 v[140:143], v[74:75], off offset:1920
	global_load_dwordx4 v[104:107], v[72:73], off offset:1920
	ds_read_b128 v[96:99], v1 offset:59936
	s_waitcnt lgkmcnt(3)
	v_mfma_f32_32x32x16_bf16 v[34:49], v[88:91], v[92:95], v[34:49]
	s_waitcnt lgkmcnt(0)
	v_mfma_f32_32x32x16_bf16 v[50:65], v[88:91], v[96:99], v[50:65]
	ds_read_b128 v[88:91], v70 offset:23072
	v_mfma_f32_32x32x16_bf16 v[2:17], v[100:103], v[128:131], v[2:17]
	v_mfma_f32_32x32x16_bf16 v[18:33], v[100:103], v[132:135], v[18:33]
	s_waitcnt vmcnt(7)
	ds_write_b128 v66, v[108:111] offset:9216
	s_waitcnt vmcnt(6)
	ds_write_b128 v66, v[112:115] offset:13824
	global_load_dwordx4 v[108:111], v[76:77], off offset:1920
	global_load_dwordx4 v[112:115], v[86:87], off offset:1920
	ds_read_b128 v[100:103], v70 offset:23136
	s_waitcnt lgkmcnt(3)
	v_mfma_f32_32x32x16_bf16 v[2:17], v[88:91], v[92:95], v[2:17]
	ds_read_b128 v[92:95], v1 offset:55360
	v_mfma_f32_32x32x16_bf16 v[18:33], v[88:91], v[96:99], v[18:33]
	ds_read_b128 v[88:91], v70 offset:18496
	ds_read_b128 v[96:99], v1 offset:59968
	s_waitcnt lgkmcnt(1)
	v_mfma_f32_32x32x16_bf16 v[34:49], v[88:91], v[92:95], v[34:49]
	s_waitcnt lgkmcnt(0)
	v_mfma_f32_32x32x16_bf16 v[50:65], v[88:91], v[96:99], v[50:65]
	s_waitcnt vmcnt(7)
	ds_write_b128 v66, v[144:147] offset:36864
	s_waitcnt vmcnt(6)
	ds_write_b128 v66, v[124:127] offset:41472
	global_load_dwordx4 v[144:147], v[78:79], off offset:1920
	global_load_dwordx4 v[124:127], v[80:81], off offset:1920
	ds_read_b128 v[88:91], v70 offset:23104
	s_waitcnt lgkmcnt(0)
	v_mfma_f32_32x32x16_bf16 v[2:17], v[88:91], v[92:95], v[2:17]
	ds_read_b128 v[92:95], v1 offset:55392
	v_mfma_f32_32x32x16_bf16 v[18:33], v[88:91], v[96:99], v[18:33]
	ds_read_b128 v[88:91], v70 offset:18528
	ds_read_b128 v[96:99], v1 offset:60000
	s_waitcnt lgkmcnt(1)
	v_mfma_f32_32x32x16_bf16 v[34:49], v[88:91], v[92:95], v[34:49]
	s_waitcnt lgkmcnt(0)
	v_mfma_f32_32x32x16_bf16 v[50:65], v[88:91], v[96:99], v[50:65]
	s_waitcnt vmcnt(7)
	ds_write_b128 v66, v[120:123] offset:46080
	s_waitcnt vmcnt(6)
	ds_write_b128 v66, v[116:119] offset:50688
	global_load_dwordx4 v[120:123], v[82:83], off offset:1920
	global_load_dwordx4 v[116:119], v[84:85], off offset:1920
	s_nop 0
	v_mfma_f32_32x32x16_bf16 v[2:17], v[100:103], v[92:95], v[2:17]
	v_mfma_f32_32x32x16_bf16 v[18:33], v[100:103], v[96:99], v[18:33]
	s_setprio 0
	s_waitcnt lgkmcnt(0)
	s_barrier
	ds_read_b128 v[76:79], v70
	ds_read_b128 v[80:83], v70 offset:4608
	ds_read_b128 v[84:87], v1 offset:36864
	ds_read_b128 v[92:95], v1 offset:41472
	s_setprio 1
	ds_read_b128 v[72:75], v70 offset:32
	s_waitcnt lgkmcnt(2)
	v_mfma_f32_32x32x16_bf16 v[34:49], v[76:79], v[84:87], v[34:49]
	s_waitcnt lgkmcnt(1)
	v_mfma_f32_32x32x16_bf16 v[50:65], v[76:79], v[92:95], v[50:65]
	s_waitcnt vmcnt(7)
	ds_write_b128 v66, v[140:143] offset:18432
	s_waitcnt vmcnt(6)
	ds_write_b128 v66, v[104:107] offset:23040
	ds_read_b128 v[76:79], v1 offset:36896
	v_mfma_f32_32x32x16_bf16 v[2:17], v[80:83], v[84:87], v[2:17]
	v_mfma_f32_32x32x16_bf16 v[18:33], v[80:83], v[92:95], v[18:33]
	ds_read_b128 v[80:83], v1 offset:41504
	s_waitcnt lgkmcnt(1)
	v_mfma_f32_32x32x16_bf16 v[34:49], v[72:75], v[76:79], v[34:49]
	s_waitcnt lgkmcnt(0)
	v_mfma_f32_32x32x16_bf16 v[50:65], v[72:75], v[80:83], v[50:65]
	s_waitcnt vmcnt(5)
	ds_write_b128 v66, v[108:111] offset:27648
	s_waitcnt vmcnt(4)
	ds_write_b128 v66, v[112:115] offset:32256
	ds_read_b128 v[72:75], v70 offset:4640
	s_waitcnt lgkmcnt(0)
	v_mfma_f32_32x32x16_bf16 v[2:17], v[72:75], v[76:79], v[2:17]
	ds_read_b128 v[76:79], v1 offset:36928
	v_mfma_f32_32x32x16_bf16 v[18:33], v[72:75], v[80:83], v[18:33]
	ds_read_b128 v[72:75], v70 offset:64
	ds_read_b128 v[80:83], v1 offset:41536
	s_waitcnt lgkmcnt(1)
	v_mfma_f32_32x32x16_bf16 v[34:49], v[72:75], v[76:79], v[34:49]
	s_waitcnt lgkmcnt(0)
	v_mfma_f32_32x32x16_bf16 v[50:65], v[72:75], v[80:83], v[50:65]
	s_waitcnt vmcnt(3)
	ds_write_b128 v66, v[144:147] offset:55296
	s_waitcnt vmcnt(2)
	ds_write_b128 v66, v[124:127] offset:59904
	ds_read_b128 v[72:75], v70 offset:4672
	s_waitcnt lgkmcnt(0)
	v_mfma_f32_32x32x16_bf16 v[2:17], v[72:75], v[76:79], v[2:17]
	ds_read_b128 v[76:79], v1 offset:36960
	v_mfma_f32_32x32x16_bf16 v[18:33], v[72:75], v[80:83], v[18:33]
	ds_read_b128 v[72:75], v70 offset:96
	ds_read_b128 v[80:83], v1 offset:41568
	s_waitcnt lgkmcnt(1)
	v_mfma_f32_32x32x16_bf16 v[34:49], v[72:75], v[76:79], v[34:49]
	s_waitcnt lgkmcnt(0)
	v_mfma_f32_32x32x16_bf16 v[50:65], v[72:75], v[80:83], v[50:65]
	s_waitcnt vmcnt(1)
	ds_write_b128 v66, v[120:123] offset:64512
	s_waitcnt vmcnt(0)
	ds_write_b128 v71, v[116:119] offset:32256
	ds_read_b128 v[72:75], v70 offset:4704
	s_waitcnt lgkmcnt(0)
	v_mfma_f32_32x32x16_bf16 v[2:17], v[72:75], v[76:79], v[2:17]
	v_mfma_f32_32x32x16_bf16 v[18:33], v[72:75], v[80:83], v[18:33]
	s_setprio 0
	s_barrier
; #define MFMA(a, b, c) __builtin_amdgcn_mfma_f32_32x32x16_bf16((a), (b), (c), 0, 0, 0)
; template <int TM, int TN>
; DI void gemm_mainloop(const u16* __restrict__ A, long lda, const u16* __restrict__ Bt, long ldb, int K, char* smem,
;                       f32x16 (&acc)[TM][TN]) {
;     ...
;     for (int tm = 0; tm < TM; tm++) af[tm] = *(const bf16x8*)(cA + tm * 32 * LD + 16);
; #pragma unroll
;     for (int tn = 0; tn < TN; tn++) bfr[tn] = *(const bf16x8*)(cB + tn * 32 * LD + 16);
; #pragma unroll
;     for (int tm = 0; tm < TM; tm++)
; #pragma unroll
;       for (int tn = 0; tn < TN; tn++) acc[tm][tn] = MFMA(af[tm], bfr[tn], acc[tm][tn]);
;     __builtin_amdgcn_sched_group_barrier(0x8, 4, 0);
;     if (kt + 2 < nk) GEMM_GLOAD((kt + 2) * 64)
; #pragma unroll
;     for (int ks = 2; ks < 4; ks++) {
; #pragma unroll
;       for (int tm = 0; tm < TM; tm++) af[tm] = *(const bf16x8*)(cA + tm * 32 * LD + ks * 16);
; #pragma unroll
;       for (int tn = 0; tn < TN; tn++) bfr[tn] = *(const bf16x8*)(cB + tn * 32 * LD + ks * 16);
; #pragma unroll
;       for (int tm = 0; tm < TM; tm++)
; #pragma unroll
;         for (int tn = 0; tn < TN; tn++) acc[tm][tn] = MFMA(af[tm], bfr[tn], acc[tm][tn]);
;     }
;     __builtin_amdgcn_s_setprio(0);
;     __syncthreads();
;   }
;     ...
; }
; template <int TM, int TN, class Epi>
; DI void gemm_tile(const u16* A, long lda, const u16* Bt, long ldb, int K, int m0, int n0, char* smem, const Epi& epi) {
;   constexpr int BM = 64 * TM, BN = 64 * TN, LDC = BN + Epi::PAD;
;   f32x16 acc[TM][TN];
;   gemm_mainloop<TM, TN>(A + (long)m0 * lda, lda, Bt + (long)n0 * ldb, ldb, K, smem, acc);
;   const int tid = tidx(), lane = tid & 63, w = tid >> 6, r = lane & 31, h = lane >> 5;
;   const int wm = w >> 1, wn = w & 1;
;   float* Ct = (float*)smem;
; #pragma unroll
;   for (int tm = 0; tm < TM; tm++)
; #pragma unroll
;     for (int tn = 0; tn < TN; tn++)
; #pragma unroll
;       for (int i = 0; i < 16; i++)
;         Ct[(wm * 32 * TM + tm * 32 + crow(i, h)) * LDC + wn * 32 * TN + tn * 32 + r] = acc[tm][tn][i];
;   __syncthreads();
;   DI void operator()(const float* Ct, int ldc, int m0, int n0, int tid, int bm) const {
; #pragma unroll 4
;     for (int it = 0; it < bm / 16; it++) {
;       int id = tid + 256 * it; int row = id >> 4, c8 = (id & 15) * 8;
;       int n = n0 + c8;
;       if (n < nmax) {
	ds_read_b128 v[72:75], v70 offset:18432
	ds_read_b128 v[76:79], v70 offset:23040
	ds_read_b128 v[80:83], v1 offset:55296
	ds_read_b128 v[84:87], v1 offset:59904
	s_setprio 1
	s_waitcnt lgkmcnt(1)
	v_mfma_f32_32x32x16_bf16 v[34:49], v[72:75], v[80:83], v[34:49]
	s_waitcnt lgkmcnt(0)
	v_mfma_f32_32x32x16_bf16 v[50:65], v[72:75], v[84:87], v[50:65]
	ds_read_b128 v[72:75], v70 offset:18464
	v_mfma_f32_32x32x16_bf16 v[2:17], v[76:79], v[80:83], v[2:17]
	ds_read_b128 v[80:83], v1 offset:59936
	v_mfma_f32_32x32x16_bf16 v[18:33], v[76:79], v[84:87], v[18:33]
	ds_read_b128 v[76:79], v1 offset:55328
	s_waitcnt lgkmcnt(0)
	v_mfma_f32_32x32x16_bf16 v[34:49], v[72:75], v[76:79], v[34:49]
	v_mfma_f32_32x32x16_bf16 v[50:65], v[72:75], v[80:83], v[50:65]
	ds_read_b128 v[72:75], v70 offset:23072
	s_waitcnt lgkmcnt(0)
	v_mfma_f32_32x32x16_bf16 v[2:17], v[72:75], v[76:79], v[2:17]
	ds_read_b128 v[76:79], v1 offset:55360
	v_mfma_f32_32x32x16_bf16 v[18:33], v[72:75], v[80:83], v[18:33]
	ds_read_b128 v[72:75], v70 offset:18496
	ds_read_b128 v[80:83], v1 offset:59968
	s_waitcnt lgkmcnt(1)
	v_mfma_f32_32x32x16_bf16 v[34:49], v[72:75], v[76:79], v[34:49]
	s_waitcnt lgkmcnt(0)
	v_mfma_f32_32x32x16_bf16 v[50:65], v[72:75], v[80:83], v[50:65]
	ds_read_b128 v[72:75], v70 offset:23104
	s_waitcnt lgkmcnt(0)
	v_mfma_f32_32x32x16_bf16 v[2:17], v[72:75], v[76:79], v[2:17]
	ds_read_b128 v[76:79], v1 offset:55392
	v_mfma_f32_32x32x16_bf16 v[18:33], v[72:75], v[80:83], v[18:33]
	ds_read_b128 v[72:75], v70 offset:18528
	ds_read_b128 v[80:83], v1 offset:60000
	s_waitcnt lgkmcnt(1)
	v_mfma_f32_32x32x16_bf16 v[34:49], v[72:75], v[76:79], v[34:49]
	s_waitcnt lgkmcnt(0)
	v_mfma_f32_32x32x16_bf16 v[50:65], v[72:75], v[80:83], v[50:65]
	ds_read_b128 v[70:73], v70 offset:23136
	s_waitcnt lgkmcnt(0)
	v_mfma_f32_32x32x16_bf16 v[2:17], v[70:73], v[76:79], v[2:17]
	v_mfma_f32_32x32x16_bf16 v[18:33], v[70:73], v[80:83], v[18:33]
	s_setprio 0
	v_mov_b32_e32 v1, v0
	s_barrier
	s_mov_b32 s4, 0
	v_lshrrev_b32_e32 v66, 1, v1
	v_and_b32_e32 v66, 0xfffffc0, v66
	v_lshrrev_b32_e32 v70, 3, v1
	v_and_or_b32 v66, v70, 4, v66
	v_and_b32_e32 v70, 0x5f, v1
	v_mul_lo_u32 v66, v66, s24
	v_lshl_add_u32 v66, v70, 2, v66
	ds_write2_b32 v66, v34, v50 offset1:32
	v_add_u32_e32 v34, 0x400, v66
	ds_write2_b32 v34, v36, v52 offset0:8 offset1:40
	ds_write2_b32 v34, v37, v53 offset0:140 offset1:172
	v_add_u32_e32 v34, 0x1000, v66
	ds_write2_b32 v34, v38, v54 offset0:32 offset1:64
	ds_write2_b32 v34, v39, v55 offset0:164 offset1:196
	v_add_u32_e32 v34, 0x1400, v66
	ds_write2_b32 v34, v40, v56 offset0:40 offset1:72
	ds_write2_b32 v34, v41, v57 offset0:172 offset1:204
	v_add_u32_e32 v34, 0x2000, v66
	ds_write2_b32 v34, v42, v58 offset0:64 offset1:96
	ds_write2_b32 v34, v43, v59 offset0:196 offset1:228
	v_add_u32_e32 v34, 0x2400, v66
	ds_write2_b32 v34, v44, v60 offset0:72 offset1:104
	ds_write2_b32 v34, v45, v61 offset0:204 offset1:236
	v_add_u32_e32 v34, 0x3000, v66
	ds_write2_b32 v34, v46, v62 offset0:96 offset1:128
	v_add_u32_e32 v34, 0x3200, v66
	ds_write2_b32 v34, v47, v63 offset0:100 offset1:132
	v_add_u32_e32 v34, 0x3400, v66
	ds_write2_b32 v34, v48, v64 offset0:104 offset1:136
	v_add_u32_e32 v34, 0x3600, v66
	ds_write2_b32 v34, v49, v65 offset0:108 offset1:140
	v_add_u32_e32 v34, 0x4000, v66
	ds_write2_b32 v34, v2, v18 offset0:128 offset1:160
	v_add_u32_e32 v2, 0x4400, v66
	ds_write2_b32 v2, v3, v19 offset0:4 offset1:36
	ds_write2_b32 v2, v4, v20 offset0:136 offset1:168
	v_add_u32_e32 v2, 0x4800, v66
	ds_write2_b32 v2, v5, v21 offset0:12 offset1:44
	v_add_u32_e32 v2, 0x5000, v66
	ds_write2_b32 v2, v6, v22 offset0:160 offset1:192
	v_add_u32_e32 v2, 0x5400, v66
	ds_write2_b32 v2, v7, v23 offset0:36 offset1:68
	ds_write2_b32 v2, v8, v24 offset0:168 offset1:200
	v_add_u32_e32 v2, 0x5800, v66
	ds_write2_b32 v2, v9, v25 offset0:44 offset1:76
	v_add_u32_e32 v2, 0x6000, v66
	ds_write2_b32 v2, v10, v26 offset0:192 offset1:224
	v_add_u32_e32 v2, 0x6400, v66
	ds_write2_b32 v2, v11, v27 offset0:68 offset1:100
	ds_write2_b32 v2, v12, v28 offset0:200 offset1:232
	v_add_u32_e32 v2, 0x6800, v66
	ds_write2_b32 v2, v13, v29 offset0:76 offset1:108
	v_add_u32_e32 v2, 0x7200, v66
	ds_write2_b32 v2, v14, v30 offset0:96 offset1:128
	v_add_u32_e32 v2, 0x7400, v66
	ds_write2_b32 v2, v15, v31 offset0:100 offset1:132
	v_add_u32_e32 v2, 0x7600, v66
	ds_write2_b32 v2, v16, v32 offset0:104 offset1:136
	v_add_u32_e32 v2, 0x7800, v66
	ds_write2_b32 v2, v17, v33 offset0:108 offset1:140
	v_lshlrev_b32_e32 v2, 3, v1
	v_and_b32_e32 v2, 0x78, v2
	v_or_b32_e32 v4, s15, v2
	v_ashrrev_i32_e32 v5, 31, v4
	v_lshlrev_b32_e32 v2, 2, v2
	v_cmp_gt_i32_e32 vcc, s25, v4
	v_lshl_add_u64 v[4:5], v[4:5], 1, s[6:7]
	ds_write2_b32 v66, v35, v51 offset0:132 offset1:164
	s_waitcnt lgkmcnt(0)
	s_barrier
	s_branch .LBB0_1074

; #define MFMA(a, b, c) __builtin_amdgcn_mfma_f32_32x32x16_bf16((a), (b), (c), 0, 0, 0)
; template <int TM, int TN>
; DI void gemm_mainloop(const u16* __restrict__ A, long lda, const u16* __restrict__ Bt, long ldb, int K, char* smem,
;                       f32x16 (&acc)[TM][TN]) {
;     ...
;   const int nk = K / 64;
;   const int lrow = tid >> 3, lch = (tid & 7) * 8;
;   const u16* gA = A + (long)lrow * lda + lch;
;   const u16* gB = Bt + (long)lrow * ldb + lch;
;   const int soff = lrow * LD + lch;
;     ...
;   GEMM_GLOAD(0)
;   __syncthreads();
;   GEMM_SSTORE(0)
;   if (nk > 1) GEMM_GLOAD(64)
;   __syncthreads();
;   for (int kt = 0; kt < nk; kt++) {
;     const int buf = kt & 1;
;     const u16* cA = sA + buf * BM * LD + (wm * 32 * TM + r) * LD + h * 8;
;     const u16* cB = sB + buf * BN * LD + (wn * 32 * TN + r) * LD + h * 8;
;     bf16x8 af[TM], bfr[TN];
; #pragma unroll
;     for (int tm = 0; tm < TM; tm++) af[tm] = *(const bf16x8*)(cA + tm * 32 * LD);
; #pragma unroll
;     for (int tn = 0; tn < TN; tn++) bfr[tn] = *(const bf16x8*)(cB + tn * 32 * LD);
;     if (kt + 1 < nk) GEMM_SSTORE(buf ^ 1)
;     __builtin_amdgcn_sched_barrier(0);
;     __builtin_amdgcn_s_setprio(1);
; #pragma unroll
;     for (int tm = 0; tm < TM; tm++)
; #pragma unroll
;       for (int tn = 0; tn < TN; tn++) acc[tm][tn] = MFMA(af[tm], bfr[tn], acc[tm][tn]);
; #pragma unroll
;     for (int tm = 0; tm < TM; tm++) af[tm] = *(const bf16x8*)(cA + tm * 32 * LD + 16);
; #pragma unroll
;     for (int tn = 0; tn < TN; tn++) bfr[tn] = *(const bf16x8*)(cB + tn * 32 * LD + 16);
; #pragma unroll
;     for (int tm = 0; tm < TM; tm++)
; #pragma unroll
;       for (int tn = 0; tn < TN; tn++) acc[tm][tn] = MFMA(af[tm], bfr[tn], acc[tm][tn]);
;     __builtin_amdgcn_sched_group_barrier(0x8, 4, 0);
;     if (kt + 2 < nk) GEMM_GLOAD((kt + 2) * 64)
; template <class Epi>
; DI void phase_gemm128(const Sched& sc, const u16* A, long lda, const u16* Bt, long ldb, int K, int MT, int NT, int SN, char* smem, const Epi& epi) {
;     ...
;     for (int t = blockIdx.x; t < MT * NT; t += gridDim.x) {
;       int mt = t / NT, nt = t % NT;
;       gemm_tile<2, 2>(A, lda, Bt, ldb, K, mt * 128, nt * 128, smem, epi);
;     }
.LBB0_1337:
	s_ashr_i32 s4, s24, 31
	s_lshr_b32 s4, s4, 27
	s_add_i32 s4, s24, s4
	s_and_b32 s5, s4, 0xffffffe0
	s_lshl_b32 s4, s4, 2
	s_sub_i32 s26, s24, s5
	s_and_b32 s25, s4, 0xffffff80
	s_lshl_b32 s6, s26, 7
	s_mul_i32 s4, s25, 0x880
	s_mul_hi_i32 s5, s25, 0x880
	s_add_u32 s4, s8, s4
	v_mov_b32_e32 v1, v0
	s_addc_u32 s5, s9, s5
	s_ashr_i32 s7, s6, 31
	v_lshlrev_b32_e32 v2, 3, v1
	v_ashrrev_i32_e32 v68, 3, v1
	v_and_b32_e32 v69, 56, v2
	v_mov_b64_e32 v[2:3], s[4:5]
	v_mad_i64_i32 v[2:3], s[4:5], v68, s15, v[2:3]
	v_lshlrev_b32_e32 v66, 1, v69
	v_lshl_add_u64 v[72:73], v[2:3], 0, v[66:67]
	s_mul_i32 s26, s26, 0x44000
	v_add_co_u32_e32 v70, vcc, s17, v72
	s_mul_hi_i32 s27, s6, 0x880
	s_add_u32 s26, s10, s26
	v_addc_co_u32_e32 v71, vcc, 0, v73, vcc
	s_addc_u32 s27, s11, s27
	v_add_co_u32_e32 v74, vcc, s18, v72
	v_mov_b64_e32 v[2:3], s[26:27]
	s_nop 0
	v_addc_co_u32_e32 v75, vcc, 0, v73, vcc
	v_mad_i64_i32 v[18:19], s[4:5], v68, s15, v[2:3]
	v_add_co_u32_e32 v76, vcc, s19, v72
	v_lshl_add_u64 v[78:79], v[18:19], 0, v[66:67]
	s_nop 0
	v_addc_co_u32_e32 v77, vcc, 0, v73, vcc
	v_add_co_u32_e32 v80, vcc, s17, v78
	global_load_dwordx4 v[2:5], v[72:73], off
	s_nop 0
	v_addc_co_u32_e32 v81, vcc, 0, v79, vcc
	v_add_co_u32_e32 v82, vcc, s18, v78
	global_load_dwordx4 v[6:9], v[70:71], off
	s_nop 0
	v_addc_co_u32_e32 v83, vcc, 0, v79, vcc
	v_add_co_u32_e32 v84, vcc, s19, v78
	global_load_dwordx4 v[10:13], v[74:75], off
	s_nop 0
	v_addc_co_u32_e32 v85, vcc, 0, v79, vcc
	global_load_dwordx4 v[14:17], v[76:77], off
	global_load_dwordx4 v[18:21], v[78:79], off
	global_load_dwordx4 v[22:25], v[80:81], off
	global_load_dwordx4 v[26:29], v[82:83], off
	global_load_dwordx4 v[30:33], v[84:85], off
	s_barrier
	global_load_dwordx4 v[34:37], v[72:73], off offset:128
	global_load_dwordx4 v[38:41], v[70:71], off offset:128
	global_load_dwordx4 v[42:45], v[74:75], off offset:128
	global_load_dwordx4 v[46:49], v[76:77], off offset:128
	global_load_dwordx4 v[50:53], v[78:79], off offset:128
	global_load_dwordx4 v[54:57], v[80:81], off offset:128
	global_load_dwordx4 v[58:61], v[82:83], off offset:128
	global_load_dwordx4 v[62:65], v[84:85], off offset:128
	v_and_b32_e32 v66, 31, v1
	v_lshrrev_b32_e32 v86, 1, v1
	v_mul_lo_u32 v68, v68, s16
	v_and_or_b32 v87, v86, s20, v66
	v_and_b32_e32 v86, 16, v86
	v_and_b32_e32 v1, 0x5f, v1
	v_add_lshl_u32 v66, v68, v69, 1
	v_mad_u64_u32 v[68:69], s[4:5], v87, s21, v[86:87]
	v_mad_u32_u24 v1, v1, s21, v86
	v_add_u32_e32 v69, 0x9000, v66
	s_waitcnt vmcnt(15)
	ds_write_b128 v66, v[2:5]
	s_waitcnt vmcnt(14)
	ds_write_b128 v66, v[6:9] offset:4608
	s_waitcnt vmcnt(13)
	ds_write_b128 v66, v[10:13] offset:9216
	s_waitcnt vmcnt(12)
	ds_write_b128 v66, v[14:17] offset:13824
	s_waitcnt vmcnt(11)
	ds_write_b128 v66, v[18:21] offset:36864
	s_waitcnt vmcnt(10)
	ds_write_b128 v66, v[22:25] offset:41472
	s_waitcnt vmcnt(9)
	ds_write_b128 v66, v[26:29] offset:46080
	s_waitcnt vmcnt(8)
	ds_write_b128 v66, v[30:33] offset:50688
	s_waitcnt lgkmcnt(0)
	s_barrier
	ds_read_b128 v[2:5], v68
	ds_read_b128 v[18:21], v68 offset:4608
	ds_read_b128 v[6:9], v1 offset:36864
	ds_read_b128 v[22:25], v1 offset:41472
	s_waitcnt vmcnt(7)
	ds_write_b128 v66, v[34:37] offset:18432
	s_waitcnt vmcnt(6)
	ds_write_b128 v66, v[38:41] offset:23040
	s_waitcnt vmcnt(5)
	ds_write_b128 v66, v[42:45] offset:27648
	s_waitcnt vmcnt(4)
	ds_write_b128 v66, v[46:49] offset:32256
	s_waitcnt vmcnt(3)
	ds_write_b128 v66, v[50:53] offset:55296
	s_waitcnt vmcnt(2)
	ds_write_b128 v66, v[54:57] offset:59904
	s_waitcnt vmcnt(1)
	ds_write_b128 v66, v[58:61] offset:64512
	s_waitcnt vmcnt(0)
	ds_write_b128 v69, v[62:65] offset:32256
	s_setprio 1
	ds_read_b128 v[86:89], v68 offset:32
	s_waitcnt lgkmcnt(10)
	v_mfma_f32_32x32x16_bf16 v[34:49], v[2:5], v[6:9], 0
	ds_read_b128 v[90:93], v1 offset:36896
	ds_read_b128 v[94:97], v1 offset:41504
	ds_read_b128 v[98:101], v68 offset:4704
	global_load_dwordx4 v[102:105], v[70:71], off offset:256
	global_load_dwordx4 v[106:109], v[74:75], off offset:256
	global_load_dwordx4 v[110:113], v[76:77], off offset:256
	global_load_dwordx4 v[114:117], v[84:85], off offset:256
	s_waitcnt lgkmcnt(12)
	v_mfma_f32_32x32x16_bf16 v[50:65], v[2:5], v[22:25], 0
	global_load_dwordx4 v[118:121], v[82:83], off offset:256
	global_load_dwordx4 v[122:125], v[80:81], off offset:256
	global_load_dwordx4 v[140:143], v[72:73], off offset:256
	global_load_dwordx4 v[144:147], v[78:79], off offset:256
	s_waitcnt lgkmcnt(2)
	v_mfma_f32_32x32x16_bf16 v[34:49], v[86:89], v[90:93], v[34:49]
	s_waitcnt lgkmcnt(1)
	v_mfma_f32_32x32x16_bf16 v[50:65], v[86:89], v[94:97], v[50:65]
	ds_read_b128 v[86:89], v68 offset:4640
	v_mfma_f32_32x32x16_bf16 v[2:17], v[18:21], v[6:9], 0
	v_mfma_f32_32x32x16_bf16 v[18:33], v[18:21], v[22:25], 0
	s_waitcnt lgkmcnt(0)
	v_mfma_f32_32x32x16_bf16 v[2:17], v[86:89], v[90:93], v[2:17]
	ds_read_b128 v[90:93], v1 offset:36928
	v_mfma_f32_32x32x16_bf16 v[18:33], v[86:89], v[94:97], v[18:33]
	ds_read_b128 v[86:89], v68 offset:64
	ds_read_b128 v[94:97], v1 offset:41536
	s_waitcnt lgkmcnt(1)
	v_mfma_f32_32x32x16_bf16 v[34:49], v[86:89], v[90:93], v[34:49]
	s_waitcnt lgkmcnt(0)
	v_mfma_f32_32x32x16_bf16 v[50:65], v[86:89], v[94:97], v[50:65]
	ds_read_b128 v[86:89], v68 offset:4672
	s_waitcnt lgkmcnt(0)
	v_mfma_f32_32x32x16_bf16 v[2:17], v[86:89], v[90:93], v[2:17]
	ds_read_b128 v[90:93], v1 offset:36960
	v_mfma_f32_32x32x16_bf16 v[18:33], v[86:89], v[94:97], v[18:33]
	ds_read_b128 v[86:89], v68 offset:96
	ds_read_b128 v[94:97], v1 offset:41568
	s_waitcnt lgkmcnt(1)
	v_mfma_f32_32x32x16_bf16 v[34:49], v[86:89], v[90:93], v[34:49]
	s_waitcnt lgkmcnt(0)
	v_mfma_f32_32x32x16_bf16 v[50:65], v[86:89], v[94:97], v[50:65]
	v_mfma_f32_32x32x16_bf16 v[2:17], v[98:101], v[90:93], v[2:17]
	v_mfma_f32_32x32x16_bf16 v[18:33], v[98:101], v[94:97], v[18:33]
	s_setprio 0
	s_barrier
; #define MFMA(a, b, c) __builtin_amdgcn_mfma_f32_32x32x16_bf16((a), (b), (c), 0, 0, 0)
; template <int TM, int TN>
; DI void gemm_mainloop(const u16* __restrict__ A, long lda, const u16* __restrict__ Bt, long ldb, int K, char* smem,
;                       f32x16 (&acc)[TM][TN]) {
;     ...
;   for (int kt = 0; kt < nk; kt++) {
;     const int buf = kt & 1;
;     const u16* cA = sA + buf * BM * LD + (wm * 32 * TM + r) * LD + h * 8;
;     const u16* cB = sB + buf * BN * LD + (wn * 32 * TN + r) * LD + h * 8;
;     bf16x8 af[TM], bfr[TN];
; #pragma unroll
;     for (int tm = 0; tm < TM; tm++) af[tm] = *(const bf16x8*)(cA + tm * 32 * LD);
; #pragma unroll
;     for (int tn = 0; tn < TN; tn++) bfr[tn] = *(const bf16x8*)(cB + tn * 32 * LD);
;     if (kt + 1 < nk) GEMM_SSTORE(buf ^ 1)
;     __builtin_amdgcn_sched_barrier(0);
;     __builtin_amdgcn_s_setprio(1);
; #pragma unroll
;     for (int tm = 0; tm < TM; tm++)
; #pragma unroll
;       for (int tn = 0; tn < TN; tn++) acc[tm][tn] = MFMA(af[tm], bfr[tn], acc[tm][tn]);
; #pragma unroll
;     for (int tm = 0; tm < TM; tm++) af[tm] = *(const bf16x8*)(cA + tm * 32 * LD + 16);
; #pragma unroll
;     for (int tn = 0; tn < TN; tn++) bfr[tn] = *(const bf16x8*)(cB + tn * 32 * LD + 16);
; #pragma unroll
;     for (int tm = 0; tm < TM; tm++)
; #pragma unroll
;       for (int tn = 0; tn < TN; tn++) acc[tm][tn] = MFMA(af[tm], bfr[tn], acc[tm][tn]);
;     __builtin_amdgcn_sched_group_barrier(0x8, 4, 0);
;     if (kt + 2 < nk) GEMM_GLOAD((kt + 2) * 64)
; #pragma unroll
;     for (int ks = 2; ks < 4; ks++) {
; #pragma unroll
;       for (int tm = 0; tm < TM; tm++) af[tm] = *(const bf16x8*)(cA + tm * 32 * LD + ks * 16);
; #pragma unroll
;       for (int tn = 0; tn < TN; tn++) bfr[tn] = *(const bf16x8*)(cB + tn * 32 * LD + ks * 16);
; #pragma unroll
;       for (int tm = 0; tm < TM; tm++)
; #pragma unroll
;         for (int tn = 0; tn < TN; tn++) acc[tm][tn] = MFMA(af[tm], bfr[tn], acc[tm][tn]);
;     }
;     __builtin_amdgcn_s_setprio(0);
;     __syncthreads();
;   }
	ds_read_b128 v[94:97], v68 offset:18432
	ds_read_b128 v[98:101], v68 offset:23040
	ds_read_b128 v[126:129], v1 offset:55296
	ds_read_b128 v[130:133], v1 offset:59904
	s_waitcnt vmcnt(1)
	ds_write_b128 v66, v[140:143]
	ds_write_b128 v66, v[102:105] offset:4608
	ds_write_b128 v66, v[106:109] offset:9216
	ds_write_b128 v66, v[110:113] offset:13824
	s_waitcnt vmcnt(0)
	ds_write_b128 v66, v[144:147] offset:36864
	ds_write_b128 v66, v[122:125] offset:41472
	ds_write_b128 v66, v[118:121] offset:46080
	ds_write_b128 v66, v[114:117] offset:50688
	s_setprio 1
	ds_read_b128 v[86:89], v68 offset:18464
	s_waitcnt lgkmcnt(10)
	v_mfma_f32_32x32x16_bf16 v[34:49], v[94:97], v[126:129], v[34:49]
	ds_read_b128 v[90:93], v1 offset:55328
	global_load_dwordx4 v[102:105], v[70:71], off offset:384
	global_load_dwordx4 v[106:109], v[74:75], off offset:384
	global_load_dwordx4 v[110:113], v[76:77], off offset:384
	global_load_dwordx4 v[114:117], v[84:85], off offset:384
	global_load_dwordx4 v[118:121], v[82:83], off offset:384
	global_load_dwordx4 v[122:125], v[80:81], off offset:384
	global_load_dwordx4 v[140:143], v[72:73], off offset:384
	global_load_dwordx4 v[144:147], v[78:79], off offset:384
	s_waitcnt lgkmcnt(10)
	v_mfma_f32_32x32x16_bf16 v[50:65], v[94:97], v[130:133], v[50:65]
	ds_read_b128 v[94:97], v1 offset:59936
	s_waitcnt lgkmcnt(1)
	v_mfma_f32_32x32x16_bf16 v[34:49], v[86:89], v[90:93], v[34:49]
	s_waitcnt lgkmcnt(0)
	v_mfma_f32_32x32x16_bf16 v[50:65], v[86:89], v[94:97], v[50:65]
	ds_read_b128 v[86:89], v68 offset:23072
	v_mfma_f32_32x32x16_bf16 v[2:17], v[98:101], v[126:129], v[2:17]
	v_mfma_f32_32x32x16_bf16 v[18:33], v[98:101], v[130:133], v[18:33]
	ds_read_b128 v[98:101], v68 offset:23136
	s_waitcnt lgkmcnt(1)
	v_mfma_f32_32x32x16_bf16 v[2:17], v[86:89], v[90:93], v[2:17]
	ds_read_b128 v[90:93], v1 offset:55360
	v_mfma_f32_32x32x16_bf16 v[18:33], v[86:89], v[94:97], v[18:33]
	ds_read_b128 v[86:89], v68 offset:18496
	ds_read_b128 v[94:97], v1 offset:59968
	s_waitcnt lgkmcnt(1)
	v_mfma_f32_32x32x16_bf16 v[34:49], v[86:89], v[90:93], v[34:49]
	s_waitcnt lgkmcnt(0)
	v_mfma_f32_32x32x16_bf16 v[50:65], v[86:89], v[94:97], v[50:65]
	ds_read_b128 v[86:89], v68 offset:23104
	s_waitcnt lgkmcnt(0)
	v_mfma_f32_32x32x16_bf16 v[2:17], v[86:89], v[90:93], v[2:17]
	ds_read_b128 v[90:93], v1 offset:55392
	v_mfma_f32_32x32x16_bf16 v[18:33], v[86:89], v[94:97], v[18:33]
	ds_read_b128 v[86:89], v68 offset:18528
	ds_read_b128 v[94:97], v1 offset:60000
	s_waitcnt lgkmcnt(1)
	v_mfma_f32_32x32x16_bf16 v[34:49], v[86:89], v[90:93], v[34:49]
	s_waitcnt lgkmcnt(0)
	v_mfma_f32_32x32x16_bf16 v[50:65], v[86:89], v[94:97], v[50:65]
	v_mfma_f32_32x32x16_bf16 v[2:17], v[98:101], v[90:93], v[2:17]
	v_mfma_f32_32x32x16_bf16 v[18:33], v[98:101], v[94:97], v[18:33]
	s_setprio 0
	s_barrier
	ds_read_b128 v[94:97], v68
	ds_read_b128 v[98:101], v68 offset:4608
	ds_read_b128 v[126:129], v1 offset:36864
	ds_read_b128 v[130:133], v1 offset:41472
	s_waitcnt vmcnt(1)
	ds_write_b128 v66, v[140:143] offset:18432
	ds_write_b128 v66, v[102:105] offset:23040
	ds_write_b128 v66, v[106:109] offset:27648
	ds_write_b128 v66, v[110:113] offset:32256
	s_waitcnt vmcnt(0)
	ds_write_b128 v66, v[144:147] offset:55296
	ds_write_b128 v66, v[122:125] offset:59904
	ds_write_b128 v66, v[118:121] offset:64512
	ds_write_b128 v69, v[114:117] offset:32256
	s_setprio 1
	ds_read_b128 v[86:89], v68 offset:32
	s_waitcnt lgkmcnt(10)
	v_mfma_f32_32x32x16_bf16 v[34:49], v[94:97], v[126:129], v[34:49]
	ds_read_b128 v[90:93], v1 offset:36896
	global_load_dwordx4 v[102:105], v[70:71], off offset:512
	global_load_dwordx4 v[106:109], v[74:75], off offset:512
	global_load_dwordx4 v[110:113], v[76:77], off offset:512
	global_load_dwordx4 v[114:117], v[84:85], off offset:512
	global_load_dwordx4 v[118:121], v[82:83], off offset:512
	global_load_dwordx4 v[122:125], v[80:81], off offset:512
	global_load_dwordx4 v[140:143], v[72:73], off offset:512
	global_load_dwordx4 v[144:147], v[78:79], off offset:512
	s_waitcnt lgkmcnt(10)
	v_mfma_f32_32x32x16_bf16 v[50:65], v[94:97], v[130:133], v[50:65]
	ds_read_b128 v[94:97], v1 offset:41504
	s_waitcnt lgkmcnt(1)
	v_mfma_f32_32x32x16_bf16 v[34:49], v[86:89], v[90:93], v[34:49]
	s_waitcnt lgkmcnt(0)
	v_mfma_f32_32x32x16_bf16 v[50:65], v[86:89], v[94:97], v[50:65]
	ds_read_b128 v[86:89], v68 offset:4640
	v_mfma_f32_32x32x16_bf16 v[2:17], v[98:101], v[126:129], v[2:17]
	v_mfma_f32_32x32x16_bf16 v[18:33], v[98:101], v[130:133], v[18:33]
	ds_read_b128 v[98:101], v68 offset:4704
	s_waitcnt lgkmcnt(1)
	v_mfma_f32_32x32x16_bf16 v[2:17], v[86:89], v[90:93], v[2:17]
	ds_read_b128 v[90:93], v1 offset:36928
	v_mfma_f32_32x32x16_bf16 v[18:33], v[86:89], v[94:97], v[18:33]
	ds_read_b128 v[86:89], v68 offset:64
	ds_read_b128 v[94:97], v1 offset:41536
	s_waitcnt lgkmcnt(1)
	v_mfma_f32_32x32x16_bf16 v[34:49], v[86:89], v[90:93], v[34:49]
	s_waitcnt lgkmcnt(0)
	v_mfma_f32_32x32x16_bf16 v[50:65], v[86:89], v[94:97], v[50:65]
	ds_read_b128 v[86:89], v68 offset:4672
	s_waitcnt lgkmcnt(0)
	v_mfma_f32_32x32x16_bf16 v[2:17], v[86:89], v[90:93], v[2:17]
	ds_read_b128 v[90:93], v1 offset:36960
	v_mfma_f32_32x32x16_bf16 v[18:33], v[86:89], v[94:97], v[18:33]
	ds_read_b128 v[86:89], v68 offset:96
	ds_read_b128 v[94:97], v1 offset:41568
	s_waitcnt lgkmcnt(1)
	v_mfma_f32_32x32x16_bf16 v[34:49], v[86:89], v[90:93], v[34:49]
	s_waitcnt lgkmcnt(0)
	v_mfma_f32_32x32x16_bf16 v[50:65], v[86:89], v[94:97], v[50:65]
	v_mfma_f32_32x32x16_bf16 v[2:17], v[98:101], v[90:93], v[2:17]
	v_mfma_f32_32x32x16_bf16 v[18:33], v[98:101], v[94:97], v[18:33]
	s_setprio 0
	s_barrier
; #define MFMA(a, b, c) __builtin_amdgcn_mfma_f32_32x32x16_bf16((a), (b), (c), 0, 0, 0)
; template <int TM, int TN>
; DI void gemm_mainloop(const u16* __restrict__ A, long lda, const u16* __restrict__ Bt, long ldb, int K, char* smem,
;                       f32x16 (&acc)[TM][TN]) {
;     ...
;   for (int kt = 0; kt < nk; kt++) {
;     const int buf = kt & 1;
;     const u16* cA = sA + buf * BM * LD + (wm * 32 * TM + r) * LD + h * 8;
;     const u16* cB = sB + buf * BN * LD + (wn * 32 * TN + r) * LD + h * 8;
;     bf16x8 af[TM], bfr[TN];
; #pragma unroll
;     for (int tm = 0; tm < TM; tm++) af[tm] = *(const bf16x8*)(cA + tm * 32 * LD);
; #pragma unroll
;     for (int tn = 0; tn < TN; tn++) bfr[tn] = *(const bf16x8*)(cB + tn * 32 * LD);
;     if (kt + 1 < nk) GEMM_SSTORE(buf ^ 1)
;     __builtin_amdgcn_sched_barrier(0);
;     __builtin_amdgcn_s_setprio(1);
; #pragma unroll
;     for (int tm = 0; tm < TM; tm++)
; #pragma unroll
;       for (int tn = 0; tn < TN; tn++) acc[tm][tn] = MFMA(af[tm], bfr[tn], acc[tm][tn]);
; #pragma unroll
;     for (int tm = 0; tm < TM; tm++) af[tm] = *(const bf16x8*)(cA + tm * 32 * LD + 16);
; #pragma unroll
;     for (int tn = 0; tn < TN; tn++) bfr[tn] = *(const bf16x8*)(cB + tn * 32 * LD + 16);
; #pragma unroll
;     for (int tm = 0; tm < TM; tm++)
; #pragma unroll
;       for (int tn = 0; tn < TN; tn++) acc[tm][tn] = MFMA(af[tm], bfr[tn], acc[tm][tn]);
;     __builtin_amdgcn_sched_group_barrier(0x8, 4, 0);
;     if (kt + 2 < nk) GEMM_GLOAD((kt + 2) * 64)
; #pragma unroll
;     for (int ks = 2; ks < 4; ks++) {
; #pragma unroll
;       for (int tm = 0; tm < TM; tm++) af[tm] = *(const bf16x8*)(cA + tm * 32 * LD + ks * 16);
; #pragma unroll
;       for (int tn = 0; tn < TN; tn++) bfr[tn] = *(const bf16x8*)(cB + tn * 32 * LD + ks * 16);
; #pragma unroll
;       for (int tm = 0; tm < TM; tm++)
; #pragma unroll
;         for (int tn = 0; tn < TN; tn++) acc[tm][tn] = MFMA(af[tm], bfr[tn], acc[tm][tn]);
;     }
;     __builtin_amdgcn_s_setprio(0);
;     __syncthreads();
;   }
	ds_read_b128 v[94:97], v68 offset:18432
	ds_read_b128 v[98:101], v68 offset:23040
	ds_read_b128 v[126:129], v1 offset:55296
	ds_read_b128 v[130:133], v1 offset:59904
	s_waitcnt vmcnt(1)
	ds_write_b128 v66, v[140:143]
	ds_write_b128 v66, v[102:105] offset:4608
	ds_write_b128 v66, v[106:109] offset:9216
	ds_write_b128 v66, v[110:113] offset:13824
	s_waitcnt vmcnt(0)
	ds_write_b128 v66, v[144:147] offset:36864
	ds_write_b128 v66, v[122:125] offset:41472
	ds_write_b128 v66, v[118:121] offset:46080
	ds_write_b128 v66, v[114:117] offset:50688
	s_setprio 1
	ds_read_b128 v[86:89], v68 offset:18464
	s_waitcnt lgkmcnt(10)
	v_mfma_f32_32x32x16_bf16 v[34:49], v[94:97], v[126:129], v[34:49]
	ds_read_b128 v[90:93], v1 offset:55328
	global_load_dwordx4 v[102:105], v[70:71], off offset:640
	global_load_dwordx4 v[106:109], v[74:75], off offset:640
	global_load_dwordx4 v[110:113], v[76:77], off offset:640
	global_load_dwordx4 v[114:117], v[84:85], off offset:640
	global_load_dwordx4 v[118:121], v[82:83], off offset:640
	global_load_dwordx4 v[122:125], v[80:81], off offset:640
	global_load_dwordx4 v[140:143], v[72:73], off offset:640
	global_load_dwordx4 v[144:147], v[78:79], off offset:640
	s_waitcnt lgkmcnt(10)
	v_mfma_f32_32x32x16_bf16 v[50:65], v[94:97], v[130:133], v[50:65]
	ds_read_b128 v[94:97], v1 offset:59936
	s_waitcnt lgkmcnt(1)
	v_mfma_f32_32x32x16_bf16 v[34:49], v[86:89], v[90:93], v[34:49]
	s_waitcnt lgkmcnt(0)
	v_mfma_f32_32x32x16_bf16 v[50:65], v[86:89], v[94:97], v[50:65]
	ds_read_b128 v[86:89], v68 offset:23072
	v_mfma_f32_32x32x16_bf16 v[2:17], v[98:101], v[126:129], v[2:17]
	v_mfma_f32_32x32x16_bf16 v[18:33], v[98:101], v[130:133], v[18:33]
	ds_read_b128 v[98:101], v68 offset:23136
	s_waitcnt lgkmcnt(1)
	v_mfma_f32_32x32x16_bf16 v[2:17], v[86:89], v[90:93], v[2:17]
	ds_read_b128 v[90:93], v1 offset:55360
	v_mfma_f32_32x32x16_bf16 v[18:33], v[86:89], v[94:97], v[18:33]
	ds_read_b128 v[86:89], v68 offset:18496
	ds_read_b128 v[94:97], v1 offset:59968
	s_waitcnt lgkmcnt(1)
	v_mfma_f32_32x32x16_bf16 v[34:49], v[86:89], v[90:93], v[34:49]
	s_waitcnt lgkmcnt(0)
	v_mfma_f32_32x32x16_bf16 v[50:65], v[86:89], v[94:97], v[50:65]
	ds_read_b128 v[86:89], v68 offset:23104
	s_waitcnt lgkmcnt(0)
	v_mfma_f32_32x32x16_bf16 v[2:17], v[86:89], v[90:93], v[2:17]
	ds_read_b128 v[90:93], v1 offset:55392
	v_mfma_f32_32x32x16_bf16 v[18:33], v[86:89], v[94:97], v[18:33]
	ds_read_b128 v[86:89], v68 offset:18528
	ds_read_b128 v[94:97], v1 offset:60000
	s_waitcnt lgkmcnt(1)
	v_mfma_f32_32x32x16_bf16 v[34:49], v[86:89], v[90:93], v[34:49]
	s_waitcnt lgkmcnt(0)
	v_mfma_f32_32x32x16_bf16 v[50:65], v[86:89], v[94:97], v[50:65]
	v_mfma_f32_32x32x16_bf16 v[2:17], v[98:101], v[90:93], v[2:17]
	v_mfma_f32_32x32x16_bf16 v[18:33], v[98:101], v[94:97], v[18:33]
	s_setprio 0
	s_barrier
	ds_read_b128 v[94:97], v68
	ds_read_b128 v[98:101], v68 offset:4608
	ds_read_b128 v[126:129], v1 offset:36864
	ds_read_b128 v[130:133], v1 offset:41472
	s_waitcnt vmcnt(1)
	ds_write_b128 v66, v[140:143] offset:18432
	ds_write_b128 v66, v[102:105] offset:23040
	ds_write_b128 v66, v[106:109] offset:27648
	ds_write_b128 v66, v[110:113] offset:32256
	s_waitcnt vmcnt(0)
	ds_write_b128 v66, v[144:147] offset:55296
	ds_write_b128 v66, v[122:125] offset:59904
	ds_write_b128 v66, v[118:121] offset:64512
	ds_write_b128 v69, v[114:117] offset:32256
	s_setprio 1
	ds_read_b128 v[86:89], v68 offset:32
	s_waitcnt lgkmcnt(10)
	v_mfma_f32_32x32x16_bf16 v[34:49], v[94:97], v[126:129], v[34:49]
	ds_read_b128 v[90:93], v1 offset:36896
	global_load_dwordx4 v[102:105], v[70:71], off offset:768
	global_load_dwordx4 v[106:109], v[74:75], off offset:768
	global_load_dwordx4 v[110:113], v[76:77], off offset:768
	global_load_dwordx4 v[114:117], v[84:85], off offset:768
	global_load_dwordx4 v[118:121], v[82:83], off offset:768
	global_load_dwordx4 v[122:125], v[80:81], off offset:768
	global_load_dwordx4 v[140:143], v[72:73], off offset:768
	global_load_dwordx4 v[144:147], v[78:79], off offset:768
	s_waitcnt lgkmcnt(10)
	v_mfma_f32_32x32x16_bf16 v[50:65], v[94:97], v[130:133], v[50:65]
	ds_read_b128 v[94:97], v1 offset:41504
	s_waitcnt lgkmcnt(1)
	v_mfma_f32_32x32x16_bf16 v[34:49], v[86:89], v[90:93], v[34:49]
	s_waitcnt lgkmcnt(0)
	v_mfma_f32_32x32x16_bf16 v[50:65], v[86:89], v[94:97], v[50:65]
	ds_read_b128 v[86:89], v68 offset:4640
	v_mfma_f32_32x32x16_bf16 v[2:17], v[98:101], v[126:129], v[2:17]
	v_mfma_f32_32x32x16_bf16 v[18:33], v[98:101], v[130:133], v[18:33]
	ds_read_b128 v[98:101], v68 offset:4704
	s_waitcnt lgkmcnt(1)
	v_mfma_f32_32x32x16_bf16 v[2:17], v[86:89], v[90:93], v[2:17]
	ds_read_b128 v[90:93], v1 offset:36928
	v_mfma_f32_32x32x16_bf16 v[18:33], v[86:89], v[94:97], v[18:33]
	ds_read_b128 v[86:89], v68 offset:64
	ds_read_b128 v[94:97], v1 offset:41536
	s_waitcnt lgkmcnt(1)
	v_mfma_f32_32x32x16_bf16 v[34:49], v[86:89], v[90:93], v[34:49]
	s_waitcnt lgkmcnt(0)
	v_mfma_f32_32x32x16_bf16 v[50:65], v[86:89], v[94:97], v[50:65]
	ds_read_b128 v[86:89], v68 offset:4672
	s_waitcnt lgkmcnt(0)
	v_mfma_f32_32x32x16_bf16 v[2:17], v[86:89], v[90:93], v[2:17]
	ds_read_b128 v[90:93], v1 offset:36960
	v_mfma_f32_32x32x16_bf16 v[18:33], v[86:89], v[94:97], v[18:33]
	ds_read_b128 v[86:89], v68 offset:96
	ds_read_b128 v[94:97], v1 offset:41568
	s_waitcnt lgkmcnt(1)
	v_mfma_f32_32x32x16_bf16 v[34:49], v[86:89], v[90:93], v[34:49]
	s_waitcnt lgkmcnt(0)
	v_mfma_f32_32x32x16_bf16 v[50:65], v[86:89], v[94:97], v[50:65]
	v_mfma_f32_32x32x16_bf16 v[2:17], v[98:101], v[90:93], v[2:17]
	v_mfma_f32_32x32x16_bf16 v[18:33], v[98:101], v[94:97], v[18:33]
	s_setprio 0
	s_barrier
; #define MFMA(a, b, c) __builtin_amdgcn_mfma_f32_32x32x16_bf16((a), (b), (c), 0, 0, 0)
; template <int TM, int TN>
; DI void gemm_mainloop(const u16* __restrict__ A, long lda, const u16* __restrict__ Bt, long ldb, int K, char* smem,
;                       f32x16 (&acc)[TM][TN]) {
;     ...
;   for (int kt = 0; kt < nk; kt++) {
;     const int buf = kt & 1;
;     const u16* cA = sA + buf * BM * LD + (wm * 32 * TM + r) * LD + h * 8;
;     const u16* cB = sB + buf * BN * LD + (wn * 32 * TN + r) * LD + h * 8;
;     bf16x8 af[TM], bfr[TN];
; #pragma unroll
;     for (int tm = 0; tm < TM; tm++) af[tm] = *(const bf16x8*)(cA + tm * 32 * LD);
; #pragma unroll
;     for (int tn = 0; tn < TN; tn++) bfr[tn] = *(const bf16x8*)(cB + tn * 32 * LD);
;     if (kt + 1 < nk) GEMM_SSTORE(buf ^ 1)
;     __builtin_amdgcn_sched_barrier(0);
;     __builtin_amdgcn_s_setprio(1);
; #pragma unroll
;     for (int tm = 0; tm < TM; tm++)
; #pragma unroll
;       for (int tn = 0; tn < TN; tn++) acc[tm][tn] = MFMA(af[tm], bfr[tn], acc[tm][tn]);
; #pragma unroll
;     for (int tm = 0; tm < TM; tm++) af[tm] = *(const bf16x8*)(cA + tm * 32 * LD + 16);
; #pragma unroll
;     for (int tn = 0; tn < TN; tn++) bfr[tn] = *(const bf16x8*)(cB + tn * 32 * LD + 16);
; #pragma unroll
;     for (int tm = 0; tm < TM; tm++)
; #pragma unroll
;       for (int tn = 0; tn < TN; tn++) acc[tm][tn] = MFMA(af[tm], bfr[tn], acc[tm][tn]);
;     __builtin_amdgcn_sched_group_barrier(0x8, 4, 0);
;     if (kt + 2 < nk) GEMM_GLOAD((kt + 2) * 64)
; #pragma unroll
;     for (int ks = 2; ks < 4; ks++) {
; #pragma unroll
;       for (int tm = 0; tm < TM; tm++) af[tm] = *(const bf16x8*)(cA + tm * 32 * LD + ks * 16);
; #pragma unroll
;       for (int tn = 0; tn < TN; tn++) bfr[tn] = *(const bf16x8*)(cB + tn * 32 * LD + ks * 16);
; #pragma unroll
;       for (int tm = 0; tm < TM; tm++)
; #pragma unroll
;         for (int tn = 0; tn < TN; tn++) acc[tm][tn] = MFMA(af[tm], bfr[tn], acc[tm][tn]);
;     }
;     __builtin_amdgcn_s_setprio(0);
;     __syncthreads();
;   }
	ds_read_b128 v[94:97], v68 offset:18432
	ds_read_b128 v[98:101], v68 offset:23040
	ds_read_b128 v[126:129], v1 offset:55296
	ds_read_b128 v[130:133], v1 offset:59904
	s_waitcnt vmcnt(1)
	ds_write_b128 v66, v[140:143]
	ds_write_b128 v66, v[102:105] offset:4608
	ds_write_b128 v66, v[106:109] offset:9216
	ds_write_b128 v66, v[110:113] offset:13824
	s_waitcnt vmcnt(0)
	ds_write_b128 v66, v[144:147] offset:36864
	ds_write_b128 v66, v[122:125] offset:41472
	ds_write_b128 v66, v[118:121] offset:46080
	ds_write_b128 v66, v[114:117] offset:50688
	s_setprio 1
	ds_read_b128 v[86:89], v68 offset:18464
	s_waitcnt lgkmcnt(10)
	v_mfma_f32_32x32x16_bf16 v[34:49], v[94:97], v[126:129], v[34:49]
	ds_read_b128 v[90:93], v1 offset:55328
	global_load_dwordx4 v[102:105], v[70:71], off offset:896
	global_load_dwordx4 v[106:109], v[74:75], off offset:896
	global_load_dwordx4 v[110:113], v[76:77], off offset:896
	global_load_dwordx4 v[114:117], v[84:85], off offset:896
	global_load_dwordx4 v[118:121], v[82:83], off offset:896
	global_load_dwordx4 v[122:125], v[80:81], off offset:896
	global_load_dwordx4 v[140:143], v[72:73], off offset:896
	global_load_dwordx4 v[144:147], v[78:79], off offset:896
	s_waitcnt lgkmcnt(10)
	v_mfma_f32_32x32x16_bf16 v[50:65], v[94:97], v[130:133], v[50:65]
	ds_read_b128 v[94:97], v1 offset:59936
	s_waitcnt lgkmcnt(1)
	v_mfma_f32_32x32x16_bf16 v[34:49], v[86:89], v[90:93], v[34:49]
	s_waitcnt lgkmcnt(0)
	v_mfma_f32_32x32x16_bf16 v[50:65], v[86:89], v[94:97], v[50:65]
	ds_read_b128 v[86:89], v68 offset:23072
	v_mfma_f32_32x32x16_bf16 v[2:17], v[98:101], v[126:129], v[2:17]
	v_mfma_f32_32x32x16_bf16 v[18:33], v[98:101], v[130:133], v[18:33]
	ds_read_b128 v[98:101], v68 offset:23136
	s_waitcnt lgkmcnt(1)
	v_mfma_f32_32x32x16_bf16 v[2:17], v[86:89], v[90:93], v[2:17]
	ds_read_b128 v[90:93], v1 offset:55360
	v_mfma_f32_32x32x16_bf16 v[18:33], v[86:89], v[94:97], v[18:33]
	ds_read_b128 v[86:89], v68 offset:18496
	ds_read_b128 v[94:97], v1 offset:59968
	s_waitcnt lgkmcnt(1)
	v_mfma_f32_32x32x16_bf16 v[34:49], v[86:89], v[90:93], v[34:49]
	s_waitcnt lgkmcnt(0)
	v_mfma_f32_32x32x16_bf16 v[50:65], v[86:89], v[94:97], v[50:65]
	ds_read_b128 v[86:89], v68 offset:23104
	s_waitcnt lgkmcnt(0)
	v_mfma_f32_32x32x16_bf16 v[2:17], v[86:89], v[90:93], v[2:17]
	ds_read_b128 v[90:93], v1 offset:55392
	v_mfma_f32_32x32x16_bf16 v[18:33], v[86:89], v[94:97], v[18:33]
	ds_read_b128 v[86:89], v68 offset:18528
	ds_read_b128 v[94:97], v1 offset:60000
	s_waitcnt lgkmcnt(1)
	v_mfma_f32_32x32x16_bf16 v[34:49], v[86:89], v[90:93], v[34:49]
	s_waitcnt lgkmcnt(0)
	v_mfma_f32_32x32x16_bf16 v[50:65], v[86:89], v[94:97], v[50:65]
	v_mfma_f32_32x32x16_bf16 v[2:17], v[98:101], v[90:93], v[2:17]
	v_mfma_f32_32x32x16_bf16 v[18:33], v[98:101], v[94:97], v[18:33]
	s_setprio 0
	s_barrier
	ds_read_b128 v[94:97], v68
	ds_read_b128 v[98:101], v68 offset:4608
	ds_read_b128 v[126:129], v1 offset:36864
	ds_read_b128 v[130:133], v1 offset:41472
	s_waitcnt vmcnt(1)
	ds_write_b128 v66, v[140:143] offset:18432
	ds_write_b128 v66, v[102:105] offset:23040
	ds_write_b128 v66, v[106:109] offset:27648
	ds_write_b128 v66, v[110:113] offset:32256
	s_waitcnt vmcnt(0)
	ds_write_b128 v66, v[144:147] offset:55296
	ds_write_b128 v66, v[122:125] offset:59904
	ds_write_b128 v66, v[118:121] offset:64512
	ds_write_b128 v69, v[114:117] offset:32256
	s_setprio 1
	ds_read_b128 v[86:89], v68 offset:32
	s_waitcnt lgkmcnt(10)
	v_mfma_f32_32x32x16_bf16 v[34:49], v[94:97], v[126:129], v[34:49]
	ds_read_b128 v[90:93], v1 offset:36896
	global_load_dwordx4 v[102:105], v[70:71], off offset:1024
	global_load_dwordx4 v[106:109], v[74:75], off offset:1024
	global_load_dwordx4 v[110:113], v[76:77], off offset:1024
	global_load_dwordx4 v[114:117], v[84:85], off offset:1024
	global_load_dwordx4 v[118:121], v[82:83], off offset:1024
	global_load_dwordx4 v[122:125], v[80:81], off offset:1024
	global_load_dwordx4 v[140:143], v[72:73], off offset:1024
	global_load_dwordx4 v[144:147], v[78:79], off offset:1024
	s_waitcnt lgkmcnt(10)
	v_mfma_f32_32x32x16_bf16 v[50:65], v[94:97], v[130:133], v[50:65]
	ds_read_b128 v[94:97], v1 offset:41504
	s_waitcnt lgkmcnt(1)
	v_mfma_f32_32x32x16_bf16 v[34:49], v[86:89], v[90:93], v[34:49]
	s_waitcnt lgkmcnt(0)
	v_mfma_f32_32x32x16_bf16 v[50:65], v[86:89], v[94:97], v[50:65]
	ds_read_b128 v[86:89], v68 offset:4640
	v_mfma_f32_32x32x16_bf16 v[2:17], v[98:101], v[126:129], v[2:17]
	v_mfma_f32_32x32x16_bf16 v[18:33], v[98:101], v[130:133], v[18:33]
	ds_read_b128 v[98:101], v68 offset:4704
	s_waitcnt lgkmcnt(1)
	v_mfma_f32_32x32x16_bf16 v[2:17], v[86:89], v[90:93], v[2:17]
	ds_read_b128 v[90:93], v1 offset:36928
	v_mfma_f32_32x32x16_bf16 v[18:33], v[86:89], v[94:97], v[18:33]
	ds_read_b128 v[86:89], v68 offset:64
	ds_read_b128 v[94:97], v1 offset:41536
	s_waitcnt lgkmcnt(1)
	v_mfma_f32_32x32x16_bf16 v[34:49], v[86:89], v[90:93], v[34:49]
	s_waitcnt lgkmcnt(0)
	v_mfma_f32_32x32x16_bf16 v[50:65], v[86:89], v[94:97], v[50:65]
	ds_read_b128 v[86:89], v68 offset:4672
	s_waitcnt lgkmcnt(0)
	v_mfma_f32_32x32x16_bf16 v[2:17], v[86:89], v[90:93], v[2:17]
	ds_read_b128 v[90:93], v1 offset:36960
	v_mfma_f32_32x32x16_bf16 v[18:33], v[86:89], v[94:97], v[18:33]
	ds_read_b128 v[86:89], v68 offset:96
	ds_read_b128 v[94:97], v1 offset:41568
	s_waitcnt lgkmcnt(1)
	v_mfma_f32_32x32x16_bf16 v[34:49], v[86:89], v[90:93], v[34:49]
	s_waitcnt lgkmcnt(0)
	v_mfma_f32_32x32x16_bf16 v[50:65], v[86:89], v[94:97], v[50:65]
	v_mfma_f32_32x32x16_bf16 v[2:17], v[98:101], v[90:93], v[2:17]
	v_mfma_f32_32x32x16_bf16 v[18:33], v[98:101], v[94:97], v[18:33]
	s_setprio 0
	s_barrier
; #define MFMA(a, b, c) __builtin_amdgcn_mfma_f32_32x32x16_bf16((a), (b), (c), 0, 0, 0)
; template <int TM, int TN>
; DI void gemm_mainloop(const u16* __restrict__ A, long lda, const u16* __restrict__ Bt, long ldb, int K, char* smem,
;                       f32x16 (&acc)[TM][TN]) {
;     ...
;   for (int kt = 0; kt < nk; kt++) {
;     const int buf = kt & 1;
;     const u16* cA = sA + buf * BM * LD + (wm * 32 * TM + r) * LD + h * 8;
;     const u16* cB = sB + buf * BN * LD + (wn * 32 * TN + r) * LD + h * 8;
;     bf16x8 af[TM], bfr[TN];
; #pragma unroll
;     for (int tm = 0; tm < TM; tm++) af[tm] = *(const bf16x8*)(cA + tm * 32 * LD);
; #pragma unroll
;     for (int tn = 0; tn < TN; tn++) bfr[tn] = *(const bf16x8*)(cB + tn * 32 * LD);
;     if (kt + 1 < nk) GEMM_SSTORE(buf ^ 1)
;     __builtin_amdgcn_sched_barrier(0);
;     __builtin_amdgcn_s_setprio(1);
; #pragma unroll
;     for (int tm = 0; tm < TM; tm++)
; #pragma unroll
;       for (int tn = 0; tn < TN; tn++) acc[tm][tn] = MFMA(af[tm], bfr[tn], acc[tm][tn]);
; #pragma unroll
;     for (int tm = 0; tm < TM; tm++) af[tm] = *(const bf16x8*)(cA + tm * 32 * LD + 16);
; #pragma unroll
;     for (int tn = 0; tn < TN; tn++) bfr[tn] = *(const bf16x8*)(cB + tn * 32 * LD + 16);
; #pragma unroll
;     for (int tm = 0; tm < TM; tm++)
; #pragma unroll
;       for (int tn = 0; tn < TN; tn++) acc[tm][tn] = MFMA(af[tm], bfr[tn], acc[tm][tn]);
;     __builtin_amdgcn_sched_group_barrier(0x8, 4, 0);
;     if (kt + 2 < nk) GEMM_GLOAD((kt + 2) * 64)
; #pragma unroll
;     for (int ks = 2; ks < 4; ks++) {
; #pragma unroll
;       for (int tm = 0; tm < TM; tm++) af[tm] = *(const bf16x8*)(cA + tm * 32 * LD + ks * 16);
; #pragma unroll
;       for (int tn = 0; tn < TN; tn++) bfr[tn] = *(const bf16x8*)(cB + tn * 32 * LD + ks * 16);
; #pragma unroll
;       for (int tm = 0; tm < TM; tm++)
; #pragma unroll
;         for (int tn = 0; tn < TN; tn++) acc[tm][tn] = MFMA(af[tm], bfr[tn], acc[tm][tn]);
;     }
;     __builtin_amdgcn_s_setprio(0);
;     __syncthreads();
;   }
	ds_read_b128 v[94:97], v68 offset:18432
	ds_read_b128 v[98:101], v68 offset:23040
	ds_read_b128 v[126:129], v1 offset:55296
	ds_read_b128 v[130:133], v1 offset:59904
	s_waitcnt vmcnt(1)
	ds_write_b128 v66, v[140:143]
	ds_write_b128 v66, v[102:105] offset:4608
	ds_write_b128 v66, v[106:109] offset:9216
	ds_write_b128 v66, v[110:113] offset:13824
	s_waitcnt vmcnt(0)
	ds_write_b128 v66, v[144:147] offset:36864
	ds_write_b128 v66, v[122:125] offset:41472
	ds_write_b128 v66, v[118:121] offset:46080
	ds_write_b128 v66, v[114:117] offset:50688
	s_setprio 1
	ds_read_b128 v[86:89], v68 offset:18464
	s_waitcnt lgkmcnt(10)
	v_mfma_f32_32x32x16_bf16 v[34:49], v[94:97], v[126:129], v[34:49]
	ds_read_b128 v[90:93], v1 offset:55328
	global_load_dwordx4 v[102:105], v[70:71], off offset:1152
	global_load_dwordx4 v[106:109], v[74:75], off offset:1152
	global_load_dwordx4 v[110:113], v[76:77], off offset:1152
	global_load_dwordx4 v[114:117], v[84:85], off offset:1152
	global_load_dwordx4 v[118:121], v[82:83], off offset:1152
	global_load_dwordx4 v[122:125], v[80:81], off offset:1152
	global_load_dwordx4 v[140:143], v[72:73], off offset:1152
	global_load_dwordx4 v[144:147], v[78:79], off offset:1152
	s_waitcnt lgkmcnt(10)
	v_mfma_f32_32x32x16_bf16 v[50:65], v[94:97], v[130:133], v[50:65]
	ds_read_b128 v[94:97], v1 offset:59936
	s_waitcnt lgkmcnt(1)
	v_mfma_f32_32x32x16_bf16 v[34:49], v[86:89], v[90:93], v[34:49]
	s_waitcnt lgkmcnt(0)
	v_mfma_f32_32x32x16_bf16 v[50:65], v[86:89], v[94:97], v[50:65]
	ds_read_b128 v[86:89], v68 offset:23072
	v_mfma_f32_32x32x16_bf16 v[2:17], v[98:101], v[126:129], v[2:17]
	v_mfma_f32_32x32x16_bf16 v[18:33], v[98:101], v[130:133], v[18:33]
	ds_read_b128 v[98:101], v68 offset:23136
	s_waitcnt lgkmcnt(1)
	v_mfma_f32_32x32x16_bf16 v[2:17], v[86:89], v[90:93], v[2:17]
	ds_read_b128 v[90:93], v1 offset:55360
	v_mfma_f32_32x32x16_bf16 v[18:33], v[86:89], v[94:97], v[18:33]
	ds_read_b128 v[86:89], v68 offset:18496
	ds_read_b128 v[94:97], v1 offset:59968
	s_waitcnt lgkmcnt(1)
	v_mfma_f32_32x32x16_bf16 v[34:49], v[86:89], v[90:93], v[34:49]
	s_waitcnt lgkmcnt(0)
	v_mfma_f32_32x32x16_bf16 v[50:65], v[86:89], v[94:97], v[50:65]
	ds_read_b128 v[86:89], v68 offset:23104
	s_waitcnt lgkmcnt(0)
	v_mfma_f32_32x32x16_bf16 v[2:17], v[86:89], v[90:93], v[2:17]
	ds_read_b128 v[90:93], v1 offset:55392
	v_mfma_f32_32x32x16_bf16 v[18:33], v[86:89], v[94:97], v[18:33]
	ds_read_b128 v[86:89], v68 offset:18528
	ds_read_b128 v[94:97], v1 offset:60000
	s_waitcnt lgkmcnt(1)
	v_mfma_f32_32x32x16_bf16 v[34:49], v[86:89], v[90:93], v[34:49]
	s_waitcnt lgkmcnt(0)
	v_mfma_f32_32x32x16_bf16 v[50:65], v[86:89], v[94:97], v[50:65]
	v_mfma_f32_32x32x16_bf16 v[2:17], v[98:101], v[90:93], v[2:17]
	v_mfma_f32_32x32x16_bf16 v[18:33], v[98:101], v[94:97], v[18:33]
	s_setprio 0
	s_barrier
	ds_read_b128 v[94:97], v68
	ds_read_b128 v[98:101], v68 offset:4608
	ds_read_b128 v[126:129], v1 offset:36864
	ds_read_b128 v[130:133], v1 offset:41472
	s_waitcnt vmcnt(1)
	ds_write_b128 v66, v[140:143] offset:18432
	ds_write_b128 v66, v[102:105] offset:23040
	ds_write_b128 v66, v[106:109] offset:27648
	ds_write_b128 v66, v[110:113] offset:32256
	s_waitcnt vmcnt(0)
	ds_write_b128 v66, v[144:147] offset:55296
	ds_write_b128 v66, v[122:125] offset:59904
	ds_write_b128 v66, v[118:121] offset:64512
	ds_write_b128 v69, v[114:117] offset:32256
	s_setprio 1
	ds_read_b128 v[86:89], v68 offset:32
	s_waitcnt lgkmcnt(10)
	v_mfma_f32_32x32x16_bf16 v[34:49], v[94:97], v[126:129], v[34:49]
	ds_read_b128 v[90:93], v1 offset:36896
	global_load_dwordx4 v[102:105], v[70:71], off offset:1280
	global_load_dwordx4 v[106:109], v[74:75], off offset:1280
	global_load_dwordx4 v[110:113], v[76:77], off offset:1280
	global_load_dwordx4 v[114:117], v[84:85], off offset:1280
	global_load_dwordx4 v[118:121], v[82:83], off offset:1280
	global_load_dwordx4 v[122:125], v[80:81], off offset:1280
	global_load_dwordx4 v[140:143], v[72:73], off offset:1280
	global_load_dwordx4 v[144:147], v[78:79], off offset:1280
	s_waitcnt lgkmcnt(10)
	v_mfma_f32_32x32x16_bf16 v[50:65], v[94:97], v[130:133], v[50:65]
	ds_read_b128 v[94:97], v1 offset:41504
	s_waitcnt lgkmcnt(1)
	v_mfma_f32_32x32x16_bf16 v[34:49], v[86:89], v[90:93], v[34:49]
	s_waitcnt lgkmcnt(0)
	v_mfma_f32_32x32x16_bf16 v[50:65], v[86:89], v[94:97], v[50:65]
	ds_read_b128 v[86:89], v68 offset:4640
	v_mfma_f32_32x32x16_bf16 v[2:17], v[98:101], v[126:129], v[2:17]
	v_mfma_f32_32x32x16_bf16 v[18:33], v[98:101], v[130:133], v[18:33]
	ds_read_b128 v[98:101], v68 offset:4704
	s_waitcnt lgkmcnt(1)
	v_mfma_f32_32x32x16_bf16 v[2:17], v[86:89], v[90:93], v[2:17]
	ds_read_b128 v[90:93], v1 offset:36928
	v_mfma_f32_32x32x16_bf16 v[18:33], v[86:89], v[94:97], v[18:33]
	ds_read_b128 v[86:89], v68 offset:64
	ds_read_b128 v[94:97], v1 offset:41536
	s_waitcnt lgkmcnt(1)
	v_mfma_f32_32x32x16_bf16 v[34:49], v[86:89], v[90:93], v[34:49]
	s_waitcnt lgkmcnt(0)
	v_mfma_f32_32x32x16_bf16 v[50:65], v[86:89], v[94:97], v[50:65]
	ds_read_b128 v[86:89], v68 offset:4672
	s_waitcnt lgkmcnt(0)
	v_mfma_f32_32x32x16_bf16 v[2:17], v[86:89], v[90:93], v[2:17]
	ds_read_b128 v[90:93], v1 offset:36960
	v_mfma_f32_32x32x16_bf16 v[18:33], v[86:89], v[94:97], v[18:33]
	ds_read_b128 v[86:89], v68 offset:96
	ds_read_b128 v[94:97], v1 offset:41568
	s_waitcnt lgkmcnt(1)
	v_mfma_f32_32x32x16_bf16 v[34:49], v[86:89], v[90:93], v[34:49]
	s_waitcnt lgkmcnt(0)
	v_mfma_f32_32x32x16_bf16 v[50:65], v[86:89], v[94:97], v[50:65]
	v_mfma_f32_32x32x16_bf16 v[2:17], v[98:101], v[90:93], v[2:17]
	v_mfma_f32_32x32x16_bf16 v[18:33], v[98:101], v[94:97], v[18:33]
	s_setprio 0
	s_barrier
; #define MFMA(a, b, c) __builtin_amdgcn_mfma_f32_32x32x16_bf16((a), (b), (c), 0, 0, 0)
; template <int TM, int TN>
; DI void gemm_mainloop(const u16* __restrict__ A, long lda, const u16* __restrict__ Bt, long ldb, int K, char* smem,
;                       f32x16 (&acc)[TM][TN]) {
;     ...
;   for (int kt = 0; kt < nk; kt++) {
;     const int buf = kt & 1;
;     const u16* cA = sA + buf * BM * LD + (wm * 32 * TM + r) * LD + h * 8;
;     const u16* cB = sB + buf * BN * LD + (wn * 32 * TN + r) * LD + h * 8;
;     bf16x8 af[TM], bfr[TN];
; #pragma unroll
;     for (int tm = 0; tm < TM; tm++) af[tm] = *(const bf16x8*)(cA + tm * 32 * LD);
; #pragma unroll
;     for (int tn = 0; tn < TN; tn++) bfr[tn] = *(const bf16x8*)(cB + tn * 32 * LD);
;     if (kt + 1 < nk) GEMM_SSTORE(buf ^ 1)
;     __builtin_amdgcn_sched_barrier(0);
;     __builtin_amdgcn_s_setprio(1);
; #pragma unroll
;     for (int tm = 0; tm < TM; tm++)
; #pragma unroll
;       for (int tn = 0; tn < TN; tn++) acc[tm][tn] = MFMA(af[tm], bfr[tn], acc[tm][tn]);
; #pragma unroll
;     for (int tm = 0; tm < TM; tm++) af[tm] = *(const bf16x8*)(cA + tm * 32 * LD + 16);
; #pragma unroll
;     for (int tn = 0; tn < TN; tn++) bfr[tn] = *(const bf16x8*)(cB + tn * 32 * LD + 16);
; #pragma unroll
;     for (int tm = 0; tm < TM; tm++)
; #pragma unroll
;       for (int tn = 0; tn < TN; tn++) acc[tm][tn] = MFMA(af[tm], bfr[tn], acc[tm][tn]);
;     __builtin_amdgcn_sched_group_barrier(0x8, 4, 0);
;     if (kt + 2 < nk) GEMM_GLOAD((kt + 2) * 64)
; #pragma unroll
;     for (int ks = 2; ks < 4; ks++) {
; #pragma unroll
;       for (int tm = 0; tm < TM; tm++) af[tm] = *(const bf16x8*)(cA + tm * 32 * LD + ks * 16);
; #pragma unroll
;       for (int tn = 0; tn < TN; tn++) bfr[tn] = *(const bf16x8*)(cB + tn * 32 * LD + ks * 16);
; #pragma unroll
;       for (int tm = 0; tm < TM; tm++)
; #pragma unroll
;         for (int tn = 0; tn < TN; tn++) acc[tm][tn] = MFMA(af[tm], bfr[tn], acc[tm][tn]);
;     }
;     __builtin_amdgcn_s_setprio(0);
;     __syncthreads();
;   }
	ds_read_b128 v[94:97], v68 offset:18432
	ds_read_b128 v[98:101], v68 offset:23040
	ds_read_b128 v[126:129], v1 offset:55296
	ds_read_b128 v[130:133], v1 offset:59904
	s_waitcnt vmcnt(1)
	ds_write_b128 v66, v[140:143]
	ds_write_b128 v66, v[102:105] offset:4608
	ds_write_b128 v66, v[106:109] offset:9216
	ds_write_b128 v66, v[110:113] offset:13824
	s_waitcnt vmcnt(0)
	ds_write_b128 v66, v[144:147] offset:36864
	ds_write_b128 v66, v[122:125] offset:41472
	ds_write_b128 v66, v[118:121] offset:46080
	ds_write_b128 v66, v[114:117] offset:50688
	s_setprio 1
	ds_read_b128 v[86:89], v68 offset:18464
	s_waitcnt lgkmcnt(10)
	v_mfma_f32_32x32x16_bf16 v[34:49], v[94:97], v[126:129], v[34:49]
	ds_read_b128 v[90:93], v1 offset:55328
	global_load_dwordx4 v[102:105], v[70:71], off offset:1408
	global_load_dwordx4 v[106:109], v[74:75], off offset:1408
	global_load_dwordx4 v[110:113], v[76:77], off offset:1408
	global_load_dwordx4 v[114:117], v[84:85], off offset:1408
	global_load_dwordx4 v[118:121], v[82:83], off offset:1408
	global_load_dwordx4 v[122:125], v[80:81], off offset:1408
	global_load_dwordx4 v[140:143], v[72:73], off offset:1408
	global_load_dwordx4 v[144:147], v[78:79], off offset:1408
	s_waitcnt lgkmcnt(10)
	v_mfma_f32_32x32x16_bf16 v[50:65], v[94:97], v[130:133], v[50:65]
	ds_read_b128 v[94:97], v1 offset:59936
	s_waitcnt lgkmcnt(1)
	v_mfma_f32_32x32x16_bf16 v[34:49], v[86:89], v[90:93], v[34:49]
	s_waitcnt lgkmcnt(0)
	v_mfma_f32_32x32x16_bf16 v[50:65], v[86:89], v[94:97], v[50:65]
	ds_read_b128 v[86:89], v68 offset:23072
	v_mfma_f32_32x32x16_bf16 v[2:17], v[98:101], v[126:129], v[2:17]
	v_mfma_f32_32x32x16_bf16 v[18:33], v[98:101], v[130:133], v[18:33]
	ds_read_b128 v[98:101], v68 offset:23136
	s_waitcnt lgkmcnt(1)
	v_mfma_f32_32x32x16_bf16 v[2:17], v[86:89], v[90:93], v[2:17]
	ds_read_b128 v[90:93], v1 offset:55360
	v_mfma_f32_32x32x16_bf16 v[18:33], v[86:89], v[94:97], v[18:33]
	ds_read_b128 v[86:89], v68 offset:18496
	ds_read_b128 v[94:97], v1 offset:59968
	s_waitcnt lgkmcnt(1)
	v_mfma_f32_32x32x16_bf16 v[34:49], v[86:89], v[90:93], v[34:49]
	s_waitcnt lgkmcnt(0)
	v_mfma_f32_32x32x16_bf16 v[50:65], v[86:89], v[94:97], v[50:65]
	ds_read_b128 v[86:89], v68 offset:23104
	s_waitcnt lgkmcnt(0)
	v_mfma_f32_32x32x16_bf16 v[2:17], v[86:89], v[90:93], v[2:17]
	ds_read_b128 v[90:93], v1 offset:55392
	v_mfma_f32_32x32x16_bf16 v[18:33], v[86:89], v[94:97], v[18:33]
	ds_read_b128 v[86:89], v68 offset:18528
	ds_read_b128 v[94:97], v1 offset:60000
	s_waitcnt lgkmcnt(1)
	v_mfma_f32_32x32x16_bf16 v[34:49], v[86:89], v[90:93], v[34:49]
	s_waitcnt lgkmcnt(0)
	v_mfma_f32_32x32x16_bf16 v[50:65], v[86:89], v[94:97], v[50:65]
	v_mfma_f32_32x32x16_bf16 v[2:17], v[98:101], v[90:93], v[2:17]
	v_mfma_f32_32x32x16_bf16 v[18:33], v[98:101], v[94:97], v[18:33]
	s_setprio 0
	s_barrier
	ds_read_b128 v[94:97], v68
	ds_read_b128 v[98:101], v68 offset:4608
	ds_read_b128 v[126:129], v1 offset:36864
	ds_read_b128 v[130:133], v1 offset:41472
	s_waitcnt vmcnt(1)
	ds_write_b128 v66, v[140:143] offset:18432
	ds_write_b128 v66, v[102:105] offset:23040
	ds_write_b128 v66, v[106:109] offset:27648
	ds_write_b128 v66, v[110:113] offset:32256
	s_waitcnt vmcnt(0)
	ds_write_b128 v66, v[144:147] offset:55296
	ds_write_b128 v66, v[122:125] offset:59904
	ds_write_b128 v66, v[118:121] offset:64512
	ds_write_b128 v69, v[114:117] offset:32256
	s_setprio 1
	ds_read_b128 v[86:89], v68 offset:32
	s_waitcnt lgkmcnt(10)
	v_mfma_f32_32x32x16_bf16 v[34:49], v[94:97], v[126:129], v[34:49]
	ds_read_b128 v[90:93], v1 offset:36896
	global_load_dwordx4 v[102:105], v[70:71], off offset:1536
	global_load_dwordx4 v[106:109], v[74:75], off offset:1536
	global_load_dwordx4 v[110:113], v[76:77], off offset:1536
	global_load_dwordx4 v[114:117], v[84:85], off offset:1536
	global_load_dwordx4 v[118:121], v[82:83], off offset:1536
	global_load_dwordx4 v[122:125], v[80:81], off offset:1536
	global_load_dwordx4 v[140:143], v[72:73], off offset:1536
	global_load_dwordx4 v[144:147], v[78:79], off offset:1536
	s_waitcnt lgkmcnt(10)
	v_mfma_f32_32x32x16_bf16 v[50:65], v[94:97], v[130:133], v[50:65]
	ds_read_b128 v[94:97], v1 offset:41504
	s_waitcnt lgkmcnt(1)
	v_mfma_f32_32x32x16_bf16 v[34:49], v[86:89], v[90:93], v[34:49]
	s_waitcnt lgkmcnt(0)
	v_mfma_f32_32x32x16_bf16 v[50:65], v[86:89], v[94:97], v[50:65]
	ds_read_b128 v[86:89], v68 offset:4640
	v_mfma_f32_32x32x16_bf16 v[2:17], v[98:101], v[126:129], v[2:17]
	v_mfma_f32_32x32x16_bf16 v[18:33], v[98:101], v[130:133], v[18:33]
	ds_read_b128 v[98:101], v68 offset:4704
	s_waitcnt lgkmcnt(1)
	v_mfma_f32_32x32x16_bf16 v[2:17], v[86:89], v[90:93], v[2:17]
	ds_read_b128 v[90:93], v1 offset:36928
	v_mfma_f32_32x32x16_bf16 v[18:33], v[86:89], v[94:97], v[18:33]
	ds_read_b128 v[86:89], v68 offset:64
	ds_read_b128 v[94:97], v1 offset:41536
	s_waitcnt lgkmcnt(1)
	v_mfma_f32_32x32x16_bf16 v[34:49], v[86:89], v[90:93], v[34:49]
	s_waitcnt lgkmcnt(0)
	v_mfma_f32_32x32x16_bf16 v[50:65], v[86:89], v[94:97], v[50:65]
	ds_read_b128 v[86:89], v68 offset:4672
	s_waitcnt lgkmcnt(0)
	v_mfma_f32_32x32x16_bf16 v[2:17], v[86:89], v[90:93], v[2:17]
	ds_read_b128 v[90:93], v1 offset:36960
	v_mfma_f32_32x32x16_bf16 v[18:33], v[86:89], v[94:97], v[18:33]
	ds_read_b128 v[86:89], v68 offset:96
	ds_read_b128 v[94:97], v1 offset:41568
	s_waitcnt lgkmcnt(1)
	v_mfma_f32_32x32x16_bf16 v[34:49], v[86:89], v[90:93], v[34:49]
	s_waitcnt lgkmcnt(0)
	v_mfma_f32_32x32x16_bf16 v[50:65], v[86:89], v[94:97], v[50:65]
	v_mfma_f32_32x32x16_bf16 v[2:17], v[98:101], v[90:93], v[2:17]
	v_mfma_f32_32x32x16_bf16 v[18:33], v[98:101], v[94:97], v[18:33]
	s_setprio 0
	s_barrier
; #define MFMA(a, b, c) __builtin_amdgcn_mfma_f32_32x32x16_bf16((a), (b), (c), 0, 0, 0)
; template <int TM, int TN>
; DI void gemm_mainloop(const u16* __restrict__ A, long lda, const u16* __restrict__ Bt, long ldb, int K, char* smem,
;                       f32x16 (&acc)[TM][TN]) {
;     ...
;   for (int kt = 0; kt < nk; kt++) {
;     const int buf = kt & 1;
;     const u16* cA = sA + buf * BM * LD + (wm * 32 * TM + r) * LD + h * 8;
;     const u16* cB = sB + buf * BN * LD + (wn * 32 * TN + r) * LD + h * 8;
;     bf16x8 af[TM], bfr[TN];
; #pragma unroll
;     for (int tm = 0; tm < TM; tm++) af[tm] = *(const bf16x8*)(cA + tm * 32 * LD);
; #pragma unroll
;     for (int tn = 0; tn < TN; tn++) bfr[tn] = *(const bf16x8*)(cB + tn * 32 * LD);
;     if (kt + 1 < nk) GEMM_SSTORE(buf ^ 1)
;     __builtin_amdgcn_sched_barrier(0);
;     __builtin_amdgcn_s_setprio(1);
; #pragma unroll
;     for (int tm = 0; tm < TM; tm++)
; #pragma unroll
;       for (int tn = 0; tn < TN; tn++) acc[tm][tn] = MFMA(af[tm], bfr[tn], acc[tm][tn]);
; #pragma unroll
;     for (int tm = 0; tm < TM; tm++) af[tm] = *(const bf16x8*)(cA + tm * 32 * LD + 16);
; #pragma unroll
;     for (int tn = 0; tn < TN; tn++) bfr[tn] = *(const bf16x8*)(cB + tn * 32 * LD + 16);
; #pragma unroll
;     for (int tm = 0; tm < TM; tm++)
; #pragma unroll
;       for (int tn = 0; tn < TN; tn++) acc[tm][tn] = MFMA(af[tm], bfr[tn], acc[tm][tn]);
;     __builtin_amdgcn_sched_group_barrier(0x8, 4, 0);
;     if (kt + 2 < nk) GEMM_GLOAD((kt + 2) * 64)
; #pragma unroll
;     for (int ks = 2; ks < 4; ks++) {
; #pragma unroll
;       for (int tm = 0; tm < TM; tm++) af[tm] = *(const bf16x8*)(cA + tm * 32 * LD + ks * 16);
; #pragma unroll
;       for (int tn = 0; tn < TN; tn++) bfr[tn] = *(const bf16x8*)(cB + tn * 32 * LD + ks * 16);
; #pragma unroll
;       for (int tm = 0; tm < TM; tm++)
; #pragma unroll
;         for (int tn = 0; tn < TN; tn++) acc[tm][tn] = MFMA(af[tm], bfr[tn], acc[tm][tn]);
;     }
;     __builtin_amdgcn_s_setprio(0);
;     __syncthreads();
;   }
	ds_read_b128 v[94:97], v68 offset:18432
	ds_read_b128 v[98:101], v68 offset:23040
	ds_read_b128 v[126:129], v1 offset:55296
	ds_read_b128 v[130:133], v1 offset:59904
	s_waitcnt vmcnt(1)
	ds_write_b128 v66, v[140:143]
	ds_write_b128 v66, v[102:105] offset:4608
	ds_write_b128 v66, v[106:109] offset:9216
	ds_write_b128 v66, v[110:113] offset:13824
	s_waitcnt vmcnt(0)
	ds_write_b128 v66, v[144:147] offset:36864
	ds_write_b128 v66, v[122:125] offset:41472
	ds_write_b128 v66, v[118:121] offset:46080
	ds_write_b128 v66, v[114:117] offset:50688
	s_setprio 1
	ds_read_b128 v[86:89], v68 offset:18464
	s_waitcnt lgkmcnt(10)
	v_mfma_f32_32x32x16_bf16 v[34:49], v[94:97], v[126:129], v[34:49]
	ds_read_b128 v[90:93], v1 offset:55328
	global_load_dwordx4 v[102:105], v[70:71], off offset:1664
	global_load_dwordx4 v[106:109], v[74:75], off offset:1664
	global_load_dwordx4 v[110:113], v[76:77], off offset:1664
	global_load_dwordx4 v[114:117], v[84:85], off offset:1664
	global_load_dwordx4 v[118:121], v[82:83], off offset:1664
	global_load_dwordx4 v[122:125], v[80:81], off offset:1664
	global_load_dwordx4 v[140:143], v[72:73], off offset:1664
	global_load_dwordx4 v[144:147], v[78:79], off offset:1664
	s_waitcnt lgkmcnt(10)
	v_mfma_f32_32x32x16_bf16 v[50:65], v[94:97], v[130:133], v[50:65]
	ds_read_b128 v[94:97], v1 offset:59936
	s_waitcnt lgkmcnt(1)
	v_mfma_f32_32x32x16_bf16 v[34:49], v[86:89], v[90:93], v[34:49]
	s_waitcnt lgkmcnt(0)
	v_mfma_f32_32x32x16_bf16 v[50:65], v[86:89], v[94:97], v[50:65]
	ds_read_b128 v[86:89], v68 offset:23072
	v_mfma_f32_32x32x16_bf16 v[2:17], v[98:101], v[126:129], v[2:17]
	v_mfma_f32_32x32x16_bf16 v[18:33], v[98:101], v[130:133], v[18:33]
	ds_read_b128 v[98:101], v68 offset:23136
	s_waitcnt lgkmcnt(1)
	v_mfma_f32_32x32x16_bf16 v[2:17], v[86:89], v[90:93], v[2:17]
	ds_read_b128 v[90:93], v1 offset:55360
	v_mfma_f32_32x32x16_bf16 v[18:33], v[86:89], v[94:97], v[18:33]
	ds_read_b128 v[86:89], v68 offset:18496
	ds_read_b128 v[94:97], v1 offset:59968
	s_waitcnt lgkmcnt(1)
	v_mfma_f32_32x32x16_bf16 v[34:49], v[86:89], v[90:93], v[34:49]
	s_waitcnt lgkmcnt(0)
	v_mfma_f32_32x32x16_bf16 v[50:65], v[86:89], v[94:97], v[50:65]
	ds_read_b128 v[86:89], v68 offset:23104
	s_waitcnt lgkmcnt(0)
	v_mfma_f32_32x32x16_bf16 v[2:17], v[86:89], v[90:93], v[2:17]
	ds_read_b128 v[90:93], v1 offset:55392
	v_mfma_f32_32x32x16_bf16 v[18:33], v[86:89], v[94:97], v[18:33]
	ds_read_b128 v[86:89], v68 offset:18528
	ds_read_b128 v[94:97], v1 offset:60000
	s_waitcnt lgkmcnt(1)
	v_mfma_f32_32x32x16_bf16 v[34:49], v[86:89], v[90:93], v[34:49]
	s_waitcnt lgkmcnt(0)
	v_mfma_f32_32x32x16_bf16 v[50:65], v[86:89], v[94:97], v[50:65]
	v_mfma_f32_32x32x16_bf16 v[2:17], v[98:101], v[90:93], v[2:17]
	v_mfma_f32_32x32x16_bf16 v[18:33], v[98:101], v[94:97], v[18:33]
	s_setprio 0
	s_barrier
	ds_read_b128 v[94:97], v68
	ds_read_b128 v[98:101], v68 offset:4608
	ds_read_b128 v[126:129], v1 offset:36864
	ds_read_b128 v[130:133], v1 offset:41472
	s_waitcnt vmcnt(1)
	ds_write_b128 v66, v[140:143] offset:18432
	ds_write_b128 v66, v[102:105] offset:23040
	ds_write_b128 v66, v[106:109] offset:27648
	ds_write_b128 v66, v[110:113] offset:32256
	s_waitcnt vmcnt(0)
	ds_write_b128 v66, v[144:147] offset:55296
	ds_write_b128 v66, v[122:125] offset:59904
	ds_write_b128 v66, v[118:121] offset:64512
	ds_write_b128 v69, v[114:117] offset:32256
	s_setprio 1
	ds_read_b128 v[86:89], v68 offset:32
	s_waitcnt lgkmcnt(10)
	v_mfma_f32_32x32x16_bf16 v[34:49], v[94:97], v[126:129], v[34:49]
	ds_read_b128 v[90:93], v1 offset:36896
	global_load_dwordx4 v[102:105], v[70:71], off offset:1792
	global_load_dwordx4 v[106:109], v[74:75], off offset:1792
	global_load_dwordx4 v[110:113], v[76:77], off offset:1792
	global_load_dwordx4 v[114:117], v[84:85], off offset:1792
	global_load_dwordx4 v[118:121], v[82:83], off offset:1792
	global_load_dwordx4 v[122:125], v[80:81], off offset:1792
	global_load_dwordx4 v[140:143], v[72:73], off offset:1792
	global_load_dwordx4 v[144:147], v[78:79], off offset:1792
	s_waitcnt lgkmcnt(10)
	v_mfma_f32_32x32x16_bf16 v[50:65], v[94:97], v[130:133], v[50:65]
	ds_read_b128 v[94:97], v1 offset:41504
	s_waitcnt lgkmcnt(1)
	v_mfma_f32_32x32x16_bf16 v[34:49], v[86:89], v[90:93], v[34:49]
	s_waitcnt lgkmcnt(0)
	v_mfma_f32_32x32x16_bf16 v[50:65], v[86:89], v[94:97], v[50:65]
	ds_read_b128 v[86:89], v68 offset:4640
	v_mfma_f32_32x32x16_bf16 v[2:17], v[98:101], v[126:129], v[2:17]
	v_mfma_f32_32x32x16_bf16 v[18:33], v[98:101], v[130:133], v[18:33]
	ds_read_b128 v[98:101], v68 offset:4704
	s_waitcnt lgkmcnt(1)
	v_mfma_f32_32x32x16_bf16 v[2:17], v[86:89], v[90:93], v[2:17]
	ds_read_b128 v[90:93], v1 offset:36928
	v_mfma_f32_32x32x16_bf16 v[18:33], v[86:89], v[94:97], v[18:33]
	ds_read_b128 v[86:89], v68 offset:64
	ds_read_b128 v[94:97], v1 offset:41536
	s_waitcnt lgkmcnt(1)
	v_mfma_f32_32x32x16_bf16 v[34:49], v[86:89], v[90:93], v[34:49]
	s_waitcnt lgkmcnt(0)
	v_mfma_f32_32x32x16_bf16 v[50:65], v[86:89], v[94:97], v[50:65]
	ds_read_b128 v[86:89], v68 offset:4672
	s_waitcnt lgkmcnt(0)
	v_mfma_f32_32x32x16_bf16 v[2:17], v[86:89], v[90:93], v[2:17]
	ds_read_b128 v[90:93], v1 offset:36960
	v_mfma_f32_32x32x16_bf16 v[18:33], v[86:89], v[94:97], v[18:33]
	ds_read_b128 v[86:89], v68 offset:96
	ds_read_b128 v[94:97], v1 offset:41568
	s_waitcnt lgkmcnt(1)
	v_mfma_f32_32x32x16_bf16 v[34:49], v[86:89], v[90:93], v[34:49]
	s_waitcnt lgkmcnt(0)
	v_mfma_f32_32x32x16_bf16 v[50:65], v[86:89], v[94:97], v[50:65]
	v_mfma_f32_32x32x16_bf16 v[2:17], v[98:101], v[90:93], v[2:17]
	v_mfma_f32_32x32x16_bf16 v[18:33], v[98:101], v[94:97], v[18:33]
	s_setprio 0
	s_barrier
; #define MFMA(a, b, c) __builtin_amdgcn_mfma_f32_32x32x16_bf16((a), (b), (c), 0, 0, 0)
; template <int TM, int TN>
; DI void gemm_mainloop(const u16* __restrict__ A, long lda, const u16* __restrict__ Bt, long ldb, int K, char* smem,
;                       f32x16 (&acc)[TM][TN]) {
;     ...
;   for (int kt = 0; kt < nk; kt++) {
;     const int buf = kt & 1;
;     const u16* cA = sA + buf * BM * LD + (wm * 32 * TM + r) * LD + h * 8;
;     const u16* cB = sB + buf * BN * LD + (wn * 32 * TN + r) * LD + h * 8;
;     bf16x8 af[TM], bfr[TN];
; #pragma unroll
;     for (int tm = 0; tm < TM; tm++) af[tm] = *(const bf16x8*)(cA + tm * 32 * LD);
; #pragma unroll
;     for (int tn = 0; tn < TN; tn++) bfr[tn] = *(const bf16x8*)(cB + tn * 32 * LD);
;     if (kt + 1 < nk) GEMM_SSTORE(buf ^ 1)
;     __builtin_amdgcn_sched_barrier(0);
;     __builtin_amdgcn_s_setprio(1);
; #pragma unroll
;     for (int tm = 0; tm < TM; tm++)
; #pragma unroll
;       for (int tn = 0; tn < TN; tn++) acc[tm][tn] = MFMA(af[tm], bfr[tn], acc[tm][tn]);
; #pragma unroll
;     for (int tm = 0; tm < TM; tm++) af[tm] = *(const bf16x8*)(cA + tm * 32 * LD + 16);
; #pragma unroll
;     for (int tn = 0; tn < TN; tn++) bfr[tn] = *(const bf16x8*)(cB + tn * 32 * LD + 16);
; #pragma unroll
;     for (int tm = 0; tm < TM; tm++)
; #pragma unroll
;       for (int tn = 0; tn < TN; tn++) acc[tm][tn] = MFMA(af[tm], bfr[tn], acc[tm][tn]);
;     __builtin_amdgcn_sched_group_barrier(0x8, 4, 0);
;     if (kt + 2 < nk) GEMM_GLOAD((kt + 2) * 64)
; #pragma unroll
;     for (int ks = 2; ks < 4; ks++) {
; #pragma unroll
;       for (int tm = 0; tm < TM; tm++) af[tm] = *(const bf16x8*)(cA + tm * 32 * LD + ks * 16);
; #pragma unroll
;       for (int tn = 0; tn < TN; tn++) bfr[tn] = *(const bf16x8*)(cB + tn * 32 * LD + ks * 16);
; #pragma unroll
;       for (int tm = 0; tm < TM; tm++)
; #pragma unroll
;         for (int tn = 0; tn < TN; tn++) acc[tm][tn] = MFMA(af[tm], bfr[tn], acc[tm][tn]);
;     }
;     __builtin_amdgcn_s_setprio(0);
;     __syncthreads();
;   }
	ds_read_b128 v[94:97], v68 offset:18432
	ds_read_b128 v[98:101], v68 offset:23040
	ds_read_b128 v[126:129], v1 offset:55296
	ds_read_b128 v[130:133], v1 offset:59904
	s_waitcnt vmcnt(1)
	ds_write_b128 v66, v[140:143]
	ds_write_b128 v66, v[102:105] offset:4608
	ds_write_b128 v66, v[106:109] offset:9216
	ds_write_b128 v66, v[110:113] offset:13824
	s_waitcnt vmcnt(0)
	ds_write_b128 v66, v[144:147] offset:36864
	ds_write_b128 v66, v[122:125] offset:41472
	ds_write_b128 v66, v[118:121] offset:46080
	ds_write_b128 v66, v[114:117] offset:50688
	s_setprio 1
	ds_read_b128 v[86:89], v68 offset:18464
	s_waitcnt lgkmcnt(10)
	v_mfma_f32_32x32x16_bf16 v[34:49], v[94:97], v[126:129], v[34:49]
	ds_read_b128 v[90:93], v1 offset:55328
	global_load_dwordx4 v[102:105], v[70:71], off offset:1920
	global_load_dwordx4 v[106:109], v[74:75], off offset:1920
	global_load_dwordx4 v[110:113], v[76:77], off offset:1920
	global_load_dwordx4 v[114:117], v[84:85], off offset:1920
	global_load_dwordx4 v[118:121], v[82:83], off offset:1920
	global_load_dwordx4 v[122:125], v[80:81], off offset:1920
	global_load_dwordx4 v[140:143], v[72:73], off offset:1920
	global_load_dwordx4 v[144:147], v[78:79], off offset:1920
	s_waitcnt lgkmcnt(10)
	v_mfma_f32_32x32x16_bf16 v[50:65], v[94:97], v[130:133], v[50:65]
	ds_read_b128 v[94:97], v1 offset:59936
	s_waitcnt lgkmcnt(1)
	v_mfma_f32_32x32x16_bf16 v[34:49], v[86:89], v[90:93], v[34:49]
	s_waitcnt lgkmcnt(0)
	v_mfma_f32_32x32x16_bf16 v[50:65], v[86:89], v[94:97], v[50:65]
	ds_read_b128 v[86:89], v68 offset:23072
	v_mfma_f32_32x32x16_bf16 v[2:17], v[98:101], v[126:129], v[2:17]
	v_mfma_f32_32x32x16_bf16 v[18:33], v[98:101], v[130:133], v[18:33]
	ds_read_b128 v[98:101], v68 offset:23136
	s_waitcnt lgkmcnt(1)
	v_mfma_f32_32x32x16_bf16 v[2:17], v[86:89], v[90:93], v[2:17]
	ds_read_b128 v[90:93], v1 offset:55360
	v_mfma_f32_32x32x16_bf16 v[18:33], v[86:89], v[94:97], v[18:33]
	ds_read_b128 v[86:89], v68 offset:18496
	ds_read_b128 v[94:97], v1 offset:59968
	s_waitcnt lgkmcnt(1)
	v_mfma_f32_32x32x16_bf16 v[34:49], v[86:89], v[90:93], v[34:49]
	s_waitcnt lgkmcnt(0)
	v_mfma_f32_32x32x16_bf16 v[50:65], v[86:89], v[94:97], v[50:65]
	ds_read_b128 v[86:89], v68 offset:23104
	s_waitcnt lgkmcnt(0)
	v_mfma_f32_32x32x16_bf16 v[2:17], v[86:89], v[90:93], v[2:17]
	ds_read_b128 v[90:93], v1 offset:55392
	v_mfma_f32_32x32x16_bf16 v[18:33], v[86:89], v[94:97], v[18:33]
	ds_read_b128 v[86:89], v68 offset:18528
	ds_read_b128 v[94:97], v1 offset:60000
	s_waitcnt lgkmcnt(1)
	v_mfma_f32_32x32x16_bf16 v[34:49], v[86:89], v[90:93], v[34:49]
	s_waitcnt lgkmcnt(0)
	v_mfma_f32_32x32x16_bf16 v[50:65], v[86:89], v[94:97], v[50:65]
	s_nop 0
	v_mfma_f32_32x32x16_bf16 v[2:17], v[98:101], v[90:93], v[2:17]
	v_mfma_f32_32x32x16_bf16 v[18:33], v[98:101], v[94:97], v[18:33]
	s_setprio 0
	s_barrier
	ds_read_b128 v[74:77], v68
	ds_read_b128 v[78:81], v68 offset:4608
	ds_read_b128 v[82:85], v1 offset:36864
	ds_read_b128 v[90:93], v1 offset:41472
	s_waitcnt vmcnt(1)
	ds_write_b128 v66, v[140:143] offset:18432
	ds_write_b128 v66, v[102:105] offset:23040
	ds_write_b128 v66, v[106:109] offset:27648
	ds_write_b128 v66, v[110:113] offset:32256
	s_waitcnt vmcnt(0)
	ds_write_b128 v66, v[144:147] offset:55296
	ds_write_b128 v66, v[122:125] offset:59904
	ds_write_b128 v66, v[118:121] offset:64512
	ds_write_b128 v69, v[114:117] offset:32256
	s_setprio 1
	ds_read_b128 v[70:73], v68 offset:32
	s_waitcnt lgkmcnt(10)
	v_mfma_f32_32x32x16_bf16 v[34:49], v[74:77], v[82:85], v[34:49]
	s_waitcnt lgkmcnt(9)
	v_mfma_f32_32x32x16_bf16 v[50:65], v[74:77], v[90:93], v[50:65]
	ds_read_b128 v[74:77], v1 offset:36896
	v_mfma_f32_32x32x16_bf16 v[2:17], v[78:81], v[82:85], v[2:17]
	v_mfma_f32_32x32x16_bf16 v[18:33], v[78:81], v[90:93], v[18:33]
	ds_read_b128 v[78:81], v1 offset:41504
	s_waitcnt lgkmcnt(1)
	v_mfma_f32_32x32x16_bf16 v[34:49], v[70:73], v[74:77], v[34:49]
	s_waitcnt lgkmcnt(0)
	v_mfma_f32_32x32x16_bf16 v[50:65], v[70:73], v[78:81], v[50:65]
	ds_read_b128 v[70:73], v68 offset:4640
	s_waitcnt lgkmcnt(0)
	v_mfma_f32_32x32x16_bf16 v[2:17], v[70:73], v[74:77], v[2:17]
	ds_read_b128 v[74:77], v1 offset:36928
	v_mfma_f32_32x32x16_bf16 v[18:33], v[70:73], v[78:81], v[18:33]
	ds_read_b128 v[70:73], v68 offset:64
	ds_read_b128 v[78:81], v1 offset:41536
	s_waitcnt lgkmcnt(1)
	v_mfma_f32_32x32x16_bf16 v[34:49], v[70:73], v[74:77], v[34:49]
	s_waitcnt lgkmcnt(0)
	v_mfma_f32_32x32x16_bf16 v[50:65], v[70:73], v[78:81], v[50:65]
	ds_read_b128 v[70:73], v68 offset:4672
	s_waitcnt lgkmcnt(0)
	v_mfma_f32_32x32x16_bf16 v[2:17], v[70:73], v[74:77], v[2:17]
	ds_read_b128 v[74:77], v1 offset:36960
	v_mfma_f32_32x32x16_bf16 v[18:33], v[70:73], v[78:81], v[18:33]
	ds_read_b128 v[70:73], v68 offset:96
	ds_read_b128 v[78:81], v1 offset:41568
	s_waitcnt lgkmcnt(1)
	v_mfma_f32_32x32x16_bf16 v[34:49], v[70:73], v[74:77], v[34:49]
	s_waitcnt lgkmcnt(0)
	v_mfma_f32_32x32x16_bf16 v[50:65], v[70:73], v[78:81], v[50:65]
	ds_read_b128 v[70:73], v68 offset:4704
	s_waitcnt lgkmcnt(0)
	v_mfma_f32_32x32x16_bf16 v[2:17], v[70:73], v[74:77], v[2:17]
	v_mfma_f32_32x32x16_bf16 v[18:33], v[70:73], v[78:81], v[18:33]
	s_setprio 0
	s_barrier
; template <int TM, int TN>
; DI void gemm_mainloop(const u16* __restrict__ A, long lda, const u16* __restrict__ Bt, long ldb, int K, char* smem,
;                       f32x16 (&acc)[TM][TN]) {
;     ...
;     for (int tm = 0; tm < TM; tm++) af[tm] = *(const bf16x8*)(cA + tm * 32 * LD + 16);
; #pragma unroll
;     for (int tn = 0; tn < TN; tn++) bfr[tn] = *(const bf16x8*)(cB + tn * 32 * LD + 16);
; #pragma unroll
;     for (int tm = 0; tm < TM; tm++)
; #pragma unroll
;       for (int tn = 0; tn < TN; tn++) acc[tm][tn] = MFMA(af[tm], bfr[tn], acc[tm][tn]);
;     __builtin_amdgcn_sched_group_barrier(0x8, 4, 0);
;     if (kt + 2 < nk) GEMM_GLOAD((kt + 2) * 64)
; #pragma unroll
;     for (int ks = 2; ks < 4; ks++) {
; #pragma unroll
;       for (int tm = 0; tm < TM; tm++) af[tm] = *(const bf16x8*)(cA + tm * 32 * LD + ks * 16);
; #pragma unroll
;       for (int tn = 0; tn < TN; tn++) bfr[tn] = *(const bf16x8*)(cB + tn * 32 * LD + ks * 16);
; #pragma unroll
;       for (int tm = 0; tm < TM; tm++)
; #pragma unroll
;         for (int tn = 0; tn < TN; tn++) acc[tm][tn] = MFMA(af[tm], bfr[tn], acc[tm][tn]);
;     }
;     __builtin_amdgcn_s_setprio(0);
;     __syncthreads();
;   }
;     ...
; }
; template <int TM, int TN, class Epi>
; DI void gemm_tile(const u16* A, long lda, const u16* Bt, long ldb, int K, int m0, int n0, char* smem, const Epi& epi) {
;   constexpr int BM = 64 * TM, BN = 64 * TN, LDC = BN + Epi::PAD;
;   f32x16 acc[TM][TN];
;   gemm_mainloop<TM, TN>(A + (long)m0 * lda, lda, Bt + (long)n0 * ldb, ldb, K, smem, acc);
;   const int tid = tidx(), lane = tid & 63, w = tid >> 6, r = lane & 31, h = lane >> 5;
;   const int wm = w >> 1, wn = w & 1;
;   float* Ct = (float*)smem;
; #pragma unroll
;   for (int tm = 0; tm < TM; tm++)
; #pragma unroll
;     for (int tn = 0; tn < TN; tn++)
; #pragma unroll
;       for (int i = 0; i < 16; i++)
;         Ct[(wm * 32 * TM + tm * 32 + crow(i, h)) * LDC + wn * 32 * TN + tn * 32 + r] = acc[tm][tn][i];
;   __syncthreads();
;   DI void operator()(const float* Ct, int ldc, int m0, int n0, int tid, int bm) const {
; #pragma unroll 4
;     for (int it = 0; it < bm / 16; it++) {
;       int id = tid + 256 * it; int row = id >> 4, c8 = (id & 15) * 8;
;       const float* c = Ct + row * ldc + c8;
;       float x[8];
; #pragma unroll
;       for (int j = 0; j < 8; j++) { float v = fmaxf(c[j], 0.f); x[j] = v * v; }
	ds_read_b128 v[70:73], v68 offset:18432
	ds_read_b128 v[74:77], v68 offset:23040
	ds_read_b128 v[78:81], v1 offset:55296
	ds_read_b128 v[82:85], v1 offset:59904
	s_setprio 1
	s_waitcnt lgkmcnt(1)
	v_mfma_f32_32x32x16_bf16 v[34:49], v[70:73], v[78:81], v[34:49]
	s_waitcnt lgkmcnt(0)
	v_mfma_f32_32x32x16_bf16 v[50:65], v[70:73], v[82:85], v[50:65]
	ds_read_b128 v[70:73], v68 offset:18464
	v_mfma_f32_32x32x16_bf16 v[2:17], v[74:77], v[78:81], v[2:17]
	ds_read_b128 v[78:81], v1 offset:59936
	v_mfma_f32_32x32x16_bf16 v[18:33], v[74:77], v[82:85], v[18:33]
	ds_read_b128 v[74:77], v1 offset:55328
	s_waitcnt lgkmcnt(0)
	v_mfma_f32_32x32x16_bf16 v[34:49], v[70:73], v[74:77], v[34:49]
	v_mfma_f32_32x32x16_bf16 v[50:65], v[70:73], v[78:81], v[50:65]
	ds_read_b128 v[70:73], v68 offset:23072
	s_waitcnt lgkmcnt(0)
	v_mfma_f32_32x32x16_bf16 v[2:17], v[70:73], v[74:77], v[2:17]
	ds_read_b128 v[74:77], v1 offset:55360
	v_mfma_f32_32x32x16_bf16 v[18:33], v[70:73], v[78:81], v[18:33]
	ds_read_b128 v[70:73], v68 offset:18496
	ds_read_b128 v[78:81], v1 offset:59968
	s_waitcnt lgkmcnt(1)
	v_mfma_f32_32x32x16_bf16 v[34:49], v[70:73], v[74:77], v[34:49]
	s_waitcnt lgkmcnt(0)
	v_mfma_f32_32x32x16_bf16 v[50:65], v[70:73], v[78:81], v[50:65]
	ds_read_b128 v[70:73], v68 offset:23104
	s_waitcnt lgkmcnt(0)
	v_mfma_f32_32x32x16_bf16 v[2:17], v[70:73], v[74:77], v[2:17]
	ds_read_b128 v[74:77], v1 offset:55392
	v_mfma_f32_32x32x16_bf16 v[18:33], v[70:73], v[78:81], v[18:33]
	ds_read_b128 v[70:73], v68 offset:18528
	ds_read_b128 v[78:81], v1 offset:60000
	s_waitcnt lgkmcnt(1)
	v_mfma_f32_32x32x16_bf16 v[34:49], v[70:73], v[74:77], v[34:49]
	s_waitcnt lgkmcnt(0)
	v_mfma_f32_32x32x16_bf16 v[50:65], v[70:73], v[78:81], v[50:65]
	ds_read_b128 v[68:71], v68 offset:23136
	s_waitcnt lgkmcnt(0)
	v_mfma_f32_32x32x16_bf16 v[2:17], v[68:71], v[74:77], v[2:17]
	v_mfma_f32_32x32x16_bf16 v[18:33], v[68:71], v[78:81], v[18:33]
	s_setprio 0
	v_mov_b32_e32 v1, v0
	s_barrier
	s_lshl_b64 s[4:5], s[6:7], 1
	v_lshrrev_b32_e32 v66, 1, v1
	v_and_b32_e32 v66, 0xfffffc0, v66
	v_lshrrev_b32_e32 v68, 3, v1
	v_and_or_b32 v66, v68, 4, v66
	v_and_b32_e32 v68, 0x5f, v1
	v_mul_lo_u32 v66, v66, s22
	v_lshl_add_u32 v66, v68, 2, v66
	ds_write2_b32 v66, v34, v50 offset1:32
	v_add_u32_e32 v34, 0x400, v66
	ds_write2_b32 v34, v36, v52 offset0:8 offset1:40
	ds_write2_b32 v34, v37, v53 offset0:140 offset1:172
	v_add_u32_e32 v34, 0x1000, v66
	ds_write2_b32 v34, v38, v54 offset0:32 offset1:64
	ds_write2_b32 v34, v39, v55 offset0:164 offset1:196
	v_add_u32_e32 v34, 0x1400, v66
	ds_write2_b32 v34, v40, v56 offset0:40 offset1:72
	ds_write2_b32 v34, v41, v57 offset0:172 offset1:204
	v_add_u32_e32 v34, 0x2000, v66
	ds_write2_b32 v34, v42, v58 offset0:64 offset1:96
	ds_write2_b32 v34, v43, v59 offset0:196 offset1:228
	v_add_u32_e32 v34, 0x2400, v66
	ds_write2_b32 v34, v44, v60 offset0:72 offset1:104
	ds_write2_b32 v34, v45, v61 offset0:204 offset1:236
	v_add_u32_e32 v34, 0x3000, v66
	ds_write2_b32 v34, v46, v62 offset0:96 offset1:128
	v_add_u32_e32 v34, 0x3200, v66
	ds_write2_b32 v34, v47, v63 offset0:100 offset1:132
	v_add_u32_e32 v34, 0x3400, v66
	ds_write2_b32 v34, v48, v64 offset0:104 offset1:136
	v_add_u32_e32 v34, 0x3600, v66
	ds_write2_b32 v34, v49, v65 offset0:108 offset1:140
	v_add_u32_e32 v34, 0x4000, v66
	ds_write2_b32 v34, v2, v18 offset0:128 offset1:160
	v_add_u32_e32 v2, 0x4400, v66
	ds_write2_b32 v2, v3, v19 offset0:4 offset1:36
	ds_write2_b32 v2, v4, v20 offset0:136 offset1:168
	v_add_u32_e32 v2, 0x4800, v66
	ds_write2_b32 v2, v5, v21 offset0:12 offset1:44
	v_add_u32_e32 v2, 0x5000, v66
	ds_write2_b32 v2, v6, v22 offset0:160 offset1:192
	v_add_u32_e32 v2, 0x5400, v66
	ds_write2_b32 v2, v7, v23 offset0:36 offset1:68
	ds_write2_b32 v2, v8, v24 offset0:168 offset1:200
	v_add_u32_e32 v2, 0x5800, v66
	ds_write2_b32 v2, v9, v25 offset0:44 offset1:76
	v_add_u32_e32 v2, 0x6000, v66
	ds_write2_b32 v2, v10, v26 offset0:192 offset1:224
	v_add_u32_e32 v2, 0x6400, v66
	ds_write2_b32 v2, v11, v27 offset0:68 offset1:100
	ds_write2_b32 v2, v12, v28 offset0:200 offset1:232
	v_add_u32_e32 v2, 0x6800, v66
	ds_write2_b32 v2, v13, v29 offset0:76 offset1:108
	v_add_u32_e32 v2, 0x7200, v66
	ds_write2_b32 v2, v14, v30 offset0:96 offset1:128
	v_add_u32_e32 v2, 0x7400, v66
	ds_write2_b32 v2, v15, v31 offset0:100 offset1:132
	v_add_u32_e32 v2, 0x7600, v66
	ds_write2_b32 v2, v16, v32 offset0:104 offset1:136
	v_add_u32_e32 v2, 0x7800, v66
	ds_write2_b32 v2, v17, v33 offset0:108 offset1:140
	v_lshlrev_b32_e32 v2, 3, v1
	v_and_b32_e32 v3, 0x78, v2
	s_add_u32 s4, s3, s4
	ds_write2_b32 v66, v35, v51 offset0:132 offset1:164
	s_addc_u32 s5, s14, s5
	v_lshlrev_b32_e32 v66, 1, v3
	v_lshlrev_b32_e32 v2, 2, v3
	v_lshl_add_u64 v[4:5], s[4:5], 0, v[66:67]
	s_mov_b32 s4, 0
	s_waitcnt lgkmcnt(0)
	s_barrier

; #define MFMA(a, b, c) __builtin_amdgcn_mfma_f32_32x32x16_bf16((a), (b), (c), 0, 0, 0)
; template <int TM, int TN>
; DI void gemm_mainloop(const u16* __restrict__ A, long lda, const u16* __restrict__ Bt, long ldb, int K, char* smem,
;                       f32x16 (&acc)[TM][TN]) {
;     ...
;   const int nk = K / 64;
;   const int lrow = tid >> 3, lch = (tid & 7) * 8;
;   const u16* gA = A + (long)lrow * lda + lch;
;   const u16* gB = Bt + (long)lrow * ldb + lch;
;   const int soff = lrow * LD + lch;
;     ...
;   GEMM_GLOAD(0)
;   __syncthreads();
;   GEMM_SSTORE(0)
;   if (nk > 1) GEMM_GLOAD(64)
;   __syncthreads();
;   for (int kt = 0; kt < nk; kt++) {
;     const int buf = kt & 1;
;     const u16* cA = sA + buf * BM * LD + (wm * 32 * TM + r) * LD + h * 8;
;     const u16* cB = sB + buf * BN * LD + (wn * 32 * TN + r) * LD + h * 8;
;     bf16x8 af[TM], bfr[TN];
; #pragma unroll
;     for (int tm = 0; tm < TM; tm++) af[tm] = *(const bf16x8*)(cA + tm * 32 * LD);
; #pragma unroll
;     for (int tn = 0; tn < TN; tn++) bfr[tn] = *(const bf16x8*)(cB + tn * 32 * LD);
;     if (kt + 1 < nk) GEMM_SSTORE(buf ^ 1)
;     __builtin_amdgcn_sched_barrier(0);
;     __builtin_amdgcn_s_setprio(1);
; #pragma unroll
;     for (int tm = 0; tm < TM; tm++)
; #pragma unroll
;       for (int tn = 0; tn < TN; tn++) acc[tm][tn] = MFMA(af[tm], bfr[tn], acc[tm][tn]);
; #pragma unroll
;     for (int tm = 0; tm < TM; tm++) af[tm] = *(const bf16x8*)(cA + tm * 32 * LD + 16);
; #pragma unroll
;     for (int tn = 0; tn < TN; tn++) bfr[tn] = *(const bf16x8*)(cB + tn * 32 * LD + 16);
; #pragma unroll
;     for (int tm = 0; tm < TM; tm++)
; #pragma unroll
;       for (int tn = 0; tn < TN; tn++) acc[tm][tn] = MFMA(af[tm], bfr[tn], acc[tm][tn]);
;     __builtin_amdgcn_sched_group_barrier(0x8, 4, 0);
;     if (kt + 2 < nk) GEMM_GLOAD((kt + 2) * 64)
; template <class Epi>
; DI void phase_gemm128(const Sched& sc, const u16* A, long lda, const u16* Bt, long ldb, int K, int MT, int NT, int SN, char* smem, const Epi& epi) {
;     ...
;     for (int st = xg; st < nfull; st += 8) {
;       int sm = st / sng, sn = st % sng;
;       int mt = sm * SM + xi / SN, nt = sn * SN + xi % SN;
;       gemm_tile<2, 2>(A, lda, Bt, ldb, K, mt * 128, nt * 128, smem, epi);
.LBB0_1343:
	s_lshl_b32 s4, s26, 8
	s_and_b32 s27, s4, 0xfffffe00
	s_lshl_b32 s4, s26, 11
	s_add_i32 s27, s27, s15
	s_and_b32 s4, s4, 0x800
	s_add_i32 s6, s4, s16
	s_mul_i32 s4, s27, 0x880
	s_mul_hi_i32 s5, s27, 0x880
	s_add_u32 s4, s8, s4
	v_mov_b32_e32 v1, v0
	s_addc_u32 s5, s9, s5
	s_ashr_i32 s7, s6, 31
	v_lshlrev_b32_e32 v2, 3, v1
	v_ashrrev_i32_e32 v68, 3, v1
	v_and_b32_e32 v69, 56, v2
	v_mov_b64_e32 v[2:3], s[4:5]
	v_mad_i64_i32 v[2:3], s[4:5], v68, s17, v[2:3]
	v_lshlrev_b32_e32 v66, 1, v69
	v_lshl_add_u64 v[72:73], v[2:3], 0, v[66:67]
	s_mul_i32 s28, s6, 0x880
	v_add_co_u32_e32 v70, vcc, s19, v72
	s_mul_hi_i32 s29, s6, 0x880
	s_add_u32 s28, s10, s28
	v_addc_co_u32_e32 v71, vcc, 0, v73, vcc
	s_addc_u32 s29, s11, s29
	v_add_co_u32_e32 v74, vcc, s20, v72
	v_mov_b64_e32 v[2:3], s[28:29]
	s_nop 0
	v_addc_co_u32_e32 v75, vcc, 0, v73, vcc
	v_mad_i64_i32 v[18:19], s[4:5], v68, s17, v[2:3]
	v_add_co_u32_e32 v78, vcc, s21, v72
	v_lshl_add_u64 v[76:77], v[18:19], 0, v[66:67]
	s_nop 0
	v_addc_co_u32_e32 v79, vcc, 0, v73, vcc
	v_add_co_u32_e32 v80, vcc, s19, v76
	global_load_dwordx4 v[2:5], v[72:73], off
	s_nop 0
	v_addc_co_u32_e32 v81, vcc, 0, v77, vcc
	v_add_co_u32_e32 v82, vcc, s20, v76
	global_load_dwordx4 v[6:9], v[70:71], off
	s_nop 0
	v_addc_co_u32_e32 v83, vcc, 0, v77, vcc
	v_add_co_u32_e32 v84, vcc, s21, v76
	global_load_dwordx4 v[10:13], v[74:75], off
	s_nop 0
	v_addc_co_u32_e32 v85, vcc, 0, v77, vcc
	global_load_dwordx4 v[14:17], v[78:79], off
	global_load_dwordx4 v[18:21], v[76:77], off
	global_load_dwordx4 v[22:25], v[80:81], off
	global_load_dwordx4 v[26:29], v[82:83], off
	global_load_dwordx4 v[30:33], v[84:85], off
	s_barrier
	global_load_dwordx4 v[34:37], v[72:73], off offset:128
	global_load_dwordx4 v[38:41], v[70:71], off offset:128
	global_load_dwordx4 v[42:45], v[74:75], off offset:128
	global_load_dwordx4 v[46:49], v[78:79], off offset:128
	global_load_dwordx4 v[50:53], v[76:77], off offset:128
	global_load_dwordx4 v[54:57], v[80:81], off offset:128
	global_load_dwordx4 v[58:61], v[82:83], off offset:128
	global_load_dwordx4 v[62:65], v[84:85], off offset:128
	v_and_b32_e32 v66, 31, v1
	v_lshrrev_b32_e32 v86, 1, v1
	v_mul_lo_u32 v68, v68, s18
	v_and_or_b32 v87, v86, s22, v66
	v_and_b32_e32 v86, 16, v86
	v_and_b32_e32 v1, 0x5f, v1
	v_add_lshl_u32 v66, v68, v69, 1
	v_mad_u64_u32 v[68:69], s[4:5], v87, s23, v[86:87]
	v_mad_u32_u24 v1, v1, s23, v86
	v_add_u32_e32 v69, 0x9000, v66
	s_waitcnt vmcnt(15)
	ds_write_b128 v66, v[2:5]
	s_waitcnt vmcnt(14)
	ds_write_b128 v66, v[6:9] offset:4608
	s_waitcnt vmcnt(13)
	ds_write_b128 v66, v[10:13] offset:9216
	s_waitcnt vmcnt(12)
	ds_write_b128 v66, v[14:17] offset:13824
	s_waitcnt vmcnt(11)
	ds_write_b128 v66, v[18:21] offset:36864
	s_waitcnt vmcnt(10)
	ds_write_b128 v66, v[22:25] offset:41472
	s_waitcnt vmcnt(9)
	ds_write_b128 v66, v[26:29] offset:46080
	s_waitcnt vmcnt(8)
	ds_write_b128 v66, v[30:33] offset:50688
	s_waitcnt lgkmcnt(0)
	s_barrier
	ds_read_b128 v[2:5], v68
	ds_read_b128 v[18:21], v68 offset:4608
	ds_read_b128 v[6:9], v1 offset:36864
	ds_read_b128 v[22:25], v1 offset:41472
	s_waitcnt vmcnt(7)
	ds_write_b128 v66, v[34:37] offset:18432
	s_waitcnt vmcnt(6)
	ds_write_b128 v66, v[38:41] offset:23040
	s_waitcnt vmcnt(5)
	ds_write_b128 v66, v[42:45] offset:27648
	s_waitcnt vmcnt(4)
	ds_write_b128 v66, v[46:49] offset:32256
	s_waitcnt vmcnt(3)
	ds_write_b128 v66, v[50:53] offset:55296
	s_waitcnt vmcnt(2)
	ds_write_b128 v66, v[54:57] offset:59904
	s_waitcnt vmcnt(1)
	ds_write_b128 v66, v[58:61] offset:64512
	s_waitcnt vmcnt(0)
	ds_write_b128 v69, v[62:65] offset:32256
	s_setprio 1
	ds_read_b128 v[86:89], v68 offset:32
	s_waitcnt lgkmcnt(10)
	v_mfma_f32_32x32x16_bf16 v[34:49], v[2:5], v[6:9], 0
	ds_read_b128 v[90:93], v1 offset:36896
	ds_read_b128 v[94:97], v1 offset:41504
	ds_read_b128 v[98:101], v68 offset:4704
	global_load_dwordx4 v[102:105], v[70:71], off offset:256
	global_load_dwordx4 v[106:109], v[74:75], off offset:256
	global_load_dwordx4 v[110:113], v[78:79], off offset:256
	global_load_dwordx4 v[114:117], v[84:85], off offset:256
	s_waitcnt lgkmcnt(12)
	v_mfma_f32_32x32x16_bf16 v[50:65], v[2:5], v[22:25], 0
	global_load_dwordx4 v[118:121], v[82:83], off offset:256
	global_load_dwordx4 v[122:125], v[80:81], off offset:256
	global_load_dwordx4 v[140:143], v[72:73], off offset:256
	global_load_dwordx4 v[144:147], v[76:77], off offset:256
	s_waitcnt lgkmcnt(2)
	v_mfma_f32_32x32x16_bf16 v[34:49], v[86:89], v[90:93], v[34:49]
	s_waitcnt lgkmcnt(1)
	v_mfma_f32_32x32x16_bf16 v[50:65], v[86:89], v[94:97], v[50:65]
	ds_read_b128 v[86:89], v68 offset:4640
	v_mfma_f32_32x32x16_bf16 v[2:17], v[18:21], v[6:9], 0
	v_mfma_f32_32x32x16_bf16 v[18:33], v[18:21], v[22:25], 0
	s_waitcnt lgkmcnt(0)
	v_mfma_f32_32x32x16_bf16 v[2:17], v[86:89], v[90:93], v[2:17]
	ds_read_b128 v[90:93], v1 offset:36928
	v_mfma_f32_32x32x16_bf16 v[18:33], v[86:89], v[94:97], v[18:33]
	ds_read_b128 v[86:89], v68 offset:64
	ds_read_b128 v[94:97], v1 offset:41536
	s_waitcnt lgkmcnt(1)
	v_mfma_f32_32x32x16_bf16 v[34:49], v[86:89], v[90:93], v[34:49]
	s_waitcnt lgkmcnt(0)
	v_mfma_f32_32x32x16_bf16 v[50:65], v[86:89], v[94:97], v[50:65]
	ds_read_b128 v[86:89], v68 offset:4672
	s_waitcnt lgkmcnt(0)
	v_mfma_f32_32x32x16_bf16 v[2:17], v[86:89], v[90:93], v[2:17]
	ds_read_b128 v[90:93], v1 offset:36960
	v_mfma_f32_32x32x16_bf16 v[18:33], v[86:89], v[94:97], v[18:33]
	ds_read_b128 v[86:89], v68 offset:96
	ds_read_b128 v[94:97], v1 offset:41568
	s_waitcnt lgkmcnt(1)
	v_mfma_f32_32x32x16_bf16 v[34:49], v[86:89], v[90:93], v[34:49]
	s_waitcnt lgkmcnt(0)
	v_mfma_f32_32x32x16_bf16 v[50:65], v[86:89], v[94:97], v[50:65]
	v_mfma_f32_32x32x16_bf16 v[2:17], v[98:101], v[90:93], v[2:17]
	v_mfma_f32_32x32x16_bf16 v[18:33], v[98:101], v[94:97], v[18:33]
	s_setprio 0
	s_barrier
; #define MFMA(a, b, c) __builtin_amdgcn_mfma_f32_32x32x16_bf16((a), (b), (c), 0, 0, 0)
; template <int TM, int TN>
; DI void gemm_mainloop(const u16* __restrict__ A, long lda, const u16* __restrict__ Bt, long ldb, int K, char* smem,
;                       f32x16 (&acc)[TM][TN]) {
;     ...
;   for (int kt = 0; kt < nk; kt++) {
;     const int buf = kt & 1;
;     const u16* cA = sA + buf * BM * LD + (wm * 32 * TM + r) * LD + h * 8;
;     const u16* cB = sB + buf * BN * LD + (wn * 32 * TN + r) * LD + h * 8;
;     bf16x8 af[TM], bfr[TN];
; #pragma unroll
;     for (int tm = 0; tm < TM; tm++) af[tm] = *(const bf16x8*)(cA + tm * 32 * LD);
; #pragma unroll
;     for (int tn = 0; tn < TN; tn++) bfr[tn] = *(const bf16x8*)(cB + tn * 32 * LD);
;     if (kt + 1 < nk) GEMM_SSTORE(buf ^ 1)
;     __builtin_amdgcn_sched_barrier(0);
;     __builtin_amdgcn_s_setprio(1);
; #pragma unroll
;     for (int tm = 0; tm < TM; tm++)
; #pragma unroll
;       for (int tn = 0; tn < TN; tn++) acc[tm][tn] = MFMA(af[tm], bfr[tn], acc[tm][tn]);
; #pragma unroll
;     for (int tm = 0; tm < TM; tm++) af[tm] = *(const bf16x8*)(cA + tm * 32 * LD + 16);
; #pragma unroll
;     for (int tn = 0; tn < TN; tn++) bfr[tn] = *(const bf16x8*)(cB + tn * 32 * LD + 16);
; #pragma unroll
;     for (int tm = 0; tm < TM; tm++)
; #pragma unroll
;       for (int tn = 0; tn < TN; tn++) acc[tm][tn] = MFMA(af[tm], bfr[tn], acc[tm][tn]);
;     __builtin_amdgcn_sched_group_barrier(0x8, 4, 0);
;     if (kt + 2 < nk) GEMM_GLOAD((kt + 2) * 64)
; #pragma unroll
;     for (int ks = 2; ks < 4; ks++) {
; #pragma unroll
;       for (int tm = 0; tm < TM; tm++) af[tm] = *(const bf16x8*)(cA + tm * 32 * LD + ks * 16);
; #pragma unroll
;       for (int tn = 0; tn < TN; tn++) bfr[tn] = *(const bf16x8*)(cB + tn * 32 * LD + ks * 16);
; #pragma unroll
;       for (int tm = 0; tm < TM; tm++)
; #pragma unroll
;         for (int tn = 0; tn < TN; tn++) acc[tm][tn] = MFMA(af[tm], bfr[tn], acc[tm][tn]);
;     }
;     __builtin_amdgcn_s_setprio(0);
;     __syncthreads();
;   }
	ds_read_b128 v[94:97], v68 offset:18432
	ds_read_b128 v[98:101], v68 offset:23040
	ds_read_b128 v[126:129], v1 offset:55296
	ds_read_b128 v[130:133], v1 offset:59904
	s_setprio 1
	ds_read_b128 v[86:89], v68 offset:18464
	s_waitcnt lgkmcnt(2)
	v_mfma_f32_32x32x16_bf16 v[34:49], v[94:97], v[126:129], v[34:49]
	ds_read_b128 v[90:93], v1 offset:55328
	s_waitcnt lgkmcnt(2)
	v_mfma_f32_32x32x16_bf16 v[50:65], v[94:97], v[130:133], v[50:65]
	s_waitcnt vmcnt(1)
	ds_write_b128 v66, v[140:143]
	ds_write_b128 v66, v[102:105] offset:4608
	global_load_dwordx4 v[140:143], v[72:73], off offset:384
	global_load_dwordx4 v[102:105], v[70:71], off offset:384
	ds_read_b128 v[94:97], v1 offset:59936
	s_waitcnt lgkmcnt(3)
	v_mfma_f32_32x32x16_bf16 v[34:49], v[86:89], v[90:93], v[34:49]
	s_waitcnt lgkmcnt(0)
	v_mfma_f32_32x32x16_bf16 v[50:65], v[86:89], v[94:97], v[50:65]
	ds_read_b128 v[86:89], v68 offset:23072
	v_mfma_f32_32x32x16_bf16 v[2:17], v[98:101], v[126:129], v[2:17]
	v_mfma_f32_32x32x16_bf16 v[18:33], v[98:101], v[130:133], v[18:33]
	ds_write_b128 v66, v[106:109] offset:9216
	ds_write_b128 v66, v[110:113] offset:13824
	global_load_dwordx4 v[106:109], v[74:75], off offset:384
	global_load_dwordx4 v[110:113], v[78:79], off offset:384
	ds_read_b128 v[98:101], v68 offset:23136
	s_waitcnt lgkmcnt(3)
	v_mfma_f32_32x32x16_bf16 v[2:17], v[86:89], v[90:93], v[2:17]
	ds_read_b128 v[90:93], v1 offset:55360
	v_mfma_f32_32x32x16_bf16 v[18:33], v[86:89], v[94:97], v[18:33]
	ds_read_b128 v[86:89], v68 offset:18496
	ds_read_b128 v[94:97], v1 offset:59968
	s_waitcnt lgkmcnt(1)
	v_mfma_f32_32x32x16_bf16 v[34:49], v[86:89], v[90:93], v[34:49]
	s_waitcnt lgkmcnt(0)
	v_mfma_f32_32x32x16_bf16 v[50:65], v[86:89], v[94:97], v[50:65]
	s_waitcnt vmcnt(4)
	ds_write_b128 v66, v[144:147] offset:36864
	ds_write_b128 v66, v[122:125] offset:41472
	global_load_dwordx4 v[144:147], v[76:77], off offset:384
	global_load_dwordx4 v[122:125], v[80:81], off offset:384
	ds_read_b128 v[86:89], v68 offset:23104
	s_waitcnt lgkmcnt(0)
	v_mfma_f32_32x32x16_bf16 v[2:17], v[86:89], v[90:93], v[2:17]
	ds_read_b128 v[90:93], v1 offset:55392
	v_mfma_f32_32x32x16_bf16 v[18:33], v[86:89], v[94:97], v[18:33]
	ds_read_b128 v[86:89], v68 offset:18528
	ds_read_b128 v[94:97], v1 offset:60000
	s_waitcnt lgkmcnt(1)
	v_mfma_f32_32x32x16_bf16 v[34:49], v[86:89], v[90:93], v[34:49]
	s_waitcnt lgkmcnt(0)
	v_mfma_f32_32x32x16_bf16 v[50:65], v[86:89], v[94:97], v[50:65]
	ds_write_b128 v66, v[118:121] offset:46080
	ds_write_b128 v66, v[114:117] offset:50688
	global_load_dwordx4 v[118:121], v[82:83], off offset:384
	global_load_dwordx4 v[114:117], v[84:85], off offset:384
	v_mfma_f32_32x32x16_bf16 v[2:17], v[98:101], v[90:93], v[2:17]
	v_mfma_f32_32x32x16_bf16 v[18:33], v[98:101], v[94:97], v[18:33]
	s_setprio 0
	s_waitcnt lgkmcnt(0)
	s_barrier
	ds_read_b128 v[94:97], v68
	ds_read_b128 v[98:101], v68 offset:4608
	ds_read_b128 v[126:129], v1 offset:36864
	ds_read_b128 v[130:133], v1 offset:41472
	s_setprio 1
	ds_read_b128 v[86:89], v68 offset:32
	s_waitcnt lgkmcnt(2)
	v_mfma_f32_32x32x16_bf16 v[34:49], v[94:97], v[126:129], v[34:49]
	ds_read_b128 v[90:93], v1 offset:36896
	s_waitcnt lgkmcnt(2)
	v_mfma_f32_32x32x16_bf16 v[50:65], v[94:97], v[130:133], v[50:65]
	s_waitcnt vmcnt(7)
	ds_write_b128 v66, v[140:143] offset:18432
	s_waitcnt vmcnt(6)
	ds_write_b128 v66, v[102:105] offset:23040
	global_load_dwordx4 v[140:143], v[72:73], off offset:512
	global_load_dwordx4 v[102:105], v[70:71], off offset:512
	ds_read_b128 v[94:97], v1 offset:41504
	s_waitcnt lgkmcnt(3)
	v_mfma_f32_32x32x16_bf16 v[34:49], v[86:89], v[90:93], v[34:49]
	s_waitcnt lgkmcnt(0)
	v_mfma_f32_32x32x16_bf16 v[50:65], v[86:89], v[94:97], v[50:65]
	ds_read_b128 v[86:89], v68 offset:4640
	v_mfma_f32_32x32x16_bf16 v[2:17], v[98:101], v[126:129], v[2:17]
	v_mfma_f32_32x32x16_bf16 v[18:33], v[98:101], v[130:133], v[18:33]
	s_waitcnt vmcnt(7)
	ds_write_b128 v66, v[106:109] offset:27648
	s_waitcnt vmcnt(6)
	ds_write_b128 v66, v[110:113] offset:32256
	global_load_dwordx4 v[106:109], v[74:75], off offset:512
	global_load_dwordx4 v[110:113], v[78:79], off offset:512
	ds_read_b128 v[98:101], v68 offset:4704
	s_waitcnt lgkmcnt(3)
	v_mfma_f32_32x32x16_bf16 v[2:17], v[86:89], v[90:93], v[2:17]
	ds_read_b128 v[90:93], v1 offset:36928
	v_mfma_f32_32x32x16_bf16 v[18:33], v[86:89], v[94:97], v[18:33]
	ds_read_b128 v[86:89], v68 offset:64
	ds_read_b128 v[94:97], v1 offset:41536
	s_waitcnt lgkmcnt(1)
	v_mfma_f32_32x32x16_bf16 v[34:49], v[86:89], v[90:93], v[34:49]
	s_waitcnt lgkmcnt(0)
	v_mfma_f32_32x32x16_bf16 v[50:65], v[86:89], v[94:97], v[50:65]
	s_waitcnt vmcnt(7)
	ds_write_b128 v66, v[144:147] offset:55296
	s_waitcnt vmcnt(6)
	ds_write_b128 v66, v[122:125] offset:59904
	global_load_dwordx4 v[144:147], v[76:77], off offset:512
	global_load_dwordx4 v[122:125], v[80:81], off offset:512
	ds_read_b128 v[86:89], v68 offset:4672
	s_waitcnt lgkmcnt(0)
	v_mfma_f32_32x32x16_bf16 v[2:17], v[86:89], v[90:93], v[2:17]
	ds_read_b128 v[90:93], v1 offset:36960
	v_mfma_f32_32x32x16_bf16 v[18:33], v[86:89], v[94:97], v[18:33]
	ds_read_b128 v[86:89], v68 offset:96
	ds_read_b128 v[94:97], v1 offset:41568
	s_waitcnt lgkmcnt(1)
	v_mfma_f32_32x32x16_bf16 v[34:49], v[86:89], v[90:93], v[34:49]
	s_waitcnt lgkmcnt(0)
	v_mfma_f32_32x32x16_bf16 v[50:65], v[86:89], v[94:97], v[50:65]
	s_waitcnt vmcnt(7)
	ds_write_b128 v66, v[118:121] offset:64512
	s_waitcnt vmcnt(6)
	ds_write_b128 v69, v[114:117] offset:32256
	global_load_dwordx4 v[118:121], v[82:83], off offset:512
	global_load_dwordx4 v[114:117], v[84:85], off offset:512
	v_mfma_f32_32x32x16_bf16 v[2:17], v[98:101], v[90:93], v[2:17]
	v_mfma_f32_32x32x16_bf16 v[18:33], v[98:101], v[94:97], v[18:33]
	s_setprio 0
	s_waitcnt lgkmcnt(0)
	s_barrier
; #define MFMA(a, b, c) __builtin_amdgcn_mfma_f32_32x32x16_bf16((a), (b), (c), 0, 0, 0)
; template <int TM, int TN>
; DI void gemm_mainloop(const u16* __restrict__ A, long lda, const u16* __restrict__ Bt, long ldb, int K, char* smem,
;                       f32x16 (&acc)[TM][TN]) {
;     ...
;   for (int kt = 0; kt < nk; kt++) {
;     const int buf = kt & 1;
;     const u16* cA = sA + buf * BM * LD + (wm * 32 * TM + r) * LD + h * 8;
;     const u16* cB = sB + buf * BN * LD + (wn * 32 * TN + r) * LD + h * 8;
;     bf16x8 af[TM], bfr[TN];
; #pragma unroll
;     for (int tm = 0; tm < TM; tm++) af[tm] = *(const bf16x8*)(cA + tm * 32 * LD);
; #pragma unroll
;     for (int tn = 0; tn < TN; tn++) bfr[tn] = *(const bf16x8*)(cB + tn * 32 * LD);
;     if (kt + 1 < nk) GEMM_SSTORE(buf ^ 1)
;     __builtin_amdgcn_sched_barrier(0);
;     __builtin_amdgcn_s_setprio(1);
; #pragma unroll
;     for (int tm = 0; tm < TM; tm++)
; #pragma unroll
;       for (int tn = 0; tn < TN; tn++) acc[tm][tn] = MFMA(af[tm], bfr[tn], acc[tm][tn]);
; #pragma unroll
;     for (int tm = 0; tm < TM; tm++) af[tm] = *(const bf16x8*)(cA + tm * 32 * LD + 16);
; #pragma unroll
;     for (int tn = 0; tn < TN; tn++) bfr[tn] = *(const bf16x8*)(cB + tn * 32 * LD + 16);
; #pragma unroll
;     for (int tm = 0; tm < TM; tm++)
; #pragma unroll
;       for (int tn = 0; tn < TN; tn++) acc[tm][tn] = MFMA(af[tm], bfr[tn], acc[tm][tn]);
;     __builtin_amdgcn_sched_group_barrier(0x8, 4, 0);
;     if (kt + 2 < nk) GEMM_GLOAD((kt + 2) * 64)
; #pragma unroll
;     for (int ks = 2; ks < 4; ks++) {
; #pragma unroll
;       for (int tm = 0; tm < TM; tm++) af[tm] = *(const bf16x8*)(cA + tm * 32 * LD + ks * 16);
; #pragma unroll
;       for (int tn = 0; tn < TN; tn++) bfr[tn] = *(const bf16x8*)(cB + tn * 32 * LD + ks * 16);
; #pragma unroll
;       for (int tm = 0; tm < TM; tm++)
; #pragma unroll
;         for (int tn = 0; tn < TN; tn++) acc[tm][tn] = MFMA(af[tm], bfr[tn], acc[tm][tn]);
;     }
;     __builtin_amdgcn_s_setprio(0);
;     __syncthreads();
;   }
	ds_read_b128 v[94:97], v68 offset:18432
	ds_read_b128 v[98:101], v68 offset:23040
	ds_read_b128 v[126:129], v1 offset:55296
	ds_read_b128 v[130:133], v1 offset:59904
	s_setprio 1
	ds_read_b128 v[86:89], v68 offset:18464
	s_waitcnt lgkmcnt(2)
	v_mfma_f32_32x32x16_bf16 v[34:49], v[94:97], v[126:129], v[34:49]
	ds_read_b128 v[90:93], v1 offset:55328
	s_waitcnt lgkmcnt(2)
	v_mfma_f32_32x32x16_bf16 v[50:65], v[94:97], v[130:133], v[50:65]
	s_waitcnt vmcnt(7)
	ds_write_b128 v66, v[140:143]
	s_waitcnt vmcnt(6)
	ds_write_b128 v66, v[102:105] offset:4608
	global_load_dwordx4 v[140:143], v[72:73], off offset:640
	global_load_dwordx4 v[102:105], v[70:71], off offset:640
	ds_read_b128 v[94:97], v1 offset:59936
	s_waitcnt lgkmcnt(3)
	v_mfma_f32_32x32x16_bf16 v[34:49], v[86:89], v[90:93], v[34:49]
	s_waitcnt lgkmcnt(0)
	v_mfma_f32_32x32x16_bf16 v[50:65], v[86:89], v[94:97], v[50:65]
	ds_read_b128 v[86:89], v68 offset:23072
	v_mfma_f32_32x32x16_bf16 v[2:17], v[98:101], v[126:129], v[2:17]
	v_mfma_f32_32x32x16_bf16 v[18:33], v[98:101], v[130:133], v[18:33]
	s_waitcnt vmcnt(7)
	ds_write_b128 v66, v[106:109] offset:9216
	s_waitcnt vmcnt(6)
	ds_write_b128 v66, v[110:113] offset:13824
	global_load_dwordx4 v[106:109], v[74:75], off offset:640
	global_load_dwordx4 v[110:113], v[78:79], off offset:640
	ds_read_b128 v[98:101], v68 offset:23136
	s_waitcnt lgkmcnt(3)
	v_mfma_f32_32x32x16_bf16 v[2:17], v[86:89], v[90:93], v[2:17]
	ds_read_b128 v[90:93], v1 offset:55360
	v_mfma_f32_32x32x16_bf16 v[18:33], v[86:89], v[94:97], v[18:33]
	ds_read_b128 v[86:89], v68 offset:18496
	ds_read_b128 v[94:97], v1 offset:59968
	s_waitcnt lgkmcnt(1)
	v_mfma_f32_32x32x16_bf16 v[34:49], v[86:89], v[90:93], v[34:49]
	s_waitcnt lgkmcnt(0)
	v_mfma_f32_32x32x16_bf16 v[50:65], v[86:89], v[94:97], v[50:65]
	s_waitcnt vmcnt(7)
	ds_write_b128 v66, v[144:147] offset:36864
	s_waitcnt vmcnt(6)
	ds_write_b128 v66, v[122:125] offset:41472
	global_load_dwordx4 v[144:147], v[76:77], off offset:640
	global_load_dwordx4 v[122:125], v[80:81], off offset:640
	ds_read_b128 v[86:89], v68 offset:23104
	s_waitcnt lgkmcnt(0)
	v_mfma_f32_32x32x16_bf16 v[2:17], v[86:89], v[90:93], v[2:17]
	ds_read_b128 v[90:93], v1 offset:55392
	v_mfma_f32_32x32x16_bf16 v[18:33], v[86:89], v[94:97], v[18:33]
	ds_read_b128 v[86:89], v68 offset:18528
	ds_read_b128 v[94:97], v1 offset:60000
	s_waitcnt lgkmcnt(1)
	v_mfma_f32_32x32x16_bf16 v[34:49], v[86:89], v[90:93], v[34:49]
	s_waitcnt lgkmcnt(0)
	v_mfma_f32_32x32x16_bf16 v[50:65], v[86:89], v[94:97], v[50:65]
	s_waitcnt vmcnt(7)
	ds_write_b128 v66, v[118:121] offset:46080
	s_waitcnt vmcnt(6)
	ds_write_b128 v66, v[114:117] offset:50688
	global_load_dwordx4 v[118:121], v[82:83], off offset:640
	global_load_dwordx4 v[114:117], v[84:85], off offset:640
	v_mfma_f32_32x32x16_bf16 v[2:17], v[98:101], v[90:93], v[2:17]
	v_mfma_f32_32x32x16_bf16 v[18:33], v[98:101], v[94:97], v[18:33]
	s_setprio 0
	s_waitcnt lgkmcnt(0)
	s_barrier
	ds_read_b128 v[94:97], v68
	ds_read_b128 v[98:101], v68 offset:4608
	ds_read_b128 v[126:129], v1 offset:36864
	ds_read_b128 v[130:133], v1 offset:41472
	s_setprio 1
	ds_read_b128 v[86:89], v68 offset:32
	s_waitcnt lgkmcnt(2)
	v_mfma_f32_32x32x16_bf16 v[34:49], v[94:97], v[126:129], v[34:49]
	ds_read_b128 v[90:93], v1 offset:36896
	s_waitcnt lgkmcnt(2)
	v_mfma_f32_32x32x16_bf16 v[50:65], v[94:97], v[130:133], v[50:65]
	s_waitcnt vmcnt(7)
	ds_write_b128 v66, v[140:143] offset:18432
	s_waitcnt vmcnt(6)
	ds_write_b128 v66, v[102:105] offset:23040
	global_load_dwordx4 v[140:143], v[72:73], off offset:768
	global_load_dwordx4 v[102:105], v[70:71], off offset:768
	ds_read_b128 v[94:97], v1 offset:41504
	s_waitcnt lgkmcnt(3)
	v_mfma_f32_32x32x16_bf16 v[34:49], v[86:89], v[90:93], v[34:49]
	s_waitcnt lgkmcnt(0)
	v_mfma_f32_32x32x16_bf16 v[50:65], v[86:89], v[94:97], v[50:65]
	ds_read_b128 v[86:89], v68 offset:4640
	v_mfma_f32_32x32x16_bf16 v[2:17], v[98:101], v[126:129], v[2:17]
	v_mfma_f32_32x32x16_bf16 v[18:33], v[98:101], v[130:133], v[18:33]
	s_waitcnt vmcnt(7)
	ds_write_b128 v66, v[106:109] offset:27648
	s_waitcnt vmcnt(6)
	ds_write_b128 v66, v[110:113] offset:32256
	global_load_dwordx4 v[106:109], v[74:75], off offset:768
	global_load_dwordx4 v[110:113], v[78:79], off offset:768
	ds_read_b128 v[98:101], v68 offset:4704
	s_waitcnt lgkmcnt(3)
	v_mfma_f32_32x32x16_bf16 v[2:17], v[86:89], v[90:93], v[2:17]
	ds_read_b128 v[90:93], v1 offset:36928
	v_mfma_f32_32x32x16_bf16 v[18:33], v[86:89], v[94:97], v[18:33]
	ds_read_b128 v[86:89], v68 offset:64
	ds_read_b128 v[94:97], v1 offset:41536
	s_waitcnt lgkmcnt(1)
	v_mfma_f32_32x32x16_bf16 v[34:49], v[86:89], v[90:93], v[34:49]
	s_waitcnt lgkmcnt(0)
	v_mfma_f32_32x32x16_bf16 v[50:65], v[86:89], v[94:97], v[50:65]
	s_waitcnt vmcnt(7)
	ds_write_b128 v66, v[144:147] offset:55296
	s_waitcnt vmcnt(6)
	ds_write_b128 v66, v[122:125] offset:59904
	global_load_dwordx4 v[144:147], v[76:77], off offset:768
	global_load_dwordx4 v[122:125], v[80:81], off offset:768
	ds_read_b128 v[86:89], v68 offset:4672
	s_waitcnt lgkmcnt(0)
	v_mfma_f32_32x32x16_bf16 v[2:17], v[86:89], v[90:93], v[2:17]
	ds_read_b128 v[90:93], v1 offset:36960
	v_mfma_f32_32x32x16_bf16 v[18:33], v[86:89], v[94:97], v[18:33]
	ds_read_b128 v[86:89], v68 offset:96
	ds_read_b128 v[94:97], v1 offset:41568
	s_waitcnt lgkmcnt(1)
	v_mfma_f32_32x32x16_bf16 v[34:49], v[86:89], v[90:93], v[34:49]
	s_waitcnt lgkmcnt(0)
	v_mfma_f32_32x32x16_bf16 v[50:65], v[86:89], v[94:97], v[50:65]
	s_waitcnt vmcnt(7)
	ds_write_b128 v66, v[118:121] offset:64512
	s_waitcnt vmcnt(6)
	ds_write_b128 v69, v[114:117] offset:32256
	global_load_dwordx4 v[118:121], v[82:83], off offset:768
	global_load_dwordx4 v[114:117], v[84:85], off offset:768
	v_mfma_f32_32x32x16_bf16 v[2:17], v[98:101], v[90:93], v[2:17]
	v_mfma_f32_32x32x16_bf16 v[18:33], v[98:101], v[94:97], v[18:33]
	s_setprio 0
	s_waitcnt lgkmcnt(0)
	s_barrier
; #define MFMA(a, b, c) __builtin_amdgcn_mfma_f32_32x32x16_bf16((a), (b), (c), 0, 0, 0)
; template <int TM, int TN>
; DI void gemm_mainloop(const u16* __restrict__ A, long lda, const u16* __restrict__ Bt, long ldb, int K, char* smem,
;                       f32x16 (&acc)[TM][TN]) {
;     ...
;   for (int kt = 0; kt < nk; kt++) {
;     const int buf = kt & 1;
;     const u16* cA = sA + buf * BM * LD + (wm * 32 * TM + r) * LD + h * 8;
;     const u16* cB = sB + buf * BN * LD + (wn * 32 * TN + r) * LD + h * 8;
;     bf16x8 af[TM], bfr[TN];
; #pragma unroll
;     for (int tm = 0; tm < TM; tm++) af[tm] = *(const bf16x8*)(cA + tm * 32 * LD);
; #pragma unroll
;     for (int tn = 0; tn < TN; tn++) bfr[tn] = *(const bf16x8*)(cB + tn * 32 * LD);
;     if (kt + 1 < nk) GEMM_SSTORE(buf ^ 1)
;     __builtin_amdgcn_sched_barrier(0);
;     __builtin_amdgcn_s_setprio(1);
; #pragma unroll
;     for (int tm = 0; tm < TM; tm++)
; #pragma unroll
;       for (int tn = 0; tn < TN; tn++) acc[tm][tn] = MFMA(af[tm], bfr[tn], acc[tm][tn]);
; #pragma unroll
;     for (int tm = 0; tm < TM; tm++) af[tm] = *(const bf16x8*)(cA + tm * 32 * LD + 16);
; #pragma unroll
;     for (int tn = 0; tn < TN; tn++) bfr[tn] = *(const bf16x8*)(cB + tn * 32 * LD + 16);
; #pragma unroll
;     for (int tm = 0; tm < TM; tm++)
; #pragma unroll
;       for (int tn = 0; tn < TN; tn++) acc[tm][tn] = MFMA(af[tm], bfr[tn], acc[tm][tn]);
;     __builtin_amdgcn_sched_group_barrier(0x8, 4, 0);
;     if (kt + 2 < nk) GEMM_GLOAD((kt + 2) * 64)
; #pragma unroll
;     for (int ks = 2; ks < 4; ks++) {
; #pragma unroll
;       for (int tm = 0; tm < TM; tm++) af[tm] = *(const bf16x8*)(cA + tm * 32 * LD + ks * 16);
; #pragma unroll
;       for (int tn = 0; tn < TN; tn++) bfr[tn] = *(const bf16x8*)(cB + tn * 32 * LD + ks * 16);
; #pragma unroll
;       for (int tm = 0; tm < TM; tm++)
; #pragma unroll
;         for (int tn = 0; tn < TN; tn++) acc[tm][tn] = MFMA(af[tm], bfr[tn], acc[tm][tn]);
;     }
;     __builtin_amdgcn_s_setprio(0);
;     __syncthreads();
;   }
	ds_read_b128 v[94:97], v68 offset:18432
	ds_read_b128 v[98:101], v68 offset:23040
	ds_read_b128 v[126:129], v1 offset:55296
	ds_read_b128 v[130:133], v1 offset:59904
	s_setprio 1
	ds_read_b128 v[86:89], v68 offset:18464
	s_waitcnt lgkmcnt(2)
	v_mfma_f32_32x32x16_bf16 v[34:49], v[94:97], v[126:129], v[34:49]
	ds_read_b128 v[90:93], v1 offset:55328
	s_waitcnt lgkmcnt(2)
	v_mfma_f32_32x32x16_bf16 v[50:65], v[94:97], v[130:133], v[50:65]
	s_waitcnt vmcnt(7)
	ds_write_b128 v66, v[140:143]
	s_waitcnt vmcnt(6)
	ds_write_b128 v66, v[102:105] offset:4608
	global_load_dwordx4 v[140:143], v[72:73], off offset:896
	global_load_dwordx4 v[102:105], v[70:71], off offset:896
	ds_read_b128 v[94:97], v1 offset:59936
	s_waitcnt lgkmcnt(3)
	v_mfma_f32_32x32x16_bf16 v[34:49], v[86:89], v[90:93], v[34:49]
	s_waitcnt lgkmcnt(0)
	v_mfma_f32_32x32x16_bf16 v[50:65], v[86:89], v[94:97], v[50:65]
	ds_read_b128 v[86:89], v68 offset:23072
	v_mfma_f32_32x32x16_bf16 v[2:17], v[98:101], v[126:129], v[2:17]
	v_mfma_f32_32x32x16_bf16 v[18:33], v[98:101], v[130:133], v[18:33]
	s_waitcnt vmcnt(7)
	ds_write_b128 v66, v[106:109] offset:9216
	s_waitcnt vmcnt(6)
	ds_write_b128 v66, v[110:113] offset:13824
	global_load_dwordx4 v[106:109], v[74:75], off offset:896
	global_load_dwordx4 v[110:113], v[78:79], off offset:896
	ds_read_b128 v[98:101], v68 offset:23136
	s_waitcnt lgkmcnt(3)
	v_mfma_f32_32x32x16_bf16 v[2:17], v[86:89], v[90:93], v[2:17]
	ds_read_b128 v[90:93], v1 offset:55360
	v_mfma_f32_32x32x16_bf16 v[18:33], v[86:89], v[94:97], v[18:33]
	ds_read_b128 v[86:89], v68 offset:18496
	ds_read_b128 v[94:97], v1 offset:59968
	s_waitcnt lgkmcnt(1)
	v_mfma_f32_32x32x16_bf16 v[34:49], v[86:89], v[90:93], v[34:49]
	s_waitcnt lgkmcnt(0)
	v_mfma_f32_32x32x16_bf16 v[50:65], v[86:89], v[94:97], v[50:65]
	s_waitcnt vmcnt(7)
	ds_write_b128 v66, v[144:147] offset:36864
	s_waitcnt vmcnt(6)
	ds_write_b128 v66, v[122:125] offset:41472
	global_load_dwordx4 v[144:147], v[76:77], off offset:896
	global_load_dwordx4 v[122:125], v[80:81], off offset:896
	ds_read_b128 v[86:89], v68 offset:23104
	s_waitcnt lgkmcnt(0)
	v_mfma_f32_32x32x16_bf16 v[2:17], v[86:89], v[90:93], v[2:17]
	ds_read_b128 v[90:93], v1 offset:55392
	v_mfma_f32_32x32x16_bf16 v[18:33], v[86:89], v[94:97], v[18:33]
	ds_read_b128 v[86:89], v68 offset:18528
	ds_read_b128 v[94:97], v1 offset:60000
	s_waitcnt lgkmcnt(1)
	v_mfma_f32_32x32x16_bf16 v[34:49], v[86:89], v[90:93], v[34:49]
	s_waitcnt lgkmcnt(0)
	v_mfma_f32_32x32x16_bf16 v[50:65], v[86:89], v[94:97], v[50:65]
	s_waitcnt vmcnt(7)
	ds_write_b128 v66, v[118:121] offset:46080
	s_waitcnt vmcnt(6)
	ds_write_b128 v66, v[114:117] offset:50688
	global_load_dwordx4 v[118:121], v[82:83], off offset:896
	global_load_dwordx4 v[114:117], v[84:85], off offset:896
	v_mfma_f32_32x32x16_bf16 v[2:17], v[98:101], v[90:93], v[2:17]
	v_mfma_f32_32x32x16_bf16 v[18:33], v[98:101], v[94:97], v[18:33]
	s_setprio 0
	s_waitcnt lgkmcnt(0)
	s_barrier
	ds_read_b128 v[94:97], v68
	ds_read_b128 v[98:101], v68 offset:4608
	ds_read_b128 v[126:129], v1 offset:36864
	ds_read_b128 v[130:133], v1 offset:41472
	s_setprio 1
	ds_read_b128 v[86:89], v68 offset:32
	s_waitcnt lgkmcnt(2)
	v_mfma_f32_32x32x16_bf16 v[34:49], v[94:97], v[126:129], v[34:49]
	ds_read_b128 v[90:93], v1 offset:36896
	s_waitcnt lgkmcnt(2)
	v_mfma_f32_32x32x16_bf16 v[50:65], v[94:97], v[130:133], v[50:65]
	s_waitcnt vmcnt(7)
	ds_write_b128 v66, v[140:143] offset:18432
	s_waitcnt vmcnt(6)
	ds_write_b128 v66, v[102:105] offset:23040
	global_load_dwordx4 v[140:143], v[72:73], off offset:1024
	global_load_dwordx4 v[102:105], v[70:71], off offset:1024
	ds_read_b128 v[94:97], v1 offset:41504
	s_waitcnt lgkmcnt(3)
	v_mfma_f32_32x32x16_bf16 v[34:49], v[86:89], v[90:93], v[34:49]
	s_waitcnt lgkmcnt(0)
	v_mfma_f32_32x32x16_bf16 v[50:65], v[86:89], v[94:97], v[50:65]
	ds_read_b128 v[86:89], v68 offset:4640
	v_mfma_f32_32x32x16_bf16 v[2:17], v[98:101], v[126:129], v[2:17]
	v_mfma_f32_32x32x16_bf16 v[18:33], v[98:101], v[130:133], v[18:33]
	s_waitcnt vmcnt(7)
	ds_write_b128 v66, v[106:109] offset:27648
	s_waitcnt vmcnt(6)
	ds_write_b128 v66, v[110:113] offset:32256
	global_load_dwordx4 v[106:109], v[74:75], off offset:1024
	global_load_dwordx4 v[110:113], v[78:79], off offset:1024
	ds_read_b128 v[98:101], v68 offset:4704
	s_waitcnt lgkmcnt(3)
	v_mfma_f32_32x32x16_bf16 v[2:17], v[86:89], v[90:93], v[2:17]
	ds_read_b128 v[90:93], v1 offset:36928
	v_mfma_f32_32x32x16_bf16 v[18:33], v[86:89], v[94:97], v[18:33]
	ds_read_b128 v[86:89], v68 offset:64
	ds_read_b128 v[94:97], v1 offset:41536
	s_waitcnt lgkmcnt(1)
	v_mfma_f32_32x32x16_bf16 v[34:49], v[86:89], v[90:93], v[34:49]
	s_waitcnt lgkmcnt(0)
	v_mfma_f32_32x32x16_bf16 v[50:65], v[86:89], v[94:97], v[50:65]
	s_waitcnt vmcnt(7)
	ds_write_b128 v66, v[144:147] offset:55296
	s_waitcnt vmcnt(6)
	ds_write_b128 v66, v[122:125] offset:59904
	global_load_dwordx4 v[144:147], v[76:77], off offset:1024
	global_load_dwordx4 v[122:125], v[80:81], off offset:1024
	ds_read_b128 v[86:89], v68 offset:4672
	s_waitcnt lgkmcnt(0)
	v_mfma_f32_32x32x16_bf16 v[2:17], v[86:89], v[90:93], v[2:17]
	ds_read_b128 v[90:93], v1 offset:36960
	v_mfma_f32_32x32x16_bf16 v[18:33], v[86:89], v[94:97], v[18:33]
	ds_read_b128 v[86:89], v68 offset:96
	ds_read_b128 v[94:97], v1 offset:41568
	s_waitcnt lgkmcnt(1)
	v_mfma_f32_32x32x16_bf16 v[34:49], v[86:89], v[90:93], v[34:49]
	s_waitcnt lgkmcnt(0)
	v_mfma_f32_32x32x16_bf16 v[50:65], v[86:89], v[94:97], v[50:65]
	s_waitcnt vmcnt(7)
	ds_write_b128 v66, v[118:121] offset:64512
	s_waitcnt vmcnt(6)
	ds_write_b128 v69, v[114:117] offset:32256
	global_load_dwordx4 v[118:121], v[82:83], off offset:1024
	global_load_dwordx4 v[114:117], v[84:85], off offset:1024
	v_mfma_f32_32x32x16_bf16 v[2:17], v[98:101], v[90:93], v[2:17]
	v_mfma_f32_32x32x16_bf16 v[18:33], v[98:101], v[94:97], v[18:33]
	s_setprio 0
	s_waitcnt lgkmcnt(0)
	s_barrier
; #define MFMA(a, b, c) __builtin_amdgcn_mfma_f32_32x32x16_bf16((a), (b), (c), 0, 0, 0)
; template <int TM, int TN>
; DI void gemm_mainloop(const u16* __restrict__ A, long lda, const u16* __restrict__ Bt, long ldb, int K, char* smem,
;                       f32x16 (&acc)[TM][TN]) {
;     ...
;   for (int kt = 0; kt < nk; kt++) {
;     const int buf = kt & 1;
;     const u16* cA = sA + buf * BM * LD + (wm * 32 * TM + r) * LD + h * 8;
;     const u16* cB = sB + buf * BN * LD + (wn * 32 * TN + r) * LD + h * 8;
;     bf16x8 af[TM], bfr[TN];
; #pragma unroll
;     for (int tm = 0; tm < TM; tm++) af[tm] = *(const bf16x8*)(cA + tm * 32 * LD);
; #pragma unroll
;     for (int tn = 0; tn < TN; tn++) bfr[tn] = *(const bf16x8*)(cB + tn * 32 * LD);
;     if (kt + 1 < nk) GEMM_SSTORE(buf ^ 1)
;     __builtin_amdgcn_sched_barrier(0);
;     __builtin_amdgcn_s_setprio(1);
; #pragma unroll
;     for (int tm = 0; tm < TM; tm++)
; #pragma unroll
;       for (int tn = 0; tn < TN; tn++) acc[tm][tn] = MFMA(af[tm], bfr[tn], acc[tm][tn]);
; #pragma unroll
;     for (int tm = 0; tm < TM; tm++) af[tm] = *(const bf16x8*)(cA + tm * 32 * LD + 16);
; #pragma unroll
;     for (int tn = 0; tn < TN; tn++) bfr[tn] = *(const bf16x8*)(cB + tn * 32 * LD + 16);
; #pragma unroll
;     for (int tm = 0; tm < TM; tm++)
; #pragma unroll
;       for (int tn = 0; tn < TN; tn++) acc[tm][tn] = MFMA(af[tm], bfr[tn], acc[tm][tn]);
;     __builtin_amdgcn_sched_group_barrier(0x8, 4, 0);
;     if (kt + 2 < nk) GEMM_GLOAD((kt + 2) * 64)
; #pragma unroll
;     for (int ks = 2; ks < 4; ks++) {
; #pragma unroll
;       for (int tm = 0; tm < TM; tm++) af[tm] = *(const bf16x8*)(cA + tm * 32 * LD + ks * 16);
; #pragma unroll
;       for (int tn = 0; tn < TN; tn++) bfr[tn] = *(const bf16x8*)(cB + tn * 32 * LD + ks * 16);
; #pragma unroll
;       for (int tm = 0; tm < TM; tm++)
; #pragma unroll
;         for (int tn = 0; tn < TN; tn++) acc[tm][tn] = MFMA(af[tm], bfr[tn], acc[tm][tn]);
;     }
;     __builtin_amdgcn_s_setprio(0);
;     __syncthreads();
;   }
	ds_read_b128 v[94:97], v68 offset:18432
	ds_read_b128 v[98:101], v68 offset:23040
	ds_read_b128 v[126:129], v1 offset:55296
	ds_read_b128 v[130:133], v1 offset:59904
	s_setprio 1
	ds_read_b128 v[86:89], v68 offset:18464
	s_waitcnt lgkmcnt(2)
	v_mfma_f32_32x32x16_bf16 v[34:49], v[94:97], v[126:129], v[34:49]
	ds_read_b128 v[90:93], v1 offset:55328
	s_waitcnt lgkmcnt(2)
	v_mfma_f32_32x32x16_bf16 v[50:65], v[94:97], v[130:133], v[50:65]
	s_waitcnt vmcnt(7)
	ds_write_b128 v66, v[140:143]
	s_waitcnt vmcnt(6)
	ds_write_b128 v66, v[102:105] offset:4608
	global_load_dwordx4 v[140:143], v[72:73], off offset:1152
	global_load_dwordx4 v[102:105], v[70:71], off offset:1152
	ds_read_b128 v[94:97], v1 offset:59936
	s_waitcnt lgkmcnt(3)
	v_mfma_f32_32x32x16_bf16 v[34:49], v[86:89], v[90:93], v[34:49]
	s_waitcnt lgkmcnt(0)
	v_mfma_f32_32x32x16_bf16 v[50:65], v[86:89], v[94:97], v[50:65]
	ds_read_b128 v[86:89], v68 offset:23072
	v_mfma_f32_32x32x16_bf16 v[2:17], v[98:101], v[126:129], v[2:17]
	v_mfma_f32_32x32x16_bf16 v[18:33], v[98:101], v[130:133], v[18:33]
	s_waitcnt vmcnt(7)
	ds_write_b128 v66, v[106:109] offset:9216
	s_waitcnt vmcnt(6)
	ds_write_b128 v66, v[110:113] offset:13824
	global_load_dwordx4 v[106:109], v[74:75], off offset:1152
	global_load_dwordx4 v[110:113], v[78:79], off offset:1152
	ds_read_b128 v[98:101], v68 offset:23136
	s_waitcnt lgkmcnt(3)
	v_mfma_f32_32x32x16_bf16 v[2:17], v[86:89], v[90:93], v[2:17]
	ds_read_b128 v[90:93], v1 offset:55360
	v_mfma_f32_32x32x16_bf16 v[18:33], v[86:89], v[94:97], v[18:33]
	ds_read_b128 v[86:89], v68 offset:18496
	ds_read_b128 v[94:97], v1 offset:59968
	s_waitcnt lgkmcnt(1)
	v_mfma_f32_32x32x16_bf16 v[34:49], v[86:89], v[90:93], v[34:49]
	s_waitcnt lgkmcnt(0)
	v_mfma_f32_32x32x16_bf16 v[50:65], v[86:89], v[94:97], v[50:65]
	s_waitcnt vmcnt(7)
	ds_write_b128 v66, v[144:147] offset:36864
	s_waitcnt vmcnt(6)
	ds_write_b128 v66, v[122:125] offset:41472
	global_load_dwordx4 v[144:147], v[76:77], off offset:1152
	global_load_dwordx4 v[122:125], v[80:81], off offset:1152
	ds_read_b128 v[86:89], v68 offset:23104
	s_waitcnt lgkmcnt(0)
	v_mfma_f32_32x32x16_bf16 v[2:17], v[86:89], v[90:93], v[2:17]
	ds_read_b128 v[90:93], v1 offset:55392
	v_mfma_f32_32x32x16_bf16 v[18:33], v[86:89], v[94:97], v[18:33]
	ds_read_b128 v[86:89], v68 offset:18528
	ds_read_b128 v[94:97], v1 offset:60000
	s_waitcnt lgkmcnt(1)
	v_mfma_f32_32x32x16_bf16 v[34:49], v[86:89], v[90:93], v[34:49]
	s_waitcnt lgkmcnt(0)
	v_mfma_f32_32x32x16_bf16 v[50:65], v[86:89], v[94:97], v[50:65]
	s_waitcnt vmcnt(7)
	ds_write_b128 v66, v[118:121] offset:46080
	s_waitcnt vmcnt(6)
	ds_write_b128 v66, v[114:117] offset:50688
	global_load_dwordx4 v[118:121], v[82:83], off offset:1152
	global_load_dwordx4 v[114:117], v[84:85], off offset:1152
	v_mfma_f32_32x32x16_bf16 v[2:17], v[98:101], v[90:93], v[2:17]
	v_mfma_f32_32x32x16_bf16 v[18:33], v[98:101], v[94:97], v[18:33]
	s_setprio 0
	s_waitcnt lgkmcnt(0)
	s_barrier
	ds_read_b128 v[94:97], v68
	ds_read_b128 v[98:101], v68 offset:4608
	ds_read_b128 v[126:129], v1 offset:36864
	ds_read_b128 v[130:133], v1 offset:41472
	s_setprio 1
	ds_read_b128 v[86:89], v68 offset:32
	s_waitcnt lgkmcnt(2)
	v_mfma_f32_32x32x16_bf16 v[34:49], v[94:97], v[126:129], v[34:49]
	ds_read_b128 v[90:93], v1 offset:36896
	s_waitcnt lgkmcnt(2)
	v_mfma_f32_32x32x16_bf16 v[50:65], v[94:97], v[130:133], v[50:65]
	s_waitcnt vmcnt(7)
	ds_write_b128 v66, v[140:143] offset:18432
	s_waitcnt vmcnt(6)
	ds_write_b128 v66, v[102:105] offset:23040
	global_load_dwordx4 v[140:143], v[72:73], off offset:1280
	global_load_dwordx4 v[102:105], v[70:71], off offset:1280
	ds_read_b128 v[94:97], v1 offset:41504
	s_waitcnt lgkmcnt(3)
	v_mfma_f32_32x32x16_bf16 v[34:49], v[86:89], v[90:93], v[34:49]
	s_waitcnt lgkmcnt(0)
	v_mfma_f32_32x32x16_bf16 v[50:65], v[86:89], v[94:97], v[50:65]
	ds_read_b128 v[86:89], v68 offset:4640
	v_mfma_f32_32x32x16_bf16 v[2:17], v[98:101], v[126:129], v[2:17]
	v_mfma_f32_32x32x16_bf16 v[18:33], v[98:101], v[130:133], v[18:33]
	s_waitcnt vmcnt(7)
	ds_write_b128 v66, v[106:109] offset:27648
	s_waitcnt vmcnt(6)
	ds_write_b128 v66, v[110:113] offset:32256
	global_load_dwordx4 v[106:109], v[74:75], off offset:1280
	global_load_dwordx4 v[110:113], v[78:79], off offset:1280
	ds_read_b128 v[98:101], v68 offset:4704
	s_waitcnt lgkmcnt(3)
	v_mfma_f32_32x32x16_bf16 v[2:17], v[86:89], v[90:93], v[2:17]
	ds_read_b128 v[90:93], v1 offset:36928
	v_mfma_f32_32x32x16_bf16 v[18:33], v[86:89], v[94:97], v[18:33]
	ds_read_b128 v[86:89], v68 offset:64
	ds_read_b128 v[94:97], v1 offset:41536
	s_waitcnt lgkmcnt(1)
	v_mfma_f32_32x32x16_bf16 v[34:49], v[86:89], v[90:93], v[34:49]
	s_waitcnt lgkmcnt(0)
	v_mfma_f32_32x32x16_bf16 v[50:65], v[86:89], v[94:97], v[50:65]
	s_waitcnt vmcnt(7)
	ds_write_b128 v66, v[144:147] offset:55296
	s_waitcnt vmcnt(6)
	ds_write_b128 v66, v[122:125] offset:59904
	global_load_dwordx4 v[144:147], v[76:77], off offset:1280
	global_load_dwordx4 v[122:125], v[80:81], off offset:1280
	ds_read_b128 v[86:89], v68 offset:4672
	s_waitcnt lgkmcnt(0)
	v_mfma_f32_32x32x16_bf16 v[2:17], v[86:89], v[90:93], v[2:17]
	ds_read_b128 v[90:93], v1 offset:36960
	v_mfma_f32_32x32x16_bf16 v[18:33], v[86:89], v[94:97], v[18:33]
	ds_read_b128 v[86:89], v68 offset:96
	ds_read_b128 v[94:97], v1 offset:41568
	s_waitcnt lgkmcnt(1)
	v_mfma_f32_32x32x16_bf16 v[34:49], v[86:89], v[90:93], v[34:49]
	s_waitcnt lgkmcnt(0)
	v_mfma_f32_32x32x16_bf16 v[50:65], v[86:89], v[94:97], v[50:65]
	s_waitcnt vmcnt(7)
	ds_write_b128 v66, v[118:121] offset:64512
	s_waitcnt vmcnt(6)
	ds_write_b128 v69, v[114:117] offset:32256
	global_load_dwordx4 v[118:121], v[82:83], off offset:1280
	global_load_dwordx4 v[114:117], v[84:85], off offset:1280
	v_mfma_f32_32x32x16_bf16 v[2:17], v[98:101], v[90:93], v[2:17]
	v_mfma_f32_32x32x16_bf16 v[18:33], v[98:101], v[94:97], v[18:33]
	s_setprio 0
	s_waitcnt lgkmcnt(0)
	s_barrier
; #define MFMA(a, b, c) __builtin_amdgcn_mfma_f32_32x32x16_bf16((a), (b), (c), 0, 0, 0)
; template <int TM, int TN>
; DI void gemm_mainloop(const u16* __restrict__ A, long lda, const u16* __restrict__ Bt, long ldb, int K, char* smem,
;                       f32x16 (&acc)[TM][TN]) {
;     ...
;   for (int kt = 0; kt < nk; kt++) {
;     const int buf = kt & 1;
;     const u16* cA = sA + buf * BM * LD + (wm * 32 * TM + r) * LD + h * 8;
;     const u16* cB = sB + buf * BN * LD + (wn * 32 * TN + r) * LD + h * 8;
;     bf16x8 af[TM], bfr[TN];
; #pragma unroll
;     for (int tm = 0; tm < TM; tm++) af[tm] = *(const bf16x8*)(cA + tm * 32 * LD);
; #pragma unroll
;     for (int tn = 0; tn < TN; tn++) bfr[tn] = *(const bf16x8*)(cB + tn * 32 * LD);
;     if (kt + 1 < nk) GEMM_SSTORE(buf ^ 1)
;     __builtin_amdgcn_sched_barrier(0);
;     __builtin_amdgcn_s_setprio(1);
; #pragma unroll
;     for (int tm = 0; tm < TM; tm++)
; #pragma unroll
;       for (int tn = 0; tn < TN; tn++) acc[tm][tn] = MFMA(af[tm], bfr[tn], acc[tm][tn]);
; #pragma unroll
;     for (int tm = 0; tm < TM; tm++) af[tm] = *(const bf16x8*)(cA + tm * 32 * LD + 16);
; #pragma unroll
;     for (int tn = 0; tn < TN; tn++) bfr[tn] = *(const bf16x8*)(cB + tn * 32 * LD + 16);
; #pragma unroll
;     for (int tm = 0; tm < TM; tm++)
; #pragma unroll
;       for (int tn = 0; tn < TN; tn++) acc[tm][tn] = MFMA(af[tm], bfr[tn], acc[tm][tn]);
;     __builtin_amdgcn_sched_group_barrier(0x8, 4, 0);
;     if (kt + 2 < nk) GEMM_GLOAD((kt + 2) * 64)
; #pragma unroll
;     for (int ks = 2; ks < 4; ks++) {
; #pragma unroll
;       for (int tm = 0; tm < TM; tm++) af[tm] = *(const bf16x8*)(cA + tm * 32 * LD + ks * 16);
; #pragma unroll
;       for (int tn = 0; tn < TN; tn++) bfr[tn] = *(const bf16x8*)(cB + tn * 32 * LD + ks * 16);
; #pragma unroll
;       for (int tm = 0; tm < TM; tm++)
; #pragma unroll
;         for (int tn = 0; tn < TN; tn++) acc[tm][tn] = MFMA(af[tm], bfr[tn], acc[tm][tn]);
;     }
;     __builtin_amdgcn_s_setprio(0);
;     __syncthreads();
;   }
	ds_read_b128 v[94:97], v68 offset:18432
	ds_read_b128 v[98:101], v68 offset:23040
	ds_read_b128 v[126:129], v1 offset:55296
	ds_read_b128 v[130:133], v1 offset:59904
	s_setprio 1
	ds_read_b128 v[86:89], v68 offset:18464
	s_waitcnt lgkmcnt(2)
	v_mfma_f32_32x32x16_bf16 v[34:49], v[94:97], v[126:129], v[34:49]
	ds_read_b128 v[90:93], v1 offset:55328
	s_waitcnt lgkmcnt(2)
	v_mfma_f32_32x32x16_bf16 v[50:65], v[94:97], v[130:133], v[50:65]
	s_waitcnt vmcnt(7)
	ds_write_b128 v66, v[140:143]
	s_waitcnt vmcnt(6)
	ds_write_b128 v66, v[102:105] offset:4608
	global_load_dwordx4 v[140:143], v[72:73], off offset:1408
	global_load_dwordx4 v[102:105], v[70:71], off offset:1408
	ds_read_b128 v[94:97], v1 offset:59936
	s_waitcnt lgkmcnt(3)
	v_mfma_f32_32x32x16_bf16 v[34:49], v[86:89], v[90:93], v[34:49]
	s_waitcnt lgkmcnt(0)
	v_mfma_f32_32x32x16_bf16 v[50:65], v[86:89], v[94:97], v[50:65]
	ds_read_b128 v[86:89], v68 offset:23072
	v_mfma_f32_32x32x16_bf16 v[2:17], v[98:101], v[126:129], v[2:17]
	v_mfma_f32_32x32x16_bf16 v[18:33], v[98:101], v[130:133], v[18:33]
	s_waitcnt vmcnt(7)
	ds_write_b128 v66, v[106:109] offset:9216
	s_waitcnt vmcnt(6)
	ds_write_b128 v66, v[110:113] offset:13824
	global_load_dwordx4 v[106:109], v[74:75], off offset:1408
	global_load_dwordx4 v[110:113], v[78:79], off offset:1408
	ds_read_b128 v[98:101], v68 offset:23136
	s_waitcnt lgkmcnt(3)
	v_mfma_f32_32x32x16_bf16 v[2:17], v[86:89], v[90:93], v[2:17]
	ds_read_b128 v[90:93], v1 offset:55360
	v_mfma_f32_32x32x16_bf16 v[18:33], v[86:89], v[94:97], v[18:33]
	ds_read_b128 v[86:89], v68 offset:18496
	ds_read_b128 v[94:97], v1 offset:59968
	s_waitcnt lgkmcnt(1)
	v_mfma_f32_32x32x16_bf16 v[34:49], v[86:89], v[90:93], v[34:49]
	s_waitcnt lgkmcnt(0)
	v_mfma_f32_32x32x16_bf16 v[50:65], v[86:89], v[94:97], v[50:65]
	s_waitcnt vmcnt(7)
	ds_write_b128 v66, v[144:147] offset:36864
	s_waitcnt vmcnt(6)
	ds_write_b128 v66, v[122:125] offset:41472
	global_load_dwordx4 v[144:147], v[76:77], off offset:1408
	global_load_dwordx4 v[122:125], v[80:81], off offset:1408
	ds_read_b128 v[86:89], v68 offset:23104
	s_waitcnt lgkmcnt(0)
	v_mfma_f32_32x32x16_bf16 v[2:17], v[86:89], v[90:93], v[2:17]
	ds_read_b128 v[90:93], v1 offset:55392
	v_mfma_f32_32x32x16_bf16 v[18:33], v[86:89], v[94:97], v[18:33]
	ds_read_b128 v[86:89], v68 offset:18528
	ds_read_b128 v[94:97], v1 offset:60000
	s_waitcnt lgkmcnt(1)
	v_mfma_f32_32x32x16_bf16 v[34:49], v[86:89], v[90:93], v[34:49]
	s_waitcnt lgkmcnt(0)
	v_mfma_f32_32x32x16_bf16 v[50:65], v[86:89], v[94:97], v[50:65]
	s_waitcnt vmcnt(7)
	ds_write_b128 v66, v[118:121] offset:46080
	s_waitcnt vmcnt(6)
	ds_write_b128 v66, v[114:117] offset:50688
	global_load_dwordx4 v[118:121], v[82:83], off offset:1408
	global_load_dwordx4 v[114:117], v[84:85], off offset:1408
	v_mfma_f32_32x32x16_bf16 v[2:17], v[98:101], v[90:93], v[2:17]
	v_mfma_f32_32x32x16_bf16 v[18:33], v[98:101], v[94:97], v[18:33]
	s_setprio 0
	s_waitcnt lgkmcnt(0)
	s_barrier
	ds_read_b128 v[94:97], v68
	ds_read_b128 v[98:101], v68 offset:4608
	ds_read_b128 v[126:129], v1 offset:36864
	ds_read_b128 v[130:133], v1 offset:41472
	s_setprio 1
	ds_read_b128 v[86:89], v68 offset:32
	s_waitcnt lgkmcnt(2)
	v_mfma_f32_32x32x16_bf16 v[34:49], v[94:97], v[126:129], v[34:49]
	ds_read_b128 v[90:93], v1 offset:36896
	s_waitcnt lgkmcnt(2)
	v_mfma_f32_32x32x16_bf16 v[50:65], v[94:97], v[130:133], v[50:65]
	s_waitcnt vmcnt(7)
	ds_write_b128 v66, v[140:143] offset:18432
	s_waitcnt vmcnt(6)
	ds_write_b128 v66, v[102:105] offset:23040
	global_load_dwordx4 v[140:143], v[72:73], off offset:1536
	global_load_dwordx4 v[102:105], v[70:71], off offset:1536
	ds_read_b128 v[94:97], v1 offset:41504
	s_waitcnt lgkmcnt(3)
	v_mfma_f32_32x32x16_bf16 v[34:49], v[86:89], v[90:93], v[34:49]
	s_waitcnt lgkmcnt(0)
	v_mfma_f32_32x32x16_bf16 v[50:65], v[86:89], v[94:97], v[50:65]
	ds_read_b128 v[86:89], v68 offset:4640
	v_mfma_f32_32x32x16_bf16 v[2:17], v[98:101], v[126:129], v[2:17]
	v_mfma_f32_32x32x16_bf16 v[18:33], v[98:101], v[130:133], v[18:33]
	s_waitcnt vmcnt(7)
	ds_write_b128 v66, v[106:109] offset:27648
	s_waitcnt vmcnt(6)
	ds_write_b128 v66, v[110:113] offset:32256
	global_load_dwordx4 v[106:109], v[74:75], off offset:1536
	global_load_dwordx4 v[110:113], v[78:79], off offset:1536
	ds_read_b128 v[98:101], v68 offset:4704
	s_waitcnt lgkmcnt(3)
	v_mfma_f32_32x32x16_bf16 v[2:17], v[86:89], v[90:93], v[2:17]
	ds_read_b128 v[90:93], v1 offset:36928
	v_mfma_f32_32x32x16_bf16 v[18:33], v[86:89], v[94:97], v[18:33]
	ds_read_b128 v[86:89], v68 offset:64
	ds_read_b128 v[94:97], v1 offset:41536
	s_waitcnt lgkmcnt(1)
	v_mfma_f32_32x32x16_bf16 v[34:49], v[86:89], v[90:93], v[34:49]
	s_waitcnt lgkmcnt(0)
	v_mfma_f32_32x32x16_bf16 v[50:65], v[86:89], v[94:97], v[50:65]
	s_waitcnt vmcnt(7)
	ds_write_b128 v66, v[144:147] offset:55296
	s_waitcnt vmcnt(6)
	ds_write_b128 v66, v[122:125] offset:59904
	global_load_dwordx4 v[144:147], v[76:77], off offset:1536
	global_load_dwordx4 v[122:125], v[80:81], off offset:1536
	ds_read_b128 v[86:89], v68 offset:4672
	s_waitcnt lgkmcnt(0)
	v_mfma_f32_32x32x16_bf16 v[2:17], v[86:89], v[90:93], v[2:17]
	ds_read_b128 v[90:93], v1 offset:36960
	v_mfma_f32_32x32x16_bf16 v[18:33], v[86:89], v[94:97], v[18:33]
	ds_read_b128 v[86:89], v68 offset:96
	ds_read_b128 v[94:97], v1 offset:41568
	s_waitcnt lgkmcnt(1)
	v_mfma_f32_32x32x16_bf16 v[34:49], v[86:89], v[90:93], v[34:49]
	s_waitcnt lgkmcnt(0)
	v_mfma_f32_32x32x16_bf16 v[50:65], v[86:89], v[94:97], v[50:65]
	s_waitcnt vmcnt(7)
	ds_write_b128 v66, v[118:121] offset:64512
	s_waitcnt vmcnt(6)
	ds_write_b128 v69, v[114:117] offset:32256
	global_load_dwordx4 v[118:121], v[82:83], off offset:1536
	global_load_dwordx4 v[114:117], v[84:85], off offset:1536
	v_mfma_f32_32x32x16_bf16 v[2:17], v[98:101], v[90:93], v[2:17]
	v_mfma_f32_32x32x16_bf16 v[18:33], v[98:101], v[94:97], v[18:33]
	s_setprio 0
	s_waitcnt lgkmcnt(0)
	s_barrier
; #define MFMA(a, b, c) __builtin_amdgcn_mfma_f32_32x32x16_bf16((a), (b), (c), 0, 0, 0)
; template <int TM, int TN>
; DI void gemm_mainloop(const u16* __restrict__ A, long lda, const u16* __restrict__ Bt, long ldb, int K, char* smem,
;                       f32x16 (&acc)[TM][TN]) {
;     ...
;   for (int kt = 0; kt < nk; kt++) {
;     const int buf = kt & 1;
;     const u16* cA = sA + buf * BM * LD + (wm * 32 * TM + r) * LD + h * 8;
;     const u16* cB = sB + buf * BN * LD + (wn * 32 * TN + r) * LD + h * 8;
;     bf16x8 af[TM], bfr[TN];
; #pragma unroll
;     for (int tm = 0; tm < TM; tm++) af[tm] = *(const bf16x8*)(cA + tm * 32 * LD);
; #pragma unroll
;     for (int tn = 0; tn < TN; tn++) bfr[tn] = *(const bf16x8*)(cB + tn * 32 * LD);
;     if (kt + 1 < nk) GEMM_SSTORE(buf ^ 1)
;     __builtin_amdgcn_sched_barrier(0);
;     __builtin_amdgcn_s_setprio(1);
; #pragma unroll
;     for (int tm = 0; tm < TM; tm++)
; #pragma unroll
;       for (int tn = 0; tn < TN; tn++) acc[tm][tn] = MFMA(af[tm], bfr[tn], acc[tm][tn]);
; #pragma unroll
;     for (int tm = 0; tm < TM; tm++) af[tm] = *(const bf16x8*)(cA + tm * 32 * LD + 16);
; #pragma unroll
;     for (int tn = 0; tn < TN; tn++) bfr[tn] = *(const bf16x8*)(cB + tn * 32 * LD + 16);
; #pragma unroll
;     for (int tm = 0; tm < TM; tm++)
; #pragma unroll
;       for (int tn = 0; tn < TN; tn++) acc[tm][tn] = MFMA(af[tm], bfr[tn], acc[tm][tn]);
;     __builtin_amdgcn_sched_group_barrier(0x8, 4, 0);
;     if (kt + 2 < nk) GEMM_GLOAD((kt + 2) * 64)
; #pragma unroll
;     for (int ks = 2; ks < 4; ks++) {
; #pragma unroll
;       for (int tm = 0; tm < TM; tm++) af[tm] = *(const bf16x8*)(cA + tm * 32 * LD + ks * 16);
; #pragma unroll
;       for (int tn = 0; tn < TN; tn++) bfr[tn] = *(const bf16x8*)(cB + tn * 32 * LD + ks * 16);
; #pragma unroll
;       for (int tm = 0; tm < TM; tm++)
; #pragma unroll
;         for (int tn = 0; tn < TN; tn++) acc[tm][tn] = MFMA(af[tm], bfr[tn], acc[tm][tn]);
;     }
;     __builtin_amdgcn_s_setprio(0);
;     __syncthreads();
;   }
	ds_read_b128 v[94:97], v68 offset:18432
	ds_read_b128 v[98:101], v68 offset:23040
	ds_read_b128 v[126:129], v1 offset:55296
	ds_read_b128 v[130:133], v1 offset:59904
	s_setprio 1
	ds_read_b128 v[86:89], v68 offset:18464
	s_waitcnt lgkmcnt(2)
	v_mfma_f32_32x32x16_bf16 v[34:49], v[94:97], v[126:129], v[34:49]
	ds_read_b128 v[90:93], v1 offset:55328
	s_waitcnt lgkmcnt(2)
	v_mfma_f32_32x32x16_bf16 v[50:65], v[94:97], v[130:133], v[50:65]
	s_waitcnt vmcnt(7)
	ds_write_b128 v66, v[140:143]
	s_waitcnt vmcnt(6)
	ds_write_b128 v66, v[102:105] offset:4608
	global_load_dwordx4 v[140:143], v[72:73], off offset:1664
	global_load_dwordx4 v[102:105], v[70:71], off offset:1664
	ds_read_b128 v[94:97], v1 offset:59936
	s_waitcnt lgkmcnt(3)
	v_mfma_f32_32x32x16_bf16 v[34:49], v[86:89], v[90:93], v[34:49]
	s_waitcnt lgkmcnt(0)
	v_mfma_f32_32x32x16_bf16 v[50:65], v[86:89], v[94:97], v[50:65]
	ds_read_b128 v[86:89], v68 offset:23072
	v_mfma_f32_32x32x16_bf16 v[2:17], v[98:101], v[126:129], v[2:17]
	v_mfma_f32_32x32x16_bf16 v[18:33], v[98:101], v[130:133], v[18:33]
	s_waitcnt vmcnt(7)
	ds_write_b128 v66, v[106:109] offset:9216
	s_waitcnt vmcnt(6)
	ds_write_b128 v66, v[110:113] offset:13824
	global_load_dwordx4 v[106:109], v[74:75], off offset:1664
	global_load_dwordx4 v[110:113], v[78:79], off offset:1664
	ds_read_b128 v[98:101], v68 offset:23136
	s_waitcnt lgkmcnt(3)
	v_mfma_f32_32x32x16_bf16 v[2:17], v[86:89], v[90:93], v[2:17]
	ds_read_b128 v[90:93], v1 offset:55360
	v_mfma_f32_32x32x16_bf16 v[18:33], v[86:89], v[94:97], v[18:33]
	ds_read_b128 v[86:89], v68 offset:18496
	ds_read_b128 v[94:97], v1 offset:59968
	s_waitcnt lgkmcnt(1)
	v_mfma_f32_32x32x16_bf16 v[34:49], v[86:89], v[90:93], v[34:49]
	s_waitcnt lgkmcnt(0)
	v_mfma_f32_32x32x16_bf16 v[50:65], v[86:89], v[94:97], v[50:65]
	s_waitcnt vmcnt(7)
	ds_write_b128 v66, v[144:147] offset:36864
	s_waitcnt vmcnt(6)
	ds_write_b128 v66, v[122:125] offset:41472
	global_load_dwordx4 v[144:147], v[76:77], off offset:1664
	global_load_dwordx4 v[122:125], v[80:81], off offset:1664
	ds_read_b128 v[86:89], v68 offset:23104
	s_waitcnt lgkmcnt(0)
	v_mfma_f32_32x32x16_bf16 v[2:17], v[86:89], v[90:93], v[2:17]
	ds_read_b128 v[90:93], v1 offset:55392
	v_mfma_f32_32x32x16_bf16 v[18:33], v[86:89], v[94:97], v[18:33]
	ds_read_b128 v[86:89], v68 offset:18528
	ds_read_b128 v[94:97], v1 offset:60000
	s_waitcnt lgkmcnt(1)
	v_mfma_f32_32x32x16_bf16 v[34:49], v[86:89], v[90:93], v[34:49]
	s_waitcnt lgkmcnt(0)
	v_mfma_f32_32x32x16_bf16 v[50:65], v[86:89], v[94:97], v[50:65]
	s_waitcnt vmcnt(7)
	ds_write_b128 v66, v[118:121] offset:46080
	s_waitcnt vmcnt(6)
	ds_write_b128 v66, v[114:117] offset:50688
	global_load_dwordx4 v[118:121], v[82:83], off offset:1664
	global_load_dwordx4 v[114:117], v[84:85], off offset:1664
	v_mfma_f32_32x32x16_bf16 v[2:17], v[98:101], v[90:93], v[2:17]
	v_mfma_f32_32x32x16_bf16 v[18:33], v[98:101], v[94:97], v[18:33]
	s_setprio 0
	s_waitcnt lgkmcnt(0)
	s_barrier
	ds_read_b128 v[94:97], v68
	ds_read_b128 v[98:101], v68 offset:4608
	ds_read_b128 v[126:129], v1 offset:36864
	ds_read_b128 v[130:133], v1 offset:41472
	s_setprio 1
	ds_read_b128 v[86:89], v68 offset:32
	s_waitcnt lgkmcnt(2)
	v_mfma_f32_32x32x16_bf16 v[34:49], v[94:97], v[126:129], v[34:49]
	ds_read_b128 v[90:93], v1 offset:36896
	s_waitcnt lgkmcnt(2)
	v_mfma_f32_32x32x16_bf16 v[50:65], v[94:97], v[130:133], v[50:65]
	s_waitcnt vmcnt(7)
	ds_write_b128 v66, v[140:143] offset:18432
	s_waitcnt vmcnt(6)
	ds_write_b128 v66, v[102:105] offset:23040
	global_load_dwordx4 v[140:143], v[72:73], off offset:1792
	global_load_dwordx4 v[102:105], v[70:71], off offset:1792
	ds_read_b128 v[94:97], v1 offset:41504
	s_waitcnt lgkmcnt(3)
	v_mfma_f32_32x32x16_bf16 v[34:49], v[86:89], v[90:93], v[34:49]
	s_waitcnt lgkmcnt(0)
	v_mfma_f32_32x32x16_bf16 v[50:65], v[86:89], v[94:97], v[50:65]
	ds_read_b128 v[86:89], v68 offset:4640
	v_mfma_f32_32x32x16_bf16 v[2:17], v[98:101], v[126:129], v[2:17]
	v_mfma_f32_32x32x16_bf16 v[18:33], v[98:101], v[130:133], v[18:33]
	s_waitcnt vmcnt(7)
	ds_write_b128 v66, v[106:109] offset:27648
	s_waitcnt vmcnt(6)
	ds_write_b128 v66, v[110:113] offset:32256
	global_load_dwordx4 v[106:109], v[74:75], off offset:1792
	global_load_dwordx4 v[110:113], v[78:79], off offset:1792
	ds_read_b128 v[98:101], v68 offset:4704
	s_waitcnt lgkmcnt(3)
	v_mfma_f32_32x32x16_bf16 v[2:17], v[86:89], v[90:93], v[2:17]
	ds_read_b128 v[90:93], v1 offset:36928
	v_mfma_f32_32x32x16_bf16 v[18:33], v[86:89], v[94:97], v[18:33]
	ds_read_b128 v[86:89], v68 offset:64
	ds_read_b128 v[94:97], v1 offset:41536
	s_waitcnt lgkmcnt(1)
	v_mfma_f32_32x32x16_bf16 v[34:49], v[86:89], v[90:93], v[34:49]
	s_waitcnt lgkmcnt(0)
	v_mfma_f32_32x32x16_bf16 v[50:65], v[86:89], v[94:97], v[50:65]
	s_waitcnt vmcnt(7)
	ds_write_b128 v66, v[144:147] offset:55296
	s_waitcnt vmcnt(6)
	ds_write_b128 v66, v[122:125] offset:59904
	global_load_dwordx4 v[144:147], v[76:77], off offset:1792
	global_load_dwordx4 v[122:125], v[80:81], off offset:1792
	ds_read_b128 v[86:89], v68 offset:4672
	s_waitcnt lgkmcnt(0)
	v_mfma_f32_32x32x16_bf16 v[2:17], v[86:89], v[90:93], v[2:17]
	ds_read_b128 v[90:93], v1 offset:36960
	v_mfma_f32_32x32x16_bf16 v[18:33], v[86:89], v[94:97], v[18:33]
	ds_read_b128 v[86:89], v68 offset:96
	ds_read_b128 v[94:97], v1 offset:41568
	s_waitcnt lgkmcnt(1)
	v_mfma_f32_32x32x16_bf16 v[34:49], v[86:89], v[90:93], v[34:49]
	s_waitcnt lgkmcnt(0)
	v_mfma_f32_32x32x16_bf16 v[50:65], v[86:89], v[94:97], v[50:65]
	s_waitcnt vmcnt(7)
	ds_write_b128 v66, v[118:121] offset:64512
	s_waitcnt vmcnt(6)
	ds_write_b128 v69, v[114:117] offset:32256
	global_load_dwordx4 v[118:121], v[82:83], off offset:1792
	global_load_dwordx4 v[114:117], v[84:85], off offset:1792
	v_mfma_f32_32x32x16_bf16 v[2:17], v[98:101], v[90:93], v[2:17]
	v_mfma_f32_32x32x16_bf16 v[18:33], v[98:101], v[94:97], v[18:33]
	s_setprio 0
	s_waitcnt lgkmcnt(0)
	s_barrier
; #define MFMA(a, b, c) __builtin_amdgcn_mfma_f32_32x32x16_bf16((a), (b), (c), 0, 0, 0)
; template <int TM, int TN>
; DI void gemm_mainloop(const u16* __restrict__ A, long lda, const u16* __restrict__ Bt, long ldb, int K, char* smem,
;                       f32x16 (&acc)[TM][TN]) {
;     ...
;   for (int kt = 0; kt < nk; kt++) {
;     const int buf = kt & 1;
;     const u16* cA = sA + buf * BM * LD + (wm * 32 * TM + r) * LD + h * 8;
;     const u16* cB = sB + buf * BN * LD + (wn * 32 * TN + r) * LD + h * 8;
;     bf16x8 af[TM], bfr[TN];
; #pragma unroll
;     for (int tm = 0; tm < TM; tm++) af[tm] = *(const bf16x8*)(cA + tm * 32 * LD);
; #pragma unroll
;     for (int tn = 0; tn < TN; tn++) bfr[tn] = *(const bf16x8*)(cB + tn * 32 * LD);
;     if (kt + 1 < nk) GEMM_SSTORE(buf ^ 1)
;     __builtin_amdgcn_sched_barrier(0);
;     __builtin_amdgcn_s_setprio(1);
; #pragma unroll
;     for (int tm = 0; tm < TM; tm++)
; #pragma unroll
;       for (int tn = 0; tn < TN; tn++) acc[tm][tn] = MFMA(af[tm], bfr[tn], acc[tm][tn]);
; #pragma unroll
;     for (int tm = 0; tm < TM; tm++) af[tm] = *(const bf16x8*)(cA + tm * 32 * LD + 16);
; #pragma unroll
;     for (int tn = 0; tn < TN; tn++) bfr[tn] = *(const bf16x8*)(cB + tn * 32 * LD + 16);
; #pragma unroll
;     for (int tm = 0; tm < TM; tm++)
; #pragma unroll
;       for (int tn = 0; tn < TN; tn++) acc[tm][tn] = MFMA(af[tm], bfr[tn], acc[tm][tn]);
;     __builtin_amdgcn_sched_group_barrier(0x8, 4, 0);
;     if (kt + 2 < nk) GEMM_GLOAD((kt + 2) * 64)
; #pragma unroll
;     for (int ks = 2; ks < 4; ks++) {
; #pragma unroll
;       for (int tm = 0; tm < TM; tm++) af[tm] = *(const bf16x8*)(cA + tm * 32 * LD + ks * 16);
; #pragma unroll
;       for (int tn = 0; tn < TN; tn++) bfr[tn] = *(const bf16x8*)(cB + tn * 32 * LD + ks * 16);
; #pragma unroll
;       for (int tm = 0; tm < TM; tm++)
; #pragma unroll
;         for (int tn = 0; tn < TN; tn++) acc[tm][tn] = MFMA(af[tm], bfr[tn], acc[tm][tn]);
;     }
;     __builtin_amdgcn_s_setprio(0);
;     __syncthreads();
;   }
	ds_read_b128 v[94:97], v68 offset:18432
	ds_read_b128 v[98:101], v68 offset:23040
	ds_read_b128 v[126:129], v1 offset:55296
	ds_read_b128 v[130:133], v1 offset:59904
	s_setprio 1
	ds_read_b128 v[86:89], v68 offset:18464
	s_waitcnt lgkmcnt(2)
	v_mfma_f32_32x32x16_bf16 v[34:49], v[94:97], v[126:129], v[34:49]
	ds_read_b128 v[90:93], v1 offset:55328
	s_waitcnt lgkmcnt(2)
	v_mfma_f32_32x32x16_bf16 v[50:65], v[94:97], v[130:133], v[50:65]
	s_waitcnt vmcnt(7)
	ds_write_b128 v66, v[140:143]
	s_waitcnt vmcnt(6)
	ds_write_b128 v66, v[102:105] offset:4608
	global_load_dwordx4 v[140:143], v[72:73], off offset:1920
	global_load_dwordx4 v[102:105], v[70:71], off offset:1920
	ds_read_b128 v[94:97], v1 offset:59936
	s_waitcnt lgkmcnt(3)
	v_mfma_f32_32x32x16_bf16 v[34:49], v[86:89], v[90:93], v[34:49]
	s_waitcnt lgkmcnt(0)
	v_mfma_f32_32x32x16_bf16 v[50:65], v[86:89], v[94:97], v[50:65]
	ds_read_b128 v[86:89], v68 offset:23072
	v_mfma_f32_32x32x16_bf16 v[2:17], v[98:101], v[126:129], v[2:17]
	v_mfma_f32_32x32x16_bf16 v[18:33], v[98:101], v[130:133], v[18:33]
	s_waitcnt vmcnt(7)
	ds_write_b128 v66, v[106:109] offset:9216
	s_waitcnt vmcnt(6)
	ds_write_b128 v66, v[110:113] offset:13824
	global_load_dwordx4 v[106:109], v[74:75], off offset:1920
	global_load_dwordx4 v[110:113], v[78:79], off offset:1920
	ds_read_b128 v[98:101], v68 offset:23136
	s_waitcnt lgkmcnt(3)
	v_mfma_f32_32x32x16_bf16 v[2:17], v[86:89], v[90:93], v[2:17]
	ds_read_b128 v[90:93], v1 offset:55360
	v_mfma_f32_32x32x16_bf16 v[18:33], v[86:89], v[94:97], v[18:33]
	ds_read_b128 v[86:89], v68 offset:18496
	ds_read_b128 v[94:97], v1 offset:59968
	s_waitcnt lgkmcnt(1)
	v_mfma_f32_32x32x16_bf16 v[34:49], v[86:89], v[90:93], v[34:49]
	s_waitcnt lgkmcnt(0)
	v_mfma_f32_32x32x16_bf16 v[50:65], v[86:89], v[94:97], v[50:65]
	s_waitcnt vmcnt(7)
	ds_write_b128 v66, v[144:147] offset:36864
	s_waitcnt vmcnt(6)
	ds_write_b128 v66, v[122:125] offset:41472
	global_load_dwordx4 v[144:147], v[76:77], off offset:1920
	global_load_dwordx4 v[122:125], v[80:81], off offset:1920
	ds_read_b128 v[86:89], v68 offset:23104
	s_waitcnt lgkmcnt(0)
	v_mfma_f32_32x32x16_bf16 v[2:17], v[86:89], v[90:93], v[2:17]
	ds_read_b128 v[90:93], v1 offset:55392
	v_mfma_f32_32x32x16_bf16 v[18:33], v[86:89], v[94:97], v[18:33]
	ds_read_b128 v[86:89], v68 offset:18528
	ds_read_b128 v[94:97], v1 offset:60000
	s_waitcnt lgkmcnt(1)
	v_mfma_f32_32x32x16_bf16 v[34:49], v[86:89], v[90:93], v[34:49]
	s_waitcnt lgkmcnt(0)
	v_mfma_f32_32x32x16_bf16 v[50:65], v[86:89], v[94:97], v[50:65]
	s_waitcnt vmcnt(7)
	ds_write_b128 v66, v[118:121] offset:46080
	s_waitcnt vmcnt(6)
	ds_write_b128 v66, v[114:117] offset:50688
	global_load_dwordx4 v[118:121], v[82:83], off offset:1920
	global_load_dwordx4 v[114:117], v[84:85], off offset:1920
	s_nop 0
	v_mfma_f32_32x32x16_bf16 v[2:17], v[98:101], v[90:93], v[2:17]
	v_mfma_f32_32x32x16_bf16 v[18:33], v[98:101], v[94:97], v[18:33]
	s_setprio 0
	s_waitcnt lgkmcnt(0)
	s_barrier
	ds_read_b128 v[74:77], v68
	ds_read_b128 v[78:81], v68 offset:4608
	ds_read_b128 v[82:85], v1 offset:36864
	ds_read_b128 v[90:93], v1 offset:41472
	s_setprio 1
	ds_read_b128 v[70:73], v68 offset:32
	s_waitcnt lgkmcnt(2)
	v_mfma_f32_32x32x16_bf16 v[34:49], v[74:77], v[82:85], v[34:49]
	s_waitcnt lgkmcnt(1)
	v_mfma_f32_32x32x16_bf16 v[50:65], v[74:77], v[90:93], v[50:65]
	s_waitcnt vmcnt(7)
	ds_write_b128 v66, v[140:143] offset:18432
	s_waitcnt vmcnt(6)
	ds_write_b128 v66, v[102:105] offset:23040
	ds_read_b128 v[74:77], v1 offset:36896
	v_mfma_f32_32x32x16_bf16 v[2:17], v[78:81], v[82:85], v[2:17]
	v_mfma_f32_32x32x16_bf16 v[18:33], v[78:81], v[90:93], v[18:33]
	ds_read_b128 v[78:81], v1 offset:41504
	s_waitcnt lgkmcnt(1)
	v_mfma_f32_32x32x16_bf16 v[34:49], v[70:73], v[74:77], v[34:49]
	s_waitcnt lgkmcnt(0)
	v_mfma_f32_32x32x16_bf16 v[50:65], v[70:73], v[78:81], v[50:65]
	s_waitcnt vmcnt(5)
	ds_write_b128 v66, v[106:109] offset:27648
	s_waitcnt vmcnt(4)
	ds_write_b128 v66, v[110:113] offset:32256
	ds_read_b128 v[70:73], v68 offset:4640
	s_waitcnt lgkmcnt(0)
	v_mfma_f32_32x32x16_bf16 v[2:17], v[70:73], v[74:77], v[2:17]
	ds_read_b128 v[74:77], v1 offset:36928
	v_mfma_f32_32x32x16_bf16 v[18:33], v[70:73], v[78:81], v[18:33]
	ds_read_b128 v[70:73], v68 offset:64
	ds_read_b128 v[78:81], v1 offset:41536
	s_waitcnt lgkmcnt(1)
	v_mfma_f32_32x32x16_bf16 v[34:49], v[70:73], v[74:77], v[34:49]
	s_waitcnt lgkmcnt(0)
	v_mfma_f32_32x32x16_bf16 v[50:65], v[70:73], v[78:81], v[50:65]
	s_waitcnt vmcnt(3)
	ds_write_b128 v66, v[144:147] offset:55296
	s_waitcnt vmcnt(2)
	ds_write_b128 v66, v[122:125] offset:59904
	ds_read_b128 v[70:73], v68 offset:4672
	s_waitcnt lgkmcnt(0)
	v_mfma_f32_32x32x16_bf16 v[2:17], v[70:73], v[74:77], v[2:17]
	ds_read_b128 v[74:77], v1 offset:36960
	v_mfma_f32_32x32x16_bf16 v[18:33], v[70:73], v[78:81], v[18:33]
	ds_read_b128 v[70:73], v68 offset:96
	ds_read_b128 v[78:81], v1 offset:41568
	s_waitcnt lgkmcnt(1)
	v_mfma_f32_32x32x16_bf16 v[34:49], v[70:73], v[74:77], v[34:49]
	s_waitcnt lgkmcnt(0)
	v_mfma_f32_32x32x16_bf16 v[50:65], v[70:73], v[78:81], v[50:65]
	s_waitcnt vmcnt(1)
	ds_write_b128 v66, v[118:121] offset:64512
	s_waitcnt vmcnt(0)
	ds_write_b128 v69, v[114:117] offset:32256
	ds_read_b128 v[70:73], v68 offset:4704
	s_waitcnt lgkmcnt(0)
	v_mfma_f32_32x32x16_bf16 v[2:17], v[70:73], v[74:77], v[2:17]
	v_mfma_f32_32x32x16_bf16 v[18:33], v[70:73], v[78:81], v[18:33]
	s_setprio 0
	s_barrier
; #define MFMA(a, b, c) __builtin_amdgcn_mfma_f32_32x32x16_bf16((a), (b), (c), 0, 0, 0)
; DI int crow(int i, int h) { return (i & 3) + 8 * (i >> 2) + 4 * h; }
; template <int TM, int TN>
; DI void gemm_mainloop(const u16* __restrict__ A, long lda, const u16* __restrict__ Bt, long ldb, int K, char* smem,
;                       f32x16 (&acc)[TM][TN]) {
;     ...
;       for (int tn = 0; tn < TN; tn++) acc[tm][tn] = MFMA(af[tm], bfr[tn], acc[tm][tn]);
; #pragma unroll
;     for (int tm = 0; tm < TM; tm++) af[tm] = *(const bf16x8*)(cA + tm * 32 * LD + 16);
; #pragma unroll
;     for (int tn = 0; tn < TN; tn++) bfr[tn] = *(const bf16x8*)(cB + tn * 32 * LD + 16);
; #pragma unroll
;     for (int tm = 0; tm < TM; tm++)
; #pragma unroll
;       for (int tn = 0; tn < TN; tn++) acc[tm][tn] = MFMA(af[tm], bfr[tn], acc[tm][tn]);
;     __builtin_amdgcn_sched_group_barrier(0x8, 4, 0);
;     if (kt + 2 < nk) GEMM_GLOAD((kt + 2) * 64)
; #pragma unroll
;     for (int ks = 2; ks < 4; ks++) {
; #pragma unroll
;       for (int tm = 0; tm < TM; tm++) af[tm] = *(const bf16x8*)(cA + tm * 32 * LD + ks * 16);
; #pragma unroll
;       for (int tn = 0; tn < TN; tn++) bfr[tn] = *(const bf16x8*)(cB + tn * 32 * LD + ks * 16);
; #pragma unroll
;       for (int tm = 0; tm < TM; tm++)
; #pragma unroll
;         for (int tn = 0; tn < TN; tn++) acc[tm][tn] = MFMA(af[tm], bfr[tn], acc[tm][tn]);
;     }
; template <int TM, int TN, class Epi>
; DI void gemm_tile(const u16* A, long lda, const u16* Bt, long ldb, int K, int m0, int n0, char* smem, const Epi& epi) {
;     ...
; #pragma unroll
;   for (int tm = 0; tm < TM; tm++)
; #pragma unroll
;     for (int tn = 0; tn < TN; tn++)
; #pragma unroll
;       for (int i = 0; i < 16; i++)
;         Ct[(wm * 32 * TM + tm * 32 + crow(i, h)) * LDC + wn * 32 * TN + tn * 32 + r] = acc[tm][tn][i];
;   __syncthreads();
	ds_read_b128 v[70:73], v68 offset:18432
	ds_read_b128 v[74:77], v68 offset:23040
	ds_read_b128 v[78:81], v1 offset:55296
	ds_read_b128 v[82:85], v1 offset:59904
	s_setprio 1
	s_waitcnt lgkmcnt(1)
	v_mfma_f32_32x32x16_bf16 v[34:49], v[70:73], v[78:81], v[34:49]
	s_waitcnt lgkmcnt(0)
	v_mfma_f32_32x32x16_bf16 v[50:65], v[70:73], v[82:85], v[50:65]
	ds_read_b128 v[70:73], v68 offset:18464
	v_mfma_f32_32x32x16_bf16 v[2:17], v[74:77], v[78:81], v[2:17]
	ds_read_b128 v[78:81], v1 offset:59936
	v_mfma_f32_32x32x16_bf16 v[18:33], v[74:77], v[82:85], v[18:33]
	ds_read_b128 v[74:77], v1 offset:55328
	s_waitcnt lgkmcnt(0)
	v_mfma_f32_32x32x16_bf16 v[34:49], v[70:73], v[74:77], v[34:49]
	v_mfma_f32_32x32x16_bf16 v[50:65], v[70:73], v[78:81], v[50:65]
	ds_read_b128 v[70:73], v68 offset:23072
	s_waitcnt lgkmcnt(0)
	v_mfma_f32_32x32x16_bf16 v[2:17], v[70:73], v[74:77], v[2:17]
	ds_read_b128 v[74:77], v1 offset:55360
	v_mfma_f32_32x32x16_bf16 v[18:33], v[70:73], v[78:81], v[18:33]
	ds_read_b128 v[70:73], v68 offset:18496
	ds_read_b128 v[78:81], v1 offset:59968
	s_waitcnt lgkmcnt(1)
	v_mfma_f32_32x32x16_bf16 v[34:49], v[70:73], v[74:77], v[34:49]
	s_waitcnt lgkmcnt(0)
	v_mfma_f32_32x32x16_bf16 v[50:65], v[70:73], v[78:81], v[50:65]
	ds_read_b128 v[70:73], v68 offset:23104
	s_waitcnt lgkmcnt(0)
	v_mfma_f32_32x32x16_bf16 v[2:17], v[70:73], v[74:77], v[2:17]
	ds_read_b128 v[74:77], v1 offset:55392
	v_mfma_f32_32x32x16_bf16 v[18:33], v[70:73], v[78:81], v[18:33]
	ds_read_b128 v[70:73], v68 offset:18528
	ds_read_b128 v[78:81], v1 offset:60000
	s_waitcnt lgkmcnt(1)
	v_mfma_f32_32x32x16_bf16 v[34:49], v[70:73], v[74:77], v[34:49]
	s_waitcnt lgkmcnt(0)
	v_mfma_f32_32x32x16_bf16 v[50:65], v[70:73], v[78:81], v[50:65]
	ds_read_b128 v[68:71], v68 offset:23136
	s_waitcnt lgkmcnt(0)
	v_mfma_f32_32x32x16_bf16 v[2:17], v[68:71], v[74:77], v[2:17]
	v_mfma_f32_32x32x16_bf16 v[18:33], v[68:71], v[78:81], v[18:33]
	s_setprio 0
	v_mov_b32_e32 v1, v0
	s_barrier
	s_lshl_b64 s[4:5], s[6:7], 1
	v_lshrrev_b32_e32 v66, 1, v1
	v_and_b32_e32 v66, 0xfffffc0, v66
	v_lshrrev_b32_e32 v68, 3, v1
	v_and_or_b32 v66, v68, 4, v66
	v_and_b32_e32 v68, 0x5f, v1
	v_mul_lo_u32 v66, v66, s24
	v_lshl_add_u32 v66, v68, 2, v66
	ds_write2_b32 v66, v34, v50 offset1:32
	v_add_u32_e32 v34, 0x400, v66
	ds_write2_b32 v34, v36, v52 offset0:8 offset1:40
	ds_write2_b32 v34, v37, v53 offset0:140 offset1:172
	v_add_u32_e32 v34, 0x1000, v66
	ds_write2_b32 v34, v38, v54 offset0:32 offset1:64
	ds_write2_b32 v34, v39, v55 offset0:164 offset1:196
	v_add_u32_e32 v34, 0x1400, v66
	ds_write2_b32 v34, v40, v56 offset0:40 offset1:72
	ds_write2_b32 v34, v41, v57 offset0:172 offset1:204
	v_add_u32_e32 v34, 0x2000, v66
	ds_write2_b32 v34, v42, v58 offset0:64 offset1:96
	ds_write2_b32 v34, v43, v59 offset0:196 offset1:228
	v_add_u32_e32 v34, 0x2400, v66
	ds_write2_b32 v34, v44, v60 offset0:72 offset1:104
	ds_write2_b32 v34, v45, v61 offset0:204 offset1:236
	v_add_u32_e32 v34, 0x3000, v66
	ds_write2_b32 v34, v46, v62 offset0:96 offset1:128
	v_add_u32_e32 v34, 0x3200, v66
	ds_write2_b32 v34, v47, v63 offset0:100 offset1:132
	v_add_u32_e32 v34, 0x3400, v66
	ds_write2_b32 v34, v48, v64 offset0:104 offset1:136
	v_add_u32_e32 v34, 0x3600, v66
	ds_write2_b32 v34, v49, v65 offset0:108 offset1:140
	v_add_u32_e32 v34, 0x4000, v66
	ds_write2_b32 v34, v2, v18 offset0:128 offset1:160
	v_add_u32_e32 v2, 0x4400, v66
	ds_write2_b32 v2, v3, v19 offset0:4 offset1:36
	ds_write2_b32 v2, v4, v20 offset0:136 offset1:168
	v_add_u32_e32 v2, 0x4800, v66
	ds_write2_b32 v2, v5, v21 offset0:12 offset1:44
	v_add_u32_e32 v2, 0x5000, v66
	ds_write2_b32 v2, v6, v22 offset0:160 offset1:192
	v_add_u32_e32 v2, 0x5400, v66
	ds_write2_b32 v2, v7, v23 offset0:36 offset1:68
	ds_write2_b32 v2, v8, v24 offset0:168 offset1:200
	v_add_u32_e32 v2, 0x5800, v66
	ds_write2_b32 v2, v9, v25 offset0:44 offset1:76
	v_add_u32_e32 v2, 0x6000, v66
	ds_write2_b32 v2, v10, v26 offset0:192 offset1:224
	v_add_u32_e32 v2, 0x6400, v66
	ds_write2_b32 v2, v11, v27 offset0:68 offset1:100
	ds_write2_b32 v2, v12, v28 offset0:200 offset1:232
	v_add_u32_e32 v2, 0x6800, v66
	ds_write2_b32 v2, v13, v29 offset0:76 offset1:108
	v_add_u32_e32 v2, 0x7200, v66
	ds_write2_b32 v2, v14, v30 offset0:96 offset1:128
	v_add_u32_e32 v2, 0x7400, v66
	ds_write2_b32 v2, v15, v31 offset0:100 offset1:132
	v_add_u32_e32 v2, 0x7600, v66
	ds_write2_b32 v2, v16, v32 offset0:104 offset1:136
	v_add_u32_e32 v2, 0x7800, v66
	ds_write2_b32 v2, v17, v33 offset0:108 offset1:140
	v_lshlrev_b32_e32 v2, 3, v1
	v_and_b32_e32 v3, 0x78, v2
	s_add_u32 s4, s3, s4
	ds_write2_b32 v66, v35, v51 offset0:132 offset1:164
	s_addc_u32 s5, s14, s5
	v_lshlrev_b32_e32 v66, 1, v3
	v_lshlrev_b32_e32 v2, 2, v3
	v_lshl_add_u64 v[4:5], s[4:5], 0, v[66:67]
	s_mov_b32 s4, 0
	s_waitcnt lgkmcnt(0)
	s_barrier

; #define MFMA(a, b, c) __builtin_amdgcn_mfma_f32_32x32x16_bf16((a), (b), (c), 0, 0, 0)
; template <int TM, int TN>
; DI void gemm_mainloop(const u16* __restrict__ A, long lda, const u16* __restrict__ Bt, long ldb, int K, char* smem,
;                       f32x16 (&acc)[TM][TN]) {
;     ...
;   const int nk = K / 64;
;   const int lrow = tid >> 3, lch = (tid & 7) * 8;
;   const u16* gA = A + (long)lrow * lda + lch;
;   const u16* gB = Bt + (long)lrow * ldb + lch;
;   const int soff = lrow * LD + lch;
;     ...
;   GEMM_GLOAD(0)
;   __syncthreads();
;   GEMM_SSTORE(0)
;   if (nk > 1) GEMM_GLOAD(64)
;   __syncthreads();
;   for (int kt = 0; kt < nk; kt++) {
;     const int buf = kt & 1;
;     const u16* cA = sA + buf * BM * LD + (wm * 32 * TM + r) * LD + h * 8;
;     const u16* cB = sB + buf * BN * LD + (wn * 32 * TN + r) * LD + h * 8;
;     bf16x8 af[TM], bfr[TN];
; #pragma unroll
;     for (int tm = 0; tm < TM; tm++) af[tm] = *(const bf16x8*)(cA + tm * 32 * LD);
; #pragma unroll
;     for (int tn = 0; tn < TN; tn++) bfr[tn] = *(const bf16x8*)(cB + tn * 32 * LD);
;     if (kt + 1 < nk) GEMM_SSTORE(buf ^ 1)
;     __builtin_amdgcn_sched_barrier(0);
;     __builtin_amdgcn_s_setprio(1);
; #pragma unroll
;     for (int tm = 0; tm < TM; tm++)
; #pragma unroll
;       for (int tn = 0; tn < TN; tn++) acc[tm][tn] = MFMA(af[tm], bfr[tn], acc[tm][tn]);
; #pragma unroll
;     for (int tm = 0; tm < TM; tm++) af[tm] = *(const bf16x8*)(cA + tm * 32 * LD + 16);
; #pragma unroll
;     for (int tn = 0; tn < TN; tn++) bfr[tn] = *(const bf16x8*)(cB + tn * 32 * LD + 16);
; #pragma unroll
;     for (int tm = 0; tm < TM; tm++)
; #pragma unroll
;       for (int tn = 0; tn < TN; tn++) acc[tm][tn] = MFMA(af[tm], bfr[tn], acc[tm][tn]);
;     __builtin_amdgcn_sched_group_barrier(0x8, 4, 0);
;     if (kt + 2 < nk) GEMM_GLOAD((kt + 2) * 64)
; template <class Epi>
; DI void phase_gemm128(const Sched& sc, const u16* A, long lda, const u16* Bt, long ldb, int K, int MT, int NT, int SN, char* smem, const Epi& epi) {
;     ...
;     for (int st = xg; st < nfull; st += 8) {
;       int sm = st / sng, sn = st % sng;
;       int mt = sm * SM + xi / SN, nt = sn * SN + xi % SN;
;       gemm_tile<2, 2>(A, lda, Bt, ldb, K, mt * 128, nt * 128, smem, epi);
.LBB0_1553:
	s_mul_hi_u32 s4, s38, 0xcccccccd
	s_lshr_b32 s4, s4, 2
	s_mul_i32 s5, s4, 5
	s_sub_i32 s5, s38, s5
	s_lshl_b32 s39, s4, 11
	s_add_i32 s39, s39, s21
	s_lshl_b32 s6, s5, 9
	s_add_i32 s6, s6, s22
	s_mul_i32 s4, s39, 0x880
	s_mul_hi_i32 s5, s39, 0x880
	s_add_u32 s4, s8, s4
	v_mov_b32_e32 v1, v0
	s_addc_u32 s5, s9, s5
	s_mul_i32 s7, s6, 0x880
	v_lshlrev_b32_e32 v2, 3, v1
	v_ashrrev_i32_e32 v68, 3, v1
	v_and_b32_e32 v69, 56, v2
	v_mov_b64_e32 v[2:3], s[4:5]
	v_mad_i64_i32 v[2:3], s[4:5], v68, s23, v[2:3]
	v_lshlrev_b32_e32 v66, 1, v69
	v_lshl_add_u64 v[72:73], v[2:3], 0, v[66:67]
	s_ashr_i32 s17, s7, 31
	v_add_co_u32_e32 v70, vcc, s25, v72
	s_add_u32 s16, s3, s7
	s_nop 0
	v_addc_co_u32_e32 v71, vcc, 0, v73, vcc
	s_addc_u32 s17, s20, s17
	v_add_co_u32_e32 v74, vcc, s26, v72
	v_mov_b64_e32 v[2:3], s[16:17]
	s_nop 0
	v_addc_co_u32_e32 v75, vcc, 0, v73, vcc
	v_mad_i64_i32 v[18:19], s[4:5], v68, s23, v[2:3]
	v_add_co_u32_e32 v76, vcc, s27, v72
	v_lshl_add_u64 v[78:79], v[18:19], 0, v[66:67]
	s_nop 0
	v_addc_co_u32_e32 v77, vcc, 0, v73, vcc
	v_add_co_u32_e32 v80, vcc, s25, v78
	global_load_dwordx4 v[2:5], v[72:73], off
	s_nop 0
	v_addc_co_u32_e32 v81, vcc, 0, v79, vcc
	v_add_co_u32_e32 v82, vcc, s26, v78
	global_load_dwordx4 v[6:9], v[70:71], off
	s_nop 0
	v_addc_co_u32_e32 v83, vcc, 0, v79, vcc
	v_add_co_u32_e32 v84, vcc, s27, v78
	global_load_dwordx4 v[10:13], v[74:75], off
	s_nop 0
	v_addc_co_u32_e32 v85, vcc, 0, v79, vcc
	global_load_dwordx4 v[14:17], v[76:77], off
	global_load_dwordx4 v[18:21], v[78:79], off
	global_load_dwordx4 v[22:25], v[80:81], off
	global_load_dwordx4 v[26:29], v[82:83], off
	global_load_dwordx4 v[30:33], v[84:85], off
	s_barrier
	global_load_dwordx4 v[34:37], v[72:73], off offset:128
	global_load_dwordx4 v[38:41], v[70:71], off offset:128
	global_load_dwordx4 v[42:45], v[74:75], off offset:128
	global_load_dwordx4 v[46:49], v[76:77], off offset:128
	global_load_dwordx4 v[50:53], v[78:79], off offset:128
	global_load_dwordx4 v[54:57], v[80:81], off offset:128
	global_load_dwordx4 v[58:61], v[82:83], off offset:128
	global_load_dwordx4 v[62:65], v[84:85], off offset:128
	v_and_b32_e32 v66, 31, v1
	v_lshrrev_b32_e32 v86, 1, v1
	v_and_b32_e32 v1, 0x5f, v1
	v_mul_lo_u32 v68, v68, s24
	v_and_or_b32 v87, v86, s28, v66
	v_and_b32_e32 v86, 16, v86
	v_add_lshl_u32 v66, v68, v69, 1
	v_mad_u64_u32 v[68:69], s[4:5], v87, s29, v[86:87]
	v_mad_u32_u24 v1, v1, s29, v86
	v_add_u32_e32 v69, 0x9000, v66
	s_waitcnt vmcnt(15)
	ds_write_b128 v66, v[2:5]
	s_waitcnt vmcnt(14)
	ds_write_b128 v66, v[6:9] offset:4608
	s_waitcnt vmcnt(13)
	ds_write_b128 v66, v[10:13] offset:9216
	s_waitcnt vmcnt(12)
	ds_write_b128 v66, v[14:17] offset:13824
	s_waitcnt vmcnt(11)
	ds_write_b128 v66, v[18:21] offset:36864
	s_waitcnt vmcnt(10)
	ds_write_b128 v66, v[22:25] offset:41472
	s_waitcnt vmcnt(9)
	ds_write_b128 v66, v[26:29] offset:46080
	s_waitcnt vmcnt(8)
	ds_write_b128 v66, v[30:33] offset:50688
	s_waitcnt lgkmcnt(0)
	s_barrier
	ds_read_b128 v[2:5], v68
	ds_read_b128 v[18:21], v68 offset:4608
	ds_read_b128 v[6:9], v1 offset:36864
	ds_read_b128 v[22:25], v1 offset:41472
	s_waitcnt vmcnt(7)
	ds_write_b128 v66, v[34:37] offset:18432
	s_waitcnt vmcnt(6)
	ds_write_b128 v66, v[38:41] offset:23040
	s_waitcnt vmcnt(5)
	ds_write_b128 v66, v[42:45] offset:27648
	s_waitcnt vmcnt(4)
	ds_write_b128 v66, v[46:49] offset:32256
	s_waitcnt vmcnt(3)
	ds_write_b128 v66, v[50:53] offset:55296
	s_waitcnt vmcnt(2)
	ds_write_b128 v66, v[54:57] offset:59904
	s_waitcnt vmcnt(1)
	ds_write_b128 v66, v[58:61] offset:64512
	s_waitcnt vmcnt(0)
	ds_write_b128 v69, v[62:65] offset:32256
	s_setprio 1
	ds_read_b128 v[86:89], v68 offset:32
	s_waitcnt lgkmcnt(10)
	v_mfma_f32_32x32x16_bf16 v[34:49], v[2:5], v[6:9], 0
	ds_read_b128 v[90:93], v1 offset:36896
	ds_read_b128 v[94:97], v1 offset:41504
	ds_read_b128 v[98:101], v68 offset:4704
	global_load_dwordx4 v[102:105], v[70:71], off offset:256
	global_load_dwordx4 v[106:109], v[74:75], off offset:256
	global_load_dwordx4 v[110:113], v[76:77], off offset:256
	global_load_dwordx4 v[114:117], v[84:85], off offset:256
	s_waitcnt lgkmcnt(12)
	v_mfma_f32_32x32x16_bf16 v[50:65], v[2:5], v[22:25], 0
	global_load_dwordx4 v[118:121], v[82:83], off offset:256
	global_load_dwordx4 v[122:125], v[80:81], off offset:256
	global_load_dwordx4 v[140:143], v[72:73], off offset:256
	global_load_dwordx4 v[144:147], v[78:79], off offset:256
	s_waitcnt lgkmcnt(2)
	v_mfma_f32_32x32x16_bf16 v[34:49], v[86:89], v[90:93], v[34:49]
	s_waitcnt lgkmcnt(1)
	v_mfma_f32_32x32x16_bf16 v[50:65], v[86:89], v[94:97], v[50:65]
	ds_read_b128 v[86:89], v68 offset:4640
	v_mfma_f32_32x32x16_bf16 v[2:17], v[18:21], v[6:9], 0
	v_mfma_f32_32x32x16_bf16 v[18:33], v[18:21], v[22:25], 0
	s_waitcnt lgkmcnt(0)
	v_mfma_f32_32x32x16_bf16 v[2:17], v[86:89], v[90:93], v[2:17]
	ds_read_b128 v[90:93], v1 offset:36928
	v_mfma_f32_32x32x16_bf16 v[18:33], v[86:89], v[94:97], v[18:33]
	ds_read_b128 v[86:89], v68 offset:64
	ds_read_b128 v[94:97], v1 offset:41536
	s_waitcnt lgkmcnt(1)
	v_mfma_f32_32x32x16_bf16 v[34:49], v[86:89], v[90:93], v[34:49]
	s_waitcnt lgkmcnt(0)
	v_mfma_f32_32x32x16_bf16 v[50:65], v[86:89], v[94:97], v[50:65]
	ds_read_b128 v[86:89], v68 offset:4672
	s_waitcnt lgkmcnt(0)
	v_mfma_f32_32x32x16_bf16 v[2:17], v[86:89], v[90:93], v[2:17]
	ds_read_b128 v[90:93], v1 offset:36960
	v_mfma_f32_32x32x16_bf16 v[18:33], v[86:89], v[94:97], v[18:33]
	ds_read_b128 v[86:89], v68 offset:96
	ds_read_b128 v[94:97], v1 offset:41568
	s_waitcnt lgkmcnt(1)
	v_mfma_f32_32x32x16_bf16 v[34:49], v[86:89], v[90:93], v[34:49]
	s_waitcnt lgkmcnt(0)
	v_mfma_f32_32x32x16_bf16 v[50:65], v[86:89], v[94:97], v[50:65]
	v_mfma_f32_32x32x16_bf16 v[2:17], v[98:101], v[90:93], v[2:17]
	v_mfma_f32_32x32x16_bf16 v[18:33], v[98:101], v[94:97], v[18:33]
	s_setprio 0
	s_barrier
; #define MFMA(a, b, c) __builtin_amdgcn_mfma_f32_32x32x16_bf16((a), (b), (c), 0, 0, 0)
; template <int TM, int TN>
; DI void gemm_mainloop(const u16* __restrict__ A, long lda, const u16* __restrict__ Bt, long ldb, int K, char* smem,
;                       f32x16 (&acc)[TM][TN]) {
;     ...
;   for (int kt = 0; kt < nk; kt++) {
;     const int buf = kt & 1;
;     const u16* cA = sA + buf * BM * LD + (wm * 32 * TM + r) * LD + h * 8;
;     const u16* cB = sB + buf * BN * LD + (wn * 32 * TN + r) * LD + h * 8;
;     bf16x8 af[TM], bfr[TN];
; #pragma unroll
;     for (int tm = 0; tm < TM; tm++) af[tm] = *(const bf16x8*)(cA + tm * 32 * LD);
; #pragma unroll
;     for (int tn = 0; tn < TN; tn++) bfr[tn] = *(const bf16x8*)(cB + tn * 32 * LD);
;     if (kt + 1 < nk) GEMM_SSTORE(buf ^ 1)
;     __builtin_amdgcn_sched_barrier(0);
;     __builtin_amdgcn_s_setprio(1);
; #pragma unroll
;     for (int tm = 0; tm < TM; tm++)
; #pragma unroll
;       for (int tn = 0; tn < TN; tn++) acc[tm][tn] = MFMA(af[tm], bfr[tn], acc[tm][tn]);
; #pragma unroll
;     for (int tm = 0; tm < TM; tm++) af[tm] = *(const bf16x8*)(cA + tm * 32 * LD + 16);
; #pragma unroll
;     for (int tn = 0; tn < TN; tn++) bfr[tn] = *(const bf16x8*)(cB + tn * 32 * LD + 16);
; #pragma unroll
;     for (int tm = 0; tm < TM; tm++)
; #pragma unroll
;       for (int tn = 0; tn < TN; tn++) acc[tm][tn] = MFMA(af[tm], bfr[tn], acc[tm][tn]);
;     __builtin_amdgcn_sched_group_barrier(0x8, 4, 0);
;     if (kt + 2 < nk) GEMM_GLOAD((kt + 2) * 64)
; #pragma unroll
;     for (int ks = 2; ks < 4; ks++) {
; #pragma unroll
;       for (int tm = 0; tm < TM; tm++) af[tm] = *(const bf16x8*)(cA + tm * 32 * LD + ks * 16);
; #pragma unroll
;       for (int tn = 0; tn < TN; tn++) bfr[tn] = *(const bf16x8*)(cB + tn * 32 * LD + ks * 16);
; #pragma unroll
;       for (int tm = 0; tm < TM; tm++)
; #pragma unroll
;         for (int tn = 0; tn < TN; tn++) acc[tm][tn] = MFMA(af[tm], bfr[tn], acc[tm][tn]);
;     }
;     __builtin_amdgcn_s_setprio(0);
;     __syncthreads();
;   }
	ds_read_b128 v[94:97], v68 offset:18432
	ds_read_b128 v[98:101], v68 offset:23040
	ds_read_b128 v[126:129], v1 offset:55296
	ds_read_b128 v[130:133], v1 offset:59904
	s_setprio 1
	ds_read_b128 v[86:89], v68 offset:18464
	s_waitcnt lgkmcnt(2)
	v_mfma_f32_32x32x16_bf16 v[34:49], v[94:97], v[126:129], v[34:49]
	ds_read_b128 v[90:93], v1 offset:55328
	s_waitcnt lgkmcnt(2)
	v_mfma_f32_32x32x16_bf16 v[50:65], v[94:97], v[130:133], v[50:65]
	s_waitcnt vmcnt(1)
	ds_write_b128 v66, v[140:143]
	ds_write_b128 v66, v[102:105] offset:4608
	global_load_dwordx4 v[140:143], v[72:73], off offset:384
	global_load_dwordx4 v[102:105], v[70:71], off offset:384
	ds_read_b128 v[94:97], v1 offset:59936
	s_waitcnt lgkmcnt(3)
	v_mfma_f32_32x32x16_bf16 v[34:49], v[86:89], v[90:93], v[34:49]
	s_waitcnt lgkmcnt(0)
	v_mfma_f32_32x32x16_bf16 v[50:65], v[86:89], v[94:97], v[50:65]
	ds_read_b128 v[86:89], v68 offset:23072
	v_mfma_f32_32x32x16_bf16 v[2:17], v[98:101], v[126:129], v[2:17]
	v_mfma_f32_32x32x16_bf16 v[18:33], v[98:101], v[130:133], v[18:33]
	ds_write_b128 v66, v[106:109] offset:9216
	ds_write_b128 v66, v[110:113] offset:13824
	global_load_dwordx4 v[106:109], v[74:75], off offset:384
	global_load_dwordx4 v[110:113], v[76:77], off offset:384
	ds_read_b128 v[98:101], v68 offset:23136
	s_waitcnt lgkmcnt(3)
	v_mfma_f32_32x32x16_bf16 v[2:17], v[86:89], v[90:93], v[2:17]
	ds_read_b128 v[90:93], v1 offset:55360
	v_mfma_f32_32x32x16_bf16 v[18:33], v[86:89], v[94:97], v[18:33]
	ds_read_b128 v[86:89], v68 offset:18496
	ds_read_b128 v[94:97], v1 offset:59968
	s_waitcnt lgkmcnt(1)
	v_mfma_f32_32x32x16_bf16 v[34:49], v[86:89], v[90:93], v[34:49]
	s_waitcnt lgkmcnt(0)
	v_mfma_f32_32x32x16_bf16 v[50:65], v[86:89], v[94:97], v[50:65]
	s_waitcnt vmcnt(4)
	ds_write_b128 v66, v[144:147] offset:36864
	ds_write_b128 v66, v[122:125] offset:41472
	global_load_dwordx4 v[144:147], v[78:79], off offset:384
	global_load_dwordx4 v[122:125], v[80:81], off offset:384
	ds_read_b128 v[86:89], v68 offset:23104
	s_waitcnt lgkmcnt(0)
	v_mfma_f32_32x32x16_bf16 v[2:17], v[86:89], v[90:93], v[2:17]
	ds_read_b128 v[90:93], v1 offset:55392
	v_mfma_f32_32x32x16_bf16 v[18:33], v[86:89], v[94:97], v[18:33]
	ds_read_b128 v[86:89], v68 offset:18528
	ds_read_b128 v[94:97], v1 offset:60000
	s_waitcnt lgkmcnt(1)
	v_mfma_f32_32x32x16_bf16 v[34:49], v[86:89], v[90:93], v[34:49]
	s_waitcnt lgkmcnt(0)
	v_mfma_f32_32x32x16_bf16 v[50:65], v[86:89], v[94:97], v[50:65]
	ds_write_b128 v66, v[118:121] offset:46080
	ds_write_b128 v66, v[114:117] offset:50688
	global_load_dwordx4 v[118:121], v[82:83], off offset:384
	global_load_dwordx4 v[114:117], v[84:85], off offset:384
	v_mfma_f32_32x32x16_bf16 v[2:17], v[98:101], v[90:93], v[2:17]
	v_mfma_f32_32x32x16_bf16 v[18:33], v[98:101], v[94:97], v[18:33]
	s_setprio 0
	s_waitcnt lgkmcnt(0)
	s_barrier
	ds_read_b128 v[94:97], v68
	ds_read_b128 v[98:101], v68 offset:4608
	ds_read_b128 v[126:129], v1 offset:36864
	ds_read_b128 v[130:133], v1 offset:41472
	s_setprio 1
	ds_read_b128 v[86:89], v68 offset:32
	s_waitcnt lgkmcnt(2)
	v_mfma_f32_32x32x16_bf16 v[34:49], v[94:97], v[126:129], v[34:49]
	ds_read_b128 v[90:93], v1 offset:36896
	s_waitcnt lgkmcnt(2)
	v_mfma_f32_32x32x16_bf16 v[50:65], v[94:97], v[130:133], v[50:65]
	s_waitcnt vmcnt(7)
	ds_write_b128 v66, v[140:143] offset:18432
	s_waitcnt vmcnt(6)
	ds_write_b128 v66, v[102:105] offset:23040
	global_load_dwordx4 v[140:143], v[72:73], off offset:512
	global_load_dwordx4 v[102:105], v[70:71], off offset:512
	ds_read_b128 v[94:97], v1 offset:41504
	s_waitcnt lgkmcnt(3)
	v_mfma_f32_32x32x16_bf16 v[34:49], v[86:89], v[90:93], v[34:49]
	s_waitcnt lgkmcnt(0)
	v_mfma_f32_32x32x16_bf16 v[50:65], v[86:89], v[94:97], v[50:65]
	ds_read_b128 v[86:89], v68 offset:4640
	v_mfma_f32_32x32x16_bf16 v[2:17], v[98:101], v[126:129], v[2:17]
	v_mfma_f32_32x32x16_bf16 v[18:33], v[98:101], v[130:133], v[18:33]
	s_waitcnt vmcnt(7)
	ds_write_b128 v66, v[106:109] offset:27648
	s_waitcnt vmcnt(6)
	ds_write_b128 v66, v[110:113] offset:32256
	global_load_dwordx4 v[106:109], v[74:75], off offset:512
	global_load_dwordx4 v[110:113], v[76:77], off offset:512
	ds_read_b128 v[98:101], v68 offset:4704
	s_waitcnt lgkmcnt(3)
	v_mfma_f32_32x32x16_bf16 v[2:17], v[86:89], v[90:93], v[2:17]
	ds_read_b128 v[90:93], v1 offset:36928
	v_mfma_f32_32x32x16_bf16 v[18:33], v[86:89], v[94:97], v[18:33]
	ds_read_b128 v[86:89], v68 offset:64
	ds_read_b128 v[94:97], v1 offset:41536
	s_waitcnt lgkmcnt(1)
	v_mfma_f32_32x32x16_bf16 v[34:49], v[86:89], v[90:93], v[34:49]
	s_waitcnt lgkmcnt(0)
	v_mfma_f32_32x32x16_bf16 v[50:65], v[86:89], v[94:97], v[50:65]
	s_waitcnt vmcnt(7)
	ds_write_b128 v66, v[144:147] offset:55296
	s_waitcnt vmcnt(6)
	ds_write_b128 v66, v[122:125] offset:59904
	global_load_dwordx4 v[144:147], v[78:79], off offset:512
	global_load_dwordx4 v[122:125], v[80:81], off offset:512
	ds_read_b128 v[86:89], v68 offset:4672
	s_waitcnt lgkmcnt(0)
	v_mfma_f32_32x32x16_bf16 v[2:17], v[86:89], v[90:93], v[2:17]
	ds_read_b128 v[90:93], v1 offset:36960
	v_mfma_f32_32x32x16_bf16 v[18:33], v[86:89], v[94:97], v[18:33]
	ds_read_b128 v[86:89], v68 offset:96
	ds_read_b128 v[94:97], v1 offset:41568
	s_waitcnt lgkmcnt(1)
	v_mfma_f32_32x32x16_bf16 v[34:49], v[86:89], v[90:93], v[34:49]
	s_waitcnt lgkmcnt(0)
	v_mfma_f32_32x32x16_bf16 v[50:65], v[86:89], v[94:97], v[50:65]
	s_waitcnt vmcnt(7)
	ds_write_b128 v66, v[118:121] offset:64512
	s_waitcnt vmcnt(6)
	ds_write_b128 v69, v[114:117] offset:32256
	global_load_dwordx4 v[118:121], v[82:83], off offset:512
	global_load_dwordx4 v[114:117], v[84:85], off offset:512
	v_mfma_f32_32x32x16_bf16 v[2:17], v[98:101], v[90:93], v[2:17]
	v_mfma_f32_32x32x16_bf16 v[18:33], v[98:101], v[94:97], v[18:33]
	s_setprio 0
	s_waitcnt lgkmcnt(0)
	s_barrier
; #define MFMA(a, b, c) __builtin_amdgcn_mfma_f32_32x32x16_bf16((a), (b), (c), 0, 0, 0)
; template <int TM, int TN>
; DI void gemm_mainloop(const u16* __restrict__ A, long lda, const u16* __restrict__ Bt, long ldb, int K, char* smem,
;                       f32x16 (&acc)[TM][TN]) {
;     ...
;   for (int kt = 0; kt < nk; kt++) {
;     const int buf = kt & 1;
;     const u16* cA = sA + buf * BM * LD + (wm * 32 * TM + r) * LD + h * 8;
;     const u16* cB = sB + buf * BN * LD + (wn * 32 * TN + r) * LD + h * 8;
;     bf16x8 af[TM], bfr[TN];
; #pragma unroll
;     for (int tm = 0; tm < TM; tm++) af[tm] = *(const bf16x8*)(cA + tm * 32 * LD);
; #pragma unroll
;     for (int tn = 0; tn < TN; tn++) bfr[tn] = *(const bf16x8*)(cB + tn * 32 * LD);
;     if (kt + 1 < nk) GEMM_SSTORE(buf ^ 1)
;     __builtin_amdgcn_sched_barrier(0);
;     __builtin_amdgcn_s_setprio(1);
; #pragma unroll
;     for (int tm = 0; tm < TM; tm++)
; #pragma unroll
;       for (int tn = 0; tn < TN; tn++) acc[tm][tn] = MFMA(af[tm], bfr[tn], acc[tm][tn]);
; #pragma unroll
;     for (int tm = 0; tm < TM; tm++) af[tm] = *(const bf16x8*)(cA + tm * 32 * LD + 16);
; #pragma unroll
;     for (int tn = 0; tn < TN; tn++) bfr[tn] = *(const bf16x8*)(cB + tn * 32 * LD + 16);
; #pragma unroll
;     for (int tm = 0; tm < TM; tm++)
; #pragma unroll
;       for (int tn = 0; tn < TN; tn++) acc[tm][tn] = MFMA(af[tm], bfr[tn], acc[tm][tn]);
;     __builtin_amdgcn_sched_group_barrier(0x8, 4, 0);
;     if (kt + 2 < nk) GEMM_GLOAD((kt + 2) * 64)
; #pragma unroll
;     for (int ks = 2; ks < 4; ks++) {
; #pragma unroll
;       for (int tm = 0; tm < TM; tm++) af[tm] = *(const bf16x8*)(cA + tm * 32 * LD + ks * 16);
; #pragma unroll
;       for (int tn = 0; tn < TN; tn++) bfr[tn] = *(const bf16x8*)(cB + tn * 32 * LD + ks * 16);
; #pragma unroll
;       for (int tm = 0; tm < TM; tm++)
; #pragma unroll
;         for (int tn = 0; tn < TN; tn++) acc[tm][tn] = MFMA(af[tm], bfr[tn], acc[tm][tn]);
;     }
;     __builtin_amdgcn_s_setprio(0);
;     __syncthreads();
;   }
	ds_read_b128 v[94:97], v68 offset:18432
	ds_read_b128 v[98:101], v68 offset:23040
	ds_read_b128 v[126:129], v1 offset:55296
	ds_read_b128 v[130:133], v1 offset:59904
	s_setprio 1
	ds_read_b128 v[86:89], v68 offset:18464
	s_waitcnt lgkmcnt(2)
	v_mfma_f32_32x32x16_bf16 v[34:49], v[94:97], v[126:129], v[34:49]
	ds_read_b128 v[90:93], v1 offset:55328
	s_waitcnt lgkmcnt(2)
	v_mfma_f32_32x32x16_bf16 v[50:65], v[94:97], v[130:133], v[50:65]
	s_waitcnt vmcnt(7)
	ds_write_b128 v66, v[140:143]
	s_waitcnt vmcnt(6)
	ds_write_b128 v66, v[102:105] offset:4608
	global_load_dwordx4 v[140:143], v[72:73], off offset:640
	global_load_dwordx4 v[102:105], v[70:71], off offset:640
	ds_read_b128 v[94:97], v1 offset:59936
	s_waitcnt lgkmcnt(3)
	v_mfma_f32_32x32x16_bf16 v[34:49], v[86:89], v[90:93], v[34:49]
	s_waitcnt lgkmcnt(0)
	v_mfma_f32_32x32x16_bf16 v[50:65], v[86:89], v[94:97], v[50:65]
	ds_read_b128 v[86:89], v68 offset:23072
	v_mfma_f32_32x32x16_bf16 v[2:17], v[98:101], v[126:129], v[2:17]
	v_mfma_f32_32x32x16_bf16 v[18:33], v[98:101], v[130:133], v[18:33]
	s_waitcnt vmcnt(7)
	ds_write_b128 v66, v[106:109] offset:9216
	s_waitcnt vmcnt(6)
	ds_write_b128 v66, v[110:113] offset:13824
	global_load_dwordx4 v[106:109], v[74:75], off offset:640
	global_load_dwordx4 v[110:113], v[76:77], off offset:640
	ds_read_b128 v[98:101], v68 offset:23136
	s_waitcnt lgkmcnt(3)
	v_mfma_f32_32x32x16_bf16 v[2:17], v[86:89], v[90:93], v[2:17]
	ds_read_b128 v[90:93], v1 offset:55360
	v_mfma_f32_32x32x16_bf16 v[18:33], v[86:89], v[94:97], v[18:33]
	ds_read_b128 v[86:89], v68 offset:18496
	ds_read_b128 v[94:97], v1 offset:59968
	s_waitcnt lgkmcnt(1)
	v_mfma_f32_32x32x16_bf16 v[34:49], v[86:89], v[90:93], v[34:49]
	s_waitcnt lgkmcnt(0)
	v_mfma_f32_32x32x16_bf16 v[50:65], v[86:89], v[94:97], v[50:65]
	s_waitcnt vmcnt(7)
	ds_write_b128 v66, v[144:147] offset:36864
	s_waitcnt vmcnt(6)
	ds_write_b128 v66, v[122:125] offset:41472
	global_load_dwordx4 v[144:147], v[78:79], off offset:640
	global_load_dwordx4 v[122:125], v[80:81], off offset:640
	ds_read_b128 v[86:89], v68 offset:23104
	s_waitcnt lgkmcnt(0)
	v_mfma_f32_32x32x16_bf16 v[2:17], v[86:89], v[90:93], v[2:17]
	ds_read_b128 v[90:93], v1 offset:55392
	v_mfma_f32_32x32x16_bf16 v[18:33], v[86:89], v[94:97], v[18:33]
	ds_read_b128 v[86:89], v68 offset:18528
	ds_read_b128 v[94:97], v1 offset:60000
	s_waitcnt lgkmcnt(1)
	v_mfma_f32_32x32x16_bf16 v[34:49], v[86:89], v[90:93], v[34:49]
	s_waitcnt lgkmcnt(0)
	v_mfma_f32_32x32x16_bf16 v[50:65], v[86:89], v[94:97], v[50:65]
	s_waitcnt vmcnt(7)
	ds_write_b128 v66, v[118:121] offset:46080
	s_waitcnt vmcnt(6)
	ds_write_b128 v66, v[114:117] offset:50688
	global_load_dwordx4 v[118:121], v[82:83], off offset:640
	global_load_dwordx4 v[114:117], v[84:85], off offset:640
	v_mfma_f32_32x32x16_bf16 v[2:17], v[98:101], v[90:93], v[2:17]
	v_mfma_f32_32x32x16_bf16 v[18:33], v[98:101], v[94:97], v[18:33]
	s_setprio 0
	s_waitcnt lgkmcnt(0)
	s_barrier
	ds_read_b128 v[94:97], v68
	ds_read_b128 v[98:101], v68 offset:4608
	ds_read_b128 v[126:129], v1 offset:36864
	ds_read_b128 v[130:133], v1 offset:41472
	s_setprio 1
	ds_read_b128 v[86:89], v68 offset:32
	s_waitcnt lgkmcnt(2)
	v_mfma_f32_32x32x16_bf16 v[34:49], v[94:97], v[126:129], v[34:49]
	ds_read_b128 v[90:93], v1 offset:36896
	s_waitcnt lgkmcnt(2)
	v_mfma_f32_32x32x16_bf16 v[50:65], v[94:97], v[130:133], v[50:65]
	s_waitcnt vmcnt(7)
	ds_write_b128 v66, v[140:143] offset:18432
	s_waitcnt vmcnt(6)
	ds_write_b128 v66, v[102:105] offset:23040
	global_load_dwordx4 v[140:143], v[72:73], off offset:768
	global_load_dwordx4 v[102:105], v[70:71], off offset:768
	ds_read_b128 v[94:97], v1 offset:41504
	s_waitcnt lgkmcnt(3)
	v_mfma_f32_32x32x16_bf16 v[34:49], v[86:89], v[90:93], v[34:49]
	s_waitcnt lgkmcnt(0)
	v_mfma_f32_32x32x16_bf16 v[50:65], v[86:89], v[94:97], v[50:65]
	ds_read_b128 v[86:89], v68 offset:4640
	v_mfma_f32_32x32x16_bf16 v[2:17], v[98:101], v[126:129], v[2:17]
	v_mfma_f32_32x32x16_bf16 v[18:33], v[98:101], v[130:133], v[18:33]
	s_waitcnt vmcnt(7)
	ds_write_b128 v66, v[106:109] offset:27648
	s_waitcnt vmcnt(6)
	ds_write_b128 v66, v[110:113] offset:32256
	global_load_dwordx4 v[106:109], v[74:75], off offset:768
	global_load_dwordx4 v[110:113], v[76:77], off offset:768
	ds_read_b128 v[98:101], v68 offset:4704
	s_waitcnt lgkmcnt(3)
	v_mfma_f32_32x32x16_bf16 v[2:17], v[86:89], v[90:93], v[2:17]
	ds_read_b128 v[90:93], v1 offset:36928
	v_mfma_f32_32x32x16_bf16 v[18:33], v[86:89], v[94:97], v[18:33]
	ds_read_b128 v[86:89], v68 offset:64
	ds_read_b128 v[94:97], v1 offset:41536
	s_waitcnt lgkmcnt(1)
	v_mfma_f32_32x32x16_bf16 v[34:49], v[86:89], v[90:93], v[34:49]
	s_waitcnt lgkmcnt(0)
	v_mfma_f32_32x32x16_bf16 v[50:65], v[86:89], v[94:97], v[50:65]
	s_waitcnt vmcnt(7)
	ds_write_b128 v66, v[144:147] offset:55296
	s_waitcnt vmcnt(6)
	ds_write_b128 v66, v[122:125] offset:59904
	global_load_dwordx4 v[144:147], v[78:79], off offset:768
	global_load_dwordx4 v[122:125], v[80:81], off offset:768
	ds_read_b128 v[86:89], v68 offset:4672
	s_waitcnt lgkmcnt(0)
	v_mfma_f32_32x32x16_bf16 v[2:17], v[86:89], v[90:93], v[2:17]
	ds_read_b128 v[90:93], v1 offset:36960
	v_mfma_f32_32x32x16_bf16 v[18:33], v[86:89], v[94:97], v[18:33]
	ds_read_b128 v[86:89], v68 offset:96
	ds_read_b128 v[94:97], v1 offset:41568
	s_waitcnt lgkmcnt(1)
	v_mfma_f32_32x32x16_bf16 v[34:49], v[86:89], v[90:93], v[34:49]
	s_waitcnt lgkmcnt(0)
	v_mfma_f32_32x32x16_bf16 v[50:65], v[86:89], v[94:97], v[50:65]
	s_waitcnt vmcnt(7)
	ds_write_b128 v66, v[118:121] offset:64512
	s_waitcnt vmcnt(6)
	ds_write_b128 v69, v[114:117] offset:32256
	global_load_dwordx4 v[118:121], v[82:83], off offset:768
	global_load_dwordx4 v[114:117], v[84:85], off offset:768
	v_mfma_f32_32x32x16_bf16 v[2:17], v[98:101], v[90:93], v[2:17]
	v_mfma_f32_32x32x16_bf16 v[18:33], v[98:101], v[94:97], v[18:33]
	s_setprio 0
	s_waitcnt lgkmcnt(0)
	s_barrier
; #define MFMA(a, b, c) __builtin_amdgcn_mfma_f32_32x32x16_bf16((a), (b), (c), 0, 0, 0)
; template <int TM, int TN>
; DI void gemm_mainloop(const u16* __restrict__ A, long lda, const u16* __restrict__ Bt, long ldb, int K, char* smem,
;                       f32x16 (&acc)[TM][TN]) {
;     ...
;   for (int kt = 0; kt < nk; kt++) {
;     const int buf = kt & 1;
;     const u16* cA = sA + buf * BM * LD + (wm * 32 * TM + r) * LD + h * 8;
;     const u16* cB = sB + buf * BN * LD + (wn * 32 * TN + r) * LD + h * 8;
;     bf16x8 af[TM], bfr[TN];
; #pragma unroll
;     for (int tm = 0; tm < TM; tm++) af[tm] = *(const bf16x8*)(cA + tm * 32 * LD);
; #pragma unroll
;     for (int tn = 0; tn < TN; tn++) bfr[tn] = *(const bf16x8*)(cB + tn * 32 * LD);
;     if (kt + 1 < nk) GEMM_SSTORE(buf ^ 1)
;     __builtin_amdgcn_sched_barrier(0);
;     __builtin_amdgcn_s_setprio(1);
; #pragma unroll
;     for (int tm = 0; tm < TM; tm++)
; #pragma unroll
;       for (int tn = 0; tn < TN; tn++) acc[tm][tn] = MFMA(af[tm], bfr[tn], acc[tm][tn]);
; #pragma unroll
;     for (int tm = 0; tm < TM; tm++) af[tm] = *(const bf16x8*)(cA + tm * 32 * LD + 16);
; #pragma unroll
;     for (int tn = 0; tn < TN; tn++) bfr[tn] = *(const bf16x8*)(cB + tn * 32 * LD + 16);
; #pragma unroll
;     for (int tm = 0; tm < TM; tm++)
; #pragma unroll
;       for (int tn = 0; tn < TN; tn++) acc[tm][tn] = MFMA(af[tm], bfr[tn], acc[tm][tn]);
;     __builtin_amdgcn_sched_group_barrier(0x8, 4, 0);
;     if (kt + 2 < nk) GEMM_GLOAD((kt + 2) * 64)
; #pragma unroll
;     for (int ks = 2; ks < 4; ks++) {
; #pragma unroll
;       for (int tm = 0; tm < TM; tm++) af[tm] = *(const bf16x8*)(cA + tm * 32 * LD + ks * 16);
; #pragma unroll
;       for (int tn = 0; tn < TN; tn++) bfr[tn] = *(const bf16x8*)(cB + tn * 32 * LD + ks * 16);
; #pragma unroll
;       for (int tm = 0; tm < TM; tm++)
; #pragma unroll
;         for (int tn = 0; tn < TN; tn++) acc[tm][tn] = MFMA(af[tm], bfr[tn], acc[tm][tn]);
;     }
;     __builtin_amdgcn_s_setprio(0);
;     __syncthreads();
;   }
	ds_read_b128 v[94:97], v68 offset:18432
	ds_read_b128 v[98:101], v68 offset:23040
	ds_read_b128 v[126:129], v1 offset:55296
	ds_read_b128 v[130:133], v1 offset:59904
	s_setprio 1
	ds_read_b128 v[86:89], v68 offset:18464
	s_waitcnt lgkmcnt(2)
	v_mfma_f32_32x32x16_bf16 v[34:49], v[94:97], v[126:129], v[34:49]
	ds_read_b128 v[90:93], v1 offset:55328
	s_waitcnt lgkmcnt(2)
	v_mfma_f32_32x32x16_bf16 v[50:65], v[94:97], v[130:133], v[50:65]
	s_waitcnt vmcnt(7)
	ds_write_b128 v66, v[140:143]
	s_waitcnt vmcnt(6)
	ds_write_b128 v66, v[102:105] offset:4608
	global_load_dwordx4 v[140:143], v[72:73], off offset:896
	global_load_dwordx4 v[102:105], v[70:71], off offset:896
	ds_read_b128 v[94:97], v1 offset:59936
	s_waitcnt lgkmcnt(3)
	v_mfma_f32_32x32x16_bf16 v[34:49], v[86:89], v[90:93], v[34:49]
	s_waitcnt lgkmcnt(0)
	v_mfma_f32_32x32x16_bf16 v[50:65], v[86:89], v[94:97], v[50:65]
	ds_read_b128 v[86:89], v68 offset:23072
	v_mfma_f32_32x32x16_bf16 v[2:17], v[98:101], v[126:129], v[2:17]
	v_mfma_f32_32x32x16_bf16 v[18:33], v[98:101], v[130:133], v[18:33]
	s_waitcnt vmcnt(7)
	ds_write_b128 v66, v[106:109] offset:9216
	s_waitcnt vmcnt(6)
	ds_write_b128 v66, v[110:113] offset:13824
	global_load_dwordx4 v[106:109], v[74:75], off offset:896
	global_load_dwordx4 v[110:113], v[76:77], off offset:896
	ds_read_b128 v[98:101], v68 offset:23136
	s_waitcnt lgkmcnt(3)
	v_mfma_f32_32x32x16_bf16 v[2:17], v[86:89], v[90:93], v[2:17]
	ds_read_b128 v[90:93], v1 offset:55360
	v_mfma_f32_32x32x16_bf16 v[18:33], v[86:89], v[94:97], v[18:33]
	ds_read_b128 v[86:89], v68 offset:18496
	ds_read_b128 v[94:97], v1 offset:59968
	s_waitcnt lgkmcnt(1)
	v_mfma_f32_32x32x16_bf16 v[34:49], v[86:89], v[90:93], v[34:49]
	s_waitcnt lgkmcnt(0)
	v_mfma_f32_32x32x16_bf16 v[50:65], v[86:89], v[94:97], v[50:65]
	s_waitcnt vmcnt(7)
	ds_write_b128 v66, v[144:147] offset:36864
	s_waitcnt vmcnt(6)
	ds_write_b128 v66, v[122:125] offset:41472
	global_load_dwordx4 v[144:147], v[78:79], off offset:896
	global_load_dwordx4 v[122:125], v[80:81], off offset:896
	ds_read_b128 v[86:89], v68 offset:23104
	s_waitcnt lgkmcnt(0)
	v_mfma_f32_32x32x16_bf16 v[2:17], v[86:89], v[90:93], v[2:17]
	ds_read_b128 v[90:93], v1 offset:55392
	v_mfma_f32_32x32x16_bf16 v[18:33], v[86:89], v[94:97], v[18:33]
	ds_read_b128 v[86:89], v68 offset:18528
	ds_read_b128 v[94:97], v1 offset:60000
	s_waitcnt lgkmcnt(1)
	v_mfma_f32_32x32x16_bf16 v[34:49], v[86:89], v[90:93], v[34:49]
	s_waitcnt lgkmcnt(0)
	v_mfma_f32_32x32x16_bf16 v[50:65], v[86:89], v[94:97], v[50:65]
	s_waitcnt vmcnt(7)
	ds_write_b128 v66, v[118:121] offset:46080
	s_waitcnt vmcnt(6)
	ds_write_b128 v66, v[114:117] offset:50688
	global_load_dwordx4 v[118:121], v[82:83], off offset:896
	global_load_dwordx4 v[114:117], v[84:85], off offset:896
	v_mfma_f32_32x32x16_bf16 v[2:17], v[98:101], v[90:93], v[2:17]
	v_mfma_f32_32x32x16_bf16 v[18:33], v[98:101], v[94:97], v[18:33]
	s_setprio 0
	s_waitcnt lgkmcnt(0)
	s_barrier
	ds_read_b128 v[94:97], v68
	ds_read_b128 v[98:101], v68 offset:4608
	ds_read_b128 v[126:129], v1 offset:36864
	ds_read_b128 v[130:133], v1 offset:41472
	s_setprio 1
	ds_read_b128 v[86:89], v68 offset:32
	s_waitcnt lgkmcnt(2)
	v_mfma_f32_32x32x16_bf16 v[34:49], v[94:97], v[126:129], v[34:49]
	ds_read_b128 v[90:93], v1 offset:36896
	s_waitcnt lgkmcnt(2)
	v_mfma_f32_32x32x16_bf16 v[50:65], v[94:97], v[130:133], v[50:65]
	s_waitcnt vmcnt(7)
	ds_write_b128 v66, v[140:143] offset:18432
	s_waitcnt vmcnt(6)
	ds_write_b128 v66, v[102:105] offset:23040
	global_load_dwordx4 v[140:143], v[72:73], off offset:1024
	global_load_dwordx4 v[102:105], v[70:71], off offset:1024
	ds_read_b128 v[94:97], v1 offset:41504
	s_waitcnt lgkmcnt(3)
	v_mfma_f32_32x32x16_bf16 v[34:49], v[86:89], v[90:93], v[34:49]
	s_waitcnt lgkmcnt(0)
	v_mfma_f32_32x32x16_bf16 v[50:65], v[86:89], v[94:97], v[50:65]
	ds_read_b128 v[86:89], v68 offset:4640
	v_mfma_f32_32x32x16_bf16 v[2:17], v[98:101], v[126:129], v[2:17]
	v_mfma_f32_32x32x16_bf16 v[18:33], v[98:101], v[130:133], v[18:33]
	s_waitcnt vmcnt(7)
	ds_write_b128 v66, v[106:109] offset:27648
	s_waitcnt vmcnt(6)
	ds_write_b128 v66, v[110:113] offset:32256
	global_load_dwordx4 v[106:109], v[74:75], off offset:1024
	global_load_dwordx4 v[110:113], v[76:77], off offset:1024
	ds_read_b128 v[98:101], v68 offset:4704
	s_waitcnt lgkmcnt(3)
	v_mfma_f32_32x32x16_bf16 v[2:17], v[86:89], v[90:93], v[2:17]
	ds_read_b128 v[90:93], v1 offset:36928
	v_mfma_f32_32x32x16_bf16 v[18:33], v[86:89], v[94:97], v[18:33]
	ds_read_b128 v[86:89], v68 offset:64
	ds_read_b128 v[94:97], v1 offset:41536
	s_waitcnt lgkmcnt(1)
	v_mfma_f32_32x32x16_bf16 v[34:49], v[86:89], v[90:93], v[34:49]
	s_waitcnt lgkmcnt(0)
	v_mfma_f32_32x32x16_bf16 v[50:65], v[86:89], v[94:97], v[50:65]
	s_waitcnt vmcnt(7)
	ds_write_b128 v66, v[144:147] offset:55296
	s_waitcnt vmcnt(6)
	ds_write_b128 v66, v[122:125] offset:59904
	global_load_dwordx4 v[144:147], v[78:79], off offset:1024
	global_load_dwordx4 v[122:125], v[80:81], off offset:1024
	ds_read_b128 v[86:89], v68 offset:4672
	s_waitcnt lgkmcnt(0)
	v_mfma_f32_32x32x16_bf16 v[2:17], v[86:89], v[90:93], v[2:17]
	ds_read_b128 v[90:93], v1 offset:36960
	v_mfma_f32_32x32x16_bf16 v[18:33], v[86:89], v[94:97], v[18:33]
	ds_read_b128 v[86:89], v68 offset:96
	ds_read_b128 v[94:97], v1 offset:41568
	s_waitcnt lgkmcnt(1)
	v_mfma_f32_32x32x16_bf16 v[34:49], v[86:89], v[90:93], v[34:49]
	s_waitcnt lgkmcnt(0)
	v_mfma_f32_32x32x16_bf16 v[50:65], v[86:89], v[94:97], v[50:65]
	s_waitcnt vmcnt(7)
	ds_write_b128 v66, v[118:121] offset:64512
	s_waitcnt vmcnt(6)
	ds_write_b128 v69, v[114:117] offset:32256
	global_load_dwordx4 v[118:121], v[82:83], off offset:1024
	global_load_dwordx4 v[114:117], v[84:85], off offset:1024
	v_mfma_f32_32x32x16_bf16 v[2:17], v[98:101], v[90:93], v[2:17]
	v_mfma_f32_32x32x16_bf16 v[18:33], v[98:101], v[94:97], v[18:33]
	s_setprio 0
	s_waitcnt lgkmcnt(0)
	s_barrier
; #define MFMA(a, b, c) __builtin_amdgcn_mfma_f32_32x32x16_bf16((a), (b), (c), 0, 0, 0)
; template <int TM, int TN>
; DI void gemm_mainloop(const u16* __restrict__ A, long lda, const u16* __restrict__ Bt, long ldb, int K, char* smem,
;                       f32x16 (&acc)[TM][TN]) {
;     ...
;   for (int kt = 0; kt < nk; kt++) {
;     const int buf = kt & 1;
;     const u16* cA = sA + buf * BM * LD + (wm * 32 * TM + r) * LD + h * 8;
;     const u16* cB = sB + buf * BN * LD + (wn * 32 * TN + r) * LD + h * 8;
;     bf16x8 af[TM], bfr[TN];
; #pragma unroll
;     for (int tm = 0; tm < TM; tm++) af[tm] = *(const bf16x8*)(cA + tm * 32 * LD);
; #pragma unroll
;     for (int tn = 0; tn < TN; tn++) bfr[tn] = *(const bf16x8*)(cB + tn * 32 * LD);
;     if (kt + 1 < nk) GEMM_SSTORE(buf ^ 1)
;     __builtin_amdgcn_sched_barrier(0);
;     __builtin_amdgcn_s_setprio(1);
; #pragma unroll
;     for (int tm = 0; tm < TM; tm++)
; #pragma unroll
;       for (int tn = 0; tn < TN; tn++) acc[tm][tn] = MFMA(af[tm], bfr[tn], acc[tm][tn]);
; #pragma unroll
;     for (int tm = 0; tm < TM; tm++) af[tm] = *(const bf16x8*)(cA + tm * 32 * LD + 16);
; #pragma unroll
;     for (int tn = 0; tn < TN; tn++) bfr[tn] = *(const bf16x8*)(cB + tn * 32 * LD + 16);
; #pragma unroll
;     for (int tm = 0; tm < TM; tm++)
; #pragma unroll
;       for (int tn = 0; tn < TN; tn++) acc[tm][tn] = MFMA(af[tm], bfr[tn], acc[tm][tn]);
;     __builtin_amdgcn_sched_group_barrier(0x8, 4, 0);
;     if (kt + 2 < nk) GEMM_GLOAD((kt + 2) * 64)
; #pragma unroll
;     for (int ks = 2; ks < 4; ks++) {
; #pragma unroll
;       for (int tm = 0; tm < TM; tm++) af[tm] = *(const bf16x8*)(cA + tm * 32 * LD + ks * 16);
; #pragma unroll
;       for (int tn = 0; tn < TN; tn++) bfr[tn] = *(const bf16x8*)(cB + tn * 32 * LD + ks * 16);
; #pragma unroll
;       for (int tm = 0; tm < TM; tm++)
; #pragma unroll
;         for (int tn = 0; tn < TN; tn++) acc[tm][tn] = MFMA(af[tm], bfr[tn], acc[tm][tn]);
;     }
;     __builtin_amdgcn_s_setprio(0);
;     __syncthreads();
;   }
	ds_read_b128 v[94:97], v68 offset:18432
	ds_read_b128 v[98:101], v68 offset:23040
	ds_read_b128 v[126:129], v1 offset:55296
	ds_read_b128 v[130:133], v1 offset:59904
	s_setprio 1
	ds_read_b128 v[86:89], v68 offset:18464
	s_waitcnt lgkmcnt(2)
	v_mfma_f32_32x32x16_bf16 v[34:49], v[94:97], v[126:129], v[34:49]
	ds_read_b128 v[90:93], v1 offset:55328
	s_waitcnt lgkmcnt(2)
	v_mfma_f32_32x32x16_bf16 v[50:65], v[94:97], v[130:133], v[50:65]
	s_waitcnt vmcnt(7)
	ds_write_b128 v66, v[140:143]
	s_waitcnt vmcnt(6)
	ds_write_b128 v66, v[102:105] offset:4608
	global_load_dwordx4 v[140:143], v[72:73], off offset:1152
	global_load_dwordx4 v[102:105], v[70:71], off offset:1152
	ds_read_b128 v[94:97], v1 offset:59936
	s_waitcnt lgkmcnt(3)
	v_mfma_f32_32x32x16_bf16 v[34:49], v[86:89], v[90:93], v[34:49]
	s_waitcnt lgkmcnt(0)
	v_mfma_f32_32x32x16_bf16 v[50:65], v[86:89], v[94:97], v[50:65]
	ds_read_b128 v[86:89], v68 offset:23072
	v_mfma_f32_32x32x16_bf16 v[2:17], v[98:101], v[126:129], v[2:17]
	v_mfma_f32_32x32x16_bf16 v[18:33], v[98:101], v[130:133], v[18:33]
	s_waitcnt vmcnt(7)
	ds_write_b128 v66, v[106:109] offset:9216
	s_waitcnt vmcnt(6)
	ds_write_b128 v66, v[110:113] offset:13824
	global_load_dwordx4 v[106:109], v[74:75], off offset:1152
	global_load_dwordx4 v[110:113], v[76:77], off offset:1152
	ds_read_b128 v[98:101], v68 offset:23136
	s_waitcnt lgkmcnt(3)
	v_mfma_f32_32x32x16_bf16 v[2:17], v[86:89], v[90:93], v[2:17]
	ds_read_b128 v[90:93], v1 offset:55360
	v_mfma_f32_32x32x16_bf16 v[18:33], v[86:89], v[94:97], v[18:33]
	ds_read_b128 v[86:89], v68 offset:18496
	ds_read_b128 v[94:97], v1 offset:59968
	s_waitcnt lgkmcnt(1)
	v_mfma_f32_32x32x16_bf16 v[34:49], v[86:89], v[90:93], v[34:49]
	s_waitcnt lgkmcnt(0)
	v_mfma_f32_32x32x16_bf16 v[50:65], v[86:89], v[94:97], v[50:65]
	s_waitcnt vmcnt(7)
	ds_write_b128 v66, v[144:147] offset:36864
	s_waitcnt vmcnt(6)
	ds_write_b128 v66, v[122:125] offset:41472
	global_load_dwordx4 v[144:147], v[78:79], off offset:1152
	global_load_dwordx4 v[122:125], v[80:81], off offset:1152
	ds_read_b128 v[86:89], v68 offset:23104
	s_waitcnt lgkmcnt(0)
	v_mfma_f32_32x32x16_bf16 v[2:17], v[86:89], v[90:93], v[2:17]
	ds_read_b128 v[90:93], v1 offset:55392
	v_mfma_f32_32x32x16_bf16 v[18:33], v[86:89], v[94:97], v[18:33]
	ds_read_b128 v[86:89], v68 offset:18528
	ds_read_b128 v[94:97], v1 offset:60000
	s_waitcnt lgkmcnt(1)
	v_mfma_f32_32x32x16_bf16 v[34:49], v[86:89], v[90:93], v[34:49]
	s_waitcnt lgkmcnt(0)
	v_mfma_f32_32x32x16_bf16 v[50:65], v[86:89], v[94:97], v[50:65]
	s_waitcnt vmcnt(7)
	ds_write_b128 v66, v[118:121] offset:46080
	s_waitcnt vmcnt(6)
	ds_write_b128 v66, v[114:117] offset:50688
	global_load_dwordx4 v[118:121], v[82:83], off offset:1152
	global_load_dwordx4 v[114:117], v[84:85], off offset:1152
	v_mfma_f32_32x32x16_bf16 v[2:17], v[98:101], v[90:93], v[2:17]
	v_mfma_f32_32x32x16_bf16 v[18:33], v[98:101], v[94:97], v[18:33]
	s_setprio 0
	s_waitcnt lgkmcnt(0)
	s_barrier
	ds_read_b128 v[94:97], v68
	ds_read_b128 v[98:101], v68 offset:4608
	ds_read_b128 v[126:129], v1 offset:36864
	ds_read_b128 v[130:133], v1 offset:41472
	s_setprio 1
	ds_read_b128 v[86:89], v68 offset:32
	s_waitcnt lgkmcnt(2)
	v_mfma_f32_32x32x16_bf16 v[34:49], v[94:97], v[126:129], v[34:49]
	ds_read_b128 v[90:93], v1 offset:36896
	s_waitcnt lgkmcnt(2)
	v_mfma_f32_32x32x16_bf16 v[50:65], v[94:97], v[130:133], v[50:65]
	s_waitcnt vmcnt(7)
	ds_write_b128 v66, v[140:143] offset:18432
	s_waitcnt vmcnt(6)
	ds_write_b128 v66, v[102:105] offset:23040
	global_load_dwordx4 v[140:143], v[72:73], off offset:1280
	global_load_dwordx4 v[102:105], v[70:71], off offset:1280
	ds_read_b128 v[94:97], v1 offset:41504
	s_waitcnt lgkmcnt(3)
	v_mfma_f32_32x32x16_bf16 v[34:49], v[86:89], v[90:93], v[34:49]
	s_waitcnt lgkmcnt(0)
	v_mfma_f32_32x32x16_bf16 v[50:65], v[86:89], v[94:97], v[50:65]
	ds_read_b128 v[86:89], v68 offset:4640
	v_mfma_f32_32x32x16_bf16 v[2:17], v[98:101], v[126:129], v[2:17]
	v_mfma_f32_32x32x16_bf16 v[18:33], v[98:101], v[130:133], v[18:33]
	s_waitcnt vmcnt(7)
	ds_write_b128 v66, v[106:109] offset:27648
	s_waitcnt vmcnt(6)
	ds_write_b128 v66, v[110:113] offset:32256
	global_load_dwordx4 v[106:109], v[74:75], off offset:1280
	global_load_dwordx4 v[110:113], v[76:77], off offset:1280
	ds_read_b128 v[98:101], v68 offset:4704
	s_waitcnt lgkmcnt(3)
	v_mfma_f32_32x32x16_bf16 v[2:17], v[86:89], v[90:93], v[2:17]
	ds_read_b128 v[90:93], v1 offset:36928
	v_mfma_f32_32x32x16_bf16 v[18:33], v[86:89], v[94:97], v[18:33]
	ds_read_b128 v[86:89], v68 offset:64
	ds_read_b128 v[94:97], v1 offset:41536
	s_waitcnt lgkmcnt(1)
	v_mfma_f32_32x32x16_bf16 v[34:49], v[86:89], v[90:93], v[34:49]
	s_waitcnt lgkmcnt(0)
	v_mfma_f32_32x32x16_bf16 v[50:65], v[86:89], v[94:97], v[50:65]
	s_waitcnt vmcnt(7)
	ds_write_b128 v66, v[144:147] offset:55296
	s_waitcnt vmcnt(6)
	ds_write_b128 v66, v[122:125] offset:59904
	global_load_dwordx4 v[144:147], v[78:79], off offset:1280
	global_load_dwordx4 v[122:125], v[80:81], off offset:1280
	ds_read_b128 v[86:89], v68 offset:4672
	s_waitcnt lgkmcnt(0)
	v_mfma_f32_32x32x16_bf16 v[2:17], v[86:89], v[90:93], v[2:17]
	ds_read_b128 v[90:93], v1 offset:36960
	v_mfma_f32_32x32x16_bf16 v[18:33], v[86:89], v[94:97], v[18:33]
	ds_read_b128 v[86:89], v68 offset:96
	ds_read_b128 v[94:97], v1 offset:41568
	s_waitcnt lgkmcnt(1)
	v_mfma_f32_32x32x16_bf16 v[34:49], v[86:89], v[90:93], v[34:49]
	s_waitcnt lgkmcnt(0)
	v_mfma_f32_32x32x16_bf16 v[50:65], v[86:89], v[94:97], v[50:65]
	s_waitcnt vmcnt(7)
	ds_write_b128 v66, v[118:121] offset:64512
	s_waitcnt vmcnt(6)
	ds_write_b128 v69, v[114:117] offset:32256
	global_load_dwordx4 v[118:121], v[82:83], off offset:1280
	global_load_dwordx4 v[114:117], v[84:85], off offset:1280
	v_mfma_f32_32x32x16_bf16 v[2:17], v[98:101], v[90:93], v[2:17]
	v_mfma_f32_32x32x16_bf16 v[18:33], v[98:101], v[94:97], v[18:33]
	s_setprio 0
	s_waitcnt lgkmcnt(0)
	s_barrier
; #define MFMA(a, b, c) __builtin_amdgcn_mfma_f32_32x32x16_bf16((a), (b), (c), 0, 0, 0)
; template <int TM, int TN>
; DI void gemm_mainloop(const u16* __restrict__ A, long lda, const u16* __restrict__ Bt, long ldb, int K, char* smem,
;                       f32x16 (&acc)[TM][TN]) {
;     ...
;   for (int kt = 0; kt < nk; kt++) {
;     const int buf = kt & 1;
;     const u16* cA = sA + buf * BM * LD + (wm * 32 * TM + r) * LD + h * 8;
;     const u16* cB = sB + buf * BN * LD + (wn * 32 * TN + r) * LD + h * 8;
;     bf16x8 af[TM], bfr[TN];
; #pragma unroll
;     for (int tm = 0; tm < TM; tm++) af[tm] = *(const bf16x8*)(cA + tm * 32 * LD);
; #pragma unroll
;     for (int tn = 0; tn < TN; tn++) bfr[tn] = *(const bf16x8*)(cB + tn * 32 * LD);
;     if (kt + 1 < nk) GEMM_SSTORE(buf ^ 1)
;     __builtin_amdgcn_sched_barrier(0);
;     __builtin_amdgcn_s_setprio(1);
; #pragma unroll
;     for (int tm = 0; tm < TM; tm++)
; #pragma unroll
;       for (int tn = 0; tn < TN; tn++) acc[tm][tn] = MFMA(af[tm], bfr[tn], acc[tm][tn]);
; #pragma unroll
;     for (int tm = 0; tm < TM; tm++) af[tm] = *(const bf16x8*)(cA + tm * 32 * LD + 16);
; #pragma unroll
;     for (int tn = 0; tn < TN; tn++) bfr[tn] = *(const bf16x8*)(cB + tn * 32 * LD + 16);
; #pragma unroll
;     for (int tm = 0; tm < TM; tm++)
; #pragma unroll
;       for (int tn = 0; tn < TN; tn++) acc[tm][tn] = MFMA(af[tm], bfr[tn], acc[tm][tn]);
;     __builtin_amdgcn_sched_group_barrier(0x8, 4, 0);
;     if (kt + 2 < nk) GEMM_GLOAD((kt + 2) * 64)
; #pragma unroll
;     for (int ks = 2; ks < 4; ks++) {
; #pragma unroll
;       for (int tm = 0; tm < TM; tm++) af[tm] = *(const bf16x8*)(cA + tm * 32 * LD + ks * 16);
; #pragma unroll
;       for (int tn = 0; tn < TN; tn++) bfr[tn] = *(const bf16x8*)(cB + tn * 32 * LD + ks * 16);
; #pragma unroll
;       for (int tm = 0; tm < TM; tm++)
; #pragma unroll
;         for (int tn = 0; tn < TN; tn++) acc[tm][tn] = MFMA(af[tm], bfr[tn], acc[tm][tn]);
;     }
;     __builtin_amdgcn_s_setprio(0);
;     __syncthreads();
;   }
	ds_read_b128 v[94:97], v68 offset:18432
	ds_read_b128 v[98:101], v68 offset:23040
	ds_read_b128 v[126:129], v1 offset:55296
	ds_read_b128 v[130:133], v1 offset:59904
	s_setprio 1
	ds_read_b128 v[86:89], v68 offset:18464
	s_waitcnt lgkmcnt(2)
	v_mfma_f32_32x32x16_bf16 v[34:49], v[94:97], v[126:129], v[34:49]
	ds_read_b128 v[90:93], v1 offset:55328
	s_waitcnt lgkmcnt(2)
	v_mfma_f32_32x32x16_bf16 v[50:65], v[94:97], v[130:133], v[50:65]
	s_waitcnt vmcnt(7)
	ds_write_b128 v66, v[140:143]
	s_waitcnt vmcnt(6)
	ds_write_b128 v66, v[102:105] offset:4608
	global_load_dwordx4 v[140:143], v[72:73], off offset:1408
	global_load_dwordx4 v[102:105], v[70:71], off offset:1408
	ds_read_b128 v[94:97], v1 offset:59936
	s_waitcnt lgkmcnt(3)
	v_mfma_f32_32x32x16_bf16 v[34:49], v[86:89], v[90:93], v[34:49]
	s_waitcnt lgkmcnt(0)
	v_mfma_f32_32x32x16_bf16 v[50:65], v[86:89], v[94:97], v[50:65]
	ds_read_b128 v[86:89], v68 offset:23072
	v_mfma_f32_32x32x16_bf16 v[2:17], v[98:101], v[126:129], v[2:17]
	v_mfma_f32_32x32x16_bf16 v[18:33], v[98:101], v[130:133], v[18:33]
	s_waitcnt vmcnt(7)
	ds_write_b128 v66, v[106:109] offset:9216
	s_waitcnt vmcnt(6)
	ds_write_b128 v66, v[110:113] offset:13824
	global_load_dwordx4 v[106:109], v[74:75], off offset:1408
	global_load_dwordx4 v[110:113], v[76:77], off offset:1408
	ds_read_b128 v[98:101], v68 offset:23136
	s_waitcnt lgkmcnt(3)
	v_mfma_f32_32x32x16_bf16 v[2:17], v[86:89], v[90:93], v[2:17]
	ds_read_b128 v[90:93], v1 offset:55360
	v_mfma_f32_32x32x16_bf16 v[18:33], v[86:89], v[94:97], v[18:33]
	ds_read_b128 v[86:89], v68 offset:18496
	ds_read_b128 v[94:97], v1 offset:59968
	s_waitcnt lgkmcnt(1)
	v_mfma_f32_32x32x16_bf16 v[34:49], v[86:89], v[90:93], v[34:49]
	s_waitcnt lgkmcnt(0)
	v_mfma_f32_32x32x16_bf16 v[50:65], v[86:89], v[94:97], v[50:65]
	s_waitcnt vmcnt(7)
	ds_write_b128 v66, v[144:147] offset:36864
	s_waitcnt vmcnt(6)
	ds_write_b128 v66, v[122:125] offset:41472
	global_load_dwordx4 v[144:147], v[78:79], off offset:1408
	global_load_dwordx4 v[122:125], v[80:81], off offset:1408
	ds_read_b128 v[86:89], v68 offset:23104
	s_waitcnt lgkmcnt(0)
	v_mfma_f32_32x32x16_bf16 v[2:17], v[86:89], v[90:93], v[2:17]
	ds_read_b128 v[90:93], v1 offset:55392
	v_mfma_f32_32x32x16_bf16 v[18:33], v[86:89], v[94:97], v[18:33]
	ds_read_b128 v[86:89], v68 offset:18528
	ds_read_b128 v[94:97], v1 offset:60000
	s_waitcnt lgkmcnt(1)
	v_mfma_f32_32x32x16_bf16 v[34:49], v[86:89], v[90:93], v[34:49]
	s_waitcnt lgkmcnt(0)
	v_mfma_f32_32x32x16_bf16 v[50:65], v[86:89], v[94:97], v[50:65]
	s_waitcnt vmcnt(7)
	ds_write_b128 v66, v[118:121] offset:46080
	s_waitcnt vmcnt(6)
	ds_write_b128 v66, v[114:117] offset:50688
	global_load_dwordx4 v[118:121], v[82:83], off offset:1408
	global_load_dwordx4 v[114:117], v[84:85], off offset:1408
	v_mfma_f32_32x32x16_bf16 v[2:17], v[98:101], v[90:93], v[2:17]
	v_mfma_f32_32x32x16_bf16 v[18:33], v[98:101], v[94:97], v[18:33]
	s_setprio 0
	s_waitcnt lgkmcnt(0)
	s_barrier
	ds_read_b128 v[94:97], v68
	ds_read_b128 v[98:101], v68 offset:4608
	ds_read_b128 v[126:129], v1 offset:36864
	ds_read_b128 v[130:133], v1 offset:41472
	s_setprio 1
	ds_read_b128 v[86:89], v68 offset:32
	s_waitcnt lgkmcnt(2)
	v_mfma_f32_32x32x16_bf16 v[34:49], v[94:97], v[126:129], v[34:49]
	ds_read_b128 v[90:93], v1 offset:36896
	s_waitcnt lgkmcnt(2)
	v_mfma_f32_32x32x16_bf16 v[50:65], v[94:97], v[130:133], v[50:65]
	s_waitcnt vmcnt(7)
	ds_write_b128 v66, v[140:143] offset:18432
	s_waitcnt vmcnt(6)
	ds_write_b128 v66, v[102:105] offset:23040
	global_load_dwordx4 v[140:143], v[72:73], off offset:1536
	global_load_dwordx4 v[102:105], v[70:71], off offset:1536
	ds_read_b128 v[94:97], v1 offset:41504
	s_waitcnt lgkmcnt(3)
	v_mfma_f32_32x32x16_bf16 v[34:49], v[86:89], v[90:93], v[34:49]
	s_waitcnt lgkmcnt(0)
	v_mfma_f32_32x32x16_bf16 v[50:65], v[86:89], v[94:97], v[50:65]
	ds_read_b128 v[86:89], v68 offset:4640
	v_mfma_f32_32x32x16_bf16 v[2:17], v[98:101], v[126:129], v[2:17]
	v_mfma_f32_32x32x16_bf16 v[18:33], v[98:101], v[130:133], v[18:33]
	s_waitcnt vmcnt(7)
	ds_write_b128 v66, v[106:109] offset:27648
	s_waitcnt vmcnt(6)
	ds_write_b128 v66, v[110:113] offset:32256
	global_load_dwordx4 v[106:109], v[74:75], off offset:1536
	global_load_dwordx4 v[110:113], v[76:77], off offset:1536
	ds_read_b128 v[98:101], v68 offset:4704
	s_waitcnt lgkmcnt(3)
	v_mfma_f32_32x32x16_bf16 v[2:17], v[86:89], v[90:93], v[2:17]
	ds_read_b128 v[90:93], v1 offset:36928
	v_mfma_f32_32x32x16_bf16 v[18:33], v[86:89], v[94:97], v[18:33]
	ds_read_b128 v[86:89], v68 offset:64
	ds_read_b128 v[94:97], v1 offset:41536
	s_waitcnt lgkmcnt(1)
	v_mfma_f32_32x32x16_bf16 v[34:49], v[86:89], v[90:93], v[34:49]
	s_waitcnt lgkmcnt(0)
	v_mfma_f32_32x32x16_bf16 v[50:65], v[86:89], v[94:97], v[50:65]
	s_waitcnt vmcnt(7)
	ds_write_b128 v66, v[144:147] offset:55296
	s_waitcnt vmcnt(6)
	ds_write_b128 v66, v[122:125] offset:59904
	global_load_dwordx4 v[144:147], v[78:79], off offset:1536
	global_load_dwordx4 v[122:125], v[80:81], off offset:1536
	ds_read_b128 v[86:89], v68 offset:4672
	s_waitcnt lgkmcnt(0)
	v_mfma_f32_32x32x16_bf16 v[2:17], v[86:89], v[90:93], v[2:17]
	ds_read_b128 v[90:93], v1 offset:36960
	v_mfma_f32_32x32x16_bf16 v[18:33], v[86:89], v[94:97], v[18:33]
	ds_read_b128 v[86:89], v68 offset:96
	ds_read_b128 v[94:97], v1 offset:41568
	s_waitcnt lgkmcnt(1)
	v_mfma_f32_32x32x16_bf16 v[34:49], v[86:89], v[90:93], v[34:49]
	s_waitcnt lgkmcnt(0)
	v_mfma_f32_32x32x16_bf16 v[50:65], v[86:89], v[94:97], v[50:65]
	s_waitcnt vmcnt(7)
	ds_write_b128 v66, v[118:121] offset:64512
	s_waitcnt vmcnt(6)
	ds_write_b128 v69, v[114:117] offset:32256
	global_load_dwordx4 v[118:121], v[82:83], off offset:1536
	global_load_dwordx4 v[114:117], v[84:85], off offset:1536
	v_mfma_f32_32x32x16_bf16 v[2:17], v[98:101], v[90:93], v[2:17]
	v_mfma_f32_32x32x16_bf16 v[18:33], v[98:101], v[94:97], v[18:33]
	s_setprio 0
	s_waitcnt lgkmcnt(0)
	s_barrier
; #define MFMA(a, b, c) __builtin_amdgcn_mfma_f32_32x32x16_bf16((a), (b), (c), 0, 0, 0)
; template <int TM, int TN>
; DI void gemm_mainloop(const u16* __restrict__ A, long lda, const u16* __restrict__ Bt, long ldb, int K, char* smem,
;                       f32x16 (&acc)[TM][TN]) {
;     ...
;   for (int kt = 0; kt < nk; kt++) {
;     const int buf = kt & 1;
;     const u16* cA = sA + buf * BM * LD + (wm * 32 * TM + r) * LD + h * 8;
;     const u16* cB = sB + buf * BN * LD + (wn * 32 * TN + r) * LD + h * 8;
;     bf16x8 af[TM], bfr[TN];
; #pragma unroll
;     for (int tm = 0; tm < TM; tm++) af[tm] = *(const bf16x8*)(cA + tm * 32 * LD);
; #pragma unroll
;     for (int tn = 0; tn < TN; tn++) bfr[tn] = *(const bf16x8*)(cB + tn * 32 * LD);
;     if (kt + 1 < nk) GEMM_SSTORE(buf ^ 1)
;     __builtin_amdgcn_sched_barrier(0);
;     __builtin_amdgcn_s_setprio(1);
; #pragma unroll
;     for (int tm = 0; tm < TM; tm++)
; #pragma unroll
;       for (int tn = 0; tn < TN; tn++) acc[tm][tn] = MFMA(af[tm], bfr[tn], acc[tm][tn]);
; #pragma unroll
;     for (int tm = 0; tm < TM; tm++) af[tm] = *(const bf16x8*)(cA + tm * 32 * LD + 16);
; #pragma unroll
;     for (int tn = 0; tn < TN; tn++) bfr[tn] = *(const bf16x8*)(cB + tn * 32 * LD + 16);
; #pragma unroll
;     for (int tm = 0; tm < TM; tm++)
; #pragma unroll
;       for (int tn = 0; tn < TN; tn++) acc[tm][tn] = MFMA(af[tm], bfr[tn], acc[tm][tn]);
;     __builtin_amdgcn_sched_group_barrier(0x8, 4, 0);
;     if (kt + 2 < nk) GEMM_GLOAD((kt + 2) * 64)
; #pragma unroll
;     for (int ks = 2; ks < 4; ks++) {
; #pragma unroll
;       for (int tm = 0; tm < TM; tm++) af[tm] = *(const bf16x8*)(cA + tm * 32 * LD + ks * 16);
; #pragma unroll
;       for (int tn = 0; tn < TN; tn++) bfr[tn] = *(const bf16x8*)(cB + tn * 32 * LD + ks * 16);
; #pragma unroll
;       for (int tm = 0; tm < TM; tm++)
; #pragma unroll
;         for (int tn = 0; tn < TN; tn++) acc[tm][tn] = MFMA(af[tm], bfr[tn], acc[tm][tn]);
;     }
;     __builtin_amdgcn_s_setprio(0);
;     __syncthreads();
;   }
	ds_read_b128 v[94:97], v68 offset:18432
	ds_read_b128 v[98:101], v68 offset:23040
	ds_read_b128 v[126:129], v1 offset:55296
	ds_read_b128 v[130:133], v1 offset:59904
	s_setprio 1
	ds_read_b128 v[86:89], v68 offset:18464
	s_waitcnt lgkmcnt(2)
	v_mfma_f32_32x32x16_bf16 v[34:49], v[94:97], v[126:129], v[34:49]
	ds_read_b128 v[90:93], v1 offset:55328
	s_waitcnt lgkmcnt(2)
	v_mfma_f32_32x32x16_bf16 v[50:65], v[94:97], v[130:133], v[50:65]
	s_waitcnt vmcnt(7)
	ds_write_b128 v66, v[140:143]
	s_waitcnt vmcnt(6)
	ds_write_b128 v66, v[102:105] offset:4608
	global_load_dwordx4 v[140:143], v[72:73], off offset:1664
	global_load_dwordx4 v[102:105], v[70:71], off offset:1664
	ds_read_b128 v[94:97], v1 offset:59936
	s_waitcnt lgkmcnt(3)
	v_mfma_f32_32x32x16_bf16 v[34:49], v[86:89], v[90:93], v[34:49]
	s_waitcnt lgkmcnt(0)
	v_mfma_f32_32x32x16_bf16 v[50:65], v[86:89], v[94:97], v[50:65]
	ds_read_b128 v[86:89], v68 offset:23072
	v_mfma_f32_32x32x16_bf16 v[2:17], v[98:101], v[126:129], v[2:17]
	v_mfma_f32_32x32x16_bf16 v[18:33], v[98:101], v[130:133], v[18:33]
	s_waitcnt vmcnt(7)
	ds_write_b128 v66, v[106:109] offset:9216
	s_waitcnt vmcnt(6)
	ds_write_b128 v66, v[110:113] offset:13824
	global_load_dwordx4 v[106:109], v[74:75], off offset:1664
	global_load_dwordx4 v[110:113], v[76:77], off offset:1664
	ds_read_b128 v[98:101], v68 offset:23136
	s_waitcnt lgkmcnt(3)
	v_mfma_f32_32x32x16_bf16 v[2:17], v[86:89], v[90:93], v[2:17]
	ds_read_b128 v[90:93], v1 offset:55360
	v_mfma_f32_32x32x16_bf16 v[18:33], v[86:89], v[94:97], v[18:33]
	ds_read_b128 v[86:89], v68 offset:18496
	ds_read_b128 v[94:97], v1 offset:59968
	s_waitcnt lgkmcnt(1)
	v_mfma_f32_32x32x16_bf16 v[34:49], v[86:89], v[90:93], v[34:49]
	s_waitcnt lgkmcnt(0)
	v_mfma_f32_32x32x16_bf16 v[50:65], v[86:89], v[94:97], v[50:65]
	s_waitcnt vmcnt(7)
	ds_write_b128 v66, v[144:147] offset:36864
	s_waitcnt vmcnt(6)
	ds_write_b128 v66, v[122:125] offset:41472
	global_load_dwordx4 v[144:147], v[78:79], off offset:1664
	global_load_dwordx4 v[122:125], v[80:81], off offset:1664
	ds_read_b128 v[86:89], v68 offset:23104
	s_waitcnt lgkmcnt(0)
	v_mfma_f32_32x32x16_bf16 v[2:17], v[86:89], v[90:93], v[2:17]
	ds_read_b128 v[90:93], v1 offset:55392
	v_mfma_f32_32x32x16_bf16 v[18:33], v[86:89], v[94:97], v[18:33]
	ds_read_b128 v[86:89], v68 offset:18528
	ds_read_b128 v[94:97], v1 offset:60000
	s_waitcnt lgkmcnt(1)
	v_mfma_f32_32x32x16_bf16 v[34:49], v[86:89], v[90:93], v[34:49]
	s_waitcnt lgkmcnt(0)
	v_mfma_f32_32x32x16_bf16 v[50:65], v[86:89], v[94:97], v[50:65]
	s_waitcnt vmcnt(7)
	ds_write_b128 v66, v[118:121] offset:46080
	s_waitcnt vmcnt(6)
	ds_write_b128 v66, v[114:117] offset:50688
	global_load_dwordx4 v[118:121], v[82:83], off offset:1664
	global_load_dwordx4 v[114:117], v[84:85], off offset:1664
	v_mfma_f32_32x32x16_bf16 v[2:17], v[98:101], v[90:93], v[2:17]
	v_mfma_f32_32x32x16_bf16 v[18:33], v[98:101], v[94:97], v[18:33]
	s_setprio 0
	s_waitcnt lgkmcnt(0)
	s_barrier
	ds_read_b128 v[94:97], v68
	ds_read_b128 v[98:101], v68 offset:4608
	ds_read_b128 v[126:129], v1 offset:36864
	ds_read_b128 v[130:133], v1 offset:41472
	s_setprio 1
	ds_read_b128 v[86:89], v68 offset:32
	s_waitcnt lgkmcnt(2)
	v_mfma_f32_32x32x16_bf16 v[34:49], v[94:97], v[126:129], v[34:49]
	ds_read_b128 v[90:93], v1 offset:36896
	s_waitcnt lgkmcnt(2)
	v_mfma_f32_32x32x16_bf16 v[50:65], v[94:97], v[130:133], v[50:65]
	s_waitcnt vmcnt(7)
	ds_write_b128 v66, v[140:143] offset:18432
	s_waitcnt vmcnt(6)
	ds_write_b128 v66, v[102:105] offset:23040
	global_load_dwordx4 v[140:143], v[72:73], off offset:1792
	global_load_dwordx4 v[102:105], v[70:71], off offset:1792
	ds_read_b128 v[94:97], v1 offset:41504
	s_waitcnt lgkmcnt(3)
	v_mfma_f32_32x32x16_bf16 v[34:49], v[86:89], v[90:93], v[34:49]
	s_waitcnt lgkmcnt(0)
	v_mfma_f32_32x32x16_bf16 v[50:65], v[86:89], v[94:97], v[50:65]
	ds_read_b128 v[86:89], v68 offset:4640
	v_mfma_f32_32x32x16_bf16 v[2:17], v[98:101], v[126:129], v[2:17]
	v_mfma_f32_32x32x16_bf16 v[18:33], v[98:101], v[130:133], v[18:33]
	s_waitcnt vmcnt(7)
	ds_write_b128 v66, v[106:109] offset:27648
	s_waitcnt vmcnt(6)
	ds_write_b128 v66, v[110:113] offset:32256
	global_load_dwordx4 v[106:109], v[74:75], off offset:1792
	global_load_dwordx4 v[110:113], v[76:77], off offset:1792
	ds_read_b128 v[98:101], v68 offset:4704
	s_waitcnt lgkmcnt(3)
	v_mfma_f32_32x32x16_bf16 v[2:17], v[86:89], v[90:93], v[2:17]
	ds_read_b128 v[90:93], v1 offset:36928
	v_mfma_f32_32x32x16_bf16 v[18:33], v[86:89], v[94:97], v[18:33]
	ds_read_b128 v[86:89], v68 offset:64
	ds_read_b128 v[94:97], v1 offset:41536
	s_waitcnt lgkmcnt(1)
	v_mfma_f32_32x32x16_bf16 v[34:49], v[86:89], v[90:93], v[34:49]
	s_waitcnt lgkmcnt(0)
	v_mfma_f32_32x32x16_bf16 v[50:65], v[86:89], v[94:97], v[50:65]
	s_waitcnt vmcnt(7)
	ds_write_b128 v66, v[144:147] offset:55296
	s_waitcnt vmcnt(6)
	ds_write_b128 v66, v[122:125] offset:59904
	global_load_dwordx4 v[144:147], v[78:79], off offset:1792
	global_load_dwordx4 v[122:125], v[80:81], off offset:1792
	ds_read_b128 v[86:89], v68 offset:4672
	s_waitcnt lgkmcnt(0)
	v_mfma_f32_32x32x16_bf16 v[2:17], v[86:89], v[90:93], v[2:17]
	ds_read_b128 v[90:93], v1 offset:36960
	v_mfma_f32_32x32x16_bf16 v[18:33], v[86:89], v[94:97], v[18:33]
	ds_read_b128 v[86:89], v68 offset:96
	ds_read_b128 v[94:97], v1 offset:41568
	s_waitcnt lgkmcnt(1)
	v_mfma_f32_32x32x16_bf16 v[34:49], v[86:89], v[90:93], v[34:49]
	s_waitcnt lgkmcnt(0)
	v_mfma_f32_32x32x16_bf16 v[50:65], v[86:89], v[94:97], v[50:65]
	s_waitcnt vmcnt(7)
	ds_write_b128 v66, v[118:121] offset:64512
	s_waitcnt vmcnt(6)
	ds_write_b128 v69, v[114:117] offset:32256
	global_load_dwordx4 v[118:121], v[82:83], off offset:1792
	global_load_dwordx4 v[114:117], v[84:85], off offset:1792
	v_mfma_f32_32x32x16_bf16 v[2:17], v[98:101], v[90:93], v[2:17]
	v_mfma_f32_32x32x16_bf16 v[18:33], v[98:101], v[94:97], v[18:33]
	s_setprio 0
	s_waitcnt lgkmcnt(0)
	s_barrier
; #define MFMA(a, b, c) __builtin_amdgcn_mfma_f32_32x32x16_bf16((a), (b), (c), 0, 0, 0)
; template <int TM, int TN>
; DI void gemm_mainloop(const u16* __restrict__ A, long lda, const u16* __restrict__ Bt, long ldb, int K, char* smem,
;                       f32x16 (&acc)[TM][TN]) {
;     ...
;   for (int kt = 0; kt < nk; kt++) {
;     const int buf = kt & 1;
;     const u16* cA = sA + buf * BM * LD + (wm * 32 * TM + r) * LD + h * 8;
;     const u16* cB = sB + buf * BN * LD + (wn * 32 * TN + r) * LD + h * 8;
;     bf16x8 af[TM], bfr[TN];
; #pragma unroll
;     for (int tm = 0; tm < TM; tm++) af[tm] = *(const bf16x8*)(cA + tm * 32 * LD);
; #pragma unroll
;     for (int tn = 0; tn < TN; tn++) bfr[tn] = *(const bf16x8*)(cB + tn * 32 * LD);
;     if (kt + 1 < nk) GEMM_SSTORE(buf ^ 1)
;     __builtin_amdgcn_sched_barrier(0);
;     __builtin_amdgcn_s_setprio(1);
; #pragma unroll
;     for (int tm = 0; tm < TM; tm++)
; #pragma unroll
;       for (int tn = 0; tn < TN; tn++) acc[tm][tn] = MFMA(af[tm], bfr[tn], acc[tm][tn]);
; #pragma unroll
;     for (int tm = 0; tm < TM; tm++) af[tm] = *(const bf16x8*)(cA + tm * 32 * LD + 16);
; #pragma unroll
;     for (int tn = 0; tn < TN; tn++) bfr[tn] = *(const bf16x8*)(cB + tn * 32 * LD + 16);
; #pragma unroll
;     for (int tm = 0; tm < TM; tm++)
; #pragma unroll
;       for (int tn = 0; tn < TN; tn++) acc[tm][tn] = MFMA(af[tm], bfr[tn], acc[tm][tn]);
;     __builtin_amdgcn_sched_group_barrier(0x8, 4, 0);
;     if (kt + 2 < nk) GEMM_GLOAD((kt + 2) * 64)
; #pragma unroll
;     for (int ks = 2; ks < 4; ks++) {
; #pragma unroll
;       for (int tm = 0; tm < TM; tm++) af[tm] = *(const bf16x8*)(cA + tm * 32 * LD + ks * 16);
; #pragma unroll
;       for (int tn = 0; tn < TN; tn++) bfr[tn] = *(const bf16x8*)(cB + tn * 32 * LD + ks * 16);
; #pragma unroll
;       for (int tm = 0; tm < TM; tm++)
; #pragma unroll
;         for (int tn = 0; tn < TN; tn++) acc[tm][tn] = MFMA(af[tm], bfr[tn], acc[tm][tn]);
;     }
;     __builtin_amdgcn_s_setprio(0);
;     __syncthreads();
;   }
	ds_read_b128 v[94:97], v68 offset:18432
	ds_read_b128 v[98:101], v68 offset:23040
	ds_read_b128 v[126:129], v1 offset:55296
	ds_read_b128 v[130:133], v1 offset:59904
	s_setprio 1
	ds_read_b128 v[86:89], v68 offset:18464
	s_waitcnt lgkmcnt(2)
	v_mfma_f32_32x32x16_bf16 v[34:49], v[94:97], v[126:129], v[34:49]
	ds_read_b128 v[90:93], v1 offset:55328
	s_waitcnt lgkmcnt(2)
	v_mfma_f32_32x32x16_bf16 v[50:65], v[94:97], v[130:133], v[50:65]
	s_waitcnt vmcnt(7)
	ds_write_b128 v66, v[140:143]
	s_waitcnt vmcnt(6)
	ds_write_b128 v66, v[102:105] offset:4608
	global_load_dwordx4 v[140:143], v[72:73], off offset:1920
	global_load_dwordx4 v[102:105], v[70:71], off offset:1920
	ds_read_b128 v[94:97], v1 offset:59936
	s_waitcnt lgkmcnt(3)
	v_mfma_f32_32x32x16_bf16 v[34:49], v[86:89], v[90:93], v[34:49]
	s_waitcnt lgkmcnt(0)
	v_mfma_f32_32x32x16_bf16 v[50:65], v[86:89], v[94:97], v[50:65]
	ds_read_b128 v[86:89], v68 offset:23072
	v_mfma_f32_32x32x16_bf16 v[2:17], v[98:101], v[126:129], v[2:17]
	v_mfma_f32_32x32x16_bf16 v[18:33], v[98:101], v[130:133], v[18:33]
	s_waitcnt vmcnt(7)
	ds_write_b128 v66, v[106:109] offset:9216
	s_waitcnt vmcnt(6)
	ds_write_b128 v66, v[110:113] offset:13824
	global_load_dwordx4 v[106:109], v[74:75], off offset:1920
	global_load_dwordx4 v[110:113], v[76:77], off offset:1920
	ds_read_b128 v[98:101], v68 offset:23136
	s_waitcnt lgkmcnt(3)
	v_mfma_f32_32x32x16_bf16 v[2:17], v[86:89], v[90:93], v[2:17]
	ds_read_b128 v[90:93], v1 offset:55360
	v_mfma_f32_32x32x16_bf16 v[18:33], v[86:89], v[94:97], v[18:33]
	ds_read_b128 v[86:89], v68 offset:18496
	ds_read_b128 v[94:97], v1 offset:59968
	s_waitcnt lgkmcnt(1)
	v_mfma_f32_32x32x16_bf16 v[34:49], v[86:89], v[90:93], v[34:49]
	s_waitcnt lgkmcnt(0)
	v_mfma_f32_32x32x16_bf16 v[50:65], v[86:89], v[94:97], v[50:65]
	s_waitcnt vmcnt(7)
	ds_write_b128 v66, v[144:147] offset:36864
	s_waitcnt vmcnt(6)
	ds_write_b128 v66, v[122:125] offset:41472
	global_load_dwordx4 v[144:147], v[78:79], off offset:1920
	global_load_dwordx4 v[122:125], v[80:81], off offset:1920
	ds_read_b128 v[86:89], v68 offset:23104
	s_waitcnt lgkmcnt(0)
	v_mfma_f32_32x32x16_bf16 v[2:17], v[86:89], v[90:93], v[2:17]
	ds_read_b128 v[90:93], v1 offset:55392
	v_mfma_f32_32x32x16_bf16 v[18:33], v[86:89], v[94:97], v[18:33]
	ds_read_b128 v[86:89], v68 offset:18528
	ds_read_b128 v[94:97], v1 offset:60000
	s_waitcnt lgkmcnt(1)
	v_mfma_f32_32x32x16_bf16 v[34:49], v[86:89], v[90:93], v[34:49]
	s_waitcnt lgkmcnt(0)
	v_mfma_f32_32x32x16_bf16 v[50:65], v[86:89], v[94:97], v[50:65]
	s_waitcnt vmcnt(7)
	ds_write_b128 v66, v[118:121] offset:46080
	s_waitcnt vmcnt(6)
	ds_write_b128 v66, v[114:117] offset:50688
	global_load_dwordx4 v[118:121], v[82:83], off offset:1920
	global_load_dwordx4 v[114:117], v[84:85], off offset:1920
	s_nop 0
	v_mfma_f32_32x32x16_bf16 v[2:17], v[98:101], v[90:93], v[2:17]
	v_mfma_f32_32x32x16_bf16 v[18:33], v[98:101], v[94:97], v[18:33]
	s_setprio 0
	s_waitcnt lgkmcnt(0)
	s_barrier
	ds_read_b128 v[74:77], v68
	ds_read_b128 v[78:81], v68 offset:4608
	ds_read_b128 v[82:85], v1 offset:36864
	ds_read_b128 v[90:93], v1 offset:41472
	s_setprio 1
	ds_read_b128 v[70:73], v68 offset:32
	s_waitcnt lgkmcnt(2)
	v_mfma_f32_32x32x16_bf16 v[34:49], v[74:77], v[82:85], v[34:49]
	s_waitcnt lgkmcnt(1)
	v_mfma_f32_32x32x16_bf16 v[50:65], v[74:77], v[90:93], v[50:65]
	s_waitcnt vmcnt(7)
	ds_write_b128 v66, v[140:143] offset:18432
	s_waitcnt vmcnt(6)
	ds_write_b128 v66, v[102:105] offset:23040
	ds_read_b128 v[74:77], v1 offset:36896
	v_mfma_f32_32x32x16_bf16 v[2:17], v[78:81], v[82:85], v[2:17]
	v_mfma_f32_32x32x16_bf16 v[18:33], v[78:81], v[90:93], v[18:33]
	ds_read_b128 v[78:81], v1 offset:41504
	s_waitcnt lgkmcnt(1)
	v_mfma_f32_32x32x16_bf16 v[34:49], v[70:73], v[74:77], v[34:49]
	s_waitcnt lgkmcnt(0)
	v_mfma_f32_32x32x16_bf16 v[50:65], v[70:73], v[78:81], v[50:65]
	s_waitcnt vmcnt(5)
	ds_write_b128 v66, v[106:109] offset:27648
	s_waitcnt vmcnt(4)
	ds_write_b128 v66, v[110:113] offset:32256
	ds_read_b128 v[70:73], v68 offset:4640
	s_waitcnt lgkmcnt(0)
	v_mfma_f32_32x32x16_bf16 v[2:17], v[70:73], v[74:77], v[2:17]
	ds_read_b128 v[74:77], v1 offset:36928
	v_mfma_f32_32x32x16_bf16 v[18:33], v[70:73], v[78:81], v[18:33]
	ds_read_b128 v[70:73], v68 offset:64
	ds_read_b128 v[78:81], v1 offset:41536
	s_waitcnt lgkmcnt(1)
	v_mfma_f32_32x32x16_bf16 v[34:49], v[70:73], v[74:77], v[34:49]
	s_waitcnt lgkmcnt(0)
	v_mfma_f32_32x32x16_bf16 v[50:65], v[70:73], v[78:81], v[50:65]
	s_waitcnt vmcnt(3)
	ds_write_b128 v66, v[144:147] offset:55296
	s_waitcnt vmcnt(2)
	ds_write_b128 v66, v[122:125] offset:59904
	ds_read_b128 v[70:73], v68 offset:4672
	s_waitcnt lgkmcnt(0)
	v_mfma_f32_32x32x16_bf16 v[2:17], v[70:73], v[74:77], v[2:17]
	ds_read_b128 v[74:77], v1 offset:36960
	v_mfma_f32_32x32x16_bf16 v[18:33], v[70:73], v[78:81], v[18:33]
	ds_read_b128 v[70:73], v68 offset:96
	ds_read_b128 v[78:81], v1 offset:41568
	s_waitcnt lgkmcnt(1)
	v_mfma_f32_32x32x16_bf16 v[34:49], v[70:73], v[74:77], v[34:49]
	s_waitcnt lgkmcnt(0)
	v_mfma_f32_32x32x16_bf16 v[50:65], v[70:73], v[78:81], v[50:65]
	s_waitcnt vmcnt(1)
	ds_write_b128 v66, v[118:121] offset:64512
	s_waitcnt vmcnt(0)
	ds_write_b128 v69, v[114:117] offset:32256
	ds_read_b128 v[70:73], v68 offset:4704
	s_waitcnt lgkmcnt(0)
	v_mfma_f32_32x32x16_bf16 v[2:17], v[70:73], v[74:77], v[2:17]
	v_mfma_f32_32x32x16_bf16 v[18:33], v[70:73], v[78:81], v[18:33]
	s_setprio 0
	s_barrier
; #define MFMA(a, b, c) __builtin_amdgcn_mfma_f32_32x32x16_bf16((a), (b), (c), 0, 0, 0)
; DI unsigned pk2(float a, float b) { fv2 v = {a, b}; bfv2 r = __builtin_convertvector(v, bfv2); return __builtin_bit_cast(unsigned, r); }
; DI int crow(int i, int h) { return (i & 3) + 8 * (i >> 2) + 4 * h; }
; template <int TM, int TN>
; DI void gemm_mainloop(const u16* __restrict__ A, long lda, const u16* __restrict__ Bt, long ldb, int K, char* smem,
;                       f32x16 (&acc)[TM][TN]) {
;     ...
;     for (int ks = 2; ks < 4; ks++) {
; #pragma unroll
;       for (int tm = 0; tm < TM; tm++) af[tm] = *(const bf16x8*)(cA + tm * 32 * LD + ks * 16);
; #pragma unroll
;       for (int tn = 0; tn < TN; tn++) bfr[tn] = *(const bf16x8*)(cB + tn * 32 * LD + ks * 16);
; #pragma unroll
;       for (int tm = 0; tm < TM; tm++)
; #pragma unroll
;         for (int tn = 0; tn < TN; tn++) acc[tm][tn] = MFMA(af[tm], bfr[tn], acc[tm][tn]);
;     }
;     __builtin_amdgcn_s_setprio(0);
;     __syncthreads();
;   }
; template <int TM, int TN, class Epi>
; DI void gemm_tile(const u16* A, long lda, const u16* Bt, long ldb, int K, int m0, int n0, char* smem, const Epi& epi) {
;     ...
; #pragma unroll
;   for (int tm = 0; tm < TM; tm++)
; #pragma unroll
;     for (int tn = 0; tn < TN; tn++)
; #pragma unroll
;       for (int i = 0; i < 16; i++)
;         Ct[(wm * 32 * TM + tm * 32 + crow(i, h)) * LDC + wn * 32 * TN + tn * 32 + r] = acc[tm][tn][i];
;   __syncthreads();
;   epi(Ct, LDC, m0, n0, tid, BM);
;   __syncthreads();
;   (void)BM;
; }
;   DI void operator()(const float* Ct, int ldc, int m0, int n0, int tid, int bm) const {
; #pragma unroll 4
;     for (int it = 0; it < bm / 16; it++) {
;       int id = tid + 256 * it; int row = id >> 4, c8 = (id & 15) * 8;
;       int n = n0 + c8;
;       if (n < nmax) {
;         const float* c = Ct + row * ldc + c8;
;         float4 a = *(const float4*)c, b = *(const float4*)(c + 4);
;         uint4 v; v.x = pk2(a.x, a.y); v.y = pk2(a.z, a.w); v.z = pk2(b.x, b.y); v.w = pk2(b.z, b.w);
;         *(uint4*)(out + (long)(m0 + row) * ldo + n) = v;
;         if (gates != nullptr && n == 1952) {
	ds_read_b128 v[70:73], v68 offset:18432
	ds_read_b128 v[74:77], v68 offset:23040
	ds_read_b128 v[78:81], v1 offset:55296
	ds_read_b128 v[82:85], v1 offset:59904
	s_setprio 1
	s_waitcnt lgkmcnt(1)
	v_mfma_f32_32x32x16_bf16 v[34:49], v[70:73], v[78:81], v[34:49]
	s_waitcnt lgkmcnt(0)
	v_mfma_f32_32x32x16_bf16 v[50:65], v[70:73], v[82:85], v[50:65]
	ds_read_b128 v[70:73], v68 offset:18464
	v_mfma_f32_32x32x16_bf16 v[2:17], v[74:77], v[78:81], v[2:17]
	ds_read_b128 v[78:81], v1 offset:59936
	v_mfma_f32_32x32x16_bf16 v[18:33], v[74:77], v[82:85], v[18:33]
	ds_read_b128 v[74:77], v1 offset:55328
	s_waitcnt lgkmcnt(0)
	v_mfma_f32_32x32x16_bf16 v[34:49], v[70:73], v[74:77], v[34:49]
	v_mfma_f32_32x32x16_bf16 v[50:65], v[70:73], v[78:81], v[50:65]
	ds_read_b128 v[70:73], v68 offset:23072
	s_waitcnt lgkmcnt(0)
	v_mfma_f32_32x32x16_bf16 v[2:17], v[70:73], v[74:77], v[2:17]
	ds_read_b128 v[74:77], v1 offset:55360
	v_mfma_f32_32x32x16_bf16 v[18:33], v[70:73], v[78:81], v[18:33]
	ds_read_b128 v[70:73], v68 offset:18496
	ds_read_b128 v[78:81], v1 offset:59968
	s_waitcnt lgkmcnt(1)
	v_mfma_f32_32x32x16_bf16 v[34:49], v[70:73], v[74:77], v[34:49]
	s_waitcnt lgkmcnt(0)
	v_mfma_f32_32x32x16_bf16 v[50:65], v[70:73], v[78:81], v[50:65]
	ds_read_b128 v[70:73], v68 offset:23104
	s_waitcnt lgkmcnt(0)
	v_mfma_f32_32x32x16_bf16 v[2:17], v[70:73], v[74:77], v[2:17]
	ds_read_b128 v[74:77], v1 offset:55392
	v_mfma_f32_32x32x16_bf16 v[18:33], v[70:73], v[78:81], v[18:33]
	ds_read_b128 v[70:73], v68 offset:18528
	ds_read_b128 v[78:81], v1 offset:60000
	s_waitcnt lgkmcnt(1)
	v_mfma_f32_32x32x16_bf16 v[34:49], v[70:73], v[74:77], v[34:49]
	s_waitcnt lgkmcnt(0)
	v_mfma_f32_32x32x16_bf16 v[50:65], v[70:73], v[78:81], v[50:65]
	ds_read_b128 v[68:71], v68 offset:23136
	s_waitcnt lgkmcnt(0)
	v_mfma_f32_32x32x16_bf16 v[2:17], v[68:71], v[74:77], v[2:17]
	v_mfma_f32_32x32x16_bf16 v[18:33], v[68:71], v[78:81], v[18:33]
	s_setprio 0
	v_mov_b32_e32 v1, v0
	s_barrier
	s_mov_b32 s4, 0
	v_lshrrev_b32_e32 v66, 1, v1
	v_and_b32_e32 v66, 0xfffffc0, v66
	v_lshrrev_b32_e32 v68, 3, v1
	v_and_or_b32 v66, v68, 4, v66
	v_and_b32_e32 v68, 0x5f, v1
	v_mul_lo_u32 v66, v66, s30
	v_lshl_add_u32 v66, v68, 2, v66
	ds_write2_b32 v66, v34, v50 offset1:32
	v_add_u32_e32 v34, 0x400, v66
	ds_write2_b32 v34, v36, v52 offset0:8 offset1:40
	ds_write2_b32 v34, v37, v53 offset0:140 offset1:172
	v_add_u32_e32 v34, 0x1000, v66
	ds_write2_b32 v34, v38, v54 offset0:32 offset1:64
	ds_write2_b32 v34, v39, v55 offset0:164 offset1:196
	v_add_u32_e32 v34, 0x1400, v66
	ds_write2_b32 v34, v40, v56 offset0:40 offset1:72
	ds_write2_b32 v34, v41, v57 offset0:172 offset1:204
	v_add_u32_e32 v34, 0x2000, v66
	ds_write2_b32 v34, v42, v58 offset0:64 offset1:96
	ds_write2_b32 v34, v43, v59 offset0:196 offset1:228
	v_add_u32_e32 v34, 0x2400, v66
	ds_write2_b32 v34, v44, v60 offset0:72 offset1:104
	ds_write2_b32 v34, v45, v61 offset0:204 offset1:236
	v_add_u32_e32 v34, 0x3000, v66
	ds_write2_b32 v34, v46, v62 offset0:96 offset1:128
	v_add_u32_e32 v34, 0x3200, v66
	ds_write2_b32 v34, v47, v63 offset0:100 offset1:132
	v_add_u32_e32 v34, 0x3400, v66
	ds_write2_b32 v34, v48, v64 offset0:104 offset1:136
	v_add_u32_e32 v34, 0x3600, v66
	ds_write2_b32 v34, v49, v65 offset0:108 offset1:140
	v_add_u32_e32 v34, 0x4000, v66
	ds_write2_b32 v34, v2, v18 offset0:128 offset1:160
	v_add_u32_e32 v2, 0x4400, v66
	ds_write2_b32 v2, v3, v19 offset0:4 offset1:36
	ds_write2_b32 v2, v4, v20 offset0:136 offset1:168
	v_add_u32_e32 v2, 0x4800, v66
	ds_write2_b32 v2, v5, v21 offset0:12 offset1:44
	v_add_u32_e32 v2, 0x5000, v66
	ds_write2_b32 v2, v6, v22 offset0:160 offset1:192
	v_add_u32_e32 v2, 0x5400, v66
	ds_write2_b32 v2, v7, v23 offset0:36 offset1:68
	ds_write2_b32 v2, v8, v24 offset0:168 offset1:200
	v_add_u32_e32 v2, 0x5800, v66
	ds_write2_b32 v2, v9, v25 offset0:44 offset1:76
	v_add_u32_e32 v2, 0x6000, v66
	ds_write2_b32 v2, v10, v26 offset0:192 offset1:224
	v_add_u32_e32 v2, 0x6400, v66
	ds_write2_b32 v2, v11, v27 offset0:68 offset1:100
	ds_write2_b32 v2, v12, v28 offset0:200 offset1:232
	v_add_u32_e32 v2, 0x6800, v66
	ds_write2_b32 v2, v13, v29 offset0:76 offset1:108
	v_add_u32_e32 v2, 0x7200, v66
	ds_write2_b32 v2, v14, v30 offset0:96 offset1:128
	v_add_u32_e32 v2, 0x7400, v66
	ds_write2_b32 v2, v15, v31 offset0:100 offset1:132
	v_add_u32_e32 v2, 0x7600, v66
	ds_write2_b32 v2, v16, v32 offset0:104 offset1:136
	v_add_u32_e32 v2, 0x7800, v66
	ds_write2_b32 v2, v17, v33 offset0:108 offset1:140
	v_lshlrev_b32_e32 v2, 3, v1
	v_and_b32_e32 v3, 0x78, v2
	v_or_b32_e32 v2, s6, v3
	v_lshlrev_b32_e32 v10, 2, v3
	v_ashrrev_i32_e32 v3, 31, v2
	v_cmp_eq_u32_e32 vcc, s31, v2
	v_cmp_gt_i32_e64 s[6:7], s36, v2
	v_lshl_add_u64 v[12:13], v[2:3], 1, s[14:15]
	ds_write2_b32 v66, v35, v51 offset0:132 offset1:164
	s_waitcnt lgkmcnt(0)
	s_barrier
	s_branch .LBB0_1555

; #define MFMA(a, b, c) __builtin_amdgcn_mfma_f32_32x32x16_bf16((a), (b), (c), 0, 0, 0)
; template <int TM, int TN>
; DI void gemm_mainloop(const u16* __restrict__ A, long lda, const u16* __restrict__ Bt, long ldb, int K, char* smem,
;                       f32x16 (&acc)[TM][TN]) {
;     ...
;   const int lrow = tid >> 3, lch = (tid & 7) * 8;
;   const u16* gA = A + (long)lrow * lda + lch;
;   const u16* gB = Bt + (long)lrow * ldb + lch;
;   const int soff = lrow * LD + lch;
;     ...
;   GEMM_GLOAD(0)
;   __syncthreads();
;   GEMM_SSTORE(0)
;   if (nk > 1) GEMM_GLOAD(64)
;   __syncthreads();
;   for (int kt = 0; kt < nk; kt++) {
;     const int buf = kt & 1;
;     const u16* cA = sA + buf * BM * LD + (wm * 32 * TM + r) * LD + h * 8;
;     const u16* cB = sB + buf * BN * LD + (wn * 32 * TN + r) * LD + h * 8;
;     bf16x8 af[TM], bfr[TN];
; #pragma unroll
;     for (int tm = 0; tm < TM; tm++) af[tm] = *(const bf16x8*)(cA + tm * 32 * LD);
; #pragma unroll
;     for (int tn = 0; tn < TN; tn++) bfr[tn] = *(const bf16x8*)(cB + tn * 32 * LD);
;     if (kt + 1 < nk) GEMM_SSTORE(buf ^ 1)
;     __builtin_amdgcn_sched_barrier(0);
;     __builtin_amdgcn_s_setprio(1);
; #pragma unroll
;     for (int tm = 0; tm < TM; tm++)
; #pragma unroll
;       for (int tn = 0; tn < TN; tn++) acc[tm][tn] = MFMA(af[tm], bfr[tn], acc[tm][tn]);
; #pragma unroll
;     for (int tm = 0; tm < TM; tm++) af[tm] = *(const bf16x8*)(cA + tm * 32 * LD + 16);
; #pragma unroll
;     for (int tn = 0; tn < TN; tn++) bfr[tn] = *(const bf16x8*)(cB + tn * 32 * LD + 16);
; #pragma unroll
;     for (int tm = 0; tm < TM; tm++)
; #pragma unroll
;       for (int tn = 0; tn < TN; tn++) acc[tm][tn] = MFMA(af[tm], bfr[tn], acc[tm][tn]);
;     __builtin_amdgcn_sched_group_barrier(0x8, 4, 0);
;     if (kt + 2 < nk) GEMM_GLOAD((kt + 2) * 64)
; #pragma unroll
;     for (int ks = 2; ks < 4; ks++) {
; #pragma unroll
;       for (int tm = 0; tm < TM; tm++) af[tm] = *(const bf16x8*)(cA + tm * 32 * LD + ks * 16);
; #pragma unroll
;       for (int tn = 0; tn < TN; tn++) bfr[tn] = *(const bf16x8*)(cB + tn * 32 * LD + ks * 16);
; #pragma unroll
;       for (int tm = 0; tm < TM; tm++)
; #pragma unroll
;         for (int tn = 0; tn < TN; tn++) acc[tm][tn] = MFMA(af[tm], bfr[tn], acc[tm][tn]);
;     }
.LBB0_2474:
	s_lshl_b32 s25, s24, 10
	s_add_i32 s25, s25, s10
	s_mul_i32 s6, s25, 0x880
	s_mul_hi_i32 s7, s25, 0x880
	s_add_u32 s6, s4, s6
	v_mov_b32_e32 v1, v0
	s_addc_u32 s7, s5, s7
	s_nop 0
	v_lshlrev_b32_e32 v2, 3, v1
	v_ashrrev_i32_e32 v70, 3, v1
	v_and_b32_e32 v71, 56, v2
	v_mov_b64_e32 v[2:3], s[6:7]
	v_mad_i64_i32 v[2:3], s[6:7], v70, s15, v[2:3]
	v_lshlrev_b32_e32 v66, 1, v71
	v_lshl_add_u64 v[74:75], v[2:3], 0, v[66:67]
	v_add_co_u32_e32 v72, vcc, s17, v74
	v_mad_i64_i32 v[10:11], s[6:7], v70, s15, v[68:69]
	s_nop 0
	v_addc_co_u32_e32 v73, vcc, 0, v75, vcc
	v_add_co_u32_e32 v76, vcc, s18, v74
	v_lshl_add_u64 v[78:79], v[10:11], 0, v[66:67]
	s_nop 0
	v_addc_co_u32_e32 v77, vcc, 0, v75, vcc
	v_add_co_u32_e32 v80, vcc, s17, v78
	global_load_dwordx4 v[2:5], v[74:75], off
	s_nop 0
	v_addc_co_u32_e32 v81, vcc, 0, v79, vcc
	v_add_co_u32_e32 v82, vcc, s18, v78
	global_load_dwordx4 v[6:9], v[72:73], off
	s_nop 0
	v_addc_co_u32_e32 v83, vcc, 0, v79, vcc
	v_add_co_u32_e32 v84, vcc, s19, v78
	global_load_dwordx4 v[10:13], v[78:79], off
	s_nop 0
	v_addc_co_u32_e32 v85, vcc, 0, v79, vcc
	v_add_co_u32_e32 v86, vcc, s19, v74
	global_load_dwordx4 v[14:17], v[80:81], off
	s_nop 0
	v_addc_co_u32_e32 v87, vcc, 0, v75, vcc
	global_load_dwordx4 v[18:21], v[82:83], off
	global_load_dwordx4 v[22:25], v[84:85], off
	global_load_dwordx4 v[26:29], v[76:77], off
	global_load_dwordx4 v[30:33], v[86:87], off
	s_barrier
	global_load_dwordx4 v[34:37], v[74:75], off offset:128
	global_load_dwordx4 v[38:41], v[72:73], off offset:128
	global_load_dwordx4 v[42:45], v[76:77], off offset:128
	global_load_dwordx4 v[46:49], v[86:87], off offset:128
	global_load_dwordx4 v[50:53], v[78:79], off offset:128
	global_load_dwordx4 v[54:57], v[80:81], off offset:128
	global_load_dwordx4 v[58:61], v[82:83], off offset:128
	global_load_dwordx4 v[62:65], v[84:85], off offset:128
	v_and_b32_e32 v66, 31, v1
	v_lshrrev_b32_e32 v88, 1, v1
	v_mul_lo_u32 v70, v70, s16
	v_and_or_b32 v89, v88, s20, v66
	v_and_b32_e32 v88, 16, v88
	v_and_b32_e32 v1, 0x5f, v1
	v_add_lshl_u32 v66, v70, v71, 1
	v_mad_u64_u32 v[70:71], s[6:7], v89, s21, v[88:89]
	v_mad_u32_u24 v1, v1, s21, v88
	v_add_u32_e32 v71, 0x9000, v66
	s_waitcnt vmcnt(15)
	ds_write_b128 v66, v[2:5]
	s_waitcnt vmcnt(14)
	ds_write_b128 v66, v[6:9] offset:4608
	s_waitcnt vmcnt(13)
	ds_write_b128 v66, v[10:13] offset:36864
	s_waitcnt vmcnt(12)
	ds_write_b128 v66, v[14:17] offset:41472
	s_waitcnt vmcnt(11)
	ds_write_b128 v66, v[18:21] offset:46080
	s_waitcnt vmcnt(10)
	ds_write_b128 v66, v[22:25] offset:50688
	s_waitcnt vmcnt(9)
	ds_write_b128 v66, v[26:29] offset:9216
	s_waitcnt vmcnt(8)
	ds_write_b128 v66, v[30:33] offset:13824
	s_waitcnt lgkmcnt(0)
	s_barrier
	ds_read_b128 v[2:5], v70
	ds_read_b128 v[18:21], v70 offset:4608
	ds_read_b128 v[6:9], v1 offset:36864
	ds_read_b128 v[22:25], v1 offset:41472
	s_waitcnt vmcnt(7)
	ds_write_b128 v66, v[34:37] offset:18432
	s_waitcnt vmcnt(6)
	ds_write_b128 v66, v[38:41] offset:23040
	s_waitcnt vmcnt(5)
	ds_write_b128 v66, v[42:45] offset:27648
	s_waitcnt vmcnt(4)
	ds_write_b128 v66, v[46:49] offset:32256
	s_waitcnt vmcnt(3)
	ds_write_b128 v66, v[50:53] offset:55296
	s_waitcnt vmcnt(2)
	ds_write_b128 v66, v[54:57] offset:59904
	s_waitcnt vmcnt(1)
	ds_write_b128 v66, v[58:61] offset:64512
	s_waitcnt vmcnt(0)
	ds_write_b128 v71, v[62:65] offset:32256
	s_setprio 1
	ds_read_b128 v[88:91], v70 offset:32
	s_waitcnt lgkmcnt(10)
	v_mfma_f32_32x32x16_bf16 v[34:49], v[2:5], v[6:9], 0
	ds_read_b128 v[92:95], v1 offset:36896
	ds_read_b128 v[96:99], v1 offset:41504
	ds_read_b128 v[100:103], v70 offset:4704
	global_load_dwordx4 v[104:107], v[72:73], off offset:256
	global_load_dwordx4 v[108:111], v[76:77], off offset:256
	global_load_dwordx4 v[112:115], v[86:87], off offset:256
	global_load_dwordx4 v[116:119], v[84:85], off offset:256
	s_waitcnt lgkmcnt(12)
	v_mfma_f32_32x32x16_bf16 v[50:65], v[2:5], v[22:25], 0
	global_load_dwordx4 v[120:123], v[82:83], off offset:256
	global_load_dwordx4 v[124:127], v[80:81], off offset:256
	global_load_dwordx4 v[140:143], v[74:75], off offset:256
	global_load_dwordx4 v[144:147], v[78:79], off offset:256
	s_waitcnt lgkmcnt(2)
	v_mfma_f32_32x32x16_bf16 v[34:49], v[88:91], v[92:95], v[34:49]
	s_waitcnt lgkmcnt(1)
	v_mfma_f32_32x32x16_bf16 v[50:65], v[88:91], v[96:99], v[50:65]
	ds_read_b128 v[88:91], v70 offset:4640
	v_mfma_f32_32x32x16_bf16 v[2:17], v[18:21], v[6:9], 0
	v_mfma_f32_32x32x16_bf16 v[18:33], v[18:21], v[22:25], 0
	s_waitcnt lgkmcnt(0)
	v_mfma_f32_32x32x16_bf16 v[2:17], v[88:91], v[92:95], v[2:17]
	ds_read_b128 v[92:95], v1 offset:36928
	v_mfma_f32_32x32x16_bf16 v[18:33], v[88:91], v[96:99], v[18:33]
	ds_read_b128 v[88:91], v70 offset:64
	ds_read_b128 v[96:99], v1 offset:41536
	s_waitcnt lgkmcnt(1)
	v_mfma_f32_32x32x16_bf16 v[34:49], v[88:91], v[92:95], v[34:49]
	s_waitcnt lgkmcnt(0)
	v_mfma_f32_32x32x16_bf16 v[50:65], v[88:91], v[96:99], v[50:65]
	ds_read_b128 v[88:91], v70 offset:4672
	s_waitcnt lgkmcnt(0)
	v_mfma_f32_32x32x16_bf16 v[2:17], v[88:91], v[92:95], v[2:17]
	ds_read_b128 v[92:95], v1 offset:36960
	v_mfma_f32_32x32x16_bf16 v[18:33], v[88:91], v[96:99], v[18:33]
	ds_read_b128 v[88:91], v70 offset:96
	ds_read_b128 v[96:99], v1 offset:41568
	s_waitcnt lgkmcnt(1)
	v_mfma_f32_32x32x16_bf16 v[34:49], v[88:91], v[92:95], v[34:49]
	s_waitcnt lgkmcnt(0)
	v_mfma_f32_32x32x16_bf16 v[50:65], v[88:91], v[96:99], v[50:65]
	v_mfma_f32_32x32x16_bf16 v[2:17], v[100:103], v[92:95], v[2:17]
	v_mfma_f32_32x32x16_bf16 v[18:33], v[100:103], v[96:99], v[18:33]
	s_setprio 0
	s_barrier
; #define MFMA(a, b, c) __builtin_amdgcn_mfma_f32_32x32x16_bf16((a), (b), (c), 0, 0, 0)
; template <int TM, int TN>
; DI void gemm_mainloop(const u16* __restrict__ A, long lda, const u16* __restrict__ Bt, long ldb, int K, char* smem,
;                       f32x16 (&acc)[TM][TN]) {
;     ...
;   for (int kt = 0; kt < nk; kt++) {
;     const int buf = kt & 1;
;     const u16* cA = sA + buf * BM * LD + (wm * 32 * TM + r) * LD + h * 8;
;     const u16* cB = sB + buf * BN * LD + (wn * 32 * TN + r) * LD + h * 8;
;     bf16x8 af[TM], bfr[TN];
; #pragma unroll
;     for (int tm = 0; tm < TM; tm++) af[tm] = *(const bf16x8*)(cA + tm * 32 * LD);
; #pragma unroll
;     for (int tn = 0; tn < TN; tn++) bfr[tn] = *(const bf16x8*)(cB + tn * 32 * LD);
;     if (kt + 1 < nk) GEMM_SSTORE(buf ^ 1)
;     __builtin_amdgcn_sched_barrier(0);
;     __builtin_amdgcn_s_setprio(1);
; #pragma unroll
;     for (int tm = 0; tm < TM; tm++)
; #pragma unroll
;       for (int tn = 0; tn < TN; tn++) acc[tm][tn] = MFMA(af[tm], bfr[tn], acc[tm][tn]);
; #pragma unroll
;     for (int tm = 0; tm < TM; tm++) af[tm] = *(const bf16x8*)(cA + tm * 32 * LD + 16);
; #pragma unroll
;     for (int tn = 0; tn < TN; tn++) bfr[tn] = *(const bf16x8*)(cB + tn * 32 * LD + 16);
; #pragma unroll
;     for (int tm = 0; tm < TM; tm++)
; #pragma unroll
;       for (int tn = 0; tn < TN; tn++) acc[tm][tn] = MFMA(af[tm], bfr[tn], acc[tm][tn]);
;     __builtin_amdgcn_sched_group_barrier(0x8, 4, 0);
;     if (kt + 2 < nk) GEMM_GLOAD((kt + 2) * 64)
; #pragma unroll
;     for (int ks = 2; ks < 4; ks++) {
; #pragma unroll
;       for (int tm = 0; tm < TM; tm++) af[tm] = *(const bf16x8*)(cA + tm * 32 * LD + ks * 16);
; #pragma unroll
;       for (int tn = 0; tn < TN; tn++) bfr[tn] = *(const bf16x8*)(cB + tn * 32 * LD + ks * 16);
; #pragma unroll
;       for (int tm = 0; tm < TM; tm++)
; #pragma unroll
;         for (int tn = 0; tn < TN; tn++) acc[tm][tn] = MFMA(af[tm], bfr[tn], acc[tm][tn]);
;     }
;     __builtin_amdgcn_s_setprio(0);
;     __syncthreads();
;   }
	ds_read_b128 v[96:99], v70 offset:18432
	ds_read_b128 v[100:103], v70 offset:23040
	ds_read_b128 v[128:131], v1 offset:55296
	ds_read_b128 v[132:135], v1 offset:59904
	s_setprio 1
	ds_read_b128 v[88:91], v70 offset:18464
	s_waitcnt lgkmcnt(2)
	v_mfma_f32_32x32x16_bf16 v[34:49], v[96:99], v[128:131], v[34:49]
	ds_read_b128 v[92:95], v1 offset:55328
	s_waitcnt lgkmcnt(2)
	v_mfma_f32_32x32x16_bf16 v[50:65], v[96:99], v[132:135], v[50:65]
	s_waitcnt vmcnt(1)
	ds_write_b128 v66, v[140:143]
	ds_write_b128 v66, v[104:107] offset:4608
	global_load_dwordx4 v[140:143], v[74:75], off offset:384
	global_load_dwordx4 v[104:107], v[72:73], off offset:384
	ds_read_b128 v[96:99], v1 offset:59936
	s_waitcnt lgkmcnt(3)
	v_mfma_f32_32x32x16_bf16 v[34:49], v[88:91], v[92:95], v[34:49]
	s_waitcnt lgkmcnt(0)
	v_mfma_f32_32x32x16_bf16 v[50:65], v[88:91], v[96:99], v[50:65]
	ds_read_b128 v[88:91], v70 offset:23072
	v_mfma_f32_32x32x16_bf16 v[2:17], v[100:103], v[128:131], v[2:17]
	v_mfma_f32_32x32x16_bf16 v[18:33], v[100:103], v[132:135], v[18:33]
	ds_write_b128 v66, v[108:111] offset:9216
	ds_write_b128 v66, v[112:115] offset:13824
	global_load_dwordx4 v[108:111], v[76:77], off offset:384
	global_load_dwordx4 v[112:115], v[86:87], off offset:384
	ds_read_b128 v[100:103], v70 offset:23136
	s_waitcnt lgkmcnt(3)
	v_mfma_f32_32x32x16_bf16 v[2:17], v[88:91], v[92:95], v[2:17]
	ds_read_b128 v[92:95], v1 offset:55360
	v_mfma_f32_32x32x16_bf16 v[18:33], v[88:91], v[96:99], v[18:33]
	ds_read_b128 v[88:91], v70 offset:18496
	ds_read_b128 v[96:99], v1 offset:59968
	s_waitcnt lgkmcnt(1)
	v_mfma_f32_32x32x16_bf16 v[34:49], v[88:91], v[92:95], v[34:49]
	s_waitcnt lgkmcnt(0)
	v_mfma_f32_32x32x16_bf16 v[50:65], v[88:91], v[96:99], v[50:65]
	s_waitcnt vmcnt(4)
	ds_write_b128 v66, v[144:147] offset:36864
	ds_write_b128 v66, v[124:127] offset:41472
	global_load_dwordx4 v[144:147], v[78:79], off offset:384
	global_load_dwordx4 v[124:127], v[80:81], off offset:384
	ds_read_b128 v[88:91], v70 offset:23104
	s_waitcnt lgkmcnt(0)
	v_mfma_f32_32x32x16_bf16 v[2:17], v[88:91], v[92:95], v[2:17]
	ds_read_b128 v[92:95], v1 offset:55392
	v_mfma_f32_32x32x16_bf16 v[18:33], v[88:91], v[96:99], v[18:33]
	ds_read_b128 v[88:91], v70 offset:18528
	ds_read_b128 v[96:99], v1 offset:60000
	s_waitcnt lgkmcnt(1)
	v_mfma_f32_32x32x16_bf16 v[34:49], v[88:91], v[92:95], v[34:49]
	s_waitcnt lgkmcnt(0)
	v_mfma_f32_32x32x16_bf16 v[50:65], v[88:91], v[96:99], v[50:65]
	ds_write_b128 v66, v[120:123] offset:46080
	ds_write_b128 v66, v[116:119] offset:50688
	global_load_dwordx4 v[120:123], v[82:83], off offset:384
	global_load_dwordx4 v[116:119], v[84:85], off offset:384
	v_mfma_f32_32x32x16_bf16 v[2:17], v[100:103], v[92:95], v[2:17]
	v_mfma_f32_32x32x16_bf16 v[18:33], v[100:103], v[96:99], v[18:33]
	s_setprio 0
	s_waitcnt lgkmcnt(0)
	s_barrier
	ds_read_b128 v[96:99], v70
	ds_read_b128 v[100:103], v70 offset:4608
	ds_read_b128 v[128:131], v1 offset:36864
	ds_read_b128 v[132:135], v1 offset:41472
	s_setprio 1
	ds_read_b128 v[88:91], v70 offset:32
	s_waitcnt lgkmcnt(2)
	v_mfma_f32_32x32x16_bf16 v[34:49], v[96:99], v[128:131], v[34:49]
	ds_read_b128 v[92:95], v1 offset:36896
	s_waitcnt lgkmcnt(2)
	v_mfma_f32_32x32x16_bf16 v[50:65], v[96:99], v[132:135], v[50:65]
	s_waitcnt vmcnt(7)
	ds_write_b128 v66, v[140:143] offset:18432
	s_waitcnt vmcnt(6)
	ds_write_b128 v66, v[104:107] offset:23040
	global_load_dwordx4 v[140:143], v[74:75], off offset:512
	global_load_dwordx4 v[104:107], v[72:73], off offset:512
	ds_read_b128 v[96:99], v1 offset:41504
	s_waitcnt lgkmcnt(3)
	v_mfma_f32_32x32x16_bf16 v[34:49], v[88:91], v[92:95], v[34:49]
	s_waitcnt lgkmcnt(0)
	v_mfma_f32_32x32x16_bf16 v[50:65], v[88:91], v[96:99], v[50:65]
	ds_read_b128 v[88:91], v70 offset:4640
	v_mfma_f32_32x32x16_bf16 v[2:17], v[100:103], v[128:131], v[2:17]
	v_mfma_f32_32x32x16_bf16 v[18:33], v[100:103], v[132:135], v[18:33]
	s_waitcnt vmcnt(7)
	ds_write_b128 v66, v[108:111] offset:27648
	s_waitcnt vmcnt(6)
	ds_write_b128 v66, v[112:115] offset:32256
	global_load_dwordx4 v[108:111], v[76:77], off offset:512
	global_load_dwordx4 v[112:115], v[86:87], off offset:512
	ds_read_b128 v[100:103], v70 offset:4704
	s_waitcnt lgkmcnt(3)
	v_mfma_f32_32x32x16_bf16 v[2:17], v[88:91], v[92:95], v[2:17]
	ds_read_b128 v[92:95], v1 offset:36928
	v_mfma_f32_32x32x16_bf16 v[18:33], v[88:91], v[96:99], v[18:33]
	ds_read_b128 v[88:91], v70 offset:64
	ds_read_b128 v[96:99], v1 offset:41536
	s_waitcnt lgkmcnt(1)
	v_mfma_f32_32x32x16_bf16 v[34:49], v[88:91], v[92:95], v[34:49]
	s_waitcnt lgkmcnt(0)
	v_mfma_f32_32x32x16_bf16 v[50:65], v[88:91], v[96:99], v[50:65]
	s_waitcnt vmcnt(7)
	ds_write_b128 v66, v[144:147] offset:55296
	s_waitcnt vmcnt(6)
	ds_write_b128 v66, v[124:127] offset:59904
	global_load_dwordx4 v[144:147], v[78:79], off offset:512
	global_load_dwordx4 v[124:127], v[80:81], off offset:512
	ds_read_b128 v[88:91], v70 offset:4672
	s_waitcnt lgkmcnt(0)
	v_mfma_f32_32x32x16_bf16 v[2:17], v[88:91], v[92:95], v[2:17]
	ds_read_b128 v[92:95], v1 offset:36960
	v_mfma_f32_32x32x16_bf16 v[18:33], v[88:91], v[96:99], v[18:33]
	ds_read_b128 v[88:91], v70 offset:96
	ds_read_b128 v[96:99], v1 offset:41568
	s_waitcnt lgkmcnt(1)
	v_mfma_f32_32x32x16_bf16 v[34:49], v[88:91], v[92:95], v[34:49]
	s_waitcnt lgkmcnt(0)
	v_mfma_f32_32x32x16_bf16 v[50:65], v[88:91], v[96:99], v[50:65]
	s_waitcnt vmcnt(7)
	ds_write_b128 v66, v[120:123] offset:64512
	s_waitcnt vmcnt(6)
	ds_write_b128 v71, v[116:119] offset:32256
	global_load_dwordx4 v[120:123], v[82:83], off offset:512
	global_load_dwordx4 v[116:119], v[84:85], off offset:512
	v_mfma_f32_32x32x16_bf16 v[2:17], v[100:103], v[92:95], v[2:17]
	v_mfma_f32_32x32x16_bf16 v[18:33], v[100:103], v[96:99], v[18:33]
	s_setprio 0
	s_waitcnt lgkmcnt(0)
	s_barrier
; #define MFMA(a, b, c) __builtin_amdgcn_mfma_f32_32x32x16_bf16((a), (b), (c), 0, 0, 0)
; template <int TM, int TN>
; DI void gemm_mainloop(const u16* __restrict__ A, long lda, const u16* __restrict__ Bt, long ldb, int K, char* smem,
;                       f32x16 (&acc)[TM][TN]) {
;     ...
;   for (int kt = 0; kt < nk; kt++) {
;     const int buf = kt & 1;
;     const u16* cA = sA + buf * BM * LD + (wm * 32 * TM + r) * LD + h * 8;
;     const u16* cB = sB + buf * BN * LD + (wn * 32 * TN + r) * LD + h * 8;
;     bf16x8 af[TM], bfr[TN];
; #pragma unroll
;     for (int tm = 0; tm < TM; tm++) af[tm] = *(const bf16x8*)(cA + tm * 32 * LD);
; #pragma unroll
;     for (int tn = 0; tn < TN; tn++) bfr[tn] = *(const bf16x8*)(cB + tn * 32 * LD);
;     if (kt + 1 < nk) GEMM_SSTORE(buf ^ 1)
;     __builtin_amdgcn_sched_barrier(0);
;     __builtin_amdgcn_s_setprio(1);
; #pragma unroll
;     for (int tm = 0; tm < TM; tm++)
; #pragma unroll
;       for (int tn = 0; tn < TN; tn++) acc[tm][tn] = MFMA(af[tm], bfr[tn], acc[tm][tn]);
; #pragma unroll
;     for (int tm = 0; tm < TM; tm++) af[tm] = *(const bf16x8*)(cA + tm * 32 * LD + 16);
; #pragma unroll
;     for (int tn = 0; tn < TN; tn++) bfr[tn] = *(const bf16x8*)(cB + tn * 32 * LD + 16);
; #pragma unroll
;     for (int tm = 0; tm < TM; tm++)
; #pragma unroll
;       for (int tn = 0; tn < TN; tn++) acc[tm][tn] = MFMA(af[tm], bfr[tn], acc[tm][tn]);
;     __builtin_amdgcn_sched_group_barrier(0x8, 4, 0);
;     if (kt + 2 < nk) GEMM_GLOAD((kt + 2) * 64)
; #pragma unroll
;     for (int ks = 2; ks < 4; ks++) {
; #pragma unroll
;       for (int tm = 0; tm < TM; tm++) af[tm] = *(const bf16x8*)(cA + tm * 32 * LD + ks * 16);
; #pragma unroll
;       for (int tn = 0; tn < TN; tn++) bfr[tn] = *(const bf16x8*)(cB + tn * 32 * LD + ks * 16);
; #pragma unroll
;       for (int tm = 0; tm < TM; tm++)
; #pragma unroll
;         for (int tn = 0; tn < TN; tn++) acc[tm][tn] = MFMA(af[tm], bfr[tn], acc[tm][tn]);
;     }
;     __builtin_amdgcn_s_setprio(0);
;     __syncthreads();
;   }
	ds_read_b128 v[96:99], v70 offset:18432
	ds_read_b128 v[100:103], v70 offset:23040
	ds_read_b128 v[128:131], v1 offset:55296
	ds_read_b128 v[132:135], v1 offset:59904
	s_setprio 1
	ds_read_b128 v[88:91], v70 offset:18464
	s_waitcnt lgkmcnt(2)
	v_mfma_f32_32x32x16_bf16 v[34:49], v[96:99], v[128:131], v[34:49]
	ds_read_b128 v[92:95], v1 offset:55328
	s_waitcnt lgkmcnt(2)
	v_mfma_f32_32x32x16_bf16 v[50:65], v[96:99], v[132:135], v[50:65]
	s_waitcnt vmcnt(7)
	ds_write_b128 v66, v[140:143]
	s_waitcnt vmcnt(6)
	ds_write_b128 v66, v[104:107] offset:4608
	global_load_dwordx4 v[140:143], v[74:75], off offset:640
	global_load_dwordx4 v[104:107], v[72:73], off offset:640
	ds_read_b128 v[96:99], v1 offset:59936
	s_waitcnt lgkmcnt(3)
	v_mfma_f32_32x32x16_bf16 v[34:49], v[88:91], v[92:95], v[34:49]
	s_waitcnt lgkmcnt(0)
	v_mfma_f32_32x32x16_bf16 v[50:65], v[88:91], v[96:99], v[50:65]
	ds_read_b128 v[88:91], v70 offset:23072
	v_mfma_f32_32x32x16_bf16 v[2:17], v[100:103], v[128:131], v[2:17]
	v_mfma_f32_32x32x16_bf16 v[18:33], v[100:103], v[132:135], v[18:33]
	s_waitcnt vmcnt(7)
	ds_write_b128 v66, v[108:111] offset:9216
	s_waitcnt vmcnt(6)
	ds_write_b128 v66, v[112:115] offset:13824
	global_load_dwordx4 v[108:111], v[76:77], off offset:640
	global_load_dwordx4 v[112:115], v[86:87], off offset:640
	ds_read_b128 v[100:103], v70 offset:23136
	s_waitcnt lgkmcnt(3)
	v_mfma_f32_32x32x16_bf16 v[2:17], v[88:91], v[92:95], v[2:17]
	ds_read_b128 v[92:95], v1 offset:55360
	v_mfma_f32_32x32x16_bf16 v[18:33], v[88:91], v[96:99], v[18:33]
	ds_read_b128 v[88:91], v70 offset:18496
	ds_read_b128 v[96:99], v1 offset:59968
	s_waitcnt lgkmcnt(1)
	v_mfma_f32_32x32x16_bf16 v[34:49], v[88:91], v[92:95], v[34:49]
	s_waitcnt lgkmcnt(0)
	v_mfma_f32_32x32x16_bf16 v[50:65], v[88:91], v[96:99], v[50:65]
	s_waitcnt vmcnt(7)
	ds_write_b128 v66, v[144:147] offset:36864
	s_waitcnt vmcnt(6)
	ds_write_b128 v66, v[124:127] offset:41472
	global_load_dwordx4 v[144:147], v[78:79], off offset:640
	global_load_dwordx4 v[124:127], v[80:81], off offset:640
	ds_read_b128 v[88:91], v70 offset:23104
	s_waitcnt lgkmcnt(0)
	v_mfma_f32_32x32x16_bf16 v[2:17], v[88:91], v[92:95], v[2:17]
	ds_read_b128 v[92:95], v1 offset:55392
	v_mfma_f32_32x32x16_bf16 v[18:33], v[88:91], v[96:99], v[18:33]
	ds_read_b128 v[88:91], v70 offset:18528
	ds_read_b128 v[96:99], v1 offset:60000
	s_waitcnt lgkmcnt(1)
	v_mfma_f32_32x32x16_bf16 v[34:49], v[88:91], v[92:95], v[34:49]
	s_waitcnt lgkmcnt(0)
	v_mfma_f32_32x32x16_bf16 v[50:65], v[88:91], v[96:99], v[50:65]
	s_waitcnt vmcnt(7)
	ds_write_b128 v66, v[120:123] offset:46080
	s_waitcnt vmcnt(6)
	ds_write_b128 v66, v[116:119] offset:50688
	global_load_dwordx4 v[120:123], v[82:83], off offset:640
	global_load_dwordx4 v[116:119], v[84:85], off offset:640
	v_mfma_f32_32x32x16_bf16 v[2:17], v[100:103], v[92:95], v[2:17]
	v_mfma_f32_32x32x16_bf16 v[18:33], v[100:103], v[96:99], v[18:33]
	s_setprio 0
	s_waitcnt lgkmcnt(0)
	s_barrier
	ds_read_b128 v[96:99], v70
	ds_read_b128 v[100:103], v70 offset:4608
	ds_read_b128 v[128:131], v1 offset:36864
	ds_read_b128 v[132:135], v1 offset:41472
	s_setprio 1
	ds_read_b128 v[88:91], v70 offset:32
	s_waitcnt lgkmcnt(2)
	v_mfma_f32_32x32x16_bf16 v[34:49], v[96:99], v[128:131], v[34:49]
	ds_read_b128 v[92:95], v1 offset:36896
	s_waitcnt lgkmcnt(2)
	v_mfma_f32_32x32x16_bf16 v[50:65], v[96:99], v[132:135], v[50:65]
	s_waitcnt vmcnt(7)
	ds_write_b128 v66, v[140:143] offset:18432
	s_waitcnt vmcnt(6)
	ds_write_b128 v66, v[104:107] offset:23040
	global_load_dwordx4 v[140:143], v[74:75], off offset:768
	global_load_dwordx4 v[104:107], v[72:73], off offset:768
	ds_read_b128 v[96:99], v1 offset:41504
	s_waitcnt lgkmcnt(3)
	v_mfma_f32_32x32x16_bf16 v[34:49], v[88:91], v[92:95], v[34:49]
	s_waitcnt lgkmcnt(0)
	v_mfma_f32_32x32x16_bf16 v[50:65], v[88:91], v[96:99], v[50:65]
	ds_read_b128 v[88:91], v70 offset:4640
	v_mfma_f32_32x32x16_bf16 v[2:17], v[100:103], v[128:131], v[2:17]
	v_mfma_f32_32x32x16_bf16 v[18:33], v[100:103], v[132:135], v[18:33]
	s_waitcnt vmcnt(7)
	ds_write_b128 v66, v[108:111] offset:27648
	s_waitcnt vmcnt(6)
	ds_write_b128 v66, v[112:115] offset:32256
	global_load_dwordx4 v[108:111], v[76:77], off offset:768
	global_load_dwordx4 v[112:115], v[86:87], off offset:768
	ds_read_b128 v[100:103], v70 offset:4704
	s_waitcnt lgkmcnt(3)
	v_mfma_f32_32x32x16_bf16 v[2:17], v[88:91], v[92:95], v[2:17]
	ds_read_b128 v[92:95], v1 offset:36928
	v_mfma_f32_32x32x16_bf16 v[18:33], v[88:91], v[96:99], v[18:33]
	ds_read_b128 v[88:91], v70 offset:64
	ds_read_b128 v[96:99], v1 offset:41536
	s_waitcnt lgkmcnt(1)
	v_mfma_f32_32x32x16_bf16 v[34:49], v[88:91], v[92:95], v[34:49]
	s_waitcnt lgkmcnt(0)
	v_mfma_f32_32x32x16_bf16 v[50:65], v[88:91], v[96:99], v[50:65]
	s_waitcnt vmcnt(7)
	ds_write_b128 v66, v[144:147] offset:55296
	s_waitcnt vmcnt(6)
	ds_write_b128 v66, v[124:127] offset:59904
	global_load_dwordx4 v[144:147], v[78:79], off offset:768
	global_load_dwordx4 v[124:127], v[80:81], off offset:768
	ds_read_b128 v[88:91], v70 offset:4672
	s_waitcnt lgkmcnt(0)
	v_mfma_f32_32x32x16_bf16 v[2:17], v[88:91], v[92:95], v[2:17]
	ds_read_b128 v[92:95], v1 offset:36960
	v_mfma_f32_32x32x16_bf16 v[18:33], v[88:91], v[96:99], v[18:33]
	ds_read_b128 v[88:91], v70 offset:96
	ds_read_b128 v[96:99], v1 offset:41568
	s_waitcnt lgkmcnt(1)
	v_mfma_f32_32x32x16_bf16 v[34:49], v[88:91], v[92:95], v[34:49]
	s_waitcnt lgkmcnt(0)
	v_mfma_f32_32x32x16_bf16 v[50:65], v[88:91], v[96:99], v[50:65]
	s_waitcnt vmcnt(7)
	ds_write_b128 v66, v[120:123] offset:64512
	s_waitcnt vmcnt(6)
	ds_write_b128 v71, v[116:119] offset:32256
	global_load_dwordx4 v[120:123], v[82:83], off offset:768
	global_load_dwordx4 v[116:119], v[84:85], off offset:768
	v_mfma_f32_32x32x16_bf16 v[2:17], v[100:103], v[92:95], v[2:17]
	v_mfma_f32_32x32x16_bf16 v[18:33], v[100:103], v[96:99], v[18:33]
	s_setprio 0
	s_waitcnt lgkmcnt(0)
	s_barrier
; #define MFMA(a, b, c) __builtin_amdgcn_mfma_f32_32x32x16_bf16((a), (b), (c), 0, 0, 0)
; template <int TM, int TN>
; DI void gemm_mainloop(const u16* __restrict__ A, long lda, const u16* __restrict__ Bt, long ldb, int K, char* smem,
;                       f32x16 (&acc)[TM][TN]) {
;     ...
;   for (int kt = 0; kt < nk; kt++) {
;     const int buf = kt & 1;
;     const u16* cA = sA + buf * BM * LD + (wm * 32 * TM + r) * LD + h * 8;
;     const u16* cB = sB + buf * BN * LD + (wn * 32 * TN + r) * LD + h * 8;
;     bf16x8 af[TM], bfr[TN];
; #pragma unroll
;     for (int tm = 0; tm < TM; tm++) af[tm] = *(const bf16x8*)(cA + tm * 32 * LD);
; #pragma unroll
;     for (int tn = 0; tn < TN; tn++) bfr[tn] = *(const bf16x8*)(cB + tn * 32 * LD);
;     if (kt + 1 < nk) GEMM_SSTORE(buf ^ 1)
;     __builtin_amdgcn_sched_barrier(0);
;     __builtin_amdgcn_s_setprio(1);
; #pragma unroll
;     for (int tm = 0; tm < TM; tm++)
; #pragma unroll
;       for (int tn = 0; tn < TN; tn++) acc[tm][tn] = MFMA(af[tm], bfr[tn], acc[tm][tn]);
; #pragma unroll
;     for (int tm = 0; tm < TM; tm++) af[tm] = *(const bf16x8*)(cA + tm * 32 * LD + 16);
; #pragma unroll
;     for (int tn = 0; tn < TN; tn++) bfr[tn] = *(const bf16x8*)(cB + tn * 32 * LD + 16);
; #pragma unroll
;     for (int tm = 0; tm < TM; tm++)
; #pragma unroll
;       for (int tn = 0; tn < TN; tn++) acc[tm][tn] = MFMA(af[tm], bfr[tn], acc[tm][tn]);
;     __builtin_amdgcn_sched_group_barrier(0x8, 4, 0);
;     if (kt + 2 < nk) GEMM_GLOAD((kt + 2) * 64)
; #pragma unroll
;     for (int ks = 2; ks < 4; ks++) {
; #pragma unroll
;       for (int tm = 0; tm < TM; tm++) af[tm] = *(const bf16x8*)(cA + tm * 32 * LD + ks * 16);
; #pragma unroll
;       for (int tn = 0; tn < TN; tn++) bfr[tn] = *(const bf16x8*)(cB + tn * 32 * LD + ks * 16);
; #pragma unroll
;       for (int tm = 0; tm < TM; tm++)
; #pragma unroll
;         for (int tn = 0; tn < TN; tn++) acc[tm][tn] = MFMA(af[tm], bfr[tn], acc[tm][tn]);
;     }
;     __builtin_amdgcn_s_setprio(0);
;     __syncthreads();
;   }
	ds_read_b128 v[96:99], v70 offset:18432
	ds_read_b128 v[100:103], v70 offset:23040
	ds_read_b128 v[128:131], v1 offset:55296
	ds_read_b128 v[132:135], v1 offset:59904
	s_setprio 1
	ds_read_b128 v[88:91], v70 offset:18464
	s_waitcnt lgkmcnt(2)
	v_mfma_f32_32x32x16_bf16 v[34:49], v[96:99], v[128:131], v[34:49]
	ds_read_b128 v[92:95], v1 offset:55328
	s_waitcnt lgkmcnt(2)
	v_mfma_f32_32x32x16_bf16 v[50:65], v[96:99], v[132:135], v[50:65]
	s_waitcnt vmcnt(7)
	ds_write_b128 v66, v[140:143]
	s_waitcnt vmcnt(6)
	ds_write_b128 v66, v[104:107] offset:4608
	global_load_dwordx4 v[140:143], v[74:75], off offset:896
	global_load_dwordx4 v[104:107], v[72:73], off offset:896
	ds_read_b128 v[96:99], v1 offset:59936
	s_waitcnt lgkmcnt(3)
	v_mfma_f32_32x32x16_bf16 v[34:49], v[88:91], v[92:95], v[34:49]
	s_waitcnt lgkmcnt(0)
	v_mfma_f32_32x32x16_bf16 v[50:65], v[88:91], v[96:99], v[50:65]
	ds_read_b128 v[88:91], v70 offset:23072
	v_mfma_f32_32x32x16_bf16 v[2:17], v[100:103], v[128:131], v[2:17]
	v_mfma_f32_32x32x16_bf16 v[18:33], v[100:103], v[132:135], v[18:33]
	s_waitcnt vmcnt(7)
	ds_write_b128 v66, v[108:111] offset:9216
	s_waitcnt vmcnt(6)
	ds_write_b128 v66, v[112:115] offset:13824
	global_load_dwordx4 v[108:111], v[76:77], off offset:896
	global_load_dwordx4 v[112:115], v[86:87], off offset:896
	ds_read_b128 v[100:103], v70 offset:23136
	s_waitcnt lgkmcnt(3)
	v_mfma_f32_32x32x16_bf16 v[2:17], v[88:91], v[92:95], v[2:17]
	ds_read_b128 v[92:95], v1 offset:55360
	v_mfma_f32_32x32x16_bf16 v[18:33], v[88:91], v[96:99], v[18:33]
	ds_read_b128 v[88:91], v70 offset:18496
	ds_read_b128 v[96:99], v1 offset:59968
	s_waitcnt lgkmcnt(1)
	v_mfma_f32_32x32x16_bf16 v[34:49], v[88:91], v[92:95], v[34:49]
	s_waitcnt lgkmcnt(0)
	v_mfma_f32_32x32x16_bf16 v[50:65], v[88:91], v[96:99], v[50:65]
	s_waitcnt vmcnt(7)
	ds_write_b128 v66, v[144:147] offset:36864
	s_waitcnt vmcnt(6)
	ds_write_b128 v66, v[124:127] offset:41472
	global_load_dwordx4 v[144:147], v[78:79], off offset:896
	global_load_dwordx4 v[124:127], v[80:81], off offset:896
	ds_read_b128 v[88:91], v70 offset:23104
	s_waitcnt lgkmcnt(0)
	v_mfma_f32_32x32x16_bf16 v[2:17], v[88:91], v[92:95], v[2:17]
	ds_read_b128 v[92:95], v1 offset:55392
	v_mfma_f32_32x32x16_bf16 v[18:33], v[88:91], v[96:99], v[18:33]
	ds_read_b128 v[88:91], v70 offset:18528
	ds_read_b128 v[96:99], v1 offset:60000
	s_waitcnt lgkmcnt(1)
	v_mfma_f32_32x32x16_bf16 v[34:49], v[88:91], v[92:95], v[34:49]
	s_waitcnt lgkmcnt(0)
	v_mfma_f32_32x32x16_bf16 v[50:65], v[88:91], v[96:99], v[50:65]
	s_waitcnt vmcnt(7)
	ds_write_b128 v66, v[120:123] offset:46080
	s_waitcnt vmcnt(6)
	ds_write_b128 v66, v[116:119] offset:50688
	global_load_dwordx4 v[120:123], v[82:83], off offset:896
	global_load_dwordx4 v[116:119], v[84:85], off offset:896
	v_mfma_f32_32x32x16_bf16 v[2:17], v[100:103], v[92:95], v[2:17]
	v_mfma_f32_32x32x16_bf16 v[18:33], v[100:103], v[96:99], v[18:33]
	s_setprio 0
	s_waitcnt lgkmcnt(0)
	s_barrier
	ds_read_b128 v[96:99], v70
	ds_read_b128 v[100:103], v70 offset:4608
	ds_read_b128 v[128:131], v1 offset:36864
	ds_read_b128 v[132:135], v1 offset:41472
	s_setprio 1
	ds_read_b128 v[88:91], v70 offset:32
	s_waitcnt lgkmcnt(2)
	v_mfma_f32_32x32x16_bf16 v[34:49], v[96:99], v[128:131], v[34:49]
	ds_read_b128 v[92:95], v1 offset:36896
	s_waitcnt lgkmcnt(2)
	v_mfma_f32_32x32x16_bf16 v[50:65], v[96:99], v[132:135], v[50:65]
	s_waitcnt vmcnt(7)
	ds_write_b128 v66, v[140:143] offset:18432
	s_waitcnt vmcnt(6)
	ds_write_b128 v66, v[104:107] offset:23040
	global_load_dwordx4 v[140:143], v[74:75], off offset:1024
	global_load_dwordx4 v[104:107], v[72:73], off offset:1024
	ds_read_b128 v[96:99], v1 offset:41504
	s_waitcnt lgkmcnt(3)
	v_mfma_f32_32x32x16_bf16 v[34:49], v[88:91], v[92:95], v[34:49]
	s_waitcnt lgkmcnt(0)
	v_mfma_f32_32x32x16_bf16 v[50:65], v[88:91], v[96:99], v[50:65]
	ds_read_b128 v[88:91], v70 offset:4640
	v_mfma_f32_32x32x16_bf16 v[2:17], v[100:103], v[128:131], v[2:17]
	v_mfma_f32_32x32x16_bf16 v[18:33], v[100:103], v[132:135], v[18:33]
	s_waitcnt vmcnt(7)
	ds_write_b128 v66, v[108:111] offset:27648
	s_waitcnt vmcnt(6)
	ds_write_b128 v66, v[112:115] offset:32256
	global_load_dwordx4 v[108:111], v[76:77], off offset:1024
	global_load_dwordx4 v[112:115], v[86:87], off offset:1024
	ds_read_b128 v[100:103], v70 offset:4704
	s_waitcnt lgkmcnt(3)
	v_mfma_f32_32x32x16_bf16 v[2:17], v[88:91], v[92:95], v[2:17]
	ds_read_b128 v[92:95], v1 offset:36928
	v_mfma_f32_32x32x16_bf16 v[18:33], v[88:91], v[96:99], v[18:33]
	ds_read_b128 v[88:91], v70 offset:64
	ds_read_b128 v[96:99], v1 offset:41536
	s_waitcnt lgkmcnt(1)
	v_mfma_f32_32x32x16_bf16 v[34:49], v[88:91], v[92:95], v[34:49]
	s_waitcnt lgkmcnt(0)
	v_mfma_f32_32x32x16_bf16 v[50:65], v[88:91], v[96:99], v[50:65]
	s_waitcnt vmcnt(7)
	ds_write_b128 v66, v[144:147] offset:55296
	s_waitcnt vmcnt(6)
	ds_write_b128 v66, v[124:127] offset:59904
	global_load_dwordx4 v[144:147], v[78:79], off offset:1024
	global_load_dwordx4 v[124:127], v[80:81], off offset:1024
	ds_read_b128 v[88:91], v70 offset:4672
	s_waitcnt lgkmcnt(0)
	v_mfma_f32_32x32x16_bf16 v[2:17], v[88:91], v[92:95], v[2:17]
	ds_read_b128 v[92:95], v1 offset:36960
	v_mfma_f32_32x32x16_bf16 v[18:33], v[88:91], v[96:99], v[18:33]
	ds_read_b128 v[88:91], v70 offset:96
	ds_read_b128 v[96:99], v1 offset:41568
	s_waitcnt lgkmcnt(1)
	v_mfma_f32_32x32x16_bf16 v[34:49], v[88:91], v[92:95], v[34:49]
	s_waitcnt lgkmcnt(0)
	v_mfma_f32_32x32x16_bf16 v[50:65], v[88:91], v[96:99], v[50:65]
	s_waitcnt vmcnt(7)
	ds_write_b128 v66, v[120:123] offset:64512
	s_waitcnt vmcnt(6)
	ds_write_b128 v71, v[116:119] offset:32256
	global_load_dwordx4 v[120:123], v[82:83], off offset:1024
	global_load_dwordx4 v[116:119], v[84:85], off offset:1024
	v_mfma_f32_32x32x16_bf16 v[2:17], v[100:103], v[92:95], v[2:17]
	v_mfma_f32_32x32x16_bf16 v[18:33], v[100:103], v[96:99], v[18:33]
	s_setprio 0
	s_waitcnt lgkmcnt(0)
	s_barrier
; #define MFMA(a, b, c) __builtin_amdgcn_mfma_f32_32x32x16_bf16((a), (b), (c), 0, 0, 0)
; template <int TM, int TN>
; DI void gemm_mainloop(const u16* __restrict__ A, long lda, const u16* __restrict__ Bt, long ldb, int K, char* smem,
;                       f32x16 (&acc)[TM][TN]) {
;     ...
;   for (int kt = 0; kt < nk; kt++) {
;     const int buf = kt & 1;
;     const u16* cA = sA + buf * BM * LD + (wm * 32 * TM + r) * LD + h * 8;
;     const u16* cB = sB + buf * BN * LD + (wn * 32 * TN + r) * LD + h * 8;
;     bf16x8 af[TM], bfr[TN];
; #pragma unroll
;     for (int tm = 0; tm < TM; tm++) af[tm] = *(const bf16x8*)(cA + tm * 32 * LD);
; #pragma unroll
;     for (int tn = 0; tn < TN; tn++) bfr[tn] = *(const bf16x8*)(cB + tn * 32 * LD);
;     if (kt + 1 < nk) GEMM_SSTORE(buf ^ 1)
;     __builtin_amdgcn_sched_barrier(0);
;     __builtin_amdgcn_s_setprio(1);
; #pragma unroll
;     for (int tm = 0; tm < TM; tm++)
; #pragma unroll
;       for (int tn = 0; tn < TN; tn++) acc[tm][tn] = MFMA(af[tm], bfr[tn], acc[tm][tn]);
; #pragma unroll
;     for (int tm = 0; tm < TM; tm++) af[tm] = *(const bf16x8*)(cA + tm * 32 * LD + 16);
; #pragma unroll
;     for (int tn = 0; tn < TN; tn++) bfr[tn] = *(const bf16x8*)(cB + tn * 32 * LD + 16);
; #pragma unroll
;     for (int tm = 0; tm < TM; tm++)
; #pragma unroll
;       for (int tn = 0; tn < TN; tn++) acc[tm][tn] = MFMA(af[tm], bfr[tn], acc[tm][tn]);
;     __builtin_amdgcn_sched_group_barrier(0x8, 4, 0);
;     if (kt + 2 < nk) GEMM_GLOAD((kt + 2) * 64)
; #pragma unroll
;     for (int ks = 2; ks < 4; ks++) {
; #pragma unroll
;       for (int tm = 0; tm < TM; tm++) af[tm] = *(const bf16x8*)(cA + tm * 32 * LD + ks * 16);
; #pragma unroll
;       for (int tn = 0; tn < TN; tn++) bfr[tn] = *(const bf16x8*)(cB + tn * 32 * LD + ks * 16);
; #pragma unroll
;       for (int tm = 0; tm < TM; tm++)
; #pragma unroll
;         for (int tn = 0; tn < TN; tn++) acc[tm][tn] = MFMA(af[tm], bfr[tn], acc[tm][tn]);
;     }
;     __builtin_amdgcn_s_setprio(0);
;     __syncthreads();
;   }
	ds_read_b128 v[96:99], v70 offset:18432
	ds_read_b128 v[100:103], v70 offset:23040
	ds_read_b128 v[128:131], v1 offset:55296
	ds_read_b128 v[132:135], v1 offset:59904
	s_setprio 1
	ds_read_b128 v[88:91], v70 offset:18464
	s_waitcnt lgkmcnt(2)
	v_mfma_f32_32x32x16_bf16 v[34:49], v[96:99], v[128:131], v[34:49]
	ds_read_b128 v[92:95], v1 offset:55328
	s_waitcnt lgkmcnt(2)
	v_mfma_f32_32x32x16_bf16 v[50:65], v[96:99], v[132:135], v[50:65]
	s_waitcnt vmcnt(7)
	ds_write_b128 v66, v[140:143]
	s_waitcnt vmcnt(6)
	ds_write_b128 v66, v[104:107] offset:4608
	global_load_dwordx4 v[140:143], v[74:75], off offset:1152
	global_load_dwordx4 v[104:107], v[72:73], off offset:1152
	ds_read_b128 v[96:99], v1 offset:59936
	s_waitcnt lgkmcnt(3)
	v_mfma_f32_32x32x16_bf16 v[34:49], v[88:91], v[92:95], v[34:49]
	s_waitcnt lgkmcnt(0)
	v_mfma_f32_32x32x16_bf16 v[50:65], v[88:91], v[96:99], v[50:65]
	ds_read_b128 v[88:91], v70 offset:23072
	v_mfma_f32_32x32x16_bf16 v[2:17], v[100:103], v[128:131], v[2:17]
	v_mfma_f32_32x32x16_bf16 v[18:33], v[100:103], v[132:135], v[18:33]
	s_waitcnt vmcnt(7)
	ds_write_b128 v66, v[108:111] offset:9216
	s_waitcnt vmcnt(6)
	ds_write_b128 v66, v[112:115] offset:13824
	global_load_dwordx4 v[108:111], v[76:77], off offset:1152
	global_load_dwordx4 v[112:115], v[86:87], off offset:1152
	ds_read_b128 v[100:103], v70 offset:23136
	s_waitcnt lgkmcnt(3)
	v_mfma_f32_32x32x16_bf16 v[2:17], v[88:91], v[92:95], v[2:17]
	ds_read_b128 v[92:95], v1 offset:55360
	v_mfma_f32_32x32x16_bf16 v[18:33], v[88:91], v[96:99], v[18:33]
	ds_read_b128 v[88:91], v70 offset:18496
	ds_read_b128 v[96:99], v1 offset:59968
	s_waitcnt lgkmcnt(1)
	v_mfma_f32_32x32x16_bf16 v[34:49], v[88:91], v[92:95], v[34:49]
	s_waitcnt lgkmcnt(0)
	v_mfma_f32_32x32x16_bf16 v[50:65], v[88:91], v[96:99], v[50:65]
	s_waitcnt vmcnt(7)
	ds_write_b128 v66, v[144:147] offset:36864
	s_waitcnt vmcnt(6)
	ds_write_b128 v66, v[124:127] offset:41472
	global_load_dwordx4 v[144:147], v[78:79], off offset:1152
	global_load_dwordx4 v[124:127], v[80:81], off offset:1152
	ds_read_b128 v[88:91], v70 offset:23104
	s_waitcnt lgkmcnt(0)
	v_mfma_f32_32x32x16_bf16 v[2:17], v[88:91], v[92:95], v[2:17]
	ds_read_b128 v[92:95], v1 offset:55392
	v_mfma_f32_32x32x16_bf16 v[18:33], v[88:91], v[96:99], v[18:33]
	ds_read_b128 v[88:91], v70 offset:18528
	ds_read_b128 v[96:99], v1 offset:60000
	s_waitcnt lgkmcnt(1)
	v_mfma_f32_32x32x16_bf16 v[34:49], v[88:91], v[92:95], v[34:49]
	s_waitcnt lgkmcnt(0)
	v_mfma_f32_32x32x16_bf16 v[50:65], v[88:91], v[96:99], v[50:65]
	s_waitcnt vmcnt(7)
	ds_write_b128 v66, v[120:123] offset:46080
	s_waitcnt vmcnt(6)
	ds_write_b128 v66, v[116:119] offset:50688
	global_load_dwordx4 v[120:123], v[82:83], off offset:1152
	global_load_dwordx4 v[116:119], v[84:85], off offset:1152
	v_mfma_f32_32x32x16_bf16 v[2:17], v[100:103], v[92:95], v[2:17]
	v_mfma_f32_32x32x16_bf16 v[18:33], v[100:103], v[96:99], v[18:33]
	s_setprio 0
	s_waitcnt lgkmcnt(0)
	s_barrier
	ds_read_b128 v[96:99], v70
	ds_read_b128 v[100:103], v70 offset:4608
	ds_read_b128 v[128:131], v1 offset:36864
	ds_read_b128 v[132:135], v1 offset:41472
	s_setprio 1
	ds_read_b128 v[88:91], v70 offset:32
	s_waitcnt lgkmcnt(2)
	v_mfma_f32_32x32x16_bf16 v[34:49], v[96:99], v[128:131], v[34:49]
	ds_read_b128 v[92:95], v1 offset:36896
	s_waitcnt lgkmcnt(2)
	v_mfma_f32_32x32x16_bf16 v[50:65], v[96:99], v[132:135], v[50:65]
	s_waitcnt vmcnt(7)
	ds_write_b128 v66, v[140:143] offset:18432
	s_waitcnt vmcnt(6)
	ds_write_b128 v66, v[104:107] offset:23040
	global_load_dwordx4 v[140:143], v[74:75], off offset:1280
	global_load_dwordx4 v[104:107], v[72:73], off offset:1280
	ds_read_b128 v[96:99], v1 offset:41504
	s_waitcnt lgkmcnt(3)
	v_mfma_f32_32x32x16_bf16 v[34:49], v[88:91], v[92:95], v[34:49]
	s_waitcnt lgkmcnt(0)
	v_mfma_f32_32x32x16_bf16 v[50:65], v[88:91], v[96:99], v[50:65]
	ds_read_b128 v[88:91], v70 offset:4640
	v_mfma_f32_32x32x16_bf16 v[2:17], v[100:103], v[128:131], v[2:17]
	v_mfma_f32_32x32x16_bf16 v[18:33], v[100:103], v[132:135], v[18:33]
	s_waitcnt vmcnt(7)
	ds_write_b128 v66, v[108:111] offset:27648
	s_waitcnt vmcnt(6)
	ds_write_b128 v66, v[112:115] offset:32256
	global_load_dwordx4 v[108:111], v[76:77], off offset:1280
	global_load_dwordx4 v[112:115], v[86:87], off offset:1280
	ds_read_b128 v[100:103], v70 offset:4704
	s_waitcnt lgkmcnt(3)
	v_mfma_f32_32x32x16_bf16 v[2:17], v[88:91], v[92:95], v[2:17]
	ds_read_b128 v[92:95], v1 offset:36928
	v_mfma_f32_32x32x16_bf16 v[18:33], v[88:91], v[96:99], v[18:33]
	ds_read_b128 v[88:91], v70 offset:64
	ds_read_b128 v[96:99], v1 offset:41536
	s_waitcnt lgkmcnt(1)
	v_mfma_f32_32x32x16_bf16 v[34:49], v[88:91], v[92:95], v[34:49]
	s_waitcnt lgkmcnt(0)
	v_mfma_f32_32x32x16_bf16 v[50:65], v[88:91], v[96:99], v[50:65]
	s_waitcnt vmcnt(7)
	ds_write_b128 v66, v[144:147] offset:55296
	s_waitcnt vmcnt(6)
	ds_write_b128 v66, v[124:127] offset:59904
	global_load_dwordx4 v[144:147], v[78:79], off offset:1280
	global_load_dwordx4 v[124:127], v[80:81], off offset:1280
	ds_read_b128 v[88:91], v70 offset:4672
	s_waitcnt lgkmcnt(0)
	v_mfma_f32_32x32x16_bf16 v[2:17], v[88:91], v[92:95], v[2:17]
	ds_read_b128 v[92:95], v1 offset:36960
	v_mfma_f32_32x32x16_bf16 v[18:33], v[88:91], v[96:99], v[18:33]
	ds_read_b128 v[88:91], v70 offset:96
	ds_read_b128 v[96:99], v1 offset:41568
	s_waitcnt lgkmcnt(1)
	v_mfma_f32_32x32x16_bf16 v[34:49], v[88:91], v[92:95], v[34:49]
	s_waitcnt lgkmcnt(0)
	v_mfma_f32_32x32x16_bf16 v[50:65], v[88:91], v[96:99], v[50:65]
	s_waitcnt vmcnt(7)
	ds_write_b128 v66, v[120:123] offset:64512
	s_waitcnt vmcnt(6)
	ds_write_b128 v71, v[116:119] offset:32256
	global_load_dwordx4 v[120:123], v[82:83], off offset:1280
	global_load_dwordx4 v[116:119], v[84:85], off offset:1280
	v_mfma_f32_32x32x16_bf16 v[2:17], v[100:103], v[92:95], v[2:17]
	v_mfma_f32_32x32x16_bf16 v[18:33], v[100:103], v[96:99], v[18:33]
	s_setprio 0
	s_waitcnt lgkmcnt(0)
	s_barrier
; #define MFMA(a, b, c) __builtin_amdgcn_mfma_f32_32x32x16_bf16((a), (b), (c), 0, 0, 0)
; template <int TM, int TN>
; DI void gemm_mainloop(const u16* __restrict__ A, long lda, const u16* __restrict__ Bt, long ldb, int K, char* smem,
;                       f32x16 (&acc)[TM][TN]) {
;     ...
;   for (int kt = 0; kt < nk; kt++) {
;     const int buf = kt & 1;
;     const u16* cA = sA + buf * BM * LD + (wm * 32 * TM + r) * LD + h * 8;
;     const u16* cB = sB + buf * BN * LD + (wn * 32 * TN + r) * LD + h * 8;
;     bf16x8 af[TM], bfr[TN];
; #pragma unroll
;     for (int tm = 0; tm < TM; tm++) af[tm] = *(const bf16x8*)(cA + tm * 32 * LD);
; #pragma unroll
;     for (int tn = 0; tn < TN; tn++) bfr[tn] = *(const bf16x8*)(cB + tn * 32 * LD);
;     if (kt + 1 < nk) GEMM_SSTORE(buf ^ 1)
;     __builtin_amdgcn_sched_barrier(0);
;     __builtin_amdgcn_s_setprio(1);
; #pragma unroll
;     for (int tm = 0; tm < TM; tm++)
; #pragma unroll
;       for (int tn = 0; tn < TN; tn++) acc[tm][tn] = MFMA(af[tm], bfr[tn], acc[tm][tn]);
; #pragma unroll
;     for (int tm = 0; tm < TM; tm++) af[tm] = *(const bf16x8*)(cA + tm * 32 * LD + 16);
; #pragma unroll
;     for (int tn = 0; tn < TN; tn++) bfr[tn] = *(const bf16x8*)(cB + tn * 32 * LD + 16);
; #pragma unroll
;     for (int tm = 0; tm < TM; tm++)
; #pragma unroll
;       for (int tn = 0; tn < TN; tn++) acc[tm][tn] = MFMA(af[tm], bfr[tn], acc[tm][tn]);
;     __builtin_amdgcn_sched_group_barrier(0x8, 4, 0);
;     if (kt + 2 < nk) GEMM_GLOAD((kt + 2) * 64)
; #pragma unroll
;     for (int ks = 2; ks < 4; ks++) {
; #pragma unroll
;       for (int tm = 0; tm < TM; tm++) af[tm] = *(const bf16x8*)(cA + tm * 32 * LD + ks * 16);
; #pragma unroll
;       for (int tn = 0; tn < TN; tn++) bfr[tn] = *(const bf16x8*)(cB + tn * 32 * LD + ks * 16);
; #pragma unroll
;       for (int tm = 0; tm < TM; tm++)
; #pragma unroll
;         for (int tn = 0; tn < TN; tn++) acc[tm][tn] = MFMA(af[tm], bfr[tn], acc[tm][tn]);
;     }
;     __builtin_amdgcn_s_setprio(0);
;     __syncthreads();
;   }
	ds_read_b128 v[96:99], v70 offset:18432
	ds_read_b128 v[100:103], v70 offset:23040
	ds_read_b128 v[128:131], v1 offset:55296
	ds_read_b128 v[132:135], v1 offset:59904
	s_setprio 1
	ds_read_b128 v[88:91], v70 offset:18464
	s_waitcnt lgkmcnt(2)
	v_mfma_f32_32x32x16_bf16 v[34:49], v[96:99], v[128:131], v[34:49]
	ds_read_b128 v[92:95], v1 offset:55328
	s_waitcnt lgkmcnt(2)
	v_mfma_f32_32x32x16_bf16 v[50:65], v[96:99], v[132:135], v[50:65]
	s_waitcnt vmcnt(7)
	ds_write_b128 v66, v[140:143]
	s_waitcnt vmcnt(6)
	ds_write_b128 v66, v[104:107] offset:4608
	global_load_dwordx4 v[140:143], v[74:75], off offset:1408
	global_load_dwordx4 v[104:107], v[72:73], off offset:1408
	ds_read_b128 v[96:99], v1 offset:59936
	s_waitcnt lgkmcnt(3)
	v_mfma_f32_32x32x16_bf16 v[34:49], v[88:91], v[92:95], v[34:49]
	s_waitcnt lgkmcnt(0)
	v_mfma_f32_32x32x16_bf16 v[50:65], v[88:91], v[96:99], v[50:65]
	ds_read_b128 v[88:91], v70 offset:23072
	v_mfma_f32_32x32x16_bf16 v[2:17], v[100:103], v[128:131], v[2:17]
	v_mfma_f32_32x32x16_bf16 v[18:33], v[100:103], v[132:135], v[18:33]
	s_waitcnt vmcnt(7)
	ds_write_b128 v66, v[108:111] offset:9216
	s_waitcnt vmcnt(6)
	ds_write_b128 v66, v[112:115] offset:13824
	global_load_dwordx4 v[108:111], v[76:77], off offset:1408
	global_load_dwordx4 v[112:115], v[86:87], off offset:1408
	ds_read_b128 v[100:103], v70 offset:23136
	s_waitcnt lgkmcnt(3)
	v_mfma_f32_32x32x16_bf16 v[2:17], v[88:91], v[92:95], v[2:17]
	ds_read_b128 v[92:95], v1 offset:55360
	v_mfma_f32_32x32x16_bf16 v[18:33], v[88:91], v[96:99], v[18:33]
	ds_read_b128 v[88:91], v70 offset:18496
	ds_read_b128 v[96:99], v1 offset:59968
	s_waitcnt lgkmcnt(1)
	v_mfma_f32_32x32x16_bf16 v[34:49], v[88:91], v[92:95], v[34:49]
	s_waitcnt lgkmcnt(0)
	v_mfma_f32_32x32x16_bf16 v[50:65], v[88:91], v[96:99], v[50:65]
	s_waitcnt vmcnt(7)
	ds_write_b128 v66, v[144:147] offset:36864
	s_waitcnt vmcnt(6)
	ds_write_b128 v66, v[124:127] offset:41472
	global_load_dwordx4 v[144:147], v[78:79], off offset:1408
	global_load_dwordx4 v[124:127], v[80:81], off offset:1408
	ds_read_b128 v[88:91], v70 offset:23104
	s_waitcnt lgkmcnt(0)
	v_mfma_f32_32x32x16_bf16 v[2:17], v[88:91], v[92:95], v[2:17]
	ds_read_b128 v[92:95], v1 offset:55392
	v_mfma_f32_32x32x16_bf16 v[18:33], v[88:91], v[96:99], v[18:33]
	ds_read_b128 v[88:91], v70 offset:18528
	ds_read_b128 v[96:99], v1 offset:60000
	s_waitcnt lgkmcnt(1)
	v_mfma_f32_32x32x16_bf16 v[34:49], v[88:91], v[92:95], v[34:49]
	s_waitcnt lgkmcnt(0)
	v_mfma_f32_32x32x16_bf16 v[50:65], v[88:91], v[96:99], v[50:65]
	s_waitcnt vmcnt(7)
	ds_write_b128 v66, v[120:123] offset:46080
	s_waitcnt vmcnt(6)
	ds_write_b128 v66, v[116:119] offset:50688
	global_load_dwordx4 v[120:123], v[82:83], off offset:1408
	global_load_dwordx4 v[116:119], v[84:85], off offset:1408
	v_mfma_f32_32x32x16_bf16 v[2:17], v[100:103], v[92:95], v[2:17]
	v_mfma_f32_32x32x16_bf16 v[18:33], v[100:103], v[96:99], v[18:33]
	s_setprio 0
	s_waitcnt lgkmcnt(0)
	s_barrier
	ds_read_b128 v[96:99], v70
	ds_read_b128 v[100:103], v70 offset:4608
	ds_read_b128 v[128:131], v1 offset:36864
	ds_read_b128 v[132:135], v1 offset:41472
	s_setprio 1
	ds_read_b128 v[88:91], v70 offset:32
	s_waitcnt lgkmcnt(2)
	v_mfma_f32_32x32x16_bf16 v[34:49], v[96:99], v[128:131], v[34:49]
	ds_read_b128 v[92:95], v1 offset:36896
	s_waitcnt lgkmcnt(2)
	v_mfma_f32_32x32x16_bf16 v[50:65], v[96:99], v[132:135], v[50:65]
	s_waitcnt vmcnt(7)
	ds_write_b128 v66, v[140:143] offset:18432
	s_waitcnt vmcnt(6)
	ds_write_b128 v66, v[104:107] offset:23040
	global_load_dwordx4 v[140:143], v[74:75], off offset:1536
	global_load_dwordx4 v[104:107], v[72:73], off offset:1536
	ds_read_b128 v[96:99], v1 offset:41504
	s_waitcnt lgkmcnt(3)
	v_mfma_f32_32x32x16_bf16 v[34:49], v[88:91], v[92:95], v[34:49]
	s_waitcnt lgkmcnt(0)
	v_mfma_f32_32x32x16_bf16 v[50:65], v[88:91], v[96:99], v[50:65]
	ds_read_b128 v[88:91], v70 offset:4640
	v_mfma_f32_32x32x16_bf16 v[2:17], v[100:103], v[128:131], v[2:17]
	v_mfma_f32_32x32x16_bf16 v[18:33], v[100:103], v[132:135], v[18:33]
	s_waitcnt vmcnt(7)
	ds_write_b128 v66, v[108:111] offset:27648
	s_waitcnt vmcnt(6)
	ds_write_b128 v66, v[112:115] offset:32256
	global_load_dwordx4 v[108:111], v[76:77], off offset:1536
	global_load_dwordx4 v[112:115], v[86:87], off offset:1536
	ds_read_b128 v[100:103], v70 offset:4704
	s_waitcnt lgkmcnt(3)
	v_mfma_f32_32x32x16_bf16 v[2:17], v[88:91], v[92:95], v[2:17]
	ds_read_b128 v[92:95], v1 offset:36928
	v_mfma_f32_32x32x16_bf16 v[18:33], v[88:91], v[96:99], v[18:33]
	ds_read_b128 v[88:91], v70 offset:64
	ds_read_b128 v[96:99], v1 offset:41536
	s_waitcnt lgkmcnt(1)
	v_mfma_f32_32x32x16_bf16 v[34:49], v[88:91], v[92:95], v[34:49]
	s_waitcnt lgkmcnt(0)
	v_mfma_f32_32x32x16_bf16 v[50:65], v[88:91], v[96:99], v[50:65]
	s_waitcnt vmcnt(7)
	ds_write_b128 v66, v[144:147] offset:55296
	s_waitcnt vmcnt(6)
	ds_write_b128 v66, v[124:127] offset:59904
	global_load_dwordx4 v[144:147], v[78:79], off offset:1536
	global_load_dwordx4 v[124:127], v[80:81], off offset:1536
	ds_read_b128 v[88:91], v70 offset:4672
	s_waitcnt lgkmcnt(0)
	v_mfma_f32_32x32x16_bf16 v[2:17], v[88:91], v[92:95], v[2:17]
	ds_read_b128 v[92:95], v1 offset:36960
	v_mfma_f32_32x32x16_bf16 v[18:33], v[88:91], v[96:99], v[18:33]
	ds_read_b128 v[88:91], v70 offset:96
	ds_read_b128 v[96:99], v1 offset:41568
	s_waitcnt lgkmcnt(1)
	v_mfma_f32_32x32x16_bf16 v[34:49], v[88:91], v[92:95], v[34:49]
	s_waitcnt lgkmcnt(0)
	v_mfma_f32_32x32x16_bf16 v[50:65], v[88:91], v[96:99], v[50:65]
	s_waitcnt vmcnt(7)
	ds_write_b128 v66, v[120:123] offset:64512
	s_waitcnt vmcnt(6)
	ds_write_b128 v71, v[116:119] offset:32256
	global_load_dwordx4 v[120:123], v[82:83], off offset:1536
	global_load_dwordx4 v[116:119], v[84:85], off offset:1536
	v_mfma_f32_32x32x16_bf16 v[2:17], v[100:103], v[92:95], v[2:17]
	v_mfma_f32_32x32x16_bf16 v[18:33], v[100:103], v[96:99], v[18:33]
	s_setprio 0
	s_waitcnt lgkmcnt(0)
	s_barrier
; #define MFMA(a, b, c) __builtin_amdgcn_mfma_f32_32x32x16_bf16((a), (b), (c), 0, 0, 0)
; template <int TM, int TN>
; DI void gemm_mainloop(const u16* __restrict__ A, long lda, const u16* __restrict__ Bt, long ldb, int K, char* smem,
;                       f32x16 (&acc)[TM][TN]) {
;     ...
;   for (int kt = 0; kt < nk; kt++) {
;     const int buf = kt & 1;
;     const u16* cA = sA + buf * BM * LD + (wm * 32 * TM + r) * LD + h * 8;
;     const u16* cB = sB + buf * BN * LD + (wn * 32 * TN + r) * LD + h * 8;
;     bf16x8 af[TM], bfr[TN];
; #pragma unroll
;     for (int tm = 0; tm < TM; tm++) af[tm] = *(const bf16x8*)(cA + tm * 32 * LD);
; #pragma unroll
;     for (int tn = 0; tn < TN; tn++) bfr[tn] = *(const bf16x8*)(cB + tn * 32 * LD);
;     if (kt + 1 < nk) GEMM_SSTORE(buf ^ 1)
;     __builtin_amdgcn_sched_barrier(0);
;     __builtin_amdgcn_s_setprio(1);
; #pragma unroll
;     for (int tm = 0; tm < TM; tm++)
; #pragma unroll
;       for (int tn = 0; tn < TN; tn++) acc[tm][tn] = MFMA(af[tm], bfr[tn], acc[tm][tn]);
; #pragma unroll
;     for (int tm = 0; tm < TM; tm++) af[tm] = *(const bf16x8*)(cA + tm * 32 * LD + 16);
; #pragma unroll
;     for (int tn = 0; tn < TN; tn++) bfr[tn] = *(const bf16x8*)(cB + tn * 32 * LD + 16);
; #pragma unroll
;     for (int tm = 0; tm < TM; tm++)
; #pragma unroll
;       for (int tn = 0; tn < TN; tn++) acc[tm][tn] = MFMA(af[tm], bfr[tn], acc[tm][tn]);
;     __builtin_amdgcn_sched_group_barrier(0x8, 4, 0);
;     if (kt + 2 < nk) GEMM_GLOAD((kt + 2) * 64)
; #pragma unroll
;     for (int ks = 2; ks < 4; ks++) {
; #pragma unroll
;       for (int tm = 0; tm < TM; tm++) af[tm] = *(const bf16x8*)(cA + tm * 32 * LD + ks * 16);
; #pragma unroll
;       for (int tn = 0; tn < TN; tn++) bfr[tn] = *(const bf16x8*)(cB + tn * 32 * LD + ks * 16);
; #pragma unroll
;       for (int tm = 0; tm < TM; tm++)
; #pragma unroll
;         for (int tn = 0; tn < TN; tn++) acc[tm][tn] = MFMA(af[tm], bfr[tn], acc[tm][tn]);
;     }
;     __builtin_amdgcn_s_setprio(0);
;     __syncthreads();
;   }
	ds_read_b128 v[96:99], v70 offset:18432
	ds_read_b128 v[100:103], v70 offset:23040
	ds_read_b128 v[128:131], v1 offset:55296
	ds_read_b128 v[132:135], v1 offset:59904
	s_setprio 1
	ds_read_b128 v[88:91], v70 offset:18464
	s_waitcnt lgkmcnt(2)
	v_mfma_f32_32x32x16_bf16 v[34:49], v[96:99], v[128:131], v[34:49]
	ds_read_b128 v[92:95], v1 offset:55328
	s_waitcnt lgkmcnt(2)
	v_mfma_f32_32x32x16_bf16 v[50:65], v[96:99], v[132:135], v[50:65]
	s_waitcnt vmcnt(7)
	ds_write_b128 v66, v[140:143]
	s_waitcnt vmcnt(6)
	ds_write_b128 v66, v[104:107] offset:4608
	global_load_dwordx4 v[140:143], v[74:75], off offset:1664
	global_load_dwordx4 v[104:107], v[72:73], off offset:1664
	ds_read_b128 v[96:99], v1 offset:59936
	s_waitcnt lgkmcnt(3)
	v_mfma_f32_32x32x16_bf16 v[34:49], v[88:91], v[92:95], v[34:49]
	s_waitcnt lgkmcnt(0)
	v_mfma_f32_32x32x16_bf16 v[50:65], v[88:91], v[96:99], v[50:65]
	ds_read_b128 v[88:91], v70 offset:23072
	v_mfma_f32_32x32x16_bf16 v[2:17], v[100:103], v[128:131], v[2:17]
	v_mfma_f32_32x32x16_bf16 v[18:33], v[100:103], v[132:135], v[18:33]
	s_waitcnt vmcnt(7)
	ds_write_b128 v66, v[108:111] offset:9216
	s_waitcnt vmcnt(6)
	ds_write_b128 v66, v[112:115] offset:13824
	global_load_dwordx4 v[108:111], v[76:77], off offset:1664
	global_load_dwordx4 v[112:115], v[86:87], off offset:1664
	ds_read_b128 v[100:103], v70 offset:23136
	s_waitcnt lgkmcnt(3)
	v_mfma_f32_32x32x16_bf16 v[2:17], v[88:91], v[92:95], v[2:17]
	ds_read_b128 v[92:95], v1 offset:55360
	v_mfma_f32_32x32x16_bf16 v[18:33], v[88:91], v[96:99], v[18:33]
	ds_read_b128 v[88:91], v70 offset:18496
	ds_read_b128 v[96:99], v1 offset:59968
	s_waitcnt lgkmcnt(1)
	v_mfma_f32_32x32x16_bf16 v[34:49], v[88:91], v[92:95], v[34:49]
	s_waitcnt lgkmcnt(0)
	v_mfma_f32_32x32x16_bf16 v[50:65], v[88:91], v[96:99], v[50:65]
	s_waitcnt vmcnt(7)
	ds_write_b128 v66, v[144:147] offset:36864
	s_waitcnt vmcnt(6)
	ds_write_b128 v66, v[124:127] offset:41472
	global_load_dwordx4 v[144:147], v[78:79], off offset:1664
	global_load_dwordx4 v[124:127], v[80:81], off offset:1664
	ds_read_b128 v[88:91], v70 offset:23104
	s_waitcnt lgkmcnt(0)
	v_mfma_f32_32x32x16_bf16 v[2:17], v[88:91], v[92:95], v[2:17]
	ds_read_b128 v[92:95], v1 offset:55392
	v_mfma_f32_32x32x16_bf16 v[18:33], v[88:91], v[96:99], v[18:33]
	ds_read_b128 v[88:91], v70 offset:18528
	ds_read_b128 v[96:99], v1 offset:60000
	s_waitcnt lgkmcnt(1)
	v_mfma_f32_32x32x16_bf16 v[34:49], v[88:91], v[92:95], v[34:49]
	s_waitcnt lgkmcnt(0)
	v_mfma_f32_32x32x16_bf16 v[50:65], v[88:91], v[96:99], v[50:65]
	s_waitcnt vmcnt(7)
	ds_write_b128 v66, v[120:123] offset:46080
	s_waitcnt vmcnt(6)
	ds_write_b128 v66, v[116:119] offset:50688
	global_load_dwordx4 v[120:123], v[82:83], off offset:1664
	global_load_dwordx4 v[116:119], v[84:85], off offset:1664
	v_mfma_f32_32x32x16_bf16 v[2:17], v[100:103], v[92:95], v[2:17]
	v_mfma_f32_32x32x16_bf16 v[18:33], v[100:103], v[96:99], v[18:33]
	s_setprio 0
	s_waitcnt lgkmcnt(0)
	s_barrier
	ds_read_b128 v[96:99], v70
	ds_read_b128 v[100:103], v70 offset:4608
	ds_read_b128 v[128:131], v1 offset:36864
	ds_read_b128 v[132:135], v1 offset:41472
	s_setprio 1
	ds_read_b128 v[88:91], v70 offset:32
	s_waitcnt lgkmcnt(2)
	v_mfma_f32_32x32x16_bf16 v[34:49], v[96:99], v[128:131], v[34:49]
	ds_read_b128 v[92:95], v1 offset:36896
	s_waitcnt lgkmcnt(2)
	v_mfma_f32_32x32x16_bf16 v[50:65], v[96:99], v[132:135], v[50:65]
	s_waitcnt vmcnt(7)
	ds_write_b128 v66, v[140:143] offset:18432
	s_waitcnt vmcnt(6)
	ds_write_b128 v66, v[104:107] offset:23040
	global_load_dwordx4 v[140:143], v[74:75], off offset:1792
	global_load_dwordx4 v[104:107], v[72:73], off offset:1792
	ds_read_b128 v[96:99], v1 offset:41504
	s_waitcnt lgkmcnt(3)
	v_mfma_f32_32x32x16_bf16 v[34:49], v[88:91], v[92:95], v[34:49]
	s_waitcnt lgkmcnt(0)
	v_mfma_f32_32x32x16_bf16 v[50:65], v[88:91], v[96:99], v[50:65]
	ds_read_b128 v[88:91], v70 offset:4640
	v_mfma_f32_32x32x16_bf16 v[2:17], v[100:103], v[128:131], v[2:17]
	v_mfma_f32_32x32x16_bf16 v[18:33], v[100:103], v[132:135], v[18:33]
	s_waitcnt vmcnt(7)
	ds_write_b128 v66, v[108:111] offset:27648
	s_waitcnt vmcnt(6)
	ds_write_b128 v66, v[112:115] offset:32256
	global_load_dwordx4 v[108:111], v[76:77], off offset:1792
	global_load_dwordx4 v[112:115], v[86:87], off offset:1792
	ds_read_b128 v[100:103], v70 offset:4704
	s_waitcnt lgkmcnt(3)
	v_mfma_f32_32x32x16_bf16 v[2:17], v[88:91], v[92:95], v[2:17]
	ds_read_b128 v[92:95], v1 offset:36928
	v_mfma_f32_32x32x16_bf16 v[18:33], v[88:91], v[96:99], v[18:33]
	ds_read_b128 v[88:91], v70 offset:64
	ds_read_b128 v[96:99], v1 offset:41536
	s_waitcnt lgkmcnt(1)
	v_mfma_f32_32x32x16_bf16 v[34:49], v[88:91], v[92:95], v[34:49]
	s_waitcnt lgkmcnt(0)
	v_mfma_f32_32x32x16_bf16 v[50:65], v[88:91], v[96:99], v[50:65]
	s_waitcnt vmcnt(7)
	ds_write_b128 v66, v[144:147] offset:55296
	s_waitcnt vmcnt(6)
	ds_write_b128 v66, v[124:127] offset:59904
	global_load_dwordx4 v[144:147], v[78:79], off offset:1792
	global_load_dwordx4 v[124:127], v[80:81], off offset:1792
	ds_read_b128 v[88:91], v70 offset:4672
	s_waitcnt lgkmcnt(0)
	v_mfma_f32_32x32x16_bf16 v[2:17], v[88:91], v[92:95], v[2:17]
	ds_read_b128 v[92:95], v1 offset:36960
	v_mfma_f32_32x32x16_bf16 v[18:33], v[88:91], v[96:99], v[18:33]
	ds_read_b128 v[88:91], v70 offset:96
	ds_read_b128 v[96:99], v1 offset:41568
	s_waitcnt lgkmcnt(1)
	v_mfma_f32_32x32x16_bf16 v[34:49], v[88:91], v[92:95], v[34:49]
	s_waitcnt lgkmcnt(0)
	v_mfma_f32_32x32x16_bf16 v[50:65], v[88:91], v[96:99], v[50:65]
	s_waitcnt vmcnt(7)
	ds_write_b128 v66, v[120:123] offset:64512
	s_waitcnt vmcnt(6)
	ds_write_b128 v71, v[116:119] offset:32256
	global_load_dwordx4 v[120:123], v[82:83], off offset:1792
	global_load_dwordx4 v[116:119], v[84:85], off offset:1792
	v_mfma_f32_32x32x16_bf16 v[2:17], v[100:103], v[92:95], v[2:17]
	v_mfma_f32_32x32x16_bf16 v[18:33], v[100:103], v[96:99], v[18:33]
	s_setprio 0
	s_waitcnt lgkmcnt(0)
	s_barrier
; #define MFMA(a, b, c) __builtin_amdgcn_mfma_f32_32x32x16_bf16((a), (b), (c), 0, 0, 0)
; template <int TM, int TN>
; DI void gemm_mainloop(const u16* __restrict__ A, long lda, const u16* __restrict__ Bt, long ldb, int K, char* smem,
;                       f32x16 (&acc)[TM][TN]) {
;     ...
;   for (int kt = 0; kt < nk; kt++) {
;     const int buf = kt & 1;
;     const u16* cA = sA + buf * BM * LD + (wm * 32 * TM + r) * LD + h * 8;
;     const u16* cB = sB + buf * BN * LD + (wn * 32 * TN + r) * LD + h * 8;
;     bf16x8 af[TM], bfr[TN];
; #pragma unroll
;     for (int tm = 0; tm < TM; tm++) af[tm] = *(const bf16x8*)(cA + tm * 32 * LD);
; #pragma unroll
;     for (int tn = 0; tn < TN; tn++) bfr[tn] = *(const bf16x8*)(cB + tn * 32 * LD);
;     if (kt + 1 < nk) GEMM_SSTORE(buf ^ 1)
;     __builtin_amdgcn_sched_barrier(0);
;     __builtin_amdgcn_s_setprio(1);
; #pragma unroll
;     for (int tm = 0; tm < TM; tm++)
; #pragma unroll
;       for (int tn = 0; tn < TN; tn++) acc[tm][tn] = MFMA(af[tm], bfr[tn], acc[tm][tn]);
; #pragma unroll
;     for (int tm = 0; tm < TM; tm++) af[tm] = *(const bf16x8*)(cA + tm * 32 * LD + 16);
; #pragma unroll
;     for (int tn = 0; tn < TN; tn++) bfr[tn] = *(const bf16x8*)(cB + tn * 32 * LD + 16);
; #pragma unroll
;     for (int tm = 0; tm < TM; tm++)
; #pragma unroll
;       for (int tn = 0; tn < TN; tn++) acc[tm][tn] = MFMA(af[tm], bfr[tn], acc[tm][tn]);
;     __builtin_amdgcn_sched_group_barrier(0x8, 4, 0);
;     if (kt + 2 < nk) GEMM_GLOAD((kt + 2) * 64)
; #pragma unroll
;     for (int ks = 2; ks < 4; ks++) {
; #pragma unroll
;       for (int tm = 0; tm < TM; tm++) af[tm] = *(const bf16x8*)(cA + tm * 32 * LD + ks * 16);
; #pragma unroll
;       for (int tn = 0; tn < TN; tn++) bfr[tn] = *(const bf16x8*)(cB + tn * 32 * LD + ks * 16);
; #pragma unroll
;       for (int tm = 0; tm < TM; tm++)
; #pragma unroll
;         for (int tn = 0; tn < TN; tn++) acc[tm][tn] = MFMA(af[tm], bfr[tn], acc[tm][tn]);
;     }
;     __builtin_amdgcn_s_setprio(0);
;     __syncthreads();
;   }
	ds_read_b128 v[96:99], v70 offset:18432
	ds_read_b128 v[100:103], v70 offset:23040
	ds_read_b128 v[128:131], v1 offset:55296
	ds_read_b128 v[132:135], v1 offset:59904
	s_setprio 1
	ds_read_b128 v[88:91], v70 offset:18464
	s_waitcnt lgkmcnt(2)
	v_mfma_f32_32x32x16_bf16 v[34:49], v[96:99], v[128:131], v[34:49]
	ds_read_b128 v[92:95], v1 offset:55328
	s_waitcnt lgkmcnt(2)
	v_mfma_f32_32x32x16_bf16 v[50:65], v[96:99], v[132:135], v[50:65]
	s_waitcnt vmcnt(7)
	ds_write_b128 v66, v[140:143]
	s_waitcnt vmcnt(6)
	ds_write_b128 v66, v[104:107] offset:4608
	global_load_dwordx4 v[140:143], v[74:75], off offset:1920
	global_load_dwordx4 v[104:107], v[72:73], off offset:1920
	ds_read_b128 v[96:99], v1 offset:59936
	s_waitcnt lgkmcnt(3)
	v_mfma_f32_32x32x16_bf16 v[34:49], v[88:91], v[92:95], v[34:49]
	s_waitcnt lgkmcnt(0)
	v_mfma_f32_32x32x16_bf16 v[50:65], v[88:91], v[96:99], v[50:65]
	ds_read_b128 v[88:91], v70 offset:23072
	v_mfma_f32_32x32x16_bf16 v[2:17], v[100:103], v[128:131], v[2:17]
	v_mfma_f32_32x32x16_bf16 v[18:33], v[100:103], v[132:135], v[18:33]
	s_waitcnt vmcnt(7)
	ds_write_b128 v66, v[108:111] offset:9216
	s_waitcnt vmcnt(6)
	ds_write_b128 v66, v[112:115] offset:13824
	global_load_dwordx4 v[108:111], v[76:77], off offset:1920
	global_load_dwordx4 v[112:115], v[86:87], off offset:1920
	ds_read_b128 v[100:103], v70 offset:23136
	s_waitcnt lgkmcnt(3)
	v_mfma_f32_32x32x16_bf16 v[2:17], v[88:91], v[92:95], v[2:17]
	ds_read_b128 v[92:95], v1 offset:55360
	v_mfma_f32_32x32x16_bf16 v[18:33], v[88:91], v[96:99], v[18:33]
	ds_read_b128 v[88:91], v70 offset:18496
	ds_read_b128 v[96:99], v1 offset:59968
	s_waitcnt lgkmcnt(1)
	v_mfma_f32_32x32x16_bf16 v[34:49], v[88:91], v[92:95], v[34:49]
	s_waitcnt lgkmcnt(0)
	v_mfma_f32_32x32x16_bf16 v[50:65], v[88:91], v[96:99], v[50:65]
	s_waitcnt vmcnt(7)
	ds_write_b128 v66, v[144:147] offset:36864
	s_waitcnt vmcnt(6)
	ds_write_b128 v66, v[124:127] offset:41472
	global_load_dwordx4 v[144:147], v[78:79], off offset:1920
	global_load_dwordx4 v[124:127], v[80:81], off offset:1920
	ds_read_b128 v[88:91], v70 offset:23104
	s_waitcnt lgkmcnt(0)
	v_mfma_f32_32x32x16_bf16 v[2:17], v[88:91], v[92:95], v[2:17]
	ds_read_b128 v[92:95], v1 offset:55392
	v_mfma_f32_32x32x16_bf16 v[18:33], v[88:91], v[96:99], v[18:33]
	ds_read_b128 v[88:91], v70 offset:18528
	ds_read_b128 v[96:99], v1 offset:60000
	s_waitcnt lgkmcnt(1)
	v_mfma_f32_32x32x16_bf16 v[34:49], v[88:91], v[92:95], v[34:49]
	s_waitcnt lgkmcnt(0)
	v_mfma_f32_32x32x16_bf16 v[50:65], v[88:91], v[96:99], v[50:65]
	s_waitcnt vmcnt(7)
	ds_write_b128 v66, v[120:123] offset:46080
	s_waitcnt vmcnt(6)
	ds_write_b128 v66, v[116:119] offset:50688
	global_load_dwordx4 v[120:123], v[82:83], off offset:1920
	global_load_dwordx4 v[116:119], v[84:85], off offset:1920
	s_nop 0
	v_mfma_f32_32x32x16_bf16 v[2:17], v[100:103], v[92:95], v[2:17]
	v_mfma_f32_32x32x16_bf16 v[18:33], v[100:103], v[96:99], v[18:33]
	s_setprio 0
	s_waitcnt lgkmcnt(0)
	s_barrier
	ds_read_b128 v[76:79], v70
	ds_read_b128 v[80:83], v70 offset:4608
	ds_read_b128 v[84:87], v1 offset:36864
	ds_read_b128 v[92:95], v1 offset:41472
	s_setprio 1
	ds_read_b128 v[72:75], v70 offset:32
	s_waitcnt lgkmcnt(2)
	v_mfma_f32_32x32x16_bf16 v[34:49], v[76:79], v[84:87], v[34:49]
	s_waitcnt lgkmcnt(1)
	v_mfma_f32_32x32x16_bf16 v[50:65], v[76:79], v[92:95], v[50:65]
	s_waitcnt vmcnt(7)
	ds_write_b128 v66, v[140:143] offset:18432
	s_waitcnt vmcnt(6)
	ds_write_b128 v66, v[104:107] offset:23040
	ds_read_b128 v[76:79], v1 offset:36896
	v_mfma_f32_32x32x16_bf16 v[2:17], v[80:83], v[84:87], v[2:17]
	v_mfma_f32_32x32x16_bf16 v[18:33], v[80:83], v[92:95], v[18:33]
	ds_read_b128 v[80:83], v1 offset:41504
	s_waitcnt lgkmcnt(1)
	v_mfma_f32_32x32x16_bf16 v[34:49], v[72:75], v[76:79], v[34:49]
	s_waitcnt lgkmcnt(0)
	v_mfma_f32_32x32x16_bf16 v[50:65], v[72:75], v[80:83], v[50:65]
	s_waitcnt vmcnt(5)
	ds_write_b128 v66, v[108:111] offset:27648
	s_waitcnt vmcnt(4)
	ds_write_b128 v66, v[112:115] offset:32256
	ds_read_b128 v[72:75], v70 offset:4640
	s_waitcnt lgkmcnt(0)
	v_mfma_f32_32x32x16_bf16 v[2:17], v[72:75], v[76:79], v[2:17]
	ds_read_b128 v[76:79], v1 offset:36928
	v_mfma_f32_32x32x16_bf16 v[18:33], v[72:75], v[80:83], v[18:33]
	ds_read_b128 v[72:75], v70 offset:64
	ds_read_b128 v[80:83], v1 offset:41536
	s_waitcnt lgkmcnt(1)
	v_mfma_f32_32x32x16_bf16 v[34:49], v[72:75], v[76:79], v[34:49]
	s_waitcnt lgkmcnt(0)
	v_mfma_f32_32x32x16_bf16 v[50:65], v[72:75], v[80:83], v[50:65]
	s_waitcnt vmcnt(3)
	ds_write_b128 v66, v[144:147] offset:55296
	s_waitcnt vmcnt(2)
	ds_write_b128 v66, v[124:127] offset:59904
	ds_read_b128 v[72:75], v70 offset:4672
	s_waitcnt lgkmcnt(0)
	v_mfma_f32_32x32x16_bf16 v[2:17], v[72:75], v[76:79], v[2:17]
	ds_read_b128 v[76:79], v1 offset:36960
	v_mfma_f32_32x32x16_bf16 v[18:33], v[72:75], v[80:83], v[18:33]
	ds_read_b128 v[72:75], v70 offset:96
	ds_read_b128 v[80:83], v1 offset:41568
	s_waitcnt lgkmcnt(1)
	v_mfma_f32_32x32x16_bf16 v[34:49], v[72:75], v[76:79], v[34:49]
	s_waitcnt lgkmcnt(0)
	v_mfma_f32_32x32x16_bf16 v[50:65], v[72:75], v[80:83], v[50:65]
	s_waitcnt vmcnt(1)
	ds_write_b128 v66, v[120:123] offset:64512
	s_waitcnt vmcnt(0)
	ds_write_b128 v71, v[116:119] offset:32256
	ds_read_b128 v[72:75], v70 offset:4704
	s_waitcnt lgkmcnt(0)
	v_mfma_f32_32x32x16_bf16 v[2:17], v[72:75], v[76:79], v[2:17]
	v_mfma_f32_32x32x16_bf16 v[18:33], v[72:75], v[80:83], v[18:33]
	s_setprio 0
	s_barrier
; #define MFMA(a, b, c) __builtin_amdgcn_mfma_f32_32x32x16_bf16((a), (b), (c), 0, 0, 0)
; DI unsigned pk2(float a, float b) { fv2 v = {a, b}; bfv2 r = __builtin_convertvector(v, bfv2); return __builtin_bit_cast(unsigned, r); }
; DI int crow(int i, int h) { return (i & 3) + 8 * (i >> 2) + 4 * h; }
; template <int TM, int TN>
; DI void gemm_mainloop(const u16* __restrict__ A, long lda, const u16* __restrict__ Bt, long ldb, int K, char* smem,
;                       f32x16 (&acc)[TM][TN]) {
;     ...
;     for (int ks = 2; ks < 4; ks++) {
; #pragma unroll
;       for (int tm = 0; tm < TM; tm++) af[tm] = *(const bf16x8*)(cA + tm * 32 * LD + ks * 16);
; #pragma unroll
;       for (int tn = 0; tn < TN; tn++) bfr[tn] = *(const bf16x8*)(cB + tn * 32 * LD + ks * 16);
; #pragma unroll
;       for (int tm = 0; tm < TM; tm++)
; #pragma unroll
;         for (int tn = 0; tn < TN; tn++) acc[tm][tn] = MFMA(af[tm], bfr[tn], acc[tm][tn]);
;     }
;     __builtin_amdgcn_s_setprio(0);
;     __syncthreads();
;   }
; template <int TM, int TN, class Epi>
; DI void gemm_tile(const u16* A, long lda, const u16* Bt, long ldb, int K, int m0, int n0, char* smem, const Epi& epi) {
;     ...
; #pragma unroll
;   for (int tm = 0; tm < TM; tm++)
; #pragma unroll
;     for (int tn = 0; tn < TN; tn++)
; #pragma unroll
;       for (int i = 0; i < 16; i++)
;         Ct[(wm * 32 * TM + tm * 32 + crow(i, h)) * LDC + wn * 32 * TN + tn * 32 + r] = acc[tm][tn][i];
;   __syncthreads();
;   epi(Ct, LDC, m0, n0, tid, BM);
;   __syncthreads();
;   (void)BM;
; }
;   DI void operator()(const float* Ct, int ldc, int m0, int n0, int tid, int bm) const {
; #pragma unroll 4
;     for (int it = 0; it < bm / 16; it++) {
;       int id = tid + 256 * it; int row = id >> 4, c8 = (id & 15) * 8;
;       int n = n0 + c8;
;       if (n < nmax) {
;         const float* c = Ct + row * ldc + c8;
;         float4 a = *(const float4*)c, b = *(const float4*)(c + 4);
;         uint4 v; v.x = pk2(a.x, a.y); v.y = pk2(a.z, a.w); v.z = pk2(b.x, b.y); v.w = pk2(b.z, b.w);
;         *(uint4*)(out + (long)(m0 + row) * ldo + n) = v;
	ds_read_b128 v[72:75], v70 offset:18432
	ds_read_b128 v[76:79], v70 offset:23040
	ds_read_b128 v[80:83], v1 offset:55296
	ds_read_b128 v[84:87], v1 offset:59904
	s_setprio 1
	s_waitcnt lgkmcnt(1)
	v_mfma_f32_32x32x16_bf16 v[34:49], v[72:75], v[80:83], v[34:49]
	s_waitcnt lgkmcnt(0)
	v_mfma_f32_32x32x16_bf16 v[50:65], v[72:75], v[84:87], v[50:65]
	ds_read_b128 v[72:75], v70 offset:18464
	v_mfma_f32_32x32x16_bf16 v[2:17], v[76:79], v[80:83], v[2:17]
	ds_read_b128 v[80:83], v1 offset:59936
	v_mfma_f32_32x32x16_bf16 v[18:33], v[76:79], v[84:87], v[18:33]
	ds_read_b128 v[76:79], v1 offset:55328
	s_waitcnt lgkmcnt(0)
	v_mfma_f32_32x32x16_bf16 v[34:49], v[72:75], v[76:79], v[34:49]
	v_mfma_f32_32x32x16_bf16 v[50:65], v[72:75], v[80:83], v[50:65]
	ds_read_b128 v[72:75], v70 offset:23072
	s_waitcnt lgkmcnt(0)
	v_mfma_f32_32x32x16_bf16 v[2:17], v[72:75], v[76:79], v[2:17]
	ds_read_b128 v[76:79], v1 offset:55360
	v_mfma_f32_32x32x16_bf16 v[18:33], v[72:75], v[80:83], v[18:33]
	ds_read_b128 v[72:75], v70 offset:18496
	ds_read_b128 v[80:83], v1 offset:59968
	s_waitcnt lgkmcnt(1)
	v_mfma_f32_32x32x16_bf16 v[34:49], v[72:75], v[76:79], v[34:49]
	s_waitcnt lgkmcnt(0)
	v_mfma_f32_32x32x16_bf16 v[50:65], v[72:75], v[80:83], v[50:65]
	ds_read_b128 v[72:75], v70 offset:23104
	s_waitcnt lgkmcnt(0)
	v_mfma_f32_32x32x16_bf16 v[2:17], v[72:75], v[76:79], v[2:17]
	ds_read_b128 v[76:79], v1 offset:55392
	v_mfma_f32_32x32x16_bf16 v[18:33], v[72:75], v[80:83], v[18:33]
	ds_read_b128 v[72:75], v70 offset:18528
	ds_read_b128 v[80:83], v1 offset:60000
	s_waitcnt lgkmcnt(1)
	v_mfma_f32_32x32x16_bf16 v[34:49], v[72:75], v[76:79], v[34:49]
	s_waitcnt lgkmcnt(0)
	v_mfma_f32_32x32x16_bf16 v[50:65], v[72:75], v[80:83], v[50:65]
	ds_read_b128 v[70:73], v70 offset:23136
	s_waitcnt lgkmcnt(0)
	v_mfma_f32_32x32x16_bf16 v[2:17], v[70:73], v[76:79], v[2:17]
	v_mfma_f32_32x32x16_bf16 v[18:33], v[70:73], v[80:83], v[18:33]
	s_setprio 0
	v_mov_b32_e32 v1, v0
	s_barrier
	s_mov_b32 s26, 0
	v_lshrrev_b32_e32 v66, 1, v1
	v_and_b32_e32 v66, 0xfffffc0, v66
	v_lshrrev_b32_e32 v70, 3, v1
	v_and_or_b32 v66, v70, 4, v66
	v_and_b32_e32 v70, 0x5f, v1
	v_mul_lo_u32 v66, v66, s22
	v_lshl_add_u32 v66, v70, 2, v66
	ds_write2_b32 v66, v34, v50 offset1:32
	v_add_u32_e32 v34, 0x400, v66
	ds_write2_b32 v34, v36, v52 offset0:8 offset1:40
	ds_write2_b32 v34, v37, v53 offset0:140 offset1:172
	v_add_u32_e32 v34, 0x1000, v66
	ds_write2_b32 v34, v38, v54 offset0:32 offset1:64
	ds_write2_b32 v34, v39, v55 offset0:164 offset1:196
	v_add_u32_e32 v34, 0x1400, v66
	ds_write2_b32 v34, v40, v56 offset0:40 offset1:72
	ds_write2_b32 v34, v41, v57 offset0:172 offset1:204
	v_add_u32_e32 v34, 0x2000, v66
	ds_write2_b32 v34, v42, v58 offset0:64 offset1:96
	ds_write2_b32 v34, v43, v59 offset0:196 offset1:228
	v_add_u32_e32 v34, 0x2400, v66
	ds_write2_b32 v34, v44, v60 offset0:72 offset1:104
	ds_write2_b32 v34, v45, v61 offset0:204 offset1:236
	v_add_u32_e32 v34, 0x3000, v66
	ds_write2_b32 v34, v46, v62 offset0:96 offset1:128
	v_add_u32_e32 v34, 0x3200, v66
	ds_write2_b32 v34, v47, v63 offset0:100 offset1:132
	v_add_u32_e32 v34, 0x3400, v66
	ds_write2_b32 v34, v48, v64 offset0:104 offset1:136
	v_add_u32_e32 v34, 0x3600, v66
	ds_write2_b32 v34, v49, v65 offset0:108 offset1:140
	v_add_u32_e32 v34, 0x4000, v66
	ds_write2_b32 v34, v2, v18 offset0:128 offset1:160
	v_add_u32_e32 v2, 0x4400, v66
	ds_write2_b32 v2, v3, v19 offset0:4 offset1:36
	ds_write2_b32 v2, v4, v20 offset0:136 offset1:168
	v_add_u32_e32 v2, 0x4800, v66
	ds_write2_b32 v2, v5, v21 offset0:12 offset1:44
	v_add_u32_e32 v2, 0x5000, v66
	ds_write2_b32 v2, v6, v22 offset0:160 offset1:192
	v_add_u32_e32 v2, 0x5400, v66
	ds_write2_b32 v2, v7, v23 offset0:36 offset1:68
	ds_write2_b32 v2, v8, v24 offset0:168 offset1:200
	v_add_u32_e32 v2, 0x5800, v66
	ds_write2_b32 v2, v9, v25 offset0:44 offset1:76
	v_add_u32_e32 v2, 0x6000, v66
	ds_write2_b32 v2, v10, v26 offset0:192 offset1:224
	v_add_u32_e32 v2, 0x6400, v66
	ds_write2_b32 v2, v11, v27 offset0:68 offset1:100
	ds_write2_b32 v2, v12, v28 offset0:200 offset1:232
	v_add_u32_e32 v2, 0x6800, v66
	ds_write2_b32 v2, v13, v29 offset0:76 offset1:108
	v_add_u32_e32 v2, 0x7200, v66
	ds_write2_b32 v2, v14, v30 offset0:96 offset1:128
	v_add_u32_e32 v2, 0x7400, v66
	ds_write2_b32 v2, v15, v31 offset0:100 offset1:132
	v_add_u32_e32 v2, 0x7600, v66
	ds_write2_b32 v2, v16, v32 offset0:104 offset1:136
	v_add_u32_e32 v2, 0x7800, v66
	ds_write2_b32 v2, v17, v33 offset0:108 offset1:140
	v_lshlrev_b32_e32 v2, 3, v1
	v_and_b32_e32 v2, 0x78, v2
	v_or_b32_e32 v4, s11, v2
	v_ashrrev_i32_e32 v5, 31, v4
	v_lshlrev_b32_e32 v2, 2, v2
	v_cmp_gt_i32_e32 vcc, s23, v4
	v_lshl_add_u64 v[4:5], v[4:5], 1, s[8:9]
	ds_write2_b32 v66, v35, v51 offset0:132 offset1:164
	s_waitcnt lgkmcnt(0)
	s_barrier
	s_branch .LBB0_2476

; #define MFMA(a, b, c) __builtin_amdgcn_mfma_f32_32x32x16_bf16((a), (b), (c), 0, 0, 0)
; template <int TM, int TN>
; DI void gemm_mainloop(const u16* __restrict__ A, long lda, const u16* __restrict__ Bt, long ldb, int K, char* smem,
;                       f32x16 (&acc)[TM][TN]) {
;     ...
;   const int lrow = tid >> 3, lch = (tid & 7) * 8;
;   const u16* gA = A + (long)lrow * lda + lch;
;   const u16* gB = Bt + (long)lrow * ldb + lch;
;   const int soff = lrow * LD + lch;
;     ...
;   GEMM_GLOAD(0)
;   __syncthreads();
;   GEMM_SSTORE(0)
;   if (nk > 1) GEMM_GLOAD(64)
;   __syncthreads();
;   for (int kt = 0; kt < nk; kt++) {
;     const int buf = kt & 1;
;     const u16* cA = sA + buf * BM * LD + (wm * 32 * TM + r) * LD + h * 8;
;     const u16* cB = sB + buf * BN * LD + (wn * 32 * TN + r) * LD + h * 8;
;     bf16x8 af[TM], bfr[TN];
; #pragma unroll
;     for (int tm = 0; tm < TM; tm++) af[tm] = *(const bf16x8*)(cA + tm * 32 * LD);
; #pragma unroll
;     for (int tn = 0; tn < TN; tn++) bfr[tn] = *(const bf16x8*)(cB + tn * 32 * LD);
;     if (kt + 1 < nk) GEMM_SSTORE(buf ^ 1)
;     __builtin_amdgcn_sched_barrier(0);
;     __builtin_amdgcn_s_setprio(1);
; #pragma unroll
;     for (int tm = 0; tm < TM; tm++)
; #pragma unroll
;       for (int tn = 0; tn < TN; tn++) acc[tm][tn] = MFMA(af[tm], bfr[tn], acc[tm][tn]);
; #pragma unroll
;     for (int tm = 0; tm < TM; tm++) af[tm] = *(const bf16x8*)(cA + tm * 32 * LD + 16);
; #pragma unroll
;     for (int tn = 0; tn < TN; tn++) bfr[tn] = *(const bf16x8*)(cB + tn * 32 * LD + 16);
; #pragma unroll
;     for (int tm = 0; tm < TM; tm++)
; #pragma unroll
;       for (int tn = 0; tn < TN; tn++) acc[tm][tn] = MFMA(af[tm], bfr[tn], acc[tm][tn]);
;     __builtin_amdgcn_sched_group_barrier(0x8, 4, 0);
;     if (kt + 2 < nk) GEMM_GLOAD((kt + 2) * 64)
; #pragma unroll
;     for (int ks = 2; ks < 4; ks++) {
; #pragma unroll
;       for (int tm = 0; tm < TM; tm++) af[tm] = *(const bf16x8*)(cA + tm * 32 * LD + ks * 16);
; #pragma unroll
;       for (int tn = 0; tn < TN; tn++) bfr[tn] = *(const bf16x8*)(cB + tn * 32 * LD + ks * 16);
; #pragma unroll
;       for (int tm = 0; tm < TM; tm++)
; #pragma unroll
;         for (int tn = 0; tn < TN; tn++) acc[tm][tn] = MFMA(af[tm], bfr[tn], acc[tm][tn]);
;     }
.LBB0_2739:
	s_ashr_i32 s6, s22, 31
	s_lshr_b32 s6, s6, 27
	s_add_i32 s6, s22, s6
	s_and_b32 s7, s6, 0xffffffe0
	s_lshl_b32 s6, s6, 2
	s_sub_i32 s26, s22, s7
	s_and_b32 s23, s6, 0xffffff80
	s_lshl_b32 s6, s26, 7
	s_mul_i32 s24, s23, 0x880
	s_mul_hi_i32 s7, s23, 0x880
	s_add_u32 s24, s4, s24
	v_mov_b32_e32 v1, v0
	s_addc_u32 s25, s5, s7
	s_ashr_i32 s7, s6, 31
	v_lshlrev_b32_e32 v2, 3, v1
	v_ashrrev_i32_e32 v68, 3, v1
	v_and_b32_e32 v69, 56, v2
	v_mov_b64_e32 v[2:3], s[24:25]
	v_mad_i64_i32 v[2:3], s[24:25], v68, s8, v[2:3]
	v_lshlrev_b32_e32 v66, 1, v69
	v_lshl_add_u64 v[72:73], v[2:3], 0, v[66:67]
	s_mul_i32 s26, s26, 0x44000
	v_add_co_u32_e32 v70, vcc, s15, v72
	s_mul_hi_i32 s27, s6, 0x880
	s_add_u32 s26, s11, s26
	v_addc_co_u32_e32 v71, vcc, 0, v73, vcc
	s_addc_u32 s27, s14, s27
	v_add_co_u32_e32 v74, vcc, s16, v72
	v_mov_b64_e32 v[2:3], s[26:27]
	s_nop 0
	v_addc_co_u32_e32 v75, vcc, 0, v73, vcc
	v_mad_i64_i32 v[18:19], s[24:25], v68, s8, v[2:3]
	v_add_co_u32_e32 v78, vcc, s17, v72
	v_lshl_add_u64 v[76:77], v[18:19], 0, v[66:67]
	s_nop 0
	v_addc_co_u32_e32 v79, vcc, 0, v73, vcc
	v_add_co_u32_e32 v80, vcc, s15, v76
	global_load_dwordx4 v[2:5], v[72:73], off
	s_nop 0
	v_addc_co_u32_e32 v81, vcc, 0, v77, vcc
	v_add_co_u32_e32 v82, vcc, s16, v76
	global_load_dwordx4 v[6:9], v[70:71], off
	s_nop 0
	v_addc_co_u32_e32 v83, vcc, 0, v77, vcc
	v_add_co_u32_e32 v84, vcc, s17, v76
	global_load_dwordx4 v[10:13], v[74:75], off
	s_nop 0
	v_addc_co_u32_e32 v85, vcc, 0, v77, vcc
	global_load_dwordx4 v[14:17], v[78:79], off
	global_load_dwordx4 v[18:21], v[76:77], off
	global_load_dwordx4 v[22:25], v[80:81], off
	global_load_dwordx4 v[26:29], v[82:83], off
	global_load_dwordx4 v[30:33], v[84:85], off
	s_barrier
	global_load_dwordx4 v[34:37], v[72:73], off offset:128
	global_load_dwordx4 v[38:41], v[70:71], off offset:128
	global_load_dwordx4 v[42:45], v[74:75], off offset:128
	global_load_dwordx4 v[46:49], v[78:79], off offset:128
	global_load_dwordx4 v[50:53], v[76:77], off offset:128
	global_load_dwordx4 v[54:57], v[80:81], off offset:128
	global_load_dwordx4 v[58:61], v[82:83], off offset:128
	global_load_dwordx4 v[62:65], v[84:85], off offset:128
	v_and_b32_e32 v66, 31, v1
	v_lshrrev_b32_e32 v86, 1, v1
	v_mul_lo_u32 v68, v68, s9
	v_and_or_b32 v87, v86, s18, v66
	v_and_b32_e32 v86, 16, v86
	v_and_b32_e32 v1, 0x5f, v1
	v_add_lshl_u32 v66, v68, v69, 1
	v_mad_u64_u32 v[68:69], s[24:25], v87, s19, v[86:87]
	v_mad_u32_u24 v1, v1, s19, v86
	v_add_u32_e32 v69, 0x9000, v66
	s_waitcnt vmcnt(15)
	ds_write_b128 v66, v[2:5]
	s_waitcnt vmcnt(14)
	ds_write_b128 v66, v[6:9] offset:4608
	s_waitcnt vmcnt(13)
	ds_write_b128 v66, v[10:13] offset:9216
	s_waitcnt vmcnt(12)
	ds_write_b128 v66, v[14:17] offset:13824
	s_waitcnt vmcnt(11)
	ds_write_b128 v66, v[18:21] offset:36864
	s_waitcnt vmcnt(10)
	ds_write_b128 v66, v[22:25] offset:41472
	s_waitcnt vmcnt(9)
	ds_write_b128 v66, v[26:29] offset:46080
	s_waitcnt vmcnt(8)
	ds_write_b128 v66, v[30:33] offset:50688
	s_waitcnt lgkmcnt(0)
	s_barrier
	ds_read_b128 v[2:5], v68
	ds_read_b128 v[18:21], v68 offset:4608
	ds_read_b128 v[6:9], v1 offset:36864
	ds_read_b128 v[22:25], v1 offset:41472
	s_waitcnt vmcnt(7)
	ds_write_b128 v66, v[34:37] offset:18432
	s_waitcnt vmcnt(6)
	ds_write_b128 v66, v[38:41] offset:23040
	s_waitcnt vmcnt(5)
	ds_write_b128 v66, v[42:45] offset:27648
	s_waitcnt vmcnt(4)
	ds_write_b128 v66, v[46:49] offset:32256
	s_waitcnt vmcnt(3)
	ds_write_b128 v66, v[50:53] offset:55296
	s_waitcnt vmcnt(2)
	ds_write_b128 v66, v[54:57] offset:59904
	s_waitcnt vmcnt(1)
	ds_write_b128 v66, v[58:61] offset:64512
	s_waitcnt vmcnt(0)
	ds_write_b128 v69, v[62:65] offset:32256
	s_setprio 1
	ds_read_b128 v[86:89], v68 offset:32
	s_waitcnt lgkmcnt(10)
	v_mfma_f32_32x32x16_bf16 v[34:49], v[2:5], v[6:9], 0
	ds_read_b128 v[90:93], v1 offset:36896
	ds_read_b128 v[94:97], v1 offset:41504
	ds_read_b128 v[98:101], v68 offset:4704
	global_load_dwordx4 v[102:105], v[70:71], off offset:256
	global_load_dwordx4 v[106:109], v[74:75], off offset:256
	global_load_dwordx4 v[110:113], v[78:79], off offset:256
	global_load_dwordx4 v[114:117], v[84:85], off offset:256
	s_waitcnt lgkmcnt(12)
	v_mfma_f32_32x32x16_bf16 v[50:65], v[2:5], v[22:25], 0
	global_load_dwordx4 v[118:121], v[82:83], off offset:256
	global_load_dwordx4 v[122:125], v[80:81], off offset:256
	global_load_dwordx4 v[140:143], v[72:73], off offset:256
	global_load_dwordx4 v[144:147], v[76:77], off offset:256
	s_waitcnt lgkmcnt(2)
	v_mfma_f32_32x32x16_bf16 v[34:49], v[86:89], v[90:93], v[34:49]
	s_waitcnt lgkmcnt(1)
	v_mfma_f32_32x32x16_bf16 v[50:65], v[86:89], v[94:97], v[50:65]
	ds_read_b128 v[86:89], v68 offset:4640
	v_mfma_f32_32x32x16_bf16 v[2:17], v[18:21], v[6:9], 0
	v_mfma_f32_32x32x16_bf16 v[18:33], v[18:21], v[22:25], 0
	s_waitcnt lgkmcnt(0)
	v_mfma_f32_32x32x16_bf16 v[2:17], v[86:89], v[90:93], v[2:17]
	ds_read_b128 v[90:93], v1 offset:36928
	v_mfma_f32_32x32x16_bf16 v[18:33], v[86:89], v[94:97], v[18:33]
	ds_read_b128 v[86:89], v68 offset:64
	ds_read_b128 v[94:97], v1 offset:41536
	s_waitcnt lgkmcnt(1)
	v_mfma_f32_32x32x16_bf16 v[34:49], v[86:89], v[90:93], v[34:49]
	s_waitcnt lgkmcnt(0)
	v_mfma_f32_32x32x16_bf16 v[50:65], v[86:89], v[94:97], v[50:65]
	ds_read_b128 v[86:89], v68 offset:4672
	s_waitcnt lgkmcnt(0)
	v_mfma_f32_32x32x16_bf16 v[2:17], v[86:89], v[90:93], v[2:17]
	ds_read_b128 v[90:93], v1 offset:36960
	v_mfma_f32_32x32x16_bf16 v[18:33], v[86:89], v[94:97], v[18:33]
	ds_read_b128 v[86:89], v68 offset:96
	ds_read_b128 v[94:97], v1 offset:41568
	s_waitcnt lgkmcnt(1)
	v_mfma_f32_32x32x16_bf16 v[34:49], v[86:89], v[90:93], v[34:49]
	s_waitcnt lgkmcnt(0)
	v_mfma_f32_32x32x16_bf16 v[50:65], v[86:89], v[94:97], v[50:65]
	v_mfma_f32_32x32x16_bf16 v[2:17], v[98:101], v[90:93], v[2:17]
	v_mfma_f32_32x32x16_bf16 v[18:33], v[98:101], v[94:97], v[18:33]
	s_setprio 0
	s_barrier
; #define MFMA(a, b, c) __builtin_amdgcn_mfma_f32_32x32x16_bf16((a), (b), (c), 0, 0, 0)
; template <int TM, int TN>
; DI void gemm_mainloop(const u16* __restrict__ A, long lda, const u16* __restrict__ Bt, long ldb, int K, char* smem,
;                       f32x16 (&acc)[TM][TN]) {
;     ...
;   for (int kt = 0; kt < nk; kt++) {
;     const int buf = kt & 1;
;     const u16* cA = sA + buf * BM * LD + (wm * 32 * TM + r) * LD + h * 8;
;     const u16* cB = sB + buf * BN * LD + (wn * 32 * TN + r) * LD + h * 8;
;     bf16x8 af[TM], bfr[TN];
; #pragma unroll
;     for (int tm = 0; tm < TM; tm++) af[tm] = *(const bf16x8*)(cA + tm * 32 * LD);
; #pragma unroll
;     for (int tn = 0; tn < TN; tn++) bfr[tn] = *(const bf16x8*)(cB + tn * 32 * LD);
;     if (kt + 1 < nk) GEMM_SSTORE(buf ^ 1)
;     __builtin_amdgcn_sched_barrier(0);
;     __builtin_amdgcn_s_setprio(1);
; #pragma unroll
;     for (int tm = 0; tm < TM; tm++)
; #pragma unroll
;       for (int tn = 0; tn < TN; tn++) acc[tm][tn] = MFMA(af[tm], bfr[tn], acc[tm][tn]);
; #pragma unroll
;     for (int tm = 0; tm < TM; tm++) af[tm] = *(const bf16x8*)(cA + tm * 32 * LD + 16);
; #pragma unroll
;     for (int tn = 0; tn < TN; tn++) bfr[tn] = *(const bf16x8*)(cB + tn * 32 * LD + 16);
; #pragma unroll
;     for (int tm = 0; tm < TM; tm++)
; #pragma unroll
;       for (int tn = 0; tn < TN; tn++) acc[tm][tn] = MFMA(af[tm], bfr[tn], acc[tm][tn]);
;     __builtin_amdgcn_sched_group_barrier(0x8, 4, 0);
;     if (kt + 2 < nk) GEMM_GLOAD((kt + 2) * 64)
; #pragma unroll
;     for (int ks = 2; ks < 4; ks++) {
; #pragma unroll
;       for (int tm = 0; tm < TM; tm++) af[tm] = *(const bf16x8*)(cA + tm * 32 * LD + ks * 16);
; #pragma unroll
;       for (int tn = 0; tn < TN; tn++) bfr[tn] = *(const bf16x8*)(cB + tn * 32 * LD + ks * 16);
; #pragma unroll
;       for (int tm = 0; tm < TM; tm++)
; #pragma unroll
;         for (int tn = 0; tn < TN; tn++) acc[tm][tn] = MFMA(af[tm], bfr[tn], acc[tm][tn]);
;     }
;     __builtin_amdgcn_s_setprio(0);
;     __syncthreads();
;   }
	ds_read_b128 v[94:97], v68 offset:18432
	ds_read_b128 v[98:101], v68 offset:23040
	ds_read_b128 v[126:129], v1 offset:55296
	ds_read_b128 v[130:133], v1 offset:59904
	s_waitcnt vmcnt(1)
	ds_write_b128 v66, v[140:143]
	ds_write_b128 v66, v[102:105] offset:4608
	ds_write_b128 v66, v[106:109] offset:9216
	ds_write_b128 v66, v[110:113] offset:13824
	s_waitcnt vmcnt(0)
	ds_write_b128 v66, v[144:147] offset:36864
	ds_write_b128 v66, v[122:125] offset:41472
	ds_write_b128 v66, v[118:121] offset:46080
	ds_write_b128 v66, v[114:117] offset:50688
	s_setprio 1
	ds_read_b128 v[86:89], v68 offset:18464
	s_waitcnt lgkmcnt(10)
	v_mfma_f32_32x32x16_bf16 v[34:49], v[94:97], v[126:129], v[34:49]
	ds_read_b128 v[90:93], v1 offset:55328
	global_load_dwordx4 v[102:105], v[70:71], off offset:384
	global_load_dwordx4 v[106:109], v[74:75], off offset:384
	global_load_dwordx4 v[110:113], v[78:79], off offset:384
	global_load_dwordx4 v[114:117], v[84:85], off offset:384
	global_load_dwordx4 v[118:121], v[82:83], off offset:384
	global_load_dwordx4 v[122:125], v[80:81], off offset:384
	global_load_dwordx4 v[140:143], v[72:73], off offset:384
	global_load_dwordx4 v[144:147], v[76:77], off offset:384
	s_waitcnt lgkmcnt(10)
	v_mfma_f32_32x32x16_bf16 v[50:65], v[94:97], v[130:133], v[50:65]
	ds_read_b128 v[94:97], v1 offset:59936
	s_waitcnt lgkmcnt(1)
	v_mfma_f32_32x32x16_bf16 v[34:49], v[86:89], v[90:93], v[34:49]
	s_waitcnt lgkmcnt(0)
	v_mfma_f32_32x32x16_bf16 v[50:65], v[86:89], v[94:97], v[50:65]
	ds_read_b128 v[86:89], v68 offset:23072
	v_mfma_f32_32x32x16_bf16 v[2:17], v[98:101], v[126:129], v[2:17]
	v_mfma_f32_32x32x16_bf16 v[18:33], v[98:101], v[130:133], v[18:33]
	ds_read_b128 v[98:101], v68 offset:23136
	s_waitcnt lgkmcnt(1)
	v_mfma_f32_32x32x16_bf16 v[2:17], v[86:89], v[90:93], v[2:17]
	ds_read_b128 v[90:93], v1 offset:55360
	v_mfma_f32_32x32x16_bf16 v[18:33], v[86:89], v[94:97], v[18:33]
	ds_read_b128 v[86:89], v68 offset:18496
	ds_read_b128 v[94:97], v1 offset:59968
	s_waitcnt lgkmcnt(1)
	v_mfma_f32_32x32x16_bf16 v[34:49], v[86:89], v[90:93], v[34:49]
	s_waitcnt lgkmcnt(0)
	v_mfma_f32_32x32x16_bf16 v[50:65], v[86:89], v[94:97], v[50:65]
	ds_read_b128 v[86:89], v68 offset:23104
	s_waitcnt lgkmcnt(0)
	v_mfma_f32_32x32x16_bf16 v[2:17], v[86:89], v[90:93], v[2:17]
	ds_read_b128 v[90:93], v1 offset:55392
	v_mfma_f32_32x32x16_bf16 v[18:33], v[86:89], v[94:97], v[18:33]
	ds_read_b128 v[86:89], v68 offset:18528
	ds_read_b128 v[94:97], v1 offset:60000
	s_waitcnt lgkmcnt(1)
	v_mfma_f32_32x32x16_bf16 v[34:49], v[86:89], v[90:93], v[34:49]
	s_waitcnt lgkmcnt(0)
	v_mfma_f32_32x32x16_bf16 v[50:65], v[86:89], v[94:97], v[50:65]
	v_mfma_f32_32x32x16_bf16 v[2:17], v[98:101], v[90:93], v[2:17]
	v_mfma_f32_32x32x16_bf16 v[18:33], v[98:101], v[94:97], v[18:33]
	s_setprio 0
	s_barrier
	ds_read_b128 v[94:97], v68
	ds_read_b128 v[98:101], v68 offset:4608
	ds_read_b128 v[126:129], v1 offset:36864
	ds_read_b128 v[130:133], v1 offset:41472
	s_waitcnt vmcnt(1)
	ds_write_b128 v66, v[140:143] offset:18432
	ds_write_b128 v66, v[102:105] offset:23040
	ds_write_b128 v66, v[106:109] offset:27648
	ds_write_b128 v66, v[110:113] offset:32256
	s_waitcnt vmcnt(0)
	ds_write_b128 v66, v[144:147] offset:55296
	ds_write_b128 v66, v[122:125] offset:59904
	ds_write_b128 v66, v[118:121] offset:64512
	ds_write_b128 v69, v[114:117] offset:32256
	s_setprio 1
	ds_read_b128 v[86:89], v68 offset:32
	s_waitcnt lgkmcnt(10)
	v_mfma_f32_32x32x16_bf16 v[34:49], v[94:97], v[126:129], v[34:49]
	ds_read_b128 v[90:93], v1 offset:36896
	global_load_dwordx4 v[102:105], v[70:71], off offset:512
	global_load_dwordx4 v[106:109], v[74:75], off offset:512
	global_load_dwordx4 v[110:113], v[78:79], off offset:512
	global_load_dwordx4 v[114:117], v[84:85], off offset:512
	global_load_dwordx4 v[118:121], v[82:83], off offset:512
	global_load_dwordx4 v[122:125], v[80:81], off offset:512
	global_load_dwordx4 v[140:143], v[72:73], off offset:512
	global_load_dwordx4 v[144:147], v[76:77], off offset:512
	s_waitcnt lgkmcnt(10)
	v_mfma_f32_32x32x16_bf16 v[50:65], v[94:97], v[130:133], v[50:65]
	ds_read_b128 v[94:97], v1 offset:41504
	s_waitcnt lgkmcnt(1)
	v_mfma_f32_32x32x16_bf16 v[34:49], v[86:89], v[90:93], v[34:49]
	s_waitcnt lgkmcnt(0)
	v_mfma_f32_32x32x16_bf16 v[50:65], v[86:89], v[94:97], v[50:65]
	ds_read_b128 v[86:89], v68 offset:4640
	v_mfma_f32_32x32x16_bf16 v[2:17], v[98:101], v[126:129], v[2:17]
	v_mfma_f32_32x32x16_bf16 v[18:33], v[98:101], v[130:133], v[18:33]
	ds_read_b128 v[98:101], v68 offset:4704
	s_waitcnt lgkmcnt(1)
	v_mfma_f32_32x32x16_bf16 v[2:17], v[86:89], v[90:93], v[2:17]
	ds_read_b128 v[90:93], v1 offset:36928
	v_mfma_f32_32x32x16_bf16 v[18:33], v[86:89], v[94:97], v[18:33]
	ds_read_b128 v[86:89], v68 offset:64
	ds_read_b128 v[94:97], v1 offset:41536
	s_waitcnt lgkmcnt(1)
	v_mfma_f32_32x32x16_bf16 v[34:49], v[86:89], v[90:93], v[34:49]
	s_waitcnt lgkmcnt(0)
	v_mfma_f32_32x32x16_bf16 v[50:65], v[86:89], v[94:97], v[50:65]
	ds_read_b128 v[86:89], v68 offset:4672
	s_waitcnt lgkmcnt(0)
	v_mfma_f32_32x32x16_bf16 v[2:17], v[86:89], v[90:93], v[2:17]
	ds_read_b128 v[90:93], v1 offset:36960
	v_mfma_f32_32x32x16_bf16 v[18:33], v[86:89], v[94:97], v[18:33]
	ds_read_b128 v[86:89], v68 offset:96
	ds_read_b128 v[94:97], v1 offset:41568
	s_waitcnt lgkmcnt(1)
	v_mfma_f32_32x32x16_bf16 v[34:49], v[86:89], v[90:93], v[34:49]
	s_waitcnt lgkmcnt(0)
	v_mfma_f32_32x32x16_bf16 v[50:65], v[86:89], v[94:97], v[50:65]
	v_mfma_f32_32x32x16_bf16 v[2:17], v[98:101], v[90:93], v[2:17]
	v_mfma_f32_32x32x16_bf16 v[18:33], v[98:101], v[94:97], v[18:33]
	s_setprio 0
	s_barrier
; #define MFMA(a, b, c) __builtin_amdgcn_mfma_f32_32x32x16_bf16((a), (b), (c), 0, 0, 0)
; template <int TM, int TN>
; DI void gemm_mainloop(const u16* __restrict__ A, long lda, const u16* __restrict__ Bt, long ldb, int K, char* smem,
;                       f32x16 (&acc)[TM][TN]) {
;     ...
;   for (int kt = 0; kt < nk; kt++) {
;     const int buf = kt & 1;
;     const u16* cA = sA + buf * BM * LD + (wm * 32 * TM + r) * LD + h * 8;
;     const u16* cB = sB + buf * BN * LD + (wn * 32 * TN + r) * LD + h * 8;
;     bf16x8 af[TM], bfr[TN];
; #pragma unroll
;     for (int tm = 0; tm < TM; tm++) af[tm] = *(const bf16x8*)(cA + tm * 32 * LD);
; #pragma unroll
;     for (int tn = 0; tn < TN; tn++) bfr[tn] = *(const bf16x8*)(cB + tn * 32 * LD);
;     if (kt + 1 < nk) GEMM_SSTORE(buf ^ 1)
;     __builtin_amdgcn_sched_barrier(0);
;     __builtin_amdgcn_s_setprio(1);
; #pragma unroll
;     for (int tm = 0; tm < TM; tm++)
; #pragma unroll
;       for (int tn = 0; tn < TN; tn++) acc[tm][tn] = MFMA(af[tm], bfr[tn], acc[tm][tn]);
; #pragma unroll
;     for (int tm = 0; tm < TM; tm++) af[tm] = *(const bf16x8*)(cA + tm * 32 * LD + 16);
; #pragma unroll
;     for (int tn = 0; tn < TN; tn++) bfr[tn] = *(const bf16x8*)(cB + tn * 32 * LD + 16);
; #pragma unroll
;     for (int tm = 0; tm < TM; tm++)
; #pragma unroll
;       for (int tn = 0; tn < TN; tn++) acc[tm][tn] = MFMA(af[tm], bfr[tn], acc[tm][tn]);
;     __builtin_amdgcn_sched_group_barrier(0x8, 4, 0);
;     if (kt + 2 < nk) GEMM_GLOAD((kt + 2) * 64)
; #pragma unroll
;     for (int ks = 2; ks < 4; ks++) {
; #pragma unroll
;       for (int tm = 0; tm < TM; tm++) af[tm] = *(const bf16x8*)(cA + tm * 32 * LD + ks * 16);
; #pragma unroll
;       for (int tn = 0; tn < TN; tn++) bfr[tn] = *(const bf16x8*)(cB + tn * 32 * LD + ks * 16);
; #pragma unroll
;       for (int tm = 0; tm < TM; tm++)
; #pragma unroll
;         for (int tn = 0; tn < TN; tn++) acc[tm][tn] = MFMA(af[tm], bfr[tn], acc[tm][tn]);
;     }
;     __builtin_amdgcn_s_setprio(0);
;     __syncthreads();
;   }
	ds_read_b128 v[94:97], v68 offset:18432
	ds_read_b128 v[98:101], v68 offset:23040
	ds_read_b128 v[126:129], v1 offset:55296
	ds_read_b128 v[130:133], v1 offset:59904
	s_waitcnt vmcnt(1)
	ds_write_b128 v66, v[140:143]
	ds_write_b128 v66, v[102:105] offset:4608
	ds_write_b128 v66, v[106:109] offset:9216
	ds_write_b128 v66, v[110:113] offset:13824
	s_waitcnt vmcnt(0)
	ds_write_b128 v66, v[144:147] offset:36864
	ds_write_b128 v66, v[122:125] offset:41472
	ds_write_b128 v66, v[118:121] offset:46080
	ds_write_b128 v66, v[114:117] offset:50688
	s_setprio 1
	ds_read_b128 v[86:89], v68 offset:18464
	s_waitcnt lgkmcnt(10)
	v_mfma_f32_32x32x16_bf16 v[34:49], v[94:97], v[126:129], v[34:49]
	ds_read_b128 v[90:93], v1 offset:55328
	global_load_dwordx4 v[102:105], v[70:71], off offset:640
	global_load_dwordx4 v[106:109], v[74:75], off offset:640
	global_load_dwordx4 v[110:113], v[78:79], off offset:640
	global_load_dwordx4 v[114:117], v[84:85], off offset:640
	global_load_dwordx4 v[118:121], v[82:83], off offset:640
	global_load_dwordx4 v[122:125], v[80:81], off offset:640
	global_load_dwordx4 v[140:143], v[72:73], off offset:640
	global_load_dwordx4 v[144:147], v[76:77], off offset:640
	s_waitcnt lgkmcnt(10)
	v_mfma_f32_32x32x16_bf16 v[50:65], v[94:97], v[130:133], v[50:65]
	ds_read_b128 v[94:97], v1 offset:59936
	s_waitcnt lgkmcnt(1)
	v_mfma_f32_32x32x16_bf16 v[34:49], v[86:89], v[90:93], v[34:49]
	s_waitcnt lgkmcnt(0)
	v_mfma_f32_32x32x16_bf16 v[50:65], v[86:89], v[94:97], v[50:65]
	ds_read_b128 v[86:89], v68 offset:23072
	v_mfma_f32_32x32x16_bf16 v[2:17], v[98:101], v[126:129], v[2:17]
	v_mfma_f32_32x32x16_bf16 v[18:33], v[98:101], v[130:133], v[18:33]
	ds_read_b128 v[98:101], v68 offset:23136
	s_waitcnt lgkmcnt(1)
	v_mfma_f32_32x32x16_bf16 v[2:17], v[86:89], v[90:93], v[2:17]
	ds_read_b128 v[90:93], v1 offset:55360
	v_mfma_f32_32x32x16_bf16 v[18:33], v[86:89], v[94:97], v[18:33]
	ds_read_b128 v[86:89], v68 offset:18496
	ds_read_b128 v[94:97], v1 offset:59968
	s_waitcnt lgkmcnt(1)
	v_mfma_f32_32x32x16_bf16 v[34:49], v[86:89], v[90:93], v[34:49]
	s_waitcnt lgkmcnt(0)
	v_mfma_f32_32x32x16_bf16 v[50:65], v[86:89], v[94:97], v[50:65]
	ds_read_b128 v[86:89], v68 offset:23104
	s_waitcnt lgkmcnt(0)
	v_mfma_f32_32x32x16_bf16 v[2:17], v[86:89], v[90:93], v[2:17]
	ds_read_b128 v[90:93], v1 offset:55392
	v_mfma_f32_32x32x16_bf16 v[18:33], v[86:89], v[94:97], v[18:33]
	ds_read_b128 v[86:89], v68 offset:18528
	ds_read_b128 v[94:97], v1 offset:60000
	s_waitcnt lgkmcnt(1)
	v_mfma_f32_32x32x16_bf16 v[34:49], v[86:89], v[90:93], v[34:49]
	s_waitcnt lgkmcnt(0)
	v_mfma_f32_32x32x16_bf16 v[50:65], v[86:89], v[94:97], v[50:65]
	v_mfma_f32_32x32x16_bf16 v[2:17], v[98:101], v[90:93], v[2:17]
	v_mfma_f32_32x32x16_bf16 v[18:33], v[98:101], v[94:97], v[18:33]
	s_setprio 0
	s_barrier
	ds_read_b128 v[94:97], v68
	ds_read_b128 v[98:101], v68 offset:4608
	ds_read_b128 v[126:129], v1 offset:36864
	ds_read_b128 v[130:133], v1 offset:41472
	s_waitcnt vmcnt(1)
	ds_write_b128 v66, v[140:143] offset:18432
	ds_write_b128 v66, v[102:105] offset:23040
	ds_write_b128 v66, v[106:109] offset:27648
	ds_write_b128 v66, v[110:113] offset:32256
	s_waitcnt vmcnt(0)
	ds_write_b128 v66, v[144:147] offset:55296
	ds_write_b128 v66, v[122:125] offset:59904
	ds_write_b128 v66, v[118:121] offset:64512
	ds_write_b128 v69, v[114:117] offset:32256
	s_setprio 1
	ds_read_b128 v[86:89], v68 offset:32
	s_waitcnt lgkmcnt(10)
	v_mfma_f32_32x32x16_bf16 v[34:49], v[94:97], v[126:129], v[34:49]
	ds_read_b128 v[90:93], v1 offset:36896
	global_load_dwordx4 v[102:105], v[70:71], off offset:768
	global_load_dwordx4 v[106:109], v[74:75], off offset:768
	global_load_dwordx4 v[110:113], v[78:79], off offset:768
	global_load_dwordx4 v[114:117], v[84:85], off offset:768
	global_load_dwordx4 v[118:121], v[82:83], off offset:768
	global_load_dwordx4 v[122:125], v[80:81], off offset:768
	global_load_dwordx4 v[140:143], v[72:73], off offset:768
	global_load_dwordx4 v[144:147], v[76:77], off offset:768
	s_waitcnt lgkmcnt(10)
	v_mfma_f32_32x32x16_bf16 v[50:65], v[94:97], v[130:133], v[50:65]
	ds_read_b128 v[94:97], v1 offset:41504
	s_waitcnt lgkmcnt(1)
	v_mfma_f32_32x32x16_bf16 v[34:49], v[86:89], v[90:93], v[34:49]
	s_waitcnt lgkmcnt(0)
	v_mfma_f32_32x32x16_bf16 v[50:65], v[86:89], v[94:97], v[50:65]
	ds_read_b128 v[86:89], v68 offset:4640
	v_mfma_f32_32x32x16_bf16 v[2:17], v[98:101], v[126:129], v[2:17]
	v_mfma_f32_32x32x16_bf16 v[18:33], v[98:101], v[130:133], v[18:33]
	ds_read_b128 v[98:101], v68 offset:4704
	s_waitcnt lgkmcnt(1)
	v_mfma_f32_32x32x16_bf16 v[2:17], v[86:89], v[90:93], v[2:17]
	ds_read_b128 v[90:93], v1 offset:36928
	v_mfma_f32_32x32x16_bf16 v[18:33], v[86:89], v[94:97], v[18:33]
	ds_read_b128 v[86:89], v68 offset:64
	ds_read_b128 v[94:97], v1 offset:41536
	s_waitcnt lgkmcnt(1)
	v_mfma_f32_32x32x16_bf16 v[34:49], v[86:89], v[90:93], v[34:49]
	s_waitcnt lgkmcnt(0)
	v_mfma_f32_32x32x16_bf16 v[50:65], v[86:89], v[94:97], v[50:65]
	ds_read_b128 v[86:89], v68 offset:4672
	s_waitcnt lgkmcnt(0)
	v_mfma_f32_32x32x16_bf16 v[2:17], v[86:89], v[90:93], v[2:17]
	ds_read_b128 v[90:93], v1 offset:36960
	v_mfma_f32_32x32x16_bf16 v[18:33], v[86:89], v[94:97], v[18:33]
	ds_read_b128 v[86:89], v68 offset:96
	ds_read_b128 v[94:97], v1 offset:41568
	s_waitcnt lgkmcnt(1)
	v_mfma_f32_32x32x16_bf16 v[34:49], v[86:89], v[90:93], v[34:49]
	s_waitcnt lgkmcnt(0)
	v_mfma_f32_32x32x16_bf16 v[50:65], v[86:89], v[94:97], v[50:65]
	v_mfma_f32_32x32x16_bf16 v[2:17], v[98:101], v[90:93], v[2:17]
	v_mfma_f32_32x32x16_bf16 v[18:33], v[98:101], v[94:97], v[18:33]
	s_setprio 0
	s_barrier
; #define MFMA(a, b, c) __builtin_amdgcn_mfma_f32_32x32x16_bf16((a), (b), (c), 0, 0, 0)
; template <int TM, int TN>
; DI void gemm_mainloop(const u16* __restrict__ A, long lda, const u16* __restrict__ Bt, long ldb, int K, char* smem,
;                       f32x16 (&acc)[TM][TN]) {
;     ...
;   for (int kt = 0; kt < nk; kt++) {
;     const int buf = kt & 1;
;     const u16* cA = sA + buf * BM * LD + (wm * 32 * TM + r) * LD + h * 8;
;     const u16* cB = sB + buf * BN * LD + (wn * 32 * TN + r) * LD + h * 8;
;     bf16x8 af[TM], bfr[TN];
; #pragma unroll
;     for (int tm = 0; tm < TM; tm++) af[tm] = *(const bf16x8*)(cA + tm * 32 * LD);
; #pragma unroll
;     for (int tn = 0; tn < TN; tn++) bfr[tn] = *(const bf16x8*)(cB + tn * 32 * LD);
;     if (kt + 1 < nk) GEMM_SSTORE(buf ^ 1)
;     __builtin_amdgcn_sched_barrier(0);
;     __builtin_amdgcn_s_setprio(1);
; #pragma unroll
;     for (int tm = 0; tm < TM; tm++)
; #pragma unroll
;       for (int tn = 0; tn < TN; tn++) acc[tm][tn] = MFMA(af[tm], bfr[tn], acc[tm][tn]);
; #pragma unroll
;     for (int tm = 0; tm < TM; tm++) af[tm] = *(const bf16x8*)(cA + tm * 32 * LD + 16);
; #pragma unroll
;     for (int tn = 0; tn < TN; tn++) bfr[tn] = *(const bf16x8*)(cB + tn * 32 * LD + 16);
; #pragma unroll
;     for (int tm = 0; tm < TM; tm++)
; #pragma unroll
;       for (int tn = 0; tn < TN; tn++) acc[tm][tn] = MFMA(af[tm], bfr[tn], acc[tm][tn]);
;     __builtin_amdgcn_sched_group_barrier(0x8, 4, 0);
;     if (kt + 2 < nk) GEMM_GLOAD((kt + 2) * 64)
; #pragma unroll
;     for (int ks = 2; ks < 4; ks++) {
; #pragma unroll
;       for (int tm = 0; tm < TM; tm++) af[tm] = *(const bf16x8*)(cA + tm * 32 * LD + ks * 16);
; #pragma unroll
;       for (int tn = 0; tn < TN; tn++) bfr[tn] = *(const bf16x8*)(cB + tn * 32 * LD + ks * 16);
; #pragma unroll
;       for (int tm = 0; tm < TM; tm++)
; #pragma unroll
;         for (int tn = 0; tn < TN; tn++) acc[tm][tn] = MFMA(af[tm], bfr[tn], acc[tm][tn]);
;     }
;     __builtin_amdgcn_s_setprio(0);
;     __syncthreads();
;   }
	ds_read_b128 v[94:97], v68 offset:18432
	ds_read_b128 v[98:101], v68 offset:23040
	ds_read_b128 v[126:129], v1 offset:55296
	ds_read_b128 v[130:133], v1 offset:59904
	s_waitcnt vmcnt(1)
	ds_write_b128 v66, v[140:143]
	ds_write_b128 v66, v[102:105] offset:4608
	ds_write_b128 v66, v[106:109] offset:9216
	ds_write_b128 v66, v[110:113] offset:13824
	s_waitcnt vmcnt(0)
	ds_write_b128 v66, v[144:147] offset:36864
	ds_write_b128 v66, v[122:125] offset:41472
	ds_write_b128 v66, v[118:121] offset:46080
	ds_write_b128 v66, v[114:117] offset:50688
	s_setprio 1
	ds_read_b128 v[86:89], v68 offset:18464
	s_waitcnt lgkmcnt(10)
	v_mfma_f32_32x32x16_bf16 v[34:49], v[94:97], v[126:129], v[34:49]
	ds_read_b128 v[90:93], v1 offset:55328
	global_load_dwordx4 v[102:105], v[70:71], off offset:896
	global_load_dwordx4 v[106:109], v[74:75], off offset:896
	global_load_dwordx4 v[110:113], v[78:79], off offset:896
	global_load_dwordx4 v[114:117], v[84:85], off offset:896
	global_load_dwordx4 v[118:121], v[82:83], off offset:896
	global_load_dwordx4 v[122:125], v[80:81], off offset:896
	global_load_dwordx4 v[140:143], v[72:73], off offset:896
	global_load_dwordx4 v[144:147], v[76:77], off offset:896
	s_waitcnt lgkmcnt(10)
	v_mfma_f32_32x32x16_bf16 v[50:65], v[94:97], v[130:133], v[50:65]
	ds_read_b128 v[94:97], v1 offset:59936
	s_waitcnt lgkmcnt(1)
	v_mfma_f32_32x32x16_bf16 v[34:49], v[86:89], v[90:93], v[34:49]
	s_waitcnt lgkmcnt(0)
	v_mfma_f32_32x32x16_bf16 v[50:65], v[86:89], v[94:97], v[50:65]
	ds_read_b128 v[86:89], v68 offset:23072
	v_mfma_f32_32x32x16_bf16 v[2:17], v[98:101], v[126:129], v[2:17]
	v_mfma_f32_32x32x16_bf16 v[18:33], v[98:101], v[130:133], v[18:33]
	ds_read_b128 v[98:101], v68 offset:23136
	s_waitcnt lgkmcnt(1)
	v_mfma_f32_32x32x16_bf16 v[2:17], v[86:89], v[90:93], v[2:17]
	ds_read_b128 v[90:93], v1 offset:55360
	v_mfma_f32_32x32x16_bf16 v[18:33], v[86:89], v[94:97], v[18:33]
	ds_read_b128 v[86:89], v68 offset:18496
	ds_read_b128 v[94:97], v1 offset:59968
	s_waitcnt lgkmcnt(1)
	v_mfma_f32_32x32x16_bf16 v[34:49], v[86:89], v[90:93], v[34:49]
	s_waitcnt lgkmcnt(0)
	v_mfma_f32_32x32x16_bf16 v[50:65], v[86:89], v[94:97], v[50:65]
	ds_read_b128 v[86:89], v68 offset:23104
	s_waitcnt lgkmcnt(0)
	v_mfma_f32_32x32x16_bf16 v[2:17], v[86:89], v[90:93], v[2:17]
	ds_read_b128 v[90:93], v1 offset:55392
	v_mfma_f32_32x32x16_bf16 v[18:33], v[86:89], v[94:97], v[18:33]
	ds_read_b128 v[86:89], v68 offset:18528
	ds_read_b128 v[94:97], v1 offset:60000
	s_waitcnt lgkmcnt(1)
	v_mfma_f32_32x32x16_bf16 v[34:49], v[86:89], v[90:93], v[34:49]
	s_waitcnt lgkmcnt(0)
	v_mfma_f32_32x32x16_bf16 v[50:65], v[86:89], v[94:97], v[50:65]
	v_mfma_f32_32x32x16_bf16 v[2:17], v[98:101], v[90:93], v[2:17]
	v_mfma_f32_32x32x16_bf16 v[18:33], v[98:101], v[94:97], v[18:33]
	s_setprio 0
	s_barrier
	ds_read_b128 v[94:97], v68
	ds_read_b128 v[98:101], v68 offset:4608
	ds_read_b128 v[126:129], v1 offset:36864
	ds_read_b128 v[130:133], v1 offset:41472
	s_waitcnt vmcnt(1)
	ds_write_b128 v66, v[140:143] offset:18432
	ds_write_b128 v66, v[102:105] offset:23040
	ds_write_b128 v66, v[106:109] offset:27648
	ds_write_b128 v66, v[110:113] offset:32256
	s_waitcnt vmcnt(0)
	ds_write_b128 v66, v[144:147] offset:55296
	ds_write_b128 v66, v[122:125] offset:59904
	ds_write_b128 v66, v[118:121] offset:64512
	ds_write_b128 v69, v[114:117] offset:32256
	s_setprio 1
	ds_read_b128 v[86:89], v68 offset:32
	s_waitcnt lgkmcnt(10)
	v_mfma_f32_32x32x16_bf16 v[34:49], v[94:97], v[126:129], v[34:49]
	ds_read_b128 v[90:93], v1 offset:36896
	global_load_dwordx4 v[102:105], v[70:71], off offset:1024
	global_load_dwordx4 v[106:109], v[74:75], off offset:1024
	global_load_dwordx4 v[110:113], v[78:79], off offset:1024
	global_load_dwordx4 v[114:117], v[84:85], off offset:1024
	global_load_dwordx4 v[118:121], v[82:83], off offset:1024
	global_load_dwordx4 v[122:125], v[80:81], off offset:1024
	global_load_dwordx4 v[140:143], v[72:73], off offset:1024
	global_load_dwordx4 v[144:147], v[76:77], off offset:1024
	s_waitcnt lgkmcnt(10)
	v_mfma_f32_32x32x16_bf16 v[50:65], v[94:97], v[130:133], v[50:65]
	ds_read_b128 v[94:97], v1 offset:41504
	s_waitcnt lgkmcnt(1)
	v_mfma_f32_32x32x16_bf16 v[34:49], v[86:89], v[90:93], v[34:49]
	s_waitcnt lgkmcnt(0)
	v_mfma_f32_32x32x16_bf16 v[50:65], v[86:89], v[94:97], v[50:65]
	ds_read_b128 v[86:89], v68 offset:4640
	v_mfma_f32_32x32x16_bf16 v[2:17], v[98:101], v[126:129], v[2:17]
	v_mfma_f32_32x32x16_bf16 v[18:33], v[98:101], v[130:133], v[18:33]
	ds_read_b128 v[98:101], v68 offset:4704
	s_waitcnt lgkmcnt(1)
	v_mfma_f32_32x32x16_bf16 v[2:17], v[86:89], v[90:93], v[2:17]
	ds_read_b128 v[90:93], v1 offset:36928
	v_mfma_f32_32x32x16_bf16 v[18:33], v[86:89], v[94:97], v[18:33]
	ds_read_b128 v[86:89], v68 offset:64
	ds_read_b128 v[94:97], v1 offset:41536
	s_waitcnt lgkmcnt(1)
	v_mfma_f32_32x32x16_bf16 v[34:49], v[86:89], v[90:93], v[34:49]
	s_waitcnt lgkmcnt(0)
	v_mfma_f32_32x32x16_bf16 v[50:65], v[86:89], v[94:97], v[50:65]
	ds_read_b128 v[86:89], v68 offset:4672
	s_waitcnt lgkmcnt(0)
	v_mfma_f32_32x32x16_bf16 v[2:17], v[86:89], v[90:93], v[2:17]
	ds_read_b128 v[90:93], v1 offset:36960
	v_mfma_f32_32x32x16_bf16 v[18:33], v[86:89], v[94:97], v[18:33]
	ds_read_b128 v[86:89], v68 offset:96
	ds_read_b128 v[94:97], v1 offset:41568
	s_waitcnt lgkmcnt(1)
	v_mfma_f32_32x32x16_bf16 v[34:49], v[86:89], v[90:93], v[34:49]
	s_waitcnt lgkmcnt(0)
	v_mfma_f32_32x32x16_bf16 v[50:65], v[86:89], v[94:97], v[50:65]
	v_mfma_f32_32x32x16_bf16 v[2:17], v[98:101], v[90:93], v[2:17]
	v_mfma_f32_32x32x16_bf16 v[18:33], v[98:101], v[94:97], v[18:33]
	s_setprio 0
	s_barrier
; #define MFMA(a, b, c) __builtin_amdgcn_mfma_f32_32x32x16_bf16((a), (b), (c), 0, 0, 0)
; template <int TM, int TN>
; DI void gemm_mainloop(const u16* __restrict__ A, long lda, const u16* __restrict__ Bt, long ldb, int K, char* smem,
;                       f32x16 (&acc)[TM][TN]) {
;     ...
;   for (int kt = 0; kt < nk; kt++) {
;     const int buf = kt & 1;
;     const u16* cA = sA + buf * BM * LD + (wm * 32 * TM + r) * LD + h * 8;
;     const u16* cB = sB + buf * BN * LD + (wn * 32 * TN + r) * LD + h * 8;
;     bf16x8 af[TM], bfr[TN];
; #pragma unroll
;     for (int tm = 0; tm < TM; tm++) af[tm] = *(const bf16x8*)(cA + tm * 32 * LD);
; #pragma unroll
;     for (int tn = 0; tn < TN; tn++) bfr[tn] = *(const bf16x8*)(cB + tn * 32 * LD);
;     if (kt + 1 < nk) GEMM_SSTORE(buf ^ 1)
;     __builtin_amdgcn_sched_barrier(0);
;     __builtin_amdgcn_s_setprio(1);
; #pragma unroll
;     for (int tm = 0; tm < TM; tm++)
; #pragma unroll
;       for (int tn = 0; tn < TN; tn++) acc[tm][tn] = MFMA(af[tm], bfr[tn], acc[tm][tn]);
; #pragma unroll
;     for (int tm = 0; tm < TM; tm++) af[tm] = *(const bf16x8*)(cA + tm * 32 * LD + 16);
; #pragma unroll
;     for (int tn = 0; tn < TN; tn++) bfr[tn] = *(const bf16x8*)(cB + tn * 32 * LD + 16);
; #pragma unroll
;     for (int tm = 0; tm < TM; tm++)
; #pragma unroll
;       for (int tn = 0; tn < TN; tn++) acc[tm][tn] = MFMA(af[tm], bfr[tn], acc[tm][tn]);
;     __builtin_amdgcn_sched_group_barrier(0x8, 4, 0);
;     if (kt + 2 < nk) GEMM_GLOAD((kt + 2) * 64)
; #pragma unroll
;     for (int ks = 2; ks < 4; ks++) {
; #pragma unroll
;       for (int tm = 0; tm < TM; tm++) af[tm] = *(const bf16x8*)(cA + tm * 32 * LD + ks * 16);
; #pragma unroll
;       for (int tn = 0; tn < TN; tn++) bfr[tn] = *(const bf16x8*)(cB + tn * 32 * LD + ks * 16);
; #pragma unroll
;       for (int tm = 0; tm < TM; tm++)
; #pragma unroll
;         for (int tn = 0; tn < TN; tn++) acc[tm][tn] = MFMA(af[tm], bfr[tn], acc[tm][tn]);
;     }
;     __builtin_amdgcn_s_setprio(0);
;     __syncthreads();
;   }
	ds_read_b128 v[94:97], v68 offset:18432
	ds_read_b128 v[98:101], v68 offset:23040
	ds_read_b128 v[126:129], v1 offset:55296
	ds_read_b128 v[130:133], v1 offset:59904
	s_waitcnt vmcnt(1)
	ds_write_b128 v66, v[140:143]
	ds_write_b128 v66, v[102:105] offset:4608
	ds_write_b128 v66, v[106:109] offset:9216
	ds_write_b128 v66, v[110:113] offset:13824
	s_waitcnt vmcnt(0)
	ds_write_b128 v66, v[144:147] offset:36864
	ds_write_b128 v66, v[122:125] offset:41472
	ds_write_b128 v66, v[118:121] offset:46080
	ds_write_b128 v66, v[114:117] offset:50688
	s_setprio 1
	ds_read_b128 v[86:89], v68 offset:18464
	s_waitcnt lgkmcnt(10)
	v_mfma_f32_32x32x16_bf16 v[34:49], v[94:97], v[126:129], v[34:49]
	ds_read_b128 v[90:93], v1 offset:55328
	global_load_dwordx4 v[102:105], v[70:71], off offset:1152
	global_load_dwordx4 v[106:109], v[74:75], off offset:1152
	global_load_dwordx4 v[110:113], v[78:79], off offset:1152
	global_load_dwordx4 v[114:117], v[84:85], off offset:1152
	global_load_dwordx4 v[118:121], v[82:83], off offset:1152
	global_load_dwordx4 v[122:125], v[80:81], off offset:1152
	global_load_dwordx4 v[140:143], v[72:73], off offset:1152
	global_load_dwordx4 v[144:147], v[76:77], off offset:1152
	s_waitcnt lgkmcnt(10)
	v_mfma_f32_32x32x16_bf16 v[50:65], v[94:97], v[130:133], v[50:65]
	ds_read_b128 v[94:97], v1 offset:59936
	s_waitcnt lgkmcnt(1)
	v_mfma_f32_32x32x16_bf16 v[34:49], v[86:89], v[90:93], v[34:49]
	s_waitcnt lgkmcnt(0)
	v_mfma_f32_32x32x16_bf16 v[50:65], v[86:89], v[94:97], v[50:65]
	ds_read_b128 v[86:89], v68 offset:23072
	v_mfma_f32_32x32x16_bf16 v[2:17], v[98:101], v[126:129], v[2:17]
	v_mfma_f32_32x32x16_bf16 v[18:33], v[98:101], v[130:133], v[18:33]
	ds_read_b128 v[98:101], v68 offset:23136
	s_waitcnt lgkmcnt(1)
	v_mfma_f32_32x32x16_bf16 v[2:17], v[86:89], v[90:93], v[2:17]
	ds_read_b128 v[90:93], v1 offset:55360
	v_mfma_f32_32x32x16_bf16 v[18:33], v[86:89], v[94:97], v[18:33]
	ds_read_b128 v[86:89], v68 offset:18496
	ds_read_b128 v[94:97], v1 offset:59968
	s_waitcnt lgkmcnt(1)
	v_mfma_f32_32x32x16_bf16 v[34:49], v[86:89], v[90:93], v[34:49]
	s_waitcnt lgkmcnt(0)
	v_mfma_f32_32x32x16_bf16 v[50:65], v[86:89], v[94:97], v[50:65]
	ds_read_b128 v[86:89], v68 offset:23104
	s_waitcnt lgkmcnt(0)
	v_mfma_f32_32x32x16_bf16 v[2:17], v[86:89], v[90:93], v[2:17]
	ds_read_b128 v[90:93], v1 offset:55392
	v_mfma_f32_32x32x16_bf16 v[18:33], v[86:89], v[94:97], v[18:33]
	ds_read_b128 v[86:89], v68 offset:18528
	ds_read_b128 v[94:97], v1 offset:60000
	s_waitcnt lgkmcnt(1)
	v_mfma_f32_32x32x16_bf16 v[34:49], v[86:89], v[90:93], v[34:49]
	s_waitcnt lgkmcnt(0)
	v_mfma_f32_32x32x16_bf16 v[50:65], v[86:89], v[94:97], v[50:65]
	v_mfma_f32_32x32x16_bf16 v[2:17], v[98:101], v[90:93], v[2:17]
	v_mfma_f32_32x32x16_bf16 v[18:33], v[98:101], v[94:97], v[18:33]
	s_setprio 0
	s_barrier
	ds_read_b128 v[94:97], v68
	ds_read_b128 v[98:101], v68 offset:4608
	ds_read_b128 v[126:129], v1 offset:36864
	ds_read_b128 v[130:133], v1 offset:41472
	s_waitcnt vmcnt(1)
	ds_write_b128 v66, v[140:143] offset:18432
	ds_write_b128 v66, v[102:105] offset:23040
	ds_write_b128 v66, v[106:109] offset:27648
	ds_write_b128 v66, v[110:113] offset:32256
	s_waitcnt vmcnt(0)
	ds_write_b128 v66, v[144:147] offset:55296
	ds_write_b128 v66, v[122:125] offset:59904
	ds_write_b128 v66, v[118:121] offset:64512
	ds_write_b128 v69, v[114:117] offset:32256
	s_setprio 1
	ds_read_b128 v[86:89], v68 offset:32
	s_waitcnt lgkmcnt(10)
	v_mfma_f32_32x32x16_bf16 v[34:49], v[94:97], v[126:129], v[34:49]
	ds_read_b128 v[90:93], v1 offset:36896
	global_load_dwordx4 v[102:105], v[70:71], off offset:1280
	global_load_dwordx4 v[106:109], v[74:75], off offset:1280
	global_load_dwordx4 v[110:113], v[78:79], off offset:1280
	global_load_dwordx4 v[114:117], v[84:85], off offset:1280
	global_load_dwordx4 v[118:121], v[82:83], off offset:1280
	global_load_dwordx4 v[122:125], v[80:81], off offset:1280
	global_load_dwordx4 v[140:143], v[72:73], off offset:1280
	global_load_dwordx4 v[144:147], v[76:77], off offset:1280
	s_waitcnt lgkmcnt(10)
	v_mfma_f32_32x32x16_bf16 v[50:65], v[94:97], v[130:133], v[50:65]
	ds_read_b128 v[94:97], v1 offset:41504
	s_waitcnt lgkmcnt(1)
	v_mfma_f32_32x32x16_bf16 v[34:49], v[86:89], v[90:93], v[34:49]
	s_waitcnt lgkmcnt(0)
	v_mfma_f32_32x32x16_bf16 v[50:65], v[86:89], v[94:97], v[50:65]
	ds_read_b128 v[86:89], v68 offset:4640
	v_mfma_f32_32x32x16_bf16 v[2:17], v[98:101], v[126:129], v[2:17]
	v_mfma_f32_32x32x16_bf16 v[18:33], v[98:101], v[130:133], v[18:33]
	ds_read_b128 v[98:101], v68 offset:4704
	s_waitcnt lgkmcnt(1)
	v_mfma_f32_32x32x16_bf16 v[2:17], v[86:89], v[90:93], v[2:17]
	ds_read_b128 v[90:93], v1 offset:36928
	v_mfma_f32_32x32x16_bf16 v[18:33], v[86:89], v[94:97], v[18:33]
	ds_read_b128 v[86:89], v68 offset:64
	ds_read_b128 v[94:97], v1 offset:41536
	s_waitcnt lgkmcnt(1)
	v_mfma_f32_32x32x16_bf16 v[34:49], v[86:89], v[90:93], v[34:49]
	s_waitcnt lgkmcnt(0)
	v_mfma_f32_32x32x16_bf16 v[50:65], v[86:89], v[94:97], v[50:65]
	ds_read_b128 v[86:89], v68 offset:4672
	s_waitcnt lgkmcnt(0)
	v_mfma_f32_32x32x16_bf16 v[2:17], v[86:89], v[90:93], v[2:17]
	ds_read_b128 v[90:93], v1 offset:36960
	v_mfma_f32_32x32x16_bf16 v[18:33], v[86:89], v[94:97], v[18:33]
	ds_read_b128 v[86:89], v68 offset:96
	ds_read_b128 v[94:97], v1 offset:41568
	s_waitcnt lgkmcnt(1)
	v_mfma_f32_32x32x16_bf16 v[34:49], v[86:89], v[90:93], v[34:49]
	s_waitcnt lgkmcnt(0)
	v_mfma_f32_32x32x16_bf16 v[50:65], v[86:89], v[94:97], v[50:65]
	v_mfma_f32_32x32x16_bf16 v[2:17], v[98:101], v[90:93], v[2:17]
	v_mfma_f32_32x32x16_bf16 v[18:33], v[98:101], v[94:97], v[18:33]
	s_setprio 0
	s_barrier
; #define MFMA(a, b, c) __builtin_amdgcn_mfma_f32_32x32x16_bf16((a), (b), (c), 0, 0, 0)
; template <int TM, int TN>
; DI void gemm_mainloop(const u16* __restrict__ A, long lda, const u16* __restrict__ Bt, long ldb, int K, char* smem,
;                       f32x16 (&acc)[TM][TN]) {
;     ...
;   for (int kt = 0; kt < nk; kt++) {
;     const int buf = kt & 1;
;     const u16* cA = sA + buf * BM * LD + (wm * 32 * TM + r) * LD + h * 8;
;     const u16* cB = sB + buf * BN * LD + (wn * 32 * TN + r) * LD + h * 8;
;     bf16x8 af[TM], bfr[TN];
; #pragma unroll
;     for (int tm = 0; tm < TM; tm++) af[tm] = *(const bf16x8*)(cA + tm * 32 * LD);
; #pragma unroll
;     for (int tn = 0; tn < TN; tn++) bfr[tn] = *(const bf16x8*)(cB + tn * 32 * LD);
;     if (kt + 1 < nk) GEMM_SSTORE(buf ^ 1)
;     __builtin_amdgcn_sched_barrier(0);
;     __builtin_amdgcn_s_setprio(1);
; #pragma unroll
;     for (int tm = 0; tm < TM; tm++)
; #pragma unroll
;       for (int tn = 0; tn < TN; tn++) acc[tm][tn] = MFMA(af[tm], bfr[tn], acc[tm][tn]);
; #pragma unroll
;     for (int tm = 0; tm < TM; tm++) af[tm] = *(const bf16x8*)(cA + tm * 32 * LD + 16);
; #pragma unroll
;     for (int tn = 0; tn < TN; tn++) bfr[tn] = *(const bf16x8*)(cB + tn * 32 * LD + 16);
; #pragma unroll
;     for (int tm = 0; tm < TM; tm++)
; #pragma unroll
;       for (int tn = 0; tn < TN; tn++) acc[tm][tn] = MFMA(af[tm], bfr[tn], acc[tm][tn]);
;     __builtin_amdgcn_sched_group_barrier(0x8, 4, 0);
;     if (kt + 2 < nk) GEMM_GLOAD((kt + 2) * 64)
; #pragma unroll
;     for (int ks = 2; ks < 4; ks++) {
; #pragma unroll
;       for (int tm = 0; tm < TM; tm++) af[tm] = *(const bf16x8*)(cA + tm * 32 * LD + ks * 16);
; #pragma unroll
;       for (int tn = 0; tn < TN; tn++) bfr[tn] = *(const bf16x8*)(cB + tn * 32 * LD + ks * 16);
; #pragma unroll
;       for (int tm = 0; tm < TM; tm++)
; #pragma unroll
;         for (int tn = 0; tn < TN; tn++) acc[tm][tn] = MFMA(af[tm], bfr[tn], acc[tm][tn]);
;     }
;     __builtin_amdgcn_s_setprio(0);
;     __syncthreads();
;   }
	ds_read_b128 v[94:97], v68 offset:18432
	ds_read_b128 v[98:101], v68 offset:23040
	ds_read_b128 v[126:129], v1 offset:55296
	ds_read_b128 v[130:133], v1 offset:59904
	s_waitcnt vmcnt(1)
	ds_write_b128 v66, v[140:143]
	ds_write_b128 v66, v[102:105] offset:4608
	ds_write_b128 v66, v[106:109] offset:9216
	ds_write_b128 v66, v[110:113] offset:13824
	s_waitcnt vmcnt(0)
	ds_write_b128 v66, v[144:147] offset:36864
	ds_write_b128 v66, v[122:125] offset:41472
	ds_write_b128 v66, v[118:121] offset:46080
	ds_write_b128 v66, v[114:117] offset:50688
	s_setprio 1
	ds_read_b128 v[86:89], v68 offset:18464
	s_waitcnt lgkmcnt(10)
	v_mfma_f32_32x32x16_bf16 v[34:49], v[94:97], v[126:129], v[34:49]
	ds_read_b128 v[90:93], v1 offset:55328
	global_load_dwordx4 v[102:105], v[70:71], off offset:1408
	global_load_dwordx4 v[106:109], v[74:75], off offset:1408
	global_load_dwordx4 v[110:113], v[78:79], off offset:1408
	global_load_dwordx4 v[114:117], v[84:85], off offset:1408
	global_load_dwordx4 v[118:121], v[82:83], off offset:1408
	global_load_dwordx4 v[122:125], v[80:81], off offset:1408
	global_load_dwordx4 v[140:143], v[72:73], off offset:1408
	global_load_dwordx4 v[144:147], v[76:77], off offset:1408
	s_waitcnt lgkmcnt(10)
	v_mfma_f32_32x32x16_bf16 v[50:65], v[94:97], v[130:133], v[50:65]
	ds_read_b128 v[94:97], v1 offset:59936
	s_waitcnt lgkmcnt(1)
	v_mfma_f32_32x32x16_bf16 v[34:49], v[86:89], v[90:93], v[34:49]
	s_waitcnt lgkmcnt(0)
	v_mfma_f32_32x32x16_bf16 v[50:65], v[86:89], v[94:97], v[50:65]
	ds_read_b128 v[86:89], v68 offset:23072
	v_mfma_f32_32x32x16_bf16 v[2:17], v[98:101], v[126:129], v[2:17]
	v_mfma_f32_32x32x16_bf16 v[18:33], v[98:101], v[130:133], v[18:33]
	ds_read_b128 v[98:101], v68 offset:23136
	s_waitcnt lgkmcnt(1)
	v_mfma_f32_32x32x16_bf16 v[2:17], v[86:89], v[90:93], v[2:17]
	ds_read_b128 v[90:93], v1 offset:55360
	v_mfma_f32_32x32x16_bf16 v[18:33], v[86:89], v[94:97], v[18:33]
	ds_read_b128 v[86:89], v68 offset:18496
	ds_read_b128 v[94:97], v1 offset:59968
	s_waitcnt lgkmcnt(1)
	v_mfma_f32_32x32x16_bf16 v[34:49], v[86:89], v[90:93], v[34:49]
	s_waitcnt lgkmcnt(0)
	v_mfma_f32_32x32x16_bf16 v[50:65], v[86:89], v[94:97], v[50:65]
	ds_read_b128 v[86:89], v68 offset:23104
	s_waitcnt lgkmcnt(0)
	v_mfma_f32_32x32x16_bf16 v[2:17], v[86:89], v[90:93], v[2:17]
	ds_read_b128 v[90:93], v1 offset:55392
	v_mfma_f32_32x32x16_bf16 v[18:33], v[86:89], v[94:97], v[18:33]
	ds_read_b128 v[86:89], v68 offset:18528
	ds_read_b128 v[94:97], v1 offset:60000
	s_waitcnt lgkmcnt(1)
	v_mfma_f32_32x32x16_bf16 v[34:49], v[86:89], v[90:93], v[34:49]
	s_waitcnt lgkmcnt(0)
	v_mfma_f32_32x32x16_bf16 v[50:65], v[86:89], v[94:97], v[50:65]
	v_mfma_f32_32x32x16_bf16 v[2:17], v[98:101], v[90:93], v[2:17]
	v_mfma_f32_32x32x16_bf16 v[18:33], v[98:101], v[94:97], v[18:33]
	s_setprio 0
	s_barrier
	ds_read_b128 v[94:97], v68
	ds_read_b128 v[98:101], v68 offset:4608
	ds_read_b128 v[126:129], v1 offset:36864
	ds_read_b128 v[130:133], v1 offset:41472
	s_waitcnt vmcnt(1)
	ds_write_b128 v66, v[140:143] offset:18432
	ds_write_b128 v66, v[102:105] offset:23040
	ds_write_b128 v66, v[106:109] offset:27648
	ds_write_b128 v66, v[110:113] offset:32256
	s_waitcnt vmcnt(0)
	ds_write_b128 v66, v[144:147] offset:55296
	ds_write_b128 v66, v[122:125] offset:59904
	ds_write_b128 v66, v[118:121] offset:64512
	ds_write_b128 v69, v[114:117] offset:32256
	s_setprio 1
	ds_read_b128 v[86:89], v68 offset:32
	s_waitcnt lgkmcnt(10)
	v_mfma_f32_32x32x16_bf16 v[34:49], v[94:97], v[126:129], v[34:49]
	ds_read_b128 v[90:93], v1 offset:36896
	global_load_dwordx4 v[102:105], v[70:71], off offset:1536
	global_load_dwordx4 v[106:109], v[74:75], off offset:1536
	global_load_dwordx4 v[110:113], v[78:79], off offset:1536
	global_load_dwordx4 v[114:117], v[84:85], off offset:1536
	global_load_dwordx4 v[118:121], v[82:83], off offset:1536
	global_load_dwordx4 v[122:125], v[80:81], off offset:1536
	global_load_dwordx4 v[140:143], v[72:73], off offset:1536
	global_load_dwordx4 v[144:147], v[76:77], off offset:1536
	s_waitcnt lgkmcnt(10)
	v_mfma_f32_32x32x16_bf16 v[50:65], v[94:97], v[130:133], v[50:65]
	ds_read_b128 v[94:97], v1 offset:41504
	s_waitcnt lgkmcnt(1)
	v_mfma_f32_32x32x16_bf16 v[34:49], v[86:89], v[90:93], v[34:49]
	s_waitcnt lgkmcnt(0)
	v_mfma_f32_32x32x16_bf16 v[50:65], v[86:89], v[94:97], v[50:65]
	ds_read_b128 v[86:89], v68 offset:4640
	v_mfma_f32_32x32x16_bf16 v[2:17], v[98:101], v[126:129], v[2:17]
	v_mfma_f32_32x32x16_bf16 v[18:33], v[98:101], v[130:133], v[18:33]
	ds_read_b128 v[98:101], v68 offset:4704
	s_waitcnt lgkmcnt(1)
	v_mfma_f32_32x32x16_bf16 v[2:17], v[86:89], v[90:93], v[2:17]
	ds_read_b128 v[90:93], v1 offset:36928
	v_mfma_f32_32x32x16_bf16 v[18:33], v[86:89], v[94:97], v[18:33]
	ds_read_b128 v[86:89], v68 offset:64
	ds_read_b128 v[94:97], v1 offset:41536
	s_waitcnt lgkmcnt(1)
	v_mfma_f32_32x32x16_bf16 v[34:49], v[86:89], v[90:93], v[34:49]
	s_waitcnt lgkmcnt(0)
	v_mfma_f32_32x32x16_bf16 v[50:65], v[86:89], v[94:97], v[50:65]
	ds_read_b128 v[86:89], v68 offset:4672
	s_waitcnt lgkmcnt(0)
	v_mfma_f32_32x32x16_bf16 v[2:17], v[86:89], v[90:93], v[2:17]
	ds_read_b128 v[90:93], v1 offset:36960
	v_mfma_f32_32x32x16_bf16 v[18:33], v[86:89], v[94:97], v[18:33]
	ds_read_b128 v[86:89], v68 offset:96
	ds_read_b128 v[94:97], v1 offset:41568
	s_waitcnt lgkmcnt(1)
	v_mfma_f32_32x32x16_bf16 v[34:49], v[86:89], v[90:93], v[34:49]
	s_waitcnt lgkmcnt(0)
	v_mfma_f32_32x32x16_bf16 v[50:65], v[86:89], v[94:97], v[50:65]
	v_mfma_f32_32x32x16_bf16 v[2:17], v[98:101], v[90:93], v[2:17]
	v_mfma_f32_32x32x16_bf16 v[18:33], v[98:101], v[94:97], v[18:33]
	s_setprio 0
	s_barrier
; #define MFMA(a, b, c) __builtin_amdgcn_mfma_f32_32x32x16_bf16((a), (b), (c), 0, 0, 0)
; template <int TM, int TN>
; DI void gemm_mainloop(const u16* __restrict__ A, long lda, const u16* __restrict__ Bt, long ldb, int K, char* smem,
;                       f32x16 (&acc)[TM][TN]) {
;     ...
;   for (int kt = 0; kt < nk; kt++) {
;     const int buf = kt & 1;
;     const u16* cA = sA + buf * BM * LD + (wm * 32 * TM + r) * LD + h * 8;
;     const u16* cB = sB + buf * BN * LD + (wn * 32 * TN + r) * LD + h * 8;
;     bf16x8 af[TM], bfr[TN];
; #pragma unroll
;     for (int tm = 0; tm < TM; tm++) af[tm] = *(const bf16x8*)(cA + tm * 32 * LD);
; #pragma unroll
;     for (int tn = 0; tn < TN; tn++) bfr[tn] = *(const bf16x8*)(cB + tn * 32 * LD);
;     if (kt + 1 < nk) GEMM_SSTORE(buf ^ 1)
;     __builtin_amdgcn_sched_barrier(0);
;     __builtin_amdgcn_s_setprio(1);
; #pragma unroll
;     for (int tm = 0; tm < TM; tm++)
; #pragma unroll
;       for (int tn = 0; tn < TN; tn++) acc[tm][tn] = MFMA(af[tm], bfr[tn], acc[tm][tn]);
; #pragma unroll
;     for (int tm = 0; tm < TM; tm++) af[tm] = *(const bf16x8*)(cA + tm * 32 * LD + 16);
; #pragma unroll
;     for (int tn = 0; tn < TN; tn++) bfr[tn] = *(const bf16x8*)(cB + tn * 32 * LD + 16);
; #pragma unroll
;     for (int tm = 0; tm < TM; tm++)
; #pragma unroll
;       for (int tn = 0; tn < TN; tn++) acc[tm][tn] = MFMA(af[tm], bfr[tn], acc[tm][tn]);
;     __builtin_amdgcn_sched_group_barrier(0x8, 4, 0);
;     if (kt + 2 < nk) GEMM_GLOAD((kt + 2) * 64)
; #pragma unroll
;     for (int ks = 2; ks < 4; ks++) {
; #pragma unroll
;       for (int tm = 0; tm < TM; tm++) af[tm] = *(const bf16x8*)(cA + tm * 32 * LD + ks * 16);
; #pragma unroll
;       for (int tn = 0; tn < TN; tn++) bfr[tn] = *(const bf16x8*)(cB + tn * 32 * LD + ks * 16);
; #pragma unroll
;       for (int tm = 0; tm < TM; tm++)
; #pragma unroll
;         for (int tn = 0; tn < TN; tn++) acc[tm][tn] = MFMA(af[tm], bfr[tn], acc[tm][tn]);
;     }
;     __builtin_amdgcn_s_setprio(0);
;     __syncthreads();
;   }
	ds_read_b128 v[94:97], v68 offset:18432
	ds_read_b128 v[98:101], v68 offset:23040
	ds_read_b128 v[126:129], v1 offset:55296
	ds_read_b128 v[130:133], v1 offset:59904
	s_waitcnt vmcnt(1)
	ds_write_b128 v66, v[140:143]
	ds_write_b128 v66, v[102:105] offset:4608
	ds_write_b128 v66, v[106:109] offset:9216
	ds_write_b128 v66, v[110:113] offset:13824
	s_waitcnt vmcnt(0)
	ds_write_b128 v66, v[144:147] offset:36864
	ds_write_b128 v66, v[122:125] offset:41472
	ds_write_b128 v66, v[118:121] offset:46080
	ds_write_b128 v66, v[114:117] offset:50688
	s_setprio 1
	ds_read_b128 v[86:89], v68 offset:18464
	s_waitcnt lgkmcnt(10)
	v_mfma_f32_32x32x16_bf16 v[34:49], v[94:97], v[126:129], v[34:49]
	ds_read_b128 v[90:93], v1 offset:55328
	global_load_dwordx4 v[102:105], v[70:71], off offset:1664
	global_load_dwordx4 v[106:109], v[74:75], off offset:1664
	global_load_dwordx4 v[110:113], v[78:79], off offset:1664
	global_load_dwordx4 v[114:117], v[84:85], off offset:1664
	global_load_dwordx4 v[118:121], v[82:83], off offset:1664
	global_load_dwordx4 v[122:125], v[80:81], off offset:1664
	global_load_dwordx4 v[140:143], v[72:73], off offset:1664
	global_load_dwordx4 v[144:147], v[76:77], off offset:1664
	s_waitcnt lgkmcnt(10)
	v_mfma_f32_32x32x16_bf16 v[50:65], v[94:97], v[130:133], v[50:65]
	ds_read_b128 v[94:97], v1 offset:59936
	s_waitcnt lgkmcnt(1)
	v_mfma_f32_32x32x16_bf16 v[34:49], v[86:89], v[90:93], v[34:49]
	s_waitcnt lgkmcnt(0)
	v_mfma_f32_32x32x16_bf16 v[50:65], v[86:89], v[94:97], v[50:65]
	ds_read_b128 v[86:89], v68 offset:23072
	v_mfma_f32_32x32x16_bf16 v[2:17], v[98:101], v[126:129], v[2:17]
	v_mfma_f32_32x32x16_bf16 v[18:33], v[98:101], v[130:133], v[18:33]
	ds_read_b128 v[98:101], v68 offset:23136
	s_waitcnt lgkmcnt(1)
	v_mfma_f32_32x32x16_bf16 v[2:17], v[86:89], v[90:93], v[2:17]
	ds_read_b128 v[90:93], v1 offset:55360
	v_mfma_f32_32x32x16_bf16 v[18:33], v[86:89], v[94:97], v[18:33]
	ds_read_b128 v[86:89], v68 offset:18496
	ds_read_b128 v[94:97], v1 offset:59968
	s_waitcnt lgkmcnt(1)
	v_mfma_f32_32x32x16_bf16 v[34:49], v[86:89], v[90:93], v[34:49]
	s_waitcnt lgkmcnt(0)
	v_mfma_f32_32x32x16_bf16 v[50:65], v[86:89], v[94:97], v[50:65]
	ds_read_b128 v[86:89], v68 offset:23104
	s_waitcnt lgkmcnt(0)
	v_mfma_f32_32x32x16_bf16 v[2:17], v[86:89], v[90:93], v[2:17]
	ds_read_b128 v[90:93], v1 offset:55392
	v_mfma_f32_32x32x16_bf16 v[18:33], v[86:89], v[94:97], v[18:33]
	ds_read_b128 v[86:89], v68 offset:18528
	ds_read_b128 v[94:97], v1 offset:60000
	s_waitcnt lgkmcnt(1)
	v_mfma_f32_32x32x16_bf16 v[34:49], v[86:89], v[90:93], v[34:49]
	s_waitcnt lgkmcnt(0)
	v_mfma_f32_32x32x16_bf16 v[50:65], v[86:89], v[94:97], v[50:65]
	v_mfma_f32_32x32x16_bf16 v[2:17], v[98:101], v[90:93], v[2:17]
	v_mfma_f32_32x32x16_bf16 v[18:33], v[98:101], v[94:97], v[18:33]
	s_setprio 0
	s_barrier
	ds_read_b128 v[94:97], v68
	ds_read_b128 v[98:101], v68 offset:4608
	ds_read_b128 v[126:129], v1 offset:36864
	ds_read_b128 v[130:133], v1 offset:41472
	s_waitcnt vmcnt(1)
	ds_write_b128 v66, v[140:143] offset:18432
	ds_write_b128 v66, v[102:105] offset:23040
	ds_write_b128 v66, v[106:109] offset:27648
	ds_write_b128 v66, v[110:113] offset:32256
	s_waitcnt vmcnt(0)
	ds_write_b128 v66, v[144:147] offset:55296
	ds_write_b128 v66, v[122:125] offset:59904
	ds_write_b128 v66, v[118:121] offset:64512
	ds_write_b128 v69, v[114:117] offset:32256
	s_setprio 1
	ds_read_b128 v[86:89], v68 offset:32
	s_waitcnt lgkmcnt(10)
	v_mfma_f32_32x32x16_bf16 v[34:49], v[94:97], v[126:129], v[34:49]
	ds_read_b128 v[90:93], v1 offset:36896
	global_load_dwordx4 v[102:105], v[70:71], off offset:1792
	global_load_dwordx4 v[106:109], v[74:75], off offset:1792
	global_load_dwordx4 v[110:113], v[78:79], off offset:1792
	global_load_dwordx4 v[114:117], v[84:85], off offset:1792
	global_load_dwordx4 v[118:121], v[82:83], off offset:1792
	global_load_dwordx4 v[122:125], v[80:81], off offset:1792
	global_load_dwordx4 v[140:143], v[72:73], off offset:1792
	global_load_dwordx4 v[144:147], v[76:77], off offset:1792
	s_waitcnt lgkmcnt(10)
	v_mfma_f32_32x32x16_bf16 v[50:65], v[94:97], v[130:133], v[50:65]
	ds_read_b128 v[94:97], v1 offset:41504
	s_waitcnt lgkmcnt(1)
	v_mfma_f32_32x32x16_bf16 v[34:49], v[86:89], v[90:93], v[34:49]
	s_waitcnt lgkmcnt(0)
	v_mfma_f32_32x32x16_bf16 v[50:65], v[86:89], v[94:97], v[50:65]
	ds_read_b128 v[86:89], v68 offset:4640
	v_mfma_f32_32x32x16_bf16 v[2:17], v[98:101], v[126:129], v[2:17]
	v_mfma_f32_32x32x16_bf16 v[18:33], v[98:101], v[130:133], v[18:33]
	ds_read_b128 v[98:101], v68 offset:4704
	s_waitcnt lgkmcnt(1)
	v_mfma_f32_32x32x16_bf16 v[2:17], v[86:89], v[90:93], v[2:17]
	ds_read_b128 v[90:93], v1 offset:36928
	v_mfma_f32_32x32x16_bf16 v[18:33], v[86:89], v[94:97], v[18:33]
	ds_read_b128 v[86:89], v68 offset:64
	ds_read_b128 v[94:97], v1 offset:41536
	s_waitcnt lgkmcnt(1)
	v_mfma_f32_32x32x16_bf16 v[34:49], v[86:89], v[90:93], v[34:49]
	s_waitcnt lgkmcnt(0)
	v_mfma_f32_32x32x16_bf16 v[50:65], v[86:89], v[94:97], v[50:65]
	ds_read_b128 v[86:89], v68 offset:4672
	s_waitcnt lgkmcnt(0)
	v_mfma_f32_32x32x16_bf16 v[2:17], v[86:89], v[90:93], v[2:17]
	ds_read_b128 v[90:93], v1 offset:36960
	v_mfma_f32_32x32x16_bf16 v[18:33], v[86:89], v[94:97], v[18:33]
	ds_read_b128 v[86:89], v68 offset:96
	ds_read_b128 v[94:97], v1 offset:41568
	s_waitcnt lgkmcnt(1)
	v_mfma_f32_32x32x16_bf16 v[34:49], v[86:89], v[90:93], v[34:49]
	s_waitcnt lgkmcnt(0)
	v_mfma_f32_32x32x16_bf16 v[50:65], v[86:89], v[94:97], v[50:65]
	v_mfma_f32_32x32x16_bf16 v[2:17], v[98:101], v[90:93], v[2:17]
	v_mfma_f32_32x32x16_bf16 v[18:33], v[98:101], v[94:97], v[18:33]
	s_setprio 0
	s_barrier
; #define MFMA(a, b, c) __builtin_amdgcn_mfma_f32_32x32x16_bf16((a), (b), (c), 0, 0, 0)
; template <int TM, int TN>
; DI void gemm_mainloop(const u16* __restrict__ A, long lda, const u16* __restrict__ Bt, long ldb, int K, char* smem,
;                       f32x16 (&acc)[TM][TN]) {
;     ...
;   for (int kt = 0; kt < nk; kt++) {
;     const int buf = kt & 1;
;     const u16* cA = sA + buf * BM * LD + (wm * 32 * TM + r) * LD + h * 8;
;     const u16* cB = sB + buf * BN * LD + (wn * 32 * TN + r) * LD + h * 8;
;     bf16x8 af[TM], bfr[TN];
; #pragma unroll
;     for (int tm = 0; tm < TM; tm++) af[tm] = *(const bf16x8*)(cA + tm * 32 * LD);
; #pragma unroll
;     for (int tn = 0; tn < TN; tn++) bfr[tn] = *(const bf16x8*)(cB + tn * 32 * LD);
;     if (kt + 1 < nk) GEMM_SSTORE(buf ^ 1)
;     __builtin_amdgcn_sched_barrier(0);
;     __builtin_amdgcn_s_setprio(1);
; #pragma unroll
;     for (int tm = 0; tm < TM; tm++)
; #pragma unroll
;       for (int tn = 0; tn < TN; tn++) acc[tm][tn] = MFMA(af[tm], bfr[tn], acc[tm][tn]);
; #pragma unroll
;     for (int tm = 0; tm < TM; tm++) af[tm] = *(const bf16x8*)(cA + tm * 32 * LD + 16);
; #pragma unroll
;     for (int tn = 0; tn < TN; tn++) bfr[tn] = *(const bf16x8*)(cB + tn * 32 * LD + 16);
; #pragma unroll
;     for (int tm = 0; tm < TM; tm++)
; #pragma unroll
;       for (int tn = 0; tn < TN; tn++) acc[tm][tn] = MFMA(af[tm], bfr[tn], acc[tm][tn]);
;     __builtin_amdgcn_sched_group_barrier(0x8, 4, 0);
;     if (kt + 2 < nk) GEMM_GLOAD((kt + 2) * 64)
; #pragma unroll
;     for (int ks = 2; ks < 4; ks++) {
; #pragma unroll
;       for (int tm = 0; tm < TM; tm++) af[tm] = *(const bf16x8*)(cA + tm * 32 * LD + ks * 16);
; #pragma unroll
;       for (int tn = 0; tn < TN; tn++) bfr[tn] = *(const bf16x8*)(cB + tn * 32 * LD + ks * 16);
; #pragma unroll
;       for (int tm = 0; tm < TM; tm++)
; #pragma unroll
;         for (int tn = 0; tn < TN; tn++) acc[tm][tn] = MFMA(af[tm], bfr[tn], acc[tm][tn]);
;     }
;     __builtin_amdgcn_s_setprio(0);
;     __syncthreads();
;   }
	ds_read_b128 v[94:97], v68 offset:18432
	ds_read_b128 v[98:101], v68 offset:23040
	ds_read_b128 v[126:129], v1 offset:55296
	ds_read_b128 v[130:133], v1 offset:59904
	s_waitcnt vmcnt(1)
	ds_write_b128 v66, v[140:143]
	ds_write_b128 v66, v[102:105] offset:4608
	ds_write_b128 v66, v[106:109] offset:9216
	ds_write_b128 v66, v[110:113] offset:13824
	s_waitcnt vmcnt(0)
	ds_write_b128 v66, v[144:147] offset:36864
	ds_write_b128 v66, v[122:125] offset:41472
	ds_write_b128 v66, v[118:121] offset:46080
	ds_write_b128 v66, v[114:117] offset:50688
	s_setprio 1
	ds_read_b128 v[86:89], v68 offset:18464
	s_waitcnt lgkmcnt(10)
	v_mfma_f32_32x32x16_bf16 v[34:49], v[94:97], v[126:129], v[34:49]
	ds_read_b128 v[90:93], v1 offset:55328
	global_load_dwordx4 v[102:105], v[70:71], off offset:1920
	global_load_dwordx4 v[106:109], v[74:75], off offset:1920
	global_load_dwordx4 v[110:113], v[78:79], off offset:1920
	global_load_dwordx4 v[114:117], v[84:85], off offset:1920
	global_load_dwordx4 v[118:121], v[82:83], off offset:1920
	global_load_dwordx4 v[122:125], v[80:81], off offset:1920
	global_load_dwordx4 v[140:143], v[72:73], off offset:1920
	global_load_dwordx4 v[144:147], v[76:77], off offset:1920
	s_waitcnt lgkmcnt(10)
	v_mfma_f32_32x32x16_bf16 v[50:65], v[94:97], v[130:133], v[50:65]
	ds_read_b128 v[94:97], v1 offset:59936
	s_waitcnt lgkmcnt(1)
	v_mfma_f32_32x32x16_bf16 v[34:49], v[86:89], v[90:93], v[34:49]
	s_waitcnt lgkmcnt(0)
	v_mfma_f32_32x32x16_bf16 v[50:65], v[86:89], v[94:97], v[50:65]
	ds_read_b128 v[86:89], v68 offset:23072
	v_mfma_f32_32x32x16_bf16 v[2:17], v[98:101], v[126:129], v[2:17]
	v_mfma_f32_32x32x16_bf16 v[18:33], v[98:101], v[130:133], v[18:33]
	ds_read_b128 v[98:101], v68 offset:23136
	s_waitcnt lgkmcnt(1)
	v_mfma_f32_32x32x16_bf16 v[2:17], v[86:89], v[90:93], v[2:17]
	ds_read_b128 v[90:93], v1 offset:55360
	v_mfma_f32_32x32x16_bf16 v[18:33], v[86:89], v[94:97], v[18:33]
	ds_read_b128 v[86:89], v68 offset:18496
	ds_read_b128 v[94:97], v1 offset:59968
	s_waitcnt lgkmcnt(1)
	v_mfma_f32_32x32x16_bf16 v[34:49], v[86:89], v[90:93], v[34:49]
	s_waitcnt lgkmcnt(0)
	v_mfma_f32_32x32x16_bf16 v[50:65], v[86:89], v[94:97], v[50:65]
	ds_read_b128 v[86:89], v68 offset:23104
	s_waitcnt lgkmcnt(0)
	v_mfma_f32_32x32x16_bf16 v[2:17], v[86:89], v[90:93], v[2:17]
	ds_read_b128 v[90:93], v1 offset:55392
	v_mfma_f32_32x32x16_bf16 v[18:33], v[86:89], v[94:97], v[18:33]
	ds_read_b128 v[86:89], v68 offset:18528
	ds_read_b128 v[94:97], v1 offset:60000
	s_waitcnt lgkmcnt(1)
	v_mfma_f32_32x32x16_bf16 v[34:49], v[86:89], v[90:93], v[34:49]
	s_waitcnt lgkmcnt(0)
	v_mfma_f32_32x32x16_bf16 v[50:65], v[86:89], v[94:97], v[50:65]
	s_nop 0
	v_mfma_f32_32x32x16_bf16 v[2:17], v[98:101], v[90:93], v[2:17]
	v_mfma_f32_32x32x16_bf16 v[18:33], v[98:101], v[94:97], v[18:33]
	s_setprio 0
	s_barrier
	ds_read_b128 v[74:77], v68
	ds_read_b128 v[78:81], v68 offset:4608
	ds_read_b128 v[82:85], v1 offset:36864
	ds_read_b128 v[90:93], v1 offset:41472
	s_waitcnt vmcnt(1)
	ds_write_b128 v66, v[140:143] offset:18432
	ds_write_b128 v66, v[102:105] offset:23040
	ds_write_b128 v66, v[106:109] offset:27648
	ds_write_b128 v66, v[110:113] offset:32256
	s_waitcnt vmcnt(0)
	ds_write_b128 v66, v[144:147] offset:55296
	ds_write_b128 v66, v[122:125] offset:59904
	ds_write_b128 v66, v[118:121] offset:64512
	ds_write_b128 v69, v[114:117] offset:32256
	s_setprio 1
	ds_read_b128 v[70:73], v68 offset:32
	s_waitcnt lgkmcnt(10)
	v_mfma_f32_32x32x16_bf16 v[34:49], v[74:77], v[82:85], v[34:49]
	s_waitcnt lgkmcnt(9)
	v_mfma_f32_32x32x16_bf16 v[50:65], v[74:77], v[90:93], v[50:65]
	ds_read_b128 v[74:77], v1 offset:36896
	v_mfma_f32_32x32x16_bf16 v[2:17], v[78:81], v[82:85], v[2:17]
	v_mfma_f32_32x32x16_bf16 v[18:33], v[78:81], v[90:93], v[18:33]
	ds_read_b128 v[78:81], v1 offset:41504
	s_waitcnt lgkmcnt(1)
	v_mfma_f32_32x32x16_bf16 v[34:49], v[70:73], v[74:77], v[34:49]
	s_waitcnt lgkmcnt(0)
	v_mfma_f32_32x32x16_bf16 v[50:65], v[70:73], v[78:81], v[50:65]
	ds_read_b128 v[70:73], v68 offset:4640
	s_waitcnt lgkmcnt(0)
	v_mfma_f32_32x32x16_bf16 v[2:17], v[70:73], v[74:77], v[2:17]
	ds_read_b128 v[74:77], v1 offset:36928
	v_mfma_f32_32x32x16_bf16 v[18:33], v[70:73], v[78:81], v[18:33]
	ds_read_b128 v[70:73], v68 offset:64
	ds_read_b128 v[78:81], v1 offset:41536
	s_waitcnt lgkmcnt(1)
	v_mfma_f32_32x32x16_bf16 v[34:49], v[70:73], v[74:77], v[34:49]
	s_waitcnt lgkmcnt(0)
	v_mfma_f32_32x32x16_bf16 v[50:65], v[70:73], v[78:81], v[50:65]
	ds_read_b128 v[70:73], v68 offset:4672
	s_waitcnt lgkmcnt(0)
	v_mfma_f32_32x32x16_bf16 v[2:17], v[70:73], v[74:77], v[2:17]
	ds_read_b128 v[74:77], v1 offset:36960
	v_mfma_f32_32x32x16_bf16 v[18:33], v[70:73], v[78:81], v[18:33]
	ds_read_b128 v[70:73], v68 offset:96
	ds_read_b128 v[78:81], v1 offset:41568
	s_waitcnt lgkmcnt(1)
	v_mfma_f32_32x32x16_bf16 v[34:49], v[70:73], v[74:77], v[34:49]
	s_waitcnt lgkmcnt(0)
	v_mfma_f32_32x32x16_bf16 v[50:65], v[70:73], v[78:81], v[50:65]
	ds_read_b128 v[70:73], v68 offset:4704
	s_waitcnt lgkmcnt(0)
	v_mfma_f32_32x32x16_bf16 v[2:17], v[70:73], v[74:77], v[2:17]
	v_mfma_f32_32x32x16_bf16 v[18:33], v[70:73], v[78:81], v[18:33]
	s_setprio 0
	s_barrier
; template <int TM, int TN>
; DI void gemm_mainloop(const u16* __restrict__ A, long lda, const u16* __restrict__ Bt, long ldb, int K, char* smem,
;                       f32x16 (&acc)[TM][TN]) {
;     ...
;     for (int ks = 2; ks < 4; ks++) {
; #pragma unroll
;       for (int tm = 0; tm < TM; tm++) af[tm] = *(const bf16x8*)(cA + tm * 32 * LD + ks * 16);
; #pragma unroll
;       for (int tn = 0; tn < TN; tn++) bfr[tn] = *(const bf16x8*)(cB + tn * 32 * LD + ks * 16);
; #pragma unroll
;       for (int tm = 0; tm < TM; tm++)
; #pragma unroll
;         for (int tn = 0; tn < TN; tn++) acc[tm][tn] = MFMA(af[tm], bfr[tn], acc[tm][tn]);
;     }
;     __builtin_amdgcn_s_setprio(0);
;     __syncthreads();
;   }
; template <int TM, int TN, class Epi>
; DI void gemm_tile(const u16* A, long lda, const u16* Bt, long ldb, int K, int m0, int n0, char* smem, const Epi& epi) {
;     ...
; #pragma unroll
;   for (int tm = 0; tm < TM; tm++)
; #pragma unroll
;     for (int tn = 0; tn < TN; tn++)
; #pragma unroll
;       for (int i = 0; i < 16; i++)
;         Ct[(wm * 32 * TM + tm * 32 + crow(i, h)) * LDC + wn * 32 * TN + tn * 32 + r] = acc[tm][tn][i];
;   __syncthreads();
;   epi(Ct, LDC, m0, n0, tid, BM);
;   __syncthreads();
;   (void)BM;
; }
;   DI void operator()(const float* Ct, int ldc, int m0, int n0, int tid, int bm) const {
; #pragma unroll 4
;     for (int it = 0; it < bm / 16; it++) {
;       int id = tid + 256 * it; int row = id >> 4, c8 = (id & 15) * 8;
;       int n = n0 + c8;
;       if (n < nmax) {
;         const float* c = Ct + row * ldc + c8;
;         float4 a = *(const float4*)c, b = *(const float4*)(c + 4);
;         uint4 v; v.x = pk2(a.x, a.y); v.y = pk2(a.z, a.w); v.z = pk2(b.x, b.y); v.w = pk2(b.z, b.w);
;         *(uint4*)(out + (long)(m0 + row) * ldo + n) = v;
;         if (gates != nullptr && n == 1952) {
;           float* g = gates + (long)(m0 + row) * 8;
;           *(float4*)g = a; *(float4*)(g + 4) = b;
;         }
;       }
;     }
;   }
;   DI void operator()(const float* Ct, int ldc, int m0, int n0, int tid, int bm) const {
; #pragma unroll 4
;     for (int it = 0; it < bm / 16; it++) {
;       int id = tid + 256 * it; int row = id >> 4, c8 = (id & 15) * 8;
;       const float* c = Ct + row * ldc + c8;
;       float x[8];
; #pragma unroll
;       for (int j = 0; j < 8; j++) { float v = fmaxf(c[j], 0.f); x[j] = v * v; }
	ds_read_b128 v[70:73], v68 offset:18432
	ds_read_b128 v[74:77], v68 offset:23040
	ds_read_b128 v[78:81], v1 offset:55296
	ds_read_b128 v[82:85], v1 offset:59904
	s_setprio 1
	s_waitcnt lgkmcnt(1)
	v_mfma_f32_32x32x16_bf16 v[34:49], v[70:73], v[78:81], v[34:49]
	s_waitcnt lgkmcnt(0)
	v_mfma_f32_32x32x16_bf16 v[50:65], v[70:73], v[82:85], v[50:65]
	ds_read_b128 v[70:73], v68 offset:18464
	v_mfma_f32_32x32x16_bf16 v[2:17], v[74:77], v[78:81], v[2:17]
	ds_read_b128 v[78:81], v1 offset:59936
	v_mfma_f32_32x32x16_bf16 v[18:33], v[74:77], v[82:85], v[18:33]
	ds_read_b128 v[74:77], v1 offset:55328
	s_waitcnt lgkmcnt(0)
	v_mfma_f32_32x32x16_bf16 v[34:49], v[70:73], v[74:77], v[34:49]
	v_mfma_f32_32x32x16_bf16 v[50:65], v[70:73], v[78:81], v[50:65]
	ds_read_b128 v[70:73], v68 offset:23072
	s_waitcnt lgkmcnt(0)
	v_mfma_f32_32x32x16_bf16 v[2:17], v[70:73], v[74:77], v[2:17]
	ds_read_b128 v[74:77], v1 offset:55360
	v_mfma_f32_32x32x16_bf16 v[18:33], v[70:73], v[78:81], v[18:33]
	ds_read_b128 v[70:73], v68 offset:18496
	ds_read_b128 v[78:81], v1 offset:59968
	s_waitcnt lgkmcnt(1)
	v_mfma_f32_32x32x16_bf16 v[34:49], v[70:73], v[74:77], v[34:49]
	s_waitcnt lgkmcnt(0)
	v_mfma_f32_32x32x16_bf16 v[50:65], v[70:73], v[78:81], v[50:65]
	ds_read_b128 v[70:73], v68 offset:23104
	s_waitcnt lgkmcnt(0)
	v_mfma_f32_32x32x16_bf16 v[2:17], v[70:73], v[74:77], v[2:17]
	ds_read_b128 v[74:77], v1 offset:55392
	v_mfma_f32_32x32x16_bf16 v[18:33], v[70:73], v[78:81], v[18:33]
	ds_read_b128 v[70:73], v68 offset:18528
	ds_read_b128 v[78:81], v1 offset:60000
	s_waitcnt lgkmcnt(1)
	v_mfma_f32_32x32x16_bf16 v[34:49], v[70:73], v[74:77], v[34:49]
	s_waitcnt lgkmcnt(0)
	v_mfma_f32_32x32x16_bf16 v[50:65], v[70:73], v[78:81], v[50:65]
	ds_read_b128 v[68:71], v68 offset:23136
	s_waitcnt lgkmcnt(0)
	v_mfma_f32_32x32x16_bf16 v[2:17], v[68:71], v[74:77], v[2:17]
	v_mfma_f32_32x32x16_bf16 v[18:33], v[68:71], v[78:81], v[18:33]
	s_setprio 0
	v_mov_b32_e32 v1, v0
	s_barrier
	s_lshl_b64 s[6:7], s[6:7], 1
	v_lshrrev_b32_e32 v66, 1, v1
	v_and_b32_e32 v66, 0xfffffc0, v66
	v_lshrrev_b32_e32 v68, 3, v1
	v_and_or_b32 v66, v68, 4, v66
	v_and_b32_e32 v68, 0x5f, v1
	v_mul_lo_u32 v66, v66, s20
	v_lshl_add_u32 v66, v68, 2, v66
	ds_write2_b32 v66, v34, v50 offset1:32
	v_add_u32_e32 v34, 0x400, v66
	ds_write2_b32 v34, v36, v52 offset0:8 offset1:40
	ds_write2_b32 v34, v37, v53 offset0:140 offset1:172
	v_add_u32_e32 v34, 0x1000, v66
	ds_write2_b32 v34, v38, v54 offset0:32 offset1:64
	ds_write2_b32 v34, v39, v55 offset0:164 offset1:196
	v_add_u32_e32 v34, 0x1400, v66
	ds_write2_b32 v34, v40, v56 offset0:40 offset1:72
	ds_write2_b32 v34, v41, v57 offset0:172 offset1:204
	v_add_u32_e32 v34, 0x2000, v66
	ds_write2_b32 v34, v42, v58 offset0:64 offset1:96
	ds_write2_b32 v34, v43, v59 offset0:196 offset1:228
	v_add_u32_e32 v34, 0x2400, v66
	ds_write2_b32 v34, v44, v60 offset0:72 offset1:104
	ds_write2_b32 v34, v45, v61 offset0:204 offset1:236
	v_add_u32_e32 v34, 0x3000, v66
	ds_write2_b32 v34, v46, v62 offset0:96 offset1:128
	v_add_u32_e32 v34, 0x3200, v66
	ds_write2_b32 v34, v47, v63 offset0:100 offset1:132
	v_add_u32_e32 v34, 0x3400, v66
	ds_write2_b32 v34, v48, v64 offset0:104 offset1:136
	v_add_u32_e32 v34, 0x3600, v66
	ds_write2_b32 v34, v49, v65 offset0:108 offset1:140
	v_add_u32_e32 v34, 0x4000, v66
	ds_write2_b32 v34, v2, v18 offset0:128 offset1:160
	v_add_u32_e32 v2, 0x4400, v66
	ds_write2_b32 v2, v3, v19 offset0:4 offset1:36
	ds_write2_b32 v2, v4, v20 offset0:136 offset1:168
	v_add_u32_e32 v2, 0x4800, v66
	ds_write2_b32 v2, v5, v21 offset0:12 offset1:44
	v_add_u32_e32 v2, 0x5000, v66
	ds_write2_b32 v2, v6, v22 offset0:160 offset1:192
	v_add_u32_e32 v2, 0x5400, v66
	ds_write2_b32 v2, v7, v23 offset0:36 offset1:68
	ds_write2_b32 v2, v8, v24 offset0:168 offset1:200
	v_add_u32_e32 v2, 0x5800, v66
	ds_write2_b32 v2, v9, v25 offset0:44 offset1:76
	v_add_u32_e32 v2, 0x6000, v66
	ds_write2_b32 v2, v10, v26 offset0:192 offset1:224
	v_add_u32_e32 v2, 0x6400, v66
	ds_write2_b32 v2, v11, v27 offset0:68 offset1:100
	ds_write2_b32 v2, v12, v28 offset0:200 offset1:232
	v_add_u32_e32 v2, 0x6800, v66
	ds_write2_b32 v2, v13, v29 offset0:76 offset1:108
	v_add_u32_e32 v2, 0x7200, v66
	ds_write2_b32 v2, v14, v30 offset0:96 offset1:128
	v_add_u32_e32 v2, 0x7400, v66
	ds_write2_b32 v2, v15, v31 offset0:100 offset1:132
	v_add_u32_e32 v2, 0x7600, v66
	ds_write2_b32 v2, v16, v32 offset0:104 offset1:136
	v_add_u32_e32 v2, 0x7800, v66
	ds_write2_b32 v2, v17, v33 offset0:108 offset1:140
	v_lshlrev_b32_e32 v2, 3, v1
	v_and_b32_e32 v3, 0x78, v2
	s_add_u32 s6, s3, s6
	ds_write2_b32 v66, v35, v51 offset0:132 offset1:164
	s_addc_u32 s7, s10, s7
	v_lshlrev_b32_e32 v66, 1, v3
	v_lshlrev_b32_e32 v2, 2, v3
	v_lshl_add_u64 v[4:5], s[6:7], 0, v[66:67]
	s_mov_b32 s6, 0
	s_waitcnt lgkmcnt(0)
	s_barrier

; #define MFMA(a, b, c) __builtin_amdgcn_mfma_f32_32x32x16_bf16((a), (b), (c), 0, 0, 0)
; template <int TM, int TN>
; DI void gemm_mainloop(const u16* __restrict__ A, long lda, const u16* __restrict__ Bt, long ldb, int K, char* smem,
;                       f32x16 (&acc)[TM][TN]) {
;     ...
;   const int nk = K / 64;
;   const int lrow = tid >> 3, lch = (tid & 7) * 8;
;   const u16* gA = A + (long)lrow * lda + lch;
;   const u16* gB = Bt + (long)lrow * ldb + lch;
;   const int soff = lrow * LD + lch;
;     ...
;   GEMM_GLOAD(0)
;   __syncthreads();
;   GEMM_SSTORE(0)
;   if (nk > 1) GEMM_GLOAD(64)
;   __syncthreads();
;   for (int kt = 0; kt < nk; kt++) {
;     const int buf = kt & 1;
;     const u16* cA = sA + buf * BM * LD + (wm * 32 * TM + r) * LD + h * 8;
;     const u16* cB = sB + buf * BN * LD + (wn * 32 * TN + r) * LD + h * 8;
;     bf16x8 af[TM], bfr[TN];
; #pragma unroll
;     for (int tm = 0; tm < TM; tm++) af[tm] = *(const bf16x8*)(cA + tm * 32 * LD);
; #pragma unroll
;     for (int tn = 0; tn < TN; tn++) bfr[tn] = *(const bf16x8*)(cB + tn * 32 * LD);
;     if (kt + 1 < nk) GEMM_SSTORE(buf ^ 1)
;     __builtin_amdgcn_sched_barrier(0);
;     __builtin_amdgcn_s_setprio(1);
; #pragma unroll
;     for (int tm = 0; tm < TM; tm++)
; #pragma unroll
;       for (int tn = 0; tn < TN; tn++) acc[tm][tn] = MFMA(af[tm], bfr[tn], acc[tm][tn]);
; #pragma unroll
;     for (int tm = 0; tm < TM; tm++) af[tm] = *(const bf16x8*)(cA + tm * 32 * LD + 16);
; #pragma unroll
;     for (int tn = 0; tn < TN; tn++) bfr[tn] = *(const bf16x8*)(cB + tn * 32 * LD + 16);
; #pragma unroll
;     for (int tm = 0; tm < TM; tm++)
; #pragma unroll
;       for (int tn = 0; tn < TN; tn++) acc[tm][tn] = MFMA(af[tm], bfr[tn], acc[tm][tn]);
;     __builtin_amdgcn_sched_group_barrier(0x8, 4, 0);
;     if (kt + 2 < nk) GEMM_GLOAD((kt + 2) * 64)
; #pragma unroll
;     for (int ks = 2; ks < 4; ks++) {
; #pragma unroll
;       for (int tm = 0; tm < TM; tm++) af[tm] = *(const bf16x8*)(cA + tm * 32 * LD + ks * 16);
; #pragma unroll
;       for (int tn = 0; tn < TN; tn++) bfr[tn] = *(const bf16x8*)(cB + tn * 32 * LD + ks * 16);
; #pragma unroll
;       for (int tm = 0; tm < TM; tm++)
; #pragma unroll
;         for (int tn = 0; tn < TN; tn++) acc[tm][tn] = MFMA(af[tm], bfr[tn], acc[tm][tn]);
;     }
.LBB0_2745:
	s_lshl_b32 s6, s24, 8
	s_and_b32 s25, s6, 0xfffffe00
	s_lshl_b32 s6, s24, 11
	s_add_i32 s25, s25, s8
	s_and_b32 s6, s6, 0x800
	s_add_i32 s6, s6, s9
	s_mul_i32 s26, s25, 0x880
	s_mul_hi_i32 s7, s25, 0x880
	s_add_u32 s26, s4, s26
	v_mov_b32_e32 v1, v0
	s_addc_u32 s27, s5, s7
	s_ashr_i32 s7, s6, 31
	v_lshlrev_b32_e32 v2, 3, v1
	v_ashrrev_i32_e32 v68, 3, v1
	v_and_b32_e32 v69, 56, v2
	v_mov_b64_e32 v[2:3], s[26:27]
	v_mad_i64_i32 v[2:3], s[26:27], v68, s15, v[2:3]
	v_lshlrev_b32_e32 v66, 1, v69
	v_lshl_add_u64 v[72:73], v[2:3], 0, v[66:67]
	s_mul_i32 s28, s6, 0x880
	v_add_co_u32_e32 v70, vcc, s17, v72
	s_mul_hi_i32 s29, s6, 0x880
	s_add_u32 s28, s11, s28
	v_addc_co_u32_e32 v71, vcc, 0, v73, vcc
	s_addc_u32 s29, s14, s29
	v_add_co_u32_e32 v74, vcc, s18, v72
	v_mov_b64_e32 v[2:3], s[28:29]
	s_nop 0
	v_addc_co_u32_e32 v75, vcc, 0, v73, vcc
	v_mad_i64_i32 v[18:19], s[26:27], v68, s15, v[2:3]
	v_add_co_u32_e32 v78, vcc, s19, v72
	v_lshl_add_u64 v[76:77], v[18:19], 0, v[66:67]
	s_nop 0
	v_addc_co_u32_e32 v79, vcc, 0, v73, vcc
	v_add_co_u32_e32 v80, vcc, s17, v76
	global_load_dwordx4 v[2:5], v[72:73], off
	s_nop 0
	v_addc_co_u32_e32 v81, vcc, 0, v77, vcc
	v_add_co_u32_e32 v82, vcc, s18, v76
	global_load_dwordx4 v[6:9], v[70:71], off
	s_nop 0
	v_addc_co_u32_e32 v83, vcc, 0, v77, vcc
	v_add_co_u32_e32 v84, vcc, s19, v76
	global_load_dwordx4 v[10:13], v[74:75], off
	s_nop 0
	v_addc_co_u32_e32 v85, vcc, 0, v77, vcc
	global_load_dwordx4 v[14:17], v[78:79], off
	global_load_dwordx4 v[18:21], v[76:77], off
	global_load_dwordx4 v[22:25], v[80:81], off
	global_load_dwordx4 v[26:29], v[82:83], off
	global_load_dwordx4 v[30:33], v[84:85], off
	s_barrier
	global_load_dwordx4 v[34:37], v[72:73], off offset:128
	global_load_dwordx4 v[38:41], v[70:71], off offset:128
	global_load_dwordx4 v[42:45], v[74:75], off offset:128
	global_load_dwordx4 v[46:49], v[78:79], off offset:128
	global_load_dwordx4 v[50:53], v[76:77], off offset:128
	global_load_dwordx4 v[54:57], v[80:81], off offset:128
	global_load_dwordx4 v[58:61], v[82:83], off offset:128
	global_load_dwordx4 v[62:65], v[84:85], off offset:128
	v_and_b32_e32 v66, 31, v1
	v_lshrrev_b32_e32 v86, 1, v1
	v_mul_lo_u32 v68, v68, s16
	v_and_or_b32 v87, v86, s20, v66
	v_and_b32_e32 v86, 16, v86
	v_and_b32_e32 v1, 0x5f, v1
	v_add_lshl_u32 v66, v68, v69, 1
	v_mad_u64_u32 v[68:69], s[26:27], v87, s21, v[86:87]
	v_mad_u32_u24 v1, v1, s21, v86
	v_add_u32_e32 v69, 0x9000, v66
	s_waitcnt vmcnt(15)
	ds_write_b128 v66, v[2:5]
	s_waitcnt vmcnt(14)
	ds_write_b128 v66, v[6:9] offset:4608
	s_waitcnt vmcnt(13)
	ds_write_b128 v66, v[10:13] offset:9216
	s_waitcnt vmcnt(12)
	ds_write_b128 v66, v[14:17] offset:13824
	s_waitcnt vmcnt(11)
	ds_write_b128 v66, v[18:21] offset:36864
	s_waitcnt vmcnt(10)
	ds_write_b128 v66, v[22:25] offset:41472
	s_waitcnt vmcnt(9)
	ds_write_b128 v66, v[26:29] offset:46080
	s_waitcnt vmcnt(8)
	ds_write_b128 v66, v[30:33] offset:50688
	s_waitcnt lgkmcnt(0)
	s_barrier
	ds_read_b128 v[2:5], v68
	ds_read_b128 v[18:21], v68 offset:4608
	ds_read_b128 v[6:9], v1 offset:36864
	ds_read_b128 v[22:25], v1 offset:41472
	s_waitcnt vmcnt(7)
	ds_write_b128 v66, v[34:37] offset:18432
	s_waitcnt vmcnt(6)
	ds_write_b128 v66, v[38:41] offset:23040
	s_waitcnt vmcnt(5)
	ds_write_b128 v66, v[42:45] offset:27648
	s_waitcnt vmcnt(4)
	ds_write_b128 v66, v[46:49] offset:32256
	s_waitcnt vmcnt(3)
	ds_write_b128 v66, v[50:53] offset:55296
	s_waitcnt vmcnt(2)
	ds_write_b128 v66, v[54:57] offset:59904
	s_waitcnt vmcnt(1)
	ds_write_b128 v66, v[58:61] offset:64512
	s_waitcnt vmcnt(0)
	ds_write_b128 v69, v[62:65] offset:32256
	s_setprio 1
	ds_read_b128 v[86:89], v68 offset:32
	s_waitcnt lgkmcnt(10)
	v_mfma_f32_32x32x16_bf16 v[34:49], v[2:5], v[6:9], 0
	ds_read_b128 v[90:93], v1 offset:36896
	ds_read_b128 v[94:97], v1 offset:41504
	ds_read_b128 v[98:101], v68 offset:4704
	global_load_dwordx4 v[102:105], v[70:71], off offset:256
	global_load_dwordx4 v[106:109], v[74:75], off offset:256
	global_load_dwordx4 v[110:113], v[78:79], off offset:256
	global_load_dwordx4 v[114:117], v[84:85], off offset:256
	s_waitcnt lgkmcnt(12)
	v_mfma_f32_32x32x16_bf16 v[50:65], v[2:5], v[22:25], 0
	global_load_dwordx4 v[118:121], v[82:83], off offset:256
	global_load_dwordx4 v[122:125], v[80:81], off offset:256
	global_load_dwordx4 v[140:143], v[72:73], off offset:256
	global_load_dwordx4 v[144:147], v[76:77], off offset:256
	s_waitcnt lgkmcnt(2)
	v_mfma_f32_32x32x16_bf16 v[34:49], v[86:89], v[90:93], v[34:49]
	s_waitcnt lgkmcnt(1)
	v_mfma_f32_32x32x16_bf16 v[50:65], v[86:89], v[94:97], v[50:65]
	ds_read_b128 v[86:89], v68 offset:4640
	v_mfma_f32_32x32x16_bf16 v[2:17], v[18:21], v[6:9], 0
	v_mfma_f32_32x32x16_bf16 v[18:33], v[18:21], v[22:25], 0
	s_waitcnt lgkmcnt(0)
	v_mfma_f32_32x32x16_bf16 v[2:17], v[86:89], v[90:93], v[2:17]
	ds_read_b128 v[90:93], v1 offset:36928
	v_mfma_f32_32x32x16_bf16 v[18:33], v[86:89], v[94:97], v[18:33]
	ds_read_b128 v[86:89], v68 offset:64
	ds_read_b128 v[94:97], v1 offset:41536
	s_waitcnt lgkmcnt(1)
	v_mfma_f32_32x32x16_bf16 v[34:49], v[86:89], v[90:93], v[34:49]
	s_waitcnt lgkmcnt(0)
	v_mfma_f32_32x32x16_bf16 v[50:65], v[86:89], v[94:97], v[50:65]
	ds_read_b128 v[86:89], v68 offset:4672
	s_waitcnt lgkmcnt(0)
	v_mfma_f32_32x32x16_bf16 v[2:17], v[86:89], v[90:93], v[2:17]
	ds_read_b128 v[90:93], v1 offset:36960
	v_mfma_f32_32x32x16_bf16 v[18:33], v[86:89], v[94:97], v[18:33]
	ds_read_b128 v[86:89], v68 offset:96
	ds_read_b128 v[94:97], v1 offset:41568
	s_waitcnt lgkmcnt(1)
	v_mfma_f32_32x32x16_bf16 v[34:49], v[86:89], v[90:93], v[34:49]
	s_waitcnt lgkmcnt(0)
	v_mfma_f32_32x32x16_bf16 v[50:65], v[86:89], v[94:97], v[50:65]
	v_mfma_f32_32x32x16_bf16 v[2:17], v[98:101], v[90:93], v[2:17]
	v_mfma_f32_32x32x16_bf16 v[18:33], v[98:101], v[94:97], v[18:33]
	s_setprio 0
	s_barrier
; #define MFMA(a, b, c) __builtin_amdgcn_mfma_f32_32x32x16_bf16((a), (b), (c), 0, 0, 0)
; template <int TM, int TN>
; DI void gemm_mainloop(const u16* __restrict__ A, long lda, const u16* __restrict__ Bt, long ldb, int K, char* smem,
;                       f32x16 (&acc)[TM][TN]) {
;     ...
;   for (int kt = 0; kt < nk; kt++) {
;     const int buf = kt & 1;
;     const u16* cA = sA + buf * BM * LD + (wm * 32 * TM + r) * LD + h * 8;
;     const u16* cB = sB + buf * BN * LD + (wn * 32 * TN + r) * LD + h * 8;
;     bf16x8 af[TM], bfr[TN];
; #pragma unroll
;     for (int tm = 0; tm < TM; tm++) af[tm] = *(const bf16x8*)(cA + tm * 32 * LD);
; #pragma unroll
;     for (int tn = 0; tn < TN; tn++) bfr[tn] = *(const bf16x8*)(cB + tn * 32 * LD);
;     if (kt + 1 < nk) GEMM_SSTORE(buf ^ 1)
;     __builtin_amdgcn_sched_barrier(0);
;     __builtin_amdgcn_s_setprio(1);
; #pragma unroll
;     for (int tm = 0; tm < TM; tm++)
; #pragma unroll
;       for (int tn = 0; tn < TN; tn++) acc[tm][tn] = MFMA(af[tm], bfr[tn], acc[tm][tn]);
; #pragma unroll
;     for (int tm = 0; tm < TM; tm++) af[tm] = *(const bf16x8*)(cA + tm * 32 * LD + 16);
; #pragma unroll
;     for (int tn = 0; tn < TN; tn++) bfr[tn] = *(const bf16x8*)(cB + tn * 32 * LD + 16);
; #pragma unroll
;     for (int tm = 0; tm < TM; tm++)
; #pragma unroll
;       for (int tn = 0; tn < TN; tn++) acc[tm][tn] = MFMA(af[tm], bfr[tn], acc[tm][tn]);
;     __builtin_amdgcn_sched_group_barrier(0x8, 4, 0);
;     if (kt + 2 < nk) GEMM_GLOAD((kt + 2) * 64)
; #pragma unroll
;     for (int ks = 2; ks < 4; ks++) {
; #pragma unroll
;       for (int tm = 0; tm < TM; tm++) af[tm] = *(const bf16x8*)(cA + tm * 32 * LD + ks * 16);
; #pragma unroll
;       for (int tn = 0; tn < TN; tn++) bfr[tn] = *(const bf16x8*)(cB + tn * 32 * LD + ks * 16);
; #pragma unroll
;       for (int tm = 0; tm < TM; tm++)
; #pragma unroll
;         for (int tn = 0; tn < TN; tn++) acc[tm][tn] = MFMA(af[tm], bfr[tn], acc[tm][tn]);
;     }
	ds_read_b128 v[94:97], v68 offset:18432
	ds_read_b128 v[98:101], v68 offset:23040
	ds_read_b128 v[126:129], v1 offset:55296
	ds_read_b128 v[130:133], v1 offset:59904
	s_setprio 1
	ds_read_b128 v[86:89], v68 offset:18464
	s_waitcnt lgkmcnt(2)
	v_mfma_f32_32x32x16_bf16 v[34:49], v[94:97], v[126:129], v[34:49]
	ds_read_b128 v[90:93], v1 offset:55328
	s_waitcnt lgkmcnt(2)
	v_mfma_f32_32x32x16_bf16 v[50:65], v[94:97], v[130:133], v[50:65]
	s_waitcnt vmcnt(1)
	ds_write_b128 v66, v[140:143]
	ds_write_b128 v66, v[102:105] offset:4608
	global_load_dwordx4 v[140:143], v[72:73], off offset:384
	global_load_dwordx4 v[102:105], v[70:71], off offset:384
	ds_read_b128 v[94:97], v1 offset:59936
	s_waitcnt lgkmcnt(3)
	v_mfma_f32_32x32x16_bf16 v[34:49], v[86:89], v[90:93], v[34:49]
	s_waitcnt lgkmcnt(0)
	v_mfma_f32_32x32x16_bf16 v[50:65], v[86:89], v[94:97], v[50:65]
	ds_read_b128 v[86:89], v68 offset:23072
	v_mfma_f32_32x32x16_bf16 v[2:17], v[98:101], v[126:129], v[2:17]
	v_mfma_f32_32x32x16_bf16 v[18:33], v[98:101], v[130:133], v[18:33]
	ds_write_b128 v66, v[106:109] offset:9216
	ds_write_b128 v66, v[110:113] offset:13824
	global_load_dwordx4 v[106:109], v[74:75], off offset:384
	global_load_dwordx4 v[110:113], v[78:79], off offset:384
	ds_read_b128 v[98:101], v68 offset:23136
	s_waitcnt lgkmcnt(3)
	v_mfma_f32_32x32x16_bf16 v[2:17], v[86:89], v[90:93], v[2:17]
	ds_read_b128 v[90:93], v1 offset:55360
	v_mfma_f32_32x32x16_bf16 v[18:33], v[86:89], v[94:97], v[18:33]
	ds_read_b128 v[86:89], v68 offset:18496
	ds_read_b128 v[94:97], v1 offset:59968
	s_waitcnt lgkmcnt(1)
	v_mfma_f32_32x32x16_bf16 v[34:49], v[86:89], v[90:93], v[34:49]
	s_waitcnt lgkmcnt(0)
	v_mfma_f32_32x32x16_bf16 v[50:65], v[86:89], v[94:97], v[50:65]
	s_waitcnt vmcnt(4)
	ds_write_b128 v66, v[144:147] offset:36864
	ds_write_b128 v66, v[122:125] offset:41472
	global_load_dwordx4 v[144:147], v[76:77], off offset:384
	global_load_dwordx4 v[122:125], v[80:81], off offset:384
	ds_read_b128 v[86:89], v68 offset:23104
	s_waitcnt lgkmcnt(0)
	v_mfma_f32_32x32x16_bf16 v[2:17], v[86:89], v[90:93], v[2:17]
	ds_read_b128 v[90:93], v1 offset:55392
	v_mfma_f32_32x32x16_bf16 v[18:33], v[86:89], v[94:97], v[18:33]
	ds_read_b128 v[86:89], v68 offset:18528
	ds_read_b128 v[94:97], v1 offset:60000
	s_waitcnt lgkmcnt(1)
	v_mfma_f32_32x32x16_bf16 v[34:49], v[86:89], v[90:93], v[34:49]
	s_waitcnt lgkmcnt(0)
	v_mfma_f32_32x32x16_bf16 v[50:65], v[86:89], v[94:97], v[50:65]
	ds_write_b128 v66, v[118:121] offset:46080
	ds_write_b128 v66, v[114:117] offset:50688
	global_load_dwordx4 v[118:121], v[82:83], off offset:384
	global_load_dwordx4 v[114:117], v[84:85], off offset:384
	v_mfma_f32_32x32x16_bf16 v[2:17], v[98:101], v[90:93], v[2:17]
	v_mfma_f32_32x32x16_bf16 v[18:33], v[98:101], v[94:97], v[18:33]
	s_setprio 0
	s_waitcnt lgkmcnt(0)
	s_barrier
	ds_read_b128 v[94:97], v68
	ds_read_b128 v[98:101], v68 offset:4608
	ds_read_b128 v[126:129], v1 offset:36864
	ds_read_b128 v[130:133], v1 offset:41472
	s_setprio 1
	ds_read_b128 v[86:89], v68 offset:32
	s_waitcnt lgkmcnt(2)
	v_mfma_f32_32x32x16_bf16 v[34:49], v[94:97], v[126:129], v[34:49]
	ds_read_b128 v[90:93], v1 offset:36896
	s_waitcnt lgkmcnt(2)
	v_mfma_f32_32x32x16_bf16 v[50:65], v[94:97], v[130:133], v[50:65]
	s_waitcnt vmcnt(7)
	ds_write_b128 v66, v[140:143] offset:18432
	s_waitcnt vmcnt(6)
	ds_write_b128 v66, v[102:105] offset:23040
	global_load_dwordx4 v[140:143], v[72:73], off offset:512
	global_load_dwordx4 v[102:105], v[70:71], off offset:512
	ds_read_b128 v[94:97], v1 offset:41504
	s_waitcnt lgkmcnt(3)
	v_mfma_f32_32x32x16_bf16 v[34:49], v[86:89], v[90:93], v[34:49]
	s_waitcnt lgkmcnt(0)
	v_mfma_f32_32x32x16_bf16 v[50:65], v[86:89], v[94:97], v[50:65]
	ds_read_b128 v[86:89], v68 offset:4640
	v_mfma_f32_32x32x16_bf16 v[2:17], v[98:101], v[126:129], v[2:17]
	v_mfma_f32_32x32x16_bf16 v[18:33], v[98:101], v[130:133], v[18:33]
	s_waitcnt vmcnt(7)
	ds_write_b128 v66, v[106:109] offset:27648
	s_waitcnt vmcnt(6)
	ds_write_b128 v66, v[110:113] offset:32256
	global_load_dwordx4 v[106:109], v[74:75], off offset:512
	global_load_dwordx4 v[110:113], v[78:79], off offset:512
	ds_read_b128 v[98:101], v68 offset:4704
	s_waitcnt lgkmcnt(3)
	v_mfma_f32_32x32x16_bf16 v[2:17], v[86:89], v[90:93], v[2:17]
	ds_read_b128 v[90:93], v1 offset:36928
	v_mfma_f32_32x32x16_bf16 v[18:33], v[86:89], v[94:97], v[18:33]
	ds_read_b128 v[86:89], v68 offset:64
	ds_read_b128 v[94:97], v1 offset:41536
	s_waitcnt lgkmcnt(1)
	v_mfma_f32_32x32x16_bf16 v[34:49], v[86:89], v[90:93], v[34:49]
	s_waitcnt lgkmcnt(0)
	v_mfma_f32_32x32x16_bf16 v[50:65], v[86:89], v[94:97], v[50:65]
	s_waitcnt vmcnt(7)
	ds_write_b128 v66, v[144:147] offset:55296
	s_waitcnt vmcnt(6)
	ds_write_b128 v66, v[122:125] offset:59904
	global_load_dwordx4 v[144:147], v[76:77], off offset:512
	global_load_dwordx4 v[122:125], v[80:81], off offset:512
	ds_read_b128 v[86:89], v68 offset:4672
	s_waitcnt lgkmcnt(0)
	v_mfma_f32_32x32x16_bf16 v[2:17], v[86:89], v[90:93], v[2:17]
	ds_read_b128 v[90:93], v1 offset:36960
	v_mfma_f32_32x32x16_bf16 v[18:33], v[86:89], v[94:97], v[18:33]
	ds_read_b128 v[86:89], v68 offset:96
	ds_read_b128 v[94:97], v1 offset:41568
	s_waitcnt lgkmcnt(1)
	v_mfma_f32_32x32x16_bf16 v[34:49], v[86:89], v[90:93], v[34:49]
	s_waitcnt lgkmcnt(0)
	v_mfma_f32_32x32x16_bf16 v[50:65], v[86:89], v[94:97], v[50:65]
	s_waitcnt vmcnt(7)
	ds_write_b128 v66, v[118:121] offset:64512
	s_waitcnt vmcnt(6)
	ds_write_b128 v69, v[114:117] offset:32256
	global_load_dwordx4 v[118:121], v[82:83], off offset:512
	global_load_dwordx4 v[114:117], v[84:85], off offset:512
	v_mfma_f32_32x32x16_bf16 v[2:17], v[98:101], v[90:93], v[2:17]
	v_mfma_f32_32x32x16_bf16 v[18:33], v[98:101], v[94:97], v[18:33]
	s_setprio 0
	s_waitcnt lgkmcnt(0)
	s_barrier
; #define MFMA(a, b, c) __builtin_amdgcn_mfma_f32_32x32x16_bf16((a), (b), (c), 0, 0, 0)
; template <int TM, int TN>
; DI void gemm_mainloop(const u16* __restrict__ A, long lda, const u16* __restrict__ Bt, long ldb, int K, char* smem,
;                       f32x16 (&acc)[TM][TN]) {
;     ...
;   for (int kt = 0; kt < nk; kt++) {
;     const int buf = kt & 1;
;     const u16* cA = sA + buf * BM * LD + (wm * 32 * TM + r) * LD + h * 8;
;     const u16* cB = sB + buf * BN * LD + (wn * 32 * TN + r) * LD + h * 8;
;     bf16x8 af[TM], bfr[TN];
; #pragma unroll
;     for (int tm = 0; tm < TM; tm++) af[tm] = *(const bf16x8*)(cA + tm * 32 * LD);
; #pragma unroll
;     for (int tn = 0; tn < TN; tn++) bfr[tn] = *(const bf16x8*)(cB + tn * 32 * LD);
;     if (kt + 1 < nk) GEMM_SSTORE(buf ^ 1)
;     __builtin_amdgcn_sched_barrier(0);
;     __builtin_amdgcn_s_setprio(1);
; #pragma unroll
;     for (int tm = 0; tm < TM; tm++)
; #pragma unroll
;       for (int tn = 0; tn < TN; tn++) acc[tm][tn] = MFMA(af[tm], bfr[tn], acc[tm][tn]);
; #pragma unroll
;     for (int tm = 0; tm < TM; tm++) af[tm] = *(const bf16x8*)(cA + tm * 32 * LD + 16);
; #pragma unroll
;     for (int tn = 0; tn < TN; tn++) bfr[tn] = *(const bf16x8*)(cB + tn * 32 * LD + 16);
; #pragma unroll
;     for (int tm = 0; tm < TM; tm++)
; #pragma unroll
;       for (int tn = 0; tn < TN; tn++) acc[tm][tn] = MFMA(af[tm], bfr[tn], acc[tm][tn]);
;     __builtin_amdgcn_sched_group_barrier(0x8, 4, 0);
;     if (kt + 2 < nk) GEMM_GLOAD((kt + 2) * 64)
; #pragma unroll
;     for (int ks = 2; ks < 4; ks++) {
; #pragma unroll
;       for (int tm = 0; tm < TM; tm++) af[tm] = *(const bf16x8*)(cA + tm * 32 * LD + ks * 16);
; #pragma unroll
;       for (int tn = 0; tn < TN; tn++) bfr[tn] = *(const bf16x8*)(cB + tn * 32 * LD + ks * 16);
; #pragma unroll
;       for (int tm = 0; tm < TM; tm++)
; #pragma unroll
;         for (int tn = 0; tn < TN; tn++) acc[tm][tn] = MFMA(af[tm], bfr[tn], acc[tm][tn]);
;     }
	ds_read_b128 v[94:97], v68 offset:18432
	ds_read_b128 v[98:101], v68 offset:23040
	ds_read_b128 v[126:129], v1 offset:55296
	ds_read_b128 v[130:133], v1 offset:59904
	s_setprio 1
	ds_read_b128 v[86:89], v68 offset:18464
	s_waitcnt lgkmcnt(2)
	v_mfma_f32_32x32x16_bf16 v[34:49], v[94:97], v[126:129], v[34:49]
	ds_read_b128 v[90:93], v1 offset:55328
	s_waitcnt lgkmcnt(2)
	v_mfma_f32_32x32x16_bf16 v[50:65], v[94:97], v[130:133], v[50:65]
	s_waitcnt vmcnt(7)
	ds_write_b128 v66, v[140:143]
	s_waitcnt vmcnt(6)
	ds_write_b128 v66, v[102:105] offset:4608
	global_load_dwordx4 v[140:143], v[72:73], off offset:640
	global_load_dwordx4 v[102:105], v[70:71], off offset:640
	ds_read_b128 v[94:97], v1 offset:59936
	s_waitcnt lgkmcnt(3)
	v_mfma_f32_32x32x16_bf16 v[34:49], v[86:89], v[90:93], v[34:49]
	s_waitcnt lgkmcnt(0)
	v_mfma_f32_32x32x16_bf16 v[50:65], v[86:89], v[94:97], v[50:65]
	ds_read_b128 v[86:89], v68 offset:23072
	v_mfma_f32_32x32x16_bf16 v[2:17], v[98:101], v[126:129], v[2:17]
	v_mfma_f32_32x32x16_bf16 v[18:33], v[98:101], v[130:133], v[18:33]
	s_waitcnt vmcnt(7)
	ds_write_b128 v66, v[106:109] offset:9216
	s_waitcnt vmcnt(6)
	ds_write_b128 v66, v[110:113] offset:13824
	global_load_dwordx4 v[106:109], v[74:75], off offset:640
	global_load_dwordx4 v[110:113], v[78:79], off offset:640
	ds_read_b128 v[98:101], v68 offset:23136
	s_waitcnt lgkmcnt(3)
	v_mfma_f32_32x32x16_bf16 v[2:17], v[86:89], v[90:93], v[2:17]
	ds_read_b128 v[90:93], v1 offset:55360
	v_mfma_f32_32x32x16_bf16 v[18:33], v[86:89], v[94:97], v[18:33]
	ds_read_b128 v[86:89], v68 offset:18496
	ds_read_b128 v[94:97], v1 offset:59968
	s_waitcnt lgkmcnt(1)
	v_mfma_f32_32x32x16_bf16 v[34:49], v[86:89], v[90:93], v[34:49]
	s_waitcnt lgkmcnt(0)
	v_mfma_f32_32x32x16_bf16 v[50:65], v[86:89], v[94:97], v[50:65]
	s_waitcnt vmcnt(7)
	ds_write_b128 v66, v[144:147] offset:36864
	s_waitcnt vmcnt(6)
	ds_write_b128 v66, v[122:125] offset:41472
	global_load_dwordx4 v[144:147], v[76:77], off offset:640
	global_load_dwordx4 v[122:125], v[80:81], off offset:640
	ds_read_b128 v[86:89], v68 offset:23104
	s_waitcnt lgkmcnt(0)
	v_mfma_f32_32x32x16_bf16 v[2:17], v[86:89], v[90:93], v[2:17]
	ds_read_b128 v[90:93], v1 offset:55392
	v_mfma_f32_32x32x16_bf16 v[18:33], v[86:89], v[94:97], v[18:33]
	ds_read_b128 v[86:89], v68 offset:18528
	ds_read_b128 v[94:97], v1 offset:60000
	s_waitcnt lgkmcnt(1)
	v_mfma_f32_32x32x16_bf16 v[34:49], v[86:89], v[90:93], v[34:49]
	s_waitcnt lgkmcnt(0)
	v_mfma_f32_32x32x16_bf16 v[50:65], v[86:89], v[94:97], v[50:65]
	s_waitcnt vmcnt(7)
	ds_write_b128 v66, v[118:121] offset:46080
	s_waitcnt vmcnt(6)
	ds_write_b128 v66, v[114:117] offset:50688
	global_load_dwordx4 v[118:121], v[82:83], off offset:640
	global_load_dwordx4 v[114:117], v[84:85], off offset:640
	v_mfma_f32_32x32x16_bf16 v[2:17], v[98:101], v[90:93], v[2:17]
	v_mfma_f32_32x32x16_bf16 v[18:33], v[98:101], v[94:97], v[18:33]
	s_setprio 0
	s_waitcnt lgkmcnt(0)
	s_barrier
	ds_read_b128 v[94:97], v68
	ds_read_b128 v[98:101], v68 offset:4608
	ds_read_b128 v[126:129], v1 offset:36864
	ds_read_b128 v[130:133], v1 offset:41472
	s_setprio 1
	ds_read_b128 v[86:89], v68 offset:32
	s_waitcnt lgkmcnt(2)
	v_mfma_f32_32x32x16_bf16 v[34:49], v[94:97], v[126:129], v[34:49]
	ds_read_b128 v[90:93], v1 offset:36896
	s_waitcnt lgkmcnt(2)
	v_mfma_f32_32x32x16_bf16 v[50:65], v[94:97], v[130:133], v[50:65]
	s_waitcnt vmcnt(7)
	ds_write_b128 v66, v[140:143] offset:18432
	s_waitcnt vmcnt(6)
	ds_write_b128 v66, v[102:105] offset:23040
	global_load_dwordx4 v[140:143], v[72:73], off offset:768
	global_load_dwordx4 v[102:105], v[70:71], off offset:768
	ds_read_b128 v[94:97], v1 offset:41504
	s_waitcnt lgkmcnt(3)
	v_mfma_f32_32x32x16_bf16 v[34:49], v[86:89], v[90:93], v[34:49]
	s_waitcnt lgkmcnt(0)
	v_mfma_f32_32x32x16_bf16 v[50:65], v[86:89], v[94:97], v[50:65]
	ds_read_b128 v[86:89], v68 offset:4640
	v_mfma_f32_32x32x16_bf16 v[2:17], v[98:101], v[126:129], v[2:17]
	v_mfma_f32_32x32x16_bf16 v[18:33], v[98:101], v[130:133], v[18:33]
	s_waitcnt vmcnt(7)
	ds_write_b128 v66, v[106:109] offset:27648
	s_waitcnt vmcnt(6)
	ds_write_b128 v66, v[110:113] offset:32256
	global_load_dwordx4 v[106:109], v[74:75], off offset:768
	global_load_dwordx4 v[110:113], v[78:79], off offset:768
	ds_read_b128 v[98:101], v68 offset:4704
	s_waitcnt lgkmcnt(3)
	v_mfma_f32_32x32x16_bf16 v[2:17], v[86:89], v[90:93], v[2:17]
	ds_read_b128 v[90:93], v1 offset:36928
	v_mfma_f32_32x32x16_bf16 v[18:33], v[86:89], v[94:97], v[18:33]
	ds_read_b128 v[86:89], v68 offset:64
	ds_read_b128 v[94:97], v1 offset:41536
	s_waitcnt lgkmcnt(1)
	v_mfma_f32_32x32x16_bf16 v[34:49], v[86:89], v[90:93], v[34:49]
	s_waitcnt lgkmcnt(0)
	v_mfma_f32_32x32x16_bf16 v[50:65], v[86:89], v[94:97], v[50:65]
	s_waitcnt vmcnt(7)
	ds_write_b128 v66, v[144:147] offset:55296
	s_waitcnt vmcnt(6)
	ds_write_b128 v66, v[122:125] offset:59904
	global_load_dwordx4 v[144:147], v[76:77], off offset:768
	global_load_dwordx4 v[122:125], v[80:81], off offset:768
	ds_read_b128 v[86:89], v68 offset:4672
	s_waitcnt lgkmcnt(0)
	v_mfma_f32_32x32x16_bf16 v[2:17], v[86:89], v[90:93], v[2:17]
	ds_read_b128 v[90:93], v1 offset:36960
	v_mfma_f32_32x32x16_bf16 v[18:33], v[86:89], v[94:97], v[18:33]
	ds_read_b128 v[86:89], v68 offset:96
	ds_read_b128 v[94:97], v1 offset:41568
	s_waitcnt lgkmcnt(1)
	v_mfma_f32_32x32x16_bf16 v[34:49], v[86:89], v[90:93], v[34:49]
	s_waitcnt lgkmcnt(0)
	v_mfma_f32_32x32x16_bf16 v[50:65], v[86:89], v[94:97], v[50:65]
	s_waitcnt vmcnt(7)
	ds_write_b128 v66, v[118:121] offset:64512
	s_waitcnt vmcnt(6)
	ds_write_b128 v69, v[114:117] offset:32256
	global_load_dwordx4 v[118:121], v[82:83], off offset:768
	global_load_dwordx4 v[114:117], v[84:85], off offset:768
	v_mfma_f32_32x32x16_bf16 v[2:17], v[98:101], v[90:93], v[2:17]
	v_mfma_f32_32x32x16_bf16 v[18:33], v[98:101], v[94:97], v[18:33]
	s_setprio 0
	s_waitcnt lgkmcnt(0)
	s_barrier
; #define MFMA(a, b, c) __builtin_amdgcn_mfma_f32_32x32x16_bf16((a), (b), (c), 0, 0, 0)
; template <int TM, int TN>
; DI void gemm_mainloop(const u16* __restrict__ A, long lda, const u16* __restrict__ Bt, long ldb, int K, char* smem,
;                       f32x16 (&acc)[TM][TN]) {
;     ...
;   for (int kt = 0; kt < nk; kt++) {
;     const int buf = kt & 1;
;     const u16* cA = sA + buf * BM * LD + (wm * 32 * TM + r) * LD + h * 8;
;     const u16* cB = sB + buf * BN * LD + (wn * 32 * TN + r) * LD + h * 8;
;     bf16x8 af[TM], bfr[TN];
; #pragma unroll
;     for (int tm = 0; tm < TM; tm++) af[tm] = *(const bf16x8*)(cA + tm * 32 * LD);
; #pragma unroll
;     for (int tn = 0; tn < TN; tn++) bfr[tn] = *(const bf16x8*)(cB + tn * 32 * LD);
;     if (kt + 1 < nk) GEMM_SSTORE(buf ^ 1)
;     __builtin_amdgcn_sched_barrier(0);
;     __builtin_amdgcn_s_setprio(1);
; #pragma unroll
;     for (int tm = 0; tm < TM; tm++)
; #pragma unroll
;       for (int tn = 0; tn < TN; tn++) acc[tm][tn] = MFMA(af[tm], bfr[tn], acc[tm][tn]);
; #pragma unroll
;     for (int tm = 0; tm < TM; tm++) af[tm] = *(const bf16x8*)(cA + tm * 32 * LD + 16);
; #pragma unroll
;     for (int tn = 0; tn < TN; tn++) bfr[tn] = *(const bf16x8*)(cB + tn * 32 * LD + 16);
; #pragma unroll
;     for (int tm = 0; tm < TM; tm++)
; #pragma unroll
;       for (int tn = 0; tn < TN; tn++) acc[tm][tn] = MFMA(af[tm], bfr[tn], acc[tm][tn]);
;     __builtin_amdgcn_sched_group_barrier(0x8, 4, 0);
;     if (kt + 2 < nk) GEMM_GLOAD((kt + 2) * 64)
; #pragma unroll
;     for (int ks = 2; ks < 4; ks++) {
; #pragma unroll
;       for (int tm = 0; tm < TM; tm++) af[tm] = *(const bf16x8*)(cA + tm * 32 * LD + ks * 16);
; #pragma unroll
;       for (int tn = 0; tn < TN; tn++) bfr[tn] = *(const bf16x8*)(cB + tn * 32 * LD + ks * 16);
; #pragma unroll
;       for (int tm = 0; tm < TM; tm++)
; #pragma unroll
;         for (int tn = 0; tn < TN; tn++) acc[tm][tn] = MFMA(af[tm], bfr[tn], acc[tm][tn]);
;     }
	ds_read_b128 v[94:97], v68 offset:18432
	ds_read_b128 v[98:101], v68 offset:23040
	ds_read_b128 v[126:129], v1 offset:55296
	ds_read_b128 v[130:133], v1 offset:59904
	s_setprio 1
	ds_read_b128 v[86:89], v68 offset:18464
	s_waitcnt lgkmcnt(2)
	v_mfma_f32_32x32x16_bf16 v[34:49], v[94:97], v[126:129], v[34:49]
	ds_read_b128 v[90:93], v1 offset:55328
	s_waitcnt lgkmcnt(2)
	v_mfma_f32_32x32x16_bf16 v[50:65], v[94:97], v[130:133], v[50:65]
	s_waitcnt vmcnt(7)
	ds_write_b128 v66, v[140:143]
	s_waitcnt vmcnt(6)
	ds_write_b128 v66, v[102:105] offset:4608
	global_load_dwordx4 v[140:143], v[72:73], off offset:896
	global_load_dwordx4 v[102:105], v[70:71], off offset:896
	ds_read_b128 v[94:97], v1 offset:59936
	s_waitcnt lgkmcnt(3)
	v_mfma_f32_32x32x16_bf16 v[34:49], v[86:89], v[90:93], v[34:49]
	s_waitcnt lgkmcnt(0)
	v_mfma_f32_32x32x16_bf16 v[50:65], v[86:89], v[94:97], v[50:65]
	ds_read_b128 v[86:89], v68 offset:23072
	v_mfma_f32_32x32x16_bf16 v[2:17], v[98:101], v[126:129], v[2:17]
	v_mfma_f32_32x32x16_bf16 v[18:33], v[98:101], v[130:133], v[18:33]
	s_waitcnt vmcnt(7)
	ds_write_b128 v66, v[106:109] offset:9216
	s_waitcnt vmcnt(6)
	ds_write_b128 v66, v[110:113] offset:13824
	global_load_dwordx4 v[106:109], v[74:75], off offset:896
	global_load_dwordx4 v[110:113], v[78:79], off offset:896
	ds_read_b128 v[98:101], v68 offset:23136
	s_waitcnt lgkmcnt(3)
	v_mfma_f32_32x32x16_bf16 v[2:17], v[86:89], v[90:93], v[2:17]
	ds_read_b128 v[90:93], v1 offset:55360
	v_mfma_f32_32x32x16_bf16 v[18:33], v[86:89], v[94:97], v[18:33]
	ds_read_b128 v[86:89], v68 offset:18496
	ds_read_b128 v[94:97], v1 offset:59968
	s_waitcnt lgkmcnt(1)
	v_mfma_f32_32x32x16_bf16 v[34:49], v[86:89], v[90:93], v[34:49]
	s_waitcnt lgkmcnt(0)
	v_mfma_f32_32x32x16_bf16 v[50:65], v[86:89], v[94:97], v[50:65]
	s_waitcnt vmcnt(7)
	ds_write_b128 v66, v[144:147] offset:36864
	s_waitcnt vmcnt(6)
	ds_write_b128 v66, v[122:125] offset:41472
	global_load_dwordx4 v[144:147], v[76:77], off offset:896
	global_load_dwordx4 v[122:125], v[80:81], off offset:896
	ds_read_b128 v[86:89], v68 offset:23104
	s_waitcnt lgkmcnt(0)
	v_mfma_f32_32x32x16_bf16 v[2:17], v[86:89], v[90:93], v[2:17]
	ds_read_b128 v[90:93], v1 offset:55392
	v_mfma_f32_32x32x16_bf16 v[18:33], v[86:89], v[94:97], v[18:33]
	ds_read_b128 v[86:89], v68 offset:18528
	ds_read_b128 v[94:97], v1 offset:60000
	s_waitcnt lgkmcnt(1)
	v_mfma_f32_32x32x16_bf16 v[34:49], v[86:89], v[90:93], v[34:49]
	s_waitcnt lgkmcnt(0)
	v_mfma_f32_32x32x16_bf16 v[50:65], v[86:89], v[94:97], v[50:65]
	s_waitcnt vmcnt(7)
	ds_write_b128 v66, v[118:121] offset:46080
	s_waitcnt vmcnt(6)
	ds_write_b128 v66, v[114:117] offset:50688
	global_load_dwordx4 v[118:121], v[82:83], off offset:896
	global_load_dwordx4 v[114:117], v[84:85], off offset:896
	v_mfma_f32_32x32x16_bf16 v[2:17], v[98:101], v[90:93], v[2:17]
	v_mfma_f32_32x32x16_bf16 v[18:33], v[98:101], v[94:97], v[18:33]
	s_setprio 0
	s_waitcnt lgkmcnt(0)
	s_barrier
	ds_read_b128 v[94:97], v68
	ds_read_b128 v[98:101], v68 offset:4608
	ds_read_b128 v[126:129], v1 offset:36864
	ds_read_b128 v[130:133], v1 offset:41472
	s_setprio 1
	ds_read_b128 v[86:89], v68 offset:32
	s_waitcnt lgkmcnt(2)
	v_mfma_f32_32x32x16_bf16 v[34:49], v[94:97], v[126:129], v[34:49]
	ds_read_b128 v[90:93], v1 offset:36896
	s_waitcnt lgkmcnt(2)
	v_mfma_f32_32x32x16_bf16 v[50:65], v[94:97], v[130:133], v[50:65]
	s_waitcnt vmcnt(7)
	ds_write_b128 v66, v[140:143] offset:18432
	s_waitcnt vmcnt(6)
	ds_write_b128 v66, v[102:105] offset:23040
	global_load_dwordx4 v[140:143], v[72:73], off offset:1024
	global_load_dwordx4 v[102:105], v[70:71], off offset:1024
	ds_read_b128 v[94:97], v1 offset:41504
	s_waitcnt lgkmcnt(3)
	v_mfma_f32_32x32x16_bf16 v[34:49], v[86:89], v[90:93], v[34:49]
	s_waitcnt lgkmcnt(0)
	v_mfma_f32_32x32x16_bf16 v[50:65], v[86:89], v[94:97], v[50:65]
	ds_read_b128 v[86:89], v68 offset:4640
	v_mfma_f32_32x32x16_bf16 v[2:17], v[98:101], v[126:129], v[2:17]
	v_mfma_f32_32x32x16_bf16 v[18:33], v[98:101], v[130:133], v[18:33]
	s_waitcnt vmcnt(7)
	ds_write_b128 v66, v[106:109] offset:27648
	s_waitcnt vmcnt(6)
	ds_write_b128 v66, v[110:113] offset:32256
	global_load_dwordx4 v[106:109], v[74:75], off offset:1024
	global_load_dwordx4 v[110:113], v[78:79], off offset:1024
	ds_read_b128 v[98:101], v68 offset:4704
	s_waitcnt lgkmcnt(3)
	v_mfma_f32_32x32x16_bf16 v[2:17], v[86:89], v[90:93], v[2:17]
	ds_read_b128 v[90:93], v1 offset:36928
	v_mfma_f32_32x32x16_bf16 v[18:33], v[86:89], v[94:97], v[18:33]
	ds_read_b128 v[86:89], v68 offset:64
	ds_read_b128 v[94:97], v1 offset:41536
	s_waitcnt lgkmcnt(1)
	v_mfma_f32_32x32x16_bf16 v[34:49], v[86:89], v[90:93], v[34:49]
	s_waitcnt lgkmcnt(0)
	v_mfma_f32_32x32x16_bf16 v[50:65], v[86:89], v[94:97], v[50:65]
	s_waitcnt vmcnt(7)
	ds_write_b128 v66, v[144:147] offset:55296
	s_waitcnt vmcnt(6)
	ds_write_b128 v66, v[122:125] offset:59904
	global_load_dwordx4 v[144:147], v[76:77], off offset:1024
	global_load_dwordx4 v[122:125], v[80:81], off offset:1024
	ds_read_b128 v[86:89], v68 offset:4672
	s_waitcnt lgkmcnt(0)
	v_mfma_f32_32x32x16_bf16 v[2:17], v[86:89], v[90:93], v[2:17]
	ds_read_b128 v[90:93], v1 offset:36960
	v_mfma_f32_32x32x16_bf16 v[18:33], v[86:89], v[94:97], v[18:33]
	ds_read_b128 v[86:89], v68 offset:96
	ds_read_b128 v[94:97], v1 offset:41568
	s_waitcnt lgkmcnt(1)
	v_mfma_f32_32x32x16_bf16 v[34:49], v[86:89], v[90:93], v[34:49]
	s_waitcnt lgkmcnt(0)
	v_mfma_f32_32x32x16_bf16 v[50:65], v[86:89], v[94:97], v[50:65]
	s_waitcnt vmcnt(7)
	ds_write_b128 v66, v[118:121] offset:64512
	s_waitcnt vmcnt(6)
	ds_write_b128 v69, v[114:117] offset:32256
	global_load_dwordx4 v[118:121], v[82:83], off offset:1024
	global_load_dwordx4 v[114:117], v[84:85], off offset:1024
	v_mfma_f32_32x32x16_bf16 v[2:17], v[98:101], v[90:93], v[2:17]
	v_mfma_f32_32x32x16_bf16 v[18:33], v[98:101], v[94:97], v[18:33]
	s_setprio 0
	s_waitcnt lgkmcnt(0)
	s_barrier
; #define MFMA(a, b, c) __builtin_amdgcn_mfma_f32_32x32x16_bf16((a), (b), (c), 0, 0, 0)
; template <int TM, int TN>
; DI void gemm_mainloop(const u16* __restrict__ A, long lda, const u16* __restrict__ Bt, long ldb, int K, char* smem,
;                       f32x16 (&acc)[TM][TN]) {
;     ...
;   for (int kt = 0; kt < nk; kt++) {
;     const int buf = kt & 1;
;     const u16* cA = sA + buf * BM * LD + (wm * 32 * TM + r) * LD + h * 8;
;     const u16* cB = sB + buf * BN * LD + (wn * 32 * TN + r) * LD + h * 8;
;     bf16x8 af[TM], bfr[TN];
; #pragma unroll
;     for (int tm = 0; tm < TM; tm++) af[tm] = *(const bf16x8*)(cA + tm * 32 * LD);
; #pragma unroll
;     for (int tn = 0; tn < TN; tn++) bfr[tn] = *(const bf16x8*)(cB + tn * 32 * LD);
;     if (kt + 1 < nk) GEMM_SSTORE(buf ^ 1)
;     __builtin_amdgcn_sched_barrier(0);
;     __builtin_amdgcn_s_setprio(1);
; #pragma unroll
;     for (int tm = 0; tm < TM; tm++)
; #pragma unroll
;       for (int tn = 0; tn < TN; tn++) acc[tm][tn] = MFMA(af[tm], bfr[tn], acc[tm][tn]);
; #pragma unroll
;     for (int tm = 0; tm < TM; tm++) af[tm] = *(const bf16x8*)(cA + tm * 32 * LD + 16);
; #pragma unroll
;     for (int tn = 0; tn < TN; tn++) bfr[tn] = *(const bf16x8*)(cB + tn * 32 * LD + 16);
; #pragma unroll
;     for (int tm = 0; tm < TM; tm++)
; #pragma unroll
;       for (int tn = 0; tn < TN; tn++) acc[tm][tn] = MFMA(af[tm], bfr[tn], acc[tm][tn]);
;     __builtin_amdgcn_sched_group_barrier(0x8, 4, 0);
;     if (kt + 2 < nk) GEMM_GLOAD((kt + 2) * 64)
; #pragma unroll
;     for (int ks = 2; ks < 4; ks++) {
; #pragma unroll
;       for (int tm = 0; tm < TM; tm++) af[tm] = *(const bf16x8*)(cA + tm * 32 * LD + ks * 16);
; #pragma unroll
;       for (int tn = 0; tn < TN; tn++) bfr[tn] = *(const bf16x8*)(cB + tn * 32 * LD + ks * 16);
; #pragma unroll
;       for (int tm = 0; tm < TM; tm++)
; #pragma unroll
;         for (int tn = 0; tn < TN; tn++) acc[tm][tn] = MFMA(af[tm], bfr[tn], acc[tm][tn]);
;     }
	ds_read_b128 v[94:97], v68 offset:18432
	ds_read_b128 v[98:101], v68 offset:23040
	ds_read_b128 v[126:129], v1 offset:55296
	ds_read_b128 v[130:133], v1 offset:59904
	s_setprio 1
	ds_read_b128 v[86:89], v68 offset:18464
	s_waitcnt lgkmcnt(2)
	v_mfma_f32_32x32x16_bf16 v[34:49], v[94:97], v[126:129], v[34:49]
	ds_read_b128 v[90:93], v1 offset:55328
	s_waitcnt lgkmcnt(2)
	v_mfma_f32_32x32x16_bf16 v[50:65], v[94:97], v[130:133], v[50:65]
	s_waitcnt vmcnt(7)
	ds_write_b128 v66, v[140:143]
	s_waitcnt vmcnt(6)
	ds_write_b128 v66, v[102:105] offset:4608
	global_load_dwordx4 v[140:143], v[72:73], off offset:1152
	global_load_dwordx4 v[102:105], v[70:71], off offset:1152
	ds_read_b128 v[94:97], v1 offset:59936
	s_waitcnt lgkmcnt(3)
	v_mfma_f32_32x32x16_bf16 v[34:49], v[86:89], v[90:93], v[34:49]
	s_waitcnt lgkmcnt(0)
	v_mfma_f32_32x32x16_bf16 v[50:65], v[86:89], v[94:97], v[50:65]
	ds_read_b128 v[86:89], v68 offset:23072
	v_mfma_f32_32x32x16_bf16 v[2:17], v[98:101], v[126:129], v[2:17]
	v_mfma_f32_32x32x16_bf16 v[18:33], v[98:101], v[130:133], v[18:33]
	s_waitcnt vmcnt(7)
	ds_write_b128 v66, v[106:109] offset:9216
	s_waitcnt vmcnt(6)
	ds_write_b128 v66, v[110:113] offset:13824
	global_load_dwordx4 v[106:109], v[74:75], off offset:1152
	global_load_dwordx4 v[110:113], v[78:79], off offset:1152
	ds_read_b128 v[98:101], v68 offset:23136
	s_waitcnt lgkmcnt(3)
	v_mfma_f32_32x32x16_bf16 v[2:17], v[86:89], v[90:93], v[2:17]
	ds_read_b128 v[90:93], v1 offset:55360
	v_mfma_f32_32x32x16_bf16 v[18:33], v[86:89], v[94:97], v[18:33]
	ds_read_b128 v[86:89], v68 offset:18496
	ds_read_b128 v[94:97], v1 offset:59968
	s_waitcnt lgkmcnt(1)
	v_mfma_f32_32x32x16_bf16 v[34:49], v[86:89], v[90:93], v[34:49]
	s_waitcnt lgkmcnt(0)
	v_mfma_f32_32x32x16_bf16 v[50:65], v[86:89], v[94:97], v[50:65]
	s_waitcnt vmcnt(7)
	ds_write_b128 v66, v[144:147] offset:36864
	s_waitcnt vmcnt(6)
	ds_write_b128 v66, v[122:125] offset:41472
	global_load_dwordx4 v[144:147], v[76:77], off offset:1152
	global_load_dwordx4 v[122:125], v[80:81], off offset:1152
	ds_read_b128 v[86:89], v68 offset:23104
	s_waitcnt lgkmcnt(0)
	v_mfma_f32_32x32x16_bf16 v[2:17], v[86:89], v[90:93], v[2:17]
	ds_read_b128 v[90:93], v1 offset:55392
	v_mfma_f32_32x32x16_bf16 v[18:33], v[86:89], v[94:97], v[18:33]
	ds_read_b128 v[86:89], v68 offset:18528
	ds_read_b128 v[94:97], v1 offset:60000
	s_waitcnt lgkmcnt(1)
	v_mfma_f32_32x32x16_bf16 v[34:49], v[86:89], v[90:93], v[34:49]
	s_waitcnt lgkmcnt(0)
	v_mfma_f32_32x32x16_bf16 v[50:65], v[86:89], v[94:97], v[50:65]
	s_waitcnt vmcnt(7)
	ds_write_b128 v66, v[118:121] offset:46080
	s_waitcnt vmcnt(6)
	ds_write_b128 v66, v[114:117] offset:50688
	global_load_dwordx4 v[118:121], v[82:83], off offset:1152
	global_load_dwordx4 v[114:117], v[84:85], off offset:1152
	v_mfma_f32_32x32x16_bf16 v[2:17], v[98:101], v[90:93], v[2:17]
	v_mfma_f32_32x32x16_bf16 v[18:33], v[98:101], v[94:97], v[18:33]
	s_setprio 0
	s_waitcnt lgkmcnt(0)
	s_barrier
	ds_read_b128 v[94:97], v68
	ds_read_b128 v[98:101], v68 offset:4608
	ds_read_b128 v[126:129], v1 offset:36864
	ds_read_b128 v[130:133], v1 offset:41472
	s_setprio 1
	ds_read_b128 v[86:89], v68 offset:32
	s_waitcnt lgkmcnt(2)
	v_mfma_f32_32x32x16_bf16 v[34:49], v[94:97], v[126:129], v[34:49]
	ds_read_b128 v[90:93], v1 offset:36896
	s_waitcnt lgkmcnt(2)
	v_mfma_f32_32x32x16_bf16 v[50:65], v[94:97], v[130:133], v[50:65]
	s_waitcnt vmcnt(7)
	ds_write_b128 v66, v[140:143] offset:18432
	s_waitcnt vmcnt(6)
	ds_write_b128 v66, v[102:105] offset:23040
	global_load_dwordx4 v[140:143], v[72:73], off offset:1280
	global_load_dwordx4 v[102:105], v[70:71], off offset:1280
	ds_read_b128 v[94:97], v1 offset:41504
	s_waitcnt lgkmcnt(3)
	v_mfma_f32_32x32x16_bf16 v[34:49], v[86:89], v[90:93], v[34:49]
	s_waitcnt lgkmcnt(0)
	v_mfma_f32_32x32x16_bf16 v[50:65], v[86:89], v[94:97], v[50:65]
	ds_read_b128 v[86:89], v68 offset:4640
	v_mfma_f32_32x32x16_bf16 v[2:17], v[98:101], v[126:129], v[2:17]
	v_mfma_f32_32x32x16_bf16 v[18:33], v[98:101], v[130:133], v[18:33]
	s_waitcnt vmcnt(7)
	ds_write_b128 v66, v[106:109] offset:27648
	s_waitcnt vmcnt(6)
	ds_write_b128 v66, v[110:113] offset:32256
	global_load_dwordx4 v[106:109], v[74:75], off offset:1280
	global_load_dwordx4 v[110:113], v[78:79], off offset:1280
	ds_read_b128 v[98:101], v68 offset:4704
	s_waitcnt lgkmcnt(3)
	v_mfma_f32_32x32x16_bf16 v[2:17], v[86:89], v[90:93], v[2:17]
	ds_read_b128 v[90:93], v1 offset:36928
	v_mfma_f32_32x32x16_bf16 v[18:33], v[86:89], v[94:97], v[18:33]
	ds_read_b128 v[86:89], v68 offset:64
	ds_read_b128 v[94:97], v1 offset:41536
	s_waitcnt lgkmcnt(1)
	v_mfma_f32_32x32x16_bf16 v[34:49], v[86:89], v[90:93], v[34:49]
	s_waitcnt lgkmcnt(0)
	v_mfma_f32_32x32x16_bf16 v[50:65], v[86:89], v[94:97], v[50:65]
	s_waitcnt vmcnt(7)
	ds_write_b128 v66, v[144:147] offset:55296
	s_waitcnt vmcnt(6)
	ds_write_b128 v66, v[122:125] offset:59904
	global_load_dwordx4 v[144:147], v[76:77], off offset:1280
	global_load_dwordx4 v[122:125], v[80:81], off offset:1280
	ds_read_b128 v[86:89], v68 offset:4672
	s_waitcnt lgkmcnt(0)
	v_mfma_f32_32x32x16_bf16 v[2:17], v[86:89], v[90:93], v[2:17]
	ds_read_b128 v[90:93], v1 offset:36960
	v_mfma_f32_32x32x16_bf16 v[18:33], v[86:89], v[94:97], v[18:33]
	ds_read_b128 v[86:89], v68 offset:96
	ds_read_b128 v[94:97], v1 offset:41568
	s_waitcnt lgkmcnt(1)
	v_mfma_f32_32x32x16_bf16 v[34:49], v[86:89], v[90:93], v[34:49]
	s_waitcnt lgkmcnt(0)
	v_mfma_f32_32x32x16_bf16 v[50:65], v[86:89], v[94:97], v[50:65]
	s_waitcnt vmcnt(7)
	ds_write_b128 v66, v[118:121] offset:64512
	s_waitcnt vmcnt(6)
	ds_write_b128 v69, v[114:117] offset:32256
	global_load_dwordx4 v[118:121], v[82:83], off offset:1280
	global_load_dwordx4 v[114:117], v[84:85], off offset:1280
	v_mfma_f32_32x32x16_bf16 v[2:17], v[98:101], v[90:93], v[2:17]
	v_mfma_f32_32x32x16_bf16 v[18:33], v[98:101], v[94:97], v[18:33]
	s_setprio 0
	s_waitcnt lgkmcnt(0)
	s_barrier
; #define MFMA(a, b, c) __builtin_amdgcn_mfma_f32_32x32x16_bf16((a), (b), (c), 0, 0, 0)
; template <int TM, int TN>
; DI void gemm_mainloop(const u16* __restrict__ A, long lda, const u16* __restrict__ Bt, long ldb, int K, char* smem,
;                       f32x16 (&acc)[TM][TN]) {
;     ...
;   for (int kt = 0; kt < nk; kt++) {
;     const int buf = kt & 1;
;     const u16* cA = sA + buf * BM * LD + (wm * 32 * TM + r) * LD + h * 8;
;     const u16* cB = sB + buf * BN * LD + (wn * 32 * TN + r) * LD + h * 8;
;     bf16x8 af[TM], bfr[TN];
; #pragma unroll
;     for (int tm = 0; tm < TM; tm++) af[tm] = *(const bf16x8*)(cA + tm * 32 * LD);
; #pragma unroll
;     for (int tn = 0; tn < TN; tn++) bfr[tn] = *(const bf16x8*)(cB + tn * 32 * LD);
;     if (kt + 1 < nk) GEMM_SSTORE(buf ^ 1)
;     __builtin_amdgcn_sched_barrier(0);
;     __builtin_amdgcn_s_setprio(1);
; #pragma unroll
;     for (int tm = 0; tm < TM; tm++)
; #pragma unroll
;       for (int tn = 0; tn < TN; tn++) acc[tm][tn] = MFMA(af[tm], bfr[tn], acc[tm][tn]);
; #pragma unroll
;     for (int tm = 0; tm < TM; tm++) af[tm] = *(const bf16x8*)(cA + tm * 32 * LD + 16);
; #pragma unroll
;     for (int tn = 0; tn < TN; tn++) bfr[tn] = *(const bf16x8*)(cB + tn * 32 * LD + 16);
; #pragma unroll
;     for (int tm = 0; tm < TM; tm++)
; #pragma unroll
;       for (int tn = 0; tn < TN; tn++) acc[tm][tn] = MFMA(af[tm], bfr[tn], acc[tm][tn]);
;     __builtin_amdgcn_sched_group_barrier(0x8, 4, 0);
;     if (kt + 2 < nk) GEMM_GLOAD((kt + 2) * 64)
; #pragma unroll
;     for (int ks = 2; ks < 4; ks++) {
; #pragma unroll
;       for (int tm = 0; tm < TM; tm++) af[tm] = *(const bf16x8*)(cA + tm * 32 * LD + ks * 16);
; #pragma unroll
;       for (int tn = 0; tn < TN; tn++) bfr[tn] = *(const bf16x8*)(cB + tn * 32 * LD + ks * 16);
; #pragma unroll
;       for (int tm = 0; tm < TM; tm++)
; #pragma unroll
;         for (int tn = 0; tn < TN; tn++) acc[tm][tn] = MFMA(af[tm], bfr[tn], acc[tm][tn]);
;     }
	ds_read_b128 v[94:97], v68 offset:18432
	ds_read_b128 v[98:101], v68 offset:23040
	ds_read_b128 v[126:129], v1 offset:55296
	ds_read_b128 v[130:133], v1 offset:59904
	s_setprio 1
	ds_read_b128 v[86:89], v68 offset:18464
	s_waitcnt lgkmcnt(2)
	v_mfma_f32_32x32x16_bf16 v[34:49], v[94:97], v[126:129], v[34:49]
	ds_read_b128 v[90:93], v1 offset:55328
	s_waitcnt lgkmcnt(2)
	v_mfma_f32_32x32x16_bf16 v[50:65], v[94:97], v[130:133], v[50:65]
	s_waitcnt vmcnt(7)
	ds_write_b128 v66, v[140:143]
	s_waitcnt vmcnt(6)
	ds_write_b128 v66, v[102:105] offset:4608
	global_load_dwordx4 v[140:143], v[72:73], off offset:1408
	global_load_dwordx4 v[102:105], v[70:71], off offset:1408
	ds_read_b128 v[94:97], v1 offset:59936
	s_waitcnt lgkmcnt(3)
	v_mfma_f32_32x32x16_bf16 v[34:49], v[86:89], v[90:93], v[34:49]
	s_waitcnt lgkmcnt(0)
	v_mfma_f32_32x32x16_bf16 v[50:65], v[86:89], v[94:97], v[50:65]
	ds_read_b128 v[86:89], v68 offset:23072
	v_mfma_f32_32x32x16_bf16 v[2:17], v[98:101], v[126:129], v[2:17]
	v_mfma_f32_32x32x16_bf16 v[18:33], v[98:101], v[130:133], v[18:33]
	s_waitcnt vmcnt(7)
	ds_write_b128 v66, v[106:109] offset:9216
	s_waitcnt vmcnt(6)
	ds_write_b128 v66, v[110:113] offset:13824
	global_load_dwordx4 v[106:109], v[74:75], off offset:1408
	global_load_dwordx4 v[110:113], v[78:79], off offset:1408
	ds_read_b128 v[98:101], v68 offset:23136
	s_waitcnt lgkmcnt(3)
	v_mfma_f32_32x32x16_bf16 v[2:17], v[86:89], v[90:93], v[2:17]
	ds_read_b128 v[90:93], v1 offset:55360
	v_mfma_f32_32x32x16_bf16 v[18:33], v[86:89], v[94:97], v[18:33]
	ds_read_b128 v[86:89], v68 offset:18496
	ds_read_b128 v[94:97], v1 offset:59968
	s_waitcnt lgkmcnt(1)
	v_mfma_f32_32x32x16_bf16 v[34:49], v[86:89], v[90:93], v[34:49]
	s_waitcnt lgkmcnt(0)
	v_mfma_f32_32x32x16_bf16 v[50:65], v[86:89], v[94:97], v[50:65]
	s_waitcnt vmcnt(7)
	ds_write_b128 v66, v[144:147] offset:36864
	s_waitcnt vmcnt(6)
	ds_write_b128 v66, v[122:125] offset:41472
	global_load_dwordx4 v[144:147], v[76:77], off offset:1408
	global_load_dwordx4 v[122:125], v[80:81], off offset:1408
	ds_read_b128 v[86:89], v68 offset:23104
	s_waitcnt lgkmcnt(0)
	v_mfma_f32_32x32x16_bf16 v[2:17], v[86:89], v[90:93], v[2:17]
	ds_read_b128 v[90:93], v1 offset:55392
	v_mfma_f32_32x32x16_bf16 v[18:33], v[86:89], v[94:97], v[18:33]
	ds_read_b128 v[86:89], v68 offset:18528
	ds_read_b128 v[94:97], v1 offset:60000
	s_waitcnt lgkmcnt(1)
	v_mfma_f32_32x32x16_bf16 v[34:49], v[86:89], v[90:93], v[34:49]
	s_waitcnt lgkmcnt(0)
	v_mfma_f32_32x32x16_bf16 v[50:65], v[86:89], v[94:97], v[50:65]
	s_waitcnt vmcnt(7)
	ds_write_b128 v66, v[118:121] offset:46080
	s_waitcnt vmcnt(6)
	ds_write_b128 v66, v[114:117] offset:50688
	global_load_dwordx4 v[118:121], v[82:83], off offset:1408
	global_load_dwordx4 v[114:117], v[84:85], off offset:1408
	v_mfma_f32_32x32x16_bf16 v[2:17], v[98:101], v[90:93], v[2:17]
	v_mfma_f32_32x32x16_bf16 v[18:33], v[98:101], v[94:97], v[18:33]
	s_setprio 0
	s_waitcnt lgkmcnt(0)
	s_barrier
	ds_read_b128 v[94:97], v68
	ds_read_b128 v[98:101], v68 offset:4608
	ds_read_b128 v[126:129], v1 offset:36864
	ds_read_b128 v[130:133], v1 offset:41472
	s_setprio 1
	ds_read_b128 v[86:89], v68 offset:32
	s_waitcnt lgkmcnt(2)
	v_mfma_f32_32x32x16_bf16 v[34:49], v[94:97], v[126:129], v[34:49]
	ds_read_b128 v[90:93], v1 offset:36896
	s_waitcnt lgkmcnt(2)
	v_mfma_f32_32x32x16_bf16 v[50:65], v[94:97], v[130:133], v[50:65]
	s_waitcnt vmcnt(7)
	ds_write_b128 v66, v[140:143] offset:18432
	s_waitcnt vmcnt(6)
	ds_write_b128 v66, v[102:105] offset:23040
	global_load_dwordx4 v[140:143], v[72:73], off offset:1536
	global_load_dwordx4 v[102:105], v[70:71], off offset:1536
	ds_read_b128 v[94:97], v1 offset:41504
	s_waitcnt lgkmcnt(3)
	v_mfma_f32_32x32x16_bf16 v[34:49], v[86:89], v[90:93], v[34:49]
	s_waitcnt lgkmcnt(0)
	v_mfma_f32_32x32x16_bf16 v[50:65], v[86:89], v[94:97], v[50:65]
	ds_read_b128 v[86:89], v68 offset:4640
	v_mfma_f32_32x32x16_bf16 v[2:17], v[98:101], v[126:129], v[2:17]
	v_mfma_f32_32x32x16_bf16 v[18:33], v[98:101], v[130:133], v[18:33]
	s_waitcnt vmcnt(7)
	ds_write_b128 v66, v[106:109] offset:27648
	s_waitcnt vmcnt(6)
	ds_write_b128 v66, v[110:113] offset:32256
	global_load_dwordx4 v[106:109], v[74:75], off offset:1536
	global_load_dwordx4 v[110:113], v[78:79], off offset:1536
	ds_read_b128 v[98:101], v68 offset:4704
	s_waitcnt lgkmcnt(3)
	v_mfma_f32_32x32x16_bf16 v[2:17], v[86:89], v[90:93], v[2:17]
	ds_read_b128 v[90:93], v1 offset:36928
	v_mfma_f32_32x32x16_bf16 v[18:33], v[86:89], v[94:97], v[18:33]
	ds_read_b128 v[86:89], v68 offset:64
	ds_read_b128 v[94:97], v1 offset:41536
	s_waitcnt lgkmcnt(1)
	v_mfma_f32_32x32x16_bf16 v[34:49], v[86:89], v[90:93], v[34:49]
	s_waitcnt lgkmcnt(0)
	v_mfma_f32_32x32x16_bf16 v[50:65], v[86:89], v[94:97], v[50:65]
	s_waitcnt vmcnt(7)
	ds_write_b128 v66, v[144:147] offset:55296
	s_waitcnt vmcnt(6)
	ds_write_b128 v66, v[122:125] offset:59904
	global_load_dwordx4 v[144:147], v[76:77], off offset:1536
	global_load_dwordx4 v[122:125], v[80:81], off offset:1536
	ds_read_b128 v[86:89], v68 offset:4672
	s_waitcnt lgkmcnt(0)
	v_mfma_f32_32x32x16_bf16 v[2:17], v[86:89], v[90:93], v[2:17]
	ds_read_b128 v[90:93], v1 offset:36960
	v_mfma_f32_32x32x16_bf16 v[18:33], v[86:89], v[94:97], v[18:33]
	ds_read_b128 v[86:89], v68 offset:96
	ds_read_b128 v[94:97], v1 offset:41568
	s_waitcnt lgkmcnt(1)
	v_mfma_f32_32x32x16_bf16 v[34:49], v[86:89], v[90:93], v[34:49]
	s_waitcnt lgkmcnt(0)
	v_mfma_f32_32x32x16_bf16 v[50:65], v[86:89], v[94:97], v[50:65]
	s_waitcnt vmcnt(7)
	ds_write_b128 v66, v[118:121] offset:64512
	s_waitcnt vmcnt(6)
	ds_write_b128 v69, v[114:117] offset:32256
	global_load_dwordx4 v[118:121], v[82:83], off offset:1536
	global_load_dwordx4 v[114:117], v[84:85], off offset:1536
	v_mfma_f32_32x32x16_bf16 v[2:17], v[98:101], v[90:93], v[2:17]
	v_mfma_f32_32x32x16_bf16 v[18:33], v[98:101], v[94:97], v[18:33]
	s_setprio 0
	s_waitcnt lgkmcnt(0)
	s_barrier
; #define MFMA(a, b, c) __builtin_amdgcn_mfma_f32_32x32x16_bf16((a), (b), (c), 0, 0, 0)
; template <int TM, int TN>
; DI void gemm_mainloop(const u16* __restrict__ A, long lda, const u16* __restrict__ Bt, long ldb, int K, char* smem,
;                       f32x16 (&acc)[TM][TN]) {
;     ...
;   for (int kt = 0; kt < nk; kt++) {
;     const int buf = kt & 1;
;     const u16* cA = sA + buf * BM * LD + (wm * 32 * TM + r) * LD + h * 8;
;     const u16* cB = sB + buf * BN * LD + (wn * 32 * TN + r) * LD + h * 8;
;     bf16x8 af[TM], bfr[TN];
; #pragma unroll
;     for (int tm = 0; tm < TM; tm++) af[tm] = *(const bf16x8*)(cA + tm * 32 * LD);
; #pragma unroll
;     for (int tn = 0; tn < TN; tn++) bfr[tn] = *(const bf16x8*)(cB + tn * 32 * LD);
;     if (kt + 1 < nk) GEMM_SSTORE(buf ^ 1)
;     __builtin_amdgcn_sched_barrier(0);
;     __builtin_amdgcn_s_setprio(1);
; #pragma unroll
;     for (int tm = 0; tm < TM; tm++)
; #pragma unroll
;       for (int tn = 0; tn < TN; tn++) acc[tm][tn] = MFMA(af[tm], bfr[tn], acc[tm][tn]);
; #pragma unroll
;     for (int tm = 0; tm < TM; tm++) af[tm] = *(const bf16x8*)(cA + tm * 32 * LD + 16);
; #pragma unroll
;     for (int tn = 0; tn < TN; tn++) bfr[tn] = *(const bf16x8*)(cB + tn * 32 * LD + 16);
; #pragma unroll
;     for (int tm = 0; tm < TM; tm++)
; #pragma unroll
;       for (int tn = 0; tn < TN; tn++) acc[tm][tn] = MFMA(af[tm], bfr[tn], acc[tm][tn]);
;     __builtin_amdgcn_sched_group_barrier(0x8, 4, 0);
;     if (kt + 2 < nk) GEMM_GLOAD((kt + 2) * 64)
; #pragma unroll
;     for (int ks = 2; ks < 4; ks++) {
; #pragma unroll
;       for (int tm = 0; tm < TM; tm++) af[tm] = *(const bf16x8*)(cA + tm * 32 * LD + ks * 16);
; #pragma unroll
;       for (int tn = 0; tn < TN; tn++) bfr[tn] = *(const bf16x8*)(cB + tn * 32 * LD + ks * 16);
; #pragma unroll
;       for (int tm = 0; tm < TM; tm++)
; #pragma unroll
;         for (int tn = 0; tn < TN; tn++) acc[tm][tn] = MFMA(af[tm], bfr[tn], acc[tm][tn]);
;     }
	ds_read_b128 v[94:97], v68 offset:18432
	ds_read_b128 v[98:101], v68 offset:23040
	ds_read_b128 v[126:129], v1 offset:55296
	ds_read_b128 v[130:133], v1 offset:59904
	s_setprio 1
	ds_read_b128 v[86:89], v68 offset:18464
	s_waitcnt lgkmcnt(2)
	v_mfma_f32_32x32x16_bf16 v[34:49], v[94:97], v[126:129], v[34:49]
	ds_read_b128 v[90:93], v1 offset:55328
	s_waitcnt lgkmcnt(2)
	v_mfma_f32_32x32x16_bf16 v[50:65], v[94:97], v[130:133], v[50:65]
	s_waitcnt vmcnt(7)
	ds_write_b128 v66, v[140:143]
	s_waitcnt vmcnt(6)
	ds_write_b128 v66, v[102:105] offset:4608
	global_load_dwordx4 v[140:143], v[72:73], off offset:1664
	global_load_dwordx4 v[102:105], v[70:71], off offset:1664
	ds_read_b128 v[94:97], v1 offset:59936
	s_waitcnt lgkmcnt(3)
	v_mfma_f32_32x32x16_bf16 v[34:49], v[86:89], v[90:93], v[34:49]
	s_waitcnt lgkmcnt(0)
	v_mfma_f32_32x32x16_bf16 v[50:65], v[86:89], v[94:97], v[50:65]
	ds_read_b128 v[86:89], v68 offset:23072
	v_mfma_f32_32x32x16_bf16 v[2:17], v[98:101], v[126:129], v[2:17]
	v_mfma_f32_32x32x16_bf16 v[18:33], v[98:101], v[130:133], v[18:33]
	s_waitcnt vmcnt(7)
	ds_write_b128 v66, v[106:109] offset:9216
	s_waitcnt vmcnt(6)
	ds_write_b128 v66, v[110:113] offset:13824
	global_load_dwordx4 v[106:109], v[74:75], off offset:1664
	global_load_dwordx4 v[110:113], v[78:79], off offset:1664
	ds_read_b128 v[98:101], v68 offset:23136
	s_waitcnt lgkmcnt(3)
	v_mfma_f32_32x32x16_bf16 v[2:17], v[86:89], v[90:93], v[2:17]
	ds_read_b128 v[90:93], v1 offset:55360
	v_mfma_f32_32x32x16_bf16 v[18:33], v[86:89], v[94:97], v[18:33]
	ds_read_b128 v[86:89], v68 offset:18496
	ds_read_b128 v[94:97], v1 offset:59968
	s_waitcnt lgkmcnt(1)
	v_mfma_f32_32x32x16_bf16 v[34:49], v[86:89], v[90:93], v[34:49]
	s_waitcnt lgkmcnt(0)
	v_mfma_f32_32x32x16_bf16 v[50:65], v[86:89], v[94:97], v[50:65]
	s_waitcnt vmcnt(7)
	ds_write_b128 v66, v[144:147] offset:36864
	s_waitcnt vmcnt(6)
	ds_write_b128 v66, v[122:125] offset:41472
	global_load_dwordx4 v[144:147], v[76:77], off offset:1664
	global_load_dwordx4 v[122:125], v[80:81], off offset:1664
	ds_read_b128 v[86:89], v68 offset:23104
	s_waitcnt lgkmcnt(0)
	v_mfma_f32_32x32x16_bf16 v[2:17], v[86:89], v[90:93], v[2:17]
	ds_read_b128 v[90:93], v1 offset:55392
	v_mfma_f32_32x32x16_bf16 v[18:33], v[86:89], v[94:97], v[18:33]
	ds_read_b128 v[86:89], v68 offset:18528
	ds_read_b128 v[94:97], v1 offset:60000
	s_waitcnt lgkmcnt(1)
	v_mfma_f32_32x32x16_bf16 v[34:49], v[86:89], v[90:93], v[34:49]
	s_waitcnt lgkmcnt(0)
	v_mfma_f32_32x32x16_bf16 v[50:65], v[86:89], v[94:97], v[50:65]
	s_waitcnt vmcnt(7)
	ds_write_b128 v66, v[118:121] offset:46080
	s_waitcnt vmcnt(6)
	ds_write_b128 v66, v[114:117] offset:50688
	global_load_dwordx4 v[118:121], v[82:83], off offset:1664
	global_load_dwordx4 v[114:117], v[84:85], off offset:1664
	v_mfma_f32_32x32x16_bf16 v[2:17], v[98:101], v[90:93], v[2:17]
	v_mfma_f32_32x32x16_bf16 v[18:33], v[98:101], v[94:97], v[18:33]
	s_setprio 0
	s_waitcnt lgkmcnt(0)
	s_barrier
	ds_read_b128 v[94:97], v68
	ds_read_b128 v[98:101], v68 offset:4608
	ds_read_b128 v[126:129], v1 offset:36864
	ds_read_b128 v[130:133], v1 offset:41472
	s_setprio 1
	ds_read_b128 v[86:89], v68 offset:32
	s_waitcnt lgkmcnt(2)
	v_mfma_f32_32x32x16_bf16 v[34:49], v[94:97], v[126:129], v[34:49]
	ds_read_b128 v[90:93], v1 offset:36896
	s_waitcnt lgkmcnt(2)
	v_mfma_f32_32x32x16_bf16 v[50:65], v[94:97], v[130:133], v[50:65]
	s_waitcnt vmcnt(7)
	ds_write_b128 v66, v[140:143] offset:18432
	s_waitcnt vmcnt(6)
	ds_write_b128 v66, v[102:105] offset:23040
	global_load_dwordx4 v[140:143], v[72:73], off offset:1792
	global_load_dwordx4 v[102:105], v[70:71], off offset:1792
	ds_read_b128 v[94:97], v1 offset:41504
	s_waitcnt lgkmcnt(3)
	v_mfma_f32_32x32x16_bf16 v[34:49], v[86:89], v[90:93], v[34:49]
	s_waitcnt lgkmcnt(0)
	v_mfma_f32_32x32x16_bf16 v[50:65], v[86:89], v[94:97], v[50:65]
	ds_read_b128 v[86:89], v68 offset:4640
	v_mfma_f32_32x32x16_bf16 v[2:17], v[98:101], v[126:129], v[2:17]
	v_mfma_f32_32x32x16_bf16 v[18:33], v[98:101], v[130:133], v[18:33]
	s_waitcnt vmcnt(7)
	ds_write_b128 v66, v[106:109] offset:27648
	s_waitcnt vmcnt(6)
	ds_write_b128 v66, v[110:113] offset:32256
	global_load_dwordx4 v[106:109], v[74:75], off offset:1792
	global_load_dwordx4 v[110:113], v[78:79], off offset:1792
	ds_read_b128 v[98:101], v68 offset:4704
	s_waitcnt lgkmcnt(3)
	v_mfma_f32_32x32x16_bf16 v[2:17], v[86:89], v[90:93], v[2:17]
	ds_read_b128 v[90:93], v1 offset:36928
	v_mfma_f32_32x32x16_bf16 v[18:33], v[86:89], v[94:97], v[18:33]
	ds_read_b128 v[86:89], v68 offset:64
	ds_read_b128 v[94:97], v1 offset:41536
	s_waitcnt lgkmcnt(1)
	v_mfma_f32_32x32x16_bf16 v[34:49], v[86:89], v[90:93], v[34:49]
	s_waitcnt lgkmcnt(0)
	v_mfma_f32_32x32x16_bf16 v[50:65], v[86:89], v[94:97], v[50:65]
	s_waitcnt vmcnt(7)
	ds_write_b128 v66, v[144:147] offset:55296
	s_waitcnt vmcnt(6)
	ds_write_b128 v66, v[122:125] offset:59904
	global_load_dwordx4 v[144:147], v[76:77], off offset:1792
	global_load_dwordx4 v[122:125], v[80:81], off offset:1792
	ds_read_b128 v[86:89], v68 offset:4672
	s_waitcnt lgkmcnt(0)
	v_mfma_f32_32x32x16_bf16 v[2:17], v[86:89], v[90:93], v[2:17]
	ds_read_b128 v[90:93], v1 offset:36960
	v_mfma_f32_32x32x16_bf16 v[18:33], v[86:89], v[94:97], v[18:33]
	ds_read_b128 v[86:89], v68 offset:96
	ds_read_b128 v[94:97], v1 offset:41568
	s_waitcnt lgkmcnt(1)
	v_mfma_f32_32x32x16_bf16 v[34:49], v[86:89], v[90:93], v[34:49]
	s_waitcnt lgkmcnt(0)
	v_mfma_f32_32x32x16_bf16 v[50:65], v[86:89], v[94:97], v[50:65]
	s_waitcnt vmcnt(7)
	ds_write_b128 v66, v[118:121] offset:64512
	s_waitcnt vmcnt(6)
	ds_write_b128 v69, v[114:117] offset:32256
	global_load_dwordx4 v[118:121], v[82:83], off offset:1792
	global_load_dwordx4 v[114:117], v[84:85], off offset:1792
	v_mfma_f32_32x32x16_bf16 v[2:17], v[98:101], v[90:93], v[2:17]
	v_mfma_f32_32x32x16_bf16 v[18:33], v[98:101], v[94:97], v[18:33]
	s_setprio 0
	s_waitcnt lgkmcnt(0)
	s_barrier
; #define MFMA(a, b, c) __builtin_amdgcn_mfma_f32_32x32x16_bf16((a), (b), (c), 0, 0, 0)
; template <int TM, int TN>
; DI void gemm_mainloop(const u16* __restrict__ A, long lda, const u16* __restrict__ Bt, long ldb, int K, char* smem,
;                       f32x16 (&acc)[TM][TN]) {
;     ...
;   for (int kt = 0; kt < nk; kt++) {
;     const int buf = kt & 1;
;     const u16* cA = sA + buf * BM * LD + (wm * 32 * TM + r) * LD + h * 8;
;     const u16* cB = sB + buf * BN * LD + (wn * 32 * TN + r) * LD + h * 8;
;     bf16x8 af[TM], bfr[TN];
; #pragma unroll
;     for (int tm = 0; tm < TM; tm++) af[tm] = *(const bf16x8*)(cA + tm * 32 * LD);
; #pragma unroll
;     for (int tn = 0; tn < TN; tn++) bfr[tn] = *(const bf16x8*)(cB + tn * 32 * LD);
;     if (kt + 1 < nk) GEMM_SSTORE(buf ^ 1)
;     __builtin_amdgcn_sched_barrier(0);
;     __builtin_amdgcn_s_setprio(1);
; #pragma unroll
;     for (int tm = 0; tm < TM; tm++)
; #pragma unroll
;       for (int tn = 0; tn < TN; tn++) acc[tm][tn] = MFMA(af[tm], bfr[tn], acc[tm][tn]);
; #pragma unroll
;     for (int tm = 0; tm < TM; tm++) af[tm] = *(const bf16x8*)(cA + tm * 32 * LD + 16);
; #pragma unroll
;     for (int tn = 0; tn < TN; tn++) bfr[tn] = *(const bf16x8*)(cB + tn * 32 * LD + 16);
; #pragma unroll
;     for (int tm = 0; tm < TM; tm++)
; #pragma unroll
;       for (int tn = 0; tn < TN; tn++) acc[tm][tn] = MFMA(af[tm], bfr[tn], acc[tm][tn]);
;     __builtin_amdgcn_sched_group_barrier(0x8, 4, 0);
;     if (kt + 2 < nk) GEMM_GLOAD((kt + 2) * 64)
; #pragma unroll
;     for (int ks = 2; ks < 4; ks++) {
; #pragma unroll
;       for (int tm = 0; tm < TM; tm++) af[tm] = *(const bf16x8*)(cA + tm * 32 * LD + ks * 16);
; #pragma unroll
;       for (int tn = 0; tn < TN; tn++) bfr[tn] = *(const bf16x8*)(cB + tn * 32 * LD + ks * 16);
; #pragma unroll
;       for (int tm = 0; tm < TM; tm++)
; #pragma unroll
;         for (int tn = 0; tn < TN; tn++) acc[tm][tn] = MFMA(af[tm], bfr[tn], acc[tm][tn]);
;     }
;     __builtin_amdgcn_s_setprio(0);
;     __syncthreads();
;   }
	ds_read_b128 v[94:97], v68 offset:18432
	ds_read_b128 v[98:101], v68 offset:23040
	ds_read_b128 v[126:129], v1 offset:55296
	ds_read_b128 v[130:133], v1 offset:59904
	s_setprio 1
	ds_read_b128 v[86:89], v68 offset:18464
	s_waitcnt lgkmcnt(2)
	v_mfma_f32_32x32x16_bf16 v[34:49], v[94:97], v[126:129], v[34:49]
	ds_read_b128 v[90:93], v1 offset:55328
	s_waitcnt lgkmcnt(2)
	v_mfma_f32_32x32x16_bf16 v[50:65], v[94:97], v[130:133], v[50:65]
	s_waitcnt vmcnt(7)
	ds_write_b128 v66, v[140:143]
	s_waitcnt vmcnt(6)
	ds_write_b128 v66, v[102:105] offset:4608
	global_load_dwordx4 v[140:143], v[72:73], off offset:1920
	global_load_dwordx4 v[102:105], v[70:71], off offset:1920
	ds_read_b128 v[94:97], v1 offset:59936
	s_waitcnt lgkmcnt(3)
	v_mfma_f32_32x32x16_bf16 v[34:49], v[86:89], v[90:93], v[34:49]
	s_waitcnt lgkmcnt(0)
	v_mfma_f32_32x32x16_bf16 v[50:65], v[86:89], v[94:97], v[50:65]
	ds_read_b128 v[86:89], v68 offset:23072
	v_mfma_f32_32x32x16_bf16 v[2:17], v[98:101], v[126:129], v[2:17]
	v_mfma_f32_32x32x16_bf16 v[18:33], v[98:101], v[130:133], v[18:33]
	s_waitcnt vmcnt(7)
	ds_write_b128 v66, v[106:109] offset:9216
	s_waitcnt vmcnt(6)
	ds_write_b128 v66, v[110:113] offset:13824
	global_load_dwordx4 v[106:109], v[74:75], off offset:1920
	global_load_dwordx4 v[110:113], v[78:79], off offset:1920
	ds_read_b128 v[98:101], v68 offset:23136
	s_waitcnt lgkmcnt(3)
	v_mfma_f32_32x32x16_bf16 v[2:17], v[86:89], v[90:93], v[2:17]
	ds_read_b128 v[90:93], v1 offset:55360
	v_mfma_f32_32x32x16_bf16 v[18:33], v[86:89], v[94:97], v[18:33]
	ds_read_b128 v[86:89], v68 offset:18496
	ds_read_b128 v[94:97], v1 offset:59968
	s_waitcnt lgkmcnt(1)
	v_mfma_f32_32x32x16_bf16 v[34:49], v[86:89], v[90:93], v[34:49]
	s_waitcnt lgkmcnt(0)
	v_mfma_f32_32x32x16_bf16 v[50:65], v[86:89], v[94:97], v[50:65]
	s_waitcnt vmcnt(7)
	ds_write_b128 v66, v[144:147] offset:36864
	s_waitcnt vmcnt(6)
	ds_write_b128 v66, v[122:125] offset:41472
	global_load_dwordx4 v[144:147], v[76:77], off offset:1920
	global_load_dwordx4 v[122:125], v[80:81], off offset:1920
	ds_read_b128 v[86:89], v68 offset:23104
	s_waitcnt lgkmcnt(0)
	v_mfma_f32_32x32x16_bf16 v[2:17], v[86:89], v[90:93], v[2:17]
	ds_read_b128 v[90:93], v1 offset:55392
	v_mfma_f32_32x32x16_bf16 v[18:33], v[86:89], v[94:97], v[18:33]
	ds_read_b128 v[86:89], v68 offset:18528
	ds_read_b128 v[94:97], v1 offset:60000
	s_waitcnt lgkmcnt(1)
	v_mfma_f32_32x32x16_bf16 v[34:49], v[86:89], v[90:93], v[34:49]
	s_waitcnt lgkmcnt(0)
	v_mfma_f32_32x32x16_bf16 v[50:65], v[86:89], v[94:97], v[50:65]
	s_waitcnt vmcnt(7)
	ds_write_b128 v66, v[118:121] offset:46080
	s_waitcnt vmcnt(6)
	ds_write_b128 v66, v[114:117] offset:50688
	global_load_dwordx4 v[118:121], v[82:83], off offset:1920
	global_load_dwordx4 v[114:117], v[84:85], off offset:1920
	s_nop 0
	v_mfma_f32_32x32x16_bf16 v[2:17], v[98:101], v[90:93], v[2:17]
	v_mfma_f32_32x32x16_bf16 v[18:33], v[98:101], v[94:97], v[18:33]
	s_setprio 0
	s_waitcnt lgkmcnt(0)
	s_barrier
	ds_read_b128 v[74:77], v68
	ds_read_b128 v[78:81], v68 offset:4608
	ds_read_b128 v[82:85], v1 offset:36864
	ds_read_b128 v[90:93], v1 offset:41472
	s_setprio 1
	ds_read_b128 v[70:73], v68 offset:32
	s_waitcnt lgkmcnt(2)
	v_mfma_f32_32x32x16_bf16 v[34:49], v[74:77], v[82:85], v[34:49]
	s_waitcnt lgkmcnt(1)
	v_mfma_f32_32x32x16_bf16 v[50:65], v[74:77], v[90:93], v[50:65]
	s_waitcnt vmcnt(7)
	ds_write_b128 v66, v[140:143] offset:18432
	s_waitcnt vmcnt(6)
	ds_write_b128 v66, v[102:105] offset:23040
	ds_read_b128 v[74:77], v1 offset:36896
	v_mfma_f32_32x32x16_bf16 v[2:17], v[78:81], v[82:85], v[2:17]
	v_mfma_f32_32x32x16_bf16 v[18:33], v[78:81], v[90:93], v[18:33]
	ds_read_b128 v[78:81], v1 offset:41504
	s_waitcnt lgkmcnt(1)
	v_mfma_f32_32x32x16_bf16 v[34:49], v[70:73], v[74:77], v[34:49]
	s_waitcnt lgkmcnt(0)
	v_mfma_f32_32x32x16_bf16 v[50:65], v[70:73], v[78:81], v[50:65]
	s_waitcnt vmcnt(5)
	ds_write_b128 v66, v[106:109] offset:27648
	s_waitcnt vmcnt(4)
	ds_write_b128 v66, v[110:113] offset:32256
	ds_read_b128 v[70:73], v68 offset:4640
	s_waitcnt lgkmcnt(0)
	v_mfma_f32_32x32x16_bf16 v[2:17], v[70:73], v[74:77], v[2:17]
	ds_read_b128 v[74:77], v1 offset:36928
	v_mfma_f32_32x32x16_bf16 v[18:33], v[70:73], v[78:81], v[18:33]
	ds_read_b128 v[70:73], v68 offset:64
	ds_read_b128 v[78:81], v1 offset:41536
	s_waitcnt lgkmcnt(1)
	v_mfma_f32_32x32x16_bf16 v[34:49], v[70:73], v[74:77], v[34:49]
	s_waitcnt lgkmcnt(0)
	v_mfma_f32_32x32x16_bf16 v[50:65], v[70:73], v[78:81], v[50:65]
	s_waitcnt vmcnt(3)
	ds_write_b128 v66, v[144:147] offset:55296
	s_waitcnt vmcnt(2)
	ds_write_b128 v66, v[122:125] offset:59904
	ds_read_b128 v[70:73], v68 offset:4672
	s_waitcnt lgkmcnt(0)
	v_mfma_f32_32x32x16_bf16 v[2:17], v[70:73], v[74:77], v[2:17]
	ds_read_b128 v[74:77], v1 offset:36960
	v_mfma_f32_32x32x16_bf16 v[18:33], v[70:73], v[78:81], v[18:33]
	ds_read_b128 v[70:73], v68 offset:96
	ds_read_b128 v[78:81], v1 offset:41568
	s_waitcnt lgkmcnt(1)
	v_mfma_f32_32x32x16_bf16 v[34:49], v[70:73], v[74:77], v[34:49]
	s_waitcnt lgkmcnt(0)
	v_mfma_f32_32x32x16_bf16 v[50:65], v[70:73], v[78:81], v[50:65]
	s_waitcnt vmcnt(1)
	ds_write_b128 v66, v[118:121] offset:64512
	s_waitcnt vmcnt(0)
	ds_write_b128 v69, v[114:117] offset:32256
	ds_read_b128 v[70:73], v68 offset:4704
	s_waitcnt lgkmcnt(0)
	v_mfma_f32_32x32x16_bf16 v[2:17], v[70:73], v[74:77], v[2:17]
	v_mfma_f32_32x32x16_bf16 v[18:33], v[70:73], v[78:81], v[18:33]
	s_setprio 0
	s_barrier
; template <int TM, int TN>
; DI void gemm_mainloop(const u16* __restrict__ A, long lda, const u16* __restrict__ Bt, long ldb, int K, char* smem,
;                       f32x16 (&acc)[TM][TN]) {
;     ...
;   for (int kt = 0; kt < nk; kt++) {
;     const int buf = kt & 1;
;     const u16* cA = sA + buf * BM * LD + (wm * 32 * TM + r) * LD + h * 8;
;     const u16* cB = sB + buf * BN * LD + (wn * 32 * TN + r) * LD + h * 8;
;     bf16x8 af[TM], bfr[TN];
; #pragma unroll
;     for (int tm = 0; tm < TM; tm++) af[tm] = *(const bf16x8*)(cA + tm * 32 * LD);
; #pragma unroll
;     for (int tn = 0; tn < TN; tn++) bfr[tn] = *(const bf16x8*)(cB + tn * 32 * LD);
;     if (kt + 1 < nk) GEMM_SSTORE(buf ^ 1)
;     __builtin_amdgcn_sched_barrier(0);
;     __builtin_amdgcn_s_setprio(1);
; #pragma unroll
;     for (int tm = 0; tm < TM; tm++)
; #pragma unroll
;       for (int tn = 0; tn < TN; tn++) acc[tm][tn] = MFMA(af[tm], bfr[tn], acc[tm][tn]);
; #pragma unroll
;     for (int tm = 0; tm < TM; tm++) af[tm] = *(const bf16x8*)(cA + tm * 32 * LD + 16);
; #pragma unroll
;     for (int tn = 0; tn < TN; tn++) bfr[tn] = *(const bf16x8*)(cB + tn * 32 * LD + 16);
; #pragma unroll
;     for (int tm = 0; tm < TM; tm++)
; #pragma unroll
;       for (int tn = 0; tn < TN; tn++) acc[tm][tn] = MFMA(af[tm], bfr[tn], acc[tm][tn]);
;     __builtin_amdgcn_sched_group_barrier(0x8, 4, 0);
;     if (kt + 2 < nk) GEMM_GLOAD((kt + 2) * 64)
; #pragma unroll
;     for (int ks = 2; ks < 4; ks++) {
; #pragma unroll
;       for (int tm = 0; tm < TM; tm++) af[tm] = *(const bf16x8*)(cA + tm * 32 * LD + ks * 16);
; #pragma unroll
;       for (int tn = 0; tn < TN; tn++) bfr[tn] = *(const bf16x8*)(cB + tn * 32 * LD + ks * 16);
; #pragma unroll
;       for (int tm = 0; tm < TM; tm++)
; #pragma unroll
;         for (int tn = 0; tn < TN; tn++) acc[tm][tn] = MFMA(af[tm], bfr[tn], acc[tm][tn]);
;     }
;     __builtin_amdgcn_s_setprio(0);
;     __syncthreads();
;   }
; template <int TM, int TN, class Epi>
; DI void gemm_tile(const u16* A, long lda, const u16* Bt, long ldb, int K, int m0, int n0, char* smem, const Epi& epi) {
;     ...
; #pragma unroll
;   for (int tm = 0; tm < TM; tm++)
; #pragma unroll
;     for (int tn = 0; tn < TN; tn++)
; #pragma unroll
;       for (int i = 0; i < 16; i++)
;         Ct[(wm * 32 * TM + tm * 32 + crow(i, h)) * LDC + wn * 32 * TN + tn * 32 + r] = acc[tm][tn][i];
;   __syncthreads();
	ds_read_b128 v[70:73], v68 offset:18432
	ds_read_b128 v[74:77], v68 offset:23040
	ds_read_b128 v[78:81], v1 offset:55296
	ds_read_b128 v[82:85], v1 offset:59904
	s_setprio 1
	s_waitcnt lgkmcnt(1)
	v_mfma_f32_32x32x16_bf16 v[34:49], v[70:73], v[78:81], v[34:49]
	s_waitcnt lgkmcnt(0)
	v_mfma_f32_32x32x16_bf16 v[50:65], v[70:73], v[82:85], v[50:65]
	ds_read_b128 v[70:73], v68 offset:18464
	v_mfma_f32_32x32x16_bf16 v[2:17], v[74:77], v[78:81], v[2:17]
	ds_read_b128 v[78:81], v1 offset:59936
	v_mfma_f32_32x32x16_bf16 v[18:33], v[74:77], v[82:85], v[18:33]
	ds_read_b128 v[74:77], v1 offset:55328
	s_waitcnt lgkmcnt(0)
	v_mfma_f32_32x32x16_bf16 v[34:49], v[70:73], v[74:77], v[34:49]
	v_mfma_f32_32x32x16_bf16 v[50:65], v[70:73], v[78:81], v[50:65]
	ds_read_b128 v[70:73], v68 offset:23072
	s_waitcnt lgkmcnt(0)
	v_mfma_f32_32x32x16_bf16 v[2:17], v[70:73], v[74:77], v[2:17]
	ds_read_b128 v[74:77], v1 offset:55360
	v_mfma_f32_32x32x16_bf16 v[18:33], v[70:73], v[78:81], v[18:33]
	ds_read_b128 v[70:73], v68 offset:18496
	ds_read_b128 v[78:81], v1 offset:59968
	s_waitcnt lgkmcnt(1)
	v_mfma_f32_32x32x16_bf16 v[34:49], v[70:73], v[74:77], v[34:49]
	s_waitcnt lgkmcnt(0)
	v_mfma_f32_32x32x16_bf16 v[50:65], v[70:73], v[78:81], v[50:65]
	ds_read_b128 v[70:73], v68 offset:23104
	s_waitcnt lgkmcnt(0)
	v_mfma_f32_32x32x16_bf16 v[2:17], v[70:73], v[74:77], v[2:17]
	ds_read_b128 v[74:77], v1 offset:55392
	v_mfma_f32_32x32x16_bf16 v[18:33], v[70:73], v[78:81], v[18:33]
	ds_read_b128 v[70:73], v68 offset:18528
	ds_read_b128 v[78:81], v1 offset:60000
	s_waitcnt lgkmcnt(1)
	v_mfma_f32_32x32x16_bf16 v[34:49], v[70:73], v[74:77], v[34:49]
	s_waitcnt lgkmcnt(0)
	v_mfma_f32_32x32x16_bf16 v[50:65], v[70:73], v[78:81], v[50:65]
	ds_read_b128 v[68:71], v68 offset:23136
	s_waitcnt lgkmcnt(0)
	v_mfma_f32_32x32x16_bf16 v[2:17], v[68:71], v[74:77], v[2:17]
	v_mfma_f32_32x32x16_bf16 v[18:33], v[68:71], v[78:81], v[18:33]
	s_setprio 0
	v_mov_b32_e32 v1, v0
	s_barrier
	s_lshl_b64 s[6:7], s[6:7], 1
	v_lshrrev_b32_e32 v66, 1, v1
	v_and_b32_e32 v66, 0xfffffc0, v66
	v_lshrrev_b32_e32 v68, 3, v1
	v_and_or_b32 v66, v68, 4, v66
	v_and_b32_e32 v68, 0x5f, v1
	v_mul_lo_u32 v66, v66, s22
	v_lshl_add_u32 v66, v68, 2, v66
	ds_write2_b32 v66, v34, v50 offset1:32
	v_add_u32_e32 v34, 0x400, v66
	ds_write2_b32 v34, v36, v52 offset0:8 offset1:40
	ds_write2_b32 v34, v37, v53 offset0:140 offset1:172
	v_add_u32_e32 v34, 0x1000, v66
	ds_write2_b32 v34, v38, v54 offset0:32 offset1:64
	ds_write2_b32 v34, v39, v55 offset0:164 offset1:196
	v_add_u32_e32 v34, 0x1400, v66
	ds_write2_b32 v34, v40, v56 offset0:40 offset1:72
	ds_write2_b32 v34, v41, v57 offset0:172 offset1:204
	v_add_u32_e32 v34, 0x2000, v66
	ds_write2_b32 v34, v42, v58 offset0:64 offset1:96
	ds_write2_b32 v34, v43, v59 offset0:196 offset1:228
	v_add_u32_e32 v34, 0x2400, v66
	ds_write2_b32 v34, v44, v60 offset0:72 offset1:104
	ds_write2_b32 v34, v45, v61 offset0:204 offset1:236
	v_add_u32_e32 v34, 0x3000, v66
	ds_write2_b32 v34, v46, v62 offset0:96 offset1:128
	v_add_u32_e32 v34, 0x3200, v66
	ds_write2_b32 v34, v47, v63 offset0:100 offset1:132
	v_add_u32_e32 v34, 0x3400, v66
	ds_write2_b32 v34, v48, v64 offset0:104 offset1:136
	v_add_u32_e32 v34, 0x3600, v66
	ds_write2_b32 v34, v49, v65 offset0:108 offset1:140
	v_add_u32_e32 v34, 0x4000, v66
	ds_write2_b32 v34, v2, v18 offset0:128 offset1:160
	v_add_u32_e32 v2, 0x4400, v66
	ds_write2_b32 v2, v3, v19 offset0:4 offset1:36
	ds_write2_b32 v2, v4, v20 offset0:136 offset1:168
	v_add_u32_e32 v2, 0x4800, v66
	ds_write2_b32 v2, v5, v21 offset0:12 offset1:44
	v_add_u32_e32 v2, 0x5000, v66
	ds_write2_b32 v2, v6, v22 offset0:160 offset1:192
	v_add_u32_e32 v2, 0x5400, v66
	ds_write2_b32 v2, v7, v23 offset0:36 offset1:68
	ds_write2_b32 v2, v8, v24 offset0:168 offset1:200
	v_add_u32_e32 v2, 0x5800, v66
	ds_write2_b32 v2, v9, v25 offset0:44 offset1:76
	v_add_u32_e32 v2, 0x6000, v66
	ds_write2_b32 v2, v10, v26 offset0:192 offset1:224
	v_add_u32_e32 v2, 0x6400, v66
	ds_write2_b32 v2, v11, v27 offset0:68 offset1:100
	ds_write2_b32 v2, v12, v28 offset0:200 offset1:232
	v_add_u32_e32 v2, 0x6800, v66
	ds_write2_b32 v2, v13, v29 offset0:76 offset1:108
	v_add_u32_e32 v2, 0x7200, v66
	ds_write2_b32 v2, v14, v30 offset0:96 offset1:128
	v_add_u32_e32 v2, 0x7400, v66
	ds_write2_b32 v2, v15, v31 offset0:100 offset1:132
	v_add_u32_e32 v2, 0x7600, v66
	ds_write2_b32 v2, v16, v32 offset0:104 offset1:136
	v_add_u32_e32 v2, 0x7800, v66
	ds_write2_b32 v2, v17, v33 offset0:108 offset1:140
	v_lshlrev_b32_e32 v2, 3, v1
	v_and_b32_e32 v3, 0x78, v2
	s_add_u32 s6, s3, s6
	ds_write2_b32 v66, v35, v51 offset0:132 offset1:164
	s_addc_u32 s7, s10, s7
	v_lshlrev_b32_e32 v66, 1, v3
	v_lshlrev_b32_e32 v2, 2, v3
	v_lshl_add_u64 v[4:5], s[6:7], 0, v[66:67]
	s_mov_b32 s6, 0
	s_waitcnt lgkmcnt(0)
	s_barrier

; __global__ void __launch_bounds__(256, 2) fwd_megakernel(Params p, int ph_begin, int ph_end) {
;   __shared__ __attribute__((aligned(16))) char smem[SMEM_BYTES];
;   cg::grid_group grid = cg::this_grid();
;   __shared__ int s_rank;
;   __shared__ __attribute__((aligned(16))) unsigned xb_words[4];
	.amdhsa_kernel _Z14fwd_megakernel6Paramsii
		.amdhsa_group_segment_fixed_size 73748
		.amdhsa_private_segment_fixed_size 0
		.amdhsa_kernarg_size 568
		.amdhsa_user_sgpr_count 2
		.amdhsa_user_sgpr_dispatch_ptr 0
		.amdhsa_user_sgpr_queue_ptr 0
		.amdhsa_user_sgpr_kernarg_segment_ptr 1
		.amdhsa_user_sgpr_dispatch_id 0
		.amdhsa_user_sgpr_kernarg_preload_length 0
		.amdhsa_user_sgpr_kernarg_preload_offset 0
		.amdhsa_user_sgpr_private_segment_size 0
		.amdhsa_uses_dynamic_stack 0
		.amdhsa_enable_private_segment 0
		.amdhsa_system_sgpr_workgroup_id_x 1
		.amdhsa_system_sgpr_workgroup_id_y 0
		.amdhsa_system_sgpr_workgroup_id_z 0
		.amdhsa_system_sgpr_workgroup_info 0
		.amdhsa_system_vgpr_workitem_id 0
		.amdhsa_next_free_vgpr 256
		.amdhsa_next_free_sgpr 98
		.amdhsa_accum_offset 256
		.amdhsa_reserve_vcc 1
		.amdhsa_float_round_mode_32 0
		.amdhsa_float_round_mode_16_64 0
		.amdhsa_float_denorm_mode_32 3
		.amdhsa_float_denorm_mode_16_64 3
		.amdhsa_dx10_clamp 1
		.amdhsa_ieee_mode 1
		.amdhsa_fp16_overflow 0
		.amdhsa_tg_split 0
		.amdhsa_exception_fp_ieee_invalid_op 0
		.amdhsa_exception_fp_denorm_src 0
		.amdhsa_exception_fp_ieee_div_zero 0
		.amdhsa_exception_fp_ieee_overflow 0
		.amdhsa_exception_fp_ieee_underflow 0
		.amdhsa_exception_fp_ieee_inexact 0
		.amdhsa_exception_int_div_zero 0
	.end_amdhsa_kernel

; __global__ void __launch_bounds__(256, 2) fwd_megakernel(Params p, int ph_begin, int ph_end) {
;   __shared__ __attribute__((aligned(16))) char smem[SMEM_BYTES];
;   cg::grid_group grid = cg::this_grid();
;   __shared__ int s_rank;
;   __shared__ __attribute__((aligned(16))) unsigned xb_words[4];
amdhsa.kernels:
  - .agpr_count:     0
    .args:
      - .offset:         0
        .size:           304
        .value_kind:     by_value
      - .offset:         304
        .size:           4
        .value_kind:     by_value
      - .offset:         308
        .size:           4
        .value_kind:     by_value
      - .offset:         312
        .size:           4
        .value_kind:     hidden_block_count_x
      - .offset:         316
        .size:           4
        .value_kind:     hidden_block_count_y
      - .offset:         320
        .size:           4
        .value_kind:     hidden_block_count_z
      - .offset:         324
        .size:           2
        .value_kind:     hidden_group_size_x
      - .offset:         326
        .size:           2
        .value_kind:     hidden_group_size_y
      - .offset:         328
        .size:           2
        .value_kind:     hidden_group_size_z
      - .offset:         330
        .size:           2
        .value_kind:     hidden_remainder_x
      - .offset:         332
        .size:           2
        .value_kind:     hidden_remainder_y
      - .offset:         334
        .size:           2
        .value_kind:     hidden_remainder_z
      - .offset:         352
        .size:           8
        .value_kind:     hidden_global_offset_x
      - .offset:         360
        .size:           8
        .value_kind:     hidden_global_offset_y
      - .offset:         368
        .size:           8
        .value_kind:     hidden_global_offset_z
      - .offset:         376
        .size:           2
        .value_kind:     hidden_grid_dims
    .group_segment_fixed_size: 73748
    .kernarg_segment_align: 8
    .kernarg_segment_size: 568
    .language:       OpenCL C
    .language_version:
      - 2
      - 0
    .max_flat_workgroup_size: 256
    .name:           _Z14fwd_megakernel6Paramsii
    .private_segment_fixed_size: 0
    .sgpr_count:     104
    .sgpr_spill_count: 3
    .symbol:         _Z14fwd_megakernel6Paramsii.kd
    .uniform_work_group_size: 1
    .uses_dynamic_stack: false
    .vgpr_count:     256
    .vgpr_spill_count: 0
    .wavefront_size: 64
